# attention unit rewritten by hand with v_mfma_f32_16x16x32_bf16 (one barrier per KV tile, in-lane P operands), flat->global, same bf16/f32 numerics
# speedup vs baseline: 1.0605x; 1.0605x over previous
; __device__ __forceinline__ unsigned char* opq(unsigned char* q) { asm volatile("" : "+s"(q)); return q; }
; __device__ __forceinline__ int opaque_tid() { int t = threadIdx.x; asm volatile("" : "+v"(t)); return t; }
; __device__ __forceinline__ void tables_phase(const KArgs& a) {
;     unsigned char* const wsb = opq(a.ws);
;     const int tid = opaque_tid();
;     const int* pos = (const int*)a.in[1];
;     float* cs = (float*)(wsb + WS_COS); float* sn = (float*)(wsb + WS_SIN);
;     const int gt = blockIdx.x * 512 + tid, ngt = gridDim.x * 512;
;     for (int idx = gt; idx < M * 32; idx += ngt) { const int tok = idx >> 5, i = idx & 31;
;         const float inv = 1.0f / exp2f((float)(2 * i) * (1.f / 64.f) * 13.287712379549449f);
;         const float ang = (float)pos[tok] * inv;
;         double rev = (double)ang * 0.15915494309189535; rev -= rint(rev);
;         const float f = (float)rev;
;         cs[idx] = __builtin_amdgcn_cosf(f); sn[idx] = __builtin_amdgcn_sinf(f); }
.LBB0_17:
	v_ashrrev_i32_e32 v8, 5, v0
	v_ashrrev_i32_e32 v9, 31, v8
	v_lshl_add_u64 v[8:9], v[8:9], 2, s[74:75]
	global_load_dword v7, v[8:9], off
	v_and_b32_e32 v8, 62, v1
	v_cvt_f32_ubyte0_e32 v8, v8
	v_add_u32_e32 v0, s62, v0
	v_mul_f32_e32 v8, 0x3c800000, v8
	v_cmp_lt_i32_e32 vcc, s12, v0
	v_mul_f32_e32 v9, 0x41549a78, v8
	s_or_b64 s[6:7], vcc, s[6:7]
	v_cmp_gt_f32_e32 vcc, s11, v9
	v_add_u32_e32 v1, s10, v1
	s_waitcnt vmcnt(0)
	v_cvt_f32_i32_e32 v7, v7
	v_cndmask_b32_e32 v9, 0, v5, vcc
	v_fmac_f32_e32 v9, 0x41549a78, v8
	v_exp_f32_e32 v9, v9
	v_cndmask_b32_e32 v8, 0, v6, vcc
	v_ldexp_f32 v9, v9, v8
	v_div_scale_f32 v8, s[14:15], v9, v9, 1.0
	v_rcp_f32_e32 v11, v8
	v_div_scale_f32 v10, vcc, 1.0, v9, 1.0
	v_fma_f32 v12, -v8, v11, 1.0
	v_fmac_f32_e32 v11, v12, v11
	v_mul_f32_e32 v12, v10, v11
	v_fma_f32 v13, -v8, v12, v10
	v_fmac_f32_e32 v12, v13, v11
	v_fma_f32 v8, -v8, v12, v10
	v_div_fmas_f32 v10, v8, v11, v12
	v_div_fixup_f32 v9, v10, v9, 1.0
	v_mul_f32_e32 v7, v9, v7
	v_cvt_f64_f32_e32 v[10:11], v7
	v_mul_f64 v[12:13], v[10:11], s[8:9]
	v_rndne_f64_e32 v[12:13], v[12:13]
	v_fma_f64 v[10:11], v[10:11], s[8:9], -v[12:13]
	v_cvt_f32_f64_e32 v7, v[10:11]
	v_cos_f32_e32 v10, v7
	v_sin_f32_e32 v7, v7
	v_add_co_u32_e32 v8, vcc, 0xffc00000, v2
	s_nop 1
	v_addc_co_u32_e32 v9, vcc, -1, v3, vcc
	global_store_dword v[8:9], v10, off
	global_store_dword v[2:3], v7, off
	v_lshl_add_u64 v[2:3], v[2:3], 0, s[4:5]
	s_andn2_b64 exec, exec, s[6:7]
	s_cbranch_execnz .LBB0_17

; __device__ __forceinline__ void tables_phase(const KArgs& a) {
;     ...
;     if (blockIdx.x == 0) { const float* lg = (const float*)a.in[6]; float* lb = (float*)(wsb + WS_LB);
;         for (int p = tid; p < 2 * 512; p += 512) { const int dir = p >> 9, c = p & 511;
;             float mx = -1e30f;
; #pragma unroll
;             for (int l = 0; l < DEPTH; ++l) mx = fmaxf(mx, lg[(dir * DEPTH + l) * 512 + c]);
;             float den = 0.f;
; #pragma unroll
;             for (int l = 0; l < DEPTH; ++l) den += __expf(lg[(dir * DEPTH + l) * 512 + c] - mx);
;             float cum = 0.f;
; #pragma unroll
;             for (int l = 0; l < DEPTH; ++l) { if (l > 0) cum += __expf(lg[(dir * DEPTH + l) * 512 + c] - mx) / den; lb[(dir * DEPTH + l) * 512 + c] = cum; } } }
.LBB0_21:
	v_and_or_b32 v4, v2, s7, v0
	v_ashrrev_i32_e32 v5, 31, v4
	v_lshlrev_b64 v[6:7], 2, v[4:5]
	v_lshl_add_u64 v[8:9], s[84:85], 0, v[6:7]
	v_lshl_add_u64 v[6:7], s[0:1], 0, v[6:7]
	global_load_dword v10, v[8:9], off
	global_load_dword v11, v[8:9], off offset:2048
	v_add_u32_e32 v1, 0x200, v1
	global_store_dword v[6:7], v3, off
	global_load_dword v6, v[8:9], off offset:2048
	v_cmp_lt_i32_e32 vcc, s6, v1
	s_or_b64 s[4:5], vcc, s[4:5]
	v_or_b32_e32 v4, 0x200, v4
	v_ashrrev_i32_e32 v5, 31, v4
	v_add_u32_e32 v2, 0x400, v2
	v_lshl_add_u64 v[4:5], v[4:5], 2, s[0:1]
	s_waitcnt vmcnt(0)
	v_max3_f32 v7, v10, s8, v11
	v_sub_f32_e32 v8, v10, v7
	v_sub_f32_e32 v9, v11, v7
	v_sub_f32_e32 v6, v6, v7
	v_mul_f32_e32 v7, 0x3fb8aa3b, v8
	v_mul_f32_e32 v8, 0x3fb8aa3b, v9
	v_exp_f32_e32 v7, v7
	v_mul_f32_e32 v6, 0x3fb8aa3b, v6
	v_exp_f32_e32 v8, v8
	v_exp_f32_e32 v6, v6
	v_add_f32_e32 v7, 0, v7
	v_add_f32_e32 v7, v8, v7
	v_div_scale_f32 v8, s[10:11], v7, v7, v6
	v_rcp_f32_e32 v9, v8
	v_div_scale_f32 v10, vcc, v6, v7, v6
	v_fma_f32 v11, -v8, v9, 1.0
	v_fmac_f32_e32 v9, v11, v9
	v_mul_f32_e32 v11, v10, v9
	v_fma_f32 v12, -v8, v11, v10
	v_fmac_f32_e32 v11, v12, v9
	v_fma_f32 v8, -v8, v11, v10
	v_div_fmas_f32 v8, v8, v9, v11
	v_div_fixup_f32 v6, v8, v7, v6
	v_add_f32_e32 v6, 0, v6
	global_store_dword v[4:5], v6, off
	s_andn2_b64 exec, exec, s[4:5]
	s_cbranch_execnz .LBB0_21

; __device__ __forceinline__ void convert_weights(const KArgs& a, int l, LAS unsigned char* lds) {
;     ...
;     for (int it = blockIdx.x; it < NIT; it += gridDim.x) {
;         int r = it, mode = 0, N, K, nkt; const float* w0; const float* w1 = nullptr; const float* gk = nullptr; bf16_t* WT;
;         if (r < I_IN) { w0 = (const float*)a.in[2] + (size_t)l * DM * DIN; N = DIN; K = DM; nkt = 32; gk = (const float*)a.in[13] + l * DM; WT = (bf16_t*)(wsb + WS_WIN); }
;         else if ((r -= I_IN) < I_QB) { w0 = (const float*)a.in[9] + (size_t)l * 512 * 1536; N = 1536; K = 512; nkt = 8; mode = 1; WT = (bf16_t*)(wsb + WS_WQB); }
;         else if ((r -= I_QB) < I_KVB) { w0 = (const float*)a.in[11] + (size_t)l * 512 * 2048; N = 2048; K = 512; nkt = 8; WT = (bf16_t*)(wsb + WS_WKVB); }
;         else if ((r -= I_KVB) < I_OUT) { w0 = (const float*)a.in[12] + (size_t)l * DM * DM; N = DM; K = DM; nkt = 32; WT = (bf16_t*)(wsb + WS_WOUT); }
;         else if ((r -= I_OUT) < I_13) { w0 = (const float*)a.in[15] + (size_t)l * DM * DFF; w1 = (const float*)a.in[16] + (size_t)l * DM * DFF; N = DFF; K = DM; nkt = 32; mode = 2; gk = (const float*)a.in[14] + l * DM; WT = (bf16_t*)(wsb + WS_W13); }
;         else { r -= I_13; w0 = (const float*)a.in[17] + (size_t)l * DFF * DM; N = DM; K = DFF; nkt = 88; WT = (bf16_t*)(wsb + WS_W2); }
;         const int kt = r % nkt, rt = r / nkt, r0 = rt * 64, k0 = kt * 64;
;         __syncthreads();
;         if (mode == 1) {
; #pragma unroll
;             for (int e = 0; e < 8; ++e) { const int idx = tid + 512 * e, rl = idx & 63, kl = idx >> 6, rr = r0 + rl, k = k0 + kl;
;                 const int hh = rr / 192, ee = rr % 192; const int col = ee < 128 ? hh * 192 + ee : hh * 192 + 128 + ((ee - 128) & 1) * 32 + ((ee - 128) >> 1);
;                 tile[kl * 65 + rl] = w0[(size_t)k * N + col]; }
;         } else {
; #pragma unroll
;             for (int e = 0; e < 2; ++e) { const int idx = tid + 512 * e, r4 = (idx & 15) * 4, kl = idx >> 4, rr = r0 + r4, k = k0 + kl;
;                 f32x4 v = {0.f, 0.f, 0.f, 0.f};
;                 if (mode == 0) { if (rr < N) v = *(const f32x4*)(w0 + (size_t)k * N + rr); }
;                 else { const int g = rr >> 5, n = (rr >> 4) & 1, i = rr & 15; v = *(const f32x4*)((n ? w1 : w0) + (size_t)k * N + 16 * g + i); }
;                 if (gk) v = v * gk[k];
.LBB0_25:
	s_waitcnt lgkmcnt(0)
	s_barrier
	ds_read2_b32 v[2:3], v17 offset1:65
	ds_read2_b32 v[4:5], v17 offset0:130 offset1:195
	s_add_i32 s39, s39, s70
	s_waitcnt lgkmcnt(0)
	v_bfe_u32 v1, v2, 16, 1
	v_add3_u32 v1, v2, v1, s37
	v_bfe_u32 v2, v3, 16, 1
	v_lshrrev_b32_e32 v1, 16, v1
	v_add3_u32 v2, v3, v2, s37
	v_and_or_b32 v2, v2, s38, v1
	v_bfe_u32 v1, v4, 16, 1
	v_add3_u32 v1, v4, v1, s37
	v_add_u32_e32 v4, 0x400, v17
	ds_read2_b32 v[10:11], v4 offset0:4 offset1:69
	v_bfe_u32 v3, v5, 16, 1
	ds_read2_b32 v[12:13], v4 offset0:134 offset1:199
	v_lshrrev_b32_e32 v1, 16, v1
	v_add3_u32 v3, v5, v3, s37
	v_and_or_b32 v3, v3, s38, v1
	s_waitcnt lgkmcnt(0)
	v_bfe_u32 v1, v10, 16, 1
	v_add3_u32 v1, v10, v1, s37
	v_bfe_u32 v4, v11, 16, 1
	v_lshrrev_b32_e32 v1, 16, v1
	v_add3_u32 v4, v11, v4, s37
	v_and_or_b32 v4, v4, s38, v1
	v_bfe_u32 v1, v12, 16, 1
	v_add3_u32 v1, v12, v1, s37
	v_bfe_u32 v5, v13, 16, 1
	v_lshrrev_b32_e32 v1, 16, v1
	v_add3_u32 v5, v13, v5, s37
	v_and_or_b32 v5, v5, s38, v1
	v_add_u32_e32 v1, s23, v16
	v_ashrrev_i32_e32 v7, 31, v1
	v_mul_lo_u32 v7, s14, v7
	v_mul_lo_u32 v9, s15, v1
	v_mad_u64_u32 v[10:11], s[14:15], s14, v1, 0
	v_add3_u32 v11, v11, v7, v9
	v_lshl_add_u64 v[10:11], v[10:11], 1, s[18:19]
	s_ashr_i32 s23, s22, 31
	v_lshl_add_u64 v[10:11], s[22:23], 1, v[10:11]
	v_mov_b32_e32 v9, v0
	v_lshl_add_u64 v[10:11], v[10:11], 0, v[8:9]
	s_cmpk_lt_i32 s39, 0x3140
	global_store_dwordx4 v[10:11], v[2:5], off
	s_cbranch_scc0 .LBB0_56

; __device__ __forceinline__ unsigned cvt_pk_bf16(float lo, float hi) { f32x2 v = {lo, hi}; bf16x2_t b = __builtin_convertvector(v, bf16x2_t); return __builtin_bit_cast(unsigned, b); }
; __device__ __forceinline__ int opaque_tid() { int t = threadIdx.x; asm volatile("" : "+v"(t)); return t; }
; __device__ __forceinline__ void cast_rows_bf16(const float* src, bf16_t* dst, float* rsq) {
;     const int tid = opaque_tid(), lane = tid & 63, gw = blockIdx.x * 8 + (tid >> 6), ngw = gridDim.x * 8;
;     for (int m = gw; m < M; m += ngw) {
;         const f32x4* xr = (const f32x4*)(src + (size_t)m * DM) + lane;
;         f32x4 v[8]; float s = 0.f;
; #pragma unroll
;         for (int j = 0; j < 8; ++j) { v[j] = xr[64 * j]; s += (v[j][0] * v[j][0] + v[j][1] * v[j][1]) + (v[j][2] * v[j][2] + v[j][3] * v[j][3]); }
;         s = wave_sum(s);
;         if (lane == 0) rsq[m] = s;
;         u32x2* o8 = (u32x2*)(dst + (size_t)m * DM) + lane;
; #pragma unroll
;         for (int j = 0; j < 8; ++j) { u32x2 w; w.x = cvt_pk_bf16(v[j][0], v[j][1]); w.y = cvt_pk_bf16(v[j][2], v[j][3]); o8[64 * j] = w; }
;     }
; }
.LBB0_58:
	s_or_b64 exec, exec, s[4:5]
	v_cvt_pk_bf16_f32 v0, v0, v1
	v_cvt_pk_bf16_f32 v1, v2, v3
	global_store_dwordx2 v[38:39], v[0:1], off
	v_cvt_pk_bf16_f32 v0, v4, v5
	v_cvt_pk_bf16_f32 v1, v6, v7
	global_store_dwordx2 v[38:39], v[0:1], off offset:512
	v_cvt_pk_bf16_f32 v0, v8, v9
	v_cvt_pk_bf16_f32 v1, v10, v11
	global_store_dwordx2 v[38:39], v[0:1], off offset:1024
	v_cvt_pk_bf16_f32 v0, v12, v13
	v_cvt_pk_bf16_f32 v1, v14, v15
	global_store_dwordx2 v[38:39], v[0:1], off offset:1536
	v_cvt_pk_bf16_f32 v0, v16, v17
	v_cvt_pk_bf16_f32 v1, v18, v19
	global_store_dwordx2 v[38:39], v[0:1], off offset:2048
	v_cvt_pk_bf16_f32 v0, v20, v21
	v_cvt_pk_bf16_f32 v1, v22, v23
	global_store_dwordx2 v[38:39], v[0:1], off offset:2560
	v_cvt_pk_bf16_f32 v0, v24, v25
	v_cvt_pk_bf16_f32 v1, v26, v27
	v_add_u32_e32 v32, s46, v32
	global_store_dwordx2 v[38:39], v[0:1], off offset:3072
	v_cvt_pk_bf16_f32 v0, v28, v29
	v_cvt_pk_bf16_f32 v1, v30, v31
	v_cmp_lt_i32_e64 s[4:5], s12, v32
	global_store_dwordx2 v[38:39], v[0:1], off offset:3584
	v_lshl_add_u64 v[34:35], v[34:35], 0, s[2:3]
	v_lshl_add_u64 v[36:37], v[36:37], 0, s[6:7]
	s_or_b64 s[10:11], s[4:5], s[10:11]
	v_lshl_add_u64 v[38:39], v[38:39], 0, s[8:9]
	s_andn2_b64 exec, exec, s[10:11]
	s_cbranch_execz .LBB0_61
.LBB0_59:
	global_load_dwordx4 v[0:3], v[36:37], off offset:-4096
	global_load_dwordx4 v[4:7], v[36:37], off offset:-3072
	global_load_dwordx4 v[8:11], v[36:37], off offset:-2048
	global_load_dwordx4 v[12:15], v[36:37], off offset:-1024
	global_load_dwordx4 v[16:19], v[36:37], off
	global_load_dwordx4 v[20:23], v[36:37], off offset:1024
	global_load_dwordx4 v[24:27], v[36:37], off offset:2048
	global_load_dwordx4 v[28:31], v[36:37], off offset:3072
	s_waitcnt vmcnt(0)
	v_mul_f32_e32 v33, v1, v1
	s_waitcnt lgkmcnt(0)
	v_mul_f32_e32 v47, v3, v3
	v_mul_f32_e32 v48, v5, v5
	v_mul_f32_e32 v49, v7, v7
	v_mul_f32_e32 v50, v9, v9
	v_mul_f32_e32 v51, v11, v11
	v_fmac_f32_e32 v33, v0, v0
	v_fmac_f32_e32 v47, v2, v2
	v_fmac_f32_e32 v48, v4, v4
	v_fmac_f32_e32 v49, v6, v6
	v_mul_f32_e32 v52, v13, v13
	v_mul_f32_e32 v53, v15, v15
	v_fmac_f32_e32 v50, v8, v8
	v_fmac_f32_e32 v51, v10, v10
	v_add_f32_e32 v33, v33, v47
	v_add_f32_e32 v47, v48, v49
	v_mul_f32_e32 v54, v17, v17
	v_mul_f32_e32 v55, v19, v19
	v_fmac_f32_e32 v52, v12, v12
	v_fmac_f32_e32 v53, v14, v14
	v_add_f32_e32 v48, v50, v51
	v_add_f32_e32 v33, v33, v47
	v_mul_f32_e32 v56, v21, v21
	v_mul_f32_e32 v57, v23, v23
	v_fmac_f32_e32 v54, v16, v16
	v_fmac_f32_e32 v55, v18, v18
	v_add_f32_e32 v49, v52, v53
	v_add_f32_e32 v33, v33, v48
	v_mul_f32_e32 v58, v25, v25
	v_mul_f32_e32 v59, v27, v27
	v_fmac_f32_e32 v56, v20, v20
	v_fmac_f32_e32 v57, v22, v22
	v_add_f32_e32 v50, v54, v55
	v_add_f32_e32 v33, v33, v49
	v_mul_f32_e32 v60, v29, v29
	v_mul_f32_e32 v61, v31, v31
	v_fmac_f32_e32 v58, v24, v24
	v_fmac_f32_e32 v59, v26, v26
	v_add_f32_e32 v51, v56, v57
	v_add_f32_e32 v33, v33, v50
	v_fmac_f32_e32 v60, v28, v28
	v_fmac_f32_e32 v61, v30, v30
	v_add_f32_e32 v52, v58, v59
	v_add_f32_e32 v33, v33, v51
	v_add_f32_e32 v33, v33, v52
	v_add_f32_e32 v47, v60, v61
	v_add_f32_e32 v33, v33, v47
	ds_bpermute_b32 v47, v41, v33
	s_waitcnt lgkmcnt(0)
	v_add_f32_e32 v33, v33, v47
	ds_bpermute_b32 v47, v42, v33
	s_waitcnt lgkmcnt(0)
	v_add_f32_e32 v33, v33, v47
	ds_bpermute_b32 v47, v43, v33
	s_waitcnt lgkmcnt(0)
	v_add_f32_e32 v33, v33, v47
	ds_bpermute_b32 v47, v44, v33
	s_waitcnt lgkmcnt(0)
	v_add_f32_e32 v33, v33, v47
	ds_bpermute_b32 v47, v45, v33
	s_waitcnt lgkmcnt(0)
	v_add_f32_e32 v33, v33, v47
	ds_bpermute_b32 v47, v46, v33
	s_and_saveexec_b64 s[4:5], vcc
	s_cbranch_execz .LBB0_58
	s_waitcnt lgkmcnt(0)
	v_add_f32_e32 v33, v33, v47
	global_store_dword v[34:35], v33, off
	s_branch .LBB0_58

; __device__ __forceinline__ unsigned xb_ld(unsigned* p)              { return __hip_atomic_load(p, __ATOMIC_RELAXED, __HIP_MEMORY_SCOPE_AGENT); }
; __device__ __forceinline__ void xcd_barrier_complete(unsigned* bar, unsigned x, unsigned& nloc, unsigned& nx) {
;     const unsigned G = gridDim.x * gridDim.y * gridDim.z;
;     unsigned sum, cnt, mine, sp = 0u;
;     for (;;) {
;         sum = 0u; cnt = 0u; mine = 0u;
; #pragma unroll
;         for (unsigned j = 0; j < 16; ++j) { const unsigned c = xb_ld(&bar[XB_XCNT(j)]); sum += c; cnt += (c > 0u) ? 1u : 0u; mine = (j == x) ? c : mine; }
;         if (sum == G) break;
;         __builtin_amdgcn_s_sleep(1);
;         if ((++sp & 255u) == 0u) { if (xb_ld(&bar[XB_TMO])) break; if (sp > XB_SPIN_CAP) { atomicAdd(&bar[XB_TMO], 1u); break; } }
;     }
;     nloc = mine > 0u ? mine : 1u; nx = cnt > 0u ? cnt : 1u;
; }
.LBB0_66:
	global_load_dword v48, v[0:1], off sc1
	global_load_dword v32, v[2:3], off sc1
	global_load_dword v33, v[4:5], off sc1
	global_load_dword v34, v[6:7], off sc1
	global_load_dword v35, v[8:9], off sc1
	global_load_dword v36, v[10:11], off sc1
	global_load_dword v37, v[12:13], off sc1
	global_load_dword v38, v[14:15], off sc1
	global_load_dword v39, v[16:17], off sc1
	global_load_dword v41, v[18:19], off sc1
	global_load_dword v42, v[20:21], off sc1
	global_load_dword v43, v[22:23], off sc1
	global_load_dword v44, v[24:25], off sc1
	global_load_dword v45, v[26:27], off sc1
	global_load_dword v46, v[28:29], off sc1
	global_load_dword v47, v[30:31], off sc1
	s_or_b64 s[12:13], s[12:13], exec
	s_or_b64 s[10:11], s[10:11], exec
	s_waitcnt vmcnt(0) lgkmcnt(0)
	v_add_u32_e32 v49, v32, v48
	v_add_u32_e32 v49, v49, v33
	v_add_u32_e32 v49, v49, v34
	v_add_u32_e32 v49, v49, v35
	v_add_u32_e32 v49, v49, v36
	v_add_u32_e32 v49, v49, v37
	v_add_u32_e32 v49, v49, v38
	v_add_u32_e32 v49, v49, v39
	v_add_u32_e32 v49, v49, v41
	v_add_u32_e32 v49, v49, v42
	v_add_u32_e32 v49, v49, v43
	v_add_u32_e32 v49, v49, v44
	v_add_u32_e32 v49, v49, v45
	v_add_u32_e32 v49, v49, v46
	v_add_u32_e32 v49, v49, v47
	v_cmp_ne_u32_e32 vcc, s24, v49
	s_and_saveexec_b64 s[14:15], vcc
	s_cbranch_execz .LBB0_65
	s_and_b32 s18, s25, 0xff
	s_mov_b64 s[16:17], -1
	s_cmp_eq_u32 s18, 0
	s_mov_b64 s[20:21], -1
	s_mov_b64 s[18:19], -1
	s_sleep 1
	s_cbranch_scc1 .LBB0_69
	s_and_saveexec_b64 s[22:23], s[20:21]
	s_cbranch_execz .LBB0_64
	s_branch .LBB0_72
.LBB0_69:
	v_mov_b64_e32 v[50:51], s[4:5]
	global_load_dword v49, v[50:51], off sc1
	s_mov_b64 s[20:21], 0
	s_waitcnt vmcnt(0) lgkmcnt(0)
	v_cmp_eq_u32_e32 vcc, 0, v49
	s_and_saveexec_b64 s[22:23], vcc
	s_cmp_lt_u32 s25, 0x40001
	s_cselect_b64 s[20:21], -1, 0
	s_xor_b64 s[18:19], exec, -1
	s_and_b64 s[20:21], s[20:21], exec
	s_or_b64 exec, exec, s[22:23]
	s_and_saveexec_b64 s[22:23], s[20:21]
	s_cbranch_execz .LBB0_64

; __device__ __forceinline__ unsigned xb_ld(unsigned* p)              { return __hip_atomic_load(p, __ATOMIC_RELAXED, __HIP_MEMORY_SCOPE_AGENT); }
; __device__ __forceinline__ unsigned xb_add(unsigned* p, unsigned v) { return __hip_atomic_fetch_add(p, v, __ATOMIC_RELAXED, __HIP_MEMORY_SCOPE_AGENT); }
; #define XB_SPIN(cond, bar) do { unsigned _sp = 0; while (cond) { __builtin_amdgcn_s_sleep(1); \
;     if ((++_sp & 255u) == 0u) { if (xb_ld(&(bar)[XB_TMO])) break; if (_sp > XB_SPIN_CAP) { atomicAdd(&(bar)[XB_TMO], 1u); break; } } } } while (0)
; __device__ __forceinline__ void xcd_barrier(const XcdBarrier& b) {
;     asm volatile("s_waitcnt vmcnt(0)" ::: "memory");
;     __syncthreads();
;     if (threadIdx.x == 0) {
;         unsigned* bar = b.bar;
;         __builtin_amdgcn_s_waitcnt(0);
;         unsigned nloc = b.st[0], nx = b.st[1];
;         if (nloc == 0u) { xcd_barrier_complete(bar, b.x, nloc, nx); b.st[0] = nloc; b.st[1] = nx; }
;         const unsigned old = xb_add(&bar[XB_XSUB(b.x)], 1u);
;         const unsigned gen = old / nloc;
;         if (old + 1u == (gen + 1u) * nloc) {
;             __builtin_amdgcn_fence(__ATOMIC_RELEASE, "agent");
;             asm volatile("s_waitcnt vmcnt(0)" ::: "memory");
;             const unsigned og = xb_add(&bar[XB_TOP], 1u);
;             const unsigned tg = og / nx;
;             if (og + 1u == (tg + 1u) * nx) xb_add(&bar[XB_TOPGEN], 1u);
;             else XB_SPIN(xb_ld(&bar[XB_TOPGEN]) == tg, bar);
;             __builtin_amdgcn_fence(__ATOMIC_ACQUIRE, "agent");
;             xb_add(&bar[XB_XGEN(b.x)], 1u);
;             asm volatile("s_waitcnt vmcnt(0)" ::: "memory");
;         } else {
;             XB_SPIN(xb_ld(&bar[XB_XGEN(b.x)]) == gen, bar);
.LBB0_76:
	s_lshl_b32 s4, s36, 8
	s_add_u32 s4, s2, s4
	s_addc_u32 s5, s3, 0
	v_mov_b32_e32 v1, s4
	v_add_co_u32_e32 v4, vcc, 0x3e301000, v1
	v_mov_b32_e32 v1, s5
	s_nop 0
	v_addc_co_u32_e32 v5, vcc, 0, v1, vcc
	v_mov_b32_e32 v1, 1
	flat_atomic_add v1, v[4:5], v1 offset:1024 sc0
	v_cvt_f32_u32_e32 v3, v2
	v_sub_u32_e32 v4, 0, v2
	s_add_u32 s27, s4, 0x3e300000
	s_addc_u32 s26, s5, 0
	v_rcp_iflag_f32_e32 v3, v3
	s_nop 0
	v_mul_f32_e32 v3, 0x4f7ffffe, v3
	v_cvt_u32_f32_e32 v3, v3
	v_mul_lo_u32 v4, v4, v3
	v_mul_hi_u32 v4, v3, v4
	v_add_u32_e32 v3, v3, v4
	s_waitcnt vmcnt(0) lgkmcnt(0)
	v_mul_hi_u32 v3, v1, v3
	v_mul_lo_u32 v5, v3, v2
	v_add_u32_e32 v4, 1, v1
	v_sub_u32_e32 v1, v1, v5
	v_add_u32_e32 v6, 1, v3
	v_cmp_ge_u32_e32 vcc, v1, v2
	v_sub_u32_e32 v5, v1, v2
	s_nop 0
	v_cndmask_b32_e32 v3, v3, v6, vcc
	v_cndmask_b32_e32 v1, v1, v5, vcc
	v_add_u32_e32 v5, 1, v3
	v_cmp_ge_u32_e32 vcc, v1, v2
	s_nop 1
	v_cndmask_b32_e32 v1, v3, v5, vcc
	v_mad_u64_u32 v[2:3], s[4:5], v2, v1, v[2:3]
	v_cmp_ne_u32_e32 vcc, v4, v2
	s_and_saveexec_b64 s[4:5], vcc
	s_xor_b64 s[4:5], exec, s[4:5]
	s_cbranch_execz .LBB0_89
	v_mov_b32_e32 v0, s27
	v_add_co_u32_e32 v2, vcc, 0x2000, v0
	v_mov_b32_e32 v0, s26
	s_nop 0
	v_addc_co_u32_e32 v3, vcc, 0, v0, vcc
	global_load_dword v0, v[2:3], off offset:1024 sc1
	s_add_u32 s10, s27, 0x2400
	s_addc_u32 s11, s26, 0
	s_waitcnt vmcnt(0) lgkmcnt(0)
	v_cmp_eq_u32_e32 vcc, v0, v1
	s_and_saveexec_b64 s[6:7], vcc
	s_cbranch_execz .LBB0_88
	s_add_u32 s8, s2, 0x3e300200
	s_addc_u32 s9, s3, 0
	s_mov_b32 s28, 1
	s_mov_b64 s[12:13], 0
	s_branch .LBB0_80

; __device__ __forceinline__ unsigned xb_ld(unsigned* p)              { return __hip_atomic_load(p, __ATOMIC_RELAXED, __HIP_MEMORY_SCOPE_AGENT); }
; #define XB_SPIN(cond, bar) do { unsigned _sp = 0; while (cond) { __builtin_amdgcn_s_sleep(1); \
;     if ((++_sp & 255u) == 0u) { if (xb_ld(&(bar)[XB_TMO])) break; if (_sp > XB_SPIN_CAP) { atomicAdd(&(bar)[XB_TMO], 1u); break; } } } } while (0)
; __device__ __forceinline__ void xcd_barrier(const XcdBarrier& b) {
;     ...
;             XB_SPIN(xb_ld(&bar[XB_XGEN(b.x)]) == gen, bar);
.LBB0_80:
	s_and_b32 s20, s28, 0xff
	s_mov_b64 s[18:19], -1
	s_cmp_lg_u32 s20, 0
	s_mov_b64 s[20:21], -1
	s_sleep 1
	s_cbranch_scc1 .LBB0_84
	v_mov_b64_e32 v[2:3], s[8:9]
	global_load_dword v0, v[2:3], off sc1
	s_mov_b64 s[20:21], 0
	s_mov_b64 s[22:23], -1
	s_waitcnt vmcnt(0) lgkmcnt(0)
	v_cmp_eq_u32_e32 vcc, 0, v0
	s_and_saveexec_b64 s[24:25], vcc
	s_cmp_lt_u32 s28, 0x40001
	s_cselect_b64 s[20:21], -1, 0
	s_xor_b64 s[22:23], exec, -1
	s_and_b64 s[20:21], s[20:21], exec
	s_or_b64 exec, exec, s[24:25]
.LBB0_84:
	s_andn2_b64 s[16:17], s[16:17], exec
	s_and_b64 s[22:23], s[22:23], exec
	s_or_b64 s[16:17], s[16:17], s[22:23]
	s_and_saveexec_b64 s[22:23], s[20:21]
	s_cbranch_execz .LBB0_79
	v_mov_b64_e32 v[2:3], s[10:11]
	global_load_dword v0, v[2:3], off sc1
	s_add_i32 s28, s28, 1
	s_or_b64 s[16:17], s[16:17], exec
	s_waitcnt vmcnt(0) lgkmcnt(0)
	v_cmp_ne_u32_e32 vcc, v0, v1
	s_orn2_b64 s[18:19], vcc, exec
	s_branch .LBB0_79

; __device__ __forceinline__ unsigned xb_ld(unsigned* p)              { return __hip_atomic_load(p, __ATOMIC_RELAXED, __HIP_MEMORY_SCOPE_AGENT); }
; __device__ __forceinline__ unsigned xb_add(unsigned* p, unsigned v) { return __hip_atomic_fetch_add(p, v, __ATOMIC_RELAXED, __HIP_MEMORY_SCOPE_AGENT); }
; #define XB_SPIN(cond, bar) do { unsigned _sp = 0; while (cond) { __builtin_amdgcn_s_sleep(1); \
;     if ((++_sp & 255u) == 0u) { if (xb_ld(&(bar)[XB_TMO])) break; if (_sp > XB_SPIN_CAP) { atomicAdd(&(bar)[XB_TMO], 1u); break; } } } } while (0)
; __device__ __forceinline__ void xcd_barrier(const XcdBarrier& b) {
;     ...
;         if (old + 1u == (gen + 1u) * nloc) {
;             __builtin_amdgcn_fence(__ATOMIC_RELEASE, "agent");
;             asm volatile("s_waitcnt vmcnt(0)" ::: "memory");
;             const unsigned og = xb_add(&bar[XB_TOP], 1u);
;             const unsigned tg = og / nx;
;             if (og + 1u == (tg + 1u) * nx) xb_add(&bar[XB_TOPGEN], 1u);
;             else XB_SPIN(xb_ld(&bar[XB_TOPGEN]) == tg, bar);
.LBB0_89:
	s_andn2_saveexec_b64 s[4:5], s[4:5]
	s_cbranch_execz .LBB0_105
	v_mov_b32_e32 v1, s2
	v_add_co_u32_e32 v2, vcc, 0x3e303000, v1
	v_mov_b32_e32 v1, s3
	buffer_wbl2 sc1
	s_waitcnt vmcnt(0)
	v_addc_co_u32_e32 v3, vcc, 0, v1, vcc
	v_mov_b32_e32 v1, 1
	flat_atomic_add v1, v[2:3], v1 offset:1024 sc0
	v_cvt_f32_u32_e32 v2, v0
	v_sub_u32_e32 v3, 0, v0
	s_add_u32 s4, s2, 0x3e303500
	s_addc_u32 s5, s3, 0
	v_rcp_iflag_f32_e32 v2, v2
	s_mov_b64 s[8:9], -1
	v_mul_f32_e32 v2, 0x4f7ffffe, v2
	v_cvt_u32_f32_e32 v2, v2
	v_mul_lo_u32 v3, v3, v2
	v_mul_hi_u32 v3, v2, v3
	v_add_u32_e32 v2, v2, v3
	s_waitcnt vmcnt(0) lgkmcnt(0)
	v_mul_hi_u32 v2, v1, v2
	v_mul_lo_u32 v4, v2, v0
	v_add_u32_e32 v3, 1, v1
	v_sub_u32_e32 v1, v1, v4
	v_add_u32_e32 v5, 1, v2
	v_cmp_ge_u32_e32 vcc, v1, v0
	v_sub_u32_e32 v4, v1, v0
	s_nop 0
	v_cndmask_b32_e32 v2, v2, v5, vcc
	v_cndmask_b32_e32 v1, v1, v4, vcc
	v_add_u32_e32 v4, 1, v2
	v_cmp_ge_u32_e32 vcc, v1, v0
	s_nop 1
	v_cndmask_b32_e32 v2, v2, v4, vcc
	v_mad_u64_u32 v[0:1], s[6:7], v0, v2, v[0:1]
	v_cmp_ne_u32_e32 vcc, v3, v0
	v_mov_b64_e32 v[0:1], s[4:5]
	s_and_saveexec_b64 s[6:7], vcc
	s_cbranch_execz .LBB0_102
	v_mov_b64_e32 v[0:1], s[4:5]
	global_load_dword v0, v[0:1], off sc1
	s_mov_b64 s[12:13], 0
	s_waitcnt vmcnt(0) lgkmcnt(0)
	v_cmp_eq_u32_e32 vcc, v0, v2
	s_and_saveexec_b64 s[10:11], vcc
	s_cbranch_execz .LBB0_101
	s_add_u32 s8, s2, 0x3e300200
	s_addc_u32 s9, s3, 0
	s_mov_b32 s22, 1
	s_mov_b64 s[2:3], 0
	s_branch .LBB0_94

; __device__ __forceinline__ unsigned xb_ld(unsigned* p)              { return __hip_atomic_load(p, __ATOMIC_RELAXED, __HIP_MEMORY_SCOPE_AGENT); }
; #define XB_SPIN(cond, bar) do { unsigned _sp = 0; while (cond) { __builtin_amdgcn_s_sleep(1); \
;     if ((++_sp & 255u) == 0u) { if (xb_ld(&(bar)[XB_TMO])) break; if (_sp > XB_SPIN_CAP) { atomicAdd(&(bar)[XB_TMO], 1u); break; } } } } while (0)
; __device__ __forceinline__ void xcd_barrier(const XcdBarrier& b) {
;     ...
;             else XB_SPIN(xb_ld(&bar[XB_TOPGEN]) == tg, bar);
.LBB0_96:
	v_mov_b64_e32 v[0:1], s[8:9]
	global_load_dword v0, v[0:1], off sc1
	s_mov_b64 s[16:17], 0
	s_mov_b64 s[14:15], -1
	s_waitcnt vmcnt(0) lgkmcnt(0)
	v_cmp_eq_u32_e32 vcc, 0, v0
	s_and_saveexec_b64 s[18:19], vcc
	s_cmp_lt_u32 s22, 0x40001
	s_cselect_b64 s[16:17], -1, 0
	s_xor_b64 s[14:15], exec, -1
	s_and_b64 s[16:17], s[16:17], exec
	s_or_b64 exec, exec, s[18:19]
	s_mov_b64 s[18:19], -1
	s_and_saveexec_b64 s[20:21], s[16:17]
	s_cbranch_execz .LBB0_93
.LBB0_99:
	v_mov_b64_e32 v[0:1], s[4:5]
	global_load_dword v0, v[0:1], off sc1
	s_add_i32 s22, s22, 1
	s_or_b64 s[14:15], s[14:15], exec
	s_waitcnt vmcnt(0) lgkmcnt(0)
	v_cmp_ne_u32_e32 vcc, v0, v2
	s_orn2_b64 s[18:19], vcc, exec
	s_branch .LBB0_93

; __device__ __forceinline__ void convert_weights(const KArgs& a, int l, LAS unsigned char* lds) {
;     ...
;     for (int it = blockIdx.x; it < NIT; it += gridDim.x) {
;         int r = it, mode = 0, N, K, nkt; const float* w0; const float* w1 = nullptr; const float* gk = nullptr; bf16_t* WT;
;         if (r < I_IN) { w0 = (const float*)a.in[2] + (size_t)l * DM * DIN; N = DIN; K = DM; nkt = 32; gk = (const float*)a.in[13] + l * DM; WT = (bf16_t*)(wsb + WS_WIN); }
;         else if ((r -= I_IN) < I_QB) { w0 = (const float*)a.in[9] + (size_t)l * 512 * 1536; N = 1536; K = 512; nkt = 8; mode = 1; WT = (bf16_t*)(wsb + WS_WQB); }
;         else if ((r -= I_QB) < I_KVB) { w0 = (const float*)a.in[11] + (size_t)l * 512 * 2048; N = 2048; K = 512; nkt = 8; WT = (bf16_t*)(wsb + WS_WKVB); }
;         else if ((r -= I_KVB) < I_OUT) { w0 = (const float*)a.in[12] + (size_t)l * DM * DM; N = DM; K = DM; nkt = 32; WT = (bf16_t*)(wsb + WS_WOUT); }
;         else if ((r -= I_OUT) < I_13) { w0 = (const float*)a.in[15] + (size_t)l * DM * DFF; w1 = (const float*)a.in[16] + (size_t)l * DM * DFF; N = DFF; K = DM; nkt = 32; mode = 2; gk = (const float*)a.in[14] + l * DM; WT = (bf16_t*)(wsb + WS_W13); }
;         else { r -= I_13; w0 = (const float*)a.in[17] + (size_t)l * DFF * DM; N = DM; K = DFF; nkt = 88; WT = (bf16_t*)(wsb + WS_W2); }
;         const int kt = r % nkt, rt = r / nkt, r0 = rt * 64, k0 = kt * 64;
;         __syncthreads();
;         if (mode == 1) {
; #pragma unroll
;             for (int e = 0; e < 8; ++e) { const int idx = tid + 512 * e, rl = idx & 63, kl = idx >> 6, rr = r0 + rl, k = k0 + kl;
;                 const int hh = rr / 192, ee = rr % 192; const int col = ee < 128 ? hh * 192 + ee : hh * 192 + 128 + ((ee - 128) & 1) * 32 + ((ee - 128) >> 1);
;                 tile[kl * 65 + rl] = w0[(size_t)k * N + col]; }
;         } else {
; #pragma unroll
;             for (int e = 0; e < 2; ++e) { const int idx = tid + 512 * e, r4 = (idx & 15) * 4, kl = idx >> 4, rr = r0 + r4, k = k0 + kl;
;                 f32x4 v = {0.f, 0.f, 0.f, 0.f};
;                 if (mode == 0) { if (rr < N) v = *(const f32x4*)(w0 + (size_t)k * N + rr); }
;                 else { const int g = rr >> 5, n = (rr >> 4) & 1, i = rr & 15; v = *(const f32x4*)((n ? w1 : w0) + (size_t)k * N + 16 * g + i); }
;                 if (gk) v = v * gk[k];
.LBB0_111:
	s_waitcnt lgkmcnt(0)
	s_barrier
	ds_read2_b32 v[0:1], v15 offset1:65
	ds_read2_b32 v[2:3], v15 offset0:130 offset1:195
	s_mov_b32 s22, 0xffff0000
	s_add_i32 s38, s38, s70
	s_waitcnt lgkmcnt(0)
	v_bfe_u32 v5, v0, 16, 1
	v_add3_u32 v0, v0, v5, s1
	v_bfe_u32 v5, v1, 16, 1
	v_lshrrev_b32_e32 v0, 16, v0
	v_add3_u32 v1, v1, v5, s1
	v_and_or_b32 v0, v1, s22, v0
	v_bfe_u32 v1, v2, 16, 1
	v_add3_u32 v1, v2, v1, s1
	v_add_u32_e32 v2, 0x400, v15
	ds_read2_b32 v[8:9], v2 offset0:4 offset1:69
	v_bfe_u32 v5, v3, 16, 1
	v_lshrrev_b32_e32 v1, 16, v1
	v_add3_u32 v3, v3, v5, s1
	ds_read2_b32 v[10:11], v2 offset0:134 offset1:199
	v_and_or_b32 v1, v3, s22, v1
	s_waitcnt lgkmcnt(0)
	v_bfe_u32 v3, v8, 16, 1
	v_add3_u32 v3, v8, v3, s1
	v_lshrrev_b32_e32 v2, 16, v3
	v_bfe_u32 v3, v9, 16, 1
	v_add3_u32 v3, v9, v3, s1
	v_and_or_b32 v2, v3, s22, v2
	v_bfe_u32 v3, v10, 16, 1
	v_add3_u32 v3, v10, v3, s1
	v_bfe_u32 v5, v11, 16, 1
	v_lshrrev_b32_e32 v3, 16, v3
	v_add3_u32 v5, v11, v5, s1
	v_and_or_b32 v3, v5, s22, v3
	v_add_u32_e32 v5, s29, v14
	v_ashrrev_i32_e32 v7, 31, v5
	v_mul_lo_u32 v7, s18, v7
	v_mul_lo_u32 v10, s19, v5
	v_mad_u64_u32 v[8:9], s[18:19], s18, v5, 0
	v_add3_u32 v9, v9, v7, v10
	v_lshl_add_u64 v[8:9], v[8:9], 1, s[20:21]
	s_ashr_i32 s29, s28, 31
	v_lshl_add_u64 v[8:9], s[28:29], 1, v[8:9]
	v_mov_b32_e32 v7, v113
	v_lshl_add_u64 v[8:9], v[8:9], 0, v[6:7]
	s_cmpk_lt_i32 s38, 0x3140
	global_store_dwordx4 v[8:9], v[0:3], off
	s_cbranch_scc0 .LBB0_142

; __device__ __forceinline__ int opaque_tid() { int t = threadIdx.x; asm volatile("" : "+v"(t)); return t; }
; __device__ __forceinline__ void reduce_slots(const float* slots, float* rsq) {
;     for (int row = blockIdx.x * 512 + opaque_tid(); row < M; row += gridDim.x * 512) {
;         const f32x4* s4 = (const f32x4*)(slots + (size_t)row * 32); float s = 0.f;
; #pragma unroll
;         for (int j = 0; j < 8; ++j) { const f32x4 v = s4[j]; s += (v[0] + v[1]) + (v[2] + v[3]); }
;         rsq[row] = s; }
; }
.LBB0_144:
	v_ashrrev_i32_e32 v1, 31, v0
	v_lshlrev_b64 v[2:3], 7, v[0:1]
	v_lshl_add_u64 v[30:31], s[6:7], 0, v[2:3]
	global_load_dwordx4 v[2:5], v[30:31], off
	global_load_dwordx4 v[6:9], v[30:31], off offset:16
	global_load_dwordx4 v[10:13], v[30:31], off offset:32
	global_load_dwordx4 v[14:17], v[30:31], off offset:48
	global_load_dwordx4 v[18:21], v[30:31], off offset:64
	global_load_dwordx4 v[22:25], v[30:31], off offset:80
	global_load_dwordx4 v[26:29], v[30:31], off offset:96
	s_nop 0
	global_load_dwordx4 v[30:33], v[30:31], off offset:112
	v_lshl_add_u64 v[34:35], v[0:1], 2, s[8:9]
	v_add_u32_e32 v0, s12, v0
	v_cmp_lt_i32_e32 vcc, s1, v0
	s_or_b64 s[10:11], vcc, s[10:11]
	s_waitcnt vmcnt(0) lgkmcnt(0)
	v_mov_b32_e32 v36, v2
	v_mov_b32_e32 v37, v6
	v_mov_b32_e32 v6, v3
	v_mov_b32_e32 v2, v4
	v_mov_b32_e32 v3, v8
	v_mov_b32_e32 v8, v5
	v_mov_b32_e32 v4, v11
	v_mov_b32_e32 v5, v12
	v_mov_b32_e32 v11, v13
	v_pk_add_f32 v[6:7], v[36:37], v[6:7]
	v_pk_add_f32 v[2:3], v[2:3], v[8:9]
	v_pk_add_f32 v[4:5], v[4:5], v[10:11]
	v_pk_add_f32 v[2:3], v[6:7], v[2:3]
	v_pk_add_f32 v[4:5], v[4:5], v[4:5] op_sel:[0,1] op_sel_hi:[1,0]
	v_add_f32_e32 v1, 0, v2
	v_add_f32_e32 v12, v14, v15
	v_add_f32_e32 v14, v16, v17
	v_mov_b32_e32 v17, v18
	v_mov_b32_e32 v13, v20
	v_mov_b32_e32 v15, v21
	v_mov_b32_e32 v5, v19
	v_add_f32_e32 v16, v1, v3
	v_mov_b32_e32 v20, v23
	v_mov_b32_e32 v21, v24
	v_mov_b32_e32 v23, v25
	v_pk_add_f32 v[8:9], v[12:13], v[14:15]
	v_pk_add_f32 v[2:3], v[16:17], v[4:5]
	v_pk_add_f32 v[10:11], v[20:21], v[22:23]
	v_pk_add_f32 v[2:3], v[2:3], v[8:9]
	v_pk_add_f32 v[6:7], v[10:11], v[10:11] op_sel:[0,1] op_sel_hi:[1,0]
	v_pk_add_f32 v[2:3], v[2:3], v[2:3] op_sel:[0,1] op_sel_hi:[1,0]
	v_add_f32_e32 v24, v26, v27
	v_add_f32_e32 v26, v28, v29
	v_mov_b32_e32 v25, v32
	v_mov_b32_e32 v27, v33
	v_mov_b32_e32 v7, v31
	v_mov_b32_e32 v3, v30
	v_pk_add_f32 v[12:13], v[24:25], v[26:27]
	v_pk_add_f32 v[2:3], v[2:3], v[6:7]
	s_nop 0
	v_pk_add_f32 v[2:3], v[2:3], v[12:13]
	s_nop 0
	v_add_f32_e32 v1, v2, v3
	global_store_dword v[34:35], v1, off
	s_andn2_b64 exec, exec, s[10:11]
	s_cbranch_execnz .LBB0_144

; __device__ __forceinline__ unsigned xb_ld(unsigned* p)              { return __hip_atomic_load(p, __ATOMIC_RELAXED, __HIP_MEMORY_SCOPE_AGENT); }
; __device__ __forceinline__ void xcd_barrier_complete(unsigned* bar, unsigned x, unsigned& nloc, unsigned& nx) {
;     const unsigned G = gridDim.x * gridDim.y * gridDim.z;
;     unsigned sum, cnt, mine, sp = 0u;
;     for (;;) {
;         sum = 0u; cnt = 0u; mine = 0u;
; #pragma unroll
;         for (unsigned j = 0; j < 16; ++j) { const unsigned c = xb_ld(&bar[XB_XCNT(j)]); sum += c; cnt += (c > 0u) ? 1u : 0u; mine = (j == x) ? c : mine; }
;         if (sum == G) break;
;         __builtin_amdgcn_s_sleep(1);
;         if ((++sp & 255u) == 0u) { if (xb_ld(&bar[XB_TMO])) break; if (sp > XB_SPIN_CAP) { atomicAdd(&bar[XB_TMO], 1u); break; } }
;     }
;     nloc = mine > 0u ? mine : 1u; nx = cnt > 0u ? cnt : 1u;
; }
.LBB0_150:
	s_waitcnt lgkmcnt(0)
	v_mov_b64_e32 v[0:1], s[6:7]
	v_mov_b64_e32 v[2:3], s[8:9]
	global_load_dword v0, v[0:1], off sc1
	v_mov_b64_e32 v[4:5], s[12:13]
	global_load_dword v1, v[2:3], off sc1
	v_mov_b64_e32 v[2:3], s[10:11]
	global_load_dword v2, v[2:3], off sc1
	v_mov_b64_e32 v[6:7], s[16:17]
	global_load_dword v3, v[4:5], off sc1
	v_mov_b64_e32 v[4:5], s[14:15]
	global_load_dword v4, v[4:5], off sc1
	v_mov_b64_e32 v[8:9], s[20:21]
	global_load_dword v5, v[6:7], off sc1
	v_mov_b64_e32 v[6:7], s[18:19]
	global_load_dword v6, v[6:7], off sc1
	v_mov_b64_e32 v[10:11], s[24:25]
	global_load_dword v7, v[8:9], off sc1
	v_mov_b64_e32 v[8:9], s[22:23]
	global_load_dword v8, v[8:9], off sc1
	v_mov_b64_e32 v[12:13], s[28:29]
	global_load_dword v9, v[10:11], off sc1
	v_mov_b64_e32 v[10:11], s[26:27]
	global_load_dword v10, v[10:11], off sc1
	v_mov_b64_e32 v[14:15], s[34:35]
	global_load_dword v11, v[12:13], off sc1
	v_mov_b64_e32 v[12:13], s[30:31]
	global_load_dword v12, v[12:13], off sc1
	v_mov_b64_e32 v[16:17], s[42:43]
	global_load_dword v13, v[14:15], off sc1
	v_mov_b64_e32 v[14:15], s[40:41]
	global_load_dword v14, v[14:15], off sc1
	v_readlane_b32 s52, v255, 5
	global_load_dword v15, v[16:17], off sc1
	s_or_b64 s[50:51], s[50:51], exec
	s_or_b64 s[48:49], s[48:49], exec
	s_waitcnt vmcnt(0) lgkmcnt(0)
	v_add_u32_e32 v16, v1, v0
	v_add_u32_e32 v16, v16, v2
	v_add_u32_e32 v16, v16, v3
	v_add_u32_e32 v16, v16, v4
	v_add_u32_e32 v16, v16, v5
	v_add_u32_e32 v16, v16, v6
	v_add_u32_e32 v16, v16, v7
	v_add_u32_e32 v16, v16, v8
	v_add_u32_e32 v16, v16, v9
	v_add_u32_e32 v16, v16, v10
	v_add_u32_e32 v16, v16, v11
	v_add_u32_e32 v16, v16, v12
	v_add_u32_e32 v16, v16, v13
	v_add_u32_e32 v16, v16, v14
	v_add_u32_e32 v16, v16, v15
	v_cmp_ne_u32_e32 vcc, s52, v16
	s_and_saveexec_b64 s[52:53], vcc
	s_cbranch_execz .LBB0_149
	s_and_b32 s56, s63, 0xff
	s_mov_b64 s[54:55], -1
	s_cmp_eq_u32 s56, 0
	s_mov_b64 s[58:59], -1
	s_mov_b64 s[56:57], -1
	s_sleep 1
	s_cbranch_scc1 .LBB0_153
	s_and_saveexec_b64 s[60:61], s[58:59]
	s_cbranch_execz .LBB0_148
	s_branch .LBB0_156
.LBB0_153:
	v_mov_b64_e32 v[16:17], s[4:5]
	global_load_dword v16, v[16:17], off sc1
	s_mov_b64 s[58:59], 0
	s_waitcnt vmcnt(0) lgkmcnt(0)
	v_cmp_eq_u32_e32 vcc, 0, v16
	s_and_saveexec_b64 s[60:61], vcc
	s_cmp_lt_u32 s63, 0x40001
	s_cselect_b64 s[58:59], -1, 0
	s_xor_b64 s[56:57], exec, -1
	s_and_b64 s[58:59], s[58:59], exec
	s_or_b64 exec, exec, s[60:61]
	s_and_saveexec_b64 s[60:61], s[58:59]
	s_cbranch_execz .LBB0_148

; __device__ __forceinline__ unsigned xb_ld(unsigned* p)              { return __hip_atomic_load(p, __ATOMIC_RELAXED, __HIP_MEMORY_SCOPE_AGENT); }
; __device__ __forceinline__ unsigned xb_add(unsigned* p, unsigned v) { return __hip_atomic_fetch_add(p, v, __ATOMIC_RELAXED, __HIP_MEMORY_SCOPE_AGENT); }
; #define XB_SPIN(cond, bar) do { unsigned _sp = 0; while (cond) { __builtin_amdgcn_s_sleep(1); \
;     if ((++_sp & 255u) == 0u) { if (xb_ld(&(bar)[XB_TMO])) break; if (_sp > XB_SPIN_CAP) { atomicAdd(&(bar)[XB_TMO], 1u); break; } } } } while (0)
; __device__ __forceinline__ void xcd_barrier(const XcdBarrier& b) {
;     asm volatile("s_waitcnt vmcnt(0)" ::: "memory");
;     __syncthreads();
;     if (threadIdx.x == 0) {
;         unsigned* bar = b.bar;
;         __builtin_amdgcn_s_waitcnt(0);
;         unsigned nloc = b.st[0], nx = b.st[1];
;         if (nloc == 0u) { xcd_barrier_complete(bar, b.x, nloc, nx); b.st[0] = nloc; b.st[1] = nx; }
;         const unsigned old = xb_add(&bar[XB_XSUB(b.x)], 1u);
;         const unsigned gen = old / nloc;
;         if (old + 1u == (gen + 1u) * nloc) {
;             __builtin_amdgcn_fence(__ATOMIC_RELEASE, "agent");
;             asm volatile("s_waitcnt vmcnt(0)" ::: "memory");
;             const unsigned og = xb_add(&bar[XB_TOP], 1u);
;             const unsigned tg = og / nx;
;             if (og + 1u == (tg + 1u) * nx) xb_add(&bar[XB_TOPGEN], 1u);
;             else XB_SPIN(xb_ld(&bar[XB_TOPGEN]) == tg, bar);
;             __builtin_amdgcn_fence(__ATOMIC_ACQUIRE, "agent");
;             xb_add(&bar[XB_XGEN(b.x)], 1u);
;             asm volatile("s_waitcnt vmcnt(0)" ::: "memory");
;         } else {
;             XB_SPIN(xb_ld(&bar[XB_XGEN(b.x)]) == gen, bar);
.LBB0_160:
	s_lshl_b32 s4, s62, 8
	s_add_u32 s4, s38, s4
	s_addc_u32 s5, s39, 0
	v_mov_b32_e32 v1, s4
	v_add_co_u32_e32 v4, vcc, 0x3e301000, v1
	v_mov_b32_e32 v1, s5
	s_nop 0
	v_addc_co_u32_e32 v5, vcc, 0, v1, vcc
	flat_atomic_add v1, v[4:5], v239 offset:1024 sc0
	v_cvt_f32_u32_e32 v3, v2
	v_sub_u32_e32 v4, 0, v2
	s_add_u32 s27, s4, 0x3e300000
	s_addc_u32 s26, s5, 0
	v_rcp_iflag_f32_e32 v3, v3
	s_nop 0
	v_mul_f32_e32 v3, 0x4f7ffffe, v3
	v_cvt_u32_f32_e32 v3, v3
	v_mul_lo_u32 v4, v4, v3
	v_mul_hi_u32 v4, v3, v4
	v_add_u32_e32 v3, v3, v4
	s_waitcnt vmcnt(0) lgkmcnt(0)
	v_mul_hi_u32 v3, v1, v3
	v_mul_lo_u32 v5, v3, v2
	v_add_u32_e32 v4, 1, v1
	v_sub_u32_e32 v1, v1, v5
	v_add_u32_e32 v6, 1, v3
	v_cmp_ge_u32_e32 vcc, v1, v2
	v_sub_u32_e32 v5, v1, v2
	s_nop 0
	v_cndmask_b32_e32 v3, v3, v6, vcc
	v_cndmask_b32_e32 v1, v1, v5, vcc
	v_add_u32_e32 v5, 1, v3
	v_cmp_ge_u32_e32 vcc, v1, v2
	s_nop 1
	v_cndmask_b32_e32 v1, v3, v5, vcc
	v_mad_u64_u32 v[2:3], s[4:5], v2, v1, v[2:3]
	v_cmp_ne_u32_e32 vcc, v4, v2
	s_and_saveexec_b64 s[4:5], vcc
	s_xor_b64 s[4:5], exec, s[4:5]
	s_cbranch_execz .LBB0_173
	v_mov_b32_e32 v0, s27
	v_add_co_u32_e32 v2, vcc, 0x2000, v0
	v_mov_b32_e32 v0, s26
	s_nop 0
	v_addc_co_u32_e32 v3, vcc, 0, v0, vcc
	global_load_dword v0, v[2:3], off offset:1024 sc1
	s_add_u32 s8, s27, 0x2400
	s_addc_u32 s9, s26, 0
	s_waitcnt vmcnt(0) lgkmcnt(0)
	v_cmp_eq_u32_e32 vcc, v0, v1
	s_and_saveexec_b64 s[6:7], vcc
	s_cbranch_execz .LBB0_172
	s_add_u32 s10, s38, 0x3e300200
	s_addc_u32 s11, s39, 0
	s_mov_b32 s28, 1
	s_mov_b64 s[12:13], 0
	s_branch .LBB0_164

; __device__ __forceinline__ unsigned xb_ld(unsigned* p)              { return __hip_atomic_load(p, __ATOMIC_RELAXED, __HIP_MEMORY_SCOPE_AGENT); }
; #define XB_SPIN(cond, bar) do { unsigned _sp = 0; while (cond) { __builtin_amdgcn_s_sleep(1); \
;     if ((++_sp & 255u) == 0u) { if (xb_ld(&(bar)[XB_TMO])) break; if (_sp > XB_SPIN_CAP) { atomicAdd(&(bar)[XB_TMO], 1u); break; } } } } while (0)
; __device__ __forceinline__ void xcd_barrier(const XcdBarrier& b) {
;     ...
;             XB_SPIN(xb_ld(&bar[XB_XGEN(b.x)]) == gen, bar);
.LBB0_164:
	s_and_b32 s20, s28, 0xff
	s_mov_b64 s[18:19], -1
	s_cmp_lg_u32 s20, 0
	s_mov_b64 s[20:21], -1
	s_sleep 1
	s_cbranch_scc1 .LBB0_168
	v_mov_b64_e32 v[2:3], s[10:11]
	global_load_dword v0, v[2:3], off sc1
	s_mov_b64 s[20:21], 0
	s_mov_b64 s[22:23], -1
	s_waitcnt vmcnt(0) lgkmcnt(0)
	v_cmp_eq_u32_e32 vcc, 0, v0
	s_and_saveexec_b64 s[24:25], vcc
	s_cmp_lt_u32 s28, 0x40001
	s_cselect_b64 s[20:21], -1, 0
	s_xor_b64 s[22:23], exec, -1
	s_and_b64 s[20:21], s[20:21], exec
	s_or_b64 exec, exec, s[24:25]
.LBB0_168:
	s_andn2_b64 s[16:17], s[16:17], exec
	s_and_b64 s[22:23], s[22:23], exec
	s_or_b64 s[16:17], s[16:17], s[22:23]
	s_and_saveexec_b64 s[22:23], s[20:21]
	s_cbranch_execz .LBB0_163
	v_mov_b64_e32 v[2:3], s[8:9]
	global_load_dword v0, v[2:3], off sc1
	s_add_i32 s28, s28, 1
	s_or_b64 s[16:17], s[16:17], exec
	s_waitcnt vmcnt(0) lgkmcnt(0)
	v_cmp_ne_u32_e32 vcc, v0, v1
	s_orn2_b64 s[18:19], vcc, exec
	s_branch .LBB0_163

; __device__ __forceinline__ unsigned xb_ld(unsigned* p)              { return __hip_atomic_load(p, __ATOMIC_RELAXED, __HIP_MEMORY_SCOPE_AGENT); }
; __device__ __forceinline__ unsigned xb_add(unsigned* p, unsigned v) { return __hip_atomic_fetch_add(p, v, __ATOMIC_RELAXED, __HIP_MEMORY_SCOPE_AGENT); }
; #define XB_SPIN(cond, bar) do { unsigned _sp = 0; while (cond) { __builtin_amdgcn_s_sleep(1); \
;     if ((++_sp & 255u) == 0u) { if (xb_ld(&(bar)[XB_TMO])) break; if (_sp > XB_SPIN_CAP) { atomicAdd(&(bar)[XB_TMO], 1u); break; } } } } while (0)
; __device__ __forceinline__ void xcd_barrier(const XcdBarrier& b) {
;     ...
;         if (old + 1u == (gen + 1u) * nloc) {
;             __builtin_amdgcn_fence(__ATOMIC_RELEASE, "agent");
;             asm volatile("s_waitcnt vmcnt(0)" ::: "memory");
;             const unsigned og = xb_add(&bar[XB_TOP], 1u);
;             const unsigned tg = og / nx;
;             if (og + 1u == (tg + 1u) * nx) xb_add(&bar[XB_TOPGEN], 1u);
;             else XB_SPIN(xb_ld(&bar[XB_TOPGEN]) == tg, bar);
.LBB0_173:
	s_andn2_saveexec_b64 s[4:5], s[4:5]
	s_cbranch_execz .LBB0_189
	v_mov_b32_e32 v1, s38
	v_add_co_u32_e32 v2, vcc, 0x3e303000, v1
	v_mov_b32_e32 v1, s39
	buffer_wbl2 sc1
	s_waitcnt vmcnt(0)
	v_addc_co_u32_e32 v3, vcc, 0, v1, vcc
	flat_atomic_add v1, v[2:3], v239 offset:1024 sc0
	v_cvt_f32_u32_e32 v2, v0
	v_sub_u32_e32 v3, 0, v0
	s_add_u32 s4, s38, 0x3e303500
	s_addc_u32 s5, s39, 0
	v_rcp_iflag_f32_e32 v2, v2
	s_mov_b64 s[8:9], -1
	v_mul_f32_e32 v2, 0x4f7ffffe, v2
	v_cvt_u32_f32_e32 v2, v2
	v_mul_lo_u32 v3, v3, v2
	v_mul_hi_u32 v3, v2, v3
	v_add_u32_e32 v2, v2, v3
	s_waitcnt vmcnt(0) lgkmcnt(0)
	v_mul_hi_u32 v2, v1, v2
	v_mul_lo_u32 v4, v2, v0
	v_add_u32_e32 v3, 1, v1
	v_sub_u32_e32 v1, v1, v4
	v_add_u32_e32 v5, 1, v2
	v_cmp_ge_u32_e32 vcc, v1, v0
	v_sub_u32_e32 v4, v1, v0
	s_nop 0
	v_cndmask_b32_e32 v2, v2, v5, vcc
	v_cndmask_b32_e32 v1, v1, v4, vcc
	v_add_u32_e32 v4, 1, v2
	v_cmp_ge_u32_e32 vcc, v1, v0
	s_nop 1
	v_cndmask_b32_e32 v2, v2, v4, vcc
	v_mad_u64_u32 v[0:1], s[6:7], v0, v2, v[0:1]
	v_cmp_ne_u32_e32 vcc, v3, v0
	v_mov_b64_e32 v[0:1], s[4:5]
	s_and_saveexec_b64 s[6:7], vcc
	s_cbranch_execz .LBB0_186
	v_mov_b64_e32 v[0:1], s[4:5]
	global_load_dword v0, v[0:1], off sc1
	s_mov_b64 s[12:13], 0
	s_waitcnt vmcnt(0) lgkmcnt(0)
	v_cmp_eq_u32_e32 vcc, v0, v2
	s_and_saveexec_b64 s[10:11], vcc
	s_cbranch_execz .LBB0_185
	s_add_u32 s8, s38, 0x3e300200
	s_addc_u32 s9, s39, 0
	s_mov_b32 s24, 1
	s_branch .LBB0_178

; __device__ __forceinline__ unsigned xb_ld(unsigned* p)              { return __hip_atomic_load(p, __ATOMIC_RELAXED, __HIP_MEMORY_SCOPE_AGENT); }
; #define XB_SPIN(cond, bar) do { unsigned _sp = 0; while (cond) { __builtin_amdgcn_s_sleep(1); \
;     if ((++_sp & 255u) == 0u) { if (xb_ld(&(bar)[XB_TMO])) break; if (_sp > XB_SPIN_CAP) { atomicAdd(&(bar)[XB_TMO], 1u); break; } } } } while (0)
; __device__ __forceinline__ void xcd_barrier(const XcdBarrier& b) {
;     ...
;             else XB_SPIN(xb_ld(&bar[XB_TOPGEN]) == tg, bar);
.LBB0_180:
	v_mov_b64_e32 v[0:1], s[8:9]
	global_load_dword v0, v[0:1], off sc1
	s_mov_b64 s[20:21], 0
	s_mov_b64 s[18:19], -1
	s_waitcnt vmcnt(0) lgkmcnt(0)
	v_cmp_eq_u32_e32 vcc, 0, v0
	s_and_saveexec_b64 s[22:23], vcc
	s_cmp_lt_u32 s24, 0x40001
	s_cselect_b64 s[20:21], -1, 0
	s_xor_b64 s[18:19], exec, -1
	s_and_b64 s[20:21], s[20:21], exec
	s_or_b64 exec, exec, s[22:23]
	s_and_saveexec_b64 s[22:23], s[20:21]
	s_cbranch_execz .LBB0_177
.LBB0_183:
	v_mov_b64_e32 v[0:1], s[4:5]
	global_load_dword v0, v[0:1], off sc1
	s_add_i32 s24, s24, 1
	s_or_b64 s[18:19], s[18:19], exec
	s_waitcnt vmcnt(0) lgkmcnt(0)
	v_cmp_ne_u32_e32 vcc, v0, v2
	s_orn2_b64 s[16:17], vcc, exec
	s_branch .LBB0_177

; __device__ __forceinline__ unsigned cvt_pk_bf16(float lo, float hi) { f32x2 v = {lo, hi}; bf16x2_t b = __builtin_convertvector(v, bf16x2_t); return __builtin_bit_cast(unsigned, b); }
; __device__ __forceinline__ float row_stat(const float* plain, const float* slots, int row, int fq) {
;     if (plain) return plain[row];
;     __device__ __forceinline__ void operator()(const f32x4 (&acc)[2][2][4][2], const Unit& u, int wr, int wc, int fr, int fq) const {
;         const int row0 = u.pm * BM + wr * 64 + fr, col0 = u.pn * BM + wc * 32 + 8 * fq;
;         float rsv[2][4];
; #pragma unroll
;         for (int ai = 0; ai < 2; ++ai)
; #pragma unroll
;             for (int m = 0; m < 4; ++m) rsv[ai][m] = row_stat(rsq, slots, row0 + ai * HALF + m * 16, fq);
; #pragma unroll
;         for (int ai = 0; ai < 2; ++ai)
; #pragma unroll
;             for (int m = 0; m < 4; ++m) { bf16_t* rowp = O + (size_t)(row0 + ai * HALF + m * 16) * ldc + col0;
;                 const float rs = rsqrtf(rsv[ai][m] * (1.f / DM) + EPS);
; #pragma unroll
;                 for (int bj = 0; bj < 2; ++bj) { const f32x4 v0 = acc[ai][bj][m][0] * rs, v1 = acc[ai][bj][m][1] * rs;
;                     u32x4 w; w.x = cvt_pk_bf16(v0[0], v0[1]); w.y = cvt_pk_bf16(v0[2], v0[3]); w.z = cvt_pk_bf16(v1[0], v1[1]); w.w = cvt_pk_bf16(v1[2], v1[3]);
;                     *(u32x4*)(rowp + bj * HALF) = w; } }
;     }
.LBB0_204:
	v_lshl_add_u32 v142, s43, 8, v144
	v_ashrrev_i32_e32 v143, 31, v142
	v_lshl_add_u64 v[140:141], v[142:143], 2, s[14:15]
	global_load_dword v162, v[140:141], off
	global_load_dword v165, v[140:141], off offset:64
	global_load_dword v167, v[140:141], off offset:128
	global_load_dword v156, v[140:141], off offset:192
	global_load_dword v154, v[140:141], off offset:512
	global_load_dword v152, v[140:141], off offset:576
	global_load_dword v150, v[140:141], off offset:640
	global_load_dword v148, v[140:141], off offset:704
	v_lshl_or_b32 v158, s42, 8, v146
	v_ashrrev_i32_e32 v159, 31, v158
	v_mov_b64_e32 v[140:141], s[12:13]
	s_movk_i32 s19, 0x2a00
	v_or_b32_e32 v164, 16, v142
	v_or_b32_e32 v166, 32, v142
	v_or_b32_e32 v157, 48, v142
	v_add_u32_e32 v155, 0x80, v142
	v_add_u32_e32 v153, 0x90, v142
	v_add_u32_e32 v151, 0xa0, v142
	v_add_u32_e32 v149, 0xb0, v142
	v_mad_i64_i32 v[160:161], s[26:27], v142, s19, v[140:141]
	v_lshlrev_b64 v[142:143], 1, v[158:159]
	v_lshl_add_u64 v[158:159], v[160:161], 0, v[142:143]
	s_waitcnt vmcnt(0) lgkmcnt(0)
	v_fmamk_f32 v160, v162, 0x3a000000, v194
	v_cmp_gt_f32_e32 vcc, s33, v160
	v_mul_f32_e32 v161, 0x4b800000, v160
	s_nop 0
	v_cndmask_b32_e32 v160, v160, v161, vcc
	v_rsq_f32_e32 v160, v160
	s_nop 0
	v_mul_f32_e32 v161, 0x45800000, v160
	v_cndmask_b32_e32 v160, v160, v161, vcc
	v_pk_mul_f32 v[128:129], v[128:129], v[160:161] op_sel_hi:[1,0]
	v_pk_mul_f32 v[126:127], v[126:127], v[160:161] op_sel_hi:[1,0]
	v_pk_mul_f32 v[162:163], v[124:125], v[160:161] op_sel_hi:[1,0]
	v_pk_mul_f32 v[124:125], v[122:123], v[160:161] op_sel_hi:[1,0]
	v_cvt_pk_bf16_f32 v122, v126, v127
	v_cvt_pk_bf16_f32 v123, v128, v129
	v_cvt_pk_bf16_f32 v124, v124, v125
	v_cvt_pk_bf16_f32 v125, v162, v163
	global_store_dwordx4 v[158:159], v[122:125], off
	v_pk_mul_f32 v[120:121], v[120:121], v[160:161] op_sel_hi:[1,0]
	v_pk_mul_f32 v[118:119], v[118:119], v[160:161] op_sel_hi:[1,0]
	v_pk_mul_f32 v[122:123], v[116:117], v[160:161] op_sel_hi:[1,0]
	v_pk_mul_f32 v[116:117], v[114:115], v[160:161] op_sel_hi:[1,0]
	v_cvt_pk_bf16_f32 v114, v118, v119
	v_cvt_pk_bf16_f32 v115, v120, v121
	v_cvt_pk_bf16_f32 v116, v116, v117
	v_cvt_pk_bf16_f32 v117, v122, v123
	global_store_dwordx4 v[158:159], v[114:117], off offset:256
	s_nop 1
	v_fmamk_f32 v116, v165, 0x3a000000, v194
	v_cmp_gt_f32_e32 vcc, s33, v116
	v_mul_f32_e32 v117, 0x4b800000, v116
	v_mad_i64_i32 v[114:115], s[26:27], v164, s19, v[140:141]
	v_cndmask_b32_e32 v116, v116, v117, vcc
	v_rsq_f32_e32 v116, v116
	v_lshl_add_u64 v[114:115], v[114:115], 0, v[142:143]
	v_mul_f32_e32 v117, 0x45800000, v116
	v_cndmask_b32_e32 v116, v116, v117, vcc
	v_pk_mul_f32 v[110:111], v[110:111], v[116:117] op_sel_hi:[1,0]
	v_pk_mul_f32 v[108:109], v[108:109], v[116:117] op_sel_hi:[1,0]
	v_pk_mul_f32 v[118:119], v[106:107], v[116:117] op_sel_hi:[1,0]
	v_pk_mul_f32 v[106:107], v[104:105], v[116:117] op_sel_hi:[1,0]
	v_cvt_pk_bf16_f32 v104, v108, v109
	v_cvt_pk_bf16_f32 v105, v110, v111
	v_cvt_pk_bf16_f32 v106, v106, v107
	v_cvt_pk_bf16_f32 v107, v118, v119
	global_store_dwordx4 v[114:115], v[104:107], off
	v_pk_mul_f32 v[102:103], v[102:103], v[116:117] op_sel_hi:[1,0]
	v_pk_mul_f32 v[100:101], v[100:101], v[116:117] op_sel_hi:[1,0]
	v_pk_mul_f32 v[104:105], v[98:99], v[116:117] op_sel_hi:[1,0]
	v_pk_mul_f32 v[98:99], v[96:97], v[116:117] op_sel_hi:[1,0]
	v_cvt_pk_bf16_f32 v96, v100, v101
	v_cvt_pk_bf16_f32 v97, v102, v103
	v_cvt_pk_bf16_f32 v98, v98, v99
	v_cvt_pk_bf16_f32 v99, v104, v105
	global_store_dwordx4 v[114:115], v[96:99], off offset:256
	s_nop 1
	v_fmamk_f32 v98, v167, 0x3a000000, v194
	v_cmp_gt_f32_e32 vcc, s33, v98
	v_mul_f32_e32 v99, 0x4b800000, v98
	v_mad_i64_i32 v[96:97], s[26:27], v166, s19, v[140:141]
	v_cndmask_b32_e32 v98, v98, v99, vcc
	v_rsq_f32_e32 v98, v98
	v_lshl_add_u64 v[96:97], v[96:97], 0, v[142:143]
	v_mul_f32_e32 v99, 0x45800000, v98
	v_cndmask_b32_e32 v98, v98, v99, vcc
	v_pk_mul_f32 v[94:95], v[94:95], v[98:99] op_sel_hi:[1,0]
	v_pk_mul_f32 v[92:93], v[92:93], v[98:99] op_sel_hi:[1,0]
	v_pk_mul_f32 v[100:101], v[90:91], v[98:99] op_sel_hi:[1,0]
	v_pk_mul_f32 v[90:91], v[88:89], v[98:99] op_sel_hi:[1,0]
	v_cvt_pk_bf16_f32 v88, v92, v93
	v_cvt_pk_bf16_f32 v89, v94, v95
	v_cvt_pk_bf16_f32 v90, v90, v91
	v_cvt_pk_bf16_f32 v91, v100, v101
	global_store_dwordx4 v[96:97], v[88:91], off
	v_pk_mul_f32 v[86:87], v[86:87], v[98:99] op_sel_hi:[1,0]
	v_pk_mul_f32 v[84:85], v[84:85], v[98:99] op_sel_hi:[1,0]
	v_pk_mul_f32 v[88:89], v[82:83], v[98:99] op_sel_hi:[1,0]
	v_pk_mul_f32 v[82:83], v[80:81], v[98:99] op_sel_hi:[1,0]
	v_cvt_pk_bf16_f32 v80, v84, v85
	v_cvt_pk_bf16_f32 v81, v86, v87
	v_cvt_pk_bf16_f32 v82, v82, v83
	v_cvt_pk_bf16_f32 v83, v88, v89
	global_store_dwordx4 v[96:97], v[80:83], off offset:256
	s_nop 1
	v_fmamk_f32 v82, v156, 0x3a000000, v194
	v_cmp_gt_f32_e32 vcc, s33, v82
	v_mul_f32_e32 v83, 0x4b800000, v82
	v_mad_i64_i32 v[80:81], s[26:27], v157, s19, v[140:141]
	v_cndmask_b32_e32 v82, v82, v83, vcc
	v_rsq_f32_e32 v82, v82
	v_lshl_add_u64 v[80:81], v[80:81], 0, v[142:143]
	v_mul_f32_e32 v83, 0x45800000, v82
	v_cndmask_b32_e32 v82, v82, v83, vcc
	v_pk_mul_f32 v[78:79], v[78:79], v[82:83] op_sel_hi:[1,0]
	v_pk_mul_f32 v[76:77], v[76:77], v[82:83] op_sel_hi:[1,0]
	v_pk_mul_f32 v[84:85], v[74:75], v[82:83] op_sel_hi:[1,0]
	v_pk_mul_f32 v[74:75], v[72:73], v[82:83] op_sel_hi:[1,0]
	v_cvt_pk_bf16_f32 v72, v76, v77
	v_cvt_pk_bf16_f32 v73, v78, v79
	v_cvt_pk_bf16_f32 v74, v74, v75
; __device__ __forceinline__ unsigned cvt_pk_bf16(float lo, float hi) { f32x2 v = {lo, hi}; bf16x2_t b = __builtin_convertvector(v, bf16x2_t); return __builtin_bit_cast(unsigned, b); }
; #define PG8_BAR __builtin_amdgcn_s_barrier()
; template <class Epi, class Sched, bool ALIGN_EPI = false, bool SP2 = false>
; __device__ __forceinline__ void gemm_phase(PG8_LAS unsigned char* lds, const Gemm g, const Sched& S, const Epi& E) {
;     ...
;         if constexpr (ALIGN_EPI) { if (wr == 0) PG8_BAR; }
;         if constexpr (!Epi::AFTER_DRAIN) { E(acc, cur, wr, wc, fr, fq); S.done(cur); }
;         if (!has_next) break;
; #pragma unroll
;         for (int a = 0; a < 2; ++a)
; #pragma unroll
;             for (int b = 0; b < 2; ++b)
; #pragma unroll
;                 for (int m = 0; m < 4; ++m)
; #pragma unroll
;                     for (int n = 0; n < 2; ++n) acc[a][b][m][n] = (f32x4){0.f, 0.f, 0.f, 0.f};
;         cur = nxt; cA = nA; cB = nB; ++ui;
;         if constexpr (ALIGN_EPI) { if (wr == 1) PG8_BAR; }
;     __device__ __forceinline__ void operator()(const f32x4 (&acc)[2][2][4][2], const Unit& u, int wr, int wc, int fr, int fq) const {
;         const int row0 = u.pm * BM + wr * 64 + fr, col0 = u.pn * BM + wc * 32 + 8 * fq;
;         float rsv[2][4];
; #pragma unroll
;         for (int ai = 0; ai < 2; ++ai)
; #pragma unroll
;             for (int m = 0; m < 4; ++m) rsv[ai][m] = row_stat(rsq, slots, row0 + ai * HALF + m * 16, fq);
; #pragma unroll
;         for (int ai = 0; ai < 2; ++ai)
; #pragma unroll
;             for (int m = 0; m < 4; ++m) { bf16_t* rowp = O + (size_t)(row0 + ai * HALF + m * 16) * ldc + col0;
;                 const float rs = rsqrtf(rsv[ai][m] * (1.f / DM) + EPS);
; #pragma unroll
;                 for (int bj = 0; bj < 2; ++bj) { const f32x4 v0 = acc[ai][bj][m][0] * rs, v1 = acc[ai][bj][m][1] * rs;
;                     u32x4 w; w.x = cvt_pk_bf16(v0[0], v0[1]); w.y = cvt_pk_bf16(v0[2], v0[3]); w.z = cvt_pk_bf16(v1[0], v1[1]); w.w = cvt_pk_bf16(v1[2], v1[3]);
;                     *(u32x4*)(rowp + bj * HALF) = w; } }
;     }
	v_cvt_pk_bf16_f32 v75, v84, v85
	global_store_dwordx4 v[80:81], v[72:75], off
	v_pk_mul_f32 v[70:71], v[70:71], v[82:83] op_sel_hi:[1,0]
	v_pk_mul_f32 v[68:69], v[68:69], v[82:83] op_sel_hi:[1,0]
	v_pk_mul_f32 v[72:73], v[66:67], v[82:83] op_sel_hi:[1,0]
	v_pk_mul_f32 v[66:67], v[64:65], v[82:83] op_sel_hi:[1,0]
	v_cvt_pk_bf16_f32 v64, v68, v69
	v_cvt_pk_bf16_f32 v65, v70, v71
	v_cvt_pk_bf16_f32 v66, v66, v67
	v_cvt_pk_bf16_f32 v67, v72, v73
	global_store_dwordx4 v[80:81], v[64:67], off offset:256
	s_nop 1
	v_fmamk_f32 v66, v154, 0x3a000000, v194
	v_cmp_gt_f32_e32 vcc, s33, v66
	v_mul_f32_e32 v67, 0x4b800000, v66
	v_mad_i64_i32 v[64:65], s[26:27], v155, s19, v[140:141]
	v_cndmask_b32_e32 v66, v66, v67, vcc
	v_rsq_f32_e32 v66, v66
	v_lshl_add_u64 v[64:65], v[64:65], 0, v[142:143]
	v_mul_f32_e32 v67, 0x45800000, v66
	v_cndmask_b32_e32 v66, v66, v67, vcc
	v_pk_mul_f32 v[62:63], v[62:63], v[66:67] op_sel_hi:[1,0]
	v_pk_mul_f32 v[60:61], v[60:61], v[66:67] op_sel_hi:[1,0]
	v_pk_mul_f32 v[68:69], v[58:59], v[66:67] op_sel_hi:[1,0]
	v_pk_mul_f32 v[58:59], v[56:57], v[66:67] op_sel_hi:[1,0]
	v_cvt_pk_bf16_f32 v56, v60, v61
	v_cvt_pk_bf16_f32 v57, v62, v63
	v_cvt_pk_bf16_f32 v58, v58, v59
	v_cvt_pk_bf16_f32 v59, v68, v69
	global_store_dwordx4 v[64:65], v[56:59], off
	v_pk_mul_f32 v[54:55], v[54:55], v[66:67] op_sel_hi:[1,0]
	v_pk_mul_f32 v[52:53], v[52:53], v[66:67] op_sel_hi:[1,0]
	v_pk_mul_f32 v[56:57], v[50:51], v[66:67] op_sel_hi:[1,0]
	v_pk_mul_f32 v[50:51], v[48:49], v[66:67] op_sel_hi:[1,0]
	v_cvt_pk_bf16_f32 v48, v52, v53
	v_cvt_pk_bf16_f32 v49, v54, v55
	v_cvt_pk_bf16_f32 v50, v50, v51
	v_cvt_pk_bf16_f32 v51, v56, v57
	global_store_dwordx4 v[64:65], v[48:51], off offset:256
	s_nop 1
	v_fmamk_f32 v50, v152, 0x3a000000, v194
	v_cmp_gt_f32_e32 vcc, s33, v50
	v_mul_f32_e32 v51, 0x4b800000, v50
	v_mad_i64_i32 v[48:49], s[26:27], v153, s19, v[140:141]
	v_cndmask_b32_e32 v50, v50, v51, vcc
	v_rsq_f32_e32 v50, v50
	v_lshl_add_u64 v[48:49], v[48:49], 0, v[142:143]
	v_mul_f32_e32 v51, 0x45800000, v50
	v_cndmask_b32_e32 v50, v50, v51, vcc
	v_pk_mul_f32 v[46:47], v[46:47], v[50:51] op_sel_hi:[1,0]
	v_pk_mul_f32 v[44:45], v[44:45], v[50:51] op_sel_hi:[1,0]
	v_pk_mul_f32 v[52:53], v[42:43], v[50:51] op_sel_hi:[1,0]
	v_pk_mul_f32 v[42:43], v[40:41], v[50:51] op_sel_hi:[1,0]
	v_cvt_pk_bf16_f32 v40, v44, v45
	v_cvt_pk_bf16_f32 v41, v46, v47
	v_cvt_pk_bf16_f32 v42, v42, v43
	v_cvt_pk_bf16_f32 v43, v52, v53
	global_store_dwordx4 v[48:49], v[40:43], off
	v_pk_mul_f32 v[38:39], v[38:39], v[50:51] op_sel_hi:[1,0]
	v_pk_mul_f32 v[36:37], v[36:37], v[50:51] op_sel_hi:[1,0]
	v_pk_mul_f32 v[40:41], v[34:35], v[50:51] op_sel_hi:[1,0]
	v_pk_mul_f32 v[34:35], v[32:33], v[50:51] op_sel_hi:[1,0]
	v_cvt_pk_bf16_f32 v32, v36, v37
	v_cvt_pk_bf16_f32 v33, v38, v39
	v_cvt_pk_bf16_f32 v34, v34, v35
	v_cvt_pk_bf16_f32 v35, v40, v41
	global_store_dwordx4 v[48:49], v[32:35], off offset:256
	s_nop 1
	v_fmamk_f32 v34, v150, 0x3a000000, v194
	v_cmp_gt_f32_e32 vcc, s33, v34
	v_mul_f32_e32 v35, 0x4b800000, v34
	v_mad_i64_i32 v[32:33], s[26:27], v151, s19, v[140:141]
	v_cndmask_b32_e32 v34, v34, v35, vcc
	v_rsq_f32_e32 v34, v34
	v_lshl_add_u64 v[32:33], v[32:33], 0, v[142:143]
	v_mul_f32_e32 v35, 0x45800000, v34
	v_cndmask_b32_e32 v34, v34, v35, vcc
	v_pk_mul_f32 v[30:31], v[30:31], v[34:35] op_sel_hi:[1,0]
	v_pk_mul_f32 v[28:29], v[28:29], v[34:35] op_sel_hi:[1,0]
	v_pk_mul_f32 v[36:37], v[26:27], v[34:35] op_sel_hi:[1,0]
	v_pk_mul_f32 v[26:27], v[24:25], v[34:35] op_sel_hi:[1,0]
	v_cvt_pk_bf16_f32 v24, v28, v29
	v_cvt_pk_bf16_f32 v25, v30, v31
	v_cvt_pk_bf16_f32 v26, v26, v27
	v_cvt_pk_bf16_f32 v27, v36, v37
	global_store_dwordx4 v[32:33], v[24:27], off
	v_pk_mul_f32 v[22:23], v[22:23], v[34:35] op_sel_hi:[1,0]
	v_pk_mul_f32 v[20:21], v[20:21], v[34:35] op_sel_hi:[1,0]
	v_pk_mul_f32 v[24:25], v[18:19], v[34:35] op_sel_hi:[1,0]
	v_pk_mul_f32 v[18:19], v[16:17], v[34:35] op_sel_hi:[1,0]
	v_cvt_pk_bf16_f32 v16, v20, v21
	v_cvt_pk_bf16_f32 v17, v22, v23
	v_cvt_pk_bf16_f32 v18, v18, v19
	v_cvt_pk_bf16_f32 v19, v24, v25
	global_store_dwordx4 v[32:33], v[16:19], off offset:256
	s_nop 1
	v_fmamk_f32 v18, v148, 0x3a000000, v194
	v_cmp_gt_f32_e32 vcc, s33, v18
	v_mul_f32_e32 v19, 0x4b800000, v18
	v_mad_i64_i32 v[16:17], s[26:27], v149, s19, v[140:141]
	v_cndmask_b32_e32 v18, v18, v19, vcc
	v_rsq_f32_e32 v18, v18
	v_lshl_add_u64 v[16:17], v[16:17], 0, v[142:143]
	s_mov_b64 s[26:27], -1
	v_mul_f32_e32 v19, 0x45800000, v18
	v_cndmask_b32_e32 v18, v18, v19, vcc
	v_pk_mul_f32 v[14:15], v[14:15], v[18:19] op_sel_hi:[1,0]
	v_pk_mul_f32 v[12:13], v[12:13], v[18:19] op_sel_hi:[1,0]
	v_pk_mul_f32 v[20:21], v[10:11], v[18:19] op_sel_hi:[1,0]
	v_pk_mul_f32 v[10:11], v[8:9], v[18:19] op_sel_hi:[1,0]
	v_cvt_pk_bf16_f32 v8, v12, v13
	v_cvt_pk_bf16_f32 v9, v14, v15
	v_cvt_pk_bf16_f32 v10, v10, v11
	v_cvt_pk_bf16_f32 v11, v20, v21
	global_store_dwordx4 v[16:17], v[8:11], off
	v_pk_mul_f32 v[6:7], v[6:7], v[18:19] op_sel_hi:[1,0]
	v_pk_mul_f32 v[4:5], v[4:5], v[18:19] op_sel_hi:[1,0]
	v_pk_mul_f32 v[8:9], v[2:3], v[18:19] op_sel_hi:[1,0]
	v_pk_mul_f32 v[2:3], v[0:1], v[18:19] op_sel_hi:[1,0]
	v_cvt_pk_bf16_f32 v0, v4, v5
	v_cvt_pk_bf16_f32 v1, v6, v7
	v_cvt_pk_bf16_f32 v2, v2, v3
	v_cvt_pk_bf16_f32 v3, v8, v9
	s_andn2_b64 vcc, exec, s[4:5]
	global_store_dwordx4 v[16:17], v[0:3], off offset:256
	s_cbranch_vccnz .LBB0_197
	s_andn2_b64 vcc, exec, s[10:11]
	s_cbranch_vccnz .LBB0_196
	s_barrier
	s_branch .LBB0_196

; __device__ __forceinline__ unsigned xb_ld(unsigned* p)              { return __hip_atomic_load(p, __ATOMIC_RELAXED, __HIP_MEMORY_SCOPE_AGENT); }
; __device__ __forceinline__ void xcd_barrier_complete(unsigned* bar, unsigned x, unsigned& nloc, unsigned& nx) {
;     const unsigned G = gridDim.x * gridDim.y * gridDim.z;
;     unsigned sum, cnt, mine, sp = 0u;
;     for (;;) {
;         sum = 0u; cnt = 0u; mine = 0u;
; #pragma unroll
;         for (unsigned j = 0; j < 16; ++j) { const unsigned c = xb_ld(&bar[XB_XCNT(j)]); sum += c; cnt += (c > 0u) ? 1u : 0u; mine = (j == x) ? c : mine; }
;         if (sum == G) break;
;         __builtin_amdgcn_s_sleep(1);
;         if ((++sp & 255u) == 0u) { if (xb_ld(&bar[XB_TMO])) break; if (sp > XB_SPIN_CAP) { atomicAdd(&bar[XB_TMO], 1u); break; } }
;     }
;     nloc = mine > 0u ? mine : 1u; nx = cnt > 0u ? cnt : 1u;
; }
.LBB0_213:
	s_waitcnt lgkmcnt(0)
	v_mov_b64_e32 v[0:1], s[6:7]
	v_mov_b64_e32 v[2:3], s[8:9]
	global_load_dword v0, v[0:1], off sc1
	v_readlane_b32 s52, v255, 5
	global_load_dword v1, v[2:3], off sc1
	v_mov_b64_e32 v[2:3], s[10:11]
	global_load_dword v2, v[2:3], off sc1
	s_or_b64 s[50:51], s[50:51], exec
	s_or_b64 s[48:49], s[48:49], exec
	s_waitcnt vmcnt(0) lgkmcnt(0)
	v_add_u32_e32 v4, v1, v0
	v_add_u32_e32 v6, v4, v2
	v_mov_b64_e32 v[4:5], s[12:13]
	global_load_dword v3, v[4:5], off sc1
	v_mov_b64_e32 v[4:5], s[14:15]
	global_load_dword v4, v[4:5], off sc1
	s_waitcnt vmcnt(0) lgkmcnt(0)
	v_add_u32_e32 v6, v6, v3
	v_add_u32_e32 v8, v6, v4
	v_mov_b64_e32 v[6:7], s[16:17]
	global_load_dword v5, v[6:7], off sc1
	v_mov_b64_e32 v[6:7], s[18:19]
	global_load_dword v6, v[6:7], off sc1
	s_waitcnt vmcnt(0) lgkmcnt(0)
	v_add_u32_e32 v8, v8, v5
	v_add_u32_e32 v10, v8, v6
	v_mov_b64_e32 v[8:9], s[20:21]
	global_load_dword v7, v[8:9], off sc1
	v_mov_b64_e32 v[8:9], s[22:23]
	global_load_dword v8, v[8:9], off sc1
	s_waitcnt vmcnt(0) lgkmcnt(0)
	v_add_u32_e32 v10, v10, v7
	v_add_u32_e32 v12, v10, v8
	v_mov_b64_e32 v[10:11], s[24:25]
	global_load_dword v9, v[10:11], off sc1
	v_mov_b64_e32 v[10:11], s[26:27]
	global_load_dword v10, v[10:11], off sc1
	s_waitcnt vmcnt(0) lgkmcnt(0)
	v_add_u32_e32 v12, v12, v9
	v_add_u32_e32 v14, v12, v10
	v_mov_b64_e32 v[12:13], s[28:29]
	global_load_dword v11, v[12:13], off sc1
	v_mov_b64_e32 v[12:13], s[30:31]
	global_load_dword v12, v[12:13], off sc1
	s_waitcnt vmcnt(0) lgkmcnt(0)
	v_add_u32_e32 v14, v14, v11
	v_add_u32_e32 v16, v14, v12
	v_mov_b64_e32 v[14:15], s[34:35]
	global_load_dword v13, v[14:15], off sc1
	v_mov_b64_e32 v[14:15], s[40:41]
	global_load_dword v14, v[14:15], off sc1
	s_waitcnt vmcnt(0) lgkmcnt(0)
	v_add_u32_e32 v16, v16, v13
	v_add_u32_e32 v18, v16, v14
	v_mov_b64_e32 v[16:17], s[42:43]
	global_load_dword v15, v[16:17], off sc1
	s_waitcnt vmcnt(0) lgkmcnt(0)
	v_add_u32_e32 v16, v18, v15
	v_cmp_ne_u32_e32 vcc, s52, v16
	s_and_saveexec_b64 s[52:53], vcc
	s_cbranch_execz .LBB0_212
	s_and_b32 s56, s63, 0xff
	s_mov_b64 s[54:55], -1
	s_cmp_eq_u32 s56, 0
	s_mov_b64 s[58:59], -1
	s_mov_b64 s[56:57], -1
	s_sleep 1
	s_cbranch_scc1 .LBB0_216
	s_and_saveexec_b64 s[60:61], s[58:59]
	s_cbranch_execz .LBB0_211
	s_branch .LBB0_219

; __device__ __forceinline__ unsigned xb_ld(unsigned* p)              { return __hip_atomic_load(p, __ATOMIC_RELAXED, __HIP_MEMORY_SCOPE_AGENT); }
; __device__ __forceinline__ unsigned xb_add(unsigned* p, unsigned v) { return __hip_atomic_fetch_add(p, v, __ATOMIC_RELAXED, __HIP_MEMORY_SCOPE_AGENT); }
; #define XB_SPIN(cond, bar) do { unsigned _sp = 0; while (cond) { __builtin_amdgcn_s_sleep(1); \
;     if ((++_sp & 255u) == 0u) { if (xb_ld(&(bar)[XB_TMO])) break; if (_sp > XB_SPIN_CAP) { atomicAdd(&(bar)[XB_TMO], 1u); break; } } } } while (0)
; __device__ __forceinline__ void xcd_barrier(const XcdBarrier& b) {
;     asm volatile("s_waitcnt vmcnt(0)" ::: "memory");
;     __syncthreads();
;     if (threadIdx.x == 0) {
;         unsigned* bar = b.bar;
;         __builtin_amdgcn_s_waitcnt(0);
;         unsigned nloc = b.st[0], nx = b.st[1];
;         if (nloc == 0u) { xcd_barrier_complete(bar, b.x, nloc, nx); b.st[0] = nloc; b.st[1] = nx; }
;         const unsigned old = xb_add(&bar[XB_XSUB(b.x)], 1u);
;         const unsigned gen = old / nloc;
;         if (old + 1u == (gen + 1u) * nloc) {
;             __builtin_amdgcn_fence(__ATOMIC_RELEASE, "agent");
;             asm volatile("s_waitcnt vmcnt(0)" ::: "memory");
;             const unsigned og = xb_add(&bar[XB_TOP], 1u);
;             const unsigned tg = og / nx;
;             if (og + 1u == (tg + 1u) * nx) xb_add(&bar[XB_TOPGEN], 1u);
;             else XB_SPIN(xb_ld(&bar[XB_TOPGEN]) == tg, bar);
;             __builtin_amdgcn_fence(__ATOMIC_ACQUIRE, "agent");
;             xb_add(&bar[XB_XGEN(b.x)], 1u);
;             asm volatile("s_waitcnt vmcnt(0)" ::: "memory");
;         } else {
;             XB_SPIN(xb_ld(&bar[XB_XGEN(b.x)]) == gen, bar);
.LBB0_223:
	s_lshl_b32 s4, s62, 8
	s_add_u32 s4, s38, s4
	s_addc_u32 s5, s39, 0
	v_mov_b32_e32 v1, s4
	v_add_co_u32_e32 v4, vcc, 0x3e301000, v1
	v_mov_b32_e32 v1, s5
	s_nop 0
	v_addc_co_u32_e32 v5, vcc, 0, v1, vcc
	flat_atomic_add v3, v[4:5], v239 offset:1024 sc0
	v_cvt_f32_u32_e32 v1, v2
	v_sub_u32_e32 v4, 0, v2
	s_add_u32 s27, s4, 0x3e300000
	s_addc_u32 s26, s5, 0
	v_rcp_iflag_f32_e32 v1, v1
	s_nop 0
	v_mul_f32_e32 v1, 0x4f7ffffe, v1
	v_cvt_u32_f32_e32 v1, v1
	v_mul_lo_u32 v4, v4, v1
	v_mul_hi_u32 v4, v1, v4
	v_add_u32_e32 v1, v1, v4
	s_waitcnt vmcnt(0) lgkmcnt(0)
	v_mul_hi_u32 v1, v3, v1
	v_mul_lo_u32 v4, v1, v2
	v_sub_u32_e32 v4, v3, v4
	v_cmp_ge_u32_e32 vcc, v4, v2
	v_add_u32_e32 v5, 1, v1
	s_nop 0
	v_cndmask_b32_e32 v1, v1, v5, vcc
	v_sub_u32_e32 v5, v4, v2
	v_cndmask_b32_e32 v4, v4, v5, vcc
	v_cmp_ge_u32_e32 vcc, v4, v2
	v_add_u32_e32 v4, 1, v1
	s_nop 0
	v_cndmask_b32_e32 v1, v1, v4, vcc
	v_add_u32_e32 v4, 1, v3
	v_mad_u64_u32 v[2:3], s[4:5], v2, v1, v[2:3]
	v_cmp_ne_u32_e32 vcc, v4, v2
	s_and_saveexec_b64 s[4:5], vcc
	s_xor_b64 s[4:5], exec, s[4:5]
	s_cbranch_execz .LBB0_236
	v_mov_b32_e32 v0, s27
	v_add_co_u32_e32 v2, vcc, 0x2000, v0
	v_mov_b32_e32 v0, s26
	s_nop 0
	v_addc_co_u32_e32 v3, vcc, 0, v0, vcc
	global_load_dword v0, v[2:3], off offset:1024 sc1
	s_add_u32 s8, s27, 0x2400
	s_addc_u32 s9, s26, 0
	s_waitcnt vmcnt(0) lgkmcnt(0)
	v_cmp_eq_u32_e32 vcc, v0, v1
	s_and_saveexec_b64 s[6:7], vcc
	s_cbranch_execz .LBB0_235
	s_add_u32 s10, s38, 0x3e300200
	s_addc_u32 s11, s39, 0
	s_mov_b32 s28, 1
	s_mov_b64 s[12:13], 0
	s_branch .LBB0_227

; __device__ __forceinline__ unsigned xb_ld(unsigned* p)              { return __hip_atomic_load(p, __ATOMIC_RELAXED, __HIP_MEMORY_SCOPE_AGENT); }
; __device__ __forceinline__ unsigned xb_add(unsigned* p, unsigned v) { return __hip_atomic_fetch_add(p, v, __ATOMIC_RELAXED, __HIP_MEMORY_SCOPE_AGENT); }
; #define XB_SPIN(cond, bar) do { unsigned _sp = 0; while (cond) { __builtin_amdgcn_s_sleep(1); \
;     if ((++_sp & 255u) == 0u) { if (xb_ld(&(bar)[XB_TMO])) break; if (_sp > XB_SPIN_CAP) { atomicAdd(&(bar)[XB_TMO], 1u); break; } } } } while (0)
; __device__ __forceinline__ void xcd_barrier(const XcdBarrier& b) {
;     ...
;         if (old + 1u == (gen + 1u) * nloc) {
;             __builtin_amdgcn_fence(__ATOMIC_RELEASE, "agent");
;             asm volatile("s_waitcnt vmcnt(0)" ::: "memory");
;             const unsigned og = xb_add(&bar[XB_TOP], 1u);
;             const unsigned tg = og / nx;
;             if (og + 1u == (tg + 1u) * nx) xb_add(&bar[XB_TOPGEN], 1u);
;             else XB_SPIN(xb_ld(&bar[XB_TOPGEN]) == tg, bar);
.LBB0_236:
	s_andn2_saveexec_b64 s[4:5], s[4:5]
	s_cbranch_execz .LBB0_252
	v_mov_b32_e32 v1, s38
	v_add_co_u32_e32 v2, vcc, 0x3e303000, v1
	v_mov_b32_e32 v1, s39
	buffer_wbl2 sc1
	s_waitcnt vmcnt(0)
	v_addc_co_u32_e32 v3, vcc, 0, v1, vcc
	flat_atomic_add v1, v[2:3], v239 offset:1024 sc0
	v_cvt_f32_u32_e32 v2, v0
	v_sub_u32_e32 v3, 0, v0
	s_mov_b64 s[8:9], -1
	v_rcp_iflag_f32_e32 v2, v2
	s_nop 0
	v_mul_f32_e32 v2, 0x4f7ffffe, v2
	v_cvt_u32_f32_e32 v2, v2
	v_mul_lo_u32 v3, v3, v2
	v_mul_hi_u32 v3, v2, v3
	v_add_u32_e32 v2, v2, v3
	s_waitcnt vmcnt(0) lgkmcnt(0)
	v_mul_hi_u32 v2, v1, v2
	v_mul_lo_u32 v3, v2, v0
	v_sub_u32_e32 v3, v1, v3
	v_cmp_ge_u32_e32 vcc, v3, v0
	v_add_u32_e32 v4, 1, v2
	s_nop 0
	v_cndmask_b32_e32 v2, v2, v4, vcc
	v_sub_u32_e32 v4, v3, v0
	v_cndmask_b32_e32 v3, v3, v4, vcc
	v_cmp_ge_u32_e32 vcc, v3, v0
	v_add_u32_e32 v3, 1, v2
	s_nop 0
	v_cndmask_b32_e32 v2, v2, v3, vcc
	v_add_u32_e32 v3, 1, v1
	v_mad_u64_u32 v[0:1], s[4:5], v0, v2, v[0:1]
	s_add_u32 s4, s38, 0x3e303500
	s_addc_u32 s5, s39, 0
	v_cmp_ne_u32_e32 vcc, v3, v0
	v_mov_b64_e32 v[0:1], s[4:5]
	s_and_saveexec_b64 s[6:7], vcc
	s_cbranch_execz .LBB0_249
	v_mov_b64_e32 v[0:1], s[4:5]
	global_load_dword v0, v[0:1], off sc1
	s_mov_b64 s[12:13], 0
	s_waitcnt vmcnt(0) lgkmcnt(0)
	v_cmp_eq_u32_e32 vcc, v0, v2
	s_and_saveexec_b64 s[10:11], vcc
	s_cbranch_execz .LBB0_248
	s_add_u32 s8, s38, 0x3e300200
	s_addc_u32 s9, s39, 0
	s_mov_b32 s24, 1
	s_branch .LBB0_241

; __device__ __forceinline__ float bf2f(unsigned v) { return __uint_as_float(v << 16); }
; __device__ __forceinline__ unsigned pk2(float lo, float hi) { return f2bf(lo) | (f2bf(hi) << 16); }
; __device__ __forceinline__ void mla_prep(const KArgs& a, int l) {
;     unsigned char* const wsb = opq(a.ws);
;     const int tid = opaque_tid(), lane = tid & 63, gw = blockIdx.x * 8 + (tid >> 6), ngw = gridDim.x * 8;
;     bf16_t* u = (bf16_t*)(wsb + WS_U); bf16_t* kr = (bf16_t*)(wsb + WS_KR);
;     const float* cs = (const float*)(wsb + WS_COS); const float* sn = (const float*)(wsb + WS_SIN);
;     const float* gq = (const float*)a.in[8] + l * 512 + lane * 8; const float* gkv = (const float*)a.in[10] + l * 512 + lane * 8;
;     const f32x4 gq0 = *(const f32x4*)gq, gq1 = *(const f32x4*)(gq + 4), gk0 = *(const f32x4*)gkv, gk1 = *(const f32x4*)(gkv + 4);
;     const float gqv[8] = {gq0[0], gq0[1], gq0[2], gq0[3], gq1[0], gq1[1], gq1[2], gq1[3]}, gkv8[8] = {gk0[0], gk0[1], gk0[2], gk0[3], gk1[0], gk1[1], gk1[2], gk1[3]};
;     for (int tok0 = gw; tok0 < M; tok0 += 2 * ngw) {
;         bf16x8 raw[2][2]; float x1[2], x2[2], c[2], s[2]; bool ok[2];
; #pragma unroll
;         for (int j = 0; j < 2; ++j) { const int tok = tok0 + j * ngw; ok[j] = tok < M; const int tk = ok[j] ? tok : tok0; bf16_t* ur = u + (size_t)tk * DINP;
;             raw[j][0] = *(const bf16x8*)(ur + C_CQ + lane * 8); raw[j][1] = *(const bf16x8*)(ur + C_CKV + lane * 8);
;             x1[j] = bf2f(ur[C_KR + (lane & 31)]); x2[j] = bf2f(ur[C_KR + 32 + (lane & 31)]); c[j] = cs[(size_t)tk * 32 + (lane & 31)]; s[j] = sn[(size_t)tk * 32 + (lane & 31)]; }
; #pragma unroll
;         for (int j = 0; j < 2; ++j) { const int tok = tok0 + j * ngw; if (!ok[j]) continue; bf16_t* ur = u + (size_t)tok * DINP;
; #pragma unroll
;             for (int w = 0; w < 2; ++w) { float f[8]; unpack8(raw[j][w], f); float ssq = 0.f;
; #pragma unroll
;                 for (int e = 0; e < 8; ++e) ssq += f[e] * f[e];
;                 const float rstd = rsqrtf(wave_sum(ssq) * (1.f / 512.f) + EPS);
; #pragma unroll
;                 for (int e = 0; e < 8; ++e) f[e] = f[e] * rstd * (w ? gkv8[e] : gqv[e]);
;                 *(bf16x8*)(ur + (w ? C_CKV : C_CQ) + lane * 8) = pack8(f); }
;             if (lane < 32) *(unsigned*)(kr + (size_t)tok * 64 + 2 * lane) = pk2(x1[j] * c[j] - x2[j] * s[j], x2[j] * c[j] + x1[j] * s[j]); }
;     }
; }
.LBB0_255:
	v_mov_b64_e32 v[16:17], s[12:13]
	v_mad_i64_i32 v[44:45], s[6:7], v46, s2, v[16:17]
	v_add_u32_e32 v32, s20, v46
	s_mov_b32 s6, 0x8000
	v_cmp_gt_i32_e64 s[6:7], s6, v32
	v_mov_b32_e32 v31, v113
	s_movk_i32 s20, 0x2000
	v_cndmask_b32_e64 v48, v46, v32, s[6:7]
	v_mad_i64_i32 v[50:51], s[8:9], v48, s2, v[16:17]
	v_lshl_add_u64 v[16:17], v[50:51], 0, v[30:31]
	v_ashrrev_i32_e32 v47, 31, v46
	v_add_co_u32_e32 v16, vcc, s20, v16
	v_lshlrev_b32_e32 v112, 1, v24
	v_lshlrev_b64 v[38:39], 7, v[46:47]
	v_lshlrev_b32_e32 v33, 2, v24
	v_ashrrev_i32_e32 v49, 31, v48
	v_addc_co_u32_e32 v17, vcc, 0, v17, vcc
	v_lshl_add_u64 v[50:51], v[50:51], 0, v[112:113]
	v_or_b32_e32 v18, v38, v33
	v_mov_b32_e32 v19, v39
	v_add_co_u32_e32 v50, vcc, s20, v50
	v_lshlrev_b64 v[48:49], 7, v[48:49]
	v_lshl_add_u64 v[20:21], s[14:15], 0, v[18:19]
	v_lshl_add_u64 v[18:19], s[16:17], 0, v[18:19]
	v_addc_co_u32_e32 v51, vcc, 0, v51, vcc
	v_or_b32_e32 v48, v48, v33
	global_load_dword v40, v[20:21], off
	global_load_dword v42, v[18:19], off
	s_nop 0
	global_load_dwordx4 v[20:23], v[16:17], off offset:64
	s_nop 0
	global_load_dwordx4 v[16:19], v[16:17], off offset:1088
	s_nop 0
	global_load_ushort v69, v[50:51], off offset:2112
	global_load_ushort v70, v[50:51], off offset:2176
	v_lshl_add_u64 v[50:51], s[14:15], 0, v[48:49]
	v_lshl_add_u64 v[48:49], s[16:17], 0, v[48:49]
	global_load_dword v34, v[50:51], off
	global_load_dword v36, v[48:49], off
	v_lshl_add_u64 v[48:49], v[44:45], 0, v[30:31]
	v_add_co_u32_e32 v48, vcc, s20, v48
	s_mov_b32 s0, 0x3b000000
	s_nop 0
	v_addc_co_u32_e32 v49, vcc, 0, v49, vcc
	global_load_dwordx4 v[72:75], v[48:49], off offset:1088
	global_load_dwordx4 v[58:61], v[48:49], off offset:64
	v_mad_i64_i32 v[48:49], s[8:9], v46, s2, v[26:27]
	s_waitcnt vmcnt(0) lgkmcnt(0)
	v_and_b32_e32 v63, 0xffff0000, v72
	v_and_b32_e32 v53, 0xffff0000, v61
	v_lshlrev_b32_e32 v52, 16, v61
	v_and_b32_e32 v61, 0xffff0000, v58
	v_and_b32_e32 v55, 0xffff0000, v60
	v_lshlrev_b32_e32 v54, 16, v60
	v_lshlrev_b32_e32 v60, 16, v58
	v_lshlrev_b32_e32 v62, 16, v72
	v_mov_b32_e32 v82, v63
	v_mov_b32_e32 v83, v61
	v_lshlrev_b32_e32 v56, 16, v59
	v_lshlrev_b32_e32 v58, 16, v73
	v_mov_b32_e32 v80, v62
	v_mov_b32_e32 v81, v60
	v_pk_mul_f32 v[82:83], v[82:83], v[82:83]
	v_and_b32_e32 v57, 0xffff0000, v59
	v_and_b32_e32 v51, 0xffff0000, v74
	v_lshlrev_b32_e32 v50, 16, v74
	v_and_b32_e32 v59, 0xffff0000, v73
	v_mov_b32_e32 v72, v58
	v_mov_b32_e32 v73, v56
	v_pk_fma_f32 v[80:81], v[80:81], v[80:81], v[82:83]
	v_pk_mul_f32 v[66:67], v[54:55], v[54:55]
	v_and_b32_e32 v47, 0xffff0000, v75
	v_lshlrev_b32_e32 v46, 16, v75
	v_pk_mul_f32 v[74:75], v[50:51], v[50:51]
	v_mov_b32_e32 v78, v59
	v_mov_b32_e32 v79, v57
	v_pk_fma_f32 v[72:73], v[72:73], v[72:73], v[80:81]
	v_pk_mul_f32 v[64:65], v[52:53], v[52:53]
	v_pk_fma_f32 v[72:73], v[78:79], v[78:79], v[72:73]
	v_mov_b32_e32 v78, v74
	v_mov_b32_e32 v79, v66
	v_pk_mul_f32 v[76:77], v[46:47], v[46:47]
	v_pk_add_f32 v[72:73], v[78:79], v[72:73]
	v_mov_b32_e32 v66, v75
	v_pk_add_f32 v[66:67], v[66:67], v[72:73]
	v_mov_b32_e32 v72, v76
	v_mov_b32_e32 v73, v64
	v_pk_add_f32 v[66:67], v[72:73], v[66:67]
	v_mov_b32_e32 v64, v77
	v_pk_add_f32 v[64:65], v[64:65], v[66:67]
	ds_bpermute_b32 v67, v25, v65
	ds_bpermute_b32 v66, v25, v64
	s_waitcnt lgkmcnt(0)
	v_pk_add_f32 v[64:65], v[64:65], v[66:67]
	ds_bpermute_b32 v67, v35, v65
	ds_bpermute_b32 v66, v35, v64
	s_waitcnt lgkmcnt(0)
	v_pk_add_f32 v[64:65], v[64:65], v[66:67]
	ds_bpermute_b32 v67, v37, v65
	ds_bpermute_b32 v66, v37, v64
	s_waitcnt lgkmcnt(0)
	v_pk_add_f32 v[64:65], v[64:65], v[66:67]
	ds_bpermute_b32 v67, v41, v65
	ds_bpermute_b32 v66, v41, v64
	s_waitcnt lgkmcnt(0)
	v_pk_add_f32 v[64:65], v[64:65], v[66:67]
	ds_bpermute_b32 v67, v43, v65
	ds_bpermute_b32 v66, v43, v64
	s_waitcnt lgkmcnt(0)
	v_pk_add_f32 v[64:65], v[64:65], v[66:67]
	ds_bpermute_b32 v67, v68, v65
	ds_bpermute_b32 v66, v68, v64
	s_waitcnt lgkmcnt(0)
	v_pk_add_f32 v[64:65], v[64:65], v[66:67]
	s_nop 0
	v_pk_fma_f32 v[64:65], v[64:65], s[0:1], v[194:195] op_sel_hi:[1,0,0]
	s_nop 0
	v_mul_f32_e32 v31, 0x4b800000, v65
	v_cmp_gt_f32_e64 s[8:9], s33, v65
	v_cmp_gt_f32_e32 vcc, s33, v64
	s_nop 0
	v_cndmask_b32_e64 v31, v65, v31, s[8:9]
	v_rsq_f32_e32 v31, v31
	s_nop 0
	v_mul_f32_e32 v33, 0x45800000, v31
	v_cndmask_b32_e64 v66, v31, v33, s[8:9]
	v_mul_f32_e32 v31, 0x4b800000, v64
	v_cndmask_b32_e32 v31, v64, v31, vcc
	v_rsq_f32_e32 v31, v31
	v_pk_mul_f32 v[56:57], v[66:67], v[56:57] op_sel_hi:[0,1]
	v_pk_mul_f32 v[60:61], v[66:67], v[60:61] op_sel_hi:[0,1]
	v_pk_mul_f32 v[56:57], v[10:11], v[56:57]
	v_pk_mul_f32 v[54:55], v[66:67], v[54:55] op_sel_hi:[0,1]
	v_pk_mul_f32 v[52:53], v[66:67], v[52:53] op_sel_hi:[0,1]
	v_pk_mul_f32 v[60:61], v[8:9], v[60:61]
	v_pk_mul_f32 v[54:55], v[12:13], v[54:55]
	v_pk_mul_f32 v[66:67], v[14:15], v[52:53]
	v_cvt_pk_bf16_f32 v53, v56, v57
	v_add_co_u32_e64 v56, s[8:9], s20, v48
	v_mul_f32_e32 v33, 0x45800000, v31
	v_cvt_pk_bf16_f32 v52, v60, v61
	v_cvt_pk_bf16_f32 v54, v54, v55
	v_cvt_pk_bf16_f32 v55, v66, v67
	v_addc_co_u32_e64 v57, s[8:9], 0, v49, s[8:9]
	v_cndmask_b32_e32 v48, v31, v33, vcc
	global_store_dwordx4 v[56:57], v[52:55], off offset:64
	v_pk_mul_f32 v[50:51], v[48:49], v[50:51] op_sel_hi:[0,1]
	v_pk_mul_f32 v[46:47], v[48:49], v[46:47] op_sel_hi:[0,1]
	v_pk_mul_f32 v[52:53], v[48:49], v[62:63] op_sel_hi:[0,1]
	v_pk_mul_f32 v[54:55], v[48:49], v[58:59] op_sel_hi:[0,1]
	v_pk_mul_f32 v[52:53], v[0:1], v[52:53]
	v_pk_mul_f32 v[54:55], v[2:3], v[54:55]
	v_pk_mul_f32 v[50:51], v[4:5], v[50:51]
	v_pk_mul_f32 v[58:59], v[6:7], v[46:47]
	v_cvt_pk_bf16_f32 v46, v52, v53
	v_cvt_pk_bf16_f32 v47, v54, v55
	v_cvt_pk_bf16_f32 v48, v50, v51
	v_cvt_pk_bf16_f32 v49, v58, v59
	global_store_dwordx4 v[56:57], v[46:49], off offset:1088
	s_and_saveexec_b64 s[8:9], s[4:5]
	s_cbranch_execz .LBB0_257
	v_lshl_add_u64 v[44:45], v[44:45], 0, v[112:113]
	v_add_co_u32_e32 v44, vcc, 0x2000, v44
	s_mov_b32 s20, 0xffff0000
	s_nop 0
	v_addc_co_u32_e32 v45, vcc, 0, v45, vcc
	global_load_ushort v31, v[44:45], off offset:2112
	global_load_ushort v33, v[44:45], off offset:2176
	v_mov_b32_e32 v239, 1
	v_lshl_add_u64 v[38:39], v[28:29], 0, v[38:39]
	s_waitcnt vmcnt(0) lgkmcnt(0)
	v_lshlrev_b32_e32 v45, 16, v31
	v_lshlrev_b32_e32 v44, 16, v33
	v_pk_mul_f32 v[46:47], v[42:43], v[44:45] op_sel:[0,1] op_sel_hi:[0,0]
	v_pk_fma_f32 v[48:49], v[40:41], v[44:45], v[46:47]
	v_pk_fma_f32 v[44:45], v[40:41], v[44:45], v[46:47] op_sel_hi:[0,1,1] neg_lo:[0,0,1] neg_hi:[0,0,1]
	v_mov_b32_e32 v33, 1
	v_and_b32_sdwa v31, v45, v33 dst_sel:DWORD dst_unused:UNUSED_PAD src0_sel:WORD_1 src1_sel:DWORD
	v_and_b32_sdwa v33, v48, v33 dst_sel:DWORD dst_unused:UNUSED_PAD src0_sel:WORD_1 src1_sel:DWORD
	v_add3_u32 v31, v45, v31, s1
	v_add3_u32 v33, v48, v33, s1
	v_lshrrev_b32_e32 v31, 16, v31
	v_and_or_b32 v31, v33, s20, v31
	global_store_dword v[38:39], v31, off
; __device__ __forceinline__ float bf2f(unsigned v) { return __uint_as_float(v << 16); }
; __device__ __forceinline__ unsigned pk2(float lo, float hi) { return f2bf(lo) | (f2bf(hi) << 16); }
; __device__ __forceinline__ void mla_prep(const KArgs& a, int l) {
;     unsigned char* const wsb = opq(a.ws);
;     const int tid = opaque_tid(), lane = tid & 63, gw = blockIdx.x * 8 + (tid >> 6), ngw = gridDim.x * 8;
;     bf16_t* u = (bf16_t*)(wsb + WS_U); bf16_t* kr = (bf16_t*)(wsb + WS_KR);
;     const float* cs = (const float*)(wsb + WS_COS); const float* sn = (const float*)(wsb + WS_SIN);
;     const float* gq = (const float*)a.in[8] + l * 512 + lane * 8; const float* gkv = (const float*)a.in[10] + l * 512 + lane * 8;
;     const f32x4 gq0 = *(const f32x4*)gq, gq1 = *(const f32x4*)(gq + 4), gk0 = *(const f32x4*)gkv, gk1 = *(const f32x4*)(gkv + 4);
;     const float gqv[8] = {gq0[0], gq0[1], gq0[2], gq0[3], gq1[0], gq1[1], gq1[2], gq1[3]}, gkv8[8] = {gk0[0], gk0[1], gk0[2], gk0[3], gk1[0], gk1[1], gk1[2], gk1[3]};
;     for (int tok0 = gw; tok0 < M; tok0 += 2 * ngw) {
;         bf16x8 raw[2][2]; float x1[2], x2[2], c[2], s[2]; bool ok[2];
; #pragma unroll
;         for (int j = 0; j < 2; ++j) { const int tok = tok0 + j * ngw; ok[j] = tok < M; const int tk = ok[j] ? tok : tok0; bf16_t* ur = u + (size_t)tk * DINP;
;             raw[j][0] = *(const bf16x8*)(ur + C_CQ + lane * 8); raw[j][1] = *(const bf16x8*)(ur + C_CKV + lane * 8);
;             x1[j] = bf2f(ur[C_KR + (lane & 31)]); x2[j] = bf2f(ur[C_KR + 32 + (lane & 31)]); c[j] = cs[(size_t)tk * 32 + (lane & 31)]; s[j] = sn[(size_t)tk * 32 + (lane & 31)]; }
; #pragma unroll
;         for (int j = 0; j < 2; ++j) { const int tok = tok0 + j * ngw; if (!ok[j]) continue; bf16_t* ur = u + (size_t)tok * DINP;
; #pragma unroll
;             for (int w = 0; w < 2; ++w) { float f[8]; unpack8(raw[j][w], f); float ssq = 0.f;
; #pragma unroll
;                 for (int e = 0; e < 8; ++e) ssq += f[e] * f[e];
;                 const float rstd = rsqrtf(wave_sum(ssq) * (1.f / 512.f) + EPS);
; #pragma unroll
;                 for (int e = 0; e < 8; ++e) f[e] = f[e] * rstd * (w ? gkv8[e] : gqv[e]);
;                 *(bf16x8*)(ur + (w ? C_CKV : C_CQ) + lane * 8) = pack8(f); }
;             if (lane < 32) *(unsigned*)(kr + (size_t)tok * 64 + 2 * lane) = pk2(x1[j] * c[j] - x2[j] * s[j], x2[j] * c[j] + x1[j] * s[j]); }
;     }
; }
.LBB0_257:
	s_or_b64 exec, exec, s[8:9]
	s_and_saveexec_b64 s[8:9], s[6:7]
	s_cbranch_execz .LBB0_254
	v_and_b32_e32 v49, 0xffff0000, v21
	v_lshlrev_b32_e32 v48, 16, v21
	v_and_b32_e32 v21, 0xffff0000, v20
	v_and_b32_e32 v59, 0xffff0000, v16
	v_lshlrev_b32_e32 v20, 16, v20
	v_lshlrev_b32_e32 v58, 16, v16
	v_mov_b32_e32 v64, v59
	v_mov_b32_e32 v65, v21
	v_lshlrev_b32_e32 v56, 16, v17
	v_mov_b32_e32 v62, v58
	v_mov_b32_e32 v63, v20
	v_pk_mul_f32 v[64:65], v[64:65], v[64:65]
	v_and_b32_e32 v39, 0xffff0000, v23
	v_lshlrev_b32_e32 v38, 16, v23
	v_and_b32_e32 v23, 0xffff0000, v22
	v_lshlrev_b32_e32 v22, 16, v22
	v_and_b32_e32 v55, 0xffff0000, v18
	v_lshlrev_b32_e32 v54, 16, v18
	v_and_b32_e32 v57, 0xffff0000, v17
	v_mov_b32_e32 v16, v56
	v_mov_b32_e32 v17, v48
	v_pk_fma_f32 v[62:63], v[62:63], v[62:63], v[64:65]
	v_pk_mul_f32 v[46:47], v[22:23], v[22:23]
	v_and_b32_e32 v51, 0xffff0000, v19
	v_lshlrev_b32_e32 v50, 16, v19
	v_pk_mul_f32 v[18:19], v[54:55], v[54:55]
	v_mov_b32_e32 v60, v57
	v_mov_b32_e32 v61, v49
	v_pk_fma_f32 v[16:17], v[16:17], v[16:17], v[62:63]
	v_pk_mul_f32 v[44:45], v[38:39], v[38:39]
	v_pk_fma_f32 v[16:17], v[60:61], v[60:61], v[16:17]
	v_mov_b32_e32 v60, v18
	v_mov_b32_e32 v61, v46
	v_pk_mul_f32 v[52:53], v[50:51], v[50:51]
	v_pk_add_f32 v[16:17], v[60:61], v[16:17]
	v_mov_b32_e32 v46, v19
	v_pk_add_f32 v[16:17], v[46:47], v[16:17]
	v_mov_b32_e32 v18, v52
	v_mov_b32_e32 v19, v44
	v_pk_add_f32 v[16:17], v[18:19], v[16:17]
	v_mov_b32_e32 v44, v53
	v_pk_add_f32 v[16:17], v[44:45], v[16:17]
	ds_bpermute_b32 v19, v25, v17
	ds_bpermute_b32 v18, v25, v16
	v_mad_i64_i32 v[46:47], s[6:7], v32, s2, v[26:27]
	s_movk_i32 s6, 0x2000
	s_waitcnt lgkmcnt(0)
	v_pk_add_f32 v[16:17], v[16:17], v[18:19]
	ds_bpermute_b32 v19, v35, v17
	ds_bpermute_b32 v18, v35, v16
	s_waitcnt lgkmcnt(0)
	v_pk_add_f32 v[16:17], v[16:17], v[18:19]
	ds_bpermute_b32 v19, v37, v17
	ds_bpermute_b32 v18, v37, v16
	s_waitcnt lgkmcnt(0)
	v_pk_add_f32 v[16:17], v[16:17], v[18:19]
	ds_bpermute_b32 v19, v41, v17
	ds_bpermute_b32 v18, v41, v16
	s_waitcnt lgkmcnt(0)
	v_pk_add_f32 v[16:17], v[16:17], v[18:19]
	ds_bpermute_b32 v19, v43, v17
	ds_bpermute_b32 v18, v43, v16
	s_waitcnt lgkmcnt(0)
	v_pk_add_f32 v[16:17], v[16:17], v[18:19]
	ds_bpermute_b32 v19, v68, v17
	ds_bpermute_b32 v18, v68, v16
	s_waitcnt lgkmcnt(0)
	v_pk_add_f32 v[16:17], v[16:17], v[18:19]
	s_nop 0
	v_pk_fma_f32 v[44:45], v[16:17], s[0:1], v[194:195] op_sel_hi:[1,0,0]
	s_nop 0
	v_mul_f32_e32 v16, 0x4b800000, v45
	v_cmp_gt_f32_e32 vcc, s33, v45
	s_nop 1
	v_cndmask_b32_e32 v16, v45, v16, vcc
	v_rsq_f32_e32 v16, v16
	s_nop 0
	v_mul_f32_e32 v17, 0x45800000, v16
	v_cndmask_b32_e32 v16, v16, v17, vcc
	v_pk_mul_f32 v[18:19], v[16:17], v[20:21] op_sel_hi:[0,1]
	v_pk_mul_f32 v[20:21], v[16:17], v[48:49] op_sel_hi:[0,1]
	v_pk_mul_f32 v[20:21], v[10:11], v[20:21]
	v_pk_mul_f32 v[22:23], v[16:17], v[22:23] op_sel_hi:[0,1]
	v_pk_mul_f32 v[16:17], v[16:17], v[38:39] op_sel_hi:[0,1]
	v_pk_mul_f32 v[38:39], v[14:15], v[16:17]
	v_cvt_pk_bf16_f32 v17, v20, v21
	v_mul_f32_e32 v20, 0x4b800000, v44
	v_cmp_gt_f32_e32 vcc, s33, v44
	v_pk_mul_f32 v[18:19], v[8:9], v[18:19]
	v_pk_mul_f32 v[22:23], v[12:13], v[22:23]
	v_cndmask_b32_e32 v20, v44, v20, vcc
	v_cvt_pk_bf16_f32 v16, v18, v19
	v_cvt_pk_bf16_f32 v18, v22, v23
	v_rsq_f32_e32 v22, v20
	v_add_co_u32_e64 v20, s[6:7], s6, v46
	v_cvt_pk_bf16_f32 v19, v38, v39
	s_nop 0
	v_addc_co_u32_e64 v21, s[6:7], 0, v47, s[6:7]
	global_store_dwordx4 v[20:21], v[16:19], off offset:64
	s_nop 1
	v_mul_f32_e32 v16, 0x45800000, v22
	v_cndmask_b32_e32 v16, v22, v16, vcc
	v_pk_mul_f32 v[18:19], v[16:17], v[58:59] op_sel_hi:[0,1]
	v_pk_mul_f32 v[22:23], v[16:17], v[56:57] op_sel_hi:[0,1]
	v_pk_mul_f32 v[38:39], v[16:17], v[54:55] op_sel_hi:[0,1]
	v_pk_mul_f32 v[16:17], v[16:17], v[50:51] op_sel_hi:[0,1]
	v_pk_mul_f32 v[18:19], v[0:1], v[18:19]
	v_pk_mul_f32 v[22:23], v[2:3], v[22:23]
	v_pk_mul_f32 v[38:39], v[4:5], v[38:39]
	v_pk_mul_f32 v[44:45], v[6:7], v[16:17]
	v_cvt_pk_bf16_f32 v16, v18, v19
	v_cvt_pk_bf16_f32 v17, v22, v23
	v_cvt_pk_bf16_f32 v18, v38, v39
	v_cvt_pk_bf16_f32 v19, v44, v45
	global_store_dwordx4 v[20:21], v[16:19], off offset:1088
	s_and_b64 exec, exec, s[4:5]
	s_cbranch_execz .LBB0_254
	v_lshlrev_b32_e32 v17, 16, v69
	v_lshlrev_b32_e32 v16, 16, v70
	v_pk_mul_f32 v[18:19], v[36:37], v[16:17] op_sel:[0,1] op_sel_hi:[0,0]
	v_pk_fma_f32 v[20:21], v[34:35], v[16:17], v[18:19]
	v_pk_fma_f32 v[16:17], v[34:35], v[16:17], v[18:19] op_sel_hi:[0,1,1] neg_lo:[0,0,1] neg_hi:[0,0,1]
	v_mov_b32_e32 v18, 1
	v_and_b32_sdwa v16, v17, v18 dst_sel:DWORD dst_unused:UNUSED_PAD src0_sel:WORD_1 src1_sel:DWORD
	v_and_b32_sdwa v18, v20, v18 dst_sel:DWORD dst_unused:UNUSED_PAD src0_sel:WORD_1 src1_sel:DWORD
	v_add3_u32 v16, v17, v16, s1
	v_ashrrev_i32_e32 v33, 31, v32
	v_add3_u32 v18, v20, v18, s1
	v_lshrrev_b32_e32 v16, 16, v16
	s_mov_b32 s6, 0xffff0000
	v_and_or_b32 v18, v18, s6, v16
	v_lshlrev_b64 v[16:17], 7, v[32:33]
	v_mov_b32_e32 v239, 1
	v_lshl_add_u64 v[16:17], v[28:29], 0, v[16:17]
	global_store_dword v[16:17], v18, off
	s_branch .LBB0_254

; #define LAS __attribute__((address_space(3)))
; __device__ __forceinline__ unsigned cvt_pk_bf16(float lo, float hi) { f32x2 v = {lo, hi}; bf16x2_t b = __builtin_convertvector(v, bf16x2_t); return __builtin_bit_cast(unsigned, b); }
; __device__ __forceinline__ unsigned char* opq(unsigned char* q) { asm volatile("" : "+s"(q)); return q; }
; __device__ __forceinline__ int opaque_tid() { int t = threadIdx.x; asm volatile("" : "+v"(t)); return t; }
; template <int TYPE>
; __device__ __forceinline__ void pass1_item(const KArgs& a, int l, int item, LAS unsigned char* lds) {
;     unsigned char* const wsb = opq(a.ws);
;     const int tid = opaque_tid();
;     using C = Cfg<TYPE>; constexpr int DK = C::DK;
;     const int c = item & (NCH - 1), dir = (item >> 8) & 1, h = (item >> 9) & 3, b = item >> 11;
;     const size_t tok0 = (size_t)b * T + (size_t)c * 64;
;     const bf16_t* u = (const bf16_t*)(wsb + WS_U);
;     const int wid = tid >> 6, lane = tid & 63, fr = lane & 15, fq = lane >> 4;
;     __syncthreads();
;     { const LgRaw raw = lg_issue<TYPE>(u, h, dir, tok0, tid); const VRaw vr = vT_issue(u + tok0 * DINP + (TYPE ? C_HI : C_GV) + h * 128, tid);
;       lg_compute<TYPE>(a, wsb, l, h, dir, raw, lds, tid); vT_write(vr, lds, tid); }
;     ...
;     bf16_t* ST = (bf16_t*)(wsb + (TYPE ? WS_SH : WS_SG)) + (size_t)item * 128 * DK;
;     const bf16x8 b0 = vt_frag(VT, wid * 16 + fr, fq), b1 = vt_frag(VT, wid * 16 + fr, 4 + fq);
; #pragma unroll
;     for (int dt = 0; dt < DK / 16; ++dt) {
;         const bf16x8 a0 = *(LAS bf16x8*)(KDT + (dt * 16 + fr) * LDT + fq * 8), a1 = *(LAS bf16x8*)(KDT + (dt * 16 + fr) * LDT + 32 + fq * 8);
;         f32x4 acc = {0.f, 0.f, 0.f, 0.f};
;         acc = __builtin_amdgcn_mfma_f32_16x16x32_bf16(a0, b0, acc, 0, 0, 0);
;         acc = __builtin_amdgcn_mfma_f32_16x16x32_bf16(a1, b1, acc, 0, 0, 0);
;         u32x2 w; w.x = cvt_pk_bf16(acc[0], acc[1]); w.y = cvt_pk_bf16(acc[2], acc[3]);
;         *(u32x2*)(ST + (size_t)(wid * 16 + fr) * DK + dt * 16 + fq * 4) = w;
;     }
.LBB0_264:
	s_or_b64 exec, exec, s[4:5]
	v_ashrrev_i32_e32 v2, 2, v12
	v_bfe_u32 v0, v12, 4, 2
	v_and_b32_e32 v1, 15, v12
	v_and_b32_e32 v3, -16, v2
	v_bfi_b32 v16, -16, v2, v12
	v_lshlrev_b32_e32 v18, 3, v0
	v_bitop3_b32 v8, v3, 56, v1 bitop3:0xc8
	v_mul_u32_u24_e32 v1, 0x90, v1
	v_lshlrev_b32_e32 v0, 4, v0
	v_mul_lo_u32 v2, v16, s3
	v_add3_u32 v19, 0, v1, v0
	s_waitcnt lgkmcnt(0)
	s_barrier
	v_add_u32_e32 v12, s95, v2
	ds_read_b128 v[0:3], v19 offset:51200
	v_bitop3_b32 v4, v16, v18, 56 bitop3:0x6c
	v_lshl_add_u32 v4, v4, 1, v12
	ds_read_b128 v[4:7], v4
	v_bitop3_b32 v13, v18, v8, 32 bitop3:0x36
	ds_read_b128 v[8:11], v19 offset:51264
	v_lshl_add_u32 v12, v13, 1, v12
	ds_read_b128 v[12:15], v12
	s_waitcnt lgkmcnt(0)
	v_mfma_f32_16x16x32_bf16 v[0:3], v[0:3], v[4:7], 0
	v_ashrrev_i32_e32 v17, 31, v16
	v_lshlrev_b64 v[16:17], 8, v[16:17]
	v_or_b32_e32 v16, v16, v18
	v_mfma_f32_16x16x32_bf16 v[0:3], v[8:11], v[12:15], v[0:3]
	v_lshl_add_u64 v[16:17], s[12:13], 0, v[16:17]
	v_lshl_add_u64 v[16:17], v[16:17], 0, s[10:11]
	v_add_u32_e32 v18, 0xc800, v19
	v_readlane_b32 s4, v254, 40
	s_nop 3
	v_cvt_pk_bf16_f32 v0, v0, v1
	v_cvt_pk_bf16_f32 v1, v2, v3
	global_store_dwordx2 v[16:17], v[0:1], off
	ds_read_b128 v[0:3], v19 offset:53504
	ds_read_b128 v[8:11], v19 offset:53568
	s_waitcnt lgkmcnt(0)
	v_mfma_f32_16x16x32_bf16 v[0:3], v[0:3], v[4:7], 0
	s_add_i32 s15, s15, s70
	s_add_i32 s14, s14, s4
	v_readlane_b32 s4, v254, 55
	v_mfma_f32_16x16x32_bf16 v[0:3], v[8:11], v[12:15], v[0:3]
	v_readlane_b32 s5, v254, 56
	s_add_u32 s10, s10, s4
	s_addc_u32 s11, s11, s5
	v_readlane_b32 s4, v254, 59
	v_readlane_b32 s5, v254, 60
	s_nop 2
	v_cvt_pk_bf16_f32 v0, v0, v1
	v_cvt_pk_bf16_f32 v1, v2, v3
	global_store_dwordx2 v[16:17], v[0:1], off offset:32
	ds_read_b128 v[0:3], v19 offset:55808
	ds_read_b128 v[8:11], v19 offset:55872
	s_waitcnt lgkmcnt(0)
	v_mfma_f32_16x16x32_bf16 v[0:3], v[0:3], v[4:7], 0
	s_add_u32 s8, s8, s4
	s_addc_u32 s9, s9, s5
	s_cmpk_gt_i32 s15, 0xfff
	v_mfma_f32_16x16x32_bf16 v[0:3], v[8:11], v[12:15], v[0:3]
	s_nop 7
	v_cvt_pk_bf16_f32 v0, v0, v1
	v_cvt_pk_bf16_f32 v1, v2, v3
	global_store_dwordx2 v[16:17], v[0:1], off offset:64
	ds_read_b128 v[0:3], v19 offset:58112
	ds_read_b128 v[8:11], v19 offset:58176
	s_waitcnt lgkmcnt(0)
	v_mfma_f32_16x16x32_bf16 v[0:3], v[0:3], v[4:7], 0
	v_mfma_f32_16x16x32_bf16 v[0:3], v[8:11], v[12:15], v[0:3]
	s_nop 7
	v_cvt_pk_bf16_f32 v0, v0, v1
	v_cvt_pk_bf16_f32 v1, v2, v3
	global_store_dwordx2 v[16:17], v[0:1], off offset:96
	ds_read_b128 v[0:3], v19 offset:60416
	ds_read_b128 v[8:11], v19 offset:60480
	s_waitcnt lgkmcnt(0)
	v_mfma_f32_16x16x32_bf16 v[0:3], v[0:3], v[4:7], 0
	v_mfma_f32_16x16x32_bf16 v[0:3], v[8:11], v[12:15], v[0:3]
	s_nop 7
	v_cvt_pk_bf16_f32 v0, v0, v1
	v_cvt_pk_bf16_f32 v1, v2, v3
	global_store_dwordx2 v[16:17], v[0:1], off offset:128
	ds_read_b128 v[0:3], v19 offset:62720
	ds_read_b128 v[8:11], v19 offset:62784
	s_waitcnt lgkmcnt(0)
	v_mfma_f32_16x16x32_bf16 v[0:3], v[0:3], v[4:7], 0
	v_mfma_f32_16x16x32_bf16 v[0:3], v[8:11], v[12:15], v[0:3]
	s_nop 7
	v_cvt_pk_bf16_f32 v0, v0, v1
	v_cvt_pk_bf16_f32 v1, v2, v3
	global_store_dwordx2 v[16:17], v[0:1], off offset:160
	ds_read_b128 v[0:3], v19 offset:65024
	ds_read_b128 v[8:11], v19 offset:65088
	s_waitcnt lgkmcnt(0)
	v_mfma_f32_16x16x32_bf16 v[0:3], v[0:3], v[4:7], 0
	v_mfma_f32_16x16x32_bf16 v[0:3], v[8:11], v[12:15], v[0:3]
	s_nop 7
	v_cvt_pk_bf16_f32 v0, v0, v1
	v_cvt_pk_bf16_f32 v1, v2, v3
	global_store_dwordx2 v[16:17], v[0:1], off offset:192
	ds_read_b128 v[0:3], v18 offset:16128
	ds_read_b128 v[8:11], v18 offset:16192
	s_waitcnt lgkmcnt(0)
	v_mfma_f32_16x16x32_bf16 v[0:3], v[0:3], v[4:7], 0
	v_mfma_f32_16x16x32_bf16 v[0:3], v[8:11], v[12:15], v[0:3]
	s_nop 7
	v_cvt_pk_bf16_f32 v0, v0, v1
	v_cvt_pk_bf16_f32 v1, v2, v3
	global_store_dwordx2 v[16:17], v[0:1], off offset:224
	s_cbranch_scc1 .LBB0_286
.LBB0_265:
	s_ashr_i32 s4, s15, 11
	s_ashr_i32 s5, s4, 31
	s_lshl_b64 s[4:5], s[4:5], 14
	s_and_b32 s6, s14, 0x3fc0
	s_mov_b64 s[12:13], s[68:69]
	s_bfe_i32 s24, s15, 0x10008
	s_bfe_u32 s16, s15, 0x10008
	s_or_b32 s4, s4, s6
	s_add_u32 s6, s12, 0xe300000
	s_addc_u32 s7, s13, 0
	s_lshr_b32 s17, s15, 2
	s_and_b32 s31, s17, 0x180
	v_mov_b32_e32 v12, v195
	s_cmp_eq_u32 s16, 0
	s_cselect_b64 vcc, -1, 0
	v_ashrrev_i32_e32 v8, 4, v12
	s_and_b64 s[18:19], vcc, exec
	s_movk_i32 s17, 0x820
	v_ashrrev_i32_e32 v9, 31, v8
	s_cselect_b32 s34, s17, 0xa20
	v_lshl_add_u64 v[0:1], s[4:5], 0, v[8:9]
	v_mov_b64_e32 v[2:3], s[6:7]
	s_cselect_b32 s30, 1, 14
	s_cselect_b32 s29, 2, 13
	s_cselect_b32 s28, 3, 12
	s_cselect_b32 s27, 4, 11
	s_cselect_b32 s26, 5, 10
	s_cselect_b32 s25, 6, 9
	s_cselect_b32 s23, 9, 6
	s_cselect_b32 s22, 10, 5
	s_cselect_b32 s21, 11, 4
	s_cselect_b32 s20, 12, 3
	s_cselect_b32 s19, 13, 2
	s_cselect_b32 s18, 14, 1
	s_cselect_b32 s17, 15, 0
	s_or_b32 s36, s34, s31
	v_mad_u64_u32 v[2:3], s[34:35], v0, s2, v[2:3]
	s_mulk_i32 s5, 0x2a00
	s_mul_hi_u32 s34, s4, 0x2a00
	s_add_i32 s34, s34, s5
	s_mulk_i32 s4, 0x2a00
	s_add_u32 s4, s6, s4
	s_addc_u32 s5, s7, s34
	s_lshl_b32 s6, s31, 1
	s_add_u32 s4, s4, s6
	s_addc_u32 s5, s5, 0
	v_lshlrev_b32_e32 v13, 3, v12
	s_add_u32 s4, s4, 0x1840
	v_and_b32_e32 v35, 0x78, v13
	s_addc_u32 s5, s5, 0
	v_mad_i32_i24 v3, v1, s2, v3
	v_add_lshl_u32 v112, s36, v35, 1
	v_mov_b64_e32 v[0:1], s[4:5]
	v_lshl_add_u64 v[10:11], v[2:3], 0, v[112:113]
	v_mad_i64_i32 v[2:3], s[4:5], v8, s2, v[0:1]
	v_lshlrev_b32_e32 v112, 1, v35
	v_lshl_add_u64 v[26:27], v[2:3], 0, v[112:113]
	v_add_u32_e32 v2, 32, v8
	v_mad_i64_i32 v[0:1], s[4:5], v2, s2, v[0:1]
	s_lshl_b32 s4, s16, 10
	s_or_b32 s72, s4, s56
	s_lshl_b64 s[4:5], s[72:73], 2
	s_add_u32 s4, s12, s4
	s_addc_u32 s5, s13, s5
	s_lshl_b32 s6, s31, 2
	s_add_u32 s4, s4, s6
	s_addc_u32 s5, s5, 0
	v_lshlrev_b32_e32 v14, 2, v35
	v_mov_b32_e32 v15, v113
	v_lshl_add_u64 v[30:31], v[0:1], 0, v[112:113]
	v_lshl_add_u64 v[0:1], s[4:5], 0, v[14:15]
	s_mov_b64 s[4:5], 0x3e200000
	v_lshl_add_u64 v[2:3], v[0:1], 0, s[4:5]
	s_mov_b32 s4, 0x3e200000
	v_add_co_u32_e64 v0, s[4:5], s4, v0
	s_waitcnt lgkmcnt(0)
	s_nop 0
	v_addc_co_u32_e64 v1, s[4:5], 0, v1, s[4:5]
	s_barrier
; #define LAS __attribute__((address_space(3)))
; __device__ __forceinline__ float sigmoid_(float z) { return __builtin_amdgcn_rcpf(1.f + __expf(-z)); }
; template <int TYPE>
; __device__ __forceinline__ void lg_compute(const KArgs& a, unsigned char* wsb, int l, int h, int dir, const LgRaw& raw, LAS unsigned char* lds, int tid) {
;     using C = Cfg<TYPE>;
;     LAS float* G = (LAS float*)(lds + SC_G); LAS bf16_t* Kb = (LAS bf16_t*)(lds + SC_K);
;     if constexpr (TYPE == 1) {
;         const float* lbp = (const float*)(wsb + WS_LB) + (dir * DEPTH + l) * 512 + h * 128;
;         const int d8 = tid & 15;
;         const f32x4 lb0 = *(const f32x4*)(lbp + d8 * 8), lb1 = *(const f32x4*)(lbp + d8 * 8 + 4);
;         const float lb[8] = {lb0[0], lb0[1], lb0[2], lb0[3], lb1[0], lb1[1], lb1[2], lb1[3]};
; #pragma unroll
;         for (int e2 = 0; e2 < 2; ++e2) { const int i = (tid >> 4) + 32 * e2;
;             float z[8], lg[8], kk[8]; unpack8(e2 ? raw.a1 : raw.a0, z);
; #pragma unroll
;             for (int e = 0; e < 8; ++e) { const float sg = sigmoid_(fmaxf(z[e], -80.f)); lg[e] = __logf(lb[e] + (1.f - lb[e]) * sg); kk[e] = (1.f - lb[e]) * (1.f - sg); }
;             *(LAS f32x4*)(G + i * C::LDG + d8 * 8) = (f32x4){lg[0], lg[1], lg[2], lg[3]}; *(LAS f32x4*)(G + i * C::LDG + d8 * 8 + 4) = (f32x4){lg[4], lg[5], lg[6], lg[7]};
;             *(LAS bf16x8*)(Kb + i * C::LDK_ + d8 * 8) = pack8(kk); }
	global_load_dwordx4 v[4:7], v[0:1], off
	s_nop 0
	global_load_dwordx4 v[0:3], v[2:3], off offset:16
	v_add_u32_e32 v22, 0, v14
	global_load_dwordx4 v[14:17], v[10:11], off
	v_sub_u32_e32 v34, v22, v112
	s_movk_i32 s0, 0xff81
	s_waitcnt vmcnt(0) lgkmcnt(0)
	v_pk_add_f32 v[36:37], v[4:5], 1.0 op_sel_hi:[1,0] neg_lo:[1,0] neg_hi:[1,0]
	v_pk_add_f32 v[40:41], v[6:7], 1.0 op_sel_hi:[1,0] neg_lo:[1,0] neg_hi:[1,0]
	v_pk_add_f32 v[44:45], v[0:1], 1.0 op_sel_hi:[1,0] neg_lo:[1,0] neg_hi:[1,0]
	v_lshlrev_b32_e32 v9, 16, v14
	v_max_f32_e32 v9, v9, v9
	v_max_f32_e32 v9, 0xc2a00000, v9
	v_mul_f32_e32 v9, 0xbfb8aa3b, v9
	v_exp_f32_e32 v9, v9
	v_and_b32_e32 v14, 0xffff0000, v14
	v_lshlrev_b32_e32 v23, 16, v16
	v_and_b32_e32 v24, 0xffff0000, v16
	v_add_f32_e32 v9, 1.0, v9
	v_rcp_f32_e32 v16, v9
	v_max_f32_e32 v9, v14, v14
	v_max_f32_e32 v9, 0xc2a00000, v9
	v_mul_f32_e32 v9, 0xbfb8aa3b, v9
	v_exp_f32_e32 v9, v9
	v_lshlrev_b32_e32 v28, 16, v17
	v_and_b32_e32 v29, 0xffff0000, v17
	v_lshlrev_b32_e32 v20, 16, v15
	v_add_f32_e32 v9, 1.0, v9
	v_rcp_f32_e32 v17, v9
	v_fma_f32 v9, v36, v16, v4
	v_cmp_gt_f32_e64 s[4:5], s33, v9
	v_and_b32_e32 v21, 0xffff0000, v15
	v_pk_add_f32 v[18:19], v[16:17], 1.0 op_sel_hi:[1,0] neg_lo:[1,0] neg_hi:[1,0]
	v_cndmask_b32_e64 v14, 0, 32, s[4:5]
	v_ldexp_f32 v9, v9, v14
	v_log_f32_e32 v9, v9
	v_pk_mul_f32 v[38:39], v[36:37], v[18:19]
	v_pk_add_f32 v[48:49], v[2:3], 1.0 op_sel_hi:[1,0] neg_lo:[1,0] neg_hi:[1,0]
	v_mul_f32_e32 v14, 0x3f317217, v9
	v_fma_f32 v14, v9, s92, -v14
	v_fmac_f32_e32 v14, 0x3377d1cf, v9
	v_fmac_f32_e32 v14, 0x3f317217, v9
	v_cmp_lt_f32_e64 s[6:7], |v9|, s90
	s_nop 1
	v_cndmask_b32_e64 v9, v9, v14, s[6:7]
	v_cndmask_b32_e64 v14, 0, v238, s[4:5]
	v_sub_f32_e32 v14, v9, v14
	v_fma_f32 v9, v37, v17, v5
	v_cmp_gt_f32_e64 s[4:5], s33, v9
	s_nop 1
	v_cndmask_b32_e64 v15, 0, 32, s[4:5]
	v_ldexp_f32 v9, v9, v15
	v_log_f32_e32 v9, v9
	s_nop 0
	v_mul_f32_e32 v15, 0x3f317217, v9
	v_fma_f32 v15, v9, s92, -v15
	v_fmac_f32_e32 v15, 0x3377d1cf, v9
	v_fmac_f32_e32 v15, 0x3f317217, v9
	v_cmp_lt_f32_e64 s[6:7], |v9|, s90
	s_nop 1
	v_cndmask_b32_e64 v9, v9, v15, s[6:7]
	v_cndmask_b32_e64 v15, 0, v238, s[4:5]
	v_sub_f32_e32 v15, v9, v15
	v_max_f32_e32 v9, v20, v20
	v_max_f32_e32 v9, 0xc2a00000, v9
	v_mul_f32_e32 v9, 0xbfb8aa3b, v9
	v_exp_f32_e32 v9, v9
	s_nop 0
	v_add_f32_e32 v9, 1.0, v9
	v_rcp_f32_e32 v18, v9
	v_max_f32_e32 v9, v21, v21
	v_max_f32_e32 v9, 0xc2a00000, v9
	v_mul_f32_e32 v9, 0xbfb8aa3b, v9
	v_exp_f32_e32 v9, v9
	s_nop 0
	v_add_f32_e32 v9, 1.0, v9
	v_rcp_f32_e32 v19, v9
	v_fma_f32 v9, v40, v18, v6
	v_cmp_gt_f32_e64 s[4:5], s33, v9
	v_pk_add_f32 v[20:21], v[18:19], 1.0 op_sel_hi:[1,0] neg_lo:[1,0] neg_hi:[1,0]
	s_nop 0
	v_cndmask_b32_e64 v16, 0, 32, s[4:5]
	v_ldexp_f32 v9, v9, v16
	v_log_f32_e32 v9, v9
	v_pk_mul_f32 v[42:43], v[40:41], v[20:21]
	v_mul_f32_e32 v16, 0x3f317217, v9
	v_fma_f32 v16, v9, s92, -v16
	v_fmac_f32_e32 v16, 0x3377d1cf, v9
	v_fmac_f32_e32 v16, 0x3f317217, v9
	v_cmp_lt_f32_e64 s[6:7], |v9|, s90
	s_nop 1
	v_cndmask_b32_e64 v9, v9, v16, s[6:7]
	v_cndmask_b32_e64 v16, 0, v238, s[4:5]
	v_sub_f32_e32 v16, v9, v16
	v_fma_f32 v9, v41, v19, v7
	v_cmp_gt_f32_e64 s[4:5], s33, v9
	s_nop 1
	v_cndmask_b32_e64 v17, 0, 32, s[4:5]
	v_ldexp_f32 v9, v9, v17
	v_log_f32_e32 v9, v9
	s_nop 0
	v_mul_f32_e32 v17, 0x3f317217, v9
	v_fma_f32 v17, v9, s92, -v17
	v_fmac_f32_e32 v17, 0x3377d1cf, v9
	v_fmac_f32_e32 v17, 0x3f317217, v9
	v_cmp_lt_f32_e64 s[6:7], |v9|, s90
	s_nop 1
	v_cndmask_b32_e64 v9, v9, v17, s[6:7]
	v_cndmask_b32_e64 v17, 0, v238, s[4:5]
	v_sub_f32_e32 v17, v9, v17
	v_max_f32_e32 v9, v23, v23
	v_max_f32_e32 v9, 0xc2a00000, v9
	v_mul_f32_e32 v9, 0xbfb8aa3b, v9
	v_exp_f32_e32 v9, v9
	s_nop 0
	v_add_f32_e32 v9, 1.0, v9
	v_rcp_f32_e32 v20, v9
	v_max_f32_e32 v9, v24, v24
	v_max_f32_e32 v9, 0xc2a00000, v9
	v_mul_f32_e32 v9, 0xbfb8aa3b, v9
	v_exp_f32_e32 v9, v9
	s_nop 0
	v_add_f32_e32 v9, 1.0, v9
	v_rcp_f32_e32 v21, v9
	v_fma_f32 v9, v44, v20, v0
	v_cmp_gt_f32_e64 s[4:5], s33, v9
	v_pk_add_f32 v[24:25], v[20:21], 1.0 op_sel_hi:[1,0] neg_lo:[1,0] neg_hi:[1,0]
	s_nop 0
	v_cndmask_b32_e64 v18, 0, 32, s[4:5]
	v_ldexp_f32 v9, v9, v18
	v_log_f32_e32 v9, v9
	v_pk_mul_f32 v[46:47], v[44:45], v[24:25]
	v_mul_f32_e32 v18, 0x3f317217, v9
	v_fma_f32 v18, v9, s92, -v18
	v_fmac_f32_e32 v18, 0x3377d1cf, v9
	v_fmac_f32_e32 v18, 0x3f317217, v9
	v_cmp_lt_f32_e64 s[6:7], |v9|, s90
	s_nop 1
	v_cndmask_b32_e64 v9, v9, v18, s[6:7]
	v_cndmask_b32_e64 v18, 0, v238, s[4:5]
	v_sub_f32_e32 v18, v9, v18
	v_fma_f32 v9, v45, v21, v1
	v_cmp_gt_f32_e64 s[4:5], s33, v9
	s_nop 1
	v_cndmask_b32_e64 v19, 0, 32, s[4:5]
	v_ldexp_f32 v9, v9, v19
	v_log_f32_e32 v9, v9
	s_nop 0
	v_mul_f32_e32 v19, 0x3f317217, v9
	v_fma_f32 v19, v9, s92, -v19
	v_fmac_f32_e32 v19, 0x3377d1cf, v9
	v_fmac_f32_e32 v19, 0x3f317217, v9
	v_cmp_lt_f32_e64 s[6:7], |v9|, s90
	s_nop 1
	v_cndmask_b32_e64 v9, v9, v19, s[6:7]
	v_cndmask_b32_e64 v19, 0, v238, s[4:5]
	v_sub_f32_e32 v19, v9, v19
	v_max_f32_e32 v9, v28, v28
	v_max_f32_e32 v9, 0xc2a00000, v9
	v_mul_f32_e32 v9, 0xbfb8aa3b, v9
	v_exp_f32_e32 v9, v9
	s_nop 0
	v_add_f32_e32 v9, 1.0, v9
	v_rcp_f32_e32 v24, v9
	v_max_f32_e32 v9, v29, v29
	v_max_f32_e32 v9, 0xc2a00000, v9
	v_mul_f32_e32 v9, 0xbfb8aa3b, v9
	v_exp_f32_e32 v9, v9
	s_nop 0
	v_add_f32_e32 v9, 1.0, v9
	v_rcp_f32_e32 v25, v9
	v_fma_f32 v9, v48, v24, v2
	v_cmp_gt_f32_e64 s[4:5], s33, v9
	v_pk_add_f32 v[28:29], v[24:25], 1.0 op_sel_hi:[1,0] neg_lo:[1,0] neg_hi:[1,0]
	s_nop 0
	v_cndmask_b32_e64 v20, 0, 32, s[4:5]
	v_ldexp_f32 v9, v9, v20
	v_log_f32_e32 v9, v9
	v_pk_mul_f32 v[50:51], v[48:49], v[28:29]
	v_mul_f32_e32 v20, 0x3f317217, v9
	v_fma_f32 v20, v9, s92, -v20
	v_fmac_f32_e32 v20, 0x3377d1cf, v9
	v_fmac_f32_e32 v20, 0x3f317217, v9
	v_cmp_lt_f32_e64 s[6:7], |v9|, s90
	s_nop 1
	v_cndmask_b32_e64 v9, v9, v20, s[6:7]
	v_cndmask_b32_e64 v20, 0, v238, s[4:5]
	v_sub_f32_e32 v20, v9, v20
	v_fma_f32 v9, v49, v25, v3
	v_cmp_gt_f32_e64 s[4:5], s33, v9
	s_nop 1
	v_cndmask_b32_e64 v21, 0, 32, s[4:5]
	v_ldexp_f32 v9, v9, v21
	v_log_f32_e32 v9, v9
	s_nop 0
	v_mul_f32_e32 v21, 0x3f317217, v9
	v_fma_f32 v21, v9, s92, -v21
	v_fmac_f32_e32 v21, 0x3377d1cf, v9
	v_fmac_f32_e32 v21, 0x3f317217, v9
	v_cmp_lt_f32_e64 s[6:7], |v9|, s90
	s_nop 1
	v_cndmask_b32_e64 v9, v9, v21, s[6:7]
	v_cndmask_b32_e64 v21, 0, v238, s[4:5]
	v_mad_u64_u32 v[52:53], s[4:5], v8, s91, v[22:23]
	s_mov_b32 s4, 0x54000
	s_nop 0
	v_add_co_u32_e64 v10, s[4:5], s4, v10
	v_sub_f32_e32 v21, v9, v21
	s_nop 0
	v_addc_co_u32_e64 v11, s[4:5], 0, v11, s[4:5]
	global_load_dwordx4 v[22:25], v[10:11], off
	s_nop 0
	global_load_dwordx4 v[26:29], v[26:27], off
	s_nop 0
	global_load_dwordx4 v[30:33], v[30:31], off
	ds_write_b128 v52, v[14:17]
	ds_write_b128 v52, v[18:21] offset:16
	v_cvt_pk_bf16_f32 v14, v38, v39
	v_cvt_pk_bf16_f32 v15, v42, v43
	v_cvt_pk_bf16_f32 v16, v46, v47
	v_cvt_pk_bf16_f32 v17, v50, v51
	v_mad_u64_u32 v[10:11], s[4:5], v8, s93, v[34:35]
	ds_write_b128 v10, v[14:17] offset:33792
	s_waitcnt vmcnt(0) lgkmcnt(0)
; __device__ __forceinline__ float sigmoid_(float z) { return __builtin_amdgcn_rcpf(1.f + __expf(-z)); }
; template <int TYPE>
; __device__ __forceinline__ void lg_compute(const KArgs& a, unsigned char* wsb, int l, int h, int dir, const LgRaw& raw, LAS unsigned char* lds, int tid) {
;     ...
;         for (int e2 = 0; e2 < 2; ++e2) { const int i = (tid >> 4) + 32 * e2;
;             float z[8], lg[8], kk[8]; unpack8(e2 ? raw.a1 : raw.a0, z);
; #pragma unroll
;             for (int e = 0; e < 8; ++e) { const float sg = sigmoid_(fmaxf(z[e], -80.f)); lg[e] = __logf(lb[e] + (1.f - lb[e]) * sg); kk[e] = (1.f - lb[e]) * (1.f - sg); }
	v_lshlrev_b32_e32 v9, 16, v22
	v_max_f32_e32 v9, v9, v9
	v_max_f32_e32 v9, 0xc2a00000, v9
	v_mul_f32_e32 v9, 0xbfb8aa3b, v9
	v_exp_f32_e32 v9, v9
	v_and_b32_e32 v11, 0xffff0000, v22
	v_lshlrev_b32_e32 v16, 16, v23
	v_and_b32_e32 v17, 0xffff0000, v23
	v_add_f32_e32 v9, 1.0, v9
	v_rcp_f32_e32 v14, v9
	v_lshlrev_b32_e32 v18, 16, v24
	v_and_b32_e32 v19, 0xffff0000, v24
	v_lshlrev_b32_e32 v20, 16, v25
	v_fma_f32 v4, v36, v14, v4
	v_cmp_gt_f32_e64 s[4:5], s33, v4
	v_and_b32_e32 v21, 0xffff0000, v25
	s_nop 0
	v_cndmask_b32_e64 v9, 0, 32, s[4:5]
	v_ldexp_f32 v4, v4, v9
	v_log_f32_e32 v4, v4
	s_nop 0
	v_mul_f32_e32 v9, 0x3f317217, v4
	v_fma_f32 v9, v4, s92, -v9
	v_fmac_f32_e32 v9, 0x3377d1cf, v4
	v_fmac_f32_e32 v9, 0x3f317217, v4
	v_cmp_lt_f32_e64 s[6:7], |v4|, s90
	s_nop 1
	v_cndmask_b32_e64 v4, v4, v9, s[6:7]
	v_cndmask_b32_e64 v9, 0, v238, s[4:5]
	v_sub_f32_e32 v4, v4, v9
	v_max_f32_e32 v9, v11, v11
	v_max_f32_e32 v9, 0xc2a00000, v9
	v_mul_f32_e32 v9, 0xbfb8aa3b, v9
	v_exp_f32_e32 v9, v9
	s_nop 0
	v_add_f32_e32 v9, 1.0, v9
	v_rcp_f32_e32 v15, v9
	s_nop 0
	v_fma_f32 v5, v37, v15, v5
	v_cmp_gt_f32_e64 s[4:5], s33, v5
	v_pk_add_f32 v[14:15], v[14:15], 1.0 op_sel_hi:[1,0] neg_lo:[1,0] neg_hi:[1,0]
	s_nop 0
	v_cndmask_b32_e64 v9, 0, 32, s[4:5]
	v_ldexp_f32 v5, v5, v9
	v_log_f32_e32 v5, v5
	v_pk_mul_f32 v[14:15], v[36:37], v[14:15]
	v_mul_f32_e32 v9, 0x3f317217, v5
	v_fma_f32 v9, v5, s92, -v9
	v_fmac_f32_e32 v9, 0x3377d1cf, v5
	v_fmac_f32_e32 v9, 0x3f317217, v5
	v_cmp_lt_f32_e64 s[6:7], |v5|, s90
	s_nop 1
	v_cndmask_b32_e64 v5, v5, v9, s[6:7]
	v_cndmask_b32_e64 v9, 0, v238, s[4:5]
	v_sub_f32_e32 v5, v5, v9
	v_max_f32_e32 v9, v16, v16
	v_max_f32_e32 v9, 0xc2a00000, v9
	v_mul_f32_e32 v9, 0xbfb8aa3b, v9
	v_exp_f32_e32 v9, v9
	s_nop 0
	v_add_f32_e32 v9, 1.0, v9
	v_rcp_f32_e32 v16, v9
	s_nop 0
	v_fma_f32 v6, v40, v16, v6
	v_cmp_gt_f32_e64 s[4:5], s33, v6
	s_nop 1
	v_cndmask_b32_e64 v9, 0, 32, s[4:5]
	v_ldexp_f32 v6, v6, v9
	v_log_f32_e32 v6, v6
	s_nop 0
	v_mul_f32_e32 v9, 0x3f317217, v6
	v_fma_f32 v9, v6, s92, -v9
	v_fmac_f32_e32 v9, 0x3377d1cf, v6
	v_fmac_f32_e32 v9, 0x3f317217, v6
	v_cmp_lt_f32_e64 s[6:7], |v6|, s90
	s_nop 1
	v_cndmask_b32_e64 v6, v6, v9, s[6:7]
	v_cndmask_b32_e64 v9, 0, v238, s[4:5]
	v_sub_f32_e32 v6, v6, v9
	v_max_f32_e32 v9, v17, v17
	v_max_f32_e32 v9, 0xc2a00000, v9
	v_mul_f32_e32 v9, 0xbfb8aa3b, v9
	v_exp_f32_e32 v9, v9
	s_nop 0
	v_add_f32_e32 v9, 1.0, v9
	v_rcp_f32_e32 v17, v9
	s_nop 0
	v_fmac_f32_e32 v7, v41, v17
	v_cmp_gt_f32_e64 s[4:5], s33, v7
	v_pk_add_f32 v[16:17], v[16:17], 1.0 op_sel_hi:[1,0] neg_lo:[1,0] neg_hi:[1,0]
	s_nop 0
	v_cndmask_b32_e64 v9, 0, 32, s[4:5]
	v_ldexp_f32 v7, v7, v9
	v_log_f32_e32 v7, v7
	v_pk_mul_f32 v[16:17], v[40:41], v[16:17]
	v_mul_f32_e32 v9, 0x3f317217, v7
	v_fma_f32 v9, v7, s92, -v9
	v_fmac_f32_e32 v9, 0x3377d1cf, v7
	v_fmac_f32_e32 v9, 0x3f317217, v7
	v_cmp_lt_f32_e64 s[6:7], |v7|, s90
	s_nop 1
	v_cndmask_b32_e64 v7, v7, v9, s[6:7]
	v_cndmask_b32_e64 v9, 0, v238, s[4:5]
	v_sub_f32_e32 v7, v7, v9
	v_max_f32_e32 v9, v18, v18
	v_max_f32_e32 v9, 0xc2a00000, v9
	v_mul_f32_e32 v9, 0xbfb8aa3b, v9
	v_exp_f32_e32 v9, v9
	s_nop 0
	v_add_f32_e32 v9, 1.0, v9
	v_rcp_f32_e32 v18, v9
	s_nop 0
	v_fma_f32 v0, v44, v18, v0
	v_cmp_gt_f32_e64 s[4:5], s33, v0
	s_nop 1
	v_cndmask_b32_e64 v9, 0, 32, s[4:5]
	v_ldexp_f32 v0, v0, v9
	v_log_f32_e32 v0, v0
	s_nop 0
	v_mul_f32_e32 v9, 0x3f317217, v0
	v_fma_f32 v9, v0, s92, -v9
	v_fmac_f32_e32 v9, 0x3377d1cf, v0
	v_fmac_f32_e32 v9, 0x3f317217, v0
	v_cmp_lt_f32_e64 s[6:7], |v0|, s90
	s_nop 1
	v_cndmask_b32_e64 v0, v0, v9, s[6:7]
	v_cndmask_b32_e64 v9, 0, v238, s[4:5]
	v_sub_f32_e32 v0, v0, v9
	v_max_f32_e32 v9, v19, v19
	v_max_f32_e32 v9, 0xc2a00000, v9
	v_mul_f32_e32 v9, 0xbfb8aa3b, v9
	v_exp_f32_e32 v9, v9
	s_nop 0
	v_add_f32_e32 v9, 1.0, v9
	v_rcp_f32_e32 v19, v9
	s_nop 0
	v_fma_f32 v1, v45, v19, v1
	v_cmp_gt_f32_e64 s[4:5], s33, v1
	v_pk_add_f32 v[18:19], v[18:19], 1.0 op_sel_hi:[1,0] neg_lo:[1,0] neg_hi:[1,0]
	s_nop 0
	v_cndmask_b32_e64 v9, 0, 32, s[4:5]
	v_ldexp_f32 v1, v1, v9
	v_log_f32_e32 v1, v1
	v_pk_mul_f32 v[18:19], v[44:45], v[18:19]
	v_mul_f32_e32 v9, 0x3f317217, v1
	v_fma_f32 v9, v1, s92, -v9
	v_fmac_f32_e32 v9, 0x3377d1cf, v1
	v_fmac_f32_e32 v9, 0x3f317217, v1
	v_cmp_lt_f32_e64 s[6:7], |v1|, s90
	s_nop 1
	v_cndmask_b32_e64 v1, v1, v9, s[6:7]
	v_cndmask_b32_e64 v9, 0, v238, s[4:5]
	v_sub_f32_e32 v1, v1, v9
	v_max_f32_e32 v9, v20, v20
	v_max_f32_e32 v9, 0xc2a00000, v9
	v_mul_f32_e32 v9, 0xbfb8aa3b, v9
	v_exp_f32_e32 v9, v9
	s_nop 0
	v_add_f32_e32 v9, 1.0, v9
	v_rcp_f32_e32 v20, v9
	s_nop 0
	v_fma_f32 v2, v48, v20, v2
	v_cmp_gt_f32_e64 s[4:5], s33, v2
	s_nop 1
	v_cndmask_b32_e64 v9, 0, 32, s[4:5]
	v_ldexp_f32 v2, v2, v9
	v_log_f32_e32 v2, v2
	s_nop 0
	v_mul_f32_e32 v9, 0x3f317217, v2
	v_fma_f32 v9, v2, s92, -v9
	v_fmac_f32_e32 v9, 0x3377d1cf, v2
	v_fmac_f32_e32 v9, 0x3f317217, v2
	v_cmp_lt_f32_e64 s[6:7], |v2|, s90
	s_nop 1
	v_cndmask_b32_e64 v2, v2, v9, s[6:7]
	v_cndmask_b32_e64 v9, 0, v238, s[4:5]
	v_sub_f32_e32 v2, v2, v9
	v_max_f32_e32 v9, v21, v21
	v_max_f32_e32 v9, 0xc2a00000, v9
	v_mul_f32_e32 v9, 0xbfb8aa3b, v9
	v_exp_f32_e32 v9, v9
	s_nop 0
	v_add_f32_e32 v9, 1.0, v9
	v_rcp_f32_e32 v21, v9
	s_nop 0
	v_fmac_f32_e32 v3, v49, v21
; #define LAS __attribute__((address_space(3)))
; __device__ __forceinline__ float sigmoid_(float z) { return __builtin_amdgcn_rcpf(1.f + __expf(-z)); }
; template <int TYPE>
; __device__ __forceinline__ void lg_compute(const KArgs& a, unsigned char* wsb, int l, int h, int dir, const LgRaw& raw, LAS unsigned char* lds, int tid) {
;     ...
;         for (int e2 = 0; e2 < 2; ++e2) { const int i = (tid >> 4) + 32 * e2;
;             float z[8], lg[8], kk[8]; unpack8(e2 ? raw.a1 : raw.a0, z);
; #pragma unroll
;             for (int e = 0; e < 8; ++e) { const float sg = sigmoid_(fmaxf(z[e], -80.f)); lg[e] = __logf(lb[e] + (1.f - lb[e]) * sg); kk[e] = (1.f - lb[e]) * (1.f - sg); }
;             *(LAS f32x4*)(G + i * C::LDG + d8 * 8) = (f32x4){lg[0], lg[1], lg[2], lg[3]}; *(LAS f32x4*)(G + i * C::LDG + d8 * 8 + 4) = (f32x4){lg[4], lg[5], lg[6], lg[7]};
;             *(LAS bf16x8*)(Kb + i * C::LDK_ + d8 * 8) = pack8(kk); }
; template <int TYPE>
; __device__ __forceinline__ void cumsum_g(int dir, LAS unsigned char* lds, int tid) {
;     using C = Cfg<TYPE>; constexpr int NSEG = 512 / C::DK, SEGL = 64 / NSEG;
;     LAS float* G = (LAS float*)(lds + SC_G); LAS float* SG = (LAS float*)(lds + SC_SEG);
;     const int d = tid % C::DK, seg = tid / C::DK;
;     __syncthreads();
;     float run = 0.f;
; #pragma unroll
;     for (int ii = 0; ii < SEGL; ++ii) { const int i = seg * SEGL + (dir ? SEGL - 1 - ii : ii); run += G[i * C::LDG + d]; G[i * C::LDG + d] = run; }
;     SG[seg * 128 + d] = run;
;     __syncthreads();
;     float off = 0.f;
; #pragma unroll
;     for (int s = 0; s < NSEG; ++s) { const bool before = dir ? (s > seg) : (s < seg); if (before) off += SG[s * 128 + d]; }
; #pragma unroll
;     for (int ii = 0; ii < SEGL; ++ii) { const int i = seg * SEGL + ii; G[i * C::LDG + d] += off; }
;     __syncthreads();
; __device__ __forceinline__ void vT_write(const VRaw& r, LAS unsigned char* lds, int tid) {
;     LAS bf16_t* VT = (LAS bf16_t*)(lds + SC_VT);
;     const int v8 = tid & 15;
; #pragma unroll
;     for (int e2 = 0; e2 < 2; ++e2) { const int i = (tid >> 4) + 32 * e2; const bf16x8 x = e2 ? r.x1 : r.x0; const int pc = ((((i >> 3) ^ (v8 & 7)) << 3) | (i & 7));
; #pragma unroll
;         for (int e = 0; e < 8; ++e) VT[(v8 * 8 + e) * LDT + pc] = (bf16_t)x[e]; }
; }
	v_cmp_gt_f32_e64 s[4:5], s33, v3
	v_pk_add_f32 v[20:21], v[20:21], 1.0 op_sel_hi:[1,0] neg_lo:[1,0] neg_hi:[1,0]
	s_nop 0
	v_cndmask_b32_e64 v9, 0, 32, s[4:5]
	v_ldexp_f32 v3, v3, v9
	v_log_f32_e32 v3, v3
	v_pk_mul_f32 v[20:21], v[48:49], v[20:21]
	v_mul_f32_e32 v9, 0x3f317217, v3
	v_fma_f32 v9, v3, s92, -v9
	v_fmac_f32_e32 v9, 0x3377d1cf, v3
	v_fmac_f32_e32 v9, 0x3f317217, v3
	v_cmp_lt_f32_e64 s[6:7], |v3|, s90
	s_nop 1
	v_cndmask_b32_e64 v3, v3, v9, s[6:7]
	v_cndmask_b32_e64 v9, 0, v238, s[4:5]
	v_sub_f32_e32 v3, v3, v9
	ds_write_b128 v52, v[4:7] offset:16896
	ds_write_b128 v52, v[0:3] offset:16912
	v_cvt_pk_bf16_f32 v0, v14, v15
	v_cvt_pk_bf16_f32 v1, v16, v17
	v_cvt_pk_bf16_f32 v2, v18, v19
	v_cvt_pk_bf16_f32 v3, v20, v21
	ds_write_b128 v10, v[0:3] offset:42496
	v_and_b32_e32 v0, 56, v13
	v_lshlrev_b32_e32 v1, 1, v8
	v_and_b32_e32 v1, 14, v1
	v_bitop3_b32 v0, v8, v0, -8 bitop3:0x6c
	v_add_u32_e32 v1, s95, v1
	v_lshlrev_b32_e32 v0, 1, v0
	v_mul_u32_u24_e32 v3, 0x90, v35
	v_and_b32_e32 v2, -8, v8
	v_add3_u32 v0, v1, v0, v3
	ds_write_b16 v0, v26
	ds_write_b16_d16_hi v0, v26 offset:144
	ds_write_b16 v0, v27 offset:288
	ds_write_b16_d16_hi v0, v27 offset:432
	ds_write_b16 v0, v28 offset:576
	ds_write_b16_d16_hi v0, v28 offset:720
	ds_write_b16 v0, v29 offset:864
	ds_write_b16_d16_hi v0, v29 offset:1008
	v_add_u32_e32 v0, 32, v2
	v_bitop3_b32 v0, v0, v13, 56 bitop3:0x78
	v_lshlrev_b32_e32 v0, 1, v0
	v_add3_u32 v0, v1, v0, v3
	ds_write_b16 v0, v30
	ds_write_b16_d16_hi v0, v30 offset:144
	ds_write_b16 v0, v31 offset:288
	ds_write_b16_d16_hi v0, v31 offset:432
	ds_write_b16 v0, v32 offset:576
	ds_write_b16_d16_hi v0, v32 offset:720
	ds_write_b16 v0, v33 offset:864
	ds_write_b16_d16_hi v0, v33 offset:1008
	v_ashrrev_i32_e32 v0, 31, v12
	v_lshrrev_b32_e32 v0, 25, v0
	v_add_u32_e32 v0, v12, v0
	v_ashrrev_i32_e32 v1, 7, v0
	v_and_b32_e32 v0, 0x3fffff80, v0
	v_sub_u32_e32 v0, v12, v0
	v_lshlrev_b32_e32 v4, 4, v1
	v_lshlrev_b32_e32 v5, 2, v0
	v_add_u32_e32 v0, 0, v5
	v_and_or_b32 v2, s24, 15, v4
	v_mad_u64_u32 v[2:3], s[4:5], v2, s91, v[0:1]
	s_waitcnt lgkmcnt(0)
	s_barrier
	ds_read_b32 v3, v2
	s_waitcnt lgkmcnt(0)
	v_add_f32_e32 v6, 0, v3
	ds_write_b32 v2, v6
	v_or_b32_e32 v2, s30, v4
	v_mad_u64_u32 v[2:3], s[4:5], v2, s91, v[0:1]
	ds_read_b32 v3, v2
	s_waitcnt lgkmcnt(0)
	v_add_f32_e32 v6, v6, v3
	ds_write_b32 v2, v6
	v_or_b32_e32 v2, s29, v4
	v_mad_u64_u32 v[2:3], s[4:5], v2, s91, v[0:1]
	ds_read_b32 v3, v2
	s_waitcnt lgkmcnt(0)
	v_add_f32_e32 v6, v6, v3
	ds_write_b32 v2, v6
	v_or_b32_e32 v2, s28, v4
	v_mad_u64_u32 v[2:3], s[4:5], v2, s91, v[0:1]
	ds_read_b32 v3, v2
	s_waitcnt lgkmcnt(0)
	v_add_f32_e32 v6, v6, v3
	ds_write_b32 v2, v6
	v_or_b32_e32 v2, s27, v4
	v_mad_u64_u32 v[2:3], s[4:5], v2, s91, v[0:1]
	ds_read_b32 v3, v2
	s_waitcnt lgkmcnt(0)
	v_add_f32_e32 v6, v6, v3
	ds_write_b32 v2, v6
	v_or_b32_e32 v2, s26, v4
	v_mad_u64_u32 v[2:3], s[4:5], v2, s91, v[0:1]
	ds_read_b32 v3, v2
	s_waitcnt lgkmcnt(0)
	v_add_f32_e32 v6, v6, v3
	ds_write_b32 v2, v6
	v_or_b32_e32 v2, s25, v4
	v_mad_u64_u32 v[2:3], s[4:5], v2, s91, v[0:1]
	ds_read_b32 v3, v2
	s_add_i32 s4, s16, 7
	s_waitcnt lgkmcnt(0)
	v_add_f32_e32 v6, v6, v3
	ds_write_b32 v2, v6
	v_or_b32_e32 v2, s4, v4
	v_mad_u64_u32 v[2:3], s[4:5], v2, s91, v[0:1]
	ds_read_b32 v3, v2
	s_waitcnt lgkmcnt(0)
	v_add_f32_e32 v6, v6, v3
	ds_write_b32 v2, v6
	v_subrev_u32_e32 v2, s16, v4
	v_mad_u64_u32 v[2:3], s[4:5], v2, s91, v[0:1]
	ds_read_b32 v3, v2 offset:4224
	s_waitcnt lgkmcnt(0)
	v_add_f32_e32 v6, v6, v3
	ds_write_b32 v2, v6 offset:4224
	v_or_b32_e32 v2, s23, v4
	v_mad_u64_u32 v[2:3], s[4:5], v2, s91, v[0:1]
	ds_read_b32 v3, v2
	s_waitcnt lgkmcnt(0)
	v_add_f32_e32 v6, v6, v3
	ds_write_b32 v2, v6
	v_or_b32_e32 v2, s22, v4
	v_mad_u64_u32 v[2:3], s[4:5], v2, s91, v[0:1]
	ds_read_b32 v3, v2
	s_waitcnt lgkmcnt(0)
	v_add_f32_e32 v6, v6, v3
	ds_write_b32 v2, v6
	v_or_b32_e32 v2, s21, v4
	v_mad_u64_u32 v[2:3], s[4:5], v2, s91, v[0:1]
	ds_read_b32 v3, v2
	s_waitcnt lgkmcnt(0)
	v_add_f32_e32 v6, v6, v3
	ds_write_b32 v2, v6
	v_or_b32_e32 v2, s20, v4
	v_mad_u64_u32 v[2:3], s[4:5], v2, s91, v[0:1]
	ds_read_b32 v3, v2
	s_waitcnt lgkmcnt(0)
	v_add_f32_e32 v6, v6, v3
	ds_write_b32 v2, v6
	v_or_b32_e32 v2, s19, v4
	v_mad_u64_u32 v[2:3], s[4:5], v2, s91, v[0:1]
	ds_read_b32 v3, v2
	s_waitcnt lgkmcnt(0)
	v_add_f32_e32 v6, v6, v3
	ds_write_b32 v2, v6
	v_or_b32_e32 v2, s18, v4
	v_mad_u64_u32 v[2:3], s[4:5], v2, s91, v[0:1]
	ds_read_b32 v3, v2
	s_waitcnt lgkmcnt(0)
	v_add_f32_e32 v6, v6, v3
	ds_write_b32 v2, v6
	v_or_b32_e32 v2, s17, v4
	v_mad_u64_u32 v[2:3], s[4:5], v2, s91, v[0:1]
	ds_read_b32 v3, v2
	v_cmp_gt_i32_e64 s[4:5], s0, v12
	s_movk_i32 s0, 0x7f
	v_cmp_lt_i32_e64 s[6:7], s0, v12
	v_cndmask_b32_e64 v4, 0, 1, s[4:5]
	s_waitcnt lgkmcnt(0)
	v_add_f32_e32 v3, v6, v3
	ds_write_b32 v2, v3
	v_lshl_add_u32 v2, v12, 2, s74
	ds_write_b32 v2, v3
	v_cndmask_b32_e64 v3, 0, 1, s[6:7]
	v_cndmask_b32_e32 v3, v4, v3, vcc
	v_and_b32_e32 v3, 1, v3
	v_add_u32_e32 v2, s74, v5
	v_cmp_eq_u32_e64 s[4:5], 1, v3
	v_mov_b32_e32 v3, 0
	s_waitcnt lgkmcnt(0)
	s_barrier
	s_and_saveexec_b64 s[6:7], s[4:5]
	s_cbranch_execz .LBB0_267
	ds_read_b32 v3, v2
	s_waitcnt lgkmcnt(0)
	v_add_f32_e32 v3, 0, v3

; #define LAS __attribute__((address_space(3)))
; __device__ __forceinline__ unsigned f2bf(float f) { unsigned u = __float_as_uint(f); return (u + 0x7fffu + ((u >> 16) & 1u)) >> 16; }
; template <int TYPE>
; __device__ __forceinline__ void cumsum_g(int dir, LAS unsigned char* lds, int tid) {
;     ...
;     float off = 0.f;
; #pragma unroll
;     for (int s = 0; s < NSEG; ++s) { const bool before = dir ? (s > seg) : (s < seg); if (before) off += SG[s * 128 + d]; }
; #pragma unroll
;     for (int ii = 0; ii < SEGL; ++ii) { const int i = seg * SEGL + ii; G[i * C::LDG + d] += off; }
;     __syncthreads();
; template <int TYPE>
; __device__ __forceinline__ void pass1_item(const KArgs& a, int l, int item, LAS unsigned char* lds) {
;     ...
; #pragma unroll
;     for (int e2 = 0; e2 < DK / 64; ++e2) { const int task = tid + 512 * e2, i = task & 63, d8 = task >> 6;
;         const f32x4 g0 = *(LAS f32x4*)(G + i * C::LDG + d8 * 8), g1 = *(LAS f32x4*)(G + i * C::LDG + d8 * 8 + 4);
;         const f32x4 t0 = *(LAS f32x4*)(G + last * C::LDG + d8 * 8), t1 = *(LAS f32x4*)(G + last * C::LDG + d8 * 8 + 4);
;         float kk[8]; unpack8(*(LAS bf16x8*)(Kb + i * C::LDK_ + d8 * 8), kk);
; #pragma unroll
;         for (int e = 0; e < 8; ++e) { const float gg = e < 4 ? g0[e] : g1[e - 4], tt = e < 4 ? t0[e] : t1[e - 4];
;             KDT[(d8 * 8 + e) * LDT + i] = (bf16_t)f2bf(kk[e] * __expf(tt - gg)); }
;         if (i == 0) { *(f32x4*)(Dout + d8 * 8) = (f32x4){__expf(t0[0]), __expf(t0[1]), __expf(t0[2]), __expf(t0[3])};
;                       *(f32x4*)(Dout + d8 * 8 + 4) = (f32x4){__expf(t1[0]), __expf(t1[1]), __expf(t1[2]), __expf(t1[3])}; } }
.LBB0_273:
	s_or_b64 exec, exec, s[6:7]
	s_movk_i32 s0, 0x2100
	v_mad_u64_u32 v[0:1], s[4:5], v1, s0, v[0:1]
	ds_read2_b32 v[4:5], v0 offset1:132
	v_add_u32_e32 v1, 0x400, v0
	ds_read2_b32 v[6:7], v1 offset0:8 offset1:140
	v_add_u32_e32 v8, 0x800, v0
	v_add_u32_e32 v10, 0xc00, v0
	s_waitcnt lgkmcnt(1)
	v_add_f32_e32 v2, v3, v4
	v_add_f32_e32 v4, v3, v5
	ds_write2_b32 v0, v2, v4 offset1:132
	ds_read2_b32 v[4:5], v8 offset0:16 offset1:148
	s_waitcnt lgkmcnt(2)
	v_add_f32_e32 v2, v3, v6
	v_add_f32_e32 v9, v3, v7
	ds_read2_b32 v[6:7], v10 offset0:24 offset1:156
	ds_write2_b32 v1, v2, v9 offset0:8 offset1:140
	s_waitcnt lgkmcnt(2)
	v_add_f32_e32 v1, v3, v4
	v_add_f32_e32 v2, v3, v5
	ds_write2_b32 v8, v1, v2 offset0:16 offset1:148
	v_add_u32_e32 v2, 0x1000, v0
	ds_read2_b32 v[4:5], v2 offset0:32 offset1:164
	v_add_u32_e32 v9, 0x1400, v0
	s_waitcnt lgkmcnt(3)
	v_add_f32_e32 v1, v3, v6
	v_add_f32_e32 v8, v3, v7
	ds_read2_b32 v[6:7], v9 offset0:40 offset1:172
	ds_write2_b32 v10, v1, v8 offset0:24 offset1:156
	s_waitcnt lgkmcnt(2)
	v_add_f32_e32 v1, v3, v4
	v_add_f32_e32 v4, v3, v5
	v_add_u32_e32 v8, 0x1c00, v0
	ds_write2_b32 v2, v1, v4 offset0:32 offset1:164
	s_waitcnt lgkmcnt(2)
	v_add_f32_e32 v2, v3, v6
	v_add_u32_e32 v6, 0x1800, v0
	ds_read2_b32 v[0:1], v8 offset0:56 offset1:188
	ds_read2_b32 v[4:5], v6 offset0:48 offset1:180
	s_and_b64 s[4:5], vcc, exec
	v_add_f32_e32 v7, v3, v7
	s_cselect_b32 s4, 0x81f0, 0
	s_waitcnt lgkmcnt(1)
	v_add_f32_e32 v0, v3, v0
	v_add_f32_e32 v1, v3, v1
	ds_write2_b32 v8, v0, v1 offset0:56 offset1:188
	v_and_b32_e32 v0, 63, v12
	v_mad_u32_u24 v13, v0, s91, 0
	v_lshlrev_b32_e32 v1, 8, v0
	v_ashrrev_i32_e32 v11, 3, v12
	ds_write2_b32 v9, v2, v7 offset0:40 offset1:172
	s_add_i32 s16, s4, 0
	v_sub_u32_e32 v9, v13, v1
	s_movk_i32 s4, 0xfef2
	v_and_b32_e32 v10, -8, v11
	s_waitcnt lgkmcnt(2)
	v_add_f32_e32 v2, v3, v4
	v_add_f32_e32 v4, v3, v5
	v_mad_i32_i24 v8, v0, s4, v9
	v_cmp_eq_u32_e32 vcc, 0, v0
	v_lshlrev_b32_e32 v0, 2, v10
	ds_write2_b32 v6, v2, v4 offset0:48 offset1:180
	v_add_u32_e32 v1, v13, v0
	v_lshl_add_u32 v2, v10, 1, v9
	v_add_u32_e32 v0, s16, v0
	s_waitcnt lgkmcnt(0)
	s_barrier
	ds_read_b128 v[14:17], v2 offset:33792
	ds_read_b128 v[18:21], v1
	ds_read_b128 v[22:25], v1 offset:16
	ds_read_b128 v[4:7], v0
	ds_read_b128 v[0:3], v0 offset:16
	v_or_b32_e32 v11, 7, v11
	s_waitcnt lgkmcnt(4)
	v_lshlrev_b32_e32 v26, 16, v14
	v_and_b32_e32 v27, 0xffff0000, v14
	s_waitcnt lgkmcnt(1)
	v_sub_f32_e32 v14, v4, v18
	v_mul_f32_e32 v14, 0x3fb8aa3b, v14
	v_exp_f32_e32 v14, v14
	v_lshlrev_b32_e32 v28, 16, v15
	v_and_b32_e32 v29, 0xffff0000, v15
	v_lshlrev_b32_e32 v30, 16, v16
	v_mul_f32_e32 v14, v14, v26
	v_bfe_u32 v15, v14, 16, 1
	v_add3_u32 v26, v14, v15, s1
	v_sub_f32_e32 v14, v5, v19
	v_mul_f32_e32 v14, 0x3fb8aa3b, v14
	v_exp_f32_e32 v19, v14
	v_mad_u64_u32 v[14:15], s[4:5], v10, s3, v[8:9]
	v_and_b32_e32 v16, 0xffff0000, v16
	v_mul_f32_e32 v15, v19, v27
	v_sub_f32_e32 v19, v6, v20
	v_mul_f32_e32 v19, 0x3fb8aa3b, v19
	v_exp_f32_e32 v19, v19
	v_bfe_u32 v20, v15, 16, 1
	v_add3_u32 v15, v15, v20, s1
	ds_write_b16_d16_hi v14, v15 offset:51344
	v_mul_f32_e32 v15, v19, v28
	v_sub_f32_e32 v19, v7, v21
	v_mul_f32_e32 v19, 0x3fb8aa3b, v19
	v_exp_f32_e32 v19, v19
	v_bfe_u32 v20, v15, 16, 1
	v_add3_u32 v15, v15, v20, s1
	ds_write_b16_d16_hi v14, v15 offset:51488
	v_mul_f32_e32 v15, v19, v29
	s_waitcnt lgkmcnt(2)
	v_sub_f32_e32 v19, v0, v22
	v_mul_f32_e32 v19, 0x3fb8aa3b, v19
	v_exp_f32_e32 v19, v19
	v_bfe_u32 v20, v15, 16, 1
	v_add3_u32 v15, v15, v20, s1
	ds_write_b16_d16_hi v14, v15 offset:51632
	v_mul_f32_e32 v15, v19, v30
	v_sub_f32_e32 v19, v1, v23
	v_mul_f32_e32 v19, 0x3fb8aa3b, v19
	v_exp_f32_e32 v19, v19
	v_bfe_u32 v20, v15, 16, 1
	v_add3_u32 v15, v15, v20, s1
	ds_write_b16_d16_hi v14, v15 offset:51776
	v_mul_f32_e32 v15, v19, v16
	v_sub_f32_e32 v16, v2, v24
	v_mul_f32_e32 v16, 0x3fb8aa3b, v16
	v_exp_f32_e32 v16, v16
	v_bfe_u32 v19, v15, 16, 1
	v_lshlrev_b32_e32 v18, 16, v17
	v_add3_u32 v15, v15, v19, s1
	ds_write_b16_d16_hi v14, v15 offset:51920
	v_mul_f32_e32 v15, v16, v18
	v_sub_f32_e32 v16, v3, v25
	v_mul_f32_e32 v16, 0x3fb8aa3b, v16
	v_exp_f32_e32 v16, v16
	v_bfe_u32 v18, v15, 16, 1
	v_and_b32_e32 v17, 0xffff0000, v17
	v_add3_u32 v15, v15, v18, s1
	ds_write_b16_d16_hi v14, v26 offset:51200
	ds_write_b16_d16_hi v14, v15 offset:52064
	v_mul_f32_e32 v14, v16, v17
	v_bfe_u32 v15, v14, 16, 1
	v_add3_u32 v16, v14, v15, s1
	v_mad_u64_u32 v[14:15], s[4:5], v11, s3, v[8:9]
	ds_write_b16_d16_hi v14, v16 offset:51200
	s_and_saveexec_b64 s[6:7], vcc
	s_cbranch_execz .LBB0_275
	v_mul_f32_e32 v4, 0x3fb8aa3b, v4
	v_mul_f32_e32 v5, 0x3fb8aa3b, v5
	v_mul_f32_e32 v6, 0x3fb8aa3b, v6
	v_mul_f32_e32 v7, 0x3fb8aa3b, v7
	v_ashrrev_i32_e32 v11, 31, v10
	v_exp_f32_e32 v4, v4
	v_exp_f32_e32 v5, v5
	v_exp_f32_e32 v6, v6
	v_exp_f32_e32 v7, v7
	v_lshl_add_u64 v[10:11], v[10:11], 2, s[12:13]
	v_mul_f32_e32 v0, 0x3fb8aa3b, v0
	v_mul_f32_e32 v1, 0x3fb8aa3b, v1
	v_mul_f32_e32 v2, 0x3fb8aa3b, v2
	v_mul_f32_e32 v3, 0x3fb8aa3b, v3
	v_lshl_add_u64 v[10:11], v[10:11], 0, s[8:9]
	v_exp_f32_e32 v0, v0
	v_exp_f32_e32 v1, v1
	v_exp_f32_e32 v2, v2
	v_exp_f32_e32 v3, v3
	v_add_co_u32_e64 v14, s[4:5], -16, v10
	s_nop 1
	v_addc_co_u32_e64 v15, s[4:5], -1, v11, s[4:5]
	global_store_dwordx4 v[14:15], v[4:7], off
	global_store_dwordx4 v[10:11], v[0:3], off
; #define LAS __attribute__((address_space(3)))
; __device__ __forceinline__ unsigned f2bf(float f) { unsigned u = __float_as_uint(f); return (u + 0x7fffu + ((u >> 16) & 1u)) >> 16; }
; template <int TYPE>
; __device__ __forceinline__ void pass1_item(const KArgs& a, int l, int item, LAS unsigned char* lds) {
;     ...
; #pragma unroll
;     for (int e2 = 0; e2 < DK / 64; ++e2) { const int task = tid + 512 * e2, i = task & 63, d8 = task >> 6;
;         const f32x4 g0 = *(LAS f32x4*)(G + i * C::LDG + d8 * 8), g1 = *(LAS f32x4*)(G + i * C::LDG + d8 * 8 + 4);
;         const f32x4 t0 = *(LAS f32x4*)(G + last * C::LDG + d8 * 8), t1 = *(LAS f32x4*)(G + last * C::LDG + d8 * 8 + 4);
;         float kk[8]; unpack8(*(LAS bf16x8*)(Kb + i * C::LDK_ + d8 * 8), kk);
; #pragma unroll
;         for (int e = 0; e < 8; ++e) { const float gg = e < 4 ? g0[e] : g1[e - 4], tt = e < 4 ? t0[e] : t1[e - 4];
;             KDT[(d8 * 8 + e) * LDT + i] = (bf16_t)f2bf(kk[e] * __expf(tt - gg)); }
;         if (i == 0) { *(f32x4*)(Dout + d8 * 8) = (f32x4){__expf(t0[0]), __expf(t0[1]), __expf(t0[2]), __expf(t0[3])};
;                       *(f32x4*)(Dout + d8 * 8 + 4) = (f32x4){__expf(t1[0]), __expf(t1[1]), __expf(t1[2]), __expf(t1[3])}; } }
.LBB0_275:
	s_or_b64 exec, exec, s[6:7]
	s_nop 0
	v_add_u32_e32 v0, 0x200, v12
	v_ashrrev_i32_e32 v11, 3, v0
	v_and_b32_e32 v10, -8, v11
	v_lshlrev_b32_e32 v0, 2, v10
	v_add_u32_e32 v1, v13, v0
	v_lshl_add_u32 v2, v10, 1, v9
	v_add_u32_e32 v0, s16, v0
	ds_read_b128 v[14:17], v2 offset:33792
	ds_read_b128 v[18:21], v1
	ds_read_b128 v[22:25], v1 offset:16
	ds_read_b128 v[4:7], v0
	ds_read_b128 v[0:3], v0 offset:16
	s_waitcnt lgkmcnt(0)
	v_lshlrev_b32_e32 v9, 16, v14
	v_and_b32_e32 v13, 0xffff0000, v14
	v_sub_f32_e32 v14, v4, v18
	v_mul_f32_e32 v14, 0x3fb8aa3b, v14
	v_exp_f32_e32 v14, v14
	v_lshlrev_b32_e32 v26, 16, v15
	v_and_b32_e32 v27, 0xffff0000, v15
	v_lshlrev_b32_e32 v28, 16, v16
	v_mul_f32_e32 v9, v14, v9
	v_bfe_u32 v14, v9, 16, 1
	v_add3_u32 v9, v9, v14, s1
	v_sub_f32_e32 v14, v5, v19
	v_mul_f32_e32 v14, 0x3fb8aa3b, v14
	v_exp_f32_e32 v19, v14
	v_mad_u64_u32 v[14:15], s[4:5], v10, s3, v[8:9]
	ds_write_b16_d16_hi v14, v9 offset:51200
	v_mul_f32_e32 v9, v19, v13
	v_sub_f32_e32 v13, v6, v20
	v_mul_f32_e32 v13, 0x3fb8aa3b, v13
	v_exp_f32_e32 v13, v13
	v_bfe_u32 v15, v9, 16, 1
	v_add3_u32 v9, v9, v15, s1
	ds_write_b16_d16_hi v14, v9 offset:51344
	v_mul_f32_e32 v9, v13, v26
	v_sub_f32_e32 v13, v7, v21
	v_mul_f32_e32 v13, 0x3fb8aa3b, v13
	v_exp_f32_e32 v13, v13
	v_bfe_u32 v15, v9, 16, 1
	v_add3_u32 v9, v9, v15, s1
	ds_write_b16_d16_hi v14, v9 offset:51488
	v_mul_f32_e32 v9, v13, v27
	v_sub_f32_e32 v13, v0, v22
	v_mul_f32_e32 v13, 0x3fb8aa3b, v13
	v_exp_f32_e32 v13, v13
	v_bfe_u32 v15, v9, 16, 1
	v_add3_u32 v9, v9, v15, s1
	ds_write_b16_d16_hi v14, v9 offset:51632
	v_mul_f32_e32 v9, v13, v28
	v_sub_f32_e32 v13, v1, v23
	v_mul_f32_e32 v13, 0x3fb8aa3b, v13
	v_exp_f32_e32 v13, v13
	v_bfe_u32 v15, v9, 16, 1
	v_and_b32_e32 v16, 0xffff0000, v16
	v_add3_u32 v9, v9, v15, s1
	ds_write_b16_d16_hi v14, v9 offset:51776
	v_mul_f32_e32 v9, v13, v16
	v_sub_f32_e32 v13, v2, v24
	v_mul_f32_e32 v13, 0x3fb8aa3b, v13
	v_exp_f32_e32 v13, v13
	v_bfe_u32 v15, v9, 16, 1
	v_lshlrev_b32_e32 v18, 16, v17
	v_add3_u32 v9, v9, v15, s1
	ds_write_b16_d16_hi v14, v9 offset:51920
	v_mul_f32_e32 v9, v13, v18
	v_sub_f32_e32 v13, v3, v25
	v_mul_f32_e32 v13, 0x3fb8aa3b, v13
	v_exp_f32_e32 v13, v13
	v_bfe_u32 v15, v9, 16, 1
	v_and_b32_e32 v17, 0xffff0000, v17
	v_add3_u32 v9, v9, v15, s1
	ds_write_b16_d16_hi v14, v9 offset:52064
	v_mul_f32_e32 v9, v13, v17
	v_bfe_u32 v13, v9, 16, 1
	v_add3_u32 v13, v9, v13, s1
	v_or_b32_e32 v9, 7, v11
	v_mad_u64_u32 v[8:9], s[4:5], v9, s3, v[8:9]
	ds_write_b16_d16_hi v8, v13 offset:51200
	s_and_saveexec_b64 s[4:5], vcc
	s_cbranch_execz .LBB0_264
	v_mul_f32_e32 v4, 0x3fb8aa3b, v4
	v_mul_f32_e32 v5, 0x3fb8aa3b, v5
	v_mul_f32_e32 v6, 0x3fb8aa3b, v6
	v_mul_f32_e32 v7, 0x3fb8aa3b, v7
	v_ashrrev_i32_e32 v11, 31, v10
	v_exp_f32_e32 v4, v4
	v_exp_f32_e32 v5, v5
	v_exp_f32_e32 v6, v6
	v_exp_f32_e32 v7, v7
	v_lshl_add_u64 v[8:9], v[10:11], 2, s[12:13]
	v_mul_f32_e32 v0, 0x3fb8aa3b, v0
	v_mul_f32_e32 v1, 0x3fb8aa3b, v1
	v_mul_f32_e32 v2, 0x3fb8aa3b, v2
	v_mul_f32_e32 v3, 0x3fb8aa3b, v3
	v_lshl_add_u64 v[8:9], v[8:9], 0, s[8:9]
	v_exp_f32_e32 v0, v0
	v_exp_f32_e32 v1, v1
	v_exp_f32_e32 v2, v2
	v_exp_f32_e32 v3, v3
	v_add_co_u32_e32 v10, vcc, -16, v8
	s_nop 1
	v_addc_co_u32_e32 v11, vcc, -1, v9, vcc
	global_store_dwordx4 v[10:11], v[4:7], off
	global_store_dwordx4 v[8:9], v[0:3], off
	s_branch .LBB0_264

; __device__ __forceinline__ unsigned xb_ld(unsigned* p)              { return __hip_atomic_load(p, __ATOMIC_RELAXED, __HIP_MEMORY_SCOPE_AGENT); }
; __device__ __forceinline__ void xcd_barrier_complete(unsigned* bar, unsigned x, unsigned& nloc, unsigned& nx) {
;     const unsigned G = gridDim.x * gridDim.y * gridDim.z;
;     unsigned sum, cnt, mine, sp = 0u;
;     for (;;) {
;         sum = 0u; cnt = 0u; mine = 0u;
; #pragma unroll
;         for (unsigned j = 0; j < 16; ++j) { const unsigned c = xb_ld(&bar[XB_XCNT(j)]); sum += c; cnt += (c > 0u) ? 1u : 0u; mine = (j == x) ? c : mine; }
;         if (sum == G) break;
;         __builtin_amdgcn_s_sleep(1);
;         if ((++sp & 255u) == 0u) { if (xb_ld(&bar[XB_TMO])) break; if (sp > XB_SPIN_CAP) { atomicAdd(&bar[XB_TMO], 1u); break; } }
;     }
;     nloc = mine > 0u ? mine : 1u; nx = cnt > 0u ? cnt : 1u;
; }
.LBB0_279:
	s_waitcnt lgkmcnt(0)
	v_mov_b64_e32 v[0:1], s[6:7]
	v_mov_b64_e32 v[2:3], s[8:9]
	global_load_dword v0, v[0:1], off sc1
	v_readlane_b32 s52, v255, 5
	global_load_dword v1, v[2:3], off sc1
	v_mov_b64_e32 v[2:3], s[10:11]
	global_load_dword v2, v[2:3], off sc1
	s_or_b64 s[50:51], s[50:51], exec
	s_or_b64 s[48:49], s[48:49], exec
	s_waitcnt vmcnt(0) lgkmcnt(0)
	v_add_u32_e32 v4, v1, v0
	v_add_u32_e32 v6, v4, v2
	v_mov_b64_e32 v[4:5], s[12:13]
	global_load_dword v3, v[4:5], off sc1
	v_mov_b64_e32 v[4:5], s[14:15]
	global_load_dword v4, v[4:5], off sc1
	s_waitcnt vmcnt(0) lgkmcnt(0)
	v_add_u32_e32 v6, v6, v3
	v_add_u32_e32 v8, v6, v4
	v_mov_b64_e32 v[6:7], s[16:17]
	global_load_dword v5, v[6:7], off sc1
	v_mov_b64_e32 v[6:7], s[18:19]
	global_load_dword v6, v[6:7], off sc1
	s_waitcnt vmcnt(0) lgkmcnt(0)
	v_add_u32_e32 v8, v8, v5
	v_add_u32_e32 v10, v8, v6
	v_mov_b64_e32 v[8:9], s[20:21]
	global_load_dword v7, v[8:9], off sc1
	v_mov_b64_e32 v[8:9], s[22:23]
	global_load_dword v8, v[8:9], off sc1
	s_waitcnt vmcnt(0) lgkmcnt(0)
	v_add_u32_e32 v10, v10, v7
	v_add_u32_e32 v12, v10, v8
	v_mov_b64_e32 v[10:11], s[24:25]
	global_load_dword v9, v[10:11], off sc1
	v_mov_b64_e32 v[10:11], s[26:27]
	global_load_dword v10, v[10:11], off sc1
	s_waitcnt vmcnt(0) lgkmcnt(0)
	v_add_u32_e32 v12, v12, v9
	v_add_u32_e32 v14, v12, v10
	v_mov_b64_e32 v[12:13], s[28:29]
	global_load_dword v11, v[12:13], off sc1
	v_mov_b64_e32 v[12:13], s[30:31]
	global_load_dword v12, v[12:13], off sc1
	s_waitcnt vmcnt(0) lgkmcnt(0)
	v_add_u32_e32 v14, v14, v11
	v_add_u32_e32 v16, v14, v12
	v_mov_b64_e32 v[14:15], s[34:35]
	global_load_dword v13, v[14:15], off sc1
	v_mov_b64_e32 v[14:15], s[40:41]
	global_load_dword v14, v[14:15], off sc1
	s_waitcnt vmcnt(0) lgkmcnt(0)
	v_add_u32_e32 v16, v16, v13
	v_add_u32_e32 v18, v16, v14
	v_mov_b64_e32 v[16:17], s[42:43]
	global_load_dword v15, v[16:17], off sc1
	s_waitcnt vmcnt(0) lgkmcnt(0)
	v_add_u32_e32 v16, v18, v15
	v_cmp_ne_u32_e32 vcc, s52, v16
	s_and_saveexec_b64 s[52:53], vcc
	s_cbranch_execz .LBB0_278
	s_and_b32 s58, s64, 0xff
	s_mov_b64 s[54:55], -1
	s_cmp_eq_u32 s58, 0
	s_mov_b64 s[60:61], -1
	s_mov_b64 s[58:59], -1
	s_sleep 1
	s_cbranch_scc1 .LBB0_282
	s_and_saveexec_b64 s[62:63], s[60:61]
	s_cbranch_execz .LBB0_277
	s_branch .LBB0_285
.LBB0_282:
	v_mov_b64_e32 v[16:17], s[4:5]
	global_load_dword v16, v[16:17], off sc1
	s_mov_b64 s[60:61], 0
	s_waitcnt vmcnt(0) lgkmcnt(0)
	v_cmp_eq_u32_e32 vcc, 0, v16
	s_and_saveexec_b64 s[62:63], vcc
	s_cmp_lt_u32 s64, 0x40001
	s_cselect_b64 s[60:61], -1, 0
	s_xor_b64 s[58:59], exec, -1
	s_and_b64 s[60:61], s[60:61], exec
	s_or_b64 exec, exec, s[62:63]
	s_movk_i32 s66, 0x80
	s_movk_i32 s67, 0x100
	s_and_saveexec_b64 s[62:63], s[60:61]
	s_cbranch_execz .LBB0_277

; #define LAS __attribute__((address_space(3)))
; __device__ __forceinline__ unsigned cvt_pk_bf16(float lo, float hi) { f32x2 v = {lo, hi}; bf16x2_t b = __builtin_convertvector(v, bf16x2_t); return __builtin_bit_cast(unsigned, b); }
; template <int TYPE>
; __device__ __forceinline__ LgRaw lg_issue(const bf16_t* u, int h, int dir, size_t tok0, int tid) {
;     ...
;         const int i0 = tid >> 4, d8 = tid & 15, col = (dir ? C_HFB : C_HFF) + h * 128 + d8 * 8;
;         r.a0 = *(const bf16x8*)(u + (tok0 + i0) * DINP + col); r.a1 = *(const bf16x8*)(u + (tok0 + 32 + i0) * DINP + col); r.k = r.a0;
;     } else {
;         const int i = tid >> 3, d8 = tid & 7; const bf16_t* ur = u + (tok0 + i) * DINP;
;         r.a0 = *(const bf16x8*)(ur + (dir ? C_GAB : C_GAF)); r.a1 = *(const bf16x8*)(ur + (dir ? C_GAB : C_GAF) + 8); r.k = *(const bf16x8*)(ur + C_GK + h * 64 + d8 * 8);
;     }
; template <int TYPE>
; __device__ __forceinline__ void pass1_item(const KArgs& a, int l, int item, LAS unsigned char* lds) {
;     ...
;     bf16_t* ST = (bf16_t*)(wsb + (TYPE ? WS_SH : WS_SG)) + (size_t)item * 128 * DK;
;     const bf16x8 b0 = vt_frag(VT, wid * 16 + fr, fq), b1 = vt_frag(VT, wid * 16 + fr, 4 + fq);
; #pragma unroll
;     for (int dt = 0; dt < DK / 16; ++dt) {
;         const bf16x8 a0 = *(LAS bf16x8*)(KDT + (dt * 16 + fr) * LDT + fq * 8), a1 = *(LAS bf16x8*)(KDT + (dt * 16 + fr) * LDT + 32 + fq * 8);
;         f32x4 acc = {0.f, 0.f, 0.f, 0.f};
;         acc = __builtin_amdgcn_mfma_f32_16x16x32_bf16(a0, b0, acc, 0, 0, 0);
;         acc = __builtin_amdgcn_mfma_f32_16x16x32_bf16(a1, b1, acc, 0, 0, 0);
;         u32x2 w; w.x = cvt_pk_bf16(acc[0], acc[1]); w.y = cvt_pk_bf16(acc[2], acc[3]);
;         *(u32x2*)(ST + (size_t)(wid * 16 + fr) * DK + dt * 16 + fq * 4) = w;
;     }
.LBB0_287:
	s_or_b64 exec, exec, s[4:5]
	v_ashrrev_i32_e32 v0, 2, v12
	v_bfe_u32 v10, v12, 4, 2
	v_bfi_b32 v8, -16, v0, v12
	v_and_b32_e32 v11, 15, v12
	v_and_b32_e32 v1, -16, v0
	v_mul_lo_u32 v0, v8, s3
	v_lshlrev_b32_e32 v12, 3, v10
	v_ashrrev_i32_e32 v9, 31, v8
	v_add_u32_e32 v4, s95, v0
	v_bitop3_b32 v0, v8, v12, 56 bitop3:0x6c
	v_lshlrev_b64 v[8:9], 7, v[8:9]
	v_or_b32_e32 v8, v8, v12
	v_bitop3_b32 v5, v1, 56, v11 bitop3:0xc8
	v_lshl_add_u64 v[8:9], s[12:13], 0, v[8:9]
	v_lshl_add_u32 v0, v0, 1, v4
	v_bitop3_b32 v5, v12, v5, 32 bitop3:0x36
	v_lshl_add_u64 v[16:17], v[8:9], 0, s[8:9]
	v_mul_u32_u24_e32 v8, 0x90, v11
	v_lshlrev_b32_e32 v9, 4, v10
	s_waitcnt lgkmcnt(0)
	s_barrier
	ds_read_b128 v[0:3], v0
	v_lshl_add_u32 v4, v5, 1, v4
	v_add3_u32 v18, 0, v8, v9
	ds_read_b128 v[4:7], v4
	ds_read_b128 v[8:11], v18 offset:51200
	ds_read_b128 v[12:15], v18 offset:51264
	s_waitcnt lgkmcnt(0)
	v_mfma_f32_16x16x32_bf16 v[8:11], v[8:11], v[0:3], 0
	s_movk_i32 s4, 0xffa0
	s_add_i32 s16, s16, s70
	v_mfma_f32_16x16x32_bf16 v[8:11], v[12:15], v[4:7], v[8:11]
	s_nop 7
	v_cvt_pk_bf16_f32 v8, v8, v9
	v_cvt_pk_bf16_f32 v9, v10, v11
	v_add_co_u32_e32 v10, vcc, s4, v16
	s_movk_i32 s4, 0xffc0
	s_nop 0
	v_addc_co_u32_e32 v11, vcc, -1, v17, vcc
	global_store_dwordx2 v[10:11], v[8:9], off
	ds_read_b128 v[8:11], v18 offset:53504
	ds_read_b128 v[12:15], v18 offset:53568
	s_waitcnt lgkmcnt(0)
	v_mfma_f32_16x16x32_bf16 v[8:11], v[8:11], v[0:3], 0
	v_mfma_f32_16x16x32_bf16 v[8:11], v[12:15], v[4:7], v[8:11]
	s_nop 7
	v_cvt_pk_bf16_f32 v8, v8, v9
	v_cvt_pk_bf16_f32 v9, v10, v11
	v_add_co_u32_e32 v10, vcc, s4, v16
	s_movk_i32 s4, 0xffe0
	s_nop 0
	v_addc_co_u32_e32 v11, vcc, -1, v17, vcc
	global_store_dwordx2 v[10:11], v[8:9], off
	ds_read_b128 v[8:11], v18 offset:55808
	ds_read_b128 v[12:15], v18 offset:55872
	s_waitcnt lgkmcnt(0)
	v_mfma_f32_16x16x32_bf16 v[8:11], v[8:11], v[0:3], 0
	v_mfma_f32_16x16x32_bf16 v[8:11], v[12:15], v[4:7], v[8:11]
	s_nop 7
	v_cvt_pk_bf16_f32 v8, v8, v9
	v_cvt_pk_bf16_f32 v9, v10, v11
	v_add_co_u32_e32 v10, vcc, s4, v16
	v_readlane_b32 s4, v254, 40
	s_nop 0
	v_addc_co_u32_e32 v11, vcc, -1, v17, vcc
	global_store_dwordx2 v[10:11], v[8:9], off
	ds_read_b128 v[8:11], v18 offset:58112
	ds_read_b128 v[12:15], v18 offset:58176
	s_waitcnt lgkmcnt(0)
	v_mfma_f32_16x16x32_bf16 v[0:3], v[8:11], v[0:3], 0
	s_add_i32 s15, s15, s4
	v_readlane_b32 s4, v254, 63
	v_readlane_b32 s5, v255, 0
	v_mfma_f32_16x16x32_bf16 v[0:3], v[12:15], v[4:7], v[0:3]
	s_add_u32 s10, s10, s4
	s_addc_u32 s11, s11, s5
	v_readlane_b32 s4, v255, 12
	v_readlane_b32 s5, v255, 13
	s_add_u32 s8, s8, s4
	s_addc_u32 s9, s9, s5
	s_nop 1
	v_cvt_pk_bf16_f32 v0, v0, v1
	v_cvt_pk_bf16_f32 v1, v2, v3
	s_cmpk_gt_i32 s16, 0xfff
	global_store_dwordx2 v[16:17], v[0:1], off
	s_cbranch_scc1 .LBB0_261
.LBB0_288:
	s_ashr_i32 s4, s16, 11
	s_ashr_i32 s5, s4, 31
	s_lshl_b64 s[4:5], s[4:5], 14
	s_and_b32 s6, s15, 0x3fc0
	s_mov_b64 s[12:13], s[68:69]
	v_mov_b32_e32 v12, v195
	s_bfe_i32 s18, s16, 0x10008
	s_bfe_u32 s17, s16, 0x10008
	s_bfe_u32 s19, s16, 0x20009
	s_or_b32 s4, s4, s6
	s_add_u32 s6, s12, 0xe300000
	v_ashrrev_i32_e32 v8, 3, v12
	s_addc_u32 s7, s13, 0
	v_ashrrev_i32_e32 v9, 31, v8
	v_lshl_add_u64 v[0:1], s[4:5], 0, v[8:9]
	v_mov_b64_e32 v[2:3], s[6:7]
	v_mad_u64_u32 v[2:3], s[20:21], v0, s2, v[2:3]
	s_mulk_i32 s5, 0x2a00
	s_mul_hi_u32 s21, s4, 0x2a00
	s_lshl_b32 s20, s19, 7
	s_add_i32 s21, s21, s5
	s_mulk_i32 s4, 0x2a00
	s_add_u32 s4, s6, s4
	s_addc_u32 s5, s7, s21
	s_lshl_b32 s19, s19, 8
	s_add_u32 s4, s4, s19
	s_addc_u32 s5, s5, 0
	s_or_b32 s21, s17, s14
	s_lshl_b32 s72, s21, 12
	v_readlane_b32 s36, v253, 48
	s_lshl_b64 s[6:7], s[72:73], 2
	v_readlane_b32 s42, v253, 54
	v_readlane_b32 s43, v253, 55
	s_add_u32 s6, s42, s6
	s_addc_u32 s7, s43, s7
	s_add_u32 s6, s6, s19
	s_addc_u32 s7, s7, 0
	s_lshl_b32 s72, s21, 8
	v_readlane_b32 s44, v253, 56
	s_lshl_b64 s[22:23], s[72:73], 2
	v_readlane_b32 s45, v253, 57
	s_add_u32 s21, s44, s22
	s_addc_u32 s23, s45, s23
	s_add_u32 s22, s21, s19
	s_addc_u32 s23, s23, 0
	s_add_i32 s19, s17, 3
	s_cmp_eq_u32 s17, 0
	s_cselect_b64 vcc, -1, 0
	s_and_b64 s[24:25], vcc, exec
	s_movk_i32 s21, 0x820
	v_lshlrev_b32_e32 v9, 3, v12
	v_mad_i32_i24 v3, v1, s2, v3
	s_cselect_b32 s72, 0x800, s21
	s_mov_b32 s21, s73
	v_and_b32_e32 v13, 56, v9
	v_ashrrev_i32_e32 v35, 4, v12
	s_movk_i32 s2, 0x2a00
	v_lshl_add_u64 v[0:1], v[2:3], 0, s[20:21]
	v_lshlrev_b32_e32 v112, 1, v13
	v_mov_b64_e32 v[6:7], s[4:5]
	v_and_b32_e32 v37, 0x78, v9
	v_add_u32_e32 v16, 32, v35
	v_lshl_add_u64 v[10:11], v[2:3], 0, s[72:73]
	v_lshl_add_u64 v[0:1], v[0:1], 0, v[112:113]
	v_mad_i64_i32 v[4:5], s[4:5], v35, s2, v[6:7]
	v_lshlrev_b32_e32 v14, 1, v37
	v_mov_b32_e32 v15, v113
	v_mad_i64_i32 v[6:7], s[4:5], v16, s2, v[6:7]
	s_waitcnt lgkmcnt(0)
	s_barrier
; template <int TYPE>
; __device__ __forceinline__ LgRaw lg_issue(const bf16_t* u, int h, int dir, size_t tok0, int tid) {
;     ...
;     } else {
;         const int i = tid >> 3, d8 = tid & 7; const bf16_t* ur = u + (tok0 + i) * DINP;
;         r.a0 = *(const bf16x8*)(ur + (dir ? C_GAB : C_GAF)); r.a1 = *(const bf16x8*)(ur + (dir ? C_GAB : C_GAF) + 8); r.k = *(const bf16x8*)(ur + C_GK + h * 64 + d8 * 8);
; template <int TYPE>
; __device__ __forceinline__ void lg_compute(const KArgs& a, unsigned char* wsb, int l, int h, int dir, const LgRaw& raw, LAS unsigned char* lds, int tid) {
;     ...
;         const int i = tid >> 3, d8 = tid & 7;
;         float ua[16]; unpack8(raw.a0, ua); unpack8(raw.a1, ua + 8);
;         const float* up = (const float*)a.in[3] + (size_t)((l * 2 + dir) * 16) * 256 + h * 64 + d8 * 8;
;         const float* bs = (const float*)a.in[4] + (l * 2 + dir) * 256 + h * 64 + d8 * 8;
;         f32x4 z0 = *(const f32x4*)bs, z1 = *(const f32x4*)(bs + 4);
; #pragma unroll
;         for (int r = 0; r < 16; ++r) { z0 += ua[r] * *(const f32x4*)(up + r * 256); z1 += ua[r] * *(const f32x4*)(up + r * 256 + 4); }
	global_load_dwordx4 v[0:3], v[0:1], off offset:512
	v_lshl_add_u64 v[4:5], v[4:5], 0, v[14:15]
	v_lshl_add_u64 v[6:7], v[6:7], 0, v[14:15]
	global_load_dwordx4 v[14:17], v[10:11], off
	s_mov_b64 s[4:5], 0x1000
	s_movk_i32 s0, 0x3000
	s_mov_b32 s20, 0xbfb8aa3b
	s_movk_i32 s93, 0x110
	v_readlane_b32 s37, v253, 49
	v_readlane_b32 s38, v253, 50
	v_readlane_b32 s39, v253, 51
	v_readlane_b32 s40, v253, 52
	v_readlane_b32 s41, v253, 53
	v_readlane_b32 s46, v253, 58
	v_readlane_b32 s47, v253, 59
	v_readlane_b32 s48, v253, 60
	v_readlane_b32 s49, v253, 61
	v_readlane_b32 s50, v253, 62
	v_readlane_b32 s51, v253, 63
	s_waitcnt vmcnt(0) lgkmcnt(0)
	v_lshlrev_b32_e32 v30, 16, v14
	v_and_b32_e32 v32, 0xffff0000, v14
	v_lshlrev_b32_e32 v34, 16, v15
	v_and_b32_e32 v36, 0xffff0000, v15
	v_lshlrev_b32_e32 v38, 16, v16
	v_and_b32_e32 v40, 0xffff0000, v16
	v_lshlrev_b32_e32 v42, 16, v17
	v_and_b32_e32 v44, 0xffff0000, v17
	global_load_dwordx4 v[14:17], v[10:11], off offset:16
	v_lshlrev_b32_e32 v10, 2, v13
	v_mov_b32_e32 v11, v113
	v_lshl_add_u64 v[62:63], s[6:7], 0, v[10:11]
	s_waitcnt vmcnt(0) lgkmcnt(0)
	v_lshlrev_b32_e32 v46, 16, v14
	v_and_b32_e32 v48, 0xffff0000, v14
	v_lshlrev_b32_e32 v50, 16, v15
	v_and_b32_e32 v52, 0xffff0000, v15
	v_lshlrev_b32_e32 v54, 16, v16
	v_and_b32_e32 v56, 0xffff0000, v16
	v_lshlrev_b32_e32 v58, 16, v17
	v_and_b32_e32 v60, 0xffff0000, v17
	global_load_dwordx4 v[14:17], v10, s[22:23] offset:16
	global_load_dwordx4 v[18:21], v10, s[22:23]
	global_load_dwordx4 v[22:25], v10, s[6:7] offset:16
	global_load_dwordx4 v[26:29], v10, s[6:7]
	s_waitcnt vmcnt(1)
	v_pk_fma_f32 v[22:23], v[30:31], v[22:23], v[14:15] op_sel_hi:[0,1,1]
	s_waitcnt vmcnt(0)
	v_pk_fma_f32 v[26:27], v[30:31], v[26:27], v[18:19] op_sel_hi:[0,1,1]
	v_pk_fma_f32 v[28:29], v[30:31], v[28:29], v[20:21] op_sel_hi:[0,1,1]
	v_pk_fma_f32 v[24:25], v[30:31], v[24:25], v[16:17] op_sel_hi:[0,1,1]
	global_load_dwordx4 v[14:17], v10, s[6:7] offset:1040
	global_load_dwordx4 v[18:21], v10, s[6:7] offset:1024
	s_waitcnt vmcnt(1)
	v_pk_fma_f32 v[24:25], v[32:33], v[16:17], v[24:25] op_sel_hi:[0,1,1]
	s_waitcnt vmcnt(0)
	v_pk_fma_f32 v[28:29], v[32:33], v[20:21], v[28:29] op_sel_hi:[0,1,1]
	v_pk_fma_f32 v[26:27], v[32:33], v[18:19], v[26:27] op_sel_hi:[0,1,1]
	v_pk_fma_f32 v[22:23], v[32:33], v[14:15], v[22:23] op_sel_hi:[0,1,1]
	global_load_dwordx4 v[14:17], v10, s[6:7] offset:2064
	global_load_dwordx4 v[18:21], v10, s[6:7] offset:2048
	s_waitcnt vmcnt(1)
	v_pk_fma_f32 v[22:23], v[34:35], v[14:15], v[22:23] op_sel_hi:[0,1,1]
	s_waitcnt vmcnt(0)
	v_pk_fma_f32 v[26:27], v[34:35], v[18:19], v[26:27] op_sel_hi:[0,1,1]
	v_pk_fma_f32 v[28:29], v[34:35], v[20:21], v[28:29] op_sel_hi:[0,1,1]
	v_pk_fma_f32 v[24:25], v[34:35], v[16:17], v[24:25] op_sel_hi:[0,1,1]
	global_load_dwordx4 v[14:17], v10, s[6:7] offset:3088
	global_load_dwordx4 v[18:21], v10, s[6:7] offset:3072
	s_waitcnt vmcnt(1)
	v_pk_fma_f32 v[24:25], v[36:37], v[16:17], v[24:25] op_sel_hi:[0,1,1]
	s_waitcnt vmcnt(0)
	v_pk_fma_f32 v[26:27], v[36:37], v[18:19], v[26:27] op_sel_hi:[0,1,1]
	v_lshl_add_u64 v[18:19], v[62:63], 0, s[4:5]
	v_add_co_u32_e64 v30, s[4:5], s77, v62
	v_pk_fma_f32 v[28:29], v[36:37], v[20:21], v[28:29] op_sel_hi:[0,1,1]
	s_nop 0
	v_addc_co_u32_e64 v31, s[4:5], 0, v63, s[4:5]
	s_movk_i32 s4, 0x2000
	s_nop 0
	v_add_co_u32_e64 v32, s[4:5], s4, v62
	v_pk_fma_f32 v[22:23], v[36:37], v[14:15], v[22:23] op_sel_hi:[0,1,1]
	s_nop 0
	v_addc_co_u32_e64 v33, s[4:5], 0, v63, s[4:5]
	global_load_dwordx4 v[14:17], v[32:33], off offset:-4096
	s_nop 0
	global_load_dwordx4 v[18:21], v[18:19], off offset:16
	s_mov_b64 s[4:5], 0x1400
	s_waitcnt vmcnt(1)
	v_pk_fma_f32 v[26:27], v[38:39], v[14:15], v[26:27] op_sel_hi:[0,1,1]
	s_waitcnt vmcnt(0)
	v_pk_fma_f32 v[22:23], v[38:39], v[18:19], v[22:23] op_sel_hi:[0,1,1]
	v_lshl_add_u64 v[18:19], v[62:63], 0, s[4:5]
	v_pk_fma_f32 v[28:29], v[38:39], v[16:17], v[28:29] op_sel_hi:[0,1,1]
	v_pk_fma_f32 v[24:25], v[38:39], v[20:21], v[24:25] op_sel_hi:[0,1,1]
	global_load_dwordx4 v[14:17], v[30:31], off offset:1024
	s_nop 0
	global_load_dwordx4 v[18:21], v[18:19], off offset:16
	s_mov_b64 s[4:5], 0x1800
	s_waitcnt vmcnt(1)
	v_pk_fma_f32 v[28:29], v[40:41], v[16:17], v[28:29] op_sel_hi:[0,1,1]
	s_waitcnt vmcnt(0)
	v_pk_fma_f32 v[22:23], v[40:41], v[18:19], v[22:23] op_sel_hi:[0,1,1]
	v_lshl_add_u64 v[18:19], v[62:63], 0, s[4:5]
	v_pk_fma_f32 v[26:27], v[40:41], v[14:15], v[26:27] op_sel_hi:[0,1,1]
	v_pk_fma_f32 v[24:25], v[40:41], v[20:21], v[24:25] op_sel_hi:[0,1,1]
	global_load_dwordx4 v[14:17], v[30:31], off offset:2048
	s_nop 0
	global_load_dwordx4 v[18:21], v[18:19], off offset:16
	s_mov_b64 s[4:5], 0x1c00
	s_waitcnt vmcnt(1)
	v_pk_fma_f32 v[26:27], v[42:43], v[14:15], v[26:27] op_sel_hi:[0,1,1]
	s_waitcnt vmcnt(0)
	v_pk_fma_f32 v[22:23], v[42:43], v[18:19], v[22:23] op_sel_hi:[0,1,1]
	v_lshl_add_u64 v[18:19], v[62:63], 0, s[4:5]
	v_pk_fma_f32 v[28:29], v[42:43], v[16:17], v[28:29] op_sel_hi:[0,1,1]
	v_pk_fma_f32 v[24:25], v[42:43], v[20:21], v[24:25] op_sel_hi:[0,1,1]
	global_load_dwordx4 v[14:17], v[30:31], off offset:3072
	s_nop 0
	global_load_dwordx4 v[18:21], v[18:19], off offset:16
	s_mov_b64 s[4:5], 0x2000
	s_waitcnt vmcnt(1)
	v_pk_fma_f32 v[28:29], v[44:45], v[16:17], v[28:29] op_sel_hi:[0,1,1]
	s_waitcnt vmcnt(0)
	v_pk_fma_f32 v[22:23], v[44:45], v[18:19], v[22:23] op_sel_hi:[0,1,1]
	v_lshl_add_u64 v[18:19], v[62:63], 0, s[4:5]
	v_pk_fma_f32 v[26:27], v[44:45], v[14:15], v[26:27] op_sel_hi:[0,1,1]
	v_pk_fma_f32 v[24:25], v[44:45], v[20:21], v[24:25] op_sel_hi:[0,1,1]
	global_load_dwordx4 v[14:17], v[32:33], off
	s_nop 0
	global_load_dwordx4 v[18:21], v[18:19], off offset:16
	s_mov_b64 s[4:5], 0x2400
	s_waitcnt vmcnt(1)
; __device__ __forceinline__ float logsigmoid_(float z) { return fminf(z, 0.f) - __logf(1.f + __expf(-fabsf(z))); }
; template <int TYPE>
; __device__ __forceinline__ void lg_compute(const KArgs& a, unsigned char* wsb, int l, int h, int dir, const LgRaw& raw, LAS unsigned char* lds, int tid) {
;     ...
;         for (int r = 0; r < 16; ++r) { z0 += ua[r] * *(const f32x4*)(up + r * 256); z1 += ua[r] * *(const f32x4*)(up + r * 256 + 4); }
;         f32x4 g0, g1;
; #pragma unroll
;         for (int e = 0; e < 4; ++e) { g0[e] = logsigmoid_(z0[e]) * (1.f / 16.f); g1[e] = logsigmoid_(z1[e]) * (1.f / 16.f); }
	v_pk_fma_f32 v[26:27], v[46:47], v[14:15], v[26:27] op_sel_hi:[0,1,1]
	s_waitcnt vmcnt(0)
	v_pk_fma_f32 v[22:23], v[46:47], v[18:19], v[22:23] op_sel_hi:[0,1,1]
	v_lshl_add_u64 v[18:19], v[62:63], 0, s[4:5]
	v_pk_fma_f32 v[28:29], v[46:47], v[16:17], v[28:29] op_sel_hi:[0,1,1]
	v_pk_fma_f32 v[24:25], v[46:47], v[20:21], v[24:25] op_sel_hi:[0,1,1]
	global_load_dwordx4 v[14:17], v[32:33], off offset:1024
	s_nop 0
	global_load_dwordx4 v[18:21], v[18:19], off offset:16
	s_mov_b64 s[4:5], 0x2800
	s_waitcnt vmcnt(1)
	v_pk_fma_f32 v[28:29], v[48:49], v[16:17], v[28:29] op_sel_hi:[0,1,1]
	s_waitcnt vmcnt(0)
	v_pk_fma_f32 v[22:23], v[48:49], v[18:19], v[22:23] op_sel_hi:[0,1,1]
	v_lshl_add_u64 v[18:19], v[62:63], 0, s[4:5]
	v_pk_fma_f32 v[26:27], v[48:49], v[14:15], v[26:27] op_sel_hi:[0,1,1]
	v_pk_fma_f32 v[24:25], v[48:49], v[20:21], v[24:25] op_sel_hi:[0,1,1]
	global_load_dwordx4 v[14:17], v[32:33], off offset:2048
	s_nop 0
	global_load_dwordx4 v[18:21], v[18:19], off offset:16
	s_mov_b64 s[4:5], 0x2c00
	s_waitcnt vmcnt(1)
	v_pk_fma_f32 v[26:27], v[50:51], v[14:15], v[26:27] op_sel_hi:[0,1,1]
	s_waitcnt vmcnt(0)
	v_pk_fma_f32 v[22:23], v[50:51], v[18:19], v[22:23] op_sel_hi:[0,1,1]
	v_lshl_add_u64 v[18:19], v[62:63], 0, s[4:5]
	v_pk_fma_f32 v[28:29], v[50:51], v[16:17], v[28:29] op_sel_hi:[0,1,1]
	v_pk_fma_f32 v[24:25], v[50:51], v[20:21], v[24:25] op_sel_hi:[0,1,1]
	global_load_dwordx4 v[14:17], v[32:33], off offset:3072
	s_nop 0
	global_load_dwordx4 v[18:21], v[18:19], off offset:16
	s_mov_b64 s[4:5], 0x3000
	s_waitcnt vmcnt(1)
	v_pk_fma_f32 v[28:29], v[52:53], v[16:17], v[28:29] op_sel_hi:[0,1,1]
	s_waitcnt vmcnt(0)
	v_pk_fma_f32 v[22:23], v[52:53], v[18:19], v[22:23] op_sel_hi:[0,1,1]
	v_lshl_add_u64 v[18:19], v[62:63], 0, s[4:5]
	v_add_co_u32_e64 v30, s[4:5], s0, v62
	v_pk_fma_f32 v[26:27], v[52:53], v[14:15], v[26:27] op_sel_hi:[0,1,1]
	s_nop 0
	v_addc_co_u32_e64 v31, s[4:5], 0, v63, s[4:5]
	v_pk_fma_f32 v[24:25], v[52:53], v[20:21], v[24:25] op_sel_hi:[0,1,1]
	global_load_dwordx4 v[14:17], v[30:31], off
	s_nop 0
	global_load_dwordx4 v[18:21], v[18:19], off offset:16
	s_mov_b64 s[4:5], 0x3400
	s_mov_b32 s0, 0x3d800000
	s_waitcnt vmcnt(1)
	v_pk_fma_f32 v[26:27], v[54:55], v[14:15], v[26:27] op_sel_hi:[0,1,1]
	s_waitcnt vmcnt(0)
	v_pk_fma_f32 v[22:23], v[54:55], v[18:19], v[22:23] op_sel_hi:[0,1,1]
	v_lshl_add_u64 v[18:19], v[62:63], 0, s[4:5]
	v_pk_fma_f32 v[28:29], v[54:55], v[16:17], v[28:29] op_sel_hi:[0,1,1]
	v_pk_fma_f32 v[24:25], v[54:55], v[20:21], v[24:25] op_sel_hi:[0,1,1]
	global_load_dwordx4 v[14:17], v[30:31], off offset:1024
	s_nop 0
	global_load_dwordx4 v[18:21], v[18:19], off offset:16
	s_mov_b64 s[4:5], 0x3800
	s_waitcnt vmcnt(1)
	v_pk_fma_f32 v[28:29], v[56:57], v[16:17], v[28:29] op_sel_hi:[0,1,1]
	s_waitcnt vmcnt(0)
	v_pk_fma_f32 v[22:23], v[56:57], v[18:19], v[22:23] op_sel_hi:[0,1,1]
	v_lshl_add_u64 v[18:19], v[62:63], 0, s[4:5]
	v_pk_fma_f32 v[26:27], v[56:57], v[14:15], v[26:27] op_sel_hi:[0,1,1]
	v_pk_fma_f32 v[24:25], v[56:57], v[20:21], v[24:25] op_sel_hi:[0,1,1]
	global_load_dwordx4 v[14:17], v[30:31], off offset:2048
	s_nop 0
	global_load_dwordx4 v[18:21], v[18:19], off offset:16
	s_mov_b64 s[4:5], 0x3c00
	s_waitcnt vmcnt(1)
	v_pk_fma_f32 v[26:27], v[58:59], v[14:15], v[26:27] op_sel_hi:[0,1,1]
	s_waitcnt vmcnt(0)
	v_pk_fma_f32 v[22:23], v[58:59], v[18:19], v[22:23] op_sel_hi:[0,1,1]
	v_lshl_add_u64 v[18:19], v[62:63], 0, s[4:5]
	v_pk_fma_f32 v[28:29], v[58:59], v[16:17], v[28:29] op_sel_hi:[0,1,1]
	v_pk_fma_f32 v[24:25], v[58:59], v[20:21], v[24:25] op_sel_hi:[0,1,1]
	global_load_dwordx4 v[14:17], v[30:31], off offset:3072
	s_nop 0
	global_load_dwordx4 v[18:21], v[18:19], off offset:16
	s_waitcnt vmcnt(1)
	v_pk_fma_f32 v[14:15], v[60:61], v[14:15], v[26:27] op_sel_hi:[0,1,1]
	v_mul_f32_e64 v11, |v14|, s20
	v_exp_f32_e32 v11, v11
	s_waitcnt vmcnt(0)
	v_pk_fma_f32 v[18:19], v[60:61], v[18:19], v[22:23] op_sel_hi:[0,1,1]
	v_min_f32_e32 v22, 0, v14
	v_pk_fma_f32 v[20:21], v[60:61], v[20:21], v[24:25] op_sel_hi:[0,1,1]
	v_add_f32_e32 v11, 1.0, v11
	v_cmp_gt_f32_e64 s[4:5], s33, v11
	v_min_f32_e32 v24, 0, v18
	v_min_f32_e32 v23, 0, v15
	v_cndmask_b32_e64 v14, 0, 32, s[4:5]
	v_ldexp_f32 v11, v11, v14
	v_log_f32_e32 v11, v11
	v_min_f32_e32 v25, 0, v19
	v_pk_fma_f32 v[16:17], v[60:61], v[16:17], v[28:29] op_sel_hi:[0,1,1]
	v_min_f32_e32 v26, 0, v16
	v_mul_f32_e32 v14, 0x3f317217, v11
	v_fma_f32 v14, v11, s92, -v14
	v_fmac_f32_e32 v14, 0x3377d1cf, v11
	v_fmac_f32_e32 v14, 0x3f317217, v11
	v_cmp_lt_f32_e64 s[6:7], |v11|, s90
	v_min_f32_e32 v28, 0, v20
	v_min_f32_e32 v27, 0, v17
	v_cndmask_b32_e64 v11, v11, v14, s[6:7]
	v_cndmask_b32_e64 v14, 0, v238, s[4:5]
	v_sub_f32_e32 v14, v11, v14
	v_mul_f32_e64 v11, |v18|, s20
	v_exp_f32_e32 v11, v11
	v_min_f32_e32 v29, 0, v21
	v_add_f32_e32 v11, 1.0, v11
	v_cmp_gt_f32_e64 s[4:5], s33, v11
	s_nop 1
	v_cndmask_b32_e64 v18, 0, 32, s[4:5]
	v_ldexp_f32 v11, v11, v18
	v_log_f32_e32 v11, v11
	s_nop 0
	v_mul_f32_e32 v18, 0x3f317217, v11
	v_fma_f32 v18, v11, s92, -v18
	v_fmac_f32_e32 v18, 0x3377d1cf, v11
	v_fmac_f32_e32 v18, 0x3f317217, v11
	v_cmp_lt_f32_e64 s[6:7], |v11|, s90
	s_nop 1
	v_cndmask_b32_e64 v11, v11, v18, s[6:7]
	v_cndmask_b32_e64 v18, 0, v238, s[4:5]
	v_sub_f32_e32 v18, v11, v18
	v_mul_f32_e64 v11, |v15|, s20
	v_exp_f32_e32 v11, v11
	s_nop 0
	v_add_f32_e32 v11, 1.0, v11
	v_cmp_gt_f32_e64 s[4:5], s33, v11
	s_nop 1
	v_cndmask_b32_e64 v15, 0, 32, s[4:5]
	v_ldexp_f32 v11, v11, v15
	v_log_f32_e32 v11, v11
	s_nop 0
	v_mul_f32_e32 v15, 0x3f317217, v11
	v_fma_f32 v15, v11, s92, -v15
	v_fmac_f32_e32 v15, 0x3377d1cf, v11
	v_fmac_f32_e32 v15, 0x3f317217, v11
	v_cmp_lt_f32_e64 s[6:7], |v11|, s90
; #define LAS __attribute__((address_space(3)))
; __device__ __forceinline__ float logsigmoid_(float z) { return fminf(z, 0.f) - __logf(1.f + __expf(-fabsf(z))); }
; template <int TYPE>
; __device__ __forceinline__ void lg_compute(const KArgs& a, unsigned char* wsb, int l, int h, int dir, const LgRaw& raw, LAS unsigned char* lds, int tid) {
;     ...
;         f32x4 g0, g1;
; #pragma unroll
;         for (int e = 0; e < 4; ++e) { g0[e] = logsigmoid_(z0[e]) * (1.f / 16.f); g1[e] = logsigmoid_(z1[e]) * (1.f / 16.f); }
;         *(LAS f32x4*)(G + i * C::LDG + d8 * 8) = g0; *(LAS f32x4*)(G + i * C::LDG + d8 * 8 + 4) = g1;
;         *(LAS bf16x8*)(Kb + i * C::LDK_ + d8 * 8) = raw.k;
;     }
; }
; template <int TYPE>
; __device__ __forceinline__ void cumsum_g(int dir, LAS unsigned char* lds, int tid) {
;     using C = Cfg<TYPE>; constexpr int NSEG = 512 / C::DK, SEGL = 64 / NSEG;
;     LAS float* G = (LAS float*)(lds + SC_G); LAS float* SG = (LAS float*)(lds + SC_SEG);
;     const int d = tid % C::DK, seg = tid / C::DK;
;     __syncthreads();
;     float run = 0.f;
; #pragma unroll
;     for (int ii = 0; ii < SEGL; ++ii) { const int i = seg * SEGL + (dir ? SEGL - 1 - ii : ii); run += G[i * C::LDG + d]; G[i * C::LDG + d] = run; }
;     SG[seg * 128 + d] = run;
;     __syncthreads();
;     float off = 0.f;
; #pragma unroll
;     for (int s = 0; s < NSEG; ++s) { const bool before = dir ? (s > seg) : (s < seg); if (before) off += SG[s * 128 + d]; }
; #pragma unroll
;     for (int ii = 0; ii < SEGL; ++ii) { const int i = seg * SEGL + ii; G[i * C::LDG + d] += off; }
;     __syncthreads();
; }
; __device__ __forceinline__ void vT_write(const VRaw& r, LAS unsigned char* lds, int tid) {
;     LAS bf16_t* VT = (LAS bf16_t*)(lds + SC_VT);
;     const int v8 = tid & 15;
; #pragma unroll
;     for (int e2 = 0; e2 < 2; ++e2) { const int i = (tid >> 4) + 32 * e2; const bf16x8 x = e2 ? r.x1 : r.x0; const int pc = ((((i >> 3) ^ (v8 & 7)) << 3) | (i & 7));
; #pragma unroll
;         for (int e = 0; e < 8; ++e) VT[(v8 * 8 + e) * LDT + pc] = (bf16_t)x[e]; }
; }
	s_nop 1
	v_cndmask_b32_e64 v11, v11, v15, s[6:7]
	v_cndmask_b32_e64 v15, 0, v238, s[4:5]
	v_sub_f32_e32 v15, v11, v15
	v_mul_f32_e64 v11, |v19|, s20
	v_exp_f32_e32 v11, v11
	v_pk_add_f32 v[14:15], v[22:23], v[14:15] neg_lo:[0,1] neg_hi:[0,1]
	v_add_f32_e32 v11, 1.0, v11
	v_cmp_gt_f32_e64 s[4:5], s33, v11
	v_pk_mul_f32 v[14:15], v[14:15], s[0:1] op_sel_hi:[1,0]
	s_nop 0
	v_cndmask_b32_e64 v19, 0, 32, s[4:5]
	v_ldexp_f32 v11, v11, v19
	v_log_f32_e32 v11, v11
	s_nop 0
	v_mul_f32_e32 v19, 0x3f317217, v11
	v_fma_f32 v19, v11, s92, -v19
	v_fmac_f32_e32 v19, 0x3377d1cf, v11
	v_fmac_f32_e32 v19, 0x3f317217, v11
	v_cmp_lt_f32_e64 s[6:7], |v11|, s90
	s_nop 1
	v_cndmask_b32_e64 v11, v11, v19, s[6:7]
	v_cndmask_b32_e64 v19, 0, v238, s[4:5]
	v_sub_f32_e32 v19, v11, v19
	v_mul_f32_e64 v11, |v16|, s20
	v_exp_f32_e32 v11, v11
	v_pk_add_f32 v[18:19], v[24:25], v[18:19] neg_lo:[0,1] neg_hi:[0,1]
	global_load_dwordx4 v[22:25], v[4:5], off offset:1024
	s_nop 0
	global_load_dwordx4 v[4:7], v[6:7], off offset:1024
	v_pk_mul_f32 v[18:19], v[18:19], s[0:1] op_sel_hi:[1,0]
	v_add_f32_e32 v11, 1.0, v11
	v_cmp_gt_f32_e64 s[4:5], s33, v11
	s_nop 1
	v_cndmask_b32_e64 v16, 0, 32, s[4:5]
	v_ldexp_f32 v11, v11, v16
	v_log_f32_e32 v11, v11
	s_nop 0
	v_mul_f32_e32 v16, 0x3f317217, v11
	v_fma_f32 v16, v11, s92, -v16
	v_fmac_f32_e32 v16, 0x3377d1cf, v11
	v_fmac_f32_e32 v16, 0x3f317217, v11
	v_cmp_lt_f32_e64 s[6:7], |v11|, s90
	s_nop 1
	v_cndmask_b32_e64 v11, v11, v16, s[6:7]
	v_cndmask_b32_e64 v16, 0, v238, s[4:5]
	v_sub_f32_e32 v16, v11, v16
	v_mul_f32_e64 v11, |v20|, s20
	v_exp_f32_e32 v11, v11
	s_nop 0
	v_add_f32_e32 v11, 1.0, v11
	v_cmp_gt_f32_e64 s[4:5], s33, v11
	s_nop 1
	v_cndmask_b32_e64 v20, 0, 32, s[4:5]
	v_ldexp_f32 v11, v11, v20
	v_log_f32_e32 v11, v11
	s_nop 0
	v_mul_f32_e32 v20, 0x3f317217, v11
	v_fma_f32 v20, v11, s92, -v20
	v_fmac_f32_e32 v20, 0x3377d1cf, v11
	v_fmac_f32_e32 v20, 0x3f317217, v11
	v_cmp_lt_f32_e64 s[6:7], |v11|, s90
	s_nop 1
	v_cndmask_b32_e64 v11, v11, v20, s[6:7]
	v_cndmask_b32_e64 v20, 0, v238, s[4:5]
	v_sub_f32_e32 v20, v11, v20
	v_mul_f32_e64 v11, |v17|, s20
	v_exp_f32_e32 v11, v11
	s_nop 0
	v_add_f32_e32 v11, 1.0, v11
	v_cmp_gt_f32_e64 s[4:5], s33, v11
	s_nop 1
	v_cndmask_b32_e64 v17, 0, 32, s[4:5]
	v_ldexp_f32 v11, v11, v17
	v_log_f32_e32 v11, v11
	s_nop 0
	v_mul_f32_e32 v17, 0x3f317217, v11
	v_fma_f32 v17, v11, s92, -v17
	v_fmac_f32_e32 v17, 0x3377d1cf, v11
	v_fmac_f32_e32 v17, 0x3f317217, v11
	v_cmp_lt_f32_e64 s[6:7], |v11|, s90
	s_nop 1
	v_cndmask_b32_e64 v11, v11, v17, s[6:7]
	v_cndmask_b32_e64 v17, 0, v238, s[4:5]
	v_sub_f32_e32 v17, v11, v17
	v_mul_f32_e64 v11, |v21|, s20
	v_exp_f32_e32 v11, v11
	v_pk_add_f32 v[16:17], v[26:27], v[16:17] neg_lo:[0,1] neg_hi:[0,1]
	v_add_f32_e32 v11, 1.0, v11
	v_cmp_gt_f32_e64 s[4:5], s33, v11
	v_pk_mul_f32 v[16:17], v[16:17], s[0:1] op_sel_hi:[1,0]
	s_nop 0
	v_cndmask_b32_e64 v21, 0, 32, s[4:5]
	v_ldexp_f32 v11, v11, v21
	v_log_f32_e32 v11, v11
	s_nop 0
	v_mul_f32_e32 v21, 0x3f317217, v11
	v_fma_f32 v21, v11, s92, -v21
	v_fmac_f32_e32 v21, 0x3377d1cf, v11
	v_fmac_f32_e32 v21, 0x3f317217, v11
	v_cmp_lt_f32_e64 s[6:7], |v11|, s90
	s_nop 1
	v_cndmask_b32_e64 v11, v11, v21, s[6:7]
	v_cndmask_b32_e64 v21, 0, v238, s[4:5]
	s_movk_i32 s6, 0x110
	v_sub_f32_e32 v21, v11, v21
	v_mul_lo_u32 v11, v8, s6
	v_add_u32_e32 v11, 0, v11
	v_pk_add_f32 v[20:21], v[28:29], v[20:21] neg_lo:[0,1] neg_hi:[0,1]
	v_add_u32_e32 v10, v11, v10
	v_pk_mul_f32 v[20:21], v[20:21], s[0:1] op_sel_hi:[1,0]
	ds_write_b128 v10, v[14:17]
	ds_write_b128 v10, v[18:21] offset:16
	v_lshlrev_b32_e32 v10, 7, v8
	v_sub_u32_e32 v10, v11, v10
	v_add_u32_e32 v10, v10, v112
	ds_write_b128 v10, v[0:3] offset:33792
	v_and_b32_e32 v1, -8, v35
	v_lshlrev_b32_e32 v0, 1, v35
	v_add_u32_e32 v1, 32, v1
	v_and_b32_e32 v0, 14, v0
	v_bitop3_b32 v2, v35, v13, -8 bitop3:0x6c
	v_bitop3_b32 v1, v1, v9, 56 bitop3:0x78
	v_add_u32_e32 v0, s95, v0
	v_lshlrev_b32_e32 v2, 1, v2
	v_mul_u32_u24_e32 v3, 0x90, v37
	v_lshlrev_b32_e32 v1, 1, v1
	v_add3_u32 v2, v0, v2, v3
	v_add3_u32 v0, v0, v1, v3
	s_waitcnt vmcnt(0) lgkmcnt(0)
	ds_write_b16 v2, v22
	ds_write_b16_d16_hi v2, v22 offset:144
	ds_write_b16 v2, v23 offset:288
	ds_write_b16_d16_hi v2, v23 offset:432
	ds_write_b16 v2, v24 offset:576
	ds_write_b16_d16_hi v2, v24 offset:720
	ds_write_b16 v2, v25 offset:864
	ds_write_b16_d16_hi v2, v25 offset:1008
	ds_write_b16 v0, v4
	ds_write_b16_d16_hi v0, v4 offset:144
	ds_write_b16 v0, v5 offset:288
	ds_write_b16_d16_hi v0, v5 offset:432
	ds_write_b16 v0, v6 offset:576
	ds_write_b16_d16_hi v0, v6 offset:720
	ds_write_b16 v0, v7 offset:864
	ds_write_b16_d16_hi v0, v7 offset:1008
	v_ashrrev_i32_e32 v0, 31, v12
	v_lshrrev_b32_e32 v0, 26, v0
	v_add_u32_e32 v0, v12, v0
	v_ashrrev_i32_e32 v1, 6, v0
	v_and_b32_e32 v0, 0x3fffffc0, v0
	v_sub_u32_e32 v0, v12, v0
	v_lshlrev_b32_e32 v4, 3, v1
	v_lshlrev_b32_e32 v5, 2, v0
	v_add_u32_e32 v0, 0, v5
	v_and_or_b32 v2, s18, 7, v4
	v_mad_u64_u32 v[2:3], s[4:5], v2, s6, v[0:1]
	s_waitcnt lgkmcnt(0)
	s_barrier
	ds_read_b32 v3, v2
	s_cselect_b32 s4, 1, 6
	s_movk_i32 s0, 0xffc1
	s_waitcnt lgkmcnt(0)
	v_add_f32_e32 v6, 0, v3
	ds_write_b32 v2, v6
	v_or_b32_e32 v2, s4, v4
	v_mad_u64_u32 v[2:3], s[4:5], v2, s6, v[0:1]
	ds_read_b32 v3, v2
	s_cselect_b32 s4, 2, 5
	s_waitcnt lgkmcnt(0)
	v_add_f32_e32 v6, v6, v3
	ds_write_b32 v2, v6
	v_or_b32_e32 v2, s4, v4
	v_mad_u64_u32 v[2:3], s[4:5], v2, s6, v[0:1]
	ds_read_b32 v3, v2
	s_waitcnt lgkmcnt(0)
	v_add_f32_e32 v6, v6, v3
	ds_write_b32 v2, v6
	v_or_b32_e32 v2, s19, v4
	v_mad_u64_u32 v[2:3], s[4:5], v2, s6, v[0:1]
	ds_read_b32 v3, v2
	s_waitcnt lgkmcnt(0)
	v_add_f32_e32 v6, v6, v3
	ds_write_b32 v2, v6
	v_subrev_u32_e32 v2, s17, v4
	v_mad_u64_u32 v[2:3], s[4:5], v2, s6, v[0:1]
	ds_read_b32 v3, v2 offset:1088
	s_cselect_b32 s4, 5, 2
	s_waitcnt lgkmcnt(0)
	v_add_f32_e32 v6, v6, v3
	ds_write_b32 v2, v6 offset:1088
	v_or_b32_e32 v2, s4, v4
	v_mad_u64_u32 v[2:3], s[4:5], v2, s6, v[0:1]
	ds_read_b32 v3, v2
	s_cselect_b32 s4, 6, 1
	s_waitcnt lgkmcnt(0)
	v_add_f32_e32 v6, v6, v3
	ds_write_b32 v2, v6
	v_or_b32_e32 v2, s4, v4
	v_mad_u64_u32 v[2:3], s[4:5], v2, s6, v[0:1]
	ds_read_b32 v3, v2
	s_cselect_b32 s4, 7, 0
	s_waitcnt lgkmcnt(0)
	v_add_f32_e32 v6, v6, v3
	ds_write_b32 v2, v6
	v_or_b32_e32 v2, s4, v4
	v_mad_u64_u32 v[2:3], s[4:5], v2, s6, v[0:1]
	ds_read_b32 v3, v2
	v_cmp_gt_i32_e64 s[4:5], s0, v12
	v_cmp_lt_i32_e64 s[6:7], 63, v12
	s_waitcnt lgkmcnt(0)
	v_add_f32_e32 v3, v6, v3
	ds_write_b32 v2, v3
	v_add_u32_e32 v2, s74, v5
	v_lshl_add_u32 v4, v1, 9, v2
	ds_write_b32 v4, v3
	v_cndmask_b32_e64 v3, 0, 1, s[6:7]
	v_cndmask_b32_e64 v4, 0, 1, s[4:5]
	v_cndmask_b32_e32 v3, v4, v3, vcc
	v_and_b32_e32 v3, 1, v3
	v_cmp_eq_u32_e64 s[4:5], 1, v3
	v_mov_b32_e32 v3, 0
	s_waitcnt lgkmcnt(0)
	s_barrier
	s_and_saveexec_b64 s[6:7], s[4:5]
	s_cbranch_execz .LBB0_290
	ds_read_b32 v3, v2
	s_waitcnt lgkmcnt(0)
	v_add_f32_e32 v3, 0, v3

; #define LAS __attribute__((address_space(3)))
; __device__ __forceinline__ unsigned f2bf(float f) { unsigned u = __float_as_uint(f); return (u + 0x7fffu + ((u >> 16) & 1u)) >> 16; }
; template <int TYPE>
; __device__ __forceinline__ void cumsum_g(int dir, LAS unsigned char* lds, int tid) {
;     ...
;     for (int s = 0; s < NSEG; ++s) { const bool before = dir ? (s > seg) : (s < seg); if (before) off += SG[s * 128 + d]; }
; #pragma unroll
;     for (int ii = 0; ii < SEGL; ++ii) { const int i = seg * SEGL + ii; G[i * C::LDG + d] += off; }
;     __syncthreads();
; template <int TYPE>
; __device__ __forceinline__ void pass1_item(const KArgs& a, int l, int item, LAS unsigned char* lds) {
;     ...
; #pragma unroll
;     for (int e2 = 0; e2 < DK / 64; ++e2) { const int task = tid + 512 * e2, i = task & 63, d8 = task >> 6;
;         const f32x4 g0 = *(LAS f32x4*)(G + i * C::LDG + d8 * 8), g1 = *(LAS f32x4*)(G + i * C::LDG + d8 * 8 + 4);
;         const f32x4 t0 = *(LAS f32x4*)(G + last * C::LDG + d8 * 8), t1 = *(LAS f32x4*)(G + last * C::LDG + d8 * 8 + 4);
;         float kk[8]; unpack8(*(LAS bf16x8*)(Kb + i * C::LDK_ + d8 * 8), kk);
; #pragma unroll
;         for (int e = 0; e < 8; ++e) { const float gg = e < 4 ? g0[e] : g1[e - 4], tt = e < 4 ? t0[e] : t1[e - 4];
;             KDT[(d8 * 8 + e) * LDT + i] = (bf16_t)f2bf(kk[e] * __expf(tt - gg)); }
;         if (i == 0) { *(f32x4*)(Dout + d8 * 8) = (f32x4){__expf(t0[0]), __expf(t0[1]), __expf(t0[2]), __expf(t0[3])};
;                       *(f32x4*)(Dout + d8 * 8 + 4) = (f32x4){__expf(t1[0]), __expf(t1[1]), __expf(t1[2]), __expf(t1[3])}; } }
.LBB0_304:
	s_or_b64 exec, exec, s[6:7]
	s_movk_i32 s0, 0x880
	v_mad_u64_u32 v[0:1], s[4:5], v1, s0, v[0:1]
	ds_read2_b32 v[4:5], v0 offset1:68
	ds_read2_b32 v[6:7], v0 offset0:136 offset1:204
	v_add_u32_e32 v1, 0x400, v0
	v_and_b32_e32 v11, 63, v12
	v_and_b32_e32 v10, -8, v8
	s_waitcnt lgkmcnt(1)
	v_add_f32_e32 v2, v3, v4
	v_add_f32_e32 v4, v3, v5
	ds_write2_b32 v0, v2, v4 offset1:68
	ds_read2_b32 v[4:5], v1 offset0:16 offset1:84
	s_waitcnt lgkmcnt(2)
	v_add_f32_e32 v2, v3, v6
	v_add_f32_e32 v9, v3, v7
	ds_read2_b32 v[6:7], v1 offset0:152 offset1:220
	ds_write2_b32 v0, v2, v9 offset0:136 offset1:204
	s_waitcnt lgkmcnt(2)
	v_add_f32_e32 v0, v3, v4
	v_add_f32_e32 v2, v3, v5
	ds_write2_b32 v1, v0, v2 offset0:16 offset1:84
	s_waitcnt lgkmcnt(2)
	v_add_f32_e32 v0, v3, v6
	v_add_f32_e32 v2, v3, v7
	s_and_b64 s[4:5], vcc, exec
	ds_write2_b32 v1, v0, v2 offset0:152 offset1:220
	v_mad_u32_u24 v0, v11, s93, 0
	v_lshlrev_b32_e32 v1, 2, v10
	s_cselect_b32 s4, 0x42f0, 0
	v_lshlrev_b32_e32 v3, 7, v11
	v_add_u32_e32 v2, v0, v1
	s_add_i32 s4, s4, 0
	v_sub_u32_e32 v0, v0, v3
	v_add_u32_e32 v1, s4, v1
	v_lshl_add_u32 v3, v10, 1, v0
	s_movk_i32 s4, 0xff72
	s_waitcnt lgkmcnt(0)
	s_barrier
	v_mad_i32_i24 v26, v11, s4, v0
	ds_read_b128 v[14:17], v3 offset:33792
	ds_read_b128 v[18:21], v2
	ds_read_b128 v[22:25], v2 offset:16
	ds_read_b128 v[4:7], v1
	ds_read_b128 v[0:3], v1 offset:16
	s_waitcnt lgkmcnt(4)
	v_lshlrev_b32_e32 v9, 16, v14
	v_and_b32_e32 v13, 0xffff0000, v14
	v_lshlrev_b32_e32 v27, 16, v15
	s_waitcnt lgkmcnt(1)
	v_sub_f32_e32 v14, v4, v18
	v_mul_f32_e32 v14, 0x3fb8aa3b, v14
	v_exp_f32_e32 v14, v14
	v_and_b32_e32 v28, 0xffff0000, v15
	v_lshlrev_b32_e32 v29, 16, v16
	v_and_b32_e32 v16, 0xffff0000, v16
	v_mul_f32_e32 v9, v14, v9
	v_bfe_u32 v14, v9, 16, 1
	v_add3_u32 v9, v9, v14, s1
	v_sub_f32_e32 v14, v5, v19
	v_mul_f32_e32 v14, 0x3fb8aa3b, v14
	v_exp_f32_e32 v19, v14
	v_mad_u64_u32 v[14:15], s[4:5], v10, s3, v[26:27]
	ds_write_b16_d16_hi v14, v9 offset:51200
	v_mul_f32_e32 v9, v19, v13
	v_sub_f32_e32 v13, v6, v20
	v_mul_f32_e32 v13, 0x3fb8aa3b, v13
	v_exp_f32_e32 v13, v13
	v_bfe_u32 v15, v9, 16, 1
	v_add3_u32 v9, v9, v15, s1
	ds_write_b16_d16_hi v14, v9 offset:51344
	v_mul_f32_e32 v9, v13, v27
	v_sub_f32_e32 v13, v7, v21
	v_mul_f32_e32 v13, 0x3fb8aa3b, v13
	v_exp_f32_e32 v13, v13
	v_bfe_u32 v15, v9, 16, 1
	v_add3_u32 v9, v9, v15, s1
	ds_write_b16_d16_hi v14, v9 offset:51488
	v_mul_f32_e32 v9, v13, v28
	s_waitcnt lgkmcnt(3)
	v_sub_f32_e32 v13, v0, v22
	v_mul_f32_e32 v13, 0x3fb8aa3b, v13
	v_exp_f32_e32 v13, v13
	v_bfe_u32 v15, v9, 16, 1
	v_add3_u32 v9, v9, v15, s1
	ds_write_b16_d16_hi v14, v9 offset:51632
	v_mul_f32_e32 v9, v13, v29
	v_sub_f32_e32 v13, v1, v23
	v_mul_f32_e32 v13, 0x3fb8aa3b, v13
	v_exp_f32_e32 v13, v13
	v_bfe_u32 v15, v9, 16, 1
	v_add3_u32 v9, v9, v15, s1
	ds_write_b16_d16_hi v14, v9 offset:51776
	v_mul_f32_e32 v9, v13, v16
	v_sub_f32_e32 v13, v2, v24
	v_mul_f32_e32 v13, 0x3fb8aa3b, v13
	v_exp_f32_e32 v13, v13
	v_bfe_u32 v15, v9, 16, 1
	v_lshlrev_b32_e32 v18, 16, v17
	v_add3_u32 v9, v9, v15, s1
	ds_write_b16_d16_hi v14, v9 offset:51920
	v_mul_f32_e32 v9, v13, v18
	v_sub_f32_e32 v13, v3, v25
	v_mul_f32_e32 v13, 0x3fb8aa3b, v13
	v_exp_f32_e32 v13, v13
	v_bfe_u32 v15, v9, 16, 1
	v_and_b32_e32 v17, 0xffff0000, v17
	v_add3_u32 v9, v9, v15, s1
	ds_write_b16_d16_hi v14, v9 offset:52064
	v_mul_f32_e32 v9, v13, v17
	v_bfe_u32 v13, v9, 16, 1
	v_or_b32_e32 v8, 7, v8
	v_add3_u32 v13, v9, v13, s1
	v_mad_u64_u32 v[8:9], s[4:5], v8, s3, v[26:27]
	v_cmp_eq_u32_e32 vcc, 0, v11
	ds_write_b16_d16_hi v8, v13 offset:51200
	s_and_saveexec_b64 s[4:5], vcc
	s_cbranch_execz .LBB0_287
	v_mul_f32_e32 v4, 0x3fb8aa3b, v4
	v_mul_f32_e32 v5, 0x3fb8aa3b, v5
	v_mul_f32_e32 v6, 0x3fb8aa3b, v6
	v_mul_f32_e32 v7, 0x3fb8aa3b, v7
	v_exp_f32_e32 v4, v4
	v_exp_f32_e32 v5, v5
	v_exp_f32_e32 v6, v6
	v_exp_f32_e32 v7, v7
	v_mul_f32_e32 v0, 0x3fb8aa3b, v0
	v_mul_f32_e32 v1, 0x3fb8aa3b, v1
	v_mul_f32_e32 v2, 0x3fb8aa3b, v2
	v_mul_f32_e32 v3, 0x3fb8aa3b, v3
	v_ashrrev_i32_e32 v11, 31, v10
	v_exp_f32_e32 v0, v0
	v_exp_f32_e32 v1, v1
	v_exp_f32_e32 v2, v2
	v_exp_f32_e32 v3, v3
	v_lshl_add_u64 v[8:9], v[10:11], 2, s[12:13]
	v_lshl_add_u64 v[8:9], v[8:9], 0, s[10:11]
	global_store_dwordx4 v[8:9], v[4:7], off
	global_store_dwordx4 v[8:9], v[0:3], off offset:16
	s_branch .LBB0_287

; __device__ __forceinline__ unsigned xb_ld(unsigned* p)              { return __hip_atomic_load(p, __ATOMIC_RELAXED, __HIP_MEMORY_SCOPE_AGENT); }
; __device__ __forceinline__ unsigned xb_add(unsigned* p, unsigned v) { return __hip_atomic_fetch_add(p, v, __ATOMIC_RELAXED, __HIP_MEMORY_SCOPE_AGENT); }
; #define XB_SPIN(cond, bar) do { unsigned _sp = 0; while (cond) { __builtin_amdgcn_s_sleep(1); \
;     if ((++_sp & 255u) == 0u) { if (xb_ld(&(bar)[XB_TMO])) break; if (_sp > XB_SPIN_CAP) { atomicAdd(&(bar)[XB_TMO], 1u); break; } } } } while (0)
; __device__ __forceinline__ void xcd_barrier(const XcdBarrier& b) {
;     ...
;     if (threadIdx.x == 0) {
;         unsigned* bar = b.bar;
;         __builtin_amdgcn_s_waitcnt(0);
;         unsigned nloc = b.st[0], nx = b.st[1];
;         if (nloc == 0u) { xcd_barrier_complete(bar, b.x, nloc, nx); b.st[0] = nloc; b.st[1] = nx; }
;         const unsigned old = xb_add(&bar[XB_XSUB(b.x)], 1u);
;         const unsigned gen = old / nloc;
;         if (old + 1u == (gen + 1u) * nloc) {
;             __builtin_amdgcn_fence(__ATOMIC_RELEASE, "agent");
;             asm volatile("s_waitcnt vmcnt(0)" ::: "memory");
;             const unsigned og = xb_add(&bar[XB_TOP], 1u);
;             const unsigned tg = og / nx;
;             if (og + 1u == (tg + 1u) * nx) xb_add(&bar[XB_TOPGEN], 1u);
;             else XB_SPIN(xb_ld(&bar[XB_TOPGEN]) == tg, bar);
;             __builtin_amdgcn_fence(__ATOMIC_ACQUIRE, "agent");
;             xb_add(&bar[XB_XGEN(b.x)], 1u);
;             asm volatile("s_waitcnt vmcnt(0)" ::: "memory");
;         } else {
;             XB_SPIN(xb_ld(&bar[XB_XGEN(b.x)]) == gen, bar);
.LBB0_309:
	s_lshl_b32 s4, s57, 8
	s_add_u32 s4, s38, s4
	s_addc_u32 s5, s39, 0
	v_mov_b32_e32 v1, s4
	v_add_co_u32_e32 v4, vcc, 0x3e301000, v1
	v_mov_b32_e32 v1, s5
	s_nop 0
	v_addc_co_u32_e32 v5, vcc, 0, v1, vcc
	flat_atomic_add v3, v[4:5], v239 offset:1024 sc0
	v_cvt_f32_u32_e32 v1, v2
	v_sub_u32_e32 v4, 0, v2
	s_add_u32 s27, s4, 0x3e300000
	s_addc_u32 s26, s5, 0
	v_rcp_iflag_f32_e32 v1, v1
	s_nop 0
	v_mul_f32_e32 v1, 0x4f7ffffe, v1
	v_cvt_u32_f32_e32 v1, v1
	v_mul_lo_u32 v4, v4, v1
	v_mul_hi_u32 v4, v1, v4
	v_add_u32_e32 v1, v1, v4
	s_waitcnt vmcnt(0) lgkmcnt(0)
	v_mul_hi_u32 v1, v3, v1
	v_mul_lo_u32 v4, v1, v2
	v_sub_u32_e32 v4, v3, v4
	v_cmp_ge_u32_e32 vcc, v4, v2
	v_add_u32_e32 v5, 1, v1
	s_nop 0
	v_cndmask_b32_e32 v1, v1, v5, vcc
	v_sub_u32_e32 v5, v4, v2
	v_cndmask_b32_e32 v4, v4, v5, vcc
	v_cmp_ge_u32_e32 vcc, v4, v2
	v_add_u32_e32 v4, 1, v1
	s_nop 0
	v_cndmask_b32_e32 v1, v1, v4, vcc
	v_add_u32_e32 v4, 1, v3
	v_mad_u64_u32 v[2:3], s[4:5], v2, v1, v[2:3]
	v_cmp_ne_u32_e32 vcc, v4, v2
	s_and_saveexec_b64 s[4:5], vcc
	s_xor_b64 s[4:5], exec, s[4:5]
	s_cbranch_execz .LBB0_322
	v_mov_b32_e32 v0, s27
	v_add_co_u32_e32 v2, vcc, 0x2000, v0
	v_mov_b32_e32 v0, s26
	s_nop 0
	v_addc_co_u32_e32 v3, vcc, 0, v0, vcc
	global_load_dword v0, v[2:3], off offset:1024 sc1
	s_add_u32 s8, s27, 0x2400
	s_addc_u32 s9, s26, 0
	s_waitcnt vmcnt(0) lgkmcnt(0)
	v_cmp_eq_u32_e32 vcc, v0, v1
	s_and_saveexec_b64 s[6:7], vcc
	s_cbranch_execz .LBB0_321
	s_add_u32 s10, s38, 0x3e300200
	s_addc_u32 s11, s39, 0
	s_mov_b32 s28, 1
	s_mov_b64 s[12:13], 0
	s_branch .LBB0_313

; __device__ __forceinline__ unsigned char* opq(unsigned char* q) { asm volatile("" : "+s"(q)); return q; }
; __device__ __forceinline__ void pass2_triple(const KArgs& a, int t) {
;     unsigned char* const wsb = opq(a.ws);
;     const P2Chain c0 = p2_chain(wsb, 1, t), c1 = p2_chain(wsb, 1, t + 131072), c2 = p2_chain(wsb, 0, t);
;     float s0 = 0.f, s1 = 0.f, s2 = 0.f;
;     unsigned short uA[3][4], uB[3][4]; float dA[3][4], dB[3][4];
;     ...
;     P2_LOAD(uA, dA, 0);
.LBB0_341:
	v_ashrrev_i32_e32 v6, 31, v84
	v_lshrrev_b32_e32 v0, 18, v6
	v_add_u32_e32 v0, v84, v0
	v_ashrrev_i32_e32 v0, 14, v0
	s_mov_b64 s[4:5], s[68:69]
	v_mul_i32_i24_e32 v1, 0x4000, v0
	v_sub_u32_e32 v2, v84, v1
	s_add_u32 s6, s4, 0x35700000
	v_ashrrev_i32_e32 v1, 31, v0
	s_addc_u32 s7, s5, 0
	v_lshlrev_b64 v[4:5], 23, v[0:1]
	v_lshl_add_u64 v[4:5], s[6:7], 0, v[4:5]
	v_ashrrev_i32_e32 v3, 31, v2
	v_lshl_add_u64 v[40:41], v[2:3], 1, v[4:5]
	v_lshlrev_b64 v[4:5], 17, v[0:1]
	v_ashrrev_i16_e32 v1, 15, v2
	v_lshrrev_b16_e32 v1, 9, v1
	v_add_u16_e32 v1, v2, v1
	v_and_b32_e32 v1, 0xffffff80, v1
	v_sub_u16_e32 v1, v2, v1
	v_bfe_i32 v2, v1, 0, 16
	v_add_u32_e32 v1, 0x20000, v84
	v_bfe_i32 v7, v0, 0, 1
	v_and_b32_e32 v12, 1, v0
	v_ashrrev_i32_e32 v0, 31, v1
	s_add_u32 s8, s4, 0x3d800000
	v_lshrrev_b32_e32 v0, 18, v0
	s_addc_u32 s9, s5, 0
	v_add_u32_e32 v0, v1, v0
	v_lshl_add_u64 v[4:5], s[8:9], 0, v[4:5]
	v_ashrrev_i32_e32 v3, 31, v2
	v_ashrrev_i32_e32 v0, 14, v0
	v_lshl_add_u64 v[42:43], v[2:3], 2, v[4:5]
	v_mul_i32_i24_e32 v2, 0x4000, v0
	v_sub_u32_e32 v2, v1, v2
	v_ashrrev_i32_e32 v1, 31, v0
	v_lshlrev_b64 v[4:5], 23, v[0:1]
	v_lshl_add_u64 v[4:5], s[6:7], 0, v[4:5]
	v_ashrrev_i32_e32 v3, 31, v2
	v_lshl_add_u64 v[44:45], v[2:3], 1, v[4:5]
	v_lshlrev_b64 v[4:5], 17, v[0:1]
	v_ashrrev_i16_e32 v1, 15, v2
	v_lshrrev_b16_e32 v1, 9, v1
	v_add_u16_e32 v1, v2, v1
	v_and_b32_e32 v1, 0xffffff80, v1
	v_and_b32_e32 v8, 1, v0
	v_lshrrev_b32_e32 v0, 19, v6
	v_sub_u16_e32 v1, v2, v1
	v_add_u32_e32 v0, v84, v0
	v_bfe_i32 v2, v1, 0, 16
	v_ashrrev_i32_e32 v0, 13, v0
	v_lshl_add_u64 v[4:5], s[8:9], 0, v[4:5]
	v_ashrrev_i32_e32 v3, 31, v2
	v_mul_i32_i24_e32 v1, 0x2000, v0
	v_lshl_add_u64 v[46:47], v[2:3], 2, v[4:5]
	v_sub_u32_e32 v2, v84, v1
	v_ashrrev_i32_e32 v1, 31, v0
	v_lshlrev_b64 v[4:5], 22, v[0:1]
	v_lshl_add_u64 v[4:5], s[4:5], 0, v[4:5]
	v_ashrrev_i32_e32 v3, 31, v2
	v_lshl_add_u64 v[4:5], v[2:3], 1, v[4:5]
	s_mov_b64 s[6:7], 0x31700000
	v_lshl_add_u64 v[48:49], v[4:5], 0, s[6:7]
	v_lshlrev_b64 v[4:5], 16, v[0:1]
	v_ashrrev_i16_e32 v1, 15, v2
	v_lshrrev_b16_e32 v1, 10, v1
	v_add_u16_e32 v1, v2, v1
	v_and_b32_e32 v1, 0xffffffc0, v1
	v_sub_u16_e32 v1, v2, v1
	v_bfe_i32 v2, v1, 0, 16
	v_lshl_add_u64 v[4:5], s[4:5], 0, v[4:5]
	v_ashrrev_i32_e32 v3, 31, v2
	v_lshl_add_u64 v[2:3], v[2:3], 2, v[4:5]
	s_mov_b64 s[4:5], 0x3d700000
	v_lshl_add_u64 v[50:51], v[2:3], 0, s[4:5]
	v_bfe_i32 v10, v0, 0, 1
	v_and_b32_e32 v13, 1, v0
	v_cmp_eq_u32_e64 s[4:5], 0, v8
	v_mov_b32_e32 v0, 0xff
	v_mov_b32_e32 v2, 9
	v_cndmask_b32_e64 v6, v0, 0, s[4:5]
	v_mov_b32_e32 v0, 15
	v_lshlrev_b32_sdwa v112, v0, v7 dst_sel:DWORD dst_unused:UNUSED_PAD src0_sel:DWORD src1_sel:BYTE_0
	v_lshl_add_u64 v[0:1], v[40:41], 0, v[112:113]
	v_lshlrev_b32_sdwa v112, v2, v7 dst_sel:DWORD dst_unused:UNUSED_PAD src0_sel:DWORD src1_sel:BYTE_0
	v_lshl_add_u64 v[2:3], v[42:43], 0, v[112:113]
	v_lshlrev_b32_e32 v112, 15, v6
	v_lshl_add_u64 v[4:5], v[44:45], 0, v[112:113]
	v_lshlrev_b32_e32 v112, 9, v6
	v_mov_b32_e32 v8, 14
	v_lshl_add_u64 v[6:7], v[46:47], 0, v[112:113]
	v_lshlrev_b32_sdwa v112, v8, v10 dst_sel:DWORD dst_unused:UNUSED_PAD src0_sel:DWORD src1_sel:BYTE_0
	v_mov_b32_e32 v11, 8
	v_cmp_eq_u32_e64 s[6:7], 0, v12
	v_mov_b32_e32 v12, 0xfe
	v_lshl_add_u64 v[8:9], v[48:49], 0, v[112:113]
	v_lshlrev_b32_sdwa v112, v11, v10 dst_sel:DWORD dst_unused:UNUSED_PAD src0_sel:DWORD src1_sel:BYTE_0
	v_cndmask_b32_e64 v14, v12, 1, s[6:7]
	v_lshl_add_u64 v[10:11], v[50:51], 0, v[112:113]
	v_cmp_eq_u32_e64 s[8:9], 0, v13
	v_lshlrev_b32_e32 v112, 15, v14
	v_cndmask_b32_e64 v16, v12, 1, s[4:5]
	v_cndmask_b32_e64 v17, v12, 1, s[8:9]
	v_lshl_add_u64 v[12:13], v[40:41], 0, v[112:113]
	v_lshlrev_b32_e32 v112, 9, v14
	v_lshl_add_u64 v[14:15], v[42:43], 0, v[112:113]
	v_lshlrev_b32_e32 v112, 15, v16
	global_load_ushort v22, v[0:1], off
	s_nop 0
	global_load_dword v0, v[2:3], off
	global_load_ushort v23, v[4:5], off
	s_nop 0
	global_load_dword v4, v[6:7], off
	global_load_ushort v28, v[8:9], off
	s_nop 0
	global_load_dword v8, v[10:11], off
	global_load_ushort v24, v[12:13], off
	global_load_dword v1, v[14:15], off
	v_lshl_add_u64 v[2:3], v[44:45], 0, v[112:113]
	v_lshlrev_b32_e32 v112, 9, v16
	v_lshl_add_u64 v[6:7], v[46:47], 0, v[112:113]
	v_lshlrev_b32_e32 v112, 14, v17
	v_lshl_add_u64 v[10:11], v[48:49], 0, v[112:113]
	v_lshlrev_b32_e32 v112, 8, v17
	v_cndmask_b32_e64 v5, v252, 2, s[6:7]
	v_lshl_add_u64 v[12:13], v[50:51], 0, v[112:113]
	v_lshlrev_b32_e32 v112, 15, v5
	v_cndmask_b32_e64 v9, v252, 2, s[4:5]
	v_lshl_add_u64 v[14:15], v[40:41], 0, v[112:113]
	v_lshlrev_b32_e32 v112, 9, v5
	v_lshl_add_u64 v[16:17], v[42:43], 0, v[112:113]
	v_lshlrev_b32_e32 v112, 15, v9
	v_cndmask_b32_e64 v25, v252, 2, s[8:9]
	v_lshl_add_u64 v[18:19], v[44:45], 0, v[112:113]
	v_lshlrev_b32_e32 v112, 9, v9
	v_lshl_add_u64 v[20:21], v[46:47], 0, v[112:113]
	v_lshlrev_b32_e32 v112, 14, v25
	global_load_ushort v26, v[2:3], off
	global_load_dword v5, v[6:7], off
	global_load_ushort v30, v[10:11], off
	global_load_dword v9, v[12:13], off
	global_load_ushort v29, v[14:15], off
	s_nop 0
	global_load_dword v2, v[16:17], off
	global_load_ushort v27, v[18:19], off
	global_load_dword v6, v[20:21], off
	v_lshl_add_u64 v[10:11], v[48:49], 0, v[112:113]
	v_lshlrev_b32_e32 v112, 8, v25
	v_cndmask_b32_e64 v3, v236, 3, s[6:7]
	v_lshl_add_u64 v[12:13], v[50:51], 0, v[112:113]
	v_lshlrev_b32_e32 v112, 15, v3
	v_cndmask_b32_e64 v7, v236, 3, s[4:5]
	v_lshl_add_u64 v[14:15], v[40:41], 0, v[112:113]
	v_lshlrev_b32_e32 v112, 9, v3
	v_lshl_add_u64 v[16:17], v[42:43], 0, v[112:113]
	v_lshlrev_b32_e32 v112, 15, v7
	v_cndmask_b32_e64 v25, v236, 3, s[8:9]
	v_lshl_add_u64 v[18:19], v[44:45], 0, v[112:113]
	v_lshlrev_b32_e32 v112, 9, v7
	global_load_ushort v31, v[18:19], off
	v_lshl_add_u64 v[18:19], v[46:47], 0, v[112:113]
	v_lshlrev_b32_e32 v112, 14, v25
	v_lshl_add_u64 v[20:21], v[48:49], 0, v[112:113]
	v_lshlrev_b32_e32 v112, 8, v25
	global_load_ushort v14, v[14:15], off
	s_nop 0
	global_load_ushort v15, v[10:11], off
	s_nop 0
	global_load_ushort v20, v[20:21], off
	v_lshl_add_u64 v[10:11], v[50:51], 0, v[112:113]
	global_load_dword v11, v[10:11], off
	s_nop 0
	global_load_dword v7, v[18:19], off
	global_load_dword v3, v[16:17], off
	global_load_dword v10, v[12:13], off
	s_mov_b32 s0, 0x5040100
	v_mov_b32_e32 v101, 0
	s_mov_b32 s17, 0
	s_movk_i32 s16, 0xf4
	v_mov_b32_e32 v82, 0
	v_mov_b32_e32 v83, v101
	s_waitcnt vmcnt(0) lgkmcnt(0)
	v_perm_b32 v24, v24, v22, s0
	v_perm_b32 v26, v26, v23, s0
	v_perm_b32 v28, v30, v28, s0
	v_perm_b32 v27, v31, v27, s0
	v_perm_b32 v25, v14, v29, s0
	v_perm_b32 v29, v20, v15, s0
	v_mov_b64_e32 v[38:39], v[30:31]
	v_mov_b64_e32 v[22:23], v[10:11]
	v_mov_b64_e32 v[20:21], v[8:9]
	v_mov_b64_e32 v[18:19], v[6:7]
	v_mov_b64_e32 v[16:17], v[4:5]
	v_mov_b64_e32 v[14:15], v[2:3]
	v_mov_b64_e32 v[12:13], v[0:1]
	v_mov_b64_e32 v[36:37], v[28:29]
	v_mov_b64_e32 v[34:35], v[26:27]
	v_mov_b64_e32 v[32:33], v[24:25]
	s_branch .LBB0_343
; __device__ __forceinline__ void pass2_triple(const KArgs& a, int t) {
;     ...
;     P2_LOAD(uA, dA, 0);
; #pragma unroll 1
;     for (int sb = 0; sb < NCH; sb += 8) {
;         P2_LOAD(uB, dB, sb + 4);
;         P2_STEP(uA, dA, sb);
;         if (sb + 8 < NCH) P2_LOAD(uA, dA, sb + 8);
;         P2_STEP(uB, dB, sb + 4);
.LBB0_342:
	v_mov_b32_e32 v6, v3
	v_and_b32_e32 v5, 0xffff0000, v27
	v_and_b32_e32 v4, 0xffff0000, v25
	v_pk_fma_f32 v[0:1], v[6:7], v[0:1], v[4:5]
	v_and_b32_e32 v3, 0xffff0000, v29
	v_fmac_f32_e32 v3, v11, v2
	v_bfe_u32 v2, v0, 16, 1
	v_add3_u32 v2, v0, v2, s1
	global_store_short_d16_hi v[52:53], v2, off
	v_bfe_u32 v2, v1, 16, 1
	v_add3_u32 v2, v1, v2, s1
	global_store_short_d16_hi v[54:55], v2, off
	v_bfe_u32 v2, v3, 16, 1
	v_add3_u32 v2, v3, v2, s1
	global_store_short_d16_hi v[58:59], v2, off
	s_waitcnt vmcnt(0) lgkmcnt(0)
	v_lshlrev_b32_e32 v2, 16, v88
	v_fmac_f32_e32 v2, v89, v3
	v_bfe_u32 v3, v2, 16, 1
	v_add3_u32 v4, v2, v3, s1
	v_lshlrev_b32_e32 v3, 16, v92
	v_fmac_f32_e32 v3, v2, v93
	v_bfe_u32 v2, v3, 16, 1
	v_lshlrev_b32_e32 v6, 16, v97
	v_add3_u32 v5, v3, v2, s1
	v_fmac_f32_e32 v6, v3, v98
	v_lshlrev_b32_e32 v3, 16, v86
	v_lshlrev_b32_e32 v2, 16, v85
	v_pk_fma_f32 v[0:1], v[30:31], v[0:1], v[2:3]
	v_lshlrev_b32_e32 v3, 16, v90
	v_bfe_u32 v2, v0, 16, 1
	v_add3_u32 v2, v0, v2, s1
	global_store_short_d16_hi v[60:61], v2, off
	v_bfe_u32 v2, v1, 16, 1
	v_add3_u32 v2, v1, v2, s1
	global_store_short_d16_hi v[62:63], v2, off
	v_lshlrev_b32_e32 v2, 16, v87
	v_pk_fma_f32 v[0:1], v[56:57], v[0:1], v[2:3]
	global_store_short_d16_hi v[64:65], v4, off
	v_bfe_u32 v2, v0, 16, 1
	v_add3_u32 v2, v0, v2, s1
	global_store_short_d16_hi v[68:69], v2, off
	v_bfe_u32 v2, v1, 16, 1
	v_add3_u32 v2, v1, v2, s1
	global_store_short_d16_hi v[70:71], v2, off
	v_lshlrev_b32_e32 v3, 16, v94
	v_lshlrev_b32_e32 v2, 16, v91
	v_pk_fma_f32 v[0:1], v[0:1], v[66:67], v[2:3]
	global_store_short_d16_hi v[72:73], v5, off
	v_bfe_u32 v2, v0, 16, 1
	v_add3_u32 v2, v0, v2, s1
	global_store_short_d16_hi v[76:77], v2, off
	v_lshlrev_b32_e32 v3, 16, v96
	v_lshlrev_b32_e32 v2, 16, v95
	v_bfe_u32 v4, v1, 16, 1
	v_pk_fma_f32 v[82:83], v[0:1], v[74:75], v[2:3]
	v_bfe_u32 v0, v6, 16, 1
	v_add3_u32 v4, v1, v4, s1
	v_add3_u32 v0, v6, v0, s1
	v_lshlrev_b32_e32 v101, 16, v99
	global_store_short_d16_hi v[78:79], v4, off
	global_store_short_d16_hi v[80:81], v0, off
	v_fmac_f32_e32 v101, v6, v100
	v_mov_b64_e32 v[24:25], v[32:33]
	v_mov_b64_e32 v[0:1], v[12:13]
	s_add_i32 s16, s16, -8
	s_andn2_b64 vcc, exec, s[14:15]
	s_mov_b32 s17, s18
	v_mov_b64_e32 v[26:27], v[34:35]
	v_mov_b64_e32 v[28:29], v[36:37]
	v_mov_b64_e32 v[2:3], v[14:15]
	v_mov_b64_e32 v[4:5], v[16:17]
	v_mov_b64_e32 v[6:7], v[18:19]
	v_mov_b64_e32 v[8:9], v[20:21]
	v_mov_b64_e32 v[10:11], v[22:23]
	v_mov_b64_e32 v[30:31], v[38:39]
	s_cbranch_vccz .LBB0_340
.LBB0_343:
	s_add_i32 s14, s16, 7
	s_add_i32 s15, s17, 4
	v_mov_b32_e32 v30, s14
	v_mov_b32_e32 v31, s15
	v_cndmask_b32_e64 v112, v30, v31, s[6:7]
	v_cndmask_b32_e64 v56, v30, v31, s[4:5]
	v_cndmask_b32_e64 v60, v30, v31, s[8:9]
	v_lshlrev_b64 v[30:31], 15, v[112:113]
	v_mov_b32_e32 v57, v113
	v_lshl_add_u64 v[52:53], v[40:41], 0, v[30:31]
	v_lshlrev_b64 v[30:31], 9, v[112:113]
	v_lshlrev_b64 v[54:55], 15, v[56:57]
	v_lshlrev_b64 v[56:57], 9, v[56:57]
	v_lshl_add_u64 v[30:31], v[42:43], 0, v[30:31]
	v_lshl_add_u64 v[54:55], v[44:45], 0, v[54:55]
	v_lshl_add_u64 v[56:57], v[46:47], 0, v[56:57]
	v_mov_b32_e32 v61, v113
	global_load_ushort v85, v[52:53], off
	global_load_ushort v86, v[54:55], off
	s_add_i32 s15, s16, 6
	global_load_dword v30, v[30:31], off
	s_add_i32 s18, s17, 5
	global_load_dword v31, v[56:57], off
	v_lshlrev_b64 v[56:57], 14, v[60:61]
	v_lshl_add_u64 v[58:59], v[48:49], 0, v[56:57]
	v_lshlrev_b64 v[56:57], 8, v[60:61]
	v_lshl_add_u64 v[56:57], v[50:51], 0, v[56:57]
	global_load_ushort v88, v[58:59], off
	global_load_dword v89, v[56:57], off
	v_mov_b32_e32 v56, s15
	v_mov_b32_e32 v57, s18
	v_cndmask_b32_e64 v112, v56, v57, s[6:7]
	v_cndmask_b32_e64 v64, v56, v57, s[4:5]
	v_cndmask_b32_e64 v66, v56, v57, s[8:9]
	v_lshlrev_b64 v[56:57], 15, v[112:113]
	v_mov_b32_e32 v65, v113
	v_lshl_add_u64 v[60:61], v[40:41], 0, v[56:57]
	v_lshlrev_b64 v[56:57], 9, v[112:113]
	v_lshlrev_b64 v[62:63], 15, v[64:65]
	v_lshlrev_b64 v[64:65], 9, v[64:65]
	v_lshl_add_u64 v[56:57], v[42:43], 0, v[56:57]
	v_lshl_add_u64 v[62:63], v[44:45], 0, v[62:63]
	v_lshl_add_u64 v[64:65], v[46:47], 0, v[64:65]
	v_mov_b32_e32 v67, v113
	global_load_ushort v87, v[60:61], off
	global_load_ushort v90, v[62:63], off
	s_add_i32 s18, s16, 5
	global_load_dword v56, v[56:57], off
	s_add_i32 s19, s17, 6
	global_load_dword v57, v[64:65], off
	v_lshlrev_b64 v[64:65], 14, v[66:67]
	v_lshlrev_b64 v[66:67], 8, v[66:67]
	v_lshl_add_u64 v[64:65], v[48:49], 0, v[64:65]
	v_lshl_add_u64 v[66:67], v[50:51], 0, v[66:67]
	global_load_ushort v92, v[64:65], off
	global_load_dword v93, v[66:67], off
	v_mov_b32_e32 v66, s18
	v_mov_b32_e32 v67, s19
	v_cndmask_b32_e64 v112, v66, v67, s[6:7]
	v_cndmask_b32_e64 v72, v66, v67, s[4:5]
	v_cndmask_b32_e64 v74, v66, v67, s[8:9]
	v_lshlrev_b64 v[66:67], 15, v[112:113]
	v_mov_b32_e32 v73, v113
	v_lshl_add_u64 v[68:69], v[40:41], 0, v[66:67]
	v_lshlrev_b64 v[66:67], 9, v[112:113]
	v_lshlrev_b64 v[70:71], 15, v[72:73]
	v_lshlrev_b64 v[72:73], 9, v[72:73]
	v_lshl_add_u64 v[66:67], v[42:43], 0, v[66:67]
	v_lshl_add_u64 v[70:71], v[44:45], 0, v[70:71]
	v_lshl_add_u64 v[72:73], v[46:47], 0, v[72:73]
	v_mov_b32_e32 v75, v113
	global_load_ushort v91, v[68:69], off
	global_load_ushort v94, v[70:71], off
	s_add_i32 s19, s16, 4
	global_load_dword v66, v[66:67], off
	s_add_i32 s20, s17, 7
	global_load_dword v67, v[72:73], off
	v_lshlrev_b64 v[72:73], 14, v[74:75]
	v_lshlrev_b64 v[74:75], 8, v[74:75]
	v_lshl_add_u64 v[72:73], v[48:49], 0, v[72:73]
	v_lshl_add_u64 v[74:75], v[50:51], 0, v[74:75]
	global_load_ushort v97, v[72:73], off
	global_load_dword v98, v[74:75], off
	v_mov_b32_e32 v74, s19
; __device__ __forceinline__ void pass2_triple(const KArgs& a, int t) {
;     ...
;     P2_LOAD(uA, dA, 0);
; #pragma unroll 1
;     for (int sb = 0; sb < NCH; sb += 8) {
;         P2_LOAD(uB, dB, sb + 4);
;         P2_STEP(uA, dA, sb);
;         if (sb + 8 < NCH) P2_LOAD(uA, dA, sb + 8);
;         P2_STEP(uB, dB, sb + 4);
	v_mov_b32_e32 v75, s20
	v_cndmask_b32_e64 v112, v74, v75, s[6:7]
	v_cndmask_b32_e64 v80, v74, v75, s[4:5]
	v_cndmask_b32_e64 v102, v74, v75, s[8:9]
	v_lshlrev_b64 v[74:75], 15, v[112:113]
	v_mov_b32_e32 v81, v113
	v_lshl_add_u64 v[76:77], v[40:41], 0, v[74:75]
	v_lshlrev_b64 v[74:75], 9, v[112:113]
	v_lshlrev_b64 v[78:79], 15, v[80:81]
	v_lshlrev_b64 v[80:81], 9, v[80:81]
	v_lshl_add_u64 v[74:75], v[42:43], 0, v[74:75]
	v_lshl_add_u64 v[78:79], v[44:45], 0, v[78:79]
	v_lshl_add_u64 v[80:81], v[46:47], 0, v[80:81]
	v_mov_b32_e32 v103, v113
	global_load_ushort v95, v[76:77], off
	global_load_ushort v96, v[78:79], off
	s_add_i32 s19, s16, 11
	global_load_dword v74, v[74:75], off
	s_add_i32 s14, s17, 1
	global_load_dword v75, v[80:81], off
	v_lshlrev_b64 v[80:81], 14, v[102:103]
	v_lshlrev_b64 v[102:103], 8, v[102:103]
	v_lshl_add_u64 v[80:81], v[48:49], 0, v[80:81]
	v_lshl_add_u64 v[102:103], v[50:51], 0, v[102:103]
	global_load_ushort v99, v[80:81], off
	global_load_dword v100, v[102:103], off
	v_mov_b32_e32 v102, s19
	v_mov_b32_e32 v103, s17
	v_cndmask_b32_e64 v104, v102, v103, s[6:7]
	v_cndmask_b32_e64 v105, v102, v103, s[4:5]
	v_cndmask_b32_e64 v106, v102, v103, s[8:9]
	v_bfe_u32 v102, v82, 16, 1
	v_lshlrev_b32_e32 v112, 15, v104
	v_add3_u32 v107, v82, v102, s1
	v_lshl_add_u64 v[102:103], v[40:41], 0, v[112:113]
	global_store_short_d16_hi v[102:103], v107, off
	v_bfe_u32 v102, v83, 16, 1
	v_lshlrev_b32_e32 v112, 15, v105
	v_add3_u32 v104, v83, v102, s1
	v_lshl_add_u64 v[102:103], v[44:45], 0, v[112:113]
	global_store_short_d16_hi v[102:103], v104, off
	v_bfe_u32 v102, v101, 16, 1
	v_lshlrev_b32_e32 v112, 14, v106
	v_lshlrev_b32_e32 v108, 16, v28
	s_add_i32 s19, s16, 10
	v_add3_u32 v104, v101, v102, s1
	v_lshl_add_u64 v[102:103], v[48:49], 0, v[112:113]
	v_fmac_f32_e32 v108, v101, v8
	v_mov_b32_e32 v8, s19
	v_mov_b32_e32 v101, s14
	v_mov_b32_e32 v110, v0
	v_mov_b32_e32 v111, v4
	v_lshlrev_b32_e32 v115, 16, v26
	v_lshlrev_b32_e32 v114, 16, v24
	global_store_short_d16_hi v[102:103], v104, off
	v_cndmask_b32_e64 v102, v8, v101, s[6:7]
	v_pk_fma_f32 v[82:83], v[82:83], v[110:111], v[114:115]
	v_lshlrev_b32_e32 v112, 15, v102
	v_bfe_u32 v0, v82, 16, 1
	v_cndmask_b32_e64 v104, v8, v101, s[4:5]
	v_lshl_add_u64 v[102:103], v[40:41], 0, v[112:113]
	v_add3_u32 v0, v82, v0, s1
	v_lshlrev_b32_e32 v112, 15, v104
	global_store_short_d16_hi v[102:103], v0, off
	v_bfe_u32 v0, v83, 16, 1
	s_add_i32 s15, s17, 2
	v_cndmask_b32_e64 v8, v8, v101, s[8:9]
	v_lshl_add_u64 v[104:105], v[44:45], 0, v[112:113]
	v_and_b32_e32 v28, 0xffff0000, v28
	s_add_i32 s14, s16, 9
	v_add3_u32 v0, v83, v0, s1
	v_bfe_u32 v101, v108, 16, 1
	v_lshlrev_b32_e32 v112, 14, v8
	v_fmac_f32_e32 v28, v9, v108
	v_mov_b32_e32 v8, s14
	v_mov_b32_e32 v9, s15
	global_store_short_d16_hi v[104:105], v0, off
	v_mov_b32_e32 v4, v1
	v_and_b32_e32 v1, 0xffff0000, v26
	v_and_b32_e32 v0, 0xffff0000, v24
	v_add3_u32 v101, v108, v101, s1
	v_cndmask_b32_e64 v108, v8, v9, s[6:7]
	v_pk_fma_f32 v[0:1], v[4:5], v[82:83], v[0:1]
	v_lshl_add_u64 v[106:107], v[48:49], 0, v[112:113]
	v_lshlrev_b32_e32 v112, 15, v108
	v_bfe_u32 v4, v0, 16, 1
	v_cndmask_b32_e64 v109, v8, v9, s[4:5]
	v_cndmask_b32_e64 v116, v8, v9, s[8:9]
	v_lshl_add_u64 v[8:9], v[40:41], 0, v[112:113]
	v_add3_u32 v4, v0, v4, s1
	v_lshlrev_b32_e32 v112, 15, v109
	global_store_short_d16_hi v[106:107], v101, off
	global_store_short_d16_hi v[8:9], v4, off
	v_bfe_u32 v4, v1, 16, 1
	v_lshl_add_u64 v[108:109], v[44:45], 0, v[112:113]
	v_add3_u32 v4, v1, v4, s1
	global_store_short_d16_hi v[108:109], v4, off
	v_mov_b32_e32 v4, v2
	v_bfe_u32 v2, v28, 16, 1
	v_lshlrev_b32_e32 v112, 14, v116
	v_add3_u32 v2, v28, v2, s1
	v_lshl_add_u64 v[82:83], v[48:49], 0, v[112:113]
	s_add_i32 s18, s17, 3
	global_store_short_d16_hi v[82:83], v2, off
	v_lshlrev_b32_e32 v2, 16, v29
	s_add_i32 s14, s16, 8
	v_mov_b32_e32 v5, v6
	v_lshlrev_b32_e32 v9, 16, v27
	v_lshlrev_b32_e32 v8, 16, v25
	v_fmac_f32_e32 v2, v10, v28
	v_mov_b32_e32 v6, s14
	v_mov_b32_e32 v10, s18
	v_cndmask_b32_e64 v24, v6, v10, s[6:7]
	v_pk_fma_f32 v[0:1], v[4:5], v[0:1], v[8:9]
	v_lshlrev_b32_e32 v112, 15, v24
	v_bfe_u32 v4, v0, 16, 1
	v_cndmask_b32_e64 v26, v6, v10, s[4:5]
	v_lshl_add_u64 v[82:83], v[40:41], 0, v[112:113]
	v_add3_u32 v4, v0, v4, s1
	v_lshlrev_b32_e32 v112, 15, v26
	global_store_short_d16_hi v[82:83], v4, off
	v_bfe_u32 v4, v1, 16, 1
	s_add_i32 s18, s17, 8
	v_cndmask_b32_e64 v6, v6, v10, s[8:9]
	v_lshl_add_u64 v[102:103], v[44:45], 0, v[112:113]
	v_add3_u32 v4, v1, v4, s1
	s_cmpk_gt_u32 s17, 0xf7
	global_store_short_d16_hi v[102:103], v4, off
	v_bfe_u32 v4, v2, 16, 1
	v_lshlrev_b32_e32 v112, 14, v6
	s_cselect_b64 s[14:15], -1, 0
	v_add3_u32 v8, v2, v4, s1
	v_lshl_add_u64 v[4:5], v[48:49], 0, v[112:113]
	s_and_b64 vcc, exec, s[14:15]
	global_store_short_d16_hi v[4:5], v8, off
	s_cbranch_vccnz .LBB0_342
; __device__ __forceinline__ void pass2_triple(const KArgs& a, int t) {
;     ...
;     P2_LOAD(uA, dA, 0);
; #pragma unroll 1
;     for (int sb = 0; sb < NCH; sb += 8) {
;         P2_LOAD(uB, dB, sb + 4);
;         P2_STEP(uA, dA, sb);
;         if (sb + 8 < NCH) P2_LOAD(uA, dA, sb + 8);
	s_add_i32 s19, s16, 3
	v_mov_b32_e32 v5, s19
	v_mov_b32_e32 v6, s18
	v_cndmask_b32_e64 v112, v5, v6, s[6:7]
	v_cndmask_b32_e64 v4, v5, v6, s[4:5]
	v_cndmask_b32_e64 v8, v5, v6, s[8:9]
	v_mov_b32_e32 v5, v113
	v_lshlrev_b64 v[12:13], 15, v[112:113]
	v_lshlrev_b64 v[14:15], 15, v[4:5]
	v_lshlrev_b64 v[4:5], 9, v[4:5]
	v_lshl_add_u64 v[12:13], v[40:41], 0, v[12:13]
	v_lshl_add_u64 v[4:5], v[46:47], 0, v[4:5]
	v_mov_b32_e32 v9, v113
	global_load_ushort v6, v[12:13], off
	global_load_dword v16, v[4:5], off
	v_lshlrev_b64 v[12:13], 9, v[112:113]
	v_lshlrev_b64 v[4:5], 14, v[8:9]
	v_lshl_add_u64 v[12:13], v[42:43], 0, v[12:13]
	v_lshl_add_u64 v[4:5], v[48:49], 0, v[4:5]
	global_load_dword v12, v[12:13], off
	v_lshl_add_u64 v[14:15], v[44:45], 0, v[14:15]
	global_load_ushort v24, v[4:5], off
	v_lshlrev_b64 v[4:5], 8, v[8:9]
	v_lshl_add_u64 v[4:5], v[50:51], 0, v[4:5]
	s_add_i32 s19, s17, 9
	s_add_i32 s20, s16, 2
	global_load_ushort v10, v[14:15], off
	global_load_dword v20, v[4:5], off
	v_mov_b32_e32 v5, s20
	v_mov_b32_e32 v8, s19
	v_cndmask_b32_e64 v112, v5, v8, s[6:7]
	v_lshlrev_b64 v[14:15], 15, v[112:113]
	v_lshl_add_u64 v[14:15], v[40:41], 0, v[14:15]
	global_load_ushort v26, v[14:15], off
	v_lshlrev_b64 v[14:15], 9, v[112:113]
	v_cndmask_b32_e64 v4, v5, v8, s[4:5]
	v_cndmask_b32_e64 v8, v5, v8, s[8:9]
	v_lshl_add_u64 v[14:15], v[42:43], 0, v[14:15]
	v_mov_b32_e32 v5, v113
	global_load_dword v13, v[14:15], off
	v_lshlrev_b64 v[14:15], 15, v[4:5]
	v_lshlrev_b64 v[4:5], 9, v[4:5]
	v_lshl_add_u64 v[14:15], v[44:45], 0, v[14:15]
	v_lshl_add_u64 v[4:5], v[46:47], 0, v[4:5]
	global_load_ushort v28, v[14:15], off
	global_load_dword v17, v[4:5], off
	v_lshlrev_b64 v[4:5], 14, v[8:9]
	v_lshl_add_u64 v[4:5], v[48:49], 0, v[4:5]
	global_load_ushort v34, v[4:5], off
	v_lshlrev_b64 v[4:5], 8, v[8:9]
	v_lshl_add_u64 v[4:5], v[50:51], 0, v[4:5]
	s_add_i32 s19, s17, 10
	s_add_i32 s20, s16, 1
	global_load_dword v21, v[4:5], off
	v_mov_b32_e32 v5, s20
	v_mov_b32_e32 v8, s19
	v_cndmask_b32_e64 v112, v5, v8, s[6:7]
	v_cndmask_b32_e64 v4, v5, v8, s[4:5]
	v_cndmask_b32_e64 v8, v5, v8, s[8:9]
	v_mov_b32_e32 v5, v113
	v_lshlrev_b64 v[14:15], 15, v[112:113]
	v_lshlrev_b64 v[18:19], 15, v[4:5]
	v_lshlrev_b64 v[4:5], 9, v[4:5]
	v_lshl_add_u64 v[14:15], v[40:41], 0, v[14:15]
	v_lshl_add_u64 v[18:19], v[44:45], 0, v[18:19]
	v_lshl_add_u64 v[4:5], v[46:47], 0, v[4:5]
	global_load_ushort v38, v[14:15], off
	global_load_ushort v35, v[18:19], off
	s_add_i32 s17, s17, 11
	global_load_dword v18, v[4:5], off
	v_lshlrev_b64 v[14:15], 9, v[112:113]
	v_lshlrev_b64 v[4:5], 14, v[8:9]
	v_lshl_add_u64 v[14:15], v[42:43], 0, v[14:15]
	v_lshl_add_u64 v[4:5], v[48:49], 0, v[4:5]
	global_load_dword v14, v[14:15], off
	s_mov_b32 s0, 0x5040100
	global_load_ushort v36, v[4:5], off
	v_lshlrev_b64 v[4:5], 8, v[8:9]
	v_lshl_add_u64 v[4:5], v[50:51], 0, v[4:5]
	global_load_dword v22, v[4:5], off
	v_mov_b32_e32 v5, s16
	v_mov_b32_e32 v8, s17
	v_cndmask_b32_e64 v112, v5, v8, s[6:7]
	v_lshlrev_b64 v[32:33], 15, v[112:113]
	v_lshl_add_u64 v[32:33], v[40:41], 0, v[32:33]
	global_load_ushort v39, v[32:33], off
	v_lshlrev_b64 v[32:33], 9, v[112:113]
	v_cndmask_b32_e64 v4, v5, v8, s[4:5]
	v_cndmask_b32_e64 v8, v5, v8, s[8:9]
	v_lshl_add_u64 v[32:33], v[42:43], 0, v[32:33]
	v_mov_b32_e32 v5, v113
	global_load_dword v15, v[32:33], off
	v_lshlrev_b64 v[32:33], 15, v[4:5]
	v_lshlrev_b64 v[4:5], 9, v[4:5]
	v_lshl_add_u64 v[32:33], v[44:45], 0, v[32:33]
	v_lshl_add_u64 v[4:5], v[46:47], 0, v[4:5]
	global_load_ushort v82, v[32:33], off
	global_load_dword v19, v[4:5], off
	v_lshlrev_b64 v[32:33], 14, v[8:9]
	v_lshl_add_u64 v[32:33], v[48:49], 0, v[32:33]
	v_lshlrev_b64 v[4:5], 8, v[8:9]
	global_load_ushort v32, v[32:33], off
	v_lshl_add_u64 v[4:5], v[50:51], 0, v[4:5]
	global_load_dword v23, v[4:5], off
	s_waitcnt vmcnt(0) lgkmcnt(0)
	v_perm_b32 v33, v39, v38, s0
	v_perm_b32 v35, v82, v35, s0
	v_perm_b32 v37, v32, v36, s0
	v_perm_b32 v36, v34, v24, s0
	v_perm_b32 v34, v28, v10, s0
	v_perm_b32 v32, v26, v6, s0
	s_branch .LBB0_342

;     __device__ __forceinline__ void operator()(const f32x4 (&acc)[2][2][4][2], const Unit& u, int wr, int wc, int fr, int fq) const {
;     ...
;                 for (int bj = 0; bj < 2; ++bj) { const int row = row0 + ai * HALF + m * 16, e = (u.pn * BM + bj * HALF + wc * 32 + 8 * fq) % 192, i0 = e >= 128 ? (e - 128) >> 1 : 0;
;                     ccv[m][bj] = *(const f32x4*)(cs + (size_t)row * 32 + i0); ssv[m][bj] = *(const f32x4*)(sn + (size_t)row * 32 + i0); }
; #pragma unroll
;             for (int m = 0; m < 4; ++m) { const int row = row0 + ai * HALF + m * 16, b = row / T, t = row % T;
; #pragma unroll
;                 for (int bj = 0; bj < 2; ++bj) { const int c = u.pn * BM + bj * HALF + wc * 32 + 8 * fq, hh = c / 192, e = c % 192;
;                     const f32x4 v0 = acc[ai][bj][m][0], v1 = acc[ai][bj][m][1];
;                     float vals[8] = {v0[0], v0[1], v0[2], v0[3], v1[0], v1[1], v1[2], v1[3]};
;                     if (e >= 128) { const f32x4 cc = ccv[m][bj], ss = ssv[m][bj];
; #pragma unroll
;                         for (int p = 0; p < 4; ++p) { const float x1 = vals[2 * p], x2 = vals[2 * p + 1]; vals[2 * p] = x1 * cc[p] - x2 * ss[p]; vals[2 * p + 1] = x2 * cc[p] + x1 * ss[p]; } }
.LBB0_359:
	v_lshl_add_u32 v212, s46, 8, v228
	v_lshl_or_b32 v126, s45, 8, v230
	s_mov_b32 s19, 0x2aaaaaab
	v_mul_hi_i32 v122, v126, s19
	v_ashrrev_i32_e32 v213, 31, v212
	v_lshrrev_b32_e32 v123, 31, v122
	v_ashrrev_i32_e32 v122, 5, v122
	v_lshlrev_b64 v[124:125], 7, v[212:213]
	v_add_u32_e32 v233, v122, v123
	s_movk_i32 s24, 0xc0
	v_lshl_add_u64 v[224:225], s[12:13], 0, v[124:125]
	v_lshl_add_u64 v[226:227], s[14:15], 0, v[124:125]
	v_or_b32_e32 v124, 0x80, v126
	v_mul_lo_u32 v122, v233, s24
	v_mul_hi_i32 v125, v124, s19
	v_sub_u32_e32 v210, v126, v122
	v_lshrrev_b32_e32 v126, 31, v125
	v_ashrrev_i32_e32 v125, 5, v125
	v_add_u32_e32 v232, v125, v126
	v_mul_lo_u32 v125, v232, s24
	v_sub_u32_e32 v208, v124, v125
	s_movk_i32 s0, 0x7f
	v_add_u32_e32 v124, 0xffffff80, v208
	v_ashrrev_i32_e32 v124, 1, v124
	v_cmp_lt_i32_e32 vcc, s0, v208
	v_add_u32_e32 v122, 0xffffff80, v210
	v_ashrrev_i32_e32 v122, 1, v122
	v_cndmask_b32_e32 v124, 0, v124, vcc
	v_ashrrev_i32_e32 v125, 31, v124
	v_lshlrev_b64 v[216:217], 2, v[124:125]
	v_cmp_lt_i32_e64 s[6:7], s0, v210
	v_lshl_add_u64 v[124:125], v[224:225], 0, v[216:217]
	v_or_b32_e32 v222, 16, v212
	v_cndmask_b32_e64 v122, 0, v122, s[6:7]
	global_load_dwordx4 v[178:181], v[124:125], off
	v_lshl_add_u64 v[124:125], v[226:227], 0, v[216:217]
	v_ashrrev_i32_e32 v223, 31, v222
	v_ashrrev_i32_e32 v123, 31, v122
	global_load_dwordx4 v[182:185], v[124:125], off
	v_lshlrev_b64 v[124:125], 7, v[222:223]
	v_lshl_add_u64 v[126:127], s[12:13], 0, v[124:125]
	v_lshlrev_b64 v[214:215], 2, v[122:123]
	v_lshl_add_u64 v[124:125], s[14:15], 0, v[124:125]
	v_lshl_add_u64 v[122:123], v[126:127], 0, v[214:215]
	global_load_dwordx4 v[170:173], v[122:123], off
	v_lshl_add_u64 v[122:123], v[124:125], 0, v[214:215]
	global_load_dwordx4 v[174:177], v[122:123], off
	v_lshl_add_u64 v[122:123], v[126:127], 0, v[216:217]
	v_or_b32_e32 v220, 32, v212
	global_load_dwordx4 v[162:165], v[122:123], off
	v_lshl_add_u64 v[122:123], v[124:125], 0, v[216:217]
	v_ashrrev_i32_e32 v221, 31, v220
	global_load_dwordx4 v[166:169], v[122:123], off
	v_lshlrev_b64 v[122:123], 7, v[220:221]
	v_lshl_add_u64 v[124:125], s[12:13], 0, v[122:123]
	v_lshl_add_u64 v[122:123], s[14:15], 0, v[122:123]
	v_lshl_add_u64 v[126:127], v[124:125], 0, v[214:215]
	v_lshl_add_u64 v[124:125], v[124:125], 0, v[216:217]
	v_or_b32_e32 v218, 48, v212
	global_load_dwordx4 v[154:157], v[126:127], off
	global_load_dwordx4 v[146:149], v[124:125], off
	v_lshl_add_u64 v[126:127], v[122:123], 0, v[214:215]
	v_lshl_add_u64 v[122:123], v[122:123], 0, v[216:217]
	v_ashrrev_i32_e32 v219, 31, v218
	global_load_dwordx4 v[150:153], v[122:123], off
	v_lshlrev_b64 v[122:123], 7, v[218:219]
	v_lshl_add_u64 v[124:125], s[12:13], 0, v[122:123]
	global_load_dwordx4 v[158:161], v[126:127], off
	v_lshl_add_u64 v[126:127], s[14:15], 0, v[122:123]
	v_lshl_add_u64 v[122:123], v[124:125], 0, v[214:215]
	global_load_dwordx4 v[138:141], v[122:123], off
	v_lshl_add_u64 v[122:123], v[126:127], 0, v[214:215]
	v_lshl_add_u64 v[126:127], v[126:127], 0, v[216:217]
	global_load_dwordx4 v[142:145], v[122:123], off
	s_nop 0
	global_load_dwordx4 v[126:129], v[126:127], off
	v_lshl_add_u64 v[122:123], v[124:125], 0, v[216:217]
	global_load_dwordx4 v[122:125], v[122:123], off
	s_and_saveexec_b64 s[24:25], s[6:7]
	s_cbranch_execz .LBB0_361
	v_lshl_add_u64 v[196:197], v[226:227], 0, v[214:215]
	global_load_dwordx4 v[244:247], v[196:197], off
	v_lshl_add_u64 v[196:197], v[224:225], 0, v[214:215]
	global_load_dwordx4 v[224:227], v[196:197], off
	s_waitcnt vmcnt(0) lgkmcnt(0)
	v_pk_mul_f32 v[202:203], v[136:137], v[244:245] op_sel:[1,1] op_sel_hi:[0,1]
	v_pk_mul_f32 v[198:199], v[134:135], v[244:245] op_sel:[1,0] op_sel_hi:[0,0]
	v_pk_fma_f32 v[204:205], v[136:137], v[224:225], v[202:203] op_sel:[0,1,0] neg_lo:[0,0,1] neg_hi:[0,0,1]
	v_pk_fma_f32 v[136:137], v[136:137], v[224:225], v[202:203] op_sel:[0,1,0]
	v_pk_mul_f32 v[202:203], v[130:131], v[246:247] op_sel:[1,0] op_sel_hi:[0,0]
	v_pk_mul_f32 v[196:197], v[134:135], v[224:225]
	v_pk_fma_f32 v[134:135], v[134:135], v[224:225], v[198:199] op_sel_hi:[1,0,1]
	v_pk_fma_f32 v[224:225], v[130:131], v[226:227], v[202:203] op_sel_hi:[1,0,1] neg_lo:[0,0,1] neg_hi:[0,0,1]
	v_pk_fma_f32 v[130:131], v[130:131], v[226:227], v[202:203] op_sel_hi:[1,0,1]
	v_mov_b32_e32 v246, v227
	v_mul_f32_e32 v130, v133, v247
	v_pk_fma_f32 v[202:203], v[132:133], v[246:247], v[130:131] op_sel_hi:[1,1,0] neg_lo:[0,0,1] neg_hi:[0,0,1]
	v_mov_b32_e32 v226, v247
	v_mul_f32_e32 v130, v133, v227
	v_pk_fma_f32 v[226:227], v[132:133], v[226:227], v[130:131] op_sel_hi:[1,1,0]
	v_sub_f32_e32 v134, v196, v198
	v_mov_b32_e32 v136, v204
	v_mov_b32_e32 v130, v224
	v_mov_b32_e32 v132, v202
	v_mov_b32_e32 v133, v226
; __device__ __forceinline__ unsigned cvt_pk_bf16(float lo, float hi) { f32x2 v = {lo, hi}; bf16x2_t b = __builtin_convertvector(v, bf16x2_t); return __builtin_bit_cast(unsigned, b); }
;     __device__ __forceinline__ void operator()(const f32x4 (&acc)[2][2][4][2], const Unit& u, int wr, int wc, int fr, int fq) const {
;     ...
;             for (int m = 0; m < 4; ++m) { const int row = row0 + ai * HALF + m * 16, b = row / T, t = row % T;
; #pragma unroll
;                 for (int bj = 0; bj < 2; ++bj) { const int c = u.pn * BM + bj * HALF + wc * 32 + 8 * fq, hh = c / 192, e = c % 192;
;                     const f32x4 v0 = acc[ai][bj][m][0], v1 = acc[ai][bj][m][1];
;                     float vals[8] = {v0[0], v0[1], v0[2], v0[3], v1[0], v1[1], v1[2], v1[3]};
;                     if (e >= 128) { const f32x4 cc = ccv[m][bj], ss = ssv[m][bj];
; #pragma unroll
;                         for (int p = 0; p < 4; ++p) { const float x1 = vals[2 * p], x2 = vals[2 * p + 1]; vals[2 * p] = x1 * cc[p] - x2 * ss[p]; vals[2 * p + 1] = x2 * cc[p] + x1 * ss[p]; } }
;                     constexpr float QS = 0.07216878364870322f * 1.4426950408889634f;
; #pragma unroll
;                     for (int p_ = 0; p_ < 8; ++p_) vals[p_] *= QS;
;                     u32x4 w; w.x = cvt_pk_bf16(vals[0], vals[1]); w.y = cvt_pk_bf16(vals[2], vals[3]); w.z = cvt_pk_bf16(vals[4], vals[5]); w.w = cvt_pk_bf16(vals[6], vals[7]);
;                     *(u32x4*)(Q + ((size_t)(b * 8 + hh) * T + t) * 192 + e) = w; } } }
.LBB0_361:
	s_or_b64 exec, exec, s[24:25]
	v_lshrrev_b32_e32 v196, 18, v213
	v_add_u32_e32 v196, v212, v196
	v_ashrrev_i32_e32 v196, 14, v196
	s_mov_b32 s0, 0x3dd53b94
	v_mul_i32_i24_e32 v197, 0x4000, v196
	v_lshlrev_b32_e32 v209, 3, v196
	v_pk_mul_f32 v[134:135], v[134:135], s[0:1] op_sel_hi:[1,0]
	v_sub_u32_e32 v224, v212, v197
	v_pk_mul_f32 v[196:197], v[130:131], s[0:1] op_sel_hi:[1,0]
	v_cvt_pk_bf16_f32 v130, v134, v135
	v_add_u32_e32 v134, v209, v233
	v_ashrrev_i32_e32 v135, 31, v134
	v_ashrrev_i32_e32 v225, 31, v224
	v_pk_mul_f32 v[136:137], v[136:137], s[0:1] op_sel_hi:[1,0]
	v_lshlrev_b64 v[134:135], 14, v[134:135]
	v_pk_mul_f32 v[198:199], v[132:133], s[0:1] op_sel_hi:[1,0]
	v_cvt_pk_bf16_f32 v131, v136, v137
	v_lshl_add_u64 v[134:135], v[134:135], 0, v[224:225]
	v_mov_b64_e32 v[136:137], s[10:11]
	s_movk_i32 s0, 0x180
	v_mad_u64_u32 v[136:137], s[24:25], v134, s0, v[136:137]
	v_mad_i32_i24 v137, v135, s0, v137
	v_ashrrev_i32_e32 v211, 31, v210
	v_cvt_pk_bf16_f32 v132, v196, v197
	v_cvt_pk_bf16_f32 v133, v198, v199
	v_lshl_add_u64 v[134:135], v[210:211], 1, v[136:137]
	global_store_dwordx4 v[134:135], v[130:133], off
	s_and_saveexec_b64 s[24:25], vcc
	s_cbranch_execz .LBB0_363
	s_waitcnt vmcnt(0) lgkmcnt(0)
	v_pk_mul_f32 v[134:135], v[120:121], v[182:183] op_sel:[1,1] op_sel_hi:[0,1]
	v_pk_mul_f32 v[132:133], v[118:119], v[182:183] op_sel:[1,0] op_sel_hi:[0,0]
	v_pk_fma_f32 v[136:137], v[120:121], v[178:179], v[134:135] op_sel:[0,1,0] neg_lo:[0,0,1] neg_hi:[0,0,1]
	v_pk_fma_f32 v[120:121], v[120:121], v[178:179], v[134:135] op_sel:[0,1,0]
	v_pk_mul_f32 v[134:135], v[114:115], v[184:185] op_sel:[1,0] op_sel_hi:[0,0]
	v_pk_mul_f32 v[130:131], v[118:119], v[178:179]
	v_pk_fma_f32 v[118:119], v[118:119], v[178:179], v[132:133] op_sel_hi:[1,0,1]
	v_pk_fma_f32 v[178:179], v[114:115], v[180:181], v[134:135] op_sel_hi:[1,0,1] neg_lo:[0,0,1] neg_hi:[0,0,1]
	v_pk_fma_f32 v[114:115], v[114:115], v[180:181], v[134:135] op_sel_hi:[1,0,1]
	v_mov_b32_e32 v184, v181
	v_mul_f32_e32 v114, v117, v185
	v_pk_fma_f32 v[134:135], v[116:117], v[184:185], v[114:115] op_sel_hi:[1,1,0] neg_lo:[0,0,1] neg_hi:[0,0,1]
	v_mov_b32_e32 v180, v185
	v_mul_f32_e32 v114, v117, v181
	v_pk_fma_f32 v[180:181], v[116:117], v[180:181], v[114:115] op_sel_hi:[1,1,0]
	v_sub_f32_e32 v118, v130, v132
	v_mov_b32_e32 v120, v136
	v_mov_b32_e32 v114, v178
	v_mov_b32_e32 v116, v134
	v_mov_b32_e32 v117, v180
.LBB0_363:
	s_or_b64 exec, exec, s[24:25]
	s_mov_b32 s0, 0x3dd53b94
	v_pk_mul_f32 v[118:119], v[118:119], s[0:1] op_sel_hi:[1,0]
	v_pk_mul_f32 v[130:131], v[114:115], s[0:1] op_sel_hi:[1,0]
	v_cvt_pk_bf16_f32 v114, v118, v119
	v_add_u32_e32 v118, v209, v232
	v_ashrrev_i32_e32 v119, 31, v118
	v_pk_mul_f32 v[120:121], v[120:121], s[0:1] op_sel_hi:[1,0]
	v_lshlrev_b64 v[118:119], 14, v[118:119]
	v_pk_mul_f32 v[132:133], v[116:117], s[0:1] op_sel_hi:[1,0]
	v_cvt_pk_bf16_f32 v115, v120, v121
	v_lshl_add_u64 v[118:119], v[118:119], 0, v[224:225]
	v_mov_b64_e32 v[120:121], s[10:11]
	s_movk_i32 s0, 0x180
	v_mad_u64_u32 v[120:121], s[24:25], v118, s0, v[120:121]
	v_mad_i32_i24 v121, v119, s0, v121
	v_ashrrev_i32_e32 v209, 31, v208
	v_cvt_pk_bf16_f32 v116, v130, v131
	v_cvt_pk_bf16_f32 v117, v132, v133
	v_lshl_add_u64 v[118:119], v[208:209], 1, v[120:121]
	global_store_dwordx4 v[118:119], v[114:117], off
	s_and_saveexec_b64 s[24:25], s[6:7]
	s_cbranch_execz .LBB0_365
	s_waitcnt vmcnt(0) lgkmcnt(0)
	v_pk_mul_f32 v[118:119], v[110:111], v[174:175] op_sel:[1,1] op_sel_hi:[0,1]
	v_pk_fma_f32 v[120:121], v[110:111], v[170:171], v[118:119] op_sel:[0,1,0] neg_lo:[0,0,1] neg_hi:[0,0,1]
	v_pk_fma_f32 v[110:111], v[110:111], v[170:171], v[118:119] op_sel:[0,1,0]
	v_pk_mul_f32 v[118:119], v[104:105], v[176:177] op_sel:[1,0] op_sel_hi:[0,0]
	v_pk_fma_f32 v[130:131], v[104:105], v[172:173], v[118:119] op_sel_hi:[1,0,1] neg_lo:[0,0,1] neg_hi:[0,0,1]
	v_pk_fma_f32 v[104:105], v[104:105], v[172:173], v[118:119] op_sel_hi:[1,0,1]
	v_mov_b32_e32 v176, v173
	v_mul_f32_e32 v104, v107, v177
	v_pk_mul_f32 v[116:117], v[108:109], v[174:175] op_sel:[1,0] op_sel_hi:[0,0]
	v_pk_fma_f32 v[118:119], v[106:107], v[176:177], v[104:105] op_sel_hi:[1,1,0] neg_lo:[0,0,1] neg_hi:[0,0,1]
	v_mov_b32_e32 v172, v177
	v_mul_f32_e32 v104, v107, v173
	v_pk_mul_f32 v[114:115], v[108:109], v[170:171]
	v_pk_fma_f32 v[108:109], v[108:109], v[170:171], v[116:117] op_sel_hi:[1,0,1]
	v_pk_fma_f32 v[132:133], v[106:107], v[172:173], v[104:105] op_sel_hi:[1,1,0]
	v_sub_f32_e32 v108, v114, v116
	v_mov_b32_e32 v110, v120
	v_mov_b32_e32 v104, v130
	v_mov_b32_e32 v106, v118
	v_mov_b32_e32 v107, v132
; __device__ __forceinline__ unsigned cvt_pk_bf16(float lo, float hi) { f32x2 v = {lo, hi}; bf16x2_t b = __builtin_convertvector(v, bf16x2_t); return __builtin_bit_cast(unsigned, b); }
;     __device__ __forceinline__ void operator()(const f32x4 (&acc)[2][2][4][2], const Unit& u, int wr, int wc, int fr, int fq) const {
;     ...
;             for (int m = 0; m < 4; ++m) { const int row = row0 + ai * HALF + m * 16, b = row / T, t = row % T;
; #pragma unroll
;                 for (int bj = 0; bj < 2; ++bj) { const int c = u.pn * BM + bj * HALF + wc * 32 + 8 * fq, hh = c / 192, e = c % 192;
;                     const f32x4 v0 = acc[ai][bj][m][0], v1 = acc[ai][bj][m][1];
;                     float vals[8] = {v0[0], v0[1], v0[2], v0[3], v1[0], v1[1], v1[2], v1[3]};
;                     if (e >= 128) { const f32x4 cc = ccv[m][bj], ss = ssv[m][bj];
; #pragma unroll
;                         for (int p = 0; p < 4; ++p) { const float x1 = vals[2 * p], x2 = vals[2 * p + 1]; vals[2 * p] = x1 * cc[p] - x2 * ss[p]; vals[2 * p + 1] = x2 * cc[p] + x1 * ss[p]; } }
;                     constexpr float QS = 0.07216878364870322f * 1.4426950408889634f;
; #pragma unroll
;                     for (int p_ = 0; p_ < 8; ++p_) vals[p_] *= QS;
;                     u32x4 w; w.x = cvt_pk_bf16(vals[0], vals[1]); w.y = cvt_pk_bf16(vals[2], vals[3]); w.z = cvt_pk_bf16(vals[4], vals[5]); w.w = cvt_pk_bf16(vals[6], vals[7]);
;                     *(u32x4*)(Q + ((size_t)(b * 8 + hh) * T + t) * 192 + e) = w; } } }
.LBB0_365:
	s_or_b64 exec, exec, s[24:25]
	v_lshrrev_b32_e32 v114, 18, v223
	v_add_u32_e32 v114, v222, v114
	v_ashrrev_i32_e32 v115, 14, v114
	s_mov_b32 s0, 0x3dd53b94
	v_lshlrev_b32_e32 v116, 3, v115
	v_pk_mul_f32 v[108:109], v[108:109], s[0:1] op_sel_hi:[1,0]
	v_mul_i32_i24_e32 v114, 0x4000, v115
	v_pk_mul_f32 v[118:119], v[104:105], s[0:1] op_sel_hi:[1,0]
	v_cvt_pk_bf16_f32 v104, v108, v109
	v_add_u32_e32 v108, v116, v233
	v_sub_u32_e32 v114, v222, v114
	v_ashrrev_i32_e32 v109, 31, v108
	v_ashrrev_i32_e32 v115, 31, v114
	v_pk_mul_f32 v[110:111], v[110:111], s[0:1] op_sel_hi:[1,0]
	v_lshlrev_b64 v[108:109], 14, v[108:109]
	v_pk_mul_f32 v[120:121], v[106:107], s[0:1] op_sel_hi:[1,0]
	v_cvt_pk_bf16_f32 v105, v110, v111
	v_lshl_add_u64 v[108:109], v[108:109], 0, v[114:115]
	v_mov_b64_e32 v[110:111], s[10:11]
	s_movk_i32 s0, 0x180
	v_mad_u64_u32 v[110:111], s[24:25], v108, s0, v[110:111]
	v_mad_i32_i24 v111, v109, s0, v111
	v_cvt_pk_bf16_f32 v106, v118, v119
	v_cvt_pk_bf16_f32 v107, v120, v121
	v_lshl_add_u64 v[108:109], v[210:211], 1, v[110:111]
	global_store_dwordx4 v[108:109], v[104:107], off
	s_and_saveexec_b64 s[24:25], vcc
	s_cbranch_execz .LBB0_367
	s_waitcnt vmcnt(0) lgkmcnt(0)
	v_pk_mul_f32 v[108:109], v[102:103], v[166:167] op_sel:[1,1] op_sel_hi:[0,1]
	v_pk_fma_f32 v[110:111], v[102:103], v[162:163], v[108:109] op_sel:[0,1,0] neg_lo:[0,0,1] neg_hi:[0,0,1]
	v_pk_fma_f32 v[102:103], v[102:103], v[162:163], v[108:109] op_sel:[0,1,0]
	v_pk_mul_f32 v[108:109], v[96:97], v[168:169] op_sel:[1,0] op_sel_hi:[0,0]
	v_pk_fma_f32 v[118:119], v[96:97], v[164:165], v[108:109] op_sel_hi:[1,0,1] neg_lo:[0,0,1] neg_hi:[0,0,1]
	v_pk_fma_f32 v[96:97], v[96:97], v[164:165], v[108:109] op_sel_hi:[1,0,1]
	v_mov_b32_e32 v168, v165
	v_mul_f32_e32 v96, v99, v169
	v_pk_mul_f32 v[106:107], v[100:101], v[166:167] op_sel:[1,0] op_sel_hi:[0,0]
	v_pk_fma_f32 v[108:109], v[98:99], v[168:169], v[96:97] op_sel_hi:[1,1,0] neg_lo:[0,0,1] neg_hi:[0,0,1]
	v_mov_b32_e32 v164, v169
	v_mul_f32_e32 v96, v99, v165
	v_pk_mul_f32 v[104:105], v[100:101], v[162:163]
	v_pk_fma_f32 v[100:101], v[100:101], v[162:163], v[106:107] op_sel_hi:[1,0,1]
	v_pk_fma_f32 v[120:121], v[98:99], v[164:165], v[96:97] op_sel_hi:[1,1,0]
	v_sub_f32_e32 v100, v104, v106
	v_mov_b32_e32 v102, v110
	v_mov_b32_e32 v96, v118
	v_mov_b32_e32 v98, v108
	v_mov_b32_e32 v99, v120
.LBB0_367:
	s_or_b64 exec, exec, s[24:25]
	s_mov_b32 s0, 0x3dd53b94
	v_pk_mul_f32 v[100:101], v[100:101], s[0:1] op_sel_hi:[1,0]
	v_pk_mul_f32 v[104:105], v[96:97], s[0:1] op_sel_hi:[1,0]
	v_cvt_pk_bf16_f32 v96, v100, v101
	v_add_u32_e32 v100, v116, v232
	v_ashrrev_i32_e32 v101, 31, v100
	v_pk_mul_f32 v[102:103], v[102:103], s[0:1] op_sel_hi:[1,0]
	v_lshlrev_b64 v[100:101], 14, v[100:101]
	v_pk_mul_f32 v[106:107], v[98:99], s[0:1] op_sel_hi:[1,0]
	v_cvt_pk_bf16_f32 v97, v102, v103
	v_lshl_add_u64 v[100:101], v[100:101], 0, v[114:115]
	v_mov_b64_e32 v[102:103], s[10:11]
	s_movk_i32 s0, 0x180
	v_mad_u64_u32 v[102:103], s[24:25], v100, s0, v[102:103]
	v_mad_i32_i24 v103, v101, s0, v103
	v_cvt_pk_bf16_f32 v98, v104, v105
	v_cvt_pk_bf16_f32 v99, v106, v107
	v_lshl_add_u64 v[100:101], v[208:209], 1, v[102:103]
	global_store_dwordx4 v[100:101], v[96:99], off
	s_and_saveexec_b64 s[24:25], s[6:7]
	s_cbranch_execz .LBB0_369
	s_waitcnt vmcnt(0) lgkmcnt(0)
	v_pk_mul_f32 v[100:101], v[94:95], v[158:159] op_sel:[1,1] op_sel_hi:[0,1]
	v_pk_fma_f32 v[102:103], v[94:95], v[154:155], v[100:101] op_sel:[0,1,0] neg_lo:[0,0,1] neg_hi:[0,0,1]
	v_pk_fma_f32 v[94:95], v[94:95], v[154:155], v[100:101] op_sel:[0,1,0]
	v_pk_mul_f32 v[100:101], v[88:89], v[160:161] op_sel:[1,0] op_sel_hi:[0,0]
	v_pk_fma_f32 v[104:105], v[88:89], v[156:157], v[100:101] op_sel_hi:[1,0,1] neg_lo:[0,0,1] neg_hi:[0,0,1]
	v_pk_fma_f32 v[88:89], v[88:89], v[156:157], v[100:101] op_sel_hi:[1,0,1]
	v_mov_b32_e32 v160, v157
	v_mul_f32_e32 v88, v91, v161
	v_pk_mul_f32 v[98:99], v[92:93], v[158:159] op_sel:[1,0] op_sel_hi:[0,0]
	v_pk_fma_f32 v[100:101], v[90:91], v[160:161], v[88:89] op_sel_hi:[1,1,0] neg_lo:[0,0,1] neg_hi:[0,0,1]
	v_mov_b32_e32 v156, v161
	v_mul_f32_e32 v88, v91, v157
	v_pk_mul_f32 v[96:97], v[92:93], v[154:155]
	v_pk_fma_f32 v[92:93], v[92:93], v[154:155], v[98:99] op_sel_hi:[1,0,1]
	v_pk_fma_f32 v[106:107], v[90:91], v[156:157], v[88:89] op_sel_hi:[1,1,0]
	v_sub_f32_e32 v92, v96, v98
	v_mov_b32_e32 v94, v102
	v_mov_b32_e32 v88, v104
	v_mov_b32_e32 v90, v100
	v_mov_b32_e32 v91, v106
.LBB0_369:
	s_or_b64 exec, exec, s[24:25]
	v_lshrrev_b32_e32 v96, 18, v221
	v_add_u32_e32 v96, v220, v96
	v_ashrrev_i32_e32 v97, 14, v96
	s_mov_b32 s0, 0x3dd53b94
	v_lshlrev_b32_e32 v98, 3, v97
	v_pk_mul_f32 v[92:93], v[92:93], s[0:1] op_sel_hi:[1,0]
	v_mul_i32_i24_e32 v96, 0x4000, v97
	v_pk_mul_f32 v[100:101], v[88:89], s[0:1] op_sel_hi:[1,0]
	v_cvt_pk_bf16_f32 v88, v92, v93
	v_add_u32_e32 v92, v98, v233
	v_sub_u32_e32 v96, v220, v96
	v_ashrrev_i32_e32 v93, 31, v92
	v_ashrrev_i32_e32 v97, 31, v96
	v_pk_mul_f32 v[94:95], v[94:95], s[0:1] op_sel_hi:[1,0]
	v_lshlrev_b64 v[92:93], 14, v[92:93]
	v_pk_mul_f32 v[102:103], v[90:91], s[0:1] op_sel_hi:[1,0]
	v_cvt_pk_bf16_f32 v89, v94, v95
	v_lshl_add_u64 v[92:93], v[92:93], 0, v[96:97]
	v_mov_b64_e32 v[94:95], s[10:11]
	s_movk_i32 s0, 0x180
	v_mad_u64_u32 v[94:95], s[24:25], v92, s0, v[94:95]
	v_mad_i32_i24 v95, v93, s0, v95
	v_cvt_pk_bf16_f32 v90, v100, v101
	v_cvt_pk_bf16_f32 v91, v102, v103
	v_lshl_add_u64 v[92:93], v[210:211], 1, v[94:95]
	global_store_dwordx4 v[92:93], v[88:91], off
	s_and_saveexec_b64 s[24:25], vcc
	s_cbranch_execz .LBB0_371
	s_waitcnt vmcnt(0) lgkmcnt(0)
	v_pk_mul_f32 v[92:93], v[86:87], v[150:151] op_sel:[1,1] op_sel_hi:[0,1]
	v_pk_fma_f32 v[94:95], v[86:87], v[146:147], v[92:93] op_sel:[0,1,0] neg_lo:[0,0,1] neg_hi:[0,0,1]
	v_pk_fma_f32 v[86:87], v[86:87], v[146:147], v[92:93] op_sel:[0,1,0]
	v_pk_mul_f32 v[92:93], v[80:81], v[152:153] op_sel:[1,0] op_sel_hi:[0,0]
	v_pk_fma_f32 v[100:101], v[80:81], v[148:149], v[92:93] op_sel_hi:[1,0,1] neg_lo:[0,0,1] neg_hi:[0,0,1]
	v_pk_fma_f32 v[80:81], v[80:81], v[148:149], v[92:93] op_sel_hi:[1,0,1]
	v_mov_b32_e32 v152, v149
	v_mul_f32_e32 v80, v83, v153
	v_pk_mul_f32 v[90:91], v[84:85], v[150:151] op_sel:[1,0] op_sel_hi:[0,0]
	v_pk_fma_f32 v[92:93], v[82:83], v[152:153], v[80:81] op_sel_hi:[1,1,0] neg_lo:[0,0,1] neg_hi:[0,0,1]
	v_mov_b32_e32 v148, v153
	v_mul_f32_e32 v80, v83, v149
	v_pk_mul_f32 v[88:89], v[84:85], v[146:147]
	v_pk_fma_f32 v[84:85], v[84:85], v[146:147], v[90:91] op_sel_hi:[1,0,1]
	v_pk_fma_f32 v[102:103], v[82:83], v[148:149], v[80:81] op_sel_hi:[1,1,0]
	v_sub_f32_e32 v84, v88, v90
	v_mov_b32_e32 v86, v94
	v_mov_b32_e32 v80, v100
	v_mov_b32_e32 v82, v92
	v_mov_b32_e32 v83, v102
; __device__ __forceinline__ unsigned cvt_pk_bf16(float lo, float hi) { f32x2 v = {lo, hi}; bf16x2_t b = __builtin_convertvector(v, bf16x2_t); return __builtin_bit_cast(unsigned, b); }
;     __device__ __forceinline__ void operator()(const f32x4 (&acc)[2][2][4][2], const Unit& u, int wr, int wc, int fr, int fq) const {
;     ...
;             for (int m = 0; m < 4; ++m) { const int row = row0 + ai * HALF + m * 16, b = row / T, t = row % T;
; #pragma unroll
;                 for (int bj = 0; bj < 2; ++bj) { const int c = u.pn * BM + bj * HALF + wc * 32 + 8 * fq, hh = c / 192, e = c % 192;
;                     const f32x4 v0 = acc[ai][bj][m][0], v1 = acc[ai][bj][m][1];
;                     float vals[8] = {v0[0], v0[1], v0[2], v0[3], v1[0], v1[1], v1[2], v1[3]};
;                     if (e >= 128) { const f32x4 cc = ccv[m][bj], ss = ssv[m][bj];
; #pragma unroll
;                         for (int p = 0; p < 4; ++p) { const float x1 = vals[2 * p], x2 = vals[2 * p + 1]; vals[2 * p] = x1 * cc[p] - x2 * ss[p]; vals[2 * p + 1] = x2 * cc[p] + x1 * ss[p]; } }
;                     constexpr float QS = 0.07216878364870322f * 1.4426950408889634f;
; #pragma unroll
;                     for (int p_ = 0; p_ < 8; ++p_) vals[p_] *= QS;
;                     u32x4 w; w.x = cvt_pk_bf16(vals[0], vals[1]); w.y = cvt_pk_bf16(vals[2], vals[3]); w.z = cvt_pk_bf16(vals[4], vals[5]); w.w = cvt_pk_bf16(vals[6], vals[7]);
;                     *(u32x4*)(Q + ((size_t)(b * 8 + hh) * T + t) * 192 + e) = w; } } }
.LBB0_371:
	s_or_b64 exec, exec, s[24:25]
	s_mov_b32 s0, 0x3dd53b94
	v_pk_mul_f32 v[84:85], v[84:85], s[0:1] op_sel_hi:[1,0]
	v_pk_mul_f32 v[88:89], v[80:81], s[0:1] op_sel_hi:[1,0]
	v_cvt_pk_bf16_f32 v80, v84, v85
	v_add_u32_e32 v84, v98, v232
	v_ashrrev_i32_e32 v85, 31, v84
	v_pk_mul_f32 v[86:87], v[86:87], s[0:1] op_sel_hi:[1,0]
	v_lshlrev_b64 v[84:85], 14, v[84:85]
	v_pk_mul_f32 v[90:91], v[82:83], s[0:1] op_sel_hi:[1,0]
	v_cvt_pk_bf16_f32 v81, v86, v87
	v_lshl_add_u64 v[84:85], v[84:85], 0, v[96:97]
	v_mov_b64_e32 v[86:87], s[10:11]
	s_movk_i32 s0, 0x180
	v_mad_u64_u32 v[86:87], s[24:25], v84, s0, v[86:87]
	v_mad_i32_i24 v87, v85, s0, v87
	v_cvt_pk_bf16_f32 v82, v88, v89
	v_cvt_pk_bf16_f32 v83, v90, v91
	v_lshl_add_u64 v[84:85], v[208:209], 1, v[86:87]
	global_store_dwordx4 v[84:85], v[80:83], off
	s_and_saveexec_b64 s[24:25], s[6:7]
	s_cbranch_execz .LBB0_373
	s_waitcnt vmcnt(0) lgkmcnt(0)
	v_pk_mul_f32 v[84:85], v[78:79], v[142:143] op_sel:[1,1] op_sel_hi:[0,1]
	v_pk_fma_f32 v[86:87], v[78:79], v[138:139], v[84:85] op_sel:[0,1,0] neg_lo:[0,0,1] neg_hi:[0,0,1]
	v_pk_fma_f32 v[78:79], v[78:79], v[138:139], v[84:85] op_sel:[0,1,0]
	v_pk_mul_f32 v[84:85], v[72:73], v[144:145] op_sel:[1,0] op_sel_hi:[0,0]
	v_pk_fma_f32 v[88:89], v[72:73], v[140:141], v[84:85] op_sel_hi:[1,0,1] neg_lo:[0,0,1] neg_hi:[0,0,1]
	v_pk_fma_f32 v[72:73], v[72:73], v[140:141], v[84:85] op_sel_hi:[1,0,1]
	v_mov_b32_e32 v144, v141
	v_mul_f32_e32 v72, v75, v145
	v_pk_mul_f32 v[82:83], v[76:77], v[142:143] op_sel:[1,0] op_sel_hi:[0,0]
	v_pk_fma_f32 v[84:85], v[74:75], v[144:145], v[72:73] op_sel_hi:[1,1,0] neg_lo:[0,0,1] neg_hi:[0,0,1]
	v_mov_b32_e32 v140, v145
	v_mul_f32_e32 v72, v75, v141
	v_pk_mul_f32 v[80:81], v[76:77], v[138:139]
	v_pk_fma_f32 v[76:77], v[76:77], v[138:139], v[82:83] op_sel_hi:[1,0,1]
	v_pk_fma_f32 v[90:91], v[74:75], v[140:141], v[72:73] op_sel_hi:[1,1,0]
	v_sub_f32_e32 v76, v80, v82
	v_mov_b32_e32 v78, v86
	v_mov_b32_e32 v72, v88
	v_mov_b32_e32 v74, v84
	v_mov_b32_e32 v75, v90
.LBB0_373:
	s_or_b64 exec, exec, s[24:25]
	v_lshrrev_b32_e32 v80, 18, v219
	v_add_u32_e32 v80, v218, v80
	v_ashrrev_i32_e32 v81, 14, v80
	s_mov_b32 s0, 0x3dd53b94
	v_lshlrev_b32_e32 v82, 3, v81
	v_pk_mul_f32 v[76:77], v[76:77], s[0:1] op_sel_hi:[1,0]
	v_mul_i32_i24_e32 v80, 0x4000, v81
	v_pk_mul_f32 v[84:85], v[72:73], s[0:1] op_sel_hi:[1,0]
	v_cvt_pk_bf16_f32 v72, v76, v77
	v_add_u32_e32 v76, v82, v233
	v_sub_u32_e32 v80, v218, v80
	v_ashrrev_i32_e32 v77, 31, v76
	v_ashrrev_i32_e32 v81, 31, v80
	v_pk_mul_f32 v[78:79], v[78:79], s[0:1] op_sel_hi:[1,0]
	v_lshlrev_b64 v[76:77], 14, v[76:77]
	v_pk_mul_f32 v[86:87], v[74:75], s[0:1] op_sel_hi:[1,0]
	v_cvt_pk_bf16_f32 v73, v78, v79
	v_lshl_add_u64 v[76:77], v[76:77], 0, v[80:81]
	v_mov_b64_e32 v[78:79], s[10:11]
	s_movk_i32 s0, 0x180
	v_mad_u64_u32 v[78:79], s[24:25], v76, s0, v[78:79]
	v_mad_i32_i24 v79, v77, s0, v79
	v_cvt_pk_bf16_f32 v74, v84, v85
	v_cvt_pk_bf16_f32 v75, v86, v87
	v_lshl_add_u64 v[76:77], v[210:211], 1, v[78:79]
	global_store_dwordx4 v[76:77], v[72:75], off
	s_and_saveexec_b64 s[24:25], vcc
	s_cbranch_execz .LBB0_375
	s_waitcnt vmcnt(0) lgkmcnt(0)
	v_pk_mul_f32 v[76:77], v[70:71], v[126:127] op_sel:[1,1] op_sel_hi:[0,1]
	v_pk_fma_f32 v[78:79], v[70:71], v[122:123], v[76:77] op_sel:[0,1,0] neg_lo:[0,0,1] neg_hi:[0,0,1]
	v_pk_fma_f32 v[70:71], v[70:71], v[122:123], v[76:77] op_sel:[0,1,0]
	v_pk_mul_f32 v[76:77], v[64:65], v[128:129] op_sel:[1,0] op_sel_hi:[0,0]
	v_pk_fma_f32 v[84:85], v[64:65], v[124:125], v[76:77] op_sel_hi:[1,0,1] neg_lo:[0,0,1] neg_hi:[0,0,1]
	v_pk_fma_f32 v[64:65], v[64:65], v[124:125], v[76:77] op_sel_hi:[1,0,1]
	v_mov_b32_e32 v128, v125
	v_mul_f32_e32 v64, v67, v129
	v_pk_mul_f32 v[74:75], v[68:69], v[126:127] op_sel:[1,0] op_sel_hi:[0,0]
	v_pk_fma_f32 v[76:77], v[66:67], v[128:129], v[64:65] op_sel_hi:[1,1,0] neg_lo:[0,0,1] neg_hi:[0,0,1]
	v_mov_b32_e32 v124, v129
	v_mul_f32_e32 v64, v67, v125
	v_pk_mul_f32 v[72:73], v[68:69], v[122:123]
	v_pk_fma_f32 v[68:69], v[68:69], v[122:123], v[74:75] op_sel_hi:[1,0,1]
	v_pk_fma_f32 v[86:87], v[66:67], v[124:125], v[64:65] op_sel_hi:[1,1,0]
	v_sub_f32_e32 v68, v72, v74
	v_mov_b32_e32 v70, v78
	v_mov_b32_e32 v64, v84
	v_mov_b32_e32 v66, v76
	v_mov_b32_e32 v67, v86
; __device__ __forceinline__ unsigned cvt_pk_bf16(float lo, float hi) { f32x2 v = {lo, hi}; bf16x2_t b = __builtin_convertvector(v, bf16x2_t); return __builtin_bit_cast(unsigned, b); }
;     __device__ __forceinline__ void operator()(const f32x4 (&acc)[2][2][4][2], const Unit& u, int wr, int wc, int fr, int fq) const {
;     ...
;                 for (int bj = 0; bj < 2; ++bj) { const int row = row0 + ai * HALF + m * 16, e = (u.pn * BM + bj * HALF + wc * 32 + 8 * fq) % 192, i0 = e >= 128 ? (e - 128) >> 1 : 0;
;                     ccv[m][bj] = *(const f32x4*)(cs + (size_t)row * 32 + i0); ssv[m][bj] = *(const f32x4*)(sn + (size_t)row * 32 + i0); }
; #pragma unroll
;             for (int m = 0; m < 4; ++m) { const int row = row0 + ai * HALF + m * 16, b = row / T, t = row % T;
; #pragma unroll
;                 for (int bj = 0; bj < 2; ++bj) { const int c = u.pn * BM + bj * HALF + wc * 32 + 8 * fq, hh = c / 192, e = c % 192;
;                     const f32x4 v0 = acc[ai][bj][m][0], v1 = acc[ai][bj][m][1];
;                     float vals[8] = {v0[0], v0[1], v0[2], v0[3], v1[0], v1[1], v1[2], v1[3]};
;                     if (e >= 128) { const f32x4 cc = ccv[m][bj], ss = ssv[m][bj];
; #pragma unroll
;                         for (int p = 0; p < 4; ++p) { const float x1 = vals[2 * p], x2 = vals[2 * p + 1]; vals[2 * p] = x1 * cc[p] - x2 * ss[p]; vals[2 * p + 1] = x2 * cc[p] + x1 * ss[p]; } }
;                     constexpr float QS = 0.07216878364870322f * 1.4426950408889634f;
; #pragma unroll
;                     for (int p_ = 0; p_ < 8; ++p_) vals[p_] *= QS;
;                     u32x4 w; w.x = cvt_pk_bf16(vals[0], vals[1]); w.y = cvt_pk_bf16(vals[2], vals[3]); w.z = cvt_pk_bf16(vals[4], vals[5]); w.w = cvt_pk_bf16(vals[6], vals[7]);
;                     *(u32x4*)(Q + ((size_t)(b * 8 + hh) * T + t) * 192 + e) = w; } } }
.LBB0_375:
	s_or_b64 exec, exec, s[24:25]
	s_mov_b32 s0, 0x3dd53b94
	v_pk_mul_f32 v[68:69], v[68:69], s[0:1] op_sel_hi:[1,0]
	v_pk_mul_f32 v[72:73], v[64:65], s[0:1] op_sel_hi:[1,0]
	v_cvt_pk_bf16_f32 v64, v68, v69
	v_add_u32_e32 v68, v82, v232
	v_ashrrev_i32_e32 v69, 31, v68
	v_pk_mul_f32 v[70:71], v[70:71], s[0:1] op_sel_hi:[1,0]
	v_lshlrev_b64 v[68:69], 14, v[68:69]
	v_pk_mul_f32 v[74:75], v[66:67], s[0:1] op_sel_hi:[1,0]
	v_cvt_pk_bf16_f32 v65, v70, v71
	v_lshl_add_u64 v[68:69], v[68:69], 0, v[80:81]
	v_mov_b64_e32 v[70:71], s[10:11]
	s_movk_i32 s0, 0x180
	v_mad_u64_u32 v[70:71], s[24:25], v68, s0, v[70:71]
	v_mad_i32_i24 v71, v69, s0, v71
	s_waitcnt vmcnt(0) lgkmcnt(0)
	v_add_u32_e32 v128, 0x80, v212
	v_cvt_pk_bf16_f32 v66, v72, v73
	v_cvt_pk_bf16_f32 v67, v74, v75
	v_lshl_add_u64 v[68:69], v[208:209], 1, v[70:71]
	v_ashrrev_i32_e32 v129, 31, v128
	global_store_dwordx4 v[68:69], v[64:67], off
	v_add_u32_e32 v126, 0x90, v212
	v_ashrrev_i32_e32 v127, 31, v126
	v_lshlrev_b64 v[64:65], 7, v[128:129]
	v_lshl_add_u64 v[130:131], s[12:13], 0, v[64:65]
	v_lshl_add_u64 v[132:133], s[14:15], 0, v[64:65]
	v_lshl_add_u64 v[64:65], v[130:131], 0, v[216:217]
	global_load_dwordx4 v[114:117], v[64:65], off
	v_lshl_add_u64 v[64:65], v[132:133], 0, v[216:217]
	global_load_dwordx4 v[118:121], v[64:65], off
	v_lshlrev_b64 v[64:65], 7, v[126:127]
	v_lshl_add_u64 v[66:67], s[12:13], 0, v[64:65]
	v_lshl_add_u64 v[64:65], s[14:15], 0, v[64:65]
	v_lshl_add_u64 v[68:69], v[66:67], 0, v[214:215]
	v_lshl_add_u64 v[66:67], v[66:67], 0, v[216:217]
	v_add_u32_e32 v124, 0xa0, v212
	global_load_dwordx4 v[104:107], v[68:69], off
	global_load_dwordx4 v[96:99], v[66:67], off
	v_lshl_add_u64 v[68:69], v[64:65], 0, v[214:215]
	v_lshl_add_u64 v[64:65], v[64:65], 0, v[216:217]
	v_ashrrev_i32_e32 v125, 31, v124
	global_load_dwordx4 v[100:103], v[64:65], off
	v_lshlrev_b64 v[64:65], 7, v[124:125]
	v_lshl_add_u64 v[66:67], s[12:13], 0, v[64:65]
	global_load_dwordx4 v[108:111], v[68:69], off
	v_lshl_add_u64 v[64:65], s[14:15], 0, v[64:65]
	v_lshl_add_u64 v[68:69], v[66:67], 0, v[214:215]
	v_lshl_add_u64 v[66:67], v[66:67], 0, v[216:217]
	v_add_u32_e32 v122, 0xb0, v212
	global_load_dwordx4 v[88:91], v[68:69], off
	global_load_dwordx4 v[80:83], v[66:67], off
	v_lshl_add_u64 v[68:69], v[64:65], 0, v[214:215]
	v_lshl_add_u64 v[64:65], v[64:65], 0, v[216:217]
	v_ashrrev_i32_e32 v123, 31, v122
	global_load_dwordx4 v[84:87], v[64:65], off
	v_lshlrev_b64 v[64:65], 7, v[122:123]
	v_lshl_add_u64 v[66:67], s[12:13], 0, v[64:65]
	global_load_dwordx4 v[92:95], v[68:69], off
	v_lshl_add_u64 v[68:69], s[14:15], 0, v[64:65]
	v_lshl_add_u64 v[64:65], v[66:67], 0, v[214:215]
	global_load_dwordx4 v[72:75], v[64:65], off
	v_lshl_add_u64 v[64:65], v[68:69], 0, v[214:215]
	v_lshl_add_u64 v[68:69], v[68:69], 0, v[216:217]
	global_load_dwordx4 v[76:79], v[64:65], off
	s_nop 0
	global_load_dwordx4 v[68:71], v[68:69], off
	v_lshl_add_u64 v[64:65], v[66:67], 0, v[216:217]
	global_load_dwordx4 v[64:67], v[64:65], off
	s_and_saveexec_b64 s[24:25], s[6:7]
	s_cbranch_execz .LBB0_377
	v_lshl_add_u64 v[132:133], v[132:133], 0, v[214:215]
	global_load_dwordx4 v[132:135], v[132:133], off
	v_lshl_add_u64 v[130:131], v[130:131], 0, v[214:215]
	global_load_dwordx4 v[136:139], v[130:131], off
	s_waitcnt vmcnt(0) lgkmcnt(0)
	v_pk_mul_f32 v[140:141], v[60:61], v[132:133] op_sel:[1,0] op_sel_hi:[0,0]
	v_pk_mul_f32 v[132:133], v[62:63], v[132:133] op_sel:[1,1] op_sel_hi:[0,1]
	v_pk_fma_f32 v[142:143], v[62:63], v[136:137], v[132:133] op_sel:[0,1,0] neg_lo:[0,0,1] neg_hi:[0,0,1]
	v_pk_fma_f32 v[62:63], v[62:63], v[136:137], v[132:133] op_sel:[0,1,0]
	v_pk_mul_f32 v[132:133], v[56:57], v[134:135] op_sel:[1,0] op_sel_hi:[0,0]
	v_pk_mul_f32 v[130:131], v[60:61], v[136:137]
	v_pk_fma_f32 v[60:61], v[60:61], v[136:137], v[140:141] op_sel_hi:[1,0,1]
	v_pk_fma_f32 v[136:137], v[56:57], v[138:139], v[132:133] op_sel_hi:[1,0,1] neg_lo:[0,0,1] neg_hi:[0,0,1]
	v_pk_fma_f32 v[56:57], v[56:57], v[138:139], v[132:133] op_sel_hi:[1,0,1]
	v_mov_b32_e32 v134, v139
	v_mul_f32_e32 v56, v59, v135
	v_pk_fma_f32 v[132:133], v[58:59], v[134:135], v[56:57] op_sel_hi:[1,1,0] neg_lo:[0,0,1] neg_hi:[0,0,1]
	v_mov_b32_e32 v138, v135
	v_mul_f32_e32 v56, v59, v139
	v_pk_fma_f32 v[134:135], v[58:59], v[138:139], v[56:57] op_sel_hi:[1,1,0]
	v_sub_f32_e32 v60, v130, v140
	v_mov_b32_e32 v62, v142
	v_mov_b32_e32 v56, v136
	v_mov_b32_e32 v58, v132
	v_mov_b32_e32 v59, v134
.LBB0_377:
	s_or_b64 exec, exec, s[24:25]
	v_lshrrev_b32_e32 v129, 18, v129
	v_add_u32_e32 v129, v128, v129
	v_ashrrev_i32_e32 v129, 14, v129
	v_mul_i32_i24_e32 v130, 0x4000, v129
	s_mov_b32 s0, 0x3dd53b94
	v_sub_u32_e32 v128, v128, v130
	v_lshlrev_b32_e32 v130, 3, v129
	v_pk_mul_f32 v[60:61], v[60:61], s[0:1] op_sel_hi:[1,0]
	v_pk_mul_f32 v[132:133], v[56:57], s[0:1] op_sel_hi:[1,0]
	v_cvt_pk_bf16_f32 v56, v60, v61
	v_add_u32_e32 v60, v130, v233
	v_ashrrev_i32_e32 v61, 31, v60
	v_ashrrev_i32_e32 v129, 31, v128
	v_pk_mul_f32 v[62:63], v[62:63], s[0:1] op_sel_hi:[1,0]
	v_lshlrev_b64 v[60:61], 14, v[60:61]
	v_pk_mul_f32 v[134:135], v[58:59], s[0:1] op_sel_hi:[1,0]
	v_cvt_pk_bf16_f32 v57, v62, v63
	v_lshl_add_u64 v[60:61], v[60:61], 0, v[128:129]
	v_mov_b64_e32 v[62:63], s[10:11]
	s_movk_i32 s0, 0x180
	v_mad_u64_u32 v[62:63], s[24:25], v60, s0, v[62:63]
	v_mad_i32_i24 v63, v61, s0, v63
	v_cvt_pk_bf16_f32 v58, v132, v133
	v_cvt_pk_bf16_f32 v59, v134, v135
	v_lshl_add_u64 v[60:61], v[210:211], 1, v[62:63]
	global_store_dwordx4 v[60:61], v[56:59], off
	s_and_saveexec_b64 s[24:25], vcc
	s_cbranch_execz .LBB0_379
	s_waitcnt vmcnt(0) lgkmcnt(0)
	v_pk_mul_f32 v[60:61], v[54:55], v[118:119] op_sel:[1,1] op_sel_hi:[0,1]
	v_pk_mul_f32 v[58:59], v[52:53], v[118:119] op_sel:[1,0] op_sel_hi:[0,0]
	v_pk_fma_f32 v[62:63], v[54:55], v[114:115], v[60:61] op_sel:[0,1,0] neg_lo:[0,0,1] neg_hi:[0,0,1]
	v_pk_fma_f32 v[54:55], v[54:55], v[114:115], v[60:61] op_sel:[0,1,0]
	v_pk_mul_f32 v[60:61], v[48:49], v[120:121] op_sel:[1,0] op_sel_hi:[0,0]
	v_pk_mul_f32 v[56:57], v[52:53], v[114:115]
	v_pk_fma_f32 v[52:53], v[52:53], v[114:115], v[58:59] op_sel_hi:[1,0,1]
	v_pk_fma_f32 v[114:115], v[48:49], v[116:117], v[60:61] op_sel_hi:[1,0,1] neg_lo:[0,0,1] neg_hi:[0,0,1]
	v_pk_fma_f32 v[48:49], v[48:49], v[116:117], v[60:61] op_sel_hi:[1,0,1]
	v_mov_b32_e32 v120, v117
	v_mul_f32_e32 v48, v51, v121
	v_pk_fma_f32 v[60:61], v[50:51], v[120:121], v[48:49] op_sel_hi:[1,1,0] neg_lo:[0,0,1] neg_hi:[0,0,1]
	v_mov_b32_e32 v116, v121
	v_mul_f32_e32 v48, v51, v117
	v_pk_fma_f32 v[116:117], v[50:51], v[116:117], v[48:49] op_sel_hi:[1,1,0]
	v_sub_f32_e32 v52, v56, v58
	v_mov_b32_e32 v54, v62
	v_mov_b32_e32 v48, v114
	v_mov_b32_e32 v50, v60
	v_mov_b32_e32 v51, v116
; __device__ __forceinline__ unsigned cvt_pk_bf16(float lo, float hi) { f32x2 v = {lo, hi}; bf16x2_t b = __builtin_convertvector(v, bf16x2_t); return __builtin_bit_cast(unsigned, b); }
;     __device__ __forceinline__ void operator()(const f32x4 (&acc)[2][2][4][2], const Unit& u, int wr, int wc, int fr, int fq) const {
;     ...
;             for (int m = 0; m < 4; ++m) { const int row = row0 + ai * HALF + m * 16, b = row / T, t = row % T;
; #pragma unroll
;                 for (int bj = 0; bj < 2; ++bj) { const int c = u.pn * BM + bj * HALF + wc * 32 + 8 * fq, hh = c / 192, e = c % 192;
;                     const f32x4 v0 = acc[ai][bj][m][0], v1 = acc[ai][bj][m][1];
;                     float vals[8] = {v0[0], v0[1], v0[2], v0[3], v1[0], v1[1], v1[2], v1[3]};
;                     if (e >= 128) { const f32x4 cc = ccv[m][bj], ss = ssv[m][bj];
; #pragma unroll
;                         for (int p = 0; p < 4; ++p) { const float x1 = vals[2 * p], x2 = vals[2 * p + 1]; vals[2 * p] = x1 * cc[p] - x2 * ss[p]; vals[2 * p + 1] = x2 * cc[p] + x1 * ss[p]; } }
;                     constexpr float QS = 0.07216878364870322f * 1.4426950408889634f;
; #pragma unroll
;                     for (int p_ = 0; p_ < 8; ++p_) vals[p_] *= QS;
;                     u32x4 w; w.x = cvt_pk_bf16(vals[0], vals[1]); w.y = cvt_pk_bf16(vals[2], vals[3]); w.z = cvt_pk_bf16(vals[4], vals[5]); w.w = cvt_pk_bf16(vals[6], vals[7]);
;                     *(u32x4*)(Q + ((size_t)(b * 8 + hh) * T + t) * 192 + e) = w; } } }
.LBB0_379:
	s_or_b64 exec, exec, s[24:25]
	s_mov_b32 s0, 0x3dd53b94
	v_pk_mul_f32 v[52:53], v[52:53], s[0:1] op_sel_hi:[1,0]
	v_pk_mul_f32 v[56:57], v[48:49], s[0:1] op_sel_hi:[1,0]
	v_cvt_pk_bf16_f32 v48, v52, v53
	v_add_u32_e32 v52, v130, v232
	v_ashrrev_i32_e32 v53, 31, v52
	v_pk_mul_f32 v[54:55], v[54:55], s[0:1] op_sel_hi:[1,0]
	v_lshlrev_b64 v[52:53], 14, v[52:53]
	v_pk_mul_f32 v[58:59], v[50:51], s[0:1] op_sel_hi:[1,0]
	v_cvt_pk_bf16_f32 v49, v54, v55
	v_lshl_add_u64 v[52:53], v[52:53], 0, v[128:129]
	v_mov_b64_e32 v[54:55], s[10:11]
	s_movk_i32 s0, 0x180
	v_mad_u64_u32 v[54:55], s[24:25], v52, s0, v[54:55]
	v_mad_i32_i24 v55, v53, s0, v55
	v_cvt_pk_bf16_f32 v50, v56, v57
	v_cvt_pk_bf16_f32 v51, v58, v59
	v_lshl_add_u64 v[52:53], v[208:209], 1, v[54:55]
	global_store_dwordx4 v[52:53], v[48:51], off
	s_and_saveexec_b64 s[24:25], s[6:7]
	s_cbranch_execz .LBB0_381
	s_waitcnt vmcnt(0) lgkmcnt(0)
	v_pk_mul_f32 v[52:53], v[46:47], v[108:109] op_sel:[1,1] op_sel_hi:[0,1]
	v_pk_fma_f32 v[54:55], v[46:47], v[104:105], v[52:53] op_sel:[0,1,0] neg_lo:[0,0,1] neg_hi:[0,0,1]
	v_pk_fma_f32 v[46:47], v[46:47], v[104:105], v[52:53] op_sel:[0,1,0]
	v_pk_mul_f32 v[52:53], v[40:41], v[110:111] op_sel:[1,0] op_sel_hi:[0,0]
	v_pk_fma_f32 v[56:57], v[40:41], v[106:107], v[52:53] op_sel_hi:[1,0,1] neg_lo:[0,0,1] neg_hi:[0,0,1]
	v_pk_fma_f32 v[40:41], v[40:41], v[106:107], v[52:53] op_sel_hi:[1,0,1]
	v_mov_b32_e32 v110, v107
	v_mul_f32_e32 v40, v43, v111
	v_pk_mul_f32 v[50:51], v[44:45], v[108:109] op_sel:[1,0] op_sel_hi:[0,0]
	v_pk_fma_f32 v[52:53], v[42:43], v[110:111], v[40:41] op_sel_hi:[1,1,0] neg_lo:[0,0,1] neg_hi:[0,0,1]
	v_mov_b32_e32 v106, v111
	v_mul_f32_e32 v40, v43, v107
	v_pk_mul_f32 v[48:49], v[44:45], v[104:105]
	v_pk_fma_f32 v[44:45], v[44:45], v[104:105], v[50:51] op_sel_hi:[1,0,1]
	v_pk_fma_f32 v[58:59], v[42:43], v[106:107], v[40:41] op_sel_hi:[1,1,0]
	v_sub_f32_e32 v44, v48, v50
	v_mov_b32_e32 v46, v54
	v_mov_b32_e32 v40, v56
	v_mov_b32_e32 v42, v52
	v_mov_b32_e32 v43, v58
.LBB0_381:
	s_or_b64 exec, exec, s[24:25]
	v_lshrrev_b32_e32 v48, 18, v127
	v_add_u32_e32 v48, v126, v48
	v_ashrrev_i32_e32 v49, 14, v48
	s_mov_b32 s0, 0x3dd53b94
	v_lshlrev_b32_e32 v50, 3, v49
	v_pk_mul_f32 v[44:45], v[44:45], s[0:1] op_sel_hi:[1,0]
	v_mul_i32_i24_e32 v48, 0x4000, v49
	v_pk_mul_f32 v[52:53], v[40:41], s[0:1] op_sel_hi:[1,0]
	v_cvt_pk_bf16_f32 v40, v44, v45
	v_add_u32_e32 v44, v50, v233
	v_sub_u32_e32 v48, v126, v48
	v_ashrrev_i32_e32 v45, 31, v44
	v_ashrrev_i32_e32 v49, 31, v48
	v_pk_mul_f32 v[46:47], v[46:47], s[0:1] op_sel_hi:[1,0]
	v_lshlrev_b64 v[44:45], 14, v[44:45]
	v_pk_mul_f32 v[54:55], v[42:43], s[0:1] op_sel_hi:[1,0]
	v_cvt_pk_bf16_f32 v41, v46, v47
	v_lshl_add_u64 v[44:45], v[44:45], 0, v[48:49]
	v_mov_b64_e32 v[46:47], s[10:11]
	s_movk_i32 s0, 0x180
	v_mad_u64_u32 v[46:47], s[24:25], v44, s0, v[46:47]
	v_mad_i32_i24 v47, v45, s0, v47
	v_cvt_pk_bf16_f32 v42, v52, v53
	v_cvt_pk_bf16_f32 v43, v54, v55
	v_lshl_add_u64 v[44:45], v[210:211], 1, v[46:47]
	global_store_dwordx4 v[44:45], v[40:43], off
	s_and_saveexec_b64 s[24:25], vcc
	s_cbranch_execz .LBB0_383
	s_waitcnt vmcnt(0) lgkmcnt(0)
	v_pk_mul_f32 v[44:45], v[38:39], v[100:101] op_sel:[1,1] op_sel_hi:[0,1]
	v_pk_fma_f32 v[46:47], v[38:39], v[96:97], v[44:45] op_sel:[0,1,0] neg_lo:[0,0,1] neg_hi:[0,0,1]
	v_pk_fma_f32 v[38:39], v[38:39], v[96:97], v[44:45] op_sel:[0,1,0]
	v_pk_mul_f32 v[44:45], v[32:33], v[102:103] op_sel:[1,0] op_sel_hi:[0,0]
	v_pk_fma_f32 v[52:53], v[32:33], v[98:99], v[44:45] op_sel_hi:[1,0,1] neg_lo:[0,0,1] neg_hi:[0,0,1]
	v_pk_fma_f32 v[32:33], v[32:33], v[98:99], v[44:45] op_sel_hi:[1,0,1]
	v_mov_b32_e32 v102, v99
	v_mul_f32_e32 v32, v35, v103
	v_pk_mul_f32 v[42:43], v[36:37], v[100:101] op_sel:[1,0] op_sel_hi:[0,0]
	v_pk_fma_f32 v[44:45], v[34:35], v[102:103], v[32:33] op_sel_hi:[1,1,0] neg_lo:[0,0,1] neg_hi:[0,0,1]
	v_mov_b32_e32 v98, v103
	v_mul_f32_e32 v32, v35, v99
	v_pk_mul_f32 v[40:41], v[36:37], v[96:97]
	v_pk_fma_f32 v[36:37], v[36:37], v[96:97], v[42:43] op_sel_hi:[1,0,1]
	v_pk_fma_f32 v[54:55], v[34:35], v[98:99], v[32:33] op_sel_hi:[1,1,0]
	v_sub_f32_e32 v36, v40, v42
	v_mov_b32_e32 v38, v46
	v_mov_b32_e32 v32, v52
	v_mov_b32_e32 v34, v44
	v_mov_b32_e32 v35, v54
.LBB0_383:
	s_or_b64 exec, exec, s[24:25]
	s_mov_b32 s0, 0x3dd53b94
	v_pk_mul_f32 v[36:37], v[36:37], s[0:1] op_sel_hi:[1,0]
	v_pk_mul_f32 v[40:41], v[32:33], s[0:1] op_sel_hi:[1,0]
	v_cvt_pk_bf16_f32 v32, v36, v37
	v_add_u32_e32 v36, v50, v232
	v_ashrrev_i32_e32 v37, 31, v36
	v_pk_mul_f32 v[38:39], v[38:39], s[0:1] op_sel_hi:[1,0]
	v_lshlrev_b64 v[36:37], 14, v[36:37]
	v_pk_mul_f32 v[42:43], v[34:35], s[0:1] op_sel_hi:[1,0]
	v_cvt_pk_bf16_f32 v33, v38, v39
	v_lshl_add_u64 v[36:37], v[36:37], 0, v[48:49]
	v_mov_b64_e32 v[38:39], s[10:11]
	s_movk_i32 s0, 0x180
	v_mad_u64_u32 v[38:39], s[24:25], v36, s0, v[38:39]
	v_mad_i32_i24 v39, v37, s0, v39
	v_cvt_pk_bf16_f32 v34, v40, v41
	v_cvt_pk_bf16_f32 v35, v42, v43
	v_lshl_add_u64 v[36:37], v[208:209], 1, v[38:39]
	global_store_dwordx4 v[36:37], v[32:35], off
	s_and_saveexec_b64 s[24:25], s[6:7]
	s_cbranch_execz .LBB0_385
	s_waitcnt vmcnt(0) lgkmcnt(0)
	v_pk_mul_f32 v[36:37], v[30:31], v[92:93] op_sel:[1,1] op_sel_hi:[0,1]
	v_pk_fma_f32 v[38:39], v[30:31], v[88:89], v[36:37] op_sel:[0,1,0] neg_lo:[0,0,1] neg_hi:[0,0,1]
	v_pk_fma_f32 v[30:31], v[30:31], v[88:89], v[36:37] op_sel:[0,1,0]
	v_pk_mul_f32 v[36:37], v[24:25], v[94:95] op_sel:[1,0] op_sel_hi:[0,0]
	v_pk_fma_f32 v[40:41], v[24:25], v[90:91], v[36:37] op_sel_hi:[1,0,1] neg_lo:[0,0,1] neg_hi:[0,0,1]
	v_pk_fma_f32 v[24:25], v[24:25], v[90:91], v[36:37] op_sel_hi:[1,0,1]
	v_mov_b32_e32 v94, v91
	v_mul_f32_e32 v24, v27, v95
	v_pk_mul_f32 v[34:35], v[28:29], v[92:93] op_sel:[1,0] op_sel_hi:[0,0]
	v_pk_fma_f32 v[36:37], v[26:27], v[94:95], v[24:25] op_sel_hi:[1,1,0] neg_lo:[0,0,1] neg_hi:[0,0,1]
	v_mov_b32_e32 v90, v95
	v_mul_f32_e32 v24, v27, v91
	v_pk_mul_f32 v[32:33], v[28:29], v[88:89]
	v_pk_fma_f32 v[28:29], v[28:29], v[88:89], v[34:35] op_sel_hi:[1,0,1]
	v_pk_fma_f32 v[42:43], v[26:27], v[90:91], v[24:25] op_sel_hi:[1,1,0]
	v_sub_f32_e32 v28, v32, v34
	v_mov_b32_e32 v30, v38
	v_mov_b32_e32 v24, v40
	v_mov_b32_e32 v26, v36
	v_mov_b32_e32 v27, v42
; __device__ __forceinline__ unsigned cvt_pk_bf16(float lo, float hi) { f32x2 v = {lo, hi}; bf16x2_t b = __builtin_convertvector(v, bf16x2_t); return __builtin_bit_cast(unsigned, b); }
;     __device__ __forceinline__ void operator()(const f32x4 (&acc)[2][2][4][2], const Unit& u, int wr, int wc, int fr, int fq) const {
;     ...
;             for (int m = 0; m < 4; ++m) { const int row = row0 + ai * HALF + m * 16, b = row / T, t = row % T;
; #pragma unroll
;                 for (int bj = 0; bj < 2; ++bj) { const int c = u.pn * BM + bj * HALF + wc * 32 + 8 * fq, hh = c / 192, e = c % 192;
;                     const f32x4 v0 = acc[ai][bj][m][0], v1 = acc[ai][bj][m][1];
;                     float vals[8] = {v0[0], v0[1], v0[2], v0[3], v1[0], v1[1], v1[2], v1[3]};
;                     if (e >= 128) { const f32x4 cc = ccv[m][bj], ss = ssv[m][bj];
; #pragma unroll
;                         for (int p = 0; p < 4; ++p) { const float x1 = vals[2 * p], x2 = vals[2 * p + 1]; vals[2 * p] = x1 * cc[p] - x2 * ss[p]; vals[2 * p + 1] = x2 * cc[p] + x1 * ss[p]; } }
;                     constexpr float QS = 0.07216878364870322f * 1.4426950408889634f;
; #pragma unroll
;                     for (int p_ = 0; p_ < 8; ++p_) vals[p_] *= QS;
;                     u32x4 w; w.x = cvt_pk_bf16(vals[0], vals[1]); w.y = cvt_pk_bf16(vals[2], vals[3]); w.z = cvt_pk_bf16(vals[4], vals[5]); w.w = cvt_pk_bf16(vals[6], vals[7]);
;                     *(u32x4*)(Q + ((size_t)(b * 8 + hh) * T + t) * 192 + e) = w; } } }
.LBB0_385:
	s_or_b64 exec, exec, s[24:25]
	v_lshrrev_b32_e32 v32, 18, v125
	v_add_u32_e32 v32, v124, v32
	v_ashrrev_i32_e32 v33, 14, v32
	s_mov_b32 s0, 0x3dd53b94
	v_lshlrev_b32_e32 v34, 3, v33
	v_pk_mul_f32 v[28:29], v[28:29], s[0:1] op_sel_hi:[1,0]
	v_mul_i32_i24_e32 v32, 0x4000, v33
	v_pk_mul_f32 v[36:37], v[24:25], s[0:1] op_sel_hi:[1,0]
	v_cvt_pk_bf16_f32 v24, v28, v29
	v_add_u32_e32 v28, v34, v233
	v_sub_u32_e32 v32, v124, v32
	v_ashrrev_i32_e32 v29, 31, v28
	v_ashrrev_i32_e32 v33, 31, v32
	v_pk_mul_f32 v[30:31], v[30:31], s[0:1] op_sel_hi:[1,0]
	v_lshlrev_b64 v[28:29], 14, v[28:29]
	v_pk_mul_f32 v[38:39], v[26:27], s[0:1] op_sel_hi:[1,0]
	v_cvt_pk_bf16_f32 v25, v30, v31
	v_lshl_add_u64 v[28:29], v[28:29], 0, v[32:33]
	v_mov_b64_e32 v[30:31], s[10:11]
	s_movk_i32 s0, 0x180
	v_mad_u64_u32 v[30:31], s[24:25], v28, s0, v[30:31]
	v_mad_i32_i24 v31, v29, s0, v31
	v_cvt_pk_bf16_f32 v26, v36, v37
	v_cvt_pk_bf16_f32 v27, v38, v39
	v_lshl_add_u64 v[28:29], v[210:211], 1, v[30:31]
	global_store_dwordx4 v[28:29], v[24:27], off
	s_and_saveexec_b64 s[24:25], vcc
	s_cbranch_execz .LBB0_387
	s_waitcnt vmcnt(0) lgkmcnt(0)
	v_pk_mul_f32 v[28:29], v[22:23], v[84:85] op_sel:[1,1] op_sel_hi:[0,1]
	v_pk_fma_f32 v[30:31], v[22:23], v[80:81], v[28:29] op_sel:[0,1,0] neg_lo:[0,0,1] neg_hi:[0,0,1]
	v_pk_fma_f32 v[22:23], v[22:23], v[80:81], v[28:29] op_sel:[0,1,0]
	v_pk_mul_f32 v[28:29], v[16:17], v[86:87] op_sel:[1,0] op_sel_hi:[0,0]
	v_pk_fma_f32 v[36:37], v[16:17], v[82:83], v[28:29] op_sel_hi:[1,0,1] neg_lo:[0,0,1] neg_hi:[0,0,1]
	v_pk_fma_f32 v[16:17], v[16:17], v[82:83], v[28:29] op_sel_hi:[1,0,1]
	v_mov_b32_e32 v86, v83
	v_mul_f32_e32 v16, v19, v87
	v_pk_mul_f32 v[26:27], v[20:21], v[84:85] op_sel:[1,0] op_sel_hi:[0,0]
	v_pk_fma_f32 v[28:29], v[18:19], v[86:87], v[16:17] op_sel_hi:[1,1,0] neg_lo:[0,0,1] neg_hi:[0,0,1]
	v_mov_b32_e32 v82, v87
	v_mul_f32_e32 v16, v19, v83
	v_pk_mul_f32 v[24:25], v[20:21], v[80:81]
	v_pk_fma_f32 v[20:21], v[20:21], v[80:81], v[26:27] op_sel_hi:[1,0,1]
	v_pk_fma_f32 v[38:39], v[18:19], v[82:83], v[16:17] op_sel_hi:[1,1,0]
	v_sub_f32_e32 v20, v24, v26
	v_mov_b32_e32 v22, v30
	v_mov_b32_e32 v16, v36
	v_mov_b32_e32 v18, v28
	v_mov_b32_e32 v19, v38
.LBB0_387:
	s_or_b64 exec, exec, s[24:25]
	s_mov_b32 s0, 0x3dd53b94
	v_pk_mul_f32 v[20:21], v[20:21], s[0:1] op_sel_hi:[1,0]
	v_pk_mul_f32 v[24:25], v[16:17], s[0:1] op_sel_hi:[1,0]
	v_cvt_pk_bf16_f32 v16, v20, v21
	v_add_u32_e32 v20, v34, v232
	v_ashrrev_i32_e32 v21, 31, v20
	v_pk_mul_f32 v[22:23], v[22:23], s[0:1] op_sel_hi:[1,0]
	v_lshlrev_b64 v[20:21], 14, v[20:21]
	v_pk_mul_f32 v[26:27], v[18:19], s[0:1] op_sel_hi:[1,0]
	v_cvt_pk_bf16_f32 v17, v22, v23
	v_lshl_add_u64 v[20:21], v[20:21], 0, v[32:33]
	v_mov_b64_e32 v[22:23], s[10:11]
	s_movk_i32 s0, 0x180
	v_mad_u64_u32 v[22:23], s[24:25], v20, s0, v[22:23]
	v_mad_i32_i24 v23, v21, s0, v23
	v_cvt_pk_bf16_f32 v18, v24, v25
	v_cvt_pk_bf16_f32 v19, v26, v27
	v_lshl_add_u64 v[20:21], v[208:209], 1, v[22:23]
	global_store_dwordx4 v[20:21], v[16:19], off
	s_and_saveexec_b64 s[24:25], s[6:7]
	s_cbranch_execz .LBB0_389
	s_waitcnt vmcnt(0) lgkmcnt(0)
	v_pk_mul_f32 v[20:21], v[14:15], v[76:77] op_sel:[1,1] op_sel_hi:[0,1]
	v_pk_fma_f32 v[22:23], v[14:15], v[72:73], v[20:21] op_sel:[0,1,0] neg_lo:[0,0,1] neg_hi:[0,0,1]
	v_pk_fma_f32 v[14:15], v[14:15], v[72:73], v[20:21] op_sel:[0,1,0]
	v_pk_mul_f32 v[20:21], v[8:9], v[78:79] op_sel:[1,0] op_sel_hi:[0,0]
	v_pk_fma_f32 v[24:25], v[8:9], v[74:75], v[20:21] op_sel_hi:[1,0,1] neg_lo:[0,0,1] neg_hi:[0,0,1]
	v_pk_fma_f32 v[8:9], v[8:9], v[74:75], v[20:21] op_sel_hi:[1,0,1]
	v_mov_b32_e32 v78, v75
	v_mul_f32_e32 v8, v11, v79
	v_pk_mul_f32 v[18:19], v[12:13], v[76:77] op_sel:[1,0] op_sel_hi:[0,0]
	v_pk_fma_f32 v[20:21], v[10:11], v[78:79], v[8:9] op_sel_hi:[1,1,0] neg_lo:[0,0,1] neg_hi:[0,0,1]
	v_mov_b32_e32 v74, v79
	v_mul_f32_e32 v8, v11, v75
	v_pk_mul_f32 v[16:17], v[12:13], v[72:73]
	v_pk_fma_f32 v[12:13], v[12:13], v[72:73], v[18:19] op_sel_hi:[1,0,1]
	v_pk_fma_f32 v[26:27], v[10:11], v[74:75], v[8:9] op_sel_hi:[1,1,0]
	v_sub_f32_e32 v12, v16, v18
	v_mov_b32_e32 v14, v22
	v_mov_b32_e32 v8, v24
	v_mov_b32_e32 v10, v20
	v_mov_b32_e32 v11, v26
; __device__ __forceinline__ unsigned cvt_pk_bf16(float lo, float hi) { f32x2 v = {lo, hi}; bf16x2_t b = __builtin_convertvector(v, bf16x2_t); return __builtin_bit_cast(unsigned, b); }
;     __device__ __forceinline__ void operator()(const f32x4 (&acc)[2][2][4][2], const Unit& u, int wr, int wc, int fr, int fq) const {
;     ...
;             for (int m = 0; m < 4; ++m) { const int row = row0 + ai * HALF + m * 16, b = row / T, t = row % T;
; #pragma unroll
;                 for (int bj = 0; bj < 2; ++bj) { const int c = u.pn * BM + bj * HALF + wc * 32 + 8 * fq, hh = c / 192, e = c % 192;
;                     const f32x4 v0 = acc[ai][bj][m][0], v1 = acc[ai][bj][m][1];
;                     float vals[8] = {v0[0], v0[1], v0[2], v0[3], v1[0], v1[1], v1[2], v1[3]};
;                     if (e >= 128) { const f32x4 cc = ccv[m][bj], ss = ssv[m][bj];
; #pragma unroll
;                         for (int p = 0; p < 4; ++p) { const float x1 = vals[2 * p], x2 = vals[2 * p + 1]; vals[2 * p] = x1 * cc[p] - x2 * ss[p]; vals[2 * p + 1] = x2 * cc[p] + x1 * ss[p]; } }
;                     constexpr float QS = 0.07216878364870322f * 1.4426950408889634f;
; #pragma unroll
;                     for (int p_ = 0; p_ < 8; ++p_) vals[p_] *= QS;
;                     u32x4 w; w.x = cvt_pk_bf16(vals[0], vals[1]); w.y = cvt_pk_bf16(vals[2], vals[3]); w.z = cvt_pk_bf16(vals[4], vals[5]); w.w = cvt_pk_bf16(vals[6], vals[7]);
;                     *(u32x4*)(Q + ((size_t)(b * 8 + hh) * T + t) * 192 + e) = w; } } }
.LBB0_389:
	s_or_b64 exec, exec, s[24:25]
	v_lshrrev_b32_e32 v16, 18, v123
	v_add_u32_e32 v16, v122, v16
	v_ashrrev_i32_e32 v17, 14, v16
	s_mov_b32 s0, 0x3dd53b94
	v_lshlrev_b32_e32 v18, 3, v17
	v_pk_mul_f32 v[12:13], v[12:13], s[0:1] op_sel_hi:[1,0]
	v_mul_i32_i24_e32 v16, 0x4000, v17
	v_pk_mul_f32 v[20:21], v[8:9], s[0:1] op_sel_hi:[1,0]
	v_cvt_pk_bf16_f32 v8, v12, v13
	v_add_u32_e32 v12, v18, v233
	v_sub_u32_e32 v16, v122, v16
	v_ashrrev_i32_e32 v13, 31, v12
	v_ashrrev_i32_e32 v17, 31, v16
	v_pk_mul_f32 v[14:15], v[14:15], s[0:1] op_sel_hi:[1,0]
	v_lshlrev_b64 v[12:13], 14, v[12:13]
	v_pk_mul_f32 v[22:23], v[10:11], s[0:1] op_sel_hi:[1,0]
	v_cvt_pk_bf16_f32 v9, v14, v15
	v_lshl_add_u64 v[12:13], v[12:13], 0, v[16:17]
	v_mov_b64_e32 v[14:15], s[10:11]
	s_movk_i32 s0, 0x180
	v_mad_u64_u32 v[14:15], s[6:7], v12, s0, v[14:15]
	v_mad_i32_i24 v15, v13, s0, v15
	v_cvt_pk_bf16_f32 v10, v20, v21
	v_cvt_pk_bf16_f32 v11, v22, v23
	v_lshl_add_u64 v[12:13], v[210:211], 1, v[14:15]
	global_store_dwordx4 v[12:13], v[8:11], off
	s_and_saveexec_b64 s[6:7], vcc
	s_cbranch_execz .LBB0_391
	s_waitcnt vmcnt(0) lgkmcnt(0)
	v_pk_mul_f32 v[12:13], v[6:7], v[68:69] op_sel:[1,1] op_sel_hi:[0,1]
	v_pk_fma_f32 v[14:15], v[6:7], v[64:65], v[12:13] op_sel:[0,1,0] neg_lo:[0,0,1] neg_hi:[0,0,1]
	v_pk_fma_f32 v[6:7], v[6:7], v[64:65], v[12:13] op_sel:[0,1,0]
	v_pk_mul_f32 v[12:13], v[0:1], v[70:71] op_sel:[1,0] op_sel_hi:[0,0]
	v_pk_fma_f32 v[20:21], v[0:1], v[66:67], v[12:13] op_sel_hi:[1,0,1] neg_lo:[0,0,1] neg_hi:[0,0,1]
	v_pk_fma_f32 v[0:1], v[0:1], v[66:67], v[12:13] op_sel_hi:[1,0,1]
	v_mov_b32_e32 v70, v67
	v_mul_f32_e32 v0, v3, v71
	v_pk_mul_f32 v[10:11], v[4:5], v[68:69] op_sel:[1,0] op_sel_hi:[0,0]
	v_pk_fma_f32 v[12:13], v[2:3], v[70:71], v[0:1] op_sel_hi:[1,1,0] neg_lo:[0,0,1] neg_hi:[0,0,1]
	v_mov_b32_e32 v66, v71
	v_mul_f32_e32 v0, v3, v67
	v_pk_mul_f32 v[8:9], v[4:5], v[64:65]
	v_pk_fma_f32 v[4:5], v[4:5], v[64:65], v[10:11] op_sel_hi:[1,0,1]
	v_pk_fma_f32 v[22:23], v[2:3], v[66:67], v[0:1] op_sel_hi:[1,1,0]
	v_sub_f32_e32 v4, v8, v10
	v_mov_b32_e32 v6, v14
	v_mov_b32_e32 v0, v20
	v_mov_b32_e32 v2, v12
	v_mov_b32_e32 v3, v22
.LBB0_391:
	s_or_b64 exec, exec, s[6:7]
	s_mov_b32 s0, 0x3dd53b94
	v_pk_mul_f32 v[4:5], v[4:5], s[0:1] op_sel_hi:[1,0]
	v_pk_mul_f32 v[8:9], v[0:1], s[0:1] op_sel_hi:[1,0]
	v_cvt_pk_bf16_f32 v0, v4, v5
	v_add_u32_e32 v4, v18, v232
	v_ashrrev_i32_e32 v5, 31, v4
	v_pk_mul_f32 v[6:7], v[6:7], s[0:1] op_sel_hi:[1,0]
	v_lshlrev_b64 v[4:5], 14, v[4:5]
	v_pk_mul_f32 v[10:11], v[2:3], s[0:1] op_sel_hi:[1,0]
	v_cvt_pk_bf16_f32 v1, v6, v7
	v_lshl_add_u64 v[4:5], v[4:5], 0, v[16:17]
	v_mov_b64_e32 v[6:7], s[10:11]
	s_movk_i32 s0, 0x180
	v_mad_u64_u32 v[6:7], s[6:7], v4, s0, v[6:7]
	v_mad_i32_i24 v7, v5, s0, v7
	v_cvt_pk_bf16_f32 v2, v8, v9
	v_cvt_pk_bf16_f32 v3, v10, v11
	v_lshl_add_u64 v[4:5], v[208:209], 1, v[6:7]
	s_and_b64 vcc, exec, s[4:5]
	s_mov_b64 s[4:5], -1
	global_store_dwordx4 v[4:5], v[0:3], off
	s_cbranch_vccnz .LBB0_350
	s_andn2_b64 vcc, exec, s[8:9]
	s_cbranch_vccnz .LBB0_349
	s_barrier
	s_branch .LBB0_349

; __device__ __forceinline__ unsigned cvt_pk_bf16(float lo, float hi) { f32x2 v = {lo, hi}; bf16x2_t b = __builtin_convertvector(v, bf16x2_t); return __builtin_bit_cast(unsigned, b); }
;     __device__ __forceinline__ void operator()(const f32x4 (&acc)[2][2][4][2], const Unit& u, int wr, int wc, int fr, int fq) const {
;         const int row0 = u.pm * BM + wr * 64 + fr, e = wc * 32 + 8 * fq;
; #pragma unroll
;         for (int ai = 0; ai < 2; ++ai)
; #pragma unroll
;             for (int m = 0; m < 4; ++m) { const int row = row0 + ai * HALF + m * 16, b = row / T, t = row % T;
;                 const size_t off = ((size_t)(b * 8 + u.pn) * T + t) * 128 + e;
; #pragma unroll
;                 for (int bj = 0; bj < 2; ++bj) { const f32x4 v0 = acc[ai][bj][m][0], v1 = acc[ai][bj][m][1];
;                     u32x4 w; w.x = cvt_pk_bf16(v0[0], v0[1]); w.y = cvt_pk_bf16(v0[2], v0[3]); w.z = cvt_pk_bf16(v1[0], v1[1]); w.w = cvt_pk_bf16(v1[2], v1[3]);
;                     *(u32x4*)((bj ? V : KN) + off) = w; } }
.LBB0_413:
	v_lshl_add_u32 v145, s44, 8, v142
	v_ashrrev_i32_e32 v146, 31, v145
	v_lshrrev_b32_e32 v150, 18, v146
	v_add_u32_e32 v146, v145, v150
	v_ashrrev_i32_e32 v147, 14, v146
	v_mul_i32_i24_e32 v146, 0x4000, v147
	v_lshl_add_u32 v148, v147, 3, s42
	v_sub_u32_e32 v146, v145, v146
	v_ashrrev_i32_e32 v149, 31, v148
	v_ashrrev_i32_e32 v147, 31, v146
	v_lshlrev_b64 v[148:149], 22, v[148:149]
	v_lshlrev_b64 v[146:147], 8, v[146:147]
	v_cvt_pk_bf16_f32 v126, v126, v127
	v_cvt_pk_bf16_f32 v127, v128, v129
	v_cvt_pk_bf16_f32 v128, v122, v123
	v_lshl_add_u64 v[122:123], s[12:13], 0, v[148:149]
	v_cvt_pk_bf16_f32 v118, v118, v119
	v_cvt_pk_bf16_f32 v119, v120, v121
	v_cvt_pk_bf16_f32 v120, v108, v109
	v_lshl_add_u64 v[108:109], s[14:15], 0, v[148:149]
	v_lshl_add_u64 v[122:123], v[122:123], 0, v[146:147]
	v_lshl_add_u64 v[108:109], v[108:109], 0, v[146:147]
	v_cvt_pk_bf16_f32 v129, v124, v125
	v_lshl_add_u64 v[122:123], v[122:123], 0, v[112:113]
	v_cvt_pk_bf16_f32 v121, v110, v111
	v_lshl_add_u64 v[108:109], v[108:109], 0, v[112:113]
	global_store_dwordx4 v[122:123], v[126:129], off
	global_store_dwordx4 v[108:109], v[118:121], off
	v_or_b32_e32 v108, 16, v145
	v_add_u32_e32 v109, v108, v150
	v_ashrrev_i32_e32 v109, 14, v109
	v_mul_i32_i24_e32 v110, 0x4000, v109
	v_sub_u32_e32 v108, v108, v110
	v_lshl_add_u32 v110, v109, 3, s42
	v_ashrrev_i32_e32 v111, 31, v110
	v_ashrrev_i32_e32 v109, 31, v108
	v_lshlrev_b64 v[118:119], 22, v[110:111]
	v_lshlrev_b64 v[120:121], 8, v[108:109]
	v_cvt_pk_bf16_f32 v110, v104, v105
	v_lshl_add_u64 v[104:105], s[12:13], 0, v[118:119]
	v_cvt_pk_bf16_f32 v100, v100, v101
	v_cvt_pk_bf16_f32 v101, v102, v103
	v_cvt_pk_bf16_f32 v102, v92, v93
	v_lshl_add_u64 v[92:93], s[14:15], 0, v[118:119]
	v_lshl_add_u64 v[104:105], v[104:105], 0, v[120:121]
	v_lshl_add_u64 v[92:93], v[92:93], 0, v[120:121]
	v_cvt_pk_bf16_f32 v108, v114, v115
	v_cvt_pk_bf16_f32 v109, v116, v117
	v_cvt_pk_bf16_f32 v111, v106, v107
	v_lshl_add_u64 v[104:105], v[104:105], 0, v[112:113]
	v_cvt_pk_bf16_f32 v103, v94, v95
	v_lshl_add_u64 v[92:93], v[92:93], 0, v[112:113]
	global_store_dwordx4 v[104:105], v[108:111], off
	global_store_dwordx4 v[92:93], v[100:103], off
	v_or_b32_e32 v92, 32, v145
	v_add_u32_e32 v93, v92, v150
	v_ashrrev_i32_e32 v93, 14, v93
	v_mul_i32_i24_e32 v94, 0x4000, v93
	v_sub_u32_e32 v92, v92, v94
	v_lshl_add_u32 v94, v93, 3, s42
	v_ashrrev_i32_e32 v95, 31, v94
	v_ashrrev_i32_e32 v93, 31, v92
	v_lshlrev_b64 v[100:101], 22, v[94:95]
	v_lshlrev_b64 v[102:103], 8, v[92:93]
	v_cvt_pk_bf16_f32 v94, v88, v89
	v_lshl_add_u64 v[88:89], s[12:13], 0, v[100:101]
	v_cvt_pk_bf16_f32 v84, v84, v85
	v_cvt_pk_bf16_f32 v85, v86, v87
	v_cvt_pk_bf16_f32 v86, v76, v77
	v_lshl_add_u64 v[76:77], s[14:15], 0, v[100:101]
	v_lshl_add_u64 v[88:89], v[88:89], 0, v[102:103]
	v_lshl_add_u64 v[76:77], v[76:77], 0, v[102:103]
	v_cvt_pk_bf16_f32 v92, v96, v97
	v_cvt_pk_bf16_f32 v93, v98, v99
	v_cvt_pk_bf16_f32 v95, v90, v91
	v_lshl_add_u64 v[88:89], v[88:89], 0, v[112:113]
	v_cvt_pk_bf16_f32 v87, v78, v79
	v_lshl_add_u64 v[76:77], v[76:77], 0, v[112:113]
	global_store_dwordx4 v[88:89], v[92:95], off
	global_store_dwordx4 v[76:77], v[84:87], off
	v_or_b32_e32 v76, 48, v145
	v_add_u32_e32 v77, v76, v150
	v_ashrrev_i32_e32 v77, 14, v77
	v_mul_i32_i24_e32 v78, 0x4000, v77
	v_sub_u32_e32 v76, v76, v78
	v_lshl_add_u32 v78, v77, 3, s42
	v_ashrrev_i32_e32 v79, 31, v78
	v_ashrrev_i32_e32 v77, 31, v76
	v_lshlrev_b64 v[84:85], 22, v[78:79]
	v_lshlrev_b64 v[86:87], 8, v[76:77]
	v_cvt_pk_bf16_f32 v78, v72, v73
	v_lshl_add_u64 v[72:73], s[12:13], 0, v[84:85]
	v_cvt_pk_bf16_f32 v68, v68, v69
	v_cvt_pk_bf16_f32 v69, v70, v71
	v_cvt_pk_bf16_f32 v70, v64, v65
	v_lshl_add_u64 v[64:65], s[14:15], 0, v[84:85]
	v_lshl_add_u64 v[72:73], v[72:73], 0, v[86:87]
	v_lshl_add_u64 v[64:65], v[64:65], 0, v[86:87]
	v_cvt_pk_bf16_f32 v76, v80, v81
	v_cvt_pk_bf16_f32 v77, v82, v83
	v_cvt_pk_bf16_f32 v79, v74, v75
	v_lshl_add_u64 v[72:73], v[72:73], 0, v[112:113]
	v_cvt_pk_bf16_f32 v71, v66, v67
	v_lshl_add_u64 v[64:65], v[64:65], 0, v[112:113]
	global_store_dwordx4 v[72:73], v[76:79], off
	global_store_dwordx4 v[64:65], v[68:71], off
	v_add_u32_e32 v64, 0x80, v145
	v_ashrrev_i32_e32 v65, 31, v64
; __device__ __forceinline__ unsigned cvt_pk_bf16(float lo, float hi) { f32x2 v = {lo, hi}; bf16x2_t b = __builtin_convertvector(v, bf16x2_t); return __builtin_bit_cast(unsigned, b); }
;     __device__ __forceinline__ void operator()(const f32x4 (&acc)[2][2][4][2], const Unit& u, int wr, int wc, int fr, int fq) const {
;         const int row0 = u.pm * BM + wr * 64 + fr, e = wc * 32 + 8 * fq;
; #pragma unroll
;         for (int ai = 0; ai < 2; ++ai)
; #pragma unroll
;             for (int m = 0; m < 4; ++m) { const int row = row0 + ai * HALF + m * 16, b = row / T, t = row % T;
;                 const size_t off = ((size_t)(b * 8 + u.pn) * T + t) * 128 + e;
; #pragma unroll
;                 for (int bj = 0; bj < 2; ++bj) { const f32x4 v0 = acc[ai][bj][m][0], v1 = acc[ai][bj][m][1];
;                     u32x4 w; w.x = cvt_pk_bf16(v0[0], v0[1]); w.y = cvt_pk_bf16(v0[2], v0[3]); w.z = cvt_pk_bf16(v1[0], v1[1]); w.w = cvt_pk_bf16(v1[2], v1[3]);
;                     *(u32x4*)((bj ? V : KN) + off) = w; } }
	v_lshrrev_b32_e32 v65, 18, v65
	v_add_u32_e32 v65, v64, v65
	v_ashrrev_i32_e32 v65, 14, v65
	v_mul_i32_i24_e32 v66, 0x4000, v65
	v_sub_u32_e32 v64, v64, v66
	v_lshl_add_u32 v66, v65, 3, s42
	v_ashrrev_i32_e32 v67, 31, v66
	v_ashrrev_i32_e32 v65, 31, v64
	v_lshlrev_b64 v[66:67], 22, v[66:67]
	v_lshlrev_b64 v[64:65], 8, v[64:65]
	v_cvt_pk_bf16_f32 v60, v60, v61
	v_cvt_pk_bf16_f32 v61, v62, v63
	v_cvt_pk_bf16_f32 v62, v56, v57
	v_lshl_add_u64 v[56:57], s[12:13], 0, v[66:67]
	v_cvt_pk_bf16_f32 v52, v52, v53
	v_cvt_pk_bf16_f32 v53, v54, v55
	v_cvt_pk_bf16_f32 v54, v44, v45
	v_lshl_add_u64 v[44:45], s[14:15], 0, v[66:67]
	v_lshl_add_u64 v[56:57], v[56:57], 0, v[64:65]
	v_lshl_add_u64 v[44:45], v[44:45], 0, v[64:65]
	v_cvt_pk_bf16_f32 v63, v58, v59
	v_lshl_add_u64 v[56:57], v[56:57], 0, v[112:113]
	v_cvt_pk_bf16_f32 v55, v46, v47
	v_lshl_add_u64 v[44:45], v[44:45], 0, v[112:113]
	global_store_dwordx4 v[56:57], v[60:63], off
	global_store_dwordx4 v[44:45], v[52:55], off
	v_add_u32_e32 v44, 0x90, v145
	v_ashrrev_i32_e32 v45, 31, v44
	v_lshrrev_b32_e32 v45, 18, v45
	v_add_u32_e32 v45, v44, v45
	v_ashrrev_i32_e32 v45, 14, v45
	v_mul_i32_i24_e32 v46, 0x4000, v45
	v_sub_u32_e32 v44, v44, v46
	v_lshl_add_u32 v46, v45, 3, s42
	v_ashrrev_i32_e32 v47, 31, v46
	v_ashrrev_i32_e32 v45, 31, v44
	v_lshlrev_b64 v[52:53], 22, v[46:47]
	v_lshlrev_b64 v[54:55], 8, v[44:45]
	v_cvt_pk_bf16_f32 v46, v40, v41
	v_lshl_add_u64 v[40:41], s[12:13], 0, v[52:53]
	v_cvt_pk_bf16_f32 v36, v36, v37
	v_cvt_pk_bf16_f32 v37, v38, v39
	v_cvt_pk_bf16_f32 v38, v28, v29
	v_lshl_add_u64 v[28:29], s[14:15], 0, v[52:53]
	v_lshl_add_u64 v[40:41], v[40:41], 0, v[54:55]
	v_lshl_add_u64 v[28:29], v[28:29], 0, v[54:55]
	v_cvt_pk_bf16_f32 v44, v48, v49
	v_cvt_pk_bf16_f32 v45, v50, v51
	v_cvt_pk_bf16_f32 v47, v42, v43
	v_lshl_add_u64 v[40:41], v[40:41], 0, v[112:113]
	v_cvt_pk_bf16_f32 v39, v30, v31
	v_lshl_add_u64 v[28:29], v[28:29], 0, v[112:113]
	global_store_dwordx4 v[40:41], v[44:47], off
	global_store_dwordx4 v[28:29], v[36:39], off
	v_add_u32_e32 v28, 0xa0, v145
	v_ashrrev_i32_e32 v29, 31, v28
	v_lshrrev_b32_e32 v29, 18, v29
	v_add_u32_e32 v29, v28, v29
	v_ashrrev_i32_e32 v29, 14, v29
	v_mul_i32_i24_e32 v30, 0x4000, v29
	v_sub_u32_e32 v28, v28, v30
	v_lshl_add_u32 v30, v29, 3, s42
	v_ashrrev_i32_e32 v31, 31, v30
	v_ashrrev_i32_e32 v29, 31, v28
	v_lshlrev_b64 v[36:37], 22, v[30:31]
	v_lshlrev_b64 v[38:39], 8, v[28:29]
	v_cvt_pk_bf16_f32 v30, v24, v25
	v_lshl_add_u64 v[24:25], s[12:13], 0, v[36:37]
	v_cvt_pk_bf16_f32 v20, v20, v21
	v_cvt_pk_bf16_f32 v21, v22, v23
	v_cvt_pk_bf16_f32 v22, v12, v13
	v_lshl_add_u64 v[12:13], s[14:15], 0, v[36:37]
	v_lshl_add_u64 v[24:25], v[24:25], 0, v[38:39]
	v_lshl_add_u64 v[12:13], v[12:13], 0, v[38:39]
	v_cvt_pk_bf16_f32 v28, v32, v33
	v_cvt_pk_bf16_f32 v29, v34, v35
	v_cvt_pk_bf16_f32 v31, v26, v27
	v_lshl_add_u64 v[24:25], v[24:25], 0, v[112:113]
	v_cvt_pk_bf16_f32 v23, v14, v15
	v_lshl_add_u64 v[12:13], v[12:13], 0, v[112:113]
	global_store_dwordx4 v[24:25], v[28:31], off
	global_store_dwordx4 v[12:13], v[20:23], off
	v_add_u32_e32 v12, 0xb0, v145
	v_ashrrev_i32_e32 v13, 31, v12
	v_lshrrev_b32_e32 v13, 18, v13
	v_add_u32_e32 v13, v12, v13
	v_ashrrev_i32_e32 v13, 14, v13
	v_mul_i32_i24_e32 v14, 0x4000, v13
	v_sub_u32_e32 v12, v12, v14
	v_lshl_add_u32 v14, v13, 3, s42
	v_ashrrev_i32_e32 v15, 31, v14
	v_ashrrev_i32_e32 v13, 31, v12
	v_lshlrev_b64 v[20:21], 22, v[14:15]
	v_lshlrev_b64 v[22:23], 8, v[12:13]
	v_cvt_pk_bf16_f32 v14, v8, v9
	v_lshl_add_u64 v[8:9], s[12:13], 0, v[20:21]
	v_cvt_pk_bf16_f32 v4, v4, v5
	v_cvt_pk_bf16_f32 v5, v6, v7
	v_cvt_pk_bf16_f32 v6, v0, v1
	v_lshl_add_u64 v[0:1], s[14:15], 0, v[20:21]
	v_lshl_add_u64 v[8:9], v[8:9], 0, v[22:23]
	v_lshl_add_u64 v[0:1], v[0:1], 0, v[22:23]
	v_cvt_pk_bf16_f32 v12, v16, v17
	v_cvt_pk_bf16_f32 v13, v18, v19
	v_cvt_pk_bf16_f32 v15, v10, v11
	v_lshl_add_u64 v[8:9], v[8:9], 0, v[112:113]
	v_cvt_pk_bf16_f32 v7, v2, v3
	v_lshl_add_u64 v[0:1], v[0:1], 0, v[112:113]
	s_and_b64 vcc, exec, s[6:7]
	s_mov_b64 s[6:7], -1
	global_store_dwordx4 v[8:9], v[12:15], off
	global_store_dwordx4 v[0:1], v[4:7], off
	s_cbranch_vccnz .LBB0_400
	s_andn2_b64 vcc, exec, s[10:11]
	s_cbranch_vccnz .LBB0_399
	s_barrier
	s_branch .LBB0_399

; __device__ __forceinline__ unsigned xb_ld(unsigned* p)              { return __hip_atomic_load(p, __ATOMIC_RELAXED, __HIP_MEMORY_SCOPE_AGENT); }
; __device__ __forceinline__ void xcd_barrier_complete(unsigned* bar, unsigned x, unsigned& nloc, unsigned& nx) {
;     const unsigned G = gridDim.x * gridDim.y * gridDim.z;
;     unsigned sum, cnt, mine, sp = 0u;
;     for (;;) {
;         sum = 0u; cnt = 0u; mine = 0u;
; #pragma unroll
;         for (unsigned j = 0; j < 16; ++j) { const unsigned c = xb_ld(&bar[XB_XCNT(j)]); sum += c; cnt += (c > 0u) ? 1u : 0u; mine = (j == x) ? c : mine; }
;         if (sum == G) break;
;         __builtin_amdgcn_s_sleep(1);
;         if ((++sp & 255u) == 0u) { if (xb_ld(&bar[XB_TMO])) break; if (sp > XB_SPIN_CAP) { atomicAdd(&bar[XB_TMO], 1u); break; } }
;     }
;     nloc = mine > 0u ? mine : 1u; nx = cnt > 0u ? cnt : 1u;
.LBB0_422:
	s_waitcnt lgkmcnt(0)
	v_mov_b64_e32 v[0:1], s[8:9]
	v_mov_b64_e32 v[2:3], s[10:11]
	global_load_dword v0, v[0:1], off sc1
	v_readlane_b32 s54, v255, 5
	global_load_dword v1, v[2:3], off sc1
	v_mov_b64_e32 v[2:3], s[12:13]
	global_load_dword v2, v[2:3], off sc1
	s_or_b64 s[52:53], s[52:53], exec
	s_or_b64 s[50:51], s[50:51], exec
	s_waitcnt vmcnt(0) lgkmcnt(0)
	v_add_u32_e32 v4, v1, v0
	v_add_u32_e32 v6, v4, v2
	v_mov_b64_e32 v[4:5], s[14:15]
	global_load_dword v3, v[4:5], off sc1
	v_mov_b64_e32 v[4:5], s[16:17]
	global_load_dword v4, v[4:5], off sc1
	s_waitcnt vmcnt(0) lgkmcnt(0)
	v_add_u32_e32 v6, v6, v3
	v_add_u32_e32 v8, v6, v4
	v_mov_b64_e32 v[6:7], s[18:19]
	global_load_dword v5, v[6:7], off sc1
	v_mov_b64_e32 v[6:7], s[20:21]
	global_load_dword v6, v[6:7], off sc1
	s_waitcnt vmcnt(0) lgkmcnt(0)
	v_add_u32_e32 v8, v8, v5
	v_add_u32_e32 v10, v8, v6
	v_mov_b64_e32 v[8:9], s[22:23]
	global_load_dword v7, v[8:9], off sc1
	v_mov_b64_e32 v[8:9], s[24:25]
	global_load_dword v8, v[8:9], off sc1
	s_waitcnt vmcnt(0) lgkmcnt(0)
	v_add_u32_e32 v10, v10, v7
	v_add_u32_e32 v12, v10, v8
	v_mov_b64_e32 v[10:11], s[26:27]
	global_load_dword v9, v[10:11], off sc1
	v_mov_b64_e32 v[10:11], s[28:29]
	global_load_dword v10, v[10:11], off sc1
	s_waitcnt vmcnt(0) lgkmcnt(0)
	v_add_u32_e32 v12, v12, v9
	v_add_u32_e32 v14, v12, v10
	v_mov_b64_e32 v[12:13], s[30:31]
	global_load_dword v11, v[12:13], off sc1
	v_mov_b64_e32 v[12:13], s[34:35]
	global_load_dword v12, v[12:13], off sc1
	s_waitcnt vmcnt(0) lgkmcnt(0)
	v_add_u32_e32 v14, v14, v11
	v_add_u32_e32 v16, v14, v12
	v_mov_b64_e32 v[14:15], s[36:37]
	global_load_dword v13, v[14:15], off sc1
	v_mov_b64_e32 v[14:15], s[42:43]
	global_load_dword v14, v[14:15], off sc1
	s_waitcnt vmcnt(0) lgkmcnt(0)
	v_add_u32_e32 v16, v16, v13
	v_add_u32_e32 v18, v16, v14
	v_mov_b64_e32 v[16:17], s[44:45]
	global_load_dword v15, v[16:17], off sc1
	s_waitcnt vmcnt(0) lgkmcnt(0)
	v_add_u32_e32 v16, v18, v15
	v_cmp_ne_u32_e32 vcc, s54, v16
	s_and_saveexec_b64 s[54:55], vcc
	s_cbranch_execz .LBB0_421
	s_and_b32 s57, s5, 0xff
	s_mov_b64 s[58:59], -1
	s_cmp_eq_u32 s57, 0
	s_mov_b64 s[62:63], -1
	s_mov_b64 s[60:61], -1
	s_sleep 1
	s_cbranch_scc1 .LBB0_425
	s_and_saveexec_b64 s[64:65], s[62:63]
	s_cbranch_execz .LBB0_420
	s_branch .LBB0_428
.LBB0_425:
	v_mov_b64_e32 v[16:17], s[6:7]
	global_load_dword v16, v[16:17], off sc1
	s_mov_b64 s[62:63], 0
	s_waitcnt vmcnt(0) lgkmcnt(0)
	v_cmp_eq_u32_e32 vcc, 0, v16
	s_and_saveexec_b64 s[64:65], vcc
	s_cmp_lt_u32 s5, 0x40001
	s_cselect_b64 s[62:63], -1, 0
	s_xor_b64 s[60:61], exec, -1
	s_and_b64 s[62:63], s[62:63], exec
	s_or_b64 exec, exec, s[64:65]
	s_movk_i32 s66, 0x80
	s_movk_i32 s67, 0x100
	s_and_saveexec_b64 s[64:65], s[62:63]
	s_cbranch_execz .LBB0_420

; __device__ __forceinline__ unsigned xb_ld(unsigned* p)              { return __hip_atomic_load(p, __ATOMIC_RELAXED, __HIP_MEMORY_SCOPE_AGENT); }
; __device__ __forceinline__ unsigned xb_add(unsigned* p, unsigned v) { return __hip_atomic_fetch_add(p, v, __ATOMIC_RELAXED, __HIP_MEMORY_SCOPE_AGENT); }
; #define XB_SPIN(cond, bar) do { unsigned _sp = 0; while (cond) { __builtin_amdgcn_s_sleep(1); \
;     if ((++_sp & 255u) == 0u) { if (xb_ld(&(bar)[XB_TMO])) break; if (_sp > XB_SPIN_CAP) { atomicAdd(&(bar)[XB_TMO], 1u); break; } } } } while (0)
; __device__ __forceinline__ void xcd_barrier(const XcdBarrier& b) {
;     ...
;     if (threadIdx.x == 0) {
;         unsigned* bar = b.bar;
;         __builtin_amdgcn_s_waitcnt(0);
;         unsigned nloc = b.st[0], nx = b.st[1];
;         if (nloc == 0u) { xcd_barrier_complete(bar, b.x, nloc, nx); b.st[0] = nloc; b.st[1] = nx; }
;         const unsigned old = xb_add(&bar[XB_XSUB(b.x)], 1u);
;         const unsigned gen = old / nloc;
;         if (old + 1u == (gen + 1u) * nloc) {
;             __builtin_amdgcn_fence(__ATOMIC_RELEASE, "agent");
;             asm volatile("s_waitcnt vmcnt(0)" ::: "memory");
;             const unsigned og = xb_add(&bar[XB_TOP], 1u);
;             const unsigned tg = og / nx;
;             if (og + 1u == (tg + 1u) * nx) xb_add(&bar[XB_TOPGEN], 1u);
;             else XB_SPIN(xb_ld(&bar[XB_TOPGEN]) == tg, bar);
;             __builtin_amdgcn_fence(__ATOMIC_ACQUIRE, "agent");
;             xb_add(&bar[XB_XGEN(b.x)], 1u);
;             asm volatile("s_waitcnt vmcnt(0)" ::: "memory");
;         } else {
;             XB_SPIN(xb_ld(&bar[XB_XGEN(b.x)]) == gen, bar);
.LBB0_432:
	s_lshl_b32 s4, s4, 8
	s_add_u32 s6, s40, s4
	s_addc_u32 s7, s41, 0
	v_mov_b32_e32 v1, s6
	v_add_co_u32_e32 v4, vcc, 0x3e301000, v1
	v_mov_b32_e32 v1, s7
	s_nop 0
	v_addc_co_u32_e32 v5, vcc, 0, v1, vcc
	flat_atomic_add v3, v[4:5], v239 offset:1024 sc0
	v_cvt_f32_u32_e32 v1, v2
	v_sub_u32_e32 v4, 0, v2
	s_add_u32 s5, s6, 0x3e300000
	s_addc_u32 s4, s7, 0
	v_rcp_iflag_f32_e32 v1, v1
	s_nop 0
	v_mul_f32_e32 v1, 0x4f7ffffe, v1
	v_cvt_u32_f32_e32 v1, v1
	v_mul_lo_u32 v4, v4, v1
	v_mul_hi_u32 v4, v1, v4
	v_add_u32_e32 v1, v1, v4
	s_waitcnt vmcnt(0) lgkmcnt(0)
	v_mul_hi_u32 v1, v3, v1
	v_mul_lo_u32 v4, v1, v2
	v_sub_u32_e32 v4, v3, v4
	v_cmp_ge_u32_e32 vcc, v4, v2
	v_add_u32_e32 v5, 1, v1
	s_nop 0
	v_cndmask_b32_e32 v1, v1, v5, vcc
	v_sub_u32_e32 v5, v4, v2
	v_cndmask_b32_e32 v4, v4, v5, vcc
	v_cmp_ge_u32_e32 vcc, v4, v2
	v_add_u32_e32 v4, 1, v1
	s_nop 0
	v_cndmask_b32_e32 v1, v1, v4, vcc
	v_add_u32_e32 v4, 1, v3
	v_mad_u64_u32 v[2:3], s[6:7], v2, v1, v[2:3]
	v_cmp_ne_u32_e32 vcc, v4, v2
	s_and_saveexec_b64 s[6:7], vcc
	s_xor_b64 s[6:7], exec, s[6:7]
	s_cbranch_execz .LBB0_445
	v_mov_b32_e32 v0, s5
	v_add_co_u32_e32 v2, vcc, 0x2000, v0
	v_mov_b32_e32 v0, s4
	s_nop 0
	v_addc_co_u32_e32 v3, vcc, 0, v0, vcc
	global_load_dword v0, v[2:3], off offset:1024 sc1
	s_add_u32 s10, s5, 0x2400
	s_addc_u32 s11, s4, 0
	s_waitcnt vmcnt(0) lgkmcnt(0)
	v_cmp_eq_u32_e32 vcc, v0, v1
	s_and_saveexec_b64 s[8:9], vcc
	s_cbranch_execz .LBB0_444
	s_add_u32 s12, s40, 0x3e300200
	s_addc_u32 s13, s41, 0
	s_mov_b32 s28, 1
	s_mov_b64 s[14:15], 0
	s_branch .LBB0_436

; __device__ __forceinline__ unsigned xb_ld(unsigned* p)              { return __hip_atomic_load(p, __ATOMIC_RELAXED, __HIP_MEMORY_SCOPE_AGENT); }
; #define XB_SPIN(cond, bar) do { unsigned _sp = 0; while (cond) { __builtin_amdgcn_s_sleep(1); \
;     if ((++_sp & 255u) == 0u) { if (xb_ld(&(bar)[XB_TMO])) break; if (_sp > XB_SPIN_CAP) { atomicAdd(&(bar)[XB_TMO], 1u); break; } } } } while (0)
; __device__ __forceinline__ void xcd_barrier(const XcdBarrier& b) {
;     ...
;             XB_SPIN(xb_ld(&bar[XB_XGEN(b.x)]) == gen, bar);
.LBB0_436:
	s_and_b32 s22, s28, 0xff
	s_mov_b64 s[20:21], -1
	s_cmp_lg_u32 s22, 0
	s_mov_b64 s[22:23], -1
	s_sleep 1
	s_cbranch_scc1 .LBB0_440
	v_mov_b64_e32 v[2:3], s[12:13]
	global_load_dword v0, v[2:3], off sc1
	s_mov_b64 s[22:23], 0
	s_mov_b64 s[24:25], -1
	s_waitcnt vmcnt(0) lgkmcnt(0)
	v_cmp_eq_u32_e32 vcc, 0, v0
	s_and_saveexec_b64 s[26:27], vcc
	s_cmp_lt_u32 s28, 0x40001
	s_cselect_b64 s[22:23], -1, 0
	s_xor_b64 s[24:25], exec, -1
	s_and_b64 s[22:23], s[22:23], exec
	s_or_b64 exec, exec, s[26:27]
.LBB0_440:
	s_andn2_b64 s[18:19], s[18:19], exec
	s_and_b64 s[24:25], s[24:25], exec
	s_or_b64 s[18:19], s[18:19], s[24:25]
	s_and_saveexec_b64 s[24:25], s[22:23]
	s_cbranch_execz .LBB0_435
	v_mov_b64_e32 v[2:3], s[10:11]
	global_load_dword v0, v[2:3], off sc1
	s_add_i32 s28, s28, 1
	s_or_b64 s[18:19], s[18:19], exec
	s_waitcnt vmcnt(0) lgkmcnt(0)
	v_cmp_ne_u32_e32 vcc, v0, v1
	s_orn2_b64 s[20:21], vcc, exec
	s_branch .LBB0_435

; __device__ __forceinline__ unsigned xb_ld(unsigned* p)              { return __hip_atomic_load(p, __ATOMIC_RELAXED, __HIP_MEMORY_SCOPE_AGENT); }
; __device__ __forceinline__ unsigned xb_add(unsigned* p, unsigned v) { return __hip_atomic_fetch_add(p, v, __ATOMIC_RELAXED, __HIP_MEMORY_SCOPE_AGENT); }
; #define XB_SPIN(cond, bar) do { unsigned _sp = 0; while (cond) { __builtin_amdgcn_s_sleep(1); \
;     if ((++_sp & 255u) == 0u) { if (xb_ld(&(bar)[XB_TMO])) break; if (_sp > XB_SPIN_CAP) { atomicAdd(&(bar)[XB_TMO], 1u); break; } } } } while (0)
; __device__ __forceinline__ void xcd_barrier(const XcdBarrier& b) {
;     ...
;         if (old + 1u == (gen + 1u) * nloc) {
;             __builtin_amdgcn_fence(__ATOMIC_RELEASE, "agent");
;             asm volatile("s_waitcnt vmcnt(0)" ::: "memory");
;             const unsigned og = xb_add(&bar[XB_TOP], 1u);
;             const unsigned tg = og / nx;
;             if (og + 1u == (tg + 1u) * nx) xb_add(&bar[XB_TOPGEN], 1u);
;             else XB_SPIN(xb_ld(&bar[XB_TOPGEN]) == tg, bar);
.LBB0_445:
	s_andn2_saveexec_b64 s[6:7], s[6:7]
	s_cbranch_execz .LBB0_461
	v_mov_b32_e32 v1, s40
	v_add_co_u32_e32 v2, vcc, 0x3e303000, v1
	v_mov_b32_e32 v1, s41
	buffer_wbl2 sc1
	s_waitcnt vmcnt(0)
	v_addc_co_u32_e32 v3, vcc, 0, v1, vcc
	flat_atomic_add v1, v[2:3], v239 offset:1024 sc0
	v_cvt_f32_u32_e32 v2, v0
	v_sub_u32_e32 v3, 0, v0
	s_mov_b64 s[10:11], -1
	v_rcp_iflag_f32_e32 v2, v2
	s_nop 0
	v_mul_f32_e32 v2, 0x4f7ffffe, v2
	v_cvt_u32_f32_e32 v2, v2
	v_mul_lo_u32 v3, v3, v2
	v_mul_hi_u32 v3, v2, v3
	v_add_u32_e32 v2, v2, v3
	s_waitcnt vmcnt(0) lgkmcnt(0)
	v_mul_hi_u32 v2, v1, v2
	v_mul_lo_u32 v3, v2, v0
	v_sub_u32_e32 v3, v1, v3
	v_cmp_ge_u32_e32 vcc, v3, v0
	v_add_u32_e32 v4, 1, v2
	s_nop 0
	v_cndmask_b32_e32 v2, v2, v4, vcc
	v_sub_u32_e32 v4, v3, v0
	v_cndmask_b32_e32 v3, v3, v4, vcc
	v_cmp_ge_u32_e32 vcc, v3, v0
	v_add_u32_e32 v3, 1, v2
	s_nop 0
	v_cndmask_b32_e32 v2, v2, v3, vcc
	v_add_u32_e32 v3, 1, v1
	v_mad_u64_u32 v[0:1], s[6:7], v0, v2, v[0:1]
	s_add_u32 s6, s40, 0x3e303500
	s_addc_u32 s7, s41, 0
	v_cmp_ne_u32_e32 vcc, v3, v0
	v_mov_b64_e32 v[0:1], s[6:7]
	s_and_saveexec_b64 s[8:9], vcc
	s_cbranch_execz .LBB0_458
	v_mov_b64_e32 v[0:1], s[6:7]
	global_load_dword v0, v[0:1], off sc1
	s_mov_b64 s[14:15], 0
	s_waitcnt vmcnt(0) lgkmcnt(0)
	v_cmp_eq_u32_e32 vcc, v0, v2
	s_and_saveexec_b64 s[12:13], vcc
	s_cbranch_execz .LBB0_457
	s_add_u32 s10, s40, 0x3e300200
	s_addc_u32 s11, s41, 0
	s_mov_b32 s26, 1
	s_branch .LBB0_450

; __device__ __forceinline__ unsigned xb_ld(unsigned* p)              { return __hip_atomic_load(p, __ATOMIC_RELAXED, __HIP_MEMORY_SCOPE_AGENT); }
; #define XB_SPIN(cond, bar) do { unsigned _sp = 0; while (cond) { __builtin_amdgcn_s_sleep(1); \
;     if ((++_sp & 255u) == 0u) { if (xb_ld(&(bar)[XB_TMO])) break; if (_sp > XB_SPIN_CAP) { atomicAdd(&(bar)[XB_TMO], 1u); break; } } } } while (0)
; __device__ __forceinline__ void xcd_barrier(const XcdBarrier& b) {
;     ...
;             else XB_SPIN(xb_ld(&bar[XB_TOPGEN]) == tg, bar);
.LBB0_452:
	v_mov_b64_e32 v[0:1], s[10:11]
	global_load_dword v0, v[0:1], off sc1
	s_mov_b64 s[22:23], 0
	s_mov_b64 s[20:21], -1
	s_waitcnt vmcnt(0) lgkmcnt(0)
	v_cmp_eq_u32_e32 vcc, 0, v0
	s_and_saveexec_b64 s[24:25], vcc
	s_cmp_lt_u32 s26, 0x40001
	s_cselect_b64 s[22:23], -1, 0
	s_xor_b64 s[20:21], exec, -1
	s_and_b64 s[22:23], s[22:23], exec
	s_or_b64 exec, exec, s[24:25]
	s_and_saveexec_b64 s[24:25], s[22:23]
	s_cbranch_execz .LBB0_449
.LBB0_455:
	v_mov_b64_e32 v[0:1], s[6:7]
	global_load_dword v0, v[0:1], off sc1
	s_add_i32 s26, s26, 1
	s_or_b64 s[20:21], s[20:21], exec
	s_waitcnt vmcnt(0) lgkmcnt(0)
	v_cmp_ne_u32_e32 vcc, v0, v2
	s_orn2_b64 s[18:19], vcc, exec
	s_branch .LBB0_449

; __device__ __forceinline__ int opaque_tid() { int t = threadIdx.x; asm volatile("" : "+v"(t)); return t; }
; __device__ __forceinline__ int v_st(int k, int c) { const int kk = (k & ~0xC) | ((k & 4) << 1) | ((k & 8) >> 1); return ((kk >> 3) * 4 + (c >> 5)) * 512 + ((kk & 7) * 32 + (c & 31)) * 2; }
; __device__ __forceinline__ int v_rd_base(int lane) { return ((lane & 3) << 3) | (((lane >> 2) & 3) << 6) | (((lane >> 4) & 1) << 5) | (((lane >> 5) & 1) << 8); }
; __device__ __forceinline__ void attn_unit(const bf16_t* __restrict__ Qb, const bf16_t* __restrict__ Kn, const bf16_t* __restrict__ Kr, const bf16_t* __restrict__ Vh,
;                                           bf16_t* __restrict__ Ob, char* lds) {
;   const int tid = opaque_tid(), wid = tid >> 6, lane = tid & 63, r32 = lane & 31, hi = lane >> 5;
;   char* V_lds = lds; char* K_lds = lds + 2 * SHM_V;
;   float* ws = (float*)(lds + 2 * SHM_V + 2 * SHM_K) + wid * 64; float* li_l = ws; float* al_l = ws + 32;
;   float m_reg = 0.f, l_reg = 0; f32x16 o[4] = {}; bf16x8 qr[8];
;   char* qL = lds + 2 * SHM_V + 2 * SHM_K + 2048 + wid * 4096 + lane * 16;
;   const bf16_t* Qw = Qb + (long)(wid * 32 + r32) * 192 + hi * 8;
; #pragma unroll
;   for (int d0 = 0; d0 < 8; ++d0) qr[d0] = *reinterpret_cast<const bf16x8*>(Qw + d0 * 16);
; #pragma unroll
;   for (int d0 = 8; d0 < 12; ++d0) *reinterpret_cast<bf16x8*>(qL + (d0 - 8) * 1024) = *reinterpret_cast<const bf16x8*>(Qw + d0 * 16);
;   const int sr = tid >> 4, sc = (tid & 15) * 8, vst0 = v_st(sr, sc), vst1 = v_st(32 + sr, sc);
;   const int rr = tid >> 3, rc = (tid & 7) * 8;
;   const int kst0 = KSWZ(sr, sc * 2), kst1 = KSWZ(32 + sr, sc * 2), kst2 = KSWZ(rr, 256 + rc * 2);
;   const int vb0 = (int)(uintptr_t)V_lds + v_rd_base(lane);
;   struct { bf16x8 vs0, vs1, ks0, ks1, ks2; } sr_[SDEPTH];
;     ...
;   f32x16 pA0, pA1, pB0, pB1; float alA, alB; bf16x8 pa0, pa1, pa2, pa3; const int NT = T / KVBLK;
.LBB0_465:
.LBB0_466:
	s_mul_i32 s41, s16, 0x18000
	s_mul_hi_u32 s42, s16, 0x18000
	s_add_u32 s20, s68, s28
	s_addc_u32 s21, s69, s5
	s_add_u32 s20, s20, s41
	s_addc_u32 s21, s21, s42
	s_add_u32 s20, s20, 0x23300000
	s_addc_u32 s21, s21, 0
	s_add_u32 s22, s68, s14
	s_addc_u32 s23, s69, s15
	s_add_u32 s26, s22, 0x2d300000
	s_addc_u32 s27, s23, 0
	s_add_u32 s22, s22, 0x29300000
	s_addc_u32 s23, s23, 0
	s_add_u32 s24, s22, 8192
	s_addc_u32 s25, s23, 0
	s_add_u32 s30, s26, 8192
	s_addc_u32 s31, s27, 0
	s_add_u32 s34, s68, s8
	s_addc_u32 s35, s69, s9
	s_add_u32 s34, s34, 0x31300000
	s_addc_u32 s35, s35, 0
	s_lshl_b32 s41, s16, 20
	s_add_u32 s36, s68, s10
	s_addc_u32 s37, s69, s11
	s_add_u32 s36, s36, s41
	s_addc_u32 s37, s37, 0
	s_add_u32 s36, s36, s29
	s_addc_u32 s37, s37, 0
	s_add_u32 s36, s36, 0x6300800
	s_addc_u32 s37, s37, 0
	s_mov_b32 s38, 0x4138aa3b
	v_and_b32_e32 v235, 63, v195
	v_lshrrev_b32_e32 v243, 6, v195
	v_lshlrev_b32_e32 v218, 4, v195
	v_readfirstlane_b32 s40, v243
	v_and_b32_e32 v244, 15, v235
	v_lshrrev_b32_e32 v245, 4, v235
	global_load_dwordx4 v[178:181], v218, s[22:23]
	global_load_dwordx4 v[182:185], v218, s[24:25]
	global_load_dwordx4 v[196:199], v218, s[34:35]
	global_load_dwordx4 v[186:189], v218, s[26:27]
	global_load_dwordx4 v[190:193], v218, s[30:31]
	s_add_u32 s22, s22, 16384
	s_addc_u32 s23, s23, 0
	s_add_u32 s24, s24, 16384
	s_addc_u32 s25, s25, 0
	s_add_u32 s26, s26, 16384
	s_addc_u32 s27, s27, 0
	s_add_u32 s30, s30, 16384
	s_addc_u32 s31, s31, 0
	s_add_u32 s34, s34, 8192
	s_addc_u32 s35, s35, 0
	s_mul_i32 s41, s40, 0x3000
	s_add_u32 s20, s20, s41
	s_addc_u32 s21, s21, 0
	s_lshl_b32 s41, s40, 17
	s_add_u32 s36, s36, s41
	s_addc_u32 s37, s37, 0
	v_mul_u32_u24_e32 v246, 0x180, v244
	v_lshl_add_u32 v246, v245, 4, v246
	v_add_u32_e32 v247, 0x1800, v246
	global_load_dwordx4 v[64:67], v246, s[20:21] offset:0
	global_load_dwordx4 v[68:71], v246, s[20:21] offset:64
	global_load_dwordx4 v[72:75], v246, s[20:21] offset:128
	global_load_dwordx4 v[76:79], v246, s[20:21] offset:192
	global_load_dwordx4 v[80:83], v246, s[20:21] offset:256
	global_load_dwordx4 v[84:87], v246, s[20:21] offset:320
	global_load_dwordx4 v[88:91], v247, s[20:21] offset:0
	global_load_dwordx4 v[92:95], v247, s[20:21] offset:64
	global_load_dwordx4 v[96:99], v247, s[20:21] offset:128
	global_load_dwordx4 v[100:103], v247, s[20:21] offset:192
	global_load_dwordx4 v[104:107], v247, s[20:21] offset:256
	global_load_dwordx4 v[108:111], v247, s[20:21] offset:320
	v_and_b32_e32 v248, 3, v244
	v_xor_b32_e32 v248, v248, v245
	v_mul_u32_u24_e32 v249, 0x180, v244
	v_lshl_add_u32 v249, v248, 4, v249
	v_bfe_u32 v248, v244, 2, 1
	v_lshlrev_b32_e32 v248, 6, v248
	v_add_u32_e32 v202, v249, v248
	v_sub_u32_e32 v203, v249, v248
	v_add_u32_e32 v203, 64, v203
	v_add_u32_e32 v204, 0x6000, v202
	v_add_u32_e32 v205, 0x6000, v203
	v_bfe_u32 v248, v235, 4, 1
	v_bfe_u32 v249, v235, 2, 2
	v_lshl_or_b32 v248, v248, 2, v249
	v_lshrrev_b32_e32 v249, 5, v235
	v_lshlrev_b32_e32 v249, 11, v249
	v_and_b32_e32 v250, 3, v235
	v_lshl_or_b32 v249, v250, 3, v249
	v_xor_b32_e32 v250, 0, v248
	v_lshl_add_u32 v206, v250, 5, v249
	v_xor_b32_e32 v250, 1, v248
	v_lshl_add_u32 v207, v250, 5, v249
	v_add_u32_e32 v207, 256, v207
	v_xor_b32_e32 v250, 2, v248
	v_lshl_add_u32 v208, v250, 5, v249
	v_add_u32_e32 v208, 512, v208
	v_xor_b32_e32 v250, 3, v248
	v_lshl_add_u32 v209, v250, 5, v249
	v_add_u32_e32 v209, 768, v209
	v_xor_b32_e32 v250, 4, v248
	v_lshl_add_u32 v210, v250, 5, v249
	v_add_u32_e32 v210, 1024, v210
	v_xor_b32_e32 v250, 5, v248
	v_lshl_add_u32 v211, v250, 5, v249
	v_add_u32_e32 v211, 1280, v211
	v_xor_b32_e32 v250, 6, v248
	v_lshl_add_u32 v212, v250, 5, v249
	v_add_u32_e32 v212, 1536, v212
	v_xor_b32_e32 v250, 7, v248
	v_lshl_add_u32 v213, v250, 5, v249
	v_add_u32_e32 v213, 1792, v213
	v_lshrrev_b32_e32 v248, 4, v195
	v_and_b32_e32 v249, 15, v195
	v_lshlrev_b32_e32 v249, 4, v249
	v_and_b32_e32 v250, 7, v248
	v_lshlrev_b32_e32 v251, 4, v250
	v_xor_b32_e32 v249, v249, v251
	v_mul_u32_u24_e32 v214, 0x180, v248
	v_add_u32_e32 v214, v214, v249
	v_add_u32_e32 v215, 0x3000, v214
	v_bfe_u32 v249, v195, 1, 3
	v_xor_b32_e32 v250, v250, v249
	v_lshrrev_b32_e32 v251, 3, v248
	v_lshl_or_b32 v251, v251, 3, v249
	v_lshlrev_b32_e32 v251, 8, v251
	v_lshl_add_u32 v217, v250, 5, v251
	v_and_b32_e32 v250, 1, v195
	v_lshl_add_u32 v217, v250, 4, v217
	v_lshrrev_b32_e32 v248, 3, v195
	v_and_b32_e32 v249, 7, v195
	v_and_b32_e32 v250, 7, v248
	v_xor_b32_e32 v249, v249, v250
	v_lshlrev_b32_e32 v249, 4, v249
	v_mul_u32_u24_e32 v216, 0x180, v248
	v_add_u32_e32 v216, v216, v249
	v_add_u32_e32 v216, 0x100, v216
	s_lshl_b32 s41, s40, 8
	s_add_u32 s41, s41, 81920
	v_lshl_add_u32 v219, v244, 2, s41
	v_lshl_add_u32 v232, v245, 4, s41
	v_xor_b32_e32 v112, 16, v235
	v_lshlrev_b32_e32 v112, 2, v112
	v_mov_b32_e32 v220, 0
	v_mov_b32_e32 v222, 0
	v_mov_b32_e32 v224, 0
	v_mov_b32_e32 v225, 0
	v_mov_b32_e32 v226, 0
	v_mov_b32_e32 v227, 0
	v_mov_b32_e32 v221, 0
	v_mov_b32_e32 v223, 0
	v_mov_b32_e32 v228, 0
	v_mov_b32_e32 v229, 0
	v_mov_b32_e32 v230, 0
	v_mov_b32_e32 v231, 0
	v_mov_b32_e32 v0, 0
	v_mov_b32_e32 v1, 0
	v_mov_b32_e32 v2, 0
	v_mov_b32_e32 v3, 0
	v_mov_b32_e32 v4, 0
	v_mov_b32_e32 v5, 0
	v_mov_b32_e32 v6, 0
	v_mov_b32_e32 v7, 0
	v_mov_b32_e32 v8, 0
	v_mov_b32_e32 v9, 0
	v_mov_b32_e32 v10, 0
	v_mov_b32_e32 v11, 0
	v_mov_b32_e32 v12, 0
	v_mov_b32_e32 v13, 0
	v_mov_b32_e32 v14, 0
	v_mov_b32_e32 v15, 0
	v_mov_b32_e32 v16, 0
	v_mov_b32_e32 v17, 0
	v_mov_b32_e32 v18, 0
	v_mov_b32_e32 v19, 0
	v_mov_b32_e32 v20, 0
	v_mov_b32_e32 v21, 0
	v_mov_b32_e32 v22, 0
	v_mov_b32_e32 v23, 0
	v_mov_b32_e32 v24, 0
	v_mov_b32_e32 v25, 0
	v_mov_b32_e32 v26, 0
	v_mov_b32_e32 v27, 0
	v_mov_b32_e32 v28, 0
	v_mov_b32_e32 v29, 0
	v_mov_b32_e32 v30, 0
	v_mov_b32_e32 v31, 0
	v_mov_b32_e32 v32, 0
	v_mov_b32_e32 v33, 0
	v_mov_b32_e32 v34, 0
	v_mov_b32_e32 v35, 0
	v_mov_b32_e32 v36, 0
	v_mov_b32_e32 v37, 0
	v_mov_b32_e32 v38, 0
	v_mov_b32_e32 v39, 0
	v_mov_b32_e32 v40, 0
	v_mov_b32_e32 v41, 0
	v_mov_b32_e32 v42, 0
	v_mov_b32_e32 v43, 0
	v_mov_b32_e32 v44, 0
	v_mov_b32_e32 v45, 0
	v_mov_b32_e32 v46, 0
	v_mov_b32_e32 v47, 0
	v_mov_b32_e32 v48, 0
	v_mov_b32_e32 v49, 0
	v_mov_b32_e32 v50, 0
	v_mov_b32_e32 v51, 0
	v_mov_b32_e32 v52, 0
	v_mov_b32_e32 v53, 0
	v_mov_b32_e32 v54, 0
	v_mov_b32_e32 v55, 0
	v_mov_b32_e32 v56, 0
	v_mov_b32_e32 v57, 0
	v_mov_b32_e32 v58, 0
	v_mov_b32_e32 v59, 0
	v_mov_b32_e32 v60, 0
	v_mov_b32_e32 v61, 0
	v_mov_b32_e32 v62, 0
	v_mov_b32_e32 v63, 0
	s_waitcnt vmcnt(12)
; #define SLOAD(i, k0) do { sr_[i].vs0 = *(const bf16x8*)(&Vh[(long)((k0) + sr) * 128 + sc]); sr_[i].vs1 = *(const bf16x8*)(&Vh[(long)((k0) + 32 + sr) * 128 + sc]); \
;     sr_[i].ks0 = *(const bf16x8*)(&Kn[(long)((k0) + sr) * 128 + sc]); sr_[i].ks1 = *(const bf16x8*)(&Kn[(long)((k0) + 32 + sr) * 128 + sc]); \
;     sr_[i].ks2 = *(const bf16x8*)(&Kr[(long)((k0) + rr) * 64 + rc]); } while (0)
; #define SWRITE(b, i) do { *(bf16x8*)(V_lds + (b) * SHM_V + vst0) = sr_[i].vs0; *(bf16x8*)(V_lds + (b) * SHM_V + vst1) = sr_[i].vs1; \
;     *(bf16x8*)(K_lds + (b) * SHM_K + kst0) = sr_[i].ks0; *(bf16x8*)(K_lds + (b) * SHM_K + kst1) = sr_[i].ks1; *(bf16x8*)(K_lds + (b) * SHM_K + kst2) = sr_[i].ks2; } while (0)
; template <bool FIRST>
; __device__ __forceinline__ void partialSM(f32x16& p0, f32x16& p1, float& m_reg, float& alpha) {
;   constexpr float THR2 = THR * 1.4426950408889634f;
;   float pmax = p0[0];
; #pragma unroll
;   for (int r = 1; r < 16; ++r) pmax = fmaxf(pmax, p0[r]);
; #pragma unroll
;   for (int r = 0; r < 16; ++r) pmax = fmaxf(pmax, p1[r]);
; __device__ __forceinline__ void qkt(f32x16& p0, f32x16& p1, const char* Ks, const bf16x8* qr, const char* qL, int r32, int hi, float negm) {
; #pragma unroll
;   for (int r = 0; r < 16; ++r) { p0[r] = negm; p1[r] = negm; }
; #pragma unroll
;   for (int d0 = 0; d0 < 12; ++d0) { int cb = (d0 * 16 + hi * 8) * 2;
;     bf16x8 b0 = *reinterpret_cast<const bf16x8*>(Ks + KSWZ(r32, cb));
;     bf16x8 b1 = *reinterpret_cast<const bf16x8*>(Ks + KSWZ(32 + r32, cb));
;     const bf16x8 q = d0 < 8 ? qr[d0 < 8 ? d0 : 0] : *reinterpret_cast<const bf16x8*>(qL + (d0 - 8) * 1024);
;     p0 = __builtin_amdgcn_mfma_f32_32x32x16_bf16(b0, q, p0, 0, 0, 0);
;     p1 = __builtin_amdgcn_mfma_f32_32x32x16_bf16(b1, q, p1, 0, 0, 0); }
; __device__ __forceinline__ void attn_unit(const bf16_t* __restrict__ Qb, const bf16_t* __restrict__ Kn, const bf16_t* __restrict__ Kr, const bf16_t* __restrict__ Vh,
;                                           bf16_t* __restrict__ Ob, char* lds) {
;     ...
;   SLOAD(SE, 0); asm volatile("s_waitcnt vmcnt(0)" ::: "memory"); SWRITE(0, SE); __syncthreads();
;   qkt(pA0, pA1, K_lds, qr, qL, r32, hi, 0.f); partialSM<true>(pA0, pA1, m_reg, alA);
;   SLOAD(SO, KVBLK); if constexpr (SDEPTH == 2) { if (2 < NT) SLOAD(SE, 2 * KVBLK); }
;   SWAIT(); SWRITE(1, SO); __syncthreads();
	ds_write_b128 v214, v[178:181] offset:32768
	ds_write_b128 v215, v[182:185] offset:32768
	ds_write_b128 v216, v[196:199] offset:32768
	ds_write_b128 v217, v[186:189] offset:0
	ds_write_b128 v217, v[190:193] offset:8192
	global_load_dwordx4 v[178:181], v218, s[22:23]
	global_load_dwordx4 v[182:185], v218, s[24:25]
	global_load_dwordx4 v[196:199], v218, s[34:35]
	global_load_dwordx4 v[186:189], v218, s[26:27]
	global_load_dwordx4 v[190:193], v218, s[30:31]
	s_add_u32 s22, s22, 16384
	s_addc_u32 s23, s23, 0
	s_add_u32 s24, s24, 16384
	s_addc_u32 s25, s25, 0
	s_add_u32 s26, s26, 16384
	s_addc_u32 s27, s27, 0
	s_add_u32 s30, s30, 16384
	s_addc_u32 s31, s31, 0
	s_add_u32 s34, s34, 8192
	s_addc_u32 s35, s35, 0
	s_waitcnt vmcnt(5)
	s_waitcnt lgkmcnt(0)
	s_barrier
	ds_read_b128 v[162:165], v202 offset:32768
	ds_read_b128 v[166:169], v203 offset:32768
	ds_read_b128 v[170:173], v202 offset:32896
	s_waitcnt lgkmcnt(2)
	v_mfma_f32_16x16x32_bf16 v[114:117], v[162:165], v[64:67], v[224:227]
	v_mfma_f32_16x16x32_bf16 v[118:121], v[162:165], v[88:91], v[228:231]
	ds_read_b128 v[174:177], v203 offset:32896
	s_waitcnt lgkmcnt(2)
	v_mfma_f32_16x16x32_bf16 v[114:117], v[166:169], v[68:71], v[114:117]
	v_mfma_f32_16x16x32_bf16 v[118:121], v[166:169], v[92:95], v[118:121]
	ds_read_b128 v[162:165], v202 offset:33024
	s_waitcnt lgkmcnt(2)
	v_mfma_f32_16x16x32_bf16 v[114:117], v[170:173], v[72:75], v[114:117]
	v_mfma_f32_16x16x32_bf16 v[118:121], v[170:173], v[96:99], v[118:121]
	ds_read_b128 v[166:169], v203 offset:33024
	s_waitcnt lgkmcnt(2)
	v_mfma_f32_16x16x32_bf16 v[114:117], v[174:177], v[76:79], v[114:117]
	v_mfma_f32_16x16x32_bf16 v[118:121], v[174:177], v[100:103], v[118:121]
	ds_read_b128 v[170:173], v202 offset:38912
	s_waitcnt lgkmcnt(2)
	v_mfma_f32_16x16x32_bf16 v[114:117], v[162:165], v[80:83], v[114:117]
	v_mfma_f32_16x16x32_bf16 v[118:121], v[162:165], v[104:107], v[118:121]
	ds_read_b128 v[174:177], v203 offset:38912
	s_waitcnt lgkmcnt(2)
	v_mfma_f32_16x16x32_bf16 v[114:117], v[166:169], v[84:87], v[114:117]
	v_mfma_f32_16x16x32_bf16 v[118:121], v[166:169], v[108:111], v[118:121]
	ds_read_b128 v[162:165], v202 offset:39040
	s_waitcnt lgkmcnt(2)
	v_mfma_f32_16x16x32_bf16 v[122:125], v[170:173], v[64:67], v[224:227]
	v_mfma_f32_16x16x32_bf16 v[126:129], v[170:173], v[88:91], v[228:231]
	ds_read_b128 v[166:169], v203 offset:39040
	s_waitcnt lgkmcnt(2)
	v_mfma_f32_16x16x32_bf16 v[122:125], v[174:177], v[68:71], v[122:125]
	v_mfma_f32_16x16x32_bf16 v[126:129], v[174:177], v[92:95], v[126:129]
	ds_read_b128 v[170:173], v202 offset:39168
	s_waitcnt lgkmcnt(2)
	v_mfma_f32_16x16x32_bf16 v[122:125], v[162:165], v[72:75], v[122:125]
	v_mfma_f32_16x16x32_bf16 v[126:129], v[162:165], v[96:99], v[126:129]
	ds_read_b128 v[174:177], v203 offset:39168
	v_max3_f32 v233, v114, v115, v116
	s_waitcnt lgkmcnt(2)
	v_mfma_f32_16x16x32_bf16 v[122:125], v[166:169], v[76:79], v[122:125]
	v_mfma_f32_16x16x32_bf16 v[126:129], v[166:169], v[100:103], v[126:129]
	ds_read_b128 v[162:165], v202 offset:45056
	v_max_f32_e32 v233, v233, v117
	s_waitcnt lgkmcnt(2)
	v_mfma_f32_16x16x32_bf16 v[122:125], v[170:173], v[80:83], v[122:125]
	v_mfma_f32_16x16x32_bf16 v[126:129], v[170:173], v[104:107], v[126:129]
	ds_read_b128 v[166:169], v203 offset:45056
	v_max3_f32 v234, v118, v119, v120
	s_waitcnt lgkmcnt(2)
	v_mfma_f32_16x16x32_bf16 v[122:125], v[174:177], v[84:87], v[122:125]
	v_mfma_f32_16x16x32_bf16 v[126:129], v[174:177], v[108:111], v[126:129]
	ds_read_b128 v[170:173], v202 offset:45184
	v_max_f32_e32 v234, v234, v121
	s_waitcnt lgkmcnt(2)
	v_mfma_f32_16x16x32_bf16 v[130:133], v[162:165], v[64:67], v[224:227]
	v_mfma_f32_16x16x32_bf16 v[134:137], v[162:165], v[88:91], v[228:231]
	ds_read_b128 v[174:177], v203 offset:45184
	s_waitcnt lgkmcnt(2)
	v_mfma_f32_16x16x32_bf16 v[130:133], v[166:169], v[68:71], v[130:133]
	v_mfma_f32_16x16x32_bf16 v[134:137], v[166:169], v[92:95], v[134:137]
	ds_read_b128 v[162:165], v202 offset:45312
	s_waitcnt lgkmcnt(2)
	v_mfma_f32_16x16x32_bf16 v[130:133], v[170:173], v[72:75], v[130:133]
	v_mfma_f32_16x16x32_bf16 v[134:137], v[170:173], v[96:99], v[134:137]
	ds_read_b128 v[166:169], v203 offset:45312
	v_max3_f32 v233, v233, v122, v123
	s_waitcnt lgkmcnt(2)
	v_mfma_f32_16x16x32_bf16 v[130:133], v[174:177], v[76:79], v[130:133]
	v_mfma_f32_16x16x32_bf16 v[134:137], v[174:177], v[100:103], v[134:137]
	ds_read_b128 v[170:173], v202 offset:51200
	v_max3_f32 v233, v233, v124, v125
	s_waitcnt lgkmcnt(2)
	v_mfma_f32_16x16x32_bf16 v[130:133], v[162:165], v[80:83], v[130:133]
	v_mfma_f32_16x16x32_bf16 v[134:137], v[162:165], v[104:107], v[134:137]
	ds_read_b128 v[174:177], v203 offset:51200
	v_max3_f32 v234, v234, v126, v127
	s_waitcnt lgkmcnt(2)
	v_mfma_f32_16x16x32_bf16 v[130:133], v[166:169], v[84:87], v[130:133]
	v_mfma_f32_16x16x32_bf16 v[134:137], v[166:169], v[108:111], v[134:137]
	ds_read_b128 v[162:165], v202 offset:51328
	v_max3_f32 v234, v234, v128, v129
	s_waitcnt lgkmcnt(2)
	v_mfma_f32_16x16x32_bf16 v[138:141], v[170:173], v[64:67], v[224:227]
	v_mfma_f32_16x16x32_bf16 v[142:145], v[170:173], v[88:91], v[228:231]
	ds_read_b128 v[166:169], v203 offset:51328
	s_waitcnt lgkmcnt(2)
	v_mfma_f32_16x16x32_bf16 v[138:141], v[174:177], v[68:71], v[138:141]
	v_mfma_f32_16x16x32_bf16 v[142:145], v[174:177], v[92:95], v[142:145]
	ds_read_b128 v[170:173], v202 offset:51456
	s_waitcnt lgkmcnt(2)
	v_mfma_f32_16x16x32_bf16 v[138:141], v[162:165], v[72:75], v[138:141]
	v_mfma_f32_16x16x32_bf16 v[142:145], v[162:165], v[96:99], v[142:145]
	ds_read_b128 v[174:177], v203 offset:51456
	v_max3_f32 v233, v233, v130, v131
	s_waitcnt lgkmcnt(2)
	v_mfma_f32_16x16x32_bf16 v[138:141], v[166:169], v[76:79], v[138:141]
	v_mfma_f32_16x16x32_bf16 v[142:145], v[166:169], v[100:103], v[142:145]
	v_max3_f32 v233, v233, v132, v133
	s_waitcnt lgkmcnt(1)
	v_mfma_f32_16x16x32_bf16 v[138:141], v[170:173], v[80:83], v[138:141]
	v_mfma_f32_16x16x32_bf16 v[142:145], v[170:173], v[104:107], v[142:145]
	v_max3_f32 v234, v234, v134, v135
	s_waitcnt lgkmcnt(0)
	v_mfma_f32_16x16x32_bf16 v[138:141], v[174:177], v[84:87], v[138:141]
	v_mfma_f32_16x16x32_bf16 v[142:145], v[174:177], v[108:111], v[142:145]
	v_max3_f32 v234, v234, v136, v137
	ds_read_b64_tr_b16 v[162:163], v206 offset:0
	ds_read_b64_tr_b16 v[164:165], v206 offset:4096
	ds_read_b64_tr_b16 v[166:167], v207 offset:0
	ds_read_b64_tr_b16 v[168:169], v207 offset:4096
	ds_read_b64_tr_b16 v[170:171], v208 offset:0
	ds_read_b64_tr_b16 v[172:173], v208 offset:4096
	s_nop 7
	v_max3_f32 v233, v233, v138, v139
	v_max3_f32 v233, v233, v140, v141
	v_max3_f32 v234, v234, v142, v143
	v_max3_f32 v234, v234, v144, v145
	s_branch .Lat_rare_0
; __device__ __forceinline__ void finishSM(f32x16& p0, f32x16& p1, float alpha, float& l_reg, bf16x8& pa0, bf16x8& pa1, bf16x8& pa2, bf16x8& pa3) {
; #pragma unroll
;   for (int r = 0; r < 16; ++r) p1[r] = __builtin_amdgcn_exp2f(p1[r]);
;   float ps = 0;
; #pragma unroll
;   for (int r = 0; r < 16; ++r) ps += p0[r];
; #pragma unroll
;   for (int r = 0; r < 16; ++r) ps += p1[r];
;   { auto rr = __builtin_amdgcn_permlane32_swap(__float_as_uint(ps), __float_as_uint(ps), false, false);
;     ps = __uint_as_float(rr[0]) + __uint_as_float(rr[1]); }
;   l_reg = l_reg * alpha + ps;
;     ...
;   PK4(p0, 0, pa0); PK4(p0, 8, pa1); PK4(p1, 0, pa2); PK4(p1, 8, pa3);
;     ...
; }
; __device__ __forceinline__ void qkt(f32x16& p0, f32x16& p1, const char* Ks, const bf16x8* qr, const char* qL, int r32, int hi, float negm) {
; #pragma unroll
;   for (int r = 0; r < 16; ++r) { p0[r] = negm; p1[r] = negm; }
; #pragma unroll
;   for (int d0 = 0; d0 < 12; ++d0) { int cb = (d0 * 16 + hi * 8) * 2;
;     bf16x8 b0 = *reinterpret_cast<const bf16x8*>(Ks + KSWZ(r32, cb));
;     bf16x8 b1 = *reinterpret_cast<const bf16x8*>(Ks + KSWZ(32 + r32, cb));
;     const bf16x8 q = d0 < 8 ? qr[d0 < 8 ? d0 : 0] : *reinterpret_cast<const bf16x8*>(qL + (d0 - 8) * 1024);
;     p0 = __builtin_amdgcn_mfma_f32_32x32x16_bf16(b0, q, p0, 0, 0, 0);
;     p1 = __builtin_amdgcn_mfma_f32_32x32x16_bf16(b1, q, p1, 0, 0, 0); }
; }
; __device__ __forceinline__ int v_st(int k, int c) { const int kk = (k & ~0xC) | ((k & 4) << 1) | ((k & 8) >> 1); return ((kk >> 3) * 4 + (c >> 5)) * 512 + ((kk & 7) * 32 + (c & 31)) * 2; }
; __device__ __forceinline__ int v_rd_base(int lane) { return ((lane & 3) << 3) | (((lane >> 2) & 3) << 6) | (((lane >> 4) & 1) << 5) | (((lane >> 5) & 1) << 8); }
; template <int OFF> __device__ __forceinline__ s16x4 tr_read(int vb) {
;   s16x4 r; asm volatile("ds_read_b64_tr_b16 %0, %1 offset:%2" : "=&v"(r) : "v"(vb), "i"(OFF) : "memory"); return r;
; }
; template <int D0> __device__ __forceinline__ void pv_one(f32x16& od, int vb, bf16x8 pa0, bf16x8 pa1, bf16x8 pa2, bf16x8 pa3) {
;   const s16x4 l0 = tr_read<v_rd_off(D0, 0, 0)>(vb), h0 = tr_read<v_rd_off(D0, 0, 1)>(vb), l1 = tr_read<v_rd_off(D0, 1, 0)>(vb), h1 = tr_read<v_rd_off(D0, 1, 1)>(vb);
;   const s16x4 l2 = tr_read<v_rd_off(D0, 2, 0)>(vb), h2 = tr_read<v_rd_off(D0, 2, 1)>(vb), l3 = tr_read<v_rd_off(D0, 3, 0)>(vb), h3 = tr_read<v_rd_off(D0, 3, 1)>(vb);
.Lat_cont_0:
	v_exp_f32_e32 v114, v114
	v_exp_f32_e32 v115, v115
	v_exp_f32_e32 v116, v116
	v_exp_f32_e32 v117, v117
	v_add_f32_e32 v222, v222, v114
	v_add_f32_e32 v222, v222, v115
	v_add_f32_e32 v222, v222, v116
	v_add_f32_e32 v222, v222, v117
	v_exp_f32_e32 v122, v122
	v_exp_f32_e32 v123, v123
	v_exp_f32_e32 v124, v124
	v_exp_f32_e32 v125, v125
	v_add_f32_e32 v222, v222, v122
	v_add_f32_e32 v222, v222, v123
	v_add_f32_e32 v222, v222, v124
	v_add_f32_e32 v222, v222, v125
	v_cvt_pk_bf16_f32 v146, v114, v115
	v_cvt_pk_bf16_f32 v147, v116, v117
	v_cvt_pk_bf16_f32 v148, v122, v123
	v_cvt_pk_bf16_f32 v149, v124, v125
	v_exp_f32_e32 v118, v118
	v_exp_f32_e32 v119, v119
	v_exp_f32_e32 v120, v120
	v_exp_f32_e32 v121, v121
	v_add_f32_e32 v223, v223, v118
	v_add_f32_e32 v223, v223, v119
	v_add_f32_e32 v223, v223, v120
	v_add_f32_e32 v223, v223, v121
	v_exp_f32_e32 v126, v126
	v_exp_f32_e32 v127, v127
	v_exp_f32_e32 v128, v128
	v_exp_f32_e32 v129, v129
	v_add_f32_e32 v223, v223, v126
	v_add_f32_e32 v223, v223, v127
	v_add_f32_e32 v223, v223, v128
	v_add_f32_e32 v223, v223, v129
	v_cvt_pk_bf16_f32 v154, v118, v119
	v_cvt_pk_bf16_f32 v155, v120, v121
	v_cvt_pk_bf16_f32 v156, v126, v127
	v_cvt_pk_bf16_f32 v157, v128, v129
	s_nop 1
	s_waitcnt lgkmcnt(4)
	v_mfma_f32_16x16x32_bf16 v[0:3], v[146:149], v[162:165], v[0:3]
	v_mfma_f32_16x16x32_bf16 v[32:35], v[154:157], v[162:165], v[32:35]
	ds_read_b64_tr_b16 v[174:175], v209 offset:0
	ds_read_b64_tr_b16 v[176:177], v209 offset:4096
	v_exp_f32_e32 v130, v130
	v_exp_f32_e32 v131, v131
	v_exp_f32_e32 v132, v132
	v_exp_f32_e32 v133, v133
	v_add_f32_e32 v222, v222, v130
	s_waitcnt lgkmcnt(4)
	v_mfma_f32_16x16x32_bf16 v[4:7], v[146:149], v[166:169], v[4:7]
	v_mfma_f32_16x16x32_bf16 v[36:39], v[154:157], v[166:169], v[36:39]
	ds_read_b64_tr_b16 v[162:163], v210 offset:0
	ds_read_b64_tr_b16 v[164:165], v210 offset:4096
	v_add_f32_e32 v222, v222, v131
	v_add_f32_e32 v222, v222, v132
	v_add_f32_e32 v222, v222, v133
	v_exp_f32_e32 v138, v138
	v_exp_f32_e32 v139, v139
	s_waitcnt lgkmcnt(4)
	v_mfma_f32_16x16x32_bf16 v[8:11], v[146:149], v[170:173], v[8:11]
	v_mfma_f32_16x16x32_bf16 v[40:43], v[154:157], v[170:173], v[40:43]
	ds_read_b64_tr_b16 v[166:167], v211 offset:0
	ds_read_b64_tr_b16 v[168:169], v211 offset:4096
	v_exp_f32_e32 v140, v140
	v_exp_f32_e32 v141, v141
	v_add_f32_e32 v222, v222, v138
	v_add_f32_e32 v222, v222, v139
	v_add_f32_e32 v222, v222, v140
	s_waitcnt lgkmcnt(4)
	v_mfma_f32_16x16x32_bf16 v[12:15], v[146:149], v[174:177], v[12:15]
	v_mfma_f32_16x16x32_bf16 v[44:47], v[154:157], v[174:177], v[44:47]
	ds_read_b64_tr_b16 v[170:171], v212 offset:0
	ds_read_b64_tr_b16 v[172:173], v212 offset:4096
	v_add_f32_e32 v222, v222, v141
	v_cvt_pk_bf16_f32 v150, v130, v131
	v_cvt_pk_bf16_f32 v151, v132, v133
	v_cvt_pk_bf16_f32 v152, v138, v139
	v_cvt_pk_bf16_f32 v153, v140, v141
	s_waitcnt lgkmcnt(4)
	v_mfma_f32_16x16x32_bf16 v[16:19], v[146:149], v[162:165], v[16:19]
	v_mfma_f32_16x16x32_bf16 v[48:51], v[154:157], v[162:165], v[48:51]
	ds_read_b64_tr_b16 v[174:175], v213 offset:0
	ds_read_b64_tr_b16 v[176:177], v213 offset:4096
	v_exp_f32_e32 v134, v134
	v_exp_f32_e32 v135, v135
	v_exp_f32_e32 v136, v136
	v_exp_f32_e32 v137, v137
	v_add_f32_e32 v223, v223, v134
	s_waitcnt lgkmcnt(4)
	v_mfma_f32_16x16x32_bf16 v[20:23], v[146:149], v[166:169], v[20:23]
	v_mfma_f32_16x16x32_bf16 v[52:55], v[154:157], v[166:169], v[52:55]
	ds_read_b64_tr_b16 v[162:163], v206 offset:8192
	ds_read_b64_tr_b16 v[164:165], v206 offset:12288
	v_add_f32_e32 v223, v223, v135
	v_add_f32_e32 v223, v223, v136
	v_add_f32_e32 v223, v223, v137
	v_exp_f32_e32 v142, v142
	v_exp_f32_e32 v143, v143
	s_waitcnt lgkmcnt(4)
	v_mfma_f32_16x16x32_bf16 v[24:27], v[146:149], v[170:173], v[24:27]
	v_mfma_f32_16x16x32_bf16 v[56:59], v[154:157], v[170:173], v[56:59]
	ds_read_b64_tr_b16 v[166:167], v207 offset:8192
	ds_read_b64_tr_b16 v[168:169], v207 offset:12288
	v_exp_f32_e32 v144, v144
	v_exp_f32_e32 v145, v145
	v_add_f32_e32 v223, v223, v142
	v_add_f32_e32 v223, v223, v143
	v_add_f32_e32 v223, v223, v144
	s_waitcnt lgkmcnt(4)
	v_mfma_f32_16x16x32_bf16 v[28:31], v[146:149], v[174:177], v[28:31]
	v_mfma_f32_16x16x32_bf16 v[60:63], v[154:157], v[174:177], v[60:63]
	ds_read_b64_tr_b16 v[170:171], v208 offset:8192
	ds_read_b64_tr_b16 v[172:173], v208 offset:12288
	v_add_f32_e32 v223, v223, v145
	v_cvt_pk_bf16_f32 v158, v134, v135
	v_cvt_pk_bf16_f32 v159, v136, v137
	v_cvt_pk_bf16_f32 v160, v142, v143
	v_cvt_pk_bf16_f32 v161, v144, v145
	s_waitcnt lgkmcnt(4)
	s_nop 1
	v_mfma_f32_16x16x32_bf16 v[0:3], v[150:153], v[162:165], v[0:3]
	v_mfma_f32_16x16x32_bf16 v[32:35], v[158:161], v[162:165], v[32:35]
	ds_read_b64_tr_b16 v[174:175], v209 offset:8192
	ds_read_b64_tr_b16 v[176:177], v209 offset:12288
	s_waitcnt lgkmcnt(4)
	v_mfma_f32_16x16x32_bf16 v[4:7], v[150:153], v[166:169], v[4:7]
	v_mfma_f32_16x16x32_bf16 v[36:39], v[158:161], v[166:169], v[36:39]
	ds_read_b64_tr_b16 v[162:163], v210 offset:8192
	ds_read_b64_tr_b16 v[164:165], v210 offset:12288
	s_waitcnt lgkmcnt(4)
	v_mfma_f32_16x16x32_bf16 v[8:11], v[150:153], v[170:173], v[8:11]
	v_mfma_f32_16x16x32_bf16 v[40:43], v[158:161], v[170:173], v[40:43]
	ds_read_b64_tr_b16 v[166:167], v211 offset:8192
	ds_read_b64_tr_b16 v[168:169], v211 offset:12288
	s_waitcnt lgkmcnt(4)
	v_mfma_f32_16x16x32_bf16 v[12:15], v[150:153], v[174:177], v[12:15]
	v_mfma_f32_16x16x32_bf16 v[44:47], v[158:161], v[174:177], v[44:47]
	ds_read_b64_tr_b16 v[170:171], v212 offset:8192
	ds_read_b64_tr_b16 v[172:173], v212 offset:12288
	s_waitcnt lgkmcnt(4)
	v_mfma_f32_16x16x32_bf16 v[16:19], v[150:153], v[162:165], v[16:19]
	v_mfma_f32_16x16x32_bf16 v[48:51], v[158:161], v[162:165], v[48:51]
	ds_read_b64_tr_b16 v[174:175], v213 offset:8192
	ds_read_b64_tr_b16 v[176:177], v213 offset:12288
	s_waitcnt lgkmcnt(4)
	v_mfma_f32_16x16x32_bf16 v[20:23], v[150:153], v[166:169], v[20:23]
	v_mfma_f32_16x16x32_bf16 v[52:55], v[158:161], v[166:169], v[52:55]
	s_waitcnt lgkmcnt(2)
	v_mfma_f32_16x16x32_bf16 v[24:27], v[150:153], v[170:173], v[24:27]
	v_mfma_f32_16x16x32_bf16 v[56:59], v[158:161], v[170:173], v[56:59]
	s_waitcnt lgkmcnt(0)
	v_mfma_f32_16x16x32_bf16 v[28:31], v[150:153], v[174:177], v[28:31]
	v_mfma_f32_16x16x32_bf16 v[60:63], v[158:161], v[174:177], v[60:63]
	s_waitcnt vmcnt(0)
	ds_write_b128 v214, v[178:181] offset:57344
	ds_write_b128 v215, v[182:185] offset:57344
	ds_write_b128 v216, v[196:199] offset:57344
	ds_write_b128 v217, v[186:189] offset:16384
	ds_write_b128 v217, v[190:193] offset:24576
	global_load_dwordx4 v[178:181], v218, s[22:23]
	global_load_dwordx4 v[182:185], v218, s[24:25]
	global_load_dwordx4 v[196:199], v218, s[34:35]
	global_load_dwordx4 v[186:189], v218, s[26:27]
	global_load_dwordx4 v[190:193], v218, s[30:31]
	s_add_u32 s22, s22, 16384
	s_addc_u32 s23, s23, 0
	s_add_u32 s24, s24, 16384
	s_addc_u32 s25, s25, 0
	s_add_u32 s26, s26, 16384
	s_addc_u32 s27, s27, 0
	s_add_u32 s30, s30, 16384
	s_addc_u32 s31, s31, 0
	s_add_u32 s34, s34, 8192
	s_addc_u32 s35, s35, 0
	s_waitcnt lgkmcnt(0)
	s_barrier
; template <bool FIRST>
; __device__ __forceinline__ void partialSM(f32x16& p0, f32x16& p1, float& m_reg, float& alpha) {
;   constexpr float THR2 = THR * 1.4426950408889634f;
;   float pmax = p0[0];
; #pragma unroll
;   for (int r = 1; r < 16; ++r) pmax = fmaxf(pmax, p0[r]);
; #pragma unroll
;   for (int r = 0; r < 16; ++r) pmax = fmaxf(pmax, p1[r]);
;   { auto rr = __builtin_amdgcn_permlane32_swap(__float_as_uint(pmax), __float_as_uint(pmax), false, false);
;     pmax = fmaxf(__uint_as_float(rr[0]), __uint_as_float(rr[1])); }
;   if (!FIRST && __builtin_expect(__all(pmax <= THR2), 1)) { alpha = 1.f; }
;   else { const float d = FIRST ? pmax : fmaxf(pmax, 0.f); alpha = FIRST ? 1.f : __builtin_amdgcn_exp2f(-d); m_reg += d;
; #pragma unroll
;     for (int r = 0; r < 16; ++r) p0[r] -= d;
; #pragma unroll
;     for (int r = 0; r < 16; ++r) p1[r] -= d; }
; #pragma unroll
;   for (int r = 0; r < 16; ++r) p0[r] = __builtin_amdgcn_exp2f(p0[r]);
; }
; __device__ __forceinline__ void finishSM(f32x16& p0, f32x16& p1, float alpha, float& l_reg, bf16x8& pa0, bf16x8& pa1, bf16x8& pa2, bf16x8& pa3) {
; #pragma unroll
;   for (int r = 0; r < 16; ++r) p1[r] = __builtin_amdgcn_exp2f(p1[r]);
;   float ps = 0;
; #pragma unroll
;   for (int r = 0; r < 16; ++r) ps += p0[r];
; #pragma unroll
;   for (int r = 0; r < 16; ++r) ps += p1[r];
;   { auto rr = __builtin_amdgcn_permlane32_swap(__float_as_uint(ps), __float_as_uint(ps), false, false);
;     ps = __uint_as_float(rr[0]) + __uint_as_float(rr[1]); }
;   l_reg = l_reg * alpha + ps;
;     ...
;   PK4(p0, 0, pa0); PK4(p0, 8, pa1); PK4(p1, 0, pa2); PK4(p1, 8, pa3);
;     ...
; }
; __device__ __forceinline__ void qkt(f32x16& p0, f32x16& p1, const char* Ks, const bf16x8* qr, const char* qL, int r32, int hi, float negm) {
; #pragma unroll
;   for (int r = 0; r < 16; ++r) { p0[r] = negm; p1[r] = negm; }
; #pragma unroll
;   for (int d0 = 0; d0 < 12; ++d0) { int cb = (d0 * 16 + hi * 8) * 2;
;     bf16x8 b0 = *reinterpret_cast<const bf16x8*>(Ks + KSWZ(r32, cb));
;     bf16x8 b1 = *reinterpret_cast<const bf16x8*>(Ks + KSWZ(32 + r32, cb));
;     const bf16x8 q = d0 < 8 ? qr[d0 < 8 ? d0 : 0] : *reinterpret_cast<const bf16x8*>(qL + (d0 - 8) * 1024);
;     p0 = __builtin_amdgcn_mfma_f32_32x32x16_bf16(b0, q, p0, 0, 0, 0);
;     p1 = __builtin_amdgcn_mfma_f32_32x32x16_bf16(b1, q, p1, 0, 0, 0); }
; }
	s_movk_i32 s39, 127
.Lat_loop:
	ds_read_b128 v[162:165], v204 offset:32768
	ds_read_b128 v[166:169], v205 offset:32768
	ds_read_b128 v[170:173], v204 offset:32896
	s_waitcnt lgkmcnt(2)
	v_mfma_f32_16x16x32_bf16 v[114:117], v[162:165], v[64:67], v[224:227]
	v_mfma_f32_16x16x32_bf16 v[118:121], v[162:165], v[88:91], v[228:231]
	ds_read_b128 v[174:177], v205 offset:32896
	s_waitcnt lgkmcnt(2)
	v_mfma_f32_16x16x32_bf16 v[114:117], v[166:169], v[68:71], v[114:117]
	v_mfma_f32_16x16x32_bf16 v[118:121], v[166:169], v[92:95], v[118:121]
	ds_read_b128 v[162:165], v204 offset:33024
	s_waitcnt lgkmcnt(2)
	v_mfma_f32_16x16x32_bf16 v[114:117], v[170:173], v[72:75], v[114:117]
	v_mfma_f32_16x16x32_bf16 v[118:121], v[170:173], v[96:99], v[118:121]
	ds_read_b128 v[166:169], v205 offset:33024
	s_waitcnt lgkmcnt(2)
	v_mfma_f32_16x16x32_bf16 v[114:117], v[174:177], v[76:79], v[114:117]
	v_mfma_f32_16x16x32_bf16 v[118:121], v[174:177], v[100:103], v[118:121]
	ds_read_b128 v[170:173], v204 offset:38912
	s_waitcnt lgkmcnt(2)
	v_mfma_f32_16x16x32_bf16 v[114:117], v[162:165], v[80:83], v[114:117]
	v_mfma_f32_16x16x32_bf16 v[118:121], v[162:165], v[104:107], v[118:121]
	ds_read_b128 v[174:177], v205 offset:38912
	s_waitcnt lgkmcnt(2)
	v_mfma_f32_16x16x32_bf16 v[114:117], v[166:169], v[84:87], v[114:117]
	v_mfma_f32_16x16x32_bf16 v[118:121], v[166:169], v[108:111], v[118:121]
	ds_read_b128 v[162:165], v204 offset:39040
	s_waitcnt lgkmcnt(2)
	v_mfma_f32_16x16x32_bf16 v[122:125], v[170:173], v[64:67], v[224:227]
	v_mfma_f32_16x16x32_bf16 v[126:129], v[170:173], v[88:91], v[228:231]
	ds_read_b128 v[166:169], v205 offset:39040
	s_waitcnt lgkmcnt(2)
	v_mfma_f32_16x16x32_bf16 v[122:125], v[174:177], v[68:71], v[122:125]
	v_mfma_f32_16x16x32_bf16 v[126:129], v[174:177], v[92:95], v[126:129]
	ds_read_b128 v[170:173], v204 offset:39168
	s_waitcnt lgkmcnt(2)
	v_mfma_f32_16x16x32_bf16 v[122:125], v[162:165], v[72:75], v[122:125]
	v_mfma_f32_16x16x32_bf16 v[126:129], v[162:165], v[96:99], v[126:129]
	ds_read_b128 v[174:177], v205 offset:39168
	v_max3_f32 v233, v114, v115, v116
	s_waitcnt lgkmcnt(2)
	v_mfma_f32_16x16x32_bf16 v[122:125], v[166:169], v[76:79], v[122:125]
	v_mfma_f32_16x16x32_bf16 v[126:129], v[166:169], v[100:103], v[126:129]
	ds_read_b128 v[162:165], v204 offset:45056
	v_max_f32_e32 v233, v233, v117
	s_waitcnt lgkmcnt(2)
	v_mfma_f32_16x16x32_bf16 v[122:125], v[170:173], v[80:83], v[122:125]
	v_mfma_f32_16x16x32_bf16 v[126:129], v[170:173], v[104:107], v[126:129]
	ds_read_b128 v[166:169], v205 offset:45056
	v_max3_f32 v234, v118, v119, v120
	s_waitcnt lgkmcnt(2)
	v_mfma_f32_16x16x32_bf16 v[122:125], v[174:177], v[84:87], v[122:125]
	v_mfma_f32_16x16x32_bf16 v[126:129], v[174:177], v[108:111], v[126:129]
	ds_read_b128 v[170:173], v204 offset:45184
	v_max_f32_e32 v234, v234, v121
	s_waitcnt lgkmcnt(2)
	v_mfma_f32_16x16x32_bf16 v[130:133], v[162:165], v[64:67], v[224:227]
	v_mfma_f32_16x16x32_bf16 v[134:137], v[162:165], v[88:91], v[228:231]
	ds_read_b128 v[174:177], v205 offset:45184
	s_waitcnt lgkmcnt(2)
	v_mfma_f32_16x16x32_bf16 v[130:133], v[166:169], v[68:71], v[130:133]
	v_mfma_f32_16x16x32_bf16 v[134:137], v[166:169], v[92:95], v[134:137]
	ds_read_b128 v[162:165], v204 offset:45312
	s_waitcnt lgkmcnt(2)
	v_mfma_f32_16x16x32_bf16 v[130:133], v[170:173], v[72:75], v[130:133]
	v_mfma_f32_16x16x32_bf16 v[134:137], v[170:173], v[96:99], v[134:137]
	ds_read_b128 v[166:169], v205 offset:45312
	v_max3_f32 v233, v233, v122, v123
	s_waitcnt lgkmcnt(2)
	v_mfma_f32_16x16x32_bf16 v[130:133], v[174:177], v[76:79], v[130:133]
	v_mfma_f32_16x16x32_bf16 v[134:137], v[174:177], v[100:103], v[134:137]
	ds_read_b128 v[170:173], v204 offset:51200
	v_max3_f32 v233, v233, v124, v125
	s_waitcnt lgkmcnt(2)
	v_mfma_f32_16x16x32_bf16 v[130:133], v[162:165], v[80:83], v[130:133]
	v_mfma_f32_16x16x32_bf16 v[134:137], v[162:165], v[104:107], v[134:137]
	ds_read_b128 v[174:177], v205 offset:51200
	v_max3_f32 v234, v234, v126, v127
	s_waitcnt lgkmcnt(2)
	v_mfma_f32_16x16x32_bf16 v[130:133], v[166:169], v[84:87], v[130:133]
	v_mfma_f32_16x16x32_bf16 v[134:137], v[166:169], v[108:111], v[134:137]
	ds_read_b128 v[162:165], v204 offset:51328
	v_max3_f32 v234, v234, v128, v129
	s_waitcnt lgkmcnt(2)
	v_mfma_f32_16x16x32_bf16 v[138:141], v[170:173], v[64:67], v[224:227]
	v_mfma_f32_16x16x32_bf16 v[142:145], v[170:173], v[88:91], v[228:231]
	ds_read_b128 v[166:169], v205 offset:51328
	s_waitcnt lgkmcnt(2)
	v_mfma_f32_16x16x32_bf16 v[138:141], v[174:177], v[68:71], v[138:141]
	v_mfma_f32_16x16x32_bf16 v[142:145], v[174:177], v[92:95], v[142:145]
	ds_read_b128 v[170:173], v204 offset:51456
	s_waitcnt lgkmcnt(2)
	v_mfma_f32_16x16x32_bf16 v[138:141], v[162:165], v[72:75], v[138:141]
	v_mfma_f32_16x16x32_bf16 v[142:145], v[162:165], v[96:99], v[142:145]
	ds_read_b128 v[174:177], v205 offset:51456
	v_max3_f32 v233, v233, v130, v131
	s_waitcnt lgkmcnt(2)
	v_mfma_f32_16x16x32_bf16 v[138:141], v[166:169], v[76:79], v[138:141]
	v_mfma_f32_16x16x32_bf16 v[142:145], v[166:169], v[100:103], v[142:145]
	v_max3_f32 v233, v233, v132, v133
	s_waitcnt lgkmcnt(1)
	v_mfma_f32_16x16x32_bf16 v[138:141], v[170:173], v[80:83], v[138:141]
	v_mfma_f32_16x16x32_bf16 v[142:145], v[170:173], v[104:107], v[142:145]
	v_max3_f32 v234, v234, v134, v135
	s_waitcnt lgkmcnt(0)
	v_mfma_f32_16x16x32_bf16 v[138:141], v[174:177], v[84:87], v[138:141]
	v_mfma_f32_16x16x32_bf16 v[142:145], v[174:177], v[108:111], v[142:145]
	v_max3_f32 v234, v234, v136, v137
	ds_read_b64_tr_b16 v[162:163], v206 offset:16384
	ds_read_b64_tr_b16 v[164:165], v206 offset:20480
	ds_read_b64_tr_b16 v[166:167], v207 offset:16384
	ds_read_b64_tr_b16 v[168:169], v207 offset:20480
	ds_read_b64_tr_b16 v[170:171], v208 offset:16384
	ds_read_b64_tr_b16 v[172:173], v208 offset:20480
	s_nop 7
	v_max3_f32 v233, v233, v138, v139
	v_max3_f32 v233, v233, v140, v141
	v_max3_f32 v234, v234, v142, v143
	v_max3_f32 v234, v234, v144, v145
	v_max_f32_e32 v235, v233, v234
	v_cmp_ge_f32_e32 vcc, s38, v235
	s_cmp_eq_u64 vcc, exec
	s_cbranch_scc0 .Lat_rare_1
; __device__ __forceinline__ void finishSM(f32x16& p0, f32x16& p1, float alpha, float& l_reg, bf16x8& pa0, bf16x8& pa1, bf16x8& pa2, bf16x8& pa3) {
; #pragma unroll
;   for (int r = 0; r < 16; ++r) p1[r] = __builtin_amdgcn_exp2f(p1[r]);
;   float ps = 0;
; #pragma unroll
;   for (int r = 0; r < 16; ++r) ps += p0[r];
; #pragma unroll
;   for (int r = 0; r < 16; ++r) ps += p1[r];
;   { auto rr = __builtin_amdgcn_permlane32_swap(__float_as_uint(ps), __float_as_uint(ps), false, false);
;     ps = __uint_as_float(rr[0]) + __uint_as_float(rr[1]); }
;   l_reg = l_reg * alpha + ps;
;     ...
;   PK4(p0, 0, pa0); PK4(p0, 8, pa1); PK4(p1, 0, pa2); PK4(p1, 8, pa3);
;     ...
; }
; __device__ __forceinline__ void qkt(f32x16& p0, f32x16& p1, const char* Ks, const bf16x8* qr, const char* qL, int r32, int hi, float negm) {
; #pragma unroll
;   for (int r = 0; r < 16; ++r) { p0[r] = negm; p1[r] = negm; }
; #pragma unroll
;   for (int d0 = 0; d0 < 12; ++d0) { int cb = (d0 * 16 + hi * 8) * 2;
;     bf16x8 b0 = *reinterpret_cast<const bf16x8*>(Ks + KSWZ(r32, cb));
;     bf16x8 b1 = *reinterpret_cast<const bf16x8*>(Ks + KSWZ(32 + r32, cb));
;     const bf16x8 q = d0 < 8 ? qr[d0 < 8 ? d0 : 0] : *reinterpret_cast<const bf16x8*>(qL + (d0 - 8) * 1024);
;     p0 = __builtin_amdgcn_mfma_f32_32x32x16_bf16(b0, q, p0, 0, 0, 0);
;     p1 = __builtin_amdgcn_mfma_f32_32x32x16_bf16(b1, q, p1, 0, 0, 0); }
; }
; __device__ __forceinline__ int v_st(int k, int c) { const int kk = (k & ~0xC) | ((k & 4) << 1) | ((k & 8) >> 1); return ((kk >> 3) * 4 + (c >> 5)) * 512 + ((kk & 7) * 32 + (c & 31)) * 2; }
; __device__ __forceinline__ int v_rd_base(int lane) { return ((lane & 3) << 3) | (((lane >> 2) & 3) << 6) | (((lane >> 4) & 1) << 5) | (((lane >> 5) & 1) << 8); }
; template <int OFF> __device__ __forceinline__ s16x4 tr_read(int vb) {
;   s16x4 r; asm volatile("ds_read_b64_tr_b16 %0, %1 offset:%2" : "=&v"(r) : "v"(vb), "i"(OFF) : "memory"); return r;
; }
; template <int D0> __device__ __forceinline__ void pv_one(f32x16& od, int vb, bf16x8 pa0, bf16x8 pa1, bf16x8 pa2, bf16x8 pa3) {
;   const s16x4 l0 = tr_read<v_rd_off(D0, 0, 0)>(vb), h0 = tr_read<v_rd_off(D0, 0, 1)>(vb), l1 = tr_read<v_rd_off(D0, 1, 0)>(vb), h1 = tr_read<v_rd_off(D0, 1, 1)>(vb);
;   const s16x4 l2 = tr_read<v_rd_off(D0, 2, 0)>(vb), h2 = tr_read<v_rd_off(D0, 2, 1)>(vb), l3 = tr_read<v_rd_off(D0, 3, 0)>(vb), h3 = tr_read<v_rd_off(D0, 3, 1)>(vb);
.Lat_cont_1:
	v_exp_f32_e32 v114, v114
	v_exp_f32_e32 v115, v115
	v_exp_f32_e32 v116, v116
	v_exp_f32_e32 v117, v117
	v_add_f32_e32 v222, v222, v114
	v_add_f32_e32 v222, v222, v115
	v_add_f32_e32 v222, v222, v116
	v_add_f32_e32 v222, v222, v117
	v_exp_f32_e32 v122, v122
	v_exp_f32_e32 v123, v123
	v_exp_f32_e32 v124, v124
	v_exp_f32_e32 v125, v125
	v_add_f32_e32 v222, v222, v122
	v_add_f32_e32 v222, v222, v123
	v_add_f32_e32 v222, v222, v124
	v_add_f32_e32 v222, v222, v125
	v_cvt_pk_bf16_f32 v146, v114, v115
	v_cvt_pk_bf16_f32 v147, v116, v117
	v_cvt_pk_bf16_f32 v148, v122, v123
	v_cvt_pk_bf16_f32 v149, v124, v125
	v_exp_f32_e32 v118, v118
	v_exp_f32_e32 v119, v119
	v_exp_f32_e32 v120, v120
	v_exp_f32_e32 v121, v121
	v_add_f32_e32 v223, v223, v118
	v_add_f32_e32 v223, v223, v119
	v_add_f32_e32 v223, v223, v120
	v_add_f32_e32 v223, v223, v121
	v_exp_f32_e32 v126, v126
	v_exp_f32_e32 v127, v127
	v_exp_f32_e32 v128, v128
	v_exp_f32_e32 v129, v129
	v_add_f32_e32 v223, v223, v126
	v_add_f32_e32 v223, v223, v127
	v_add_f32_e32 v223, v223, v128
	v_add_f32_e32 v223, v223, v129
	v_cvt_pk_bf16_f32 v154, v118, v119
	v_cvt_pk_bf16_f32 v155, v120, v121
	v_cvt_pk_bf16_f32 v156, v126, v127
	v_cvt_pk_bf16_f32 v157, v128, v129
	s_nop 1
	s_waitcnt lgkmcnt(4)
	v_mfma_f32_16x16x32_bf16 v[0:3], v[146:149], v[162:165], v[0:3]
	v_mfma_f32_16x16x32_bf16 v[32:35], v[154:157], v[162:165], v[32:35]
	ds_read_b64_tr_b16 v[174:175], v209 offset:16384
	ds_read_b64_tr_b16 v[176:177], v209 offset:20480
	v_exp_f32_e32 v130, v130
	v_exp_f32_e32 v131, v131
	v_exp_f32_e32 v132, v132
	v_exp_f32_e32 v133, v133
	v_add_f32_e32 v222, v222, v130
	s_waitcnt lgkmcnt(4)
	v_mfma_f32_16x16x32_bf16 v[4:7], v[146:149], v[166:169], v[4:7]
	v_mfma_f32_16x16x32_bf16 v[36:39], v[154:157], v[166:169], v[36:39]
	ds_read_b64_tr_b16 v[162:163], v210 offset:16384
	ds_read_b64_tr_b16 v[164:165], v210 offset:20480
	v_add_f32_e32 v222, v222, v131
	v_add_f32_e32 v222, v222, v132
	v_add_f32_e32 v222, v222, v133
	v_exp_f32_e32 v138, v138
	v_exp_f32_e32 v139, v139
	s_waitcnt lgkmcnt(4)
	v_mfma_f32_16x16x32_bf16 v[8:11], v[146:149], v[170:173], v[8:11]
	v_mfma_f32_16x16x32_bf16 v[40:43], v[154:157], v[170:173], v[40:43]
	ds_read_b64_tr_b16 v[166:167], v211 offset:16384
	ds_read_b64_tr_b16 v[168:169], v211 offset:20480
	v_exp_f32_e32 v140, v140
	v_exp_f32_e32 v141, v141
	v_add_f32_e32 v222, v222, v138
	v_add_f32_e32 v222, v222, v139
	v_add_f32_e32 v222, v222, v140
	s_waitcnt lgkmcnt(4)
	v_mfma_f32_16x16x32_bf16 v[12:15], v[146:149], v[174:177], v[12:15]
	v_mfma_f32_16x16x32_bf16 v[44:47], v[154:157], v[174:177], v[44:47]
	ds_read_b64_tr_b16 v[170:171], v212 offset:16384
	ds_read_b64_tr_b16 v[172:173], v212 offset:20480
	v_add_f32_e32 v222, v222, v141
	v_cvt_pk_bf16_f32 v150, v130, v131
	v_cvt_pk_bf16_f32 v151, v132, v133
	v_cvt_pk_bf16_f32 v152, v138, v139
	v_cvt_pk_bf16_f32 v153, v140, v141
	s_waitcnt lgkmcnt(4)
	v_mfma_f32_16x16x32_bf16 v[16:19], v[146:149], v[162:165], v[16:19]
	v_mfma_f32_16x16x32_bf16 v[48:51], v[154:157], v[162:165], v[48:51]
	ds_read_b64_tr_b16 v[174:175], v213 offset:16384
	ds_read_b64_tr_b16 v[176:177], v213 offset:20480
	v_exp_f32_e32 v134, v134
	v_exp_f32_e32 v135, v135
	v_exp_f32_e32 v136, v136
	v_exp_f32_e32 v137, v137
	v_add_f32_e32 v223, v223, v134
	s_waitcnt lgkmcnt(4)
	v_mfma_f32_16x16x32_bf16 v[20:23], v[146:149], v[166:169], v[20:23]
	v_mfma_f32_16x16x32_bf16 v[52:55], v[154:157], v[166:169], v[52:55]
	ds_read_b64_tr_b16 v[162:163], v206 offset:24576
	ds_read_b64_tr_b16 v[164:165], v206 offset:28672
	v_add_f32_e32 v223, v223, v135
	v_add_f32_e32 v223, v223, v136
	v_add_f32_e32 v223, v223, v137
	v_exp_f32_e32 v142, v142
	v_exp_f32_e32 v143, v143
	s_waitcnt lgkmcnt(4)
	v_mfma_f32_16x16x32_bf16 v[24:27], v[146:149], v[170:173], v[24:27]
	v_mfma_f32_16x16x32_bf16 v[56:59], v[154:157], v[170:173], v[56:59]
	ds_read_b64_tr_b16 v[166:167], v207 offset:24576
	ds_read_b64_tr_b16 v[168:169], v207 offset:28672
	v_exp_f32_e32 v144, v144
	v_exp_f32_e32 v145, v145
	v_add_f32_e32 v223, v223, v142
	v_add_f32_e32 v223, v223, v143
	v_add_f32_e32 v223, v223, v144
	s_waitcnt lgkmcnt(4)
	v_mfma_f32_16x16x32_bf16 v[28:31], v[146:149], v[174:177], v[28:31]
	v_mfma_f32_16x16x32_bf16 v[60:63], v[154:157], v[174:177], v[60:63]
	ds_read_b64_tr_b16 v[170:171], v208 offset:24576
	ds_read_b64_tr_b16 v[172:173], v208 offset:28672
	v_add_f32_e32 v223, v223, v145
	v_cvt_pk_bf16_f32 v158, v134, v135
	v_cvt_pk_bf16_f32 v159, v136, v137
	v_cvt_pk_bf16_f32 v160, v142, v143
	v_cvt_pk_bf16_f32 v161, v144, v145
	s_waitcnt lgkmcnt(4)
	s_nop 1
	v_mfma_f32_16x16x32_bf16 v[0:3], v[150:153], v[162:165], v[0:3]
	v_mfma_f32_16x16x32_bf16 v[32:35], v[158:161], v[162:165], v[32:35]
	ds_read_b64_tr_b16 v[174:175], v209 offset:24576
	ds_read_b64_tr_b16 v[176:177], v209 offset:28672
	s_waitcnt lgkmcnt(4)
	v_mfma_f32_16x16x32_bf16 v[4:7], v[150:153], v[166:169], v[4:7]
	v_mfma_f32_16x16x32_bf16 v[36:39], v[158:161], v[166:169], v[36:39]
	ds_read_b64_tr_b16 v[162:163], v210 offset:24576
	ds_read_b64_tr_b16 v[164:165], v210 offset:28672
	s_waitcnt lgkmcnt(4)
	v_mfma_f32_16x16x32_bf16 v[8:11], v[150:153], v[170:173], v[8:11]
	v_mfma_f32_16x16x32_bf16 v[40:43], v[158:161], v[170:173], v[40:43]
	ds_read_b64_tr_b16 v[166:167], v211 offset:24576
	ds_read_b64_tr_b16 v[168:169], v211 offset:28672
	s_waitcnt lgkmcnt(4)
	v_mfma_f32_16x16x32_bf16 v[12:15], v[150:153], v[174:177], v[12:15]
	v_mfma_f32_16x16x32_bf16 v[44:47], v[158:161], v[174:177], v[44:47]
	ds_read_b64_tr_b16 v[170:171], v212 offset:24576
	ds_read_b64_tr_b16 v[172:173], v212 offset:28672
	s_waitcnt lgkmcnt(4)
; __device__ __forceinline__ void qkt(f32x16& p0, f32x16& p1, const char* Ks, const bf16x8* qr, const char* qL, int r32, int hi, float negm) {
; #pragma unroll
;   for (int r = 0; r < 16; ++r) { p0[r] = negm; p1[r] = negm; }
; #pragma unroll
;   for (int d0 = 0; d0 < 12; ++d0) { int cb = (d0 * 16 + hi * 8) * 2;
;     bf16x8 b0 = *reinterpret_cast<const bf16x8*>(Ks + KSWZ(r32, cb));
;     bf16x8 b1 = *reinterpret_cast<const bf16x8*>(Ks + KSWZ(32 + r32, cb));
;     const bf16x8 q = d0 < 8 ? qr[d0 < 8 ? d0 : 0] : *reinterpret_cast<const bf16x8*>(qL + (d0 - 8) * 1024);
;     p0 = __builtin_amdgcn_mfma_f32_32x32x16_bf16(b0, q, p0, 0, 0, 0);
;     p1 = __builtin_amdgcn_mfma_f32_32x32x16_bf16(b1, q, p1, 0, 0, 0); }
; }
; __device__ __forceinline__ int v_st(int k, int c) { const int kk = (k & ~0xC) | ((k & 4) << 1) | ((k & 8) >> 1); return ((kk >> 3) * 4 + (c >> 5)) * 512 + ((kk & 7) * 32 + (c & 31)) * 2; }
; __device__ __forceinline__ int v_rd_base(int lane) { return ((lane & 3) << 3) | (((lane >> 2) & 3) << 6) | (((lane >> 4) & 1) << 5) | (((lane >> 5) & 1) << 8); }
; template <int OFF> __device__ __forceinline__ s16x4 tr_read(int vb) {
;   s16x4 r; asm volatile("ds_read_b64_tr_b16 %0, %1 offset:%2" : "=&v"(r) : "v"(vb), "i"(OFF) : "memory"); return r;
; }
; template <int D0> __device__ __forceinline__ void pv_one(f32x16& od, int vb, bf16x8 pa0, bf16x8 pa1, bf16x8 pa2, bf16x8 pa3) {
;   const s16x4 l0 = tr_read<v_rd_off(D0, 0, 0)>(vb), h0 = tr_read<v_rd_off(D0, 0, 1)>(vb), l1 = tr_read<v_rd_off(D0, 1, 0)>(vb), h1 = tr_read<v_rd_off(D0, 1, 1)>(vb);
;   const s16x4 l2 = tr_read<v_rd_off(D0, 2, 0)>(vb), h2 = tr_read<v_rd_off(D0, 2, 1)>(vb), l3 = tr_read<v_rd_off(D0, 3, 0)>(vb), h3 = tr_read<v_rd_off(D0, 3, 1)>(vb);
;   asm volatile("s_waitcnt lgkmcnt(0)" ::: "memory"); SBAR();
;     ...
;   od = __builtin_amdgcn_mfma_f32_32x32x16_bf16(pa0, PK(l0, h0), od, 0, 0, 0);
;   od = __builtin_amdgcn_mfma_f32_32x32x16_bf16(pa1, PK(l1, h1), od, 0, 0, 0);
;   od = __builtin_amdgcn_mfma_f32_32x32x16_bf16(pa2, PK(l2, h2), od, 0, 0, 0);
;   od = __builtin_amdgcn_mfma_f32_32x32x16_bf16(pa3, PK(l3, h3), od, 0, 0, 0);
;     ...
; }
; __device__ __forceinline__ void pv_d0(f32x16* o, int vb, bf16x8 pa0, bf16x8 pa1, bf16x8 pa2, bf16x8 pa3) {
;   pv_one<0>(o[0], vb, pa0, pa1, pa2, pa3); pv_one<1>(o[1], vb, pa0, pa1, pa2, pa3); pv_one<2>(o[2], vb, pa0, pa1, pa2, pa3); pv_one<3>(o[3], vb, pa0, pa1, pa2, pa3);
	v_mfma_f32_16x16x32_bf16 v[16:19], v[150:153], v[162:165], v[16:19]
	v_mfma_f32_16x16x32_bf16 v[48:51], v[158:161], v[162:165], v[48:51]
	ds_read_b64_tr_b16 v[174:175], v213 offset:24576
	ds_read_b64_tr_b16 v[176:177], v213 offset:28672
	s_waitcnt lgkmcnt(4)
	v_mfma_f32_16x16x32_bf16 v[20:23], v[150:153], v[166:169], v[20:23]
	v_mfma_f32_16x16x32_bf16 v[52:55], v[158:161], v[166:169], v[52:55]
	s_waitcnt lgkmcnt(2)
	v_mfma_f32_16x16x32_bf16 v[24:27], v[150:153], v[170:173], v[24:27]
	v_mfma_f32_16x16x32_bf16 v[56:59], v[158:161], v[170:173], v[56:59]
	s_waitcnt lgkmcnt(0)
	v_mfma_f32_16x16x32_bf16 v[28:31], v[150:153], v[174:177], v[28:31]
	v_mfma_f32_16x16x32_bf16 v[60:63], v[158:161], v[174:177], v[60:63]
	s_waitcnt vmcnt(0)
	ds_write_b128 v214, v[178:181] offset:32768
	ds_write_b128 v215, v[182:185] offset:32768
	ds_write_b128 v216, v[196:199] offset:32768
	ds_write_b128 v217, v[186:189] offset:0
	ds_write_b128 v217, v[190:193] offset:8192
	global_load_dwordx4 v[178:181], v218, s[22:23]
	global_load_dwordx4 v[182:185], v218, s[24:25]
	global_load_dwordx4 v[196:199], v218, s[34:35]
	global_load_dwordx4 v[186:189], v218, s[26:27]
	global_load_dwordx4 v[190:193], v218, s[30:31]
	s_add_u32 s22, s22, 16384
	s_addc_u32 s23, s23, 0
	s_add_u32 s24, s24, 16384
	s_addc_u32 s25, s25, 0
	s_add_u32 s26, s26, 16384
	s_addc_u32 s27, s27, 0
	s_add_u32 s30, s30, 16384
	s_addc_u32 s31, s31, 0
	s_add_u32 s34, s34, 8192
	s_addc_u32 s35, s35, 0
	s_waitcnt lgkmcnt(0)
	s_barrier
	ds_read_b128 v[162:165], v202 offset:32768
	ds_read_b128 v[166:169], v203 offset:32768
	ds_read_b128 v[170:173], v202 offset:32896
	s_waitcnt lgkmcnt(2)
	v_mfma_f32_16x16x32_bf16 v[114:117], v[162:165], v[64:67], v[224:227]
	v_mfma_f32_16x16x32_bf16 v[118:121], v[162:165], v[88:91], v[228:231]
	ds_read_b128 v[174:177], v203 offset:32896
	s_waitcnt lgkmcnt(2)
	v_mfma_f32_16x16x32_bf16 v[114:117], v[166:169], v[68:71], v[114:117]
	v_mfma_f32_16x16x32_bf16 v[118:121], v[166:169], v[92:95], v[118:121]
	ds_read_b128 v[162:165], v202 offset:33024
	s_waitcnt lgkmcnt(2)
	v_mfma_f32_16x16x32_bf16 v[114:117], v[170:173], v[72:75], v[114:117]
	v_mfma_f32_16x16x32_bf16 v[118:121], v[170:173], v[96:99], v[118:121]
	ds_read_b128 v[166:169], v203 offset:33024
	s_waitcnt lgkmcnt(2)
	v_mfma_f32_16x16x32_bf16 v[114:117], v[174:177], v[76:79], v[114:117]
	v_mfma_f32_16x16x32_bf16 v[118:121], v[174:177], v[100:103], v[118:121]
	ds_read_b128 v[170:173], v202 offset:38912
	s_waitcnt lgkmcnt(2)
	v_mfma_f32_16x16x32_bf16 v[114:117], v[162:165], v[80:83], v[114:117]
	v_mfma_f32_16x16x32_bf16 v[118:121], v[162:165], v[104:107], v[118:121]
	ds_read_b128 v[174:177], v203 offset:38912
	s_waitcnt lgkmcnt(2)
	v_mfma_f32_16x16x32_bf16 v[114:117], v[166:169], v[84:87], v[114:117]
	v_mfma_f32_16x16x32_bf16 v[118:121], v[166:169], v[108:111], v[118:121]
	ds_read_b128 v[162:165], v202 offset:39040
	s_waitcnt lgkmcnt(2)
	v_mfma_f32_16x16x32_bf16 v[122:125], v[170:173], v[64:67], v[224:227]
	v_mfma_f32_16x16x32_bf16 v[126:129], v[170:173], v[88:91], v[228:231]
	ds_read_b128 v[166:169], v203 offset:39040
	s_waitcnt lgkmcnt(2)
	v_mfma_f32_16x16x32_bf16 v[122:125], v[174:177], v[68:71], v[122:125]
	v_mfma_f32_16x16x32_bf16 v[126:129], v[174:177], v[92:95], v[126:129]
	ds_read_b128 v[170:173], v202 offset:39168
	s_waitcnt lgkmcnt(2)
	v_mfma_f32_16x16x32_bf16 v[122:125], v[162:165], v[72:75], v[122:125]
	v_mfma_f32_16x16x32_bf16 v[126:129], v[162:165], v[96:99], v[126:129]
	ds_read_b128 v[174:177], v203 offset:39168
	v_max3_f32 v233, v114, v115, v116
	s_waitcnt lgkmcnt(2)
	v_mfma_f32_16x16x32_bf16 v[122:125], v[166:169], v[76:79], v[122:125]
	v_mfma_f32_16x16x32_bf16 v[126:129], v[166:169], v[100:103], v[126:129]
	ds_read_b128 v[162:165], v202 offset:45056
	v_max_f32_e32 v233, v233, v117
	s_waitcnt lgkmcnt(2)
	v_mfma_f32_16x16x32_bf16 v[122:125], v[170:173], v[80:83], v[122:125]
	v_mfma_f32_16x16x32_bf16 v[126:129], v[170:173], v[104:107], v[126:129]
	ds_read_b128 v[166:169], v203 offset:45056
	v_max3_f32 v234, v118, v119, v120
	s_waitcnt lgkmcnt(2)
	v_mfma_f32_16x16x32_bf16 v[122:125], v[174:177], v[84:87], v[122:125]
	v_mfma_f32_16x16x32_bf16 v[126:129], v[174:177], v[108:111], v[126:129]
	ds_read_b128 v[170:173], v202 offset:45184
	v_max_f32_e32 v234, v234, v121
	s_waitcnt lgkmcnt(2)
	v_mfma_f32_16x16x32_bf16 v[130:133], v[162:165], v[64:67], v[224:227]
	v_mfma_f32_16x16x32_bf16 v[134:137], v[162:165], v[88:91], v[228:231]
	ds_read_b128 v[174:177], v203 offset:45184
	s_waitcnt lgkmcnt(2)
	v_mfma_f32_16x16x32_bf16 v[130:133], v[166:169], v[68:71], v[130:133]
	v_mfma_f32_16x16x32_bf16 v[134:137], v[166:169], v[92:95], v[134:137]
	ds_read_b128 v[162:165], v202 offset:45312
	s_waitcnt lgkmcnt(2)
	v_mfma_f32_16x16x32_bf16 v[130:133], v[170:173], v[72:75], v[130:133]
	v_mfma_f32_16x16x32_bf16 v[134:137], v[170:173], v[96:99], v[134:137]
	ds_read_b128 v[166:169], v203 offset:45312
	v_max3_f32 v233, v233, v122, v123
	s_waitcnt lgkmcnt(2)
	v_mfma_f32_16x16x32_bf16 v[130:133], v[174:177], v[76:79], v[130:133]
	v_mfma_f32_16x16x32_bf16 v[134:137], v[174:177], v[100:103], v[134:137]
	ds_read_b128 v[170:173], v202 offset:51200
	v_max3_f32 v233, v233, v124, v125
	s_waitcnt lgkmcnt(2)
	v_mfma_f32_16x16x32_bf16 v[130:133], v[162:165], v[80:83], v[130:133]
	v_mfma_f32_16x16x32_bf16 v[134:137], v[162:165], v[104:107], v[134:137]
	ds_read_b128 v[174:177], v203 offset:51200
	v_max3_f32 v234, v234, v126, v127
	s_waitcnt lgkmcnt(2)
	v_mfma_f32_16x16x32_bf16 v[130:133], v[166:169], v[84:87], v[130:133]
	v_mfma_f32_16x16x32_bf16 v[134:137], v[166:169], v[108:111], v[134:137]
	ds_read_b128 v[162:165], v202 offset:51328
	v_max3_f32 v234, v234, v128, v129
	s_waitcnt lgkmcnt(2)
; template <bool FIRST>
; __device__ __forceinline__ void partialSM(f32x16& p0, f32x16& p1, float& m_reg, float& alpha) {
;   constexpr float THR2 = THR * 1.4426950408889634f;
;   float pmax = p0[0];
; #pragma unroll
;   for (int r = 1; r < 16; ++r) pmax = fmaxf(pmax, p0[r]);
; #pragma unroll
;   for (int r = 0; r < 16; ++r) pmax = fmaxf(pmax, p1[r]);
;   { auto rr = __builtin_amdgcn_permlane32_swap(__float_as_uint(pmax), __float_as_uint(pmax), false, false);
;     pmax = fmaxf(__uint_as_float(rr[0]), __uint_as_float(rr[1])); }
;   if (!FIRST && __builtin_expect(__all(pmax <= THR2), 1)) { alpha = 1.f; }
;   else { const float d = FIRST ? pmax : fmaxf(pmax, 0.f); alpha = FIRST ? 1.f : __builtin_amdgcn_exp2f(-d); m_reg += d;
; #pragma unroll
;     for (int r = 0; r < 16; ++r) p0[r] -= d;
; #pragma unroll
;     for (int r = 0; r < 16; ++r) p1[r] -= d; }
; #pragma unroll
;   for (int r = 0; r < 16; ++r) p0[r] = __builtin_amdgcn_exp2f(p0[r]);
; }
; __device__ __forceinline__ void finishSM(f32x16& p0, f32x16& p1, float alpha, float& l_reg, bf16x8& pa0, bf16x8& pa1, bf16x8& pa2, bf16x8& pa3) {
; #pragma unroll
;   for (int r = 0; r < 16; ++r) p1[r] = __builtin_amdgcn_exp2f(p1[r]);
;   float ps = 0;
; #pragma unroll
;   for (int r = 0; r < 16; ++r) ps += p0[r];
; #pragma unroll
;   for (int r = 0; r < 16; ++r) ps += p1[r];
;   { auto rr = __builtin_amdgcn_permlane32_swap(__float_as_uint(ps), __float_as_uint(ps), false, false);
;     ps = __uint_as_float(rr[0]) + __uint_as_float(rr[1]); }
;   l_reg = l_reg * alpha + ps;
;     ...
;   PK4(p0, 0, pa0); PK4(p0, 8, pa1); PK4(p1, 0, pa2); PK4(p1, 8, pa3);
;     ...
; }
; template <int D0> __device__ __forceinline__ void pv_one(f32x16& od, int vb, bf16x8 pa0, bf16x8 pa1, bf16x8 pa2, bf16x8 pa3) {
;   const s16x4 l0 = tr_read<v_rd_off(D0, 0, 0)>(vb), h0 = tr_read<v_rd_off(D0, 0, 1)>(vb), l1 = tr_read<v_rd_off(D0, 1, 0)>(vb), h1 = tr_read<v_rd_off(D0, 1, 1)>(vb);
;   const s16x4 l2 = tr_read<v_rd_off(D0, 2, 0)>(vb), h2 = tr_read<v_rd_off(D0, 2, 1)>(vb), l3 = tr_read<v_rd_off(D0, 3, 0)>(vb), h3 = tr_read<v_rd_off(D0, 3, 1)>(vb);
;   asm volatile("s_waitcnt lgkmcnt(0)" ::: "memory"); SBAR();
;     ...
;   od = __builtin_amdgcn_mfma_f32_32x32x16_bf16(pa0, PK(l0, h0), od, 0, 0, 0);
;   od = __builtin_amdgcn_mfma_f32_32x32x16_bf16(pa1, PK(l1, h1), od, 0, 0, 0);
;   od = __builtin_amdgcn_mfma_f32_32x32x16_bf16(pa2, PK(l2, h2), od, 0, 0, 0);
	v_mfma_f32_16x16x32_bf16 v[138:141], v[170:173], v[64:67], v[224:227]
	v_mfma_f32_16x16x32_bf16 v[142:145], v[170:173], v[88:91], v[228:231]
	ds_read_b128 v[166:169], v203 offset:51328
	s_waitcnt lgkmcnt(2)
	v_mfma_f32_16x16x32_bf16 v[138:141], v[174:177], v[68:71], v[138:141]
	v_mfma_f32_16x16x32_bf16 v[142:145], v[174:177], v[92:95], v[142:145]
	ds_read_b128 v[170:173], v202 offset:51456
	s_waitcnt lgkmcnt(2)
	v_mfma_f32_16x16x32_bf16 v[138:141], v[162:165], v[72:75], v[138:141]
	v_mfma_f32_16x16x32_bf16 v[142:145], v[162:165], v[96:99], v[142:145]
	ds_read_b128 v[174:177], v203 offset:51456
	v_max3_f32 v233, v233, v130, v131
	s_waitcnt lgkmcnt(2)
	v_mfma_f32_16x16x32_bf16 v[138:141], v[166:169], v[76:79], v[138:141]
	v_mfma_f32_16x16x32_bf16 v[142:145], v[166:169], v[100:103], v[142:145]
	v_max3_f32 v233, v233, v132, v133
	s_waitcnt lgkmcnt(1)
	v_mfma_f32_16x16x32_bf16 v[138:141], v[170:173], v[80:83], v[138:141]
	v_mfma_f32_16x16x32_bf16 v[142:145], v[170:173], v[104:107], v[142:145]
	v_max3_f32 v234, v234, v134, v135
	s_waitcnt lgkmcnt(0)
	v_mfma_f32_16x16x32_bf16 v[138:141], v[174:177], v[84:87], v[138:141]
	v_mfma_f32_16x16x32_bf16 v[142:145], v[174:177], v[108:111], v[142:145]
	v_max3_f32 v234, v234, v136, v137
	ds_read_b64_tr_b16 v[162:163], v206 offset:0
	ds_read_b64_tr_b16 v[164:165], v206 offset:4096
	ds_read_b64_tr_b16 v[166:167], v207 offset:0
	ds_read_b64_tr_b16 v[168:169], v207 offset:4096
	ds_read_b64_tr_b16 v[170:171], v208 offset:0
	ds_read_b64_tr_b16 v[172:173], v208 offset:4096
	s_nop 7
	v_max3_f32 v233, v233, v138, v139
	v_max3_f32 v233, v233, v140, v141
	v_max3_f32 v234, v234, v142, v143
	v_max3_f32 v234, v234, v144, v145
	v_max_f32_e32 v235, v233, v234
	v_cmp_ge_f32_e32 vcc, s38, v235
	s_cmp_eq_u64 vcc, exec
	s_cbranch_scc0 .Lat_rare_2
.Lat_cont_2:
	v_exp_f32_e32 v114, v114
	v_exp_f32_e32 v115, v115
	v_exp_f32_e32 v116, v116
	v_exp_f32_e32 v117, v117
	v_add_f32_e32 v222, v222, v114
	v_add_f32_e32 v222, v222, v115
	v_add_f32_e32 v222, v222, v116
	v_add_f32_e32 v222, v222, v117
	v_exp_f32_e32 v122, v122
	v_exp_f32_e32 v123, v123
	v_exp_f32_e32 v124, v124
	v_exp_f32_e32 v125, v125
	v_add_f32_e32 v222, v222, v122
	v_add_f32_e32 v222, v222, v123
	v_add_f32_e32 v222, v222, v124
	v_add_f32_e32 v222, v222, v125
	v_cvt_pk_bf16_f32 v146, v114, v115
	v_cvt_pk_bf16_f32 v147, v116, v117
	v_cvt_pk_bf16_f32 v148, v122, v123
	v_cvt_pk_bf16_f32 v149, v124, v125
	v_exp_f32_e32 v118, v118
	v_exp_f32_e32 v119, v119
	v_exp_f32_e32 v120, v120
	v_exp_f32_e32 v121, v121
	v_add_f32_e32 v223, v223, v118
	v_add_f32_e32 v223, v223, v119
	v_add_f32_e32 v223, v223, v120
	v_add_f32_e32 v223, v223, v121
	v_exp_f32_e32 v126, v126
	v_exp_f32_e32 v127, v127
	v_exp_f32_e32 v128, v128
	v_exp_f32_e32 v129, v129
	v_add_f32_e32 v223, v223, v126
	v_add_f32_e32 v223, v223, v127
	v_add_f32_e32 v223, v223, v128
	v_add_f32_e32 v223, v223, v129
	v_cvt_pk_bf16_f32 v154, v118, v119
	v_cvt_pk_bf16_f32 v155, v120, v121
	v_cvt_pk_bf16_f32 v156, v126, v127
	v_cvt_pk_bf16_f32 v157, v128, v129
	s_nop 1
	s_waitcnt lgkmcnt(4)
	v_mfma_f32_16x16x32_bf16 v[0:3], v[146:149], v[162:165], v[0:3]
	v_mfma_f32_16x16x32_bf16 v[32:35], v[154:157], v[162:165], v[32:35]
	ds_read_b64_tr_b16 v[174:175], v209 offset:0
	ds_read_b64_tr_b16 v[176:177], v209 offset:4096
	v_exp_f32_e32 v130, v130
	v_exp_f32_e32 v131, v131
	v_exp_f32_e32 v132, v132
	v_exp_f32_e32 v133, v133
	v_add_f32_e32 v222, v222, v130
	s_waitcnt lgkmcnt(4)
	v_mfma_f32_16x16x32_bf16 v[4:7], v[146:149], v[166:169], v[4:7]
	v_mfma_f32_16x16x32_bf16 v[36:39], v[154:157], v[166:169], v[36:39]
	ds_read_b64_tr_b16 v[162:163], v210 offset:0
	ds_read_b64_tr_b16 v[164:165], v210 offset:4096
	v_add_f32_e32 v222, v222, v131
	v_add_f32_e32 v222, v222, v132
	v_add_f32_e32 v222, v222, v133
	v_exp_f32_e32 v138, v138
	v_exp_f32_e32 v139, v139
	s_waitcnt lgkmcnt(4)
	v_mfma_f32_16x16x32_bf16 v[8:11], v[146:149], v[170:173], v[8:11]
	v_mfma_f32_16x16x32_bf16 v[40:43], v[154:157], v[170:173], v[40:43]
	ds_read_b64_tr_b16 v[166:167], v211 offset:0
	ds_read_b64_tr_b16 v[168:169], v211 offset:4096
	v_exp_f32_e32 v140, v140
	v_exp_f32_e32 v141, v141
	v_add_f32_e32 v222, v222, v138
	v_add_f32_e32 v222, v222, v139
	v_add_f32_e32 v222, v222, v140
	s_waitcnt lgkmcnt(4)
	v_mfma_f32_16x16x32_bf16 v[12:15], v[146:149], v[174:177], v[12:15]
	v_mfma_f32_16x16x32_bf16 v[44:47], v[154:157], v[174:177], v[44:47]
	ds_read_b64_tr_b16 v[170:171], v212 offset:0
	ds_read_b64_tr_b16 v[172:173], v212 offset:4096
	v_add_f32_e32 v222, v222, v141
	v_cvt_pk_bf16_f32 v150, v130, v131
	v_cvt_pk_bf16_f32 v151, v132, v133
	v_cvt_pk_bf16_f32 v152, v138, v139
	v_cvt_pk_bf16_f32 v153, v140, v141
	s_waitcnt lgkmcnt(4)
	v_mfma_f32_16x16x32_bf16 v[16:19], v[146:149], v[162:165], v[16:19]
	v_mfma_f32_16x16x32_bf16 v[48:51], v[154:157], v[162:165], v[48:51]
	ds_read_b64_tr_b16 v[174:175], v213 offset:0
	ds_read_b64_tr_b16 v[176:177], v213 offset:4096
	v_exp_f32_e32 v134, v134
	v_exp_f32_e32 v135, v135
	v_exp_f32_e32 v136, v136
	v_exp_f32_e32 v137, v137
	v_add_f32_e32 v223, v223, v134
	s_waitcnt lgkmcnt(4)
	v_mfma_f32_16x16x32_bf16 v[20:23], v[146:149], v[166:169], v[20:23]
	v_mfma_f32_16x16x32_bf16 v[52:55], v[154:157], v[166:169], v[52:55]
	ds_read_b64_tr_b16 v[162:163], v206 offset:8192
	ds_read_b64_tr_b16 v[164:165], v206 offset:12288
	v_add_f32_e32 v223, v223, v135
	v_add_f32_e32 v223, v223, v136
	v_add_f32_e32 v223, v223, v137
	v_exp_f32_e32 v142, v142
	v_exp_f32_e32 v143, v143
	s_waitcnt lgkmcnt(4)
; __device__ __forceinline__ void qkt(f32x16& p0, f32x16& p1, const char* Ks, const bf16x8* qr, const char* qL, int r32, int hi, float negm) {
; #pragma unroll
;   for (int r = 0; r < 16; ++r) { p0[r] = negm; p1[r] = negm; }
; #pragma unroll
;   for (int d0 = 0; d0 < 12; ++d0) { int cb = (d0 * 16 + hi * 8) * 2;
;     bf16x8 b0 = *reinterpret_cast<const bf16x8*>(Ks + KSWZ(r32, cb));
;     bf16x8 b1 = *reinterpret_cast<const bf16x8*>(Ks + KSWZ(32 + r32, cb));
;     const bf16x8 q = d0 < 8 ? qr[d0 < 8 ? d0 : 0] : *reinterpret_cast<const bf16x8*>(qL + (d0 - 8) * 1024);
;     p0 = __builtin_amdgcn_mfma_f32_32x32x16_bf16(b0, q, p0, 0, 0, 0);
;     p1 = __builtin_amdgcn_mfma_f32_32x32x16_bf16(b1, q, p1, 0, 0, 0); }
; }
; __device__ __forceinline__ int v_st(int k, int c) { const int kk = (k & ~0xC) | ((k & 4) << 1) | ((k & 8) >> 1); return ((kk >> 3) * 4 + (c >> 5)) * 512 + ((kk & 7) * 32 + (c & 31)) * 2; }
; __device__ __forceinline__ int v_rd_base(int lane) { return ((lane & 3) << 3) | (((lane >> 2) & 3) << 6) | (((lane >> 4) & 1) << 5) | (((lane >> 5) & 1) << 8); }
; template <int OFF> __device__ __forceinline__ s16x4 tr_read(int vb) {
;   s16x4 r; asm volatile("ds_read_b64_tr_b16 %0, %1 offset:%2" : "=&v"(r) : "v"(vb), "i"(OFF) : "memory"); return r;
; }
; template <int D0> __device__ __forceinline__ void pv_one(f32x16& od, int vb, bf16x8 pa0, bf16x8 pa1, bf16x8 pa2, bf16x8 pa3) {
;   const s16x4 l0 = tr_read<v_rd_off(D0, 0, 0)>(vb), h0 = tr_read<v_rd_off(D0, 0, 1)>(vb), l1 = tr_read<v_rd_off(D0, 1, 0)>(vb), h1 = tr_read<v_rd_off(D0, 1, 1)>(vb);
;   const s16x4 l2 = tr_read<v_rd_off(D0, 2, 0)>(vb), h2 = tr_read<v_rd_off(D0, 2, 1)>(vb), l3 = tr_read<v_rd_off(D0, 3, 0)>(vb), h3 = tr_read<v_rd_off(D0, 3, 1)>(vb);
;   asm volatile("s_waitcnt lgkmcnt(0)" ::: "memory"); SBAR();
;     ...
;   od = __builtin_amdgcn_mfma_f32_32x32x16_bf16(pa0, PK(l0, h0), od, 0, 0, 0);
;   od = __builtin_amdgcn_mfma_f32_32x32x16_bf16(pa1, PK(l1, h1), od, 0, 0, 0);
;   od = __builtin_amdgcn_mfma_f32_32x32x16_bf16(pa2, PK(l2, h2), od, 0, 0, 0);
;   od = __builtin_amdgcn_mfma_f32_32x32x16_bf16(pa3, PK(l3, h3), od, 0, 0, 0);
;     ...
; }
; __device__ __forceinline__ void pv_d0(f32x16* o, int vb, bf16x8 pa0, bf16x8 pa1, bf16x8 pa2, bf16x8 pa3) {
;   pv_one<0>(o[0], vb, pa0, pa1, pa2, pa3); pv_one<1>(o[1], vb, pa0, pa1, pa2, pa3); pv_one<2>(o[2], vb, pa0, pa1, pa2, pa3); pv_one<3>(o[3], vb, pa0, pa1, pa2, pa3);
	v_mfma_f32_16x16x32_bf16 v[24:27], v[146:149], v[170:173], v[24:27]
	v_mfma_f32_16x16x32_bf16 v[56:59], v[154:157], v[170:173], v[56:59]
	ds_read_b64_tr_b16 v[166:167], v207 offset:8192
	ds_read_b64_tr_b16 v[168:169], v207 offset:12288
	v_exp_f32_e32 v144, v144
	v_exp_f32_e32 v145, v145
	v_add_f32_e32 v223, v223, v142
	v_add_f32_e32 v223, v223, v143
	v_add_f32_e32 v223, v223, v144
	s_waitcnt lgkmcnt(4)
	v_mfma_f32_16x16x32_bf16 v[28:31], v[146:149], v[174:177], v[28:31]
	v_mfma_f32_16x16x32_bf16 v[60:63], v[154:157], v[174:177], v[60:63]
	ds_read_b64_tr_b16 v[170:171], v208 offset:8192
	ds_read_b64_tr_b16 v[172:173], v208 offset:12288
	v_add_f32_e32 v223, v223, v145
	v_cvt_pk_bf16_f32 v158, v134, v135
	v_cvt_pk_bf16_f32 v159, v136, v137
	v_cvt_pk_bf16_f32 v160, v142, v143
	v_cvt_pk_bf16_f32 v161, v144, v145
	s_waitcnt lgkmcnt(4)
	s_nop 1
	v_mfma_f32_16x16x32_bf16 v[0:3], v[150:153], v[162:165], v[0:3]
	v_mfma_f32_16x16x32_bf16 v[32:35], v[158:161], v[162:165], v[32:35]
	ds_read_b64_tr_b16 v[174:175], v209 offset:8192
	ds_read_b64_tr_b16 v[176:177], v209 offset:12288
	s_waitcnt lgkmcnt(4)
	v_mfma_f32_16x16x32_bf16 v[4:7], v[150:153], v[166:169], v[4:7]
	v_mfma_f32_16x16x32_bf16 v[36:39], v[158:161], v[166:169], v[36:39]
	ds_read_b64_tr_b16 v[162:163], v210 offset:8192
	ds_read_b64_tr_b16 v[164:165], v210 offset:12288
	s_waitcnt lgkmcnt(4)
	v_mfma_f32_16x16x32_bf16 v[8:11], v[150:153], v[170:173], v[8:11]
	v_mfma_f32_16x16x32_bf16 v[40:43], v[158:161], v[170:173], v[40:43]
	ds_read_b64_tr_b16 v[166:167], v211 offset:8192
	ds_read_b64_tr_b16 v[168:169], v211 offset:12288
	s_waitcnt lgkmcnt(4)
	v_mfma_f32_16x16x32_bf16 v[12:15], v[150:153], v[174:177], v[12:15]
	v_mfma_f32_16x16x32_bf16 v[44:47], v[158:161], v[174:177], v[44:47]
	ds_read_b64_tr_b16 v[170:171], v212 offset:8192
	ds_read_b64_tr_b16 v[172:173], v212 offset:12288
	s_waitcnt lgkmcnt(4)
	v_mfma_f32_16x16x32_bf16 v[16:19], v[150:153], v[162:165], v[16:19]
	v_mfma_f32_16x16x32_bf16 v[48:51], v[158:161], v[162:165], v[48:51]
	ds_read_b64_tr_b16 v[174:175], v213 offset:8192
	ds_read_b64_tr_b16 v[176:177], v213 offset:12288
	s_waitcnt lgkmcnt(4)
	v_mfma_f32_16x16x32_bf16 v[20:23], v[150:153], v[166:169], v[20:23]
	v_mfma_f32_16x16x32_bf16 v[52:55], v[158:161], v[166:169], v[52:55]
	s_waitcnt lgkmcnt(2)
	v_mfma_f32_16x16x32_bf16 v[24:27], v[150:153], v[170:173], v[24:27]
	v_mfma_f32_16x16x32_bf16 v[56:59], v[158:161], v[170:173], v[56:59]
	s_waitcnt lgkmcnt(0)
	v_mfma_f32_16x16x32_bf16 v[28:31], v[150:153], v[174:177], v[28:31]
	v_mfma_f32_16x16x32_bf16 v[60:63], v[158:161], v[174:177], v[60:63]
	s_waitcnt vmcnt(0)
	ds_write_b128 v214, v[178:181] offset:57344
	ds_write_b128 v215, v[182:185] offset:57344
	ds_write_b128 v216, v[196:199] offset:57344
	ds_write_b128 v217, v[186:189] offset:16384
	ds_write_b128 v217, v[190:193] offset:24576
	global_load_dwordx4 v[178:181], v218, s[22:23]
	global_load_dwordx4 v[182:185], v218, s[24:25]
	global_load_dwordx4 v[196:199], v218, s[34:35]
	global_load_dwordx4 v[186:189], v218, s[26:27]
	global_load_dwordx4 v[190:193], v218, s[30:31]
	s_add_u32 s22, s22, 16384
	s_addc_u32 s23, s23, 0
	s_add_u32 s24, s24, 16384
	s_addc_u32 s25, s25, 0
	s_add_u32 s26, s26, 16384
	s_addc_u32 s27, s27, 0
	s_add_u32 s30, s30, 16384
	s_addc_u32 s31, s31, 0
	s_add_u32 s34, s34, 8192
	s_addc_u32 s35, s35, 0
	s_waitcnt lgkmcnt(0)
	s_barrier
	s_sub_u32 s39, s39, 1
	s_cmp_lg_u32 s39, 0
	s_cbranch_scc1 .Lat_loop
	ds_read_b128 v[162:165], v204 offset:32768
	ds_read_b128 v[166:169], v205 offset:32768
	ds_read_b128 v[170:173], v204 offset:32896
	s_waitcnt lgkmcnt(2)
	v_mfma_f32_16x16x32_bf16 v[114:117], v[162:165], v[64:67], v[224:227]
	v_mfma_f32_16x16x32_bf16 v[118:121], v[162:165], v[88:91], v[228:231]
	ds_read_b128 v[174:177], v205 offset:32896
	s_waitcnt lgkmcnt(2)
	v_mfma_f32_16x16x32_bf16 v[114:117], v[166:169], v[68:71], v[114:117]
	v_mfma_f32_16x16x32_bf16 v[118:121], v[166:169], v[92:95], v[118:121]
	ds_read_b128 v[162:165], v204 offset:33024
	s_waitcnt lgkmcnt(2)
	v_mfma_f32_16x16x32_bf16 v[114:117], v[170:173], v[72:75], v[114:117]
	v_mfma_f32_16x16x32_bf16 v[118:121], v[170:173], v[96:99], v[118:121]
	ds_read_b128 v[166:169], v205 offset:33024
	s_waitcnt lgkmcnt(2)
	v_mfma_f32_16x16x32_bf16 v[114:117], v[174:177], v[76:79], v[114:117]
	v_mfma_f32_16x16x32_bf16 v[118:121], v[174:177], v[100:103], v[118:121]
	ds_read_b128 v[170:173], v204 offset:38912
	s_waitcnt lgkmcnt(2)
	v_mfma_f32_16x16x32_bf16 v[114:117], v[162:165], v[80:83], v[114:117]
	v_mfma_f32_16x16x32_bf16 v[118:121], v[162:165], v[104:107], v[118:121]
	ds_read_b128 v[174:177], v205 offset:38912
	s_waitcnt lgkmcnt(2)
	v_mfma_f32_16x16x32_bf16 v[114:117], v[166:169], v[84:87], v[114:117]
	v_mfma_f32_16x16x32_bf16 v[118:121], v[166:169], v[108:111], v[118:121]
	ds_read_b128 v[162:165], v204 offset:39040
	s_waitcnt lgkmcnt(2)
	v_mfma_f32_16x16x32_bf16 v[122:125], v[170:173], v[64:67], v[224:227]
	v_mfma_f32_16x16x32_bf16 v[126:129], v[170:173], v[88:91], v[228:231]
	ds_read_b128 v[166:169], v205 offset:39040
	s_waitcnt lgkmcnt(2)
	v_mfma_f32_16x16x32_bf16 v[122:125], v[174:177], v[68:71], v[122:125]
	v_mfma_f32_16x16x32_bf16 v[126:129], v[174:177], v[92:95], v[126:129]
	ds_read_b128 v[170:173], v204 offset:39168
	s_waitcnt lgkmcnt(2)
	v_mfma_f32_16x16x32_bf16 v[122:125], v[162:165], v[72:75], v[122:125]
	v_mfma_f32_16x16x32_bf16 v[126:129], v[162:165], v[96:99], v[126:129]
	ds_read_b128 v[174:177], v205 offset:39168
	v_max3_f32 v233, v114, v115, v116
	s_waitcnt lgkmcnt(2)
	v_mfma_f32_16x16x32_bf16 v[122:125], v[166:169], v[76:79], v[122:125]
	v_mfma_f32_16x16x32_bf16 v[126:129], v[166:169], v[100:103], v[126:129]
	ds_read_b128 v[162:165], v204 offset:45056
	v_max_f32_e32 v233, v233, v117
	s_waitcnt lgkmcnt(2)
; template <bool FIRST>
; __device__ __forceinline__ void partialSM(f32x16& p0, f32x16& p1, float& m_reg, float& alpha) {
;   constexpr float THR2 = THR * 1.4426950408889634f;
;   float pmax = p0[0];
; #pragma unroll
;   for (int r = 1; r < 16; ++r) pmax = fmaxf(pmax, p0[r]);
; #pragma unroll
;   for (int r = 0; r < 16; ++r) pmax = fmaxf(pmax, p1[r]);
;   { auto rr = __builtin_amdgcn_permlane32_swap(__float_as_uint(pmax), __float_as_uint(pmax), false, false);
;     pmax = fmaxf(__uint_as_float(rr[0]), __uint_as_float(rr[1])); }
;   if (!FIRST && __builtin_expect(__all(pmax <= THR2), 1)) { alpha = 1.f; }
;   else { const float d = FIRST ? pmax : fmaxf(pmax, 0.f); alpha = FIRST ? 1.f : __builtin_amdgcn_exp2f(-d); m_reg += d;
; #pragma unroll
;     for (int r = 0; r < 16; ++r) p0[r] -= d;
; #pragma unroll
;     for (int r = 0; r < 16; ++r) p1[r] -= d; }
; #pragma unroll
;   for (int r = 0; r < 16; ++r) p0[r] = __builtin_amdgcn_exp2f(p0[r]);
; }
; __device__ __forceinline__ void finishSM(f32x16& p0, f32x16& p1, float alpha, float& l_reg, bf16x8& pa0, bf16x8& pa1, bf16x8& pa2, bf16x8& pa3) {
; #pragma unroll
;   for (int r = 0; r < 16; ++r) p1[r] = __builtin_amdgcn_exp2f(p1[r]);
;   float ps = 0;
; #pragma unroll
;   for (int r = 0; r < 16; ++r) ps += p0[r];
; #pragma unroll
;   for (int r = 0; r < 16; ++r) ps += p1[r];
;   { auto rr = __builtin_amdgcn_permlane32_swap(__float_as_uint(ps), __float_as_uint(ps), false, false);
;     ps = __uint_as_float(rr[0]) + __uint_as_float(rr[1]); }
;   l_reg = l_reg * alpha + ps;
;     ...
;   PK4(p0, 0, pa0); PK4(p0, 8, pa1); PK4(p1, 0, pa2); PK4(p1, 8, pa3);
;     ...
; }
; __device__ __forceinline__ void qkt(f32x16& p0, f32x16& p1, const char* Ks, const bf16x8* qr, const char* qL, int r32, int hi, float negm) {
; #pragma unroll
;   for (int r = 0; r < 16; ++r) { p0[r] = negm; p1[r] = negm; }
; #pragma unroll
;   for (int d0 = 0; d0 < 12; ++d0) { int cb = (d0 * 16 + hi * 8) * 2;
;     bf16x8 b0 = *reinterpret_cast<const bf16x8*>(Ks + KSWZ(r32, cb));
;     bf16x8 b1 = *reinterpret_cast<const bf16x8*>(Ks + KSWZ(32 + r32, cb));
;     const bf16x8 q = d0 < 8 ? qr[d0 < 8 ? d0 : 0] : *reinterpret_cast<const bf16x8*>(qL + (d0 - 8) * 1024);
;     p0 = __builtin_amdgcn_mfma_f32_32x32x16_bf16(b0, q, p0, 0, 0, 0);
;     p1 = __builtin_amdgcn_mfma_f32_32x32x16_bf16(b1, q, p1, 0, 0, 0); }
; }
	v_mfma_f32_16x16x32_bf16 v[122:125], v[170:173], v[80:83], v[122:125]
	v_mfma_f32_16x16x32_bf16 v[126:129], v[170:173], v[104:107], v[126:129]
	ds_read_b128 v[166:169], v205 offset:45056
	v_max3_f32 v234, v118, v119, v120
	s_waitcnt lgkmcnt(2)
	v_mfma_f32_16x16x32_bf16 v[122:125], v[174:177], v[84:87], v[122:125]
	v_mfma_f32_16x16x32_bf16 v[126:129], v[174:177], v[108:111], v[126:129]
	ds_read_b128 v[170:173], v204 offset:45184
	v_max_f32_e32 v234, v234, v121
	s_waitcnt lgkmcnt(2)
	v_mfma_f32_16x16x32_bf16 v[130:133], v[162:165], v[64:67], v[224:227]
	v_mfma_f32_16x16x32_bf16 v[134:137], v[162:165], v[88:91], v[228:231]
	ds_read_b128 v[174:177], v205 offset:45184
	s_waitcnt lgkmcnt(2)
	v_mfma_f32_16x16x32_bf16 v[130:133], v[166:169], v[68:71], v[130:133]
	v_mfma_f32_16x16x32_bf16 v[134:137], v[166:169], v[92:95], v[134:137]
	ds_read_b128 v[162:165], v204 offset:45312
	s_waitcnt lgkmcnt(2)
	v_mfma_f32_16x16x32_bf16 v[130:133], v[170:173], v[72:75], v[130:133]
	v_mfma_f32_16x16x32_bf16 v[134:137], v[170:173], v[96:99], v[134:137]
	ds_read_b128 v[166:169], v205 offset:45312
	v_max3_f32 v233, v233, v122, v123
	s_waitcnt lgkmcnt(2)
	v_mfma_f32_16x16x32_bf16 v[130:133], v[174:177], v[76:79], v[130:133]
	v_mfma_f32_16x16x32_bf16 v[134:137], v[174:177], v[100:103], v[134:137]
	ds_read_b128 v[170:173], v204 offset:51200
	v_max3_f32 v233, v233, v124, v125
	s_waitcnt lgkmcnt(2)
	v_mfma_f32_16x16x32_bf16 v[130:133], v[162:165], v[80:83], v[130:133]
	v_mfma_f32_16x16x32_bf16 v[134:137], v[162:165], v[104:107], v[134:137]
	ds_read_b128 v[174:177], v205 offset:51200
	v_max3_f32 v234, v234, v126, v127
	s_waitcnt lgkmcnt(2)
	v_mfma_f32_16x16x32_bf16 v[130:133], v[166:169], v[84:87], v[130:133]
	v_mfma_f32_16x16x32_bf16 v[134:137], v[166:169], v[108:111], v[134:137]
	ds_read_b128 v[162:165], v204 offset:51328
	v_max3_f32 v234, v234, v128, v129
	s_waitcnt lgkmcnt(2)
	v_mfma_f32_16x16x32_bf16 v[138:141], v[170:173], v[64:67], v[224:227]
	v_mfma_f32_16x16x32_bf16 v[142:145], v[170:173], v[88:91], v[228:231]
	ds_read_b128 v[166:169], v205 offset:51328
	s_waitcnt lgkmcnt(2)
	v_mfma_f32_16x16x32_bf16 v[138:141], v[174:177], v[68:71], v[138:141]
	v_mfma_f32_16x16x32_bf16 v[142:145], v[174:177], v[92:95], v[142:145]
	ds_read_b128 v[170:173], v204 offset:51456
	s_waitcnt lgkmcnt(2)
	v_mfma_f32_16x16x32_bf16 v[138:141], v[162:165], v[72:75], v[138:141]
	v_mfma_f32_16x16x32_bf16 v[142:145], v[162:165], v[96:99], v[142:145]
	ds_read_b128 v[174:177], v205 offset:51456
	v_max3_f32 v233, v233, v130, v131
	s_waitcnt lgkmcnt(2)
	v_mfma_f32_16x16x32_bf16 v[138:141], v[166:169], v[76:79], v[138:141]
	v_mfma_f32_16x16x32_bf16 v[142:145], v[166:169], v[100:103], v[142:145]
	v_max3_f32 v233, v233, v132, v133
	s_waitcnt lgkmcnt(1)
	v_mfma_f32_16x16x32_bf16 v[138:141], v[170:173], v[80:83], v[138:141]
	v_mfma_f32_16x16x32_bf16 v[142:145], v[170:173], v[104:107], v[142:145]
	v_max3_f32 v234, v234, v134, v135
	s_waitcnt lgkmcnt(0)
	v_mfma_f32_16x16x32_bf16 v[138:141], v[174:177], v[84:87], v[138:141]
	v_mfma_f32_16x16x32_bf16 v[142:145], v[174:177], v[108:111], v[142:145]
	v_max3_f32 v234, v234, v136, v137
	ds_read_b64_tr_b16 v[162:163], v206 offset:16384
	ds_read_b64_tr_b16 v[164:165], v206 offset:20480
	ds_read_b64_tr_b16 v[166:167], v207 offset:16384
	ds_read_b64_tr_b16 v[168:169], v207 offset:20480
	ds_read_b64_tr_b16 v[170:171], v208 offset:16384
	ds_read_b64_tr_b16 v[172:173], v208 offset:20480
	s_nop 7
	v_max3_f32 v233, v233, v138, v139
	v_max3_f32 v233, v233, v140, v141
	v_max3_f32 v234, v234, v142, v143
	v_max3_f32 v234, v234, v144, v145
	v_max_f32_e32 v235, v233, v234
	v_cmp_ge_f32_e32 vcc, s38, v235
	s_cmp_eq_u64 vcc, exec
	s_cbranch_scc0 .Lat_rare_3
.Lat_cont_3:
	v_exp_f32_e32 v114, v114
	v_exp_f32_e32 v115, v115
	v_exp_f32_e32 v116, v116
	v_exp_f32_e32 v117, v117
	v_add_f32_e32 v222, v222, v114
	v_add_f32_e32 v222, v222, v115
	v_add_f32_e32 v222, v222, v116
	v_add_f32_e32 v222, v222, v117
	v_exp_f32_e32 v122, v122
	v_exp_f32_e32 v123, v123
	v_exp_f32_e32 v124, v124
	v_exp_f32_e32 v125, v125
	v_add_f32_e32 v222, v222, v122
	v_add_f32_e32 v222, v222, v123
	v_add_f32_e32 v222, v222, v124
	v_add_f32_e32 v222, v222, v125
	v_cvt_pk_bf16_f32 v146, v114, v115
	v_cvt_pk_bf16_f32 v147, v116, v117
	v_cvt_pk_bf16_f32 v148, v122, v123
	v_cvt_pk_bf16_f32 v149, v124, v125
	v_exp_f32_e32 v118, v118
	v_exp_f32_e32 v119, v119
	v_exp_f32_e32 v120, v120
	v_exp_f32_e32 v121, v121
	v_add_f32_e32 v223, v223, v118
	v_add_f32_e32 v223, v223, v119
	v_add_f32_e32 v223, v223, v120
	v_add_f32_e32 v223, v223, v121
	v_exp_f32_e32 v126, v126
	v_exp_f32_e32 v127, v127
	v_exp_f32_e32 v128, v128
	v_exp_f32_e32 v129, v129
	v_add_f32_e32 v223, v223, v126
	v_add_f32_e32 v223, v223, v127
	v_add_f32_e32 v223, v223, v128
	v_add_f32_e32 v223, v223, v129
	v_cvt_pk_bf16_f32 v154, v118, v119
	v_cvt_pk_bf16_f32 v155, v120, v121
	v_cvt_pk_bf16_f32 v156, v126, v127
	v_cvt_pk_bf16_f32 v157, v128, v129
	s_nop 1
	s_waitcnt lgkmcnt(4)
	v_mfma_f32_16x16x32_bf16 v[0:3], v[146:149], v[162:165], v[0:3]
	v_mfma_f32_16x16x32_bf16 v[32:35], v[154:157], v[162:165], v[32:35]
	ds_read_b64_tr_b16 v[174:175], v209 offset:16384
	ds_read_b64_tr_b16 v[176:177], v209 offset:20480
	v_exp_f32_e32 v130, v130
	v_exp_f32_e32 v131, v131
	v_exp_f32_e32 v132, v132
	v_exp_f32_e32 v133, v133
	v_add_f32_e32 v222, v222, v130
	s_waitcnt lgkmcnt(4)
	v_mfma_f32_16x16x32_bf16 v[4:7], v[146:149], v[166:169], v[4:7]
	v_mfma_f32_16x16x32_bf16 v[36:39], v[154:157], v[166:169], v[36:39]
	ds_read_b64_tr_b16 v[162:163], v210 offset:16384
	ds_read_b64_tr_b16 v[164:165], v210 offset:20480
	v_add_f32_e32 v222, v222, v131
	v_add_f32_e32 v222, v222, v132
	v_add_f32_e32 v222, v222, v133
	v_exp_f32_e32 v138, v138
	v_exp_f32_e32 v139, v139
	s_waitcnt lgkmcnt(4)
; #define SBAR() __builtin_amdgcn_sched_barrier(0)
; __device__ __forceinline__ int crow(int r, int hi) { return (r & 3) + 8 * (r >> 2) + 4 * hi; }
; #define RESC(a) do { if (__any((a) < 1.f)) { if (hi == 0) al_l[r32] = (a); asm volatile("s_waitcnt lgkmcnt(0)" ::: "memory"); \
;     _Pragma("unroll") for (int d = 0; d < 4; ++d) _Pragma("unroll") for (int r = 0; r < 16; ++r) o[d][r] *= al_l[crow(r, hi)]; } } while (0)
; template <int D0> __device__ __forceinline__ void pv_one(f32x16& od, int vb, bf16x8 pa0, bf16x8 pa1, bf16x8 pa2, bf16x8 pa3) {
;   const s16x4 l0 = tr_read<v_rd_off(D0, 0, 0)>(vb), h0 = tr_read<v_rd_off(D0, 0, 1)>(vb), l1 = tr_read<v_rd_off(D0, 1, 0)>(vb), h1 = tr_read<v_rd_off(D0, 1, 1)>(vb);
;   const s16x4 l2 = tr_read<v_rd_off(D0, 2, 0)>(vb), h2 = tr_read<v_rd_off(D0, 2, 1)>(vb), l3 = tr_read<v_rd_off(D0, 3, 0)>(vb), h3 = tr_read<v_rd_off(D0, 3, 1)>(vb);
;   asm volatile("s_waitcnt lgkmcnt(0)" ::: "memory"); SBAR();
;     ...
;   od = __builtin_amdgcn_mfma_f32_32x32x16_bf16(pa0, PK(l0, h0), od, 0, 0, 0);
;   od = __builtin_amdgcn_mfma_f32_32x32x16_bf16(pa1, PK(l1, h1), od, 0, 0, 0);
;   od = __builtin_amdgcn_mfma_f32_32x32x16_bf16(pa2, PK(l2, h2), od, 0, 0, 0);
;   od = __builtin_amdgcn_mfma_f32_32x32x16_bf16(pa3, PK(l3, h3), od, 0, 0, 0);
;     ...
; }
; __device__ __forceinline__ void pv_d0(f32x16* o, int vb, bf16x8 pa0, bf16x8 pa1, bf16x8 pa2, bf16x8 pa3) {
;   pv_one<0>(o[0], vb, pa0, pa1, pa2, pa3); pv_one<1>(o[1], vb, pa0, pa1, pa2, pa3); pv_one<2>(o[2], vb, pa0, pa1, pa2, pa3); pv_one<3>(o[3], vb, pa0, pa1, pa2, pa3);
; }
; __device__ __forceinline__ void attn_unit(const bf16_t* __restrict__ Qb, const bf16_t* __restrict__ Kn, const bf16_t* __restrict__ Kr, const bf16_t* __restrict__ Vh,
;                                           bf16_t* __restrict__ Ob, char* lds) {
;     ...
;   SBAR(); qkt(pB0, pB1, K_lds + SHM_K, qr, qL, r32, hi, -m_reg);
;   finishSM(pA0, pA1, alA, l_reg, pa0, pa1, pa2, pa3); SBAR();
;   pv_d0(o, vb0, pa0, pa1, pa2, pa3); partialSM<false>(pB0, pB1, m_reg, alB);
;   __syncthreads(); RESC(alB);
;   finishSM(pB0, pB1, alB, l_reg, pa0, pa1, pa2, pa3); SBAR();
;   pv_d0(o, vb0 + (int)SHM_V, pa0, pa1, pa2, pa3);
;   if (hi == 0) li_l[r32] = l_reg; asm volatile("s_waitcnt lgkmcnt(0)" ::: "memory");
;   float rli[16];
; #pragma unroll
;   for (int r = 0; r < 16; ++r) rli[r] = __builtin_amdgcn_rcpf(li_l[crow(r, hi)]);
	v_mfma_f32_16x16x32_bf16 v[8:11], v[146:149], v[170:173], v[8:11]
	v_mfma_f32_16x16x32_bf16 v[40:43], v[154:157], v[170:173], v[40:43]
	ds_read_b64_tr_b16 v[166:167], v211 offset:16384
	ds_read_b64_tr_b16 v[168:169], v211 offset:20480
	v_exp_f32_e32 v140, v140
	v_exp_f32_e32 v141, v141
	v_add_f32_e32 v222, v222, v138
	v_add_f32_e32 v222, v222, v139
	v_add_f32_e32 v222, v222, v140
	s_waitcnt lgkmcnt(4)
	v_mfma_f32_16x16x32_bf16 v[12:15], v[146:149], v[174:177], v[12:15]
	v_mfma_f32_16x16x32_bf16 v[44:47], v[154:157], v[174:177], v[44:47]
	ds_read_b64_tr_b16 v[170:171], v212 offset:16384
	ds_read_b64_tr_b16 v[172:173], v212 offset:20480
	v_add_f32_e32 v222, v222, v141
	v_cvt_pk_bf16_f32 v150, v130, v131
	v_cvt_pk_bf16_f32 v151, v132, v133
	v_cvt_pk_bf16_f32 v152, v138, v139
	v_cvt_pk_bf16_f32 v153, v140, v141
	s_waitcnt lgkmcnt(4)
	v_mfma_f32_16x16x32_bf16 v[16:19], v[146:149], v[162:165], v[16:19]
	v_mfma_f32_16x16x32_bf16 v[48:51], v[154:157], v[162:165], v[48:51]
	ds_read_b64_tr_b16 v[174:175], v213 offset:16384
	ds_read_b64_tr_b16 v[176:177], v213 offset:20480
	v_exp_f32_e32 v134, v134
	v_exp_f32_e32 v135, v135
	v_exp_f32_e32 v136, v136
	v_exp_f32_e32 v137, v137
	v_add_f32_e32 v223, v223, v134
	s_waitcnt lgkmcnt(4)
	v_mfma_f32_16x16x32_bf16 v[20:23], v[146:149], v[166:169], v[20:23]
	v_mfma_f32_16x16x32_bf16 v[52:55], v[154:157], v[166:169], v[52:55]
	ds_read_b64_tr_b16 v[162:163], v206 offset:24576
	ds_read_b64_tr_b16 v[164:165], v206 offset:28672
	v_add_f32_e32 v223, v223, v135
	v_add_f32_e32 v223, v223, v136
	v_add_f32_e32 v223, v223, v137
	v_exp_f32_e32 v142, v142
	v_exp_f32_e32 v143, v143
	s_waitcnt lgkmcnt(4)
	v_mfma_f32_16x16x32_bf16 v[24:27], v[146:149], v[170:173], v[24:27]
	v_mfma_f32_16x16x32_bf16 v[56:59], v[154:157], v[170:173], v[56:59]
	ds_read_b64_tr_b16 v[166:167], v207 offset:24576
	ds_read_b64_tr_b16 v[168:169], v207 offset:28672
	v_exp_f32_e32 v144, v144
	v_exp_f32_e32 v145, v145
	v_add_f32_e32 v223, v223, v142
	v_add_f32_e32 v223, v223, v143
	v_add_f32_e32 v223, v223, v144
	s_waitcnt lgkmcnt(4)
	v_mfma_f32_16x16x32_bf16 v[28:31], v[146:149], v[174:177], v[28:31]
	v_mfma_f32_16x16x32_bf16 v[60:63], v[154:157], v[174:177], v[60:63]
	ds_read_b64_tr_b16 v[170:171], v208 offset:24576
	ds_read_b64_tr_b16 v[172:173], v208 offset:28672
	v_add_f32_e32 v223, v223, v145
	v_cvt_pk_bf16_f32 v158, v134, v135
	v_cvt_pk_bf16_f32 v159, v136, v137
	v_cvt_pk_bf16_f32 v160, v142, v143
	v_cvt_pk_bf16_f32 v161, v144, v145
	s_waitcnt lgkmcnt(4)
	s_nop 1
	v_mfma_f32_16x16x32_bf16 v[0:3], v[150:153], v[162:165], v[0:3]
	v_mfma_f32_16x16x32_bf16 v[32:35], v[158:161], v[162:165], v[32:35]
	ds_read_b64_tr_b16 v[174:175], v209 offset:24576
	ds_read_b64_tr_b16 v[176:177], v209 offset:28672
	s_waitcnt lgkmcnt(4)
	v_mfma_f32_16x16x32_bf16 v[4:7], v[150:153], v[166:169], v[4:7]
	v_mfma_f32_16x16x32_bf16 v[36:39], v[158:161], v[166:169], v[36:39]
	ds_read_b64_tr_b16 v[162:163], v210 offset:24576
	ds_read_b64_tr_b16 v[164:165], v210 offset:28672
	s_waitcnt lgkmcnt(4)
	v_mfma_f32_16x16x32_bf16 v[8:11], v[150:153], v[170:173], v[8:11]
	v_mfma_f32_16x16x32_bf16 v[40:43], v[158:161], v[170:173], v[40:43]
	ds_read_b64_tr_b16 v[166:167], v211 offset:24576
	ds_read_b64_tr_b16 v[168:169], v211 offset:28672
	s_waitcnt lgkmcnt(4)
	v_mfma_f32_16x16x32_bf16 v[12:15], v[150:153], v[174:177], v[12:15]
	v_mfma_f32_16x16x32_bf16 v[44:47], v[158:161], v[174:177], v[44:47]
	ds_read_b64_tr_b16 v[170:171], v212 offset:24576
	ds_read_b64_tr_b16 v[172:173], v212 offset:28672
	s_waitcnt lgkmcnt(4)
	v_mfma_f32_16x16x32_bf16 v[16:19], v[150:153], v[162:165], v[16:19]
	v_mfma_f32_16x16x32_bf16 v[48:51], v[158:161], v[162:165], v[48:51]
	ds_read_b64_tr_b16 v[174:175], v213 offset:24576
	ds_read_b64_tr_b16 v[176:177], v213 offset:28672
	s_waitcnt lgkmcnt(4)
	v_mfma_f32_16x16x32_bf16 v[20:23], v[150:153], v[166:169], v[20:23]
	v_mfma_f32_16x16x32_bf16 v[52:55], v[158:161], v[166:169], v[52:55]
	s_waitcnt lgkmcnt(2)
	v_mfma_f32_16x16x32_bf16 v[24:27], v[150:153], v[170:173], v[24:27]
	v_mfma_f32_16x16x32_bf16 v[56:59], v[158:161], v[170:173], v[56:59]
	s_waitcnt lgkmcnt(0)
	v_mfma_f32_16x16x32_bf16 v[28:31], v[150:153], v[174:177], v[28:31]
	v_mfma_f32_16x16x32_bf16 v[60:63], v[158:161], v[174:177], v[60:63]
	v_mov_b32_e32 v243, v222
	s_nop 1
	v_permlane32_swap_b32_e32 v222, v243
	s_nop 1
	v_add_f32_e32 v222, v222, v243
	s_nop 1
	ds_bpermute_b32 v243, v112, v222
	s_waitcnt lgkmcnt(0)
	v_add_f32_e32 v222, v222, v243
	v_rcp_f32_e32 v222, v222
	s_nop 0
	ds_write_b32 v219, v222 offset:0
	v_mov_b32_e32 v243, v223
	s_nop 1
	v_permlane32_swap_b32_e32 v223, v243
	s_nop 1
	v_add_f32_e32 v223, v223, v243
	s_nop 1
	ds_bpermute_b32 v243, v112, v223
	s_waitcnt lgkmcnt(0)
	v_add_f32_e32 v223, v223, v243
	v_rcp_f32_e32 v223, v223
	s_nop 0
	ds_write_b32 v219, v223 offset:64
	s_waitcnt lgkmcnt(0)
	v_and_b32_e32 v235, 63, v195
	v_lshrrev_b32_e32 v243, 4, v235
	v_and_b32_e32 v235, 15, v235
	v_lshlrev_b32_e32 v235, 1, v235
	v_lshl_add_u32 v235, v243, 14, v235
	ds_read_b128 v[246:249], v232 offset:0
	s_waitcnt lgkmcnt(0)
; __device__ __forceinline__ unsigned f2bf(float f) { unsigned u = __float_as_uint(f); return (u + 0x7fffu + ((u >> 16) & 1u)) >> 16; }
; __device__ __forceinline__ int crow(int r, int hi) { return (r & 3) + 8 * (r >> 2) + 4 * hi; }
; __device__ __forceinline__ void attn_unit(const bf16_t* __restrict__ Qb, const bf16_t* __restrict__ Kn, const bf16_t* __restrict__ Kr, const bf16_t* __restrict__ Vh,
;                                           bf16_t* __restrict__ Ob, char* lds) {
;     ...
;   if (hi == 0) li_l[r32] = l_reg; asm volatile("s_waitcnt lgkmcnt(0)" ::: "memory");
;   float rli[16];
; #pragma unroll
;   for (int r = 0; r < 16; ++r) rli[r] = __builtin_amdgcn_rcpf(li_l[crow(r, hi)]);
;   bf16_t* Ow = Ob + (long)(wid * 32) * DM;
; #pragma unroll
;   for (int r = 0; r < 16; ++r) { int orow = crow(r, hi);
; #pragma unroll
;     for (int d0 = 0; d0 < 4; ++d0) Ow[(long)orow * DM + d0 * 32 + r32] = (bf16_t)f2bf(o[d0][r] * rli[r]); }
	s_add_u32 s74, s36, 0
	s_addc_u32 s75, s37, 0
	v_mul_f32_e32 v0, v0, v246
	v_mul_f32_e32 v4, v4, v246
	v_cvt_pk_bf16_f32 v0, v0, v4
	s_nop 0
	global_store_short v235, v0, s[74:75] offset:0
	global_store_short_d16_hi v235, v0, s[74:75] offset:32
	v_mul_f32_e32 v8, v8, v246
	v_mul_f32_e32 v12, v12, v246
	v_cvt_pk_bf16_f32 v8, v8, v12
	s_nop 0
	global_store_short v235, v8, s[74:75] offset:64
	global_store_short_d16_hi v235, v8, s[74:75] offset:96
	v_mul_f32_e32 v16, v16, v246
	v_mul_f32_e32 v20, v20, v246
	v_cvt_pk_bf16_f32 v16, v16, v20
	s_nop 0
	global_store_short v235, v16, s[74:75] offset:128
	global_store_short_d16_hi v235, v16, s[74:75] offset:160
	v_mul_f32_e32 v24, v24, v246
	v_mul_f32_e32 v28, v28, v246
	v_cvt_pk_bf16_f32 v24, v24, v28
	s_nop 0
	global_store_short v235, v24, s[74:75] offset:192
	global_store_short_d16_hi v235, v24, s[74:75] offset:224
	s_add_u32 s74, s36, 4096
	s_addc_u32 s75, s37, 0
	v_mul_f32_e32 v1, v1, v247
	v_mul_f32_e32 v5, v5, v247
	v_cvt_pk_bf16_f32 v1, v1, v5
	s_nop 0
	global_store_short v235, v1, s[74:75] offset:0
	global_store_short_d16_hi v235, v1, s[74:75] offset:32
	v_mul_f32_e32 v9, v9, v247
	v_mul_f32_e32 v13, v13, v247
	v_cvt_pk_bf16_f32 v9, v9, v13
	s_nop 0
	global_store_short v235, v9, s[74:75] offset:64
	global_store_short_d16_hi v235, v9, s[74:75] offset:96
	v_mul_f32_e32 v17, v17, v247
	v_mul_f32_e32 v21, v21, v247
	v_cvt_pk_bf16_f32 v17, v17, v21
	s_nop 0
	global_store_short v235, v17, s[74:75] offset:128
	global_store_short_d16_hi v235, v17, s[74:75] offset:160
	v_mul_f32_e32 v25, v25, v247
	v_mul_f32_e32 v29, v29, v247
	v_cvt_pk_bf16_f32 v25, v25, v29
	s_nop 0
	global_store_short v235, v25, s[74:75] offset:192
	global_store_short_d16_hi v235, v25, s[74:75] offset:224
	s_add_u32 s74, s36, 8192
	s_addc_u32 s75, s37, 0
	v_mul_f32_e32 v2, v2, v248
	v_mul_f32_e32 v6, v6, v248
	v_cvt_pk_bf16_f32 v2, v2, v6
	s_nop 0
	global_store_short v235, v2, s[74:75] offset:0
	global_store_short_d16_hi v235, v2, s[74:75] offset:32
	v_mul_f32_e32 v10, v10, v248
	v_mul_f32_e32 v14, v14, v248
	v_cvt_pk_bf16_f32 v10, v10, v14
	s_nop 0
	global_store_short v235, v10, s[74:75] offset:64
	global_store_short_d16_hi v235, v10, s[74:75] offset:96
	v_mul_f32_e32 v18, v18, v248
	v_mul_f32_e32 v22, v22, v248
	v_cvt_pk_bf16_f32 v18, v18, v22
	s_nop 0
	global_store_short v235, v18, s[74:75] offset:128
	global_store_short_d16_hi v235, v18, s[74:75] offset:160
	v_mul_f32_e32 v26, v26, v248
	v_mul_f32_e32 v30, v30, v248
	v_cvt_pk_bf16_f32 v26, v26, v30
	s_nop 0
	global_store_short v235, v26, s[74:75] offset:192
	global_store_short_d16_hi v235, v26, s[74:75] offset:224
	s_add_u32 s74, s36, 12288
	s_addc_u32 s75, s37, 0
	v_mul_f32_e32 v3, v3, v249
	v_mul_f32_e32 v7, v7, v249
	v_cvt_pk_bf16_f32 v3, v3, v7
	s_nop 0
	global_store_short v235, v3, s[74:75] offset:0
	global_store_short_d16_hi v235, v3, s[74:75] offset:32
	v_mul_f32_e32 v11, v11, v249
	v_mul_f32_e32 v15, v15, v249
	v_cvt_pk_bf16_f32 v11, v11, v15
	s_nop 0
	global_store_short v235, v11, s[74:75] offset:64
	global_store_short_d16_hi v235, v11, s[74:75] offset:96
	v_mul_f32_e32 v19, v19, v249
	v_mul_f32_e32 v23, v23, v249
	v_cvt_pk_bf16_f32 v19, v19, v23
	s_nop 0
	global_store_short v235, v19, s[74:75] offset:128
	global_store_short_d16_hi v235, v19, s[74:75] offset:160
	v_mul_f32_e32 v27, v27, v249
	v_mul_f32_e32 v31, v31, v249
	v_cvt_pk_bf16_f32 v27, v27, v31
	s_nop 0
	global_store_short v235, v27, s[74:75] offset:192
	global_store_short_d16_hi v235, v27, s[74:75] offset:224
	ds_read_b128 v[246:249], v232 offset:64
	s_waitcnt lgkmcnt(0)
	s_add_u32 s74, s36, 65536
	s_addc_u32 s75, s37, 0
	v_mul_f32_e32 v32, v32, v246
	v_mul_f32_e32 v36, v36, v246
	v_cvt_pk_bf16_f32 v32, v32, v36
	s_nop 0
	global_store_short v235, v32, s[74:75] offset:0
	global_store_short_d16_hi v235, v32, s[74:75] offset:32
	v_mul_f32_e32 v40, v40, v246
	v_mul_f32_e32 v44, v44, v246
	v_cvt_pk_bf16_f32 v40, v40, v44
	s_nop 0
	global_store_short v235, v40, s[74:75] offset:64
	global_store_short_d16_hi v235, v40, s[74:75] offset:96
	v_mul_f32_e32 v48, v48, v246
	v_mul_f32_e32 v52, v52, v246
	v_cvt_pk_bf16_f32 v48, v48, v52
	s_nop 0
	global_store_short v235, v48, s[74:75] offset:128
	global_store_short_d16_hi v235, v48, s[74:75] offset:160
	v_mul_f32_e32 v56, v56, v246
	v_mul_f32_e32 v60, v60, v246
	v_cvt_pk_bf16_f32 v56, v56, v60
	s_nop 0
	global_store_short v235, v56, s[74:75] offset:192
	global_store_short_d16_hi v235, v56, s[74:75] offset:224
	s_add_u32 s74, s36, 69632
	s_addc_u32 s75, s37, 0
	v_mul_f32_e32 v33, v33, v247
	v_mul_f32_e32 v37, v37, v247
	v_cvt_pk_bf16_f32 v33, v33, v37
	s_nop 0
	global_store_short v235, v33, s[74:75] offset:0
	global_store_short_d16_hi v235, v33, s[74:75] offset:32
	v_mul_f32_e32 v41, v41, v247
	v_mul_f32_e32 v45, v45, v247
	v_cvt_pk_bf16_f32 v41, v41, v45
	s_nop 0
	global_store_short v235, v41, s[74:75] offset:64
	global_store_short_d16_hi v235, v41, s[74:75] offset:96
	v_mul_f32_e32 v49, v49, v247
	v_mul_f32_e32 v53, v53, v247
	v_cvt_pk_bf16_f32 v49, v49, v53
	s_nop 0
	global_store_short v235, v49, s[74:75] offset:128
	global_store_short_d16_hi v235, v49, s[74:75] offset:160
	v_mul_f32_e32 v57, v57, v247
	v_mul_f32_e32 v61, v61, v247
	v_cvt_pk_bf16_f32 v57, v57, v61
	s_nop 0
	global_store_short v235, v57, s[74:75] offset:192
	global_store_short_d16_hi v235, v57, s[74:75] offset:224
	s_add_u32 s74, s36, 73728
	s_addc_u32 s75, s37, 0
	v_mul_f32_e32 v34, v34, v248
	v_mul_f32_e32 v38, v38, v248
	v_cvt_pk_bf16_f32 v34, v34, v38
	s_nop 0
	global_store_short v235, v34, s[74:75] offset:0
	global_store_short_d16_hi v235, v34, s[74:75] offset:32
	v_mul_f32_e32 v42, v42, v248
; __device__ __forceinline__ unsigned char* opq(unsigned char* q) { asm volatile("" : "+s"(q)); return q; }
; template <bool FIRST>
; __device__ __forceinline__ void partialSM(f32x16& p0, f32x16& p1, float& m_reg, float& alpha) {
;     ...
;   { auto rr = __builtin_amdgcn_permlane32_swap(__float_as_uint(pmax), __float_as_uint(pmax), false, false);
;     pmax = fmaxf(__uint_as_float(rr[0]), __uint_as_float(rr[1])); }
;   if (!FIRST && __builtin_expect(__all(pmax <= THR2), 1)) { alpha = 1.f; }
;   else { const float d = FIRST ? pmax : fmaxf(pmax, 0.f); alpha = FIRST ? 1.f : __builtin_amdgcn_exp2f(-d); m_reg += d;
; #pragma unroll
;     for (int r = 0; r < 16; ++r) p0[r] -= d;
; #pragma unroll
;     for (int r = 0; r < 16; ++r) p1[r] -= d; }
; __global__ void __launch_bounds__(512, 2) mega_fwd(KArgs a) {
;     ...
;             for (int qb = x8 ? slot : bx; qb < 64; qb += x8 ? nslot : G) {
;               const bf16_t* Qb = (const bf16_t*)(opq(a.ws) + WS_Q) + ((size_t)(b * 8 + h) * T + (size_t)qb * 256) * 192;
;               const bf16_t* Kn = (const bf16_t*)(opq(a.ws) + WS_KN) + (size_t)(b * 8 + h) * T * 128;
;               const bf16_t* Kr = (const bf16_t*)(opq(a.ws) + WS_KR) + (size_t)b * T * 64;
;               const bf16_t* Vh = (const bf16_t*)(opq(a.ws) + WS_V) + (size_t)(b * 8 + h) * T * 128;
;               bf16_t* Ob = (bf16_t*)(opq(a.ws) + WS_XN) + ((size_t)b * T + (size_t)qb * 256) * DM + 1024 + h * 128;
;     ...
;               for (int rep_ = 0; rep_ < PROBE_ATT_REP; ++rep_) att::attn_unit(Qb, Kn, Kr, Vh, Ob, (char*)smem);
	v_mul_f32_e32 v46, v46, v248
	v_cvt_pk_bf16_f32 v42, v42, v46
	s_nop 0
	global_store_short v235, v42, s[74:75] offset:64
	global_store_short_d16_hi v235, v42, s[74:75] offset:96
	v_mul_f32_e32 v50, v50, v248
	v_mul_f32_e32 v54, v54, v248
	v_cvt_pk_bf16_f32 v50, v50, v54
	s_nop 0
	global_store_short v235, v50, s[74:75] offset:128
	global_store_short_d16_hi v235, v50, s[74:75] offset:160
	v_mul_f32_e32 v58, v58, v248
	v_mul_f32_e32 v62, v62, v248
	v_cvt_pk_bf16_f32 v58, v58, v62
	s_nop 0
	global_store_short v235, v58, s[74:75] offset:192
	global_store_short_d16_hi v235, v58, s[74:75] offset:224
	s_add_u32 s74, s36, 77824
	s_addc_u32 s75, s37, 0
	v_mul_f32_e32 v35, v35, v249
	v_mul_f32_e32 v39, v39, v249
	v_cvt_pk_bf16_f32 v35, v35, v39
	s_nop 0
	global_store_short v235, v35, s[74:75] offset:0
	global_store_short_d16_hi v235, v35, s[74:75] offset:32
	v_mul_f32_e32 v43, v43, v249
	v_mul_f32_e32 v47, v47, v249
	v_cvt_pk_bf16_f32 v43, v43, v47
	s_nop 0
	global_store_short v235, v43, s[74:75] offset:64
	global_store_short_d16_hi v235, v43, s[74:75] offset:96
	v_mul_f32_e32 v51, v51, v249
	v_mul_f32_e32 v55, v55, v249
	v_cvt_pk_bf16_f32 v51, v51, v55
	s_nop 0
	global_store_short v235, v51, s[74:75] offset:128
	global_store_short_d16_hi v235, v51, s[74:75] offset:160
	v_mul_f32_e32 v59, v59, v249
	v_mul_f32_e32 v63, v63, v249
	v_cvt_pk_bf16_f32 v59, v59, v63
	s_nop 0
	global_store_short v235, v59, s[74:75] offset:192
	global_store_short_d16_hi v235, v59, s[74:75] offset:224
	v_bfrev_b32_e32 v236, 0.5
	v_mbcnt_lo_u32_b32 v237, -1, 0
	v_mov_b32_e32 v238, 0x41b17218
	v_mov_b32_e32 v239, 1
	v_mov_b64_e32 v[240:241], 0x400
	v_mov_b32_e32 v242, 0x3000
	v_mbcnt_hi_u32_b32 v237, -1, v237
	s_waitcnt vmcnt(0)
	v_readlane_b32 s6, v254, 15
	s_add_i32 s16, s16, s6
	s_cmp_gt_i32 s16, 63
	s_waitcnt lgkmcnt(0)
	s_barrier
	s_cbranch_scc1 .LBB0_462
	s_branch .LBB0_466
.Lat_rare_0:
	v_mov_b32_e32 v243, v233
	s_nop 1
	v_permlane32_swap_b32_e32 v233, v243
	s_nop 1
	v_max_f32_e32 v233, v233, v243
	s_nop 1
	ds_bpermute_b32 v243, v112, v233
	s_waitcnt lgkmcnt(0)
	v_max_f32_e32 v233, v233, v243
	v_add_f32_e32 v220, v220, v233
	v_exp_f32_e64 v244, -v233
	v_sub_f32_e32 v114, v114, v233
	v_sub_f32_e32 v115, v115, v233
	v_sub_f32_e32 v116, v116, v233
	v_sub_f32_e32 v117, v117, v233
	v_sub_f32_e32 v122, v122, v233
	v_sub_f32_e32 v123, v123, v233
	v_sub_f32_e32 v124, v124, v233
	v_sub_f32_e32 v125, v125, v233
	v_sub_f32_e32 v130, v130, v233
	v_sub_f32_e32 v131, v131, v233
	v_sub_f32_e32 v132, v132, v233
	v_sub_f32_e32 v133, v133, v233
	v_sub_f32_e32 v138, v138, v233
	v_sub_f32_e32 v139, v139, v233
	v_sub_f32_e32 v140, v140, v233
	v_sub_f32_e32 v141, v141, v233
	v_sub_f32_e32 v224, 0, v220
	v_sub_f32_e32 v225, 0, v220
	v_sub_f32_e32 v226, 0, v220
	v_sub_f32_e32 v227, 0, v220
	v_mov_b32_e32 v243, v234
	s_nop 1
	v_permlane32_swap_b32_e32 v234, v243
	s_nop 1
	v_max_f32_e32 v234, v234, v243
	s_nop 1
	ds_bpermute_b32 v243, v112, v234
	s_waitcnt lgkmcnt(0)
	v_max_f32_e32 v234, v234, v243
	v_add_f32_e32 v221, v221, v234
	v_exp_f32_e64 v244, -v234
	v_sub_f32_e32 v118, v118, v234
	v_sub_f32_e32 v119, v119, v234
	v_sub_f32_e32 v120, v120, v234
	v_sub_f32_e32 v121, v121, v234
	v_sub_f32_e32 v126, v126, v234
	v_sub_f32_e32 v127, v127, v234
	v_sub_f32_e32 v128, v128, v234
	v_sub_f32_e32 v129, v129, v234
	v_sub_f32_e32 v134, v134, v234
	v_sub_f32_e32 v135, v135, v234
	v_sub_f32_e32 v136, v136, v234
	v_sub_f32_e32 v137, v137, v234
	v_sub_f32_e32 v142, v142, v234
	v_sub_f32_e32 v143, v143, v234
	v_sub_f32_e32 v144, v144, v234
	v_sub_f32_e32 v145, v145, v234
	v_sub_f32_e32 v228, 0, v221
	v_sub_f32_e32 v229, 0, v221
	v_sub_f32_e32 v230, 0, v221
	v_sub_f32_e32 v231, 0, v221
	s_nop 1
	s_branch .Lat_cont_0
; template <bool FIRST>
; __device__ __forceinline__ void partialSM(f32x16& p0, f32x16& p1, float& m_reg, float& alpha) {
;     ...
;   { auto rr = __builtin_amdgcn_permlane32_swap(__float_as_uint(pmax), __float_as_uint(pmax), false, false);
;     pmax = fmaxf(__uint_as_float(rr[0]), __uint_as_float(rr[1])); }
;   if (!FIRST && __builtin_expect(__all(pmax <= THR2), 1)) { alpha = 1.f; }
;   else { const float d = FIRST ? pmax : fmaxf(pmax, 0.f); alpha = FIRST ? 1.f : __builtin_amdgcn_exp2f(-d); m_reg += d;
; #pragma unroll
;     for (int r = 0; r < 16; ++r) p0[r] -= d;
; #pragma unroll
;     for (int r = 0; r < 16; ++r) p1[r] -= d; }
.Lat_rare_1:
	v_mov_b32_e32 v243, v233
	s_nop 1
	v_permlane32_swap_b32_e32 v233, v243
	s_nop 1
	v_max_f32_e32 v233, v233, v243
	s_nop 1
	ds_bpermute_b32 v243, v112, v233
	s_waitcnt lgkmcnt(0)
	v_max_f32_e32 v233, v233, v243
	v_max_f32_e32 v233, 0, v233
	v_add_f32_e32 v220, v220, v233
	v_exp_f32_e64 v244, -v233
	v_sub_f32_e32 v114, v114, v233
	v_sub_f32_e32 v115, v115, v233
	v_sub_f32_e32 v116, v116, v233
	v_sub_f32_e32 v117, v117, v233
	v_sub_f32_e32 v122, v122, v233
	v_sub_f32_e32 v123, v123, v233
	v_sub_f32_e32 v124, v124, v233
	v_sub_f32_e32 v125, v125, v233
	v_sub_f32_e32 v130, v130, v233
	v_sub_f32_e32 v131, v131, v233
	v_sub_f32_e32 v132, v132, v233
	v_sub_f32_e32 v133, v133, v233
	v_sub_f32_e32 v138, v138, v233
	v_sub_f32_e32 v139, v139, v233
	v_sub_f32_e32 v140, v140, v233
	v_sub_f32_e32 v141, v141, v233
	v_sub_f32_e32 v224, 0, v220
	v_sub_f32_e32 v225, 0, v220
	v_sub_f32_e32 v226, 0, v220
	v_sub_f32_e32 v227, 0, v220
	v_mul_f32_e32 v222, v222, v244
	ds_write_b32 v219, v244 offset:0
	s_waitcnt lgkmcnt(0)
	ds_read_b128 v[246:249], v232 offset:0
	s_waitcnt lgkmcnt(0)
	v_mul_f32_e32 v0, v0, v246
	v_mul_f32_e32 v1, v1, v247
	v_mul_f32_e32 v2, v2, v248
	v_mul_f32_e32 v3, v3, v249
	v_mul_f32_e32 v4, v4, v246
	v_mul_f32_e32 v5, v5, v247
	v_mul_f32_e32 v6, v6, v248
	v_mul_f32_e32 v7, v7, v249
	v_mul_f32_e32 v8, v8, v246
	v_mul_f32_e32 v9, v9, v247
	v_mul_f32_e32 v10, v10, v248
	v_mul_f32_e32 v11, v11, v249
	v_mul_f32_e32 v12, v12, v246
	v_mul_f32_e32 v13, v13, v247
	v_mul_f32_e32 v14, v14, v248
	v_mul_f32_e32 v15, v15, v249
	v_mul_f32_e32 v16, v16, v246
	v_mul_f32_e32 v17, v17, v247
	v_mul_f32_e32 v18, v18, v248
	v_mul_f32_e32 v19, v19, v249
	v_mul_f32_e32 v20, v20, v246
	v_mul_f32_e32 v21, v21, v247
	v_mul_f32_e32 v22, v22, v248
	v_mul_f32_e32 v23, v23, v249
	v_mul_f32_e32 v24, v24, v246
	v_mul_f32_e32 v25, v25, v247
	v_mul_f32_e32 v26, v26, v248
	v_mul_f32_e32 v27, v27, v249
	v_mul_f32_e32 v28, v28, v246
	v_mul_f32_e32 v29, v29, v247
	v_mul_f32_e32 v30, v30, v248
	v_mul_f32_e32 v31, v31, v249
	v_mov_b32_e32 v243, v234
	s_nop 1
	v_permlane32_swap_b32_e32 v234, v243
	s_nop 1
	v_max_f32_e32 v234, v234, v243
	s_nop 1
	ds_bpermute_b32 v243, v112, v234
	s_waitcnt lgkmcnt(0)
	v_max_f32_e32 v234, v234, v243
	v_max_f32_e32 v234, 0, v234
	v_add_f32_e32 v221, v221, v234
	v_exp_f32_e64 v244, -v234
	v_sub_f32_e32 v118, v118, v234
	v_sub_f32_e32 v119, v119, v234
	v_sub_f32_e32 v120, v120, v234
	v_sub_f32_e32 v121, v121, v234
	v_sub_f32_e32 v126, v126, v234
	v_sub_f32_e32 v127, v127, v234
	v_sub_f32_e32 v128, v128, v234
	v_sub_f32_e32 v129, v129, v234
	v_sub_f32_e32 v134, v134, v234
	v_sub_f32_e32 v135, v135, v234
	v_sub_f32_e32 v136, v136, v234
	v_sub_f32_e32 v137, v137, v234
	v_sub_f32_e32 v142, v142, v234
	v_sub_f32_e32 v143, v143, v234
	v_sub_f32_e32 v144, v144, v234
	v_sub_f32_e32 v145, v145, v234
	v_sub_f32_e32 v228, 0, v221
	v_sub_f32_e32 v229, 0, v221
	v_sub_f32_e32 v230, 0, v221
	v_sub_f32_e32 v231, 0, v221
	v_mul_f32_e32 v223, v223, v244
	ds_write_b32 v219, v244 offset:64
	s_waitcnt lgkmcnt(0)
	ds_read_b128 v[246:249], v232 offset:64
	s_waitcnt lgkmcnt(0)
	v_mul_f32_e32 v32, v32, v246
	v_mul_f32_e32 v33, v33, v247
	v_mul_f32_e32 v34, v34, v248
	v_mul_f32_e32 v35, v35, v249
	v_mul_f32_e32 v36, v36, v246
	v_mul_f32_e32 v37, v37, v247
	v_mul_f32_e32 v38, v38, v248
	v_mul_f32_e32 v39, v39, v249
	v_mul_f32_e32 v40, v40, v246
	v_mul_f32_e32 v41, v41, v247
	v_mul_f32_e32 v42, v42, v248
	v_mul_f32_e32 v43, v43, v249
	v_mul_f32_e32 v44, v44, v246
	v_mul_f32_e32 v45, v45, v247
	v_mul_f32_e32 v46, v46, v248
	v_mul_f32_e32 v47, v47, v249
	v_mul_f32_e32 v48, v48, v246
	v_mul_f32_e32 v49, v49, v247
	v_mul_f32_e32 v50, v50, v248
	v_mul_f32_e32 v51, v51, v249
	v_mul_f32_e32 v52, v52, v246
	v_mul_f32_e32 v53, v53, v247
	v_mul_f32_e32 v54, v54, v248
	v_mul_f32_e32 v55, v55, v249
	v_mul_f32_e32 v56, v56, v246
	v_mul_f32_e32 v57, v57, v247
	v_mul_f32_e32 v58, v58, v248
	v_mul_f32_e32 v59, v59, v249
	v_mul_f32_e32 v60, v60, v246
	v_mul_f32_e32 v61, v61, v247
	v_mul_f32_e32 v62, v62, v248
	v_mul_f32_e32 v63, v63, v249
	s_nop 1
	s_branch .Lat_cont_1

; __device__ __forceinline__ float bf2f(unsigned v) { return __uint_as_float(v << 16); }
; template <int TYPE>
; __device__ __forceinline__ void pass3_item(const KArgs& a, int l, int item, LAS unsigned char* lds) {
;     ...
;     const float gain = ((const float*)a.in[TYPE ? 7 : 5])[l * 128 + wid * 16 + fr];
;     bf16_t* mix = (bf16_t*)(wsb + WS_XN);
;     float gtv[4][4];
; #pragma unroll
;     for (int it = 0; it < 4; ++it)
; #pragma unroll
;         for (int r = 0; r < 4; ++r) gtv[it][r] = bf2f(u[(tok0 + it * 16 + fq * 4 + r) * DINP + (TYPE ? C_HG : C_GG) + h * 128 + wid * 16 + fr]);
.LBB0_492:
	s_or_b64 exec, exec, s[6:7]
	v_readlane_b32 s6, v255, 29
	v_readlane_b32 s8, v253, 48
	v_readlane_b32 s22, v253, 62
	v_add_u32_e32 v16, s6, v64
	v_or_b32_e32 v16, v16, v89
	v_ashrrev_i32_e32 v17, 31, v16
	v_readlane_b32 s23, v253, 63
	v_readlane_b32 s9, v253, 49
	v_or_b32_e32 v42, s60, v83
	v_lshl_add_u64 v[16:17], v[16:17], 2, s[22:23]
	v_mov_b64_e32 v[50:51], s[62:63]
	s_movk_i32 s2, 0x2a00
	s_waitcnt lgkmcnt(0)
	s_barrier
	global_load_dword v52, v[16:17], off
	s_mul_i32 s6, s61, 0x2a00
	v_mad_u64_u32 v[16:17], s[8:9], v42, s2, v[50:51]
	v_ashrrev_i32_e32 v65, 31, v64
	v_add_u32_e32 v17, s6, v17
	s_lshl_b32 s72, s5, 1
	v_lshl_add_u64 v[16:17], v[16:17], 0, s[72:73]
	v_lshlrev_b64 v[24:25], 1, v[64:65]
	v_lshl_add_u64 v[16:17], v[16:17], 0, v[24:25]
	v_lshlrev_b32_e32 v112, 1, v89
	v_lshl_add_u64 v[16:17], v[16:17], 0, v[112:113]
	s_movk_i32 s77, 0x1000
	v_add_co_u32_e32 v16, vcc, s77, v16
	v_or_b32_e32 v44, 1, v42
	s_nop 0
	v_addc_co_u32_e32 v17, vcc, 0, v17, vcc
	global_load_ushort v16, v[16:17], off offset:3136
	v_or_b32_e32 v46, 2, v42
	v_or_b32_e32 v48, 3, v42
	v_or_b32_e32 v66, 16, v83
	v_or_b32_e32 v40, s60, v66
	v_or_b32_e32 v38, 17, v42
	v_or_b32_e32 v34, 18, v42
	v_or_b32_e32 v28, 19, v42
	v_or_b32_e32 v59, 32, v83
	v_or_b32_e32 v26, s60, v59
	v_or_b32_e32 v30, 33, v42
	v_or_b32_e32 v32, 34, v42
	v_or_b32_e32 v36, 35, v42
	v_or_b32_e32 v56, 48, v83
	v_or_b32_e32 v22, s60, v56
	v_or_b32_e32 v20, 49, v42
	v_or_b32_e32 v18, 50, v42
	v_mov_b32_e32 v43, s61
	v_mov_b32_e32 v45, s61
	v_mov_b32_e32 v47, s61
	v_mov_b32_e32 v49, s61
	v_mov_b32_e32 v41, s61
	v_mov_b32_e32 v39, s61
	v_mov_b32_e32 v35, s61
	v_mov_b32_e32 v29, s61
	v_mov_b32_e32 v27, s61
	v_mov_b32_e32 v31, s61
	v_mov_b32_e32 v33, s61
	v_mov_b32_e32 v37, s61
	v_mov_b32_e32 v23, s61
	v_mov_b32_e32 v21, s61
	v_mov_b32_e32 v19, s61
	v_readlane_b32 s68, v255, 16
	v_readlane_b32 s70, v255, 18
	v_readlane_b32 s69, v255, 17
	s_movk_i32 s66, 0x80
	s_movk_i32 s67, 0x100
	s_movk_i32 s3, 0x90
	v_readlane_b32 s10, v253, 50
	v_readlane_b32 s11, v253, 51
	v_readlane_b32 s12, v253, 52
	v_readlane_b32 s13, v253, 53
	v_readlane_b32 s14, v253, 54
	v_readlane_b32 s15, v253, 55
	v_readlane_b32 s16, v253, 56
	v_readlane_b32 s17, v253, 57
	v_readlane_b32 s18, v253, 58
	v_readlane_b32 s19, v253, 59
	v_readlane_b32 s20, v253, 60
	v_readlane_b32 s21, v253, 61
	v_readlane_b32 s71, v255, 19
	s_waitcnt vmcnt(0) lgkmcnt(0)
	v_lshlrev_b32_e32 v67, 16, v16
	v_mad_u64_u32 v[16:17], s[8:9], v44, s2, v[50:51]
	v_add_u32_e32 v17, s6, v17
	v_lshl_add_u64 v[16:17], v[16:17], 0, s[72:73]
	v_lshl_add_u64 v[16:17], v[16:17], 0, v[24:25]
	v_lshl_add_u64 v[16:17], v[16:17], 0, v[112:113]
	v_add_co_u32_e32 v16, vcc, s77, v16
	s_nop 1
	v_addc_co_u32_e32 v17, vcc, 0, v17, vcc
	global_load_ushort v16, v[16:17], off offset:3136
	s_waitcnt vmcnt(0) lgkmcnt(0)
	v_lshlrev_b32_e32 v68, 16, v16
	v_mad_u64_u32 v[16:17], s[8:9], v46, s2, v[50:51]
	v_add_u32_e32 v17, s6, v17
	v_lshl_add_u64 v[16:17], v[16:17], 0, s[72:73]
	v_lshl_add_u64 v[16:17], v[16:17], 0, v[24:25]
	v_lshl_add_u64 v[16:17], v[16:17], 0, v[112:113]
	v_add_co_u32_e32 v16, vcc, s77, v16
	s_nop 1
	v_addc_co_u32_e32 v17, vcc, 0, v17, vcc
	global_load_ushort v16, v[16:17], off offset:3136
	s_waitcnt vmcnt(0) lgkmcnt(0)
	v_lshlrev_b32_e32 v69, 16, v16
	v_mad_u64_u32 v[16:17], s[8:9], v48, s2, v[50:51]
	v_add_u32_e32 v17, s6, v17
	v_lshl_add_u64 v[16:17], v[16:17], 0, s[72:73]
	v_lshl_add_u64 v[16:17], v[16:17], 0, v[24:25]
	v_lshl_add_u64 v[16:17], v[16:17], 0, v[112:113]
	v_add_co_u32_e32 v16, vcc, s77, v16
	s_nop 1
	v_addc_co_u32_e32 v17, vcc, 0, v17, vcc
	global_load_ushort v16, v[16:17], off offset:3136
	s_waitcnt vmcnt(0) lgkmcnt(0)
	v_lshlrev_b32_e32 v70, 16, v16
	v_mad_u64_u32 v[16:17], s[8:9], v40, s2, v[50:51]
	v_add_u32_e32 v17, s6, v17
	v_lshl_add_u64 v[16:17], v[16:17], 0, s[72:73]
	v_lshl_add_u64 v[16:17], v[16:17], 0, v[24:25]
	v_lshl_add_u64 v[16:17], v[16:17], 0, v[112:113]
	v_add_co_u32_e32 v16, vcc, s77, v16
	v_lshlrev_b64 v[40:41], 12, v[40:41]
	s_nop 0
	v_addc_co_u32_e32 v17, vcc, 0, v17, vcc
	global_load_ushort v16, v[16:17], off offset:3136
	s_waitcnt vmcnt(0) lgkmcnt(0)
	v_lshlrev_b32_e32 v65, 16, v16
	v_mad_u64_u32 v[16:17], s[8:9], v38, s2, v[50:51]
	v_add_u32_e32 v17, s6, v17
	v_lshl_add_u64 v[16:17], v[16:17], 0, s[72:73]
	v_lshl_add_u64 v[16:17], v[16:17], 0, v[24:25]
	v_lshl_add_u64 v[16:17], v[16:17], 0, v[112:113]
	v_add_co_u32_e32 v16, vcc, s77, v16
	s_nop 1
	v_addc_co_u32_e32 v17, vcc, 0, v17, vcc
	global_load_ushort v16, v[16:17], off offset:3136
	s_waitcnt vmcnt(0) lgkmcnt(0)
	v_lshlrev_b32_e32 v64, 16, v16
	v_mad_u64_u32 v[16:17], s[8:9], v34, s2, v[50:51]
	v_add_u32_e32 v17, s6, v17
	v_lshl_add_u64 v[16:17], v[16:17], 0, s[72:73]
	v_lshl_add_u64 v[16:17], v[16:17], 0, v[24:25]
	v_lshl_add_u64 v[16:17], v[16:17], 0, v[112:113]
	v_add_co_u32_e32 v16, vcc, s77, v16
	s_nop 1
	v_addc_co_u32_e32 v17, vcc, 0, v17, vcc
	global_load_ushort v16, v[16:17], off offset:3136
	s_waitcnt vmcnt(0) lgkmcnt(0)
	v_lshlrev_b32_e32 v62, 16, v16
	v_mad_u64_u32 v[16:17], s[8:9], v28, s2, v[50:51]
	v_add_u32_e32 v17, s6, v17
	v_lshl_add_u64 v[16:17], v[16:17], 0, s[72:73]
	v_lshl_add_u64 v[16:17], v[16:17], 0, v[24:25]
	v_lshl_add_u64 v[16:17], v[16:17], 0, v[112:113]
	v_add_co_u32_e32 v16, vcc, s77, v16
	s_nop 1
	v_addc_co_u32_e32 v17, vcc, 0, v17, vcc
	global_load_ushort v16, v[16:17], off offset:3136
	s_waitcnt vmcnt(0) lgkmcnt(0)
; __device__ __forceinline__ float bf2f(unsigned v) { return __uint_as_float(v << 16); }
; __device__ __forceinline__ unsigned f2bf(float f) { unsigned u = __float_as_uint(f); return (u + 0x7fffu + ((u >> 16) & 1u)) >> 16; }
; __device__ __forceinline__ float silu_(float z) { return z * sigmoid_(z); }
; template <int TYPE>
; __device__ __forceinline__ void pass3_item(const KArgs& a, int l, int item, LAS unsigned char* lds) {
;     ...
;     const float gain = ((const float*)a.in[TYPE ? 7 : 5])[l * 128 + wid * 16 + fr];
;     bf16_t* mix = (bf16_t*)(wsb + WS_XN);
;     float gtv[4][4];
; #pragma unroll
;     for (int it = 0; it < 4; ++it)
; #pragma unroll
;         for (int r = 0; r < 4; ++r) gtv[it][r] = bf2f(u[(tok0 + it * 16 + fq * 4 + r) * DINP + (TYPE ? C_HG : C_GG) + h * 128 + wid * 16 + fr]);
; #pragma unroll
;     for (int it = 0; it < 4; ++it)
; #pragma unroll
;         for (int r = 0; r < 4; ++r) { const int i = it * 16 + fq * 4 + r;
;             const float rstd = RSTD[i];
;             const float gt = gtv[it][r];
;             const float yv = o[it][r] * rstd * gain * silu_(gt);
;             mix[(tok0 + i) * DM + (TYPE ? 512 : 0) + h * 128 + wid * 16 + fr] = (bf16_t)f2bf(yv); }
	v_lshlrev_b32_e32 v60, 16, v16
	v_mad_u64_u32 v[16:17], s[8:9], v26, s2, v[50:51]
	v_add_u32_e32 v17, s6, v17
	v_lshl_add_u64 v[16:17], v[16:17], 0, s[72:73]
	v_lshl_add_u64 v[16:17], v[16:17], 0, v[24:25]
	v_lshl_add_u64 v[16:17], v[16:17], 0, v[112:113]
	v_add_co_u32_e32 v16, vcc, s77, v16
	s_nop 1
	v_addc_co_u32_e32 v17, vcc, 0, v17, vcc
	global_load_ushort v16, v[16:17], off offset:3136
	s_waitcnt vmcnt(0) lgkmcnt(0)
	v_lshlrev_b32_e32 v57, 16, v16
	v_mad_u64_u32 v[16:17], s[8:9], v30, s2, v[50:51]
	v_add_u32_e32 v17, s6, v17
	v_lshl_add_u64 v[16:17], v[16:17], 0, s[72:73]
	v_lshl_add_u64 v[16:17], v[16:17], 0, v[24:25]
	v_lshl_add_u64 v[16:17], v[16:17], 0, v[112:113]
	v_add_co_u32_e32 v16, vcc, s77, v16
	s_nop 1
	v_addc_co_u32_e32 v17, vcc, 0, v17, vcc
	global_load_ushort v16, v[16:17], off offset:3136
	s_waitcnt vmcnt(0) lgkmcnt(0)
	v_lshlrev_b32_e32 v58, 16, v16
	v_mad_u64_u32 v[16:17], s[8:9], v32, s2, v[50:51]
	v_add_u32_e32 v17, s6, v17
	v_lshl_add_u64 v[16:17], v[16:17], 0, s[72:73]
	v_lshl_add_u64 v[16:17], v[16:17], 0, v[24:25]
	v_lshl_add_u64 v[16:17], v[16:17], 0, v[112:113]
	v_add_co_u32_e32 v16, vcc, s77, v16
	s_nop 1
	v_addc_co_u32_e32 v17, vcc, 0, v17, vcc
	global_load_ushort v16, v[16:17], off offset:3136
	s_waitcnt vmcnt(0) lgkmcnt(0)
	v_lshlrev_b32_e32 v61, 16, v16
	v_mad_u64_u32 v[16:17], s[8:9], v36, s2, v[50:51]
	v_add_u32_e32 v17, s6, v17
	v_lshl_add_u64 v[16:17], v[16:17], 0, s[72:73]
	v_lshl_add_u64 v[16:17], v[16:17], 0, v[24:25]
	v_lshl_add_u64 v[16:17], v[16:17], 0, v[112:113]
	v_add_co_u32_e32 v16, vcc, s77, v16
	s_nop 1
	v_addc_co_u32_e32 v17, vcc, 0, v17, vcc
	global_load_ushort v16, v[16:17], off offset:3136
	s_waitcnt vmcnt(0) lgkmcnt(0)
	v_lshlrev_b32_e32 v63, 16, v16
	v_mad_u64_u32 v[16:17], s[8:9], v22, s2, v[50:51]
	v_add_u32_e32 v17, s6, v17
	v_lshl_add_u64 v[16:17], v[16:17], 0, s[72:73]
	v_lshl_add_u64 v[16:17], v[16:17], 0, v[24:25]
	v_lshl_add_u64 v[16:17], v[16:17], 0, v[112:113]
	v_add_co_u32_e32 v16, vcc, s77, v16
	s_nop 1
	v_addc_co_u32_e32 v17, vcc, 0, v17, vcc
	global_load_ushort v16, v[16:17], off offset:3136
	s_waitcnt vmcnt(0) lgkmcnt(0)
	v_lshlrev_b32_e32 v55, 16, v16
	v_mad_u64_u32 v[16:17], s[8:9], v20, s2, v[50:51]
	v_add_u32_e32 v17, s6, v17
	v_lshl_add_u64 v[16:17], v[16:17], 0, s[72:73]
	v_lshl_add_u64 v[16:17], v[16:17], 0, v[24:25]
	v_lshl_add_u64 v[16:17], v[16:17], 0, v[112:113]
	v_add_co_u32_e32 v16, vcc, s77, v16
	s_nop 1
	v_addc_co_u32_e32 v17, vcc, 0, v17, vcc
	global_load_ushort v16, v[16:17], off offset:3136
	s_waitcnt vmcnt(0) lgkmcnt(0)
	v_lshlrev_b32_e32 v54, 16, v16
	v_mad_u64_u32 v[16:17], s[8:9], v18, s2, v[50:51]
	v_add_u32_e32 v17, s6, v17
	v_lshl_add_u64 v[16:17], v[16:17], 0, s[72:73]
	v_lshl_add_u64 v[16:17], v[16:17], 0, v[24:25]
	v_lshl_add_u64 v[16:17], v[16:17], 0, v[112:113]
	v_add_co_u32_e32 v16, vcc, s77, v16
	s_nop 1
	v_addc_co_u32_e32 v17, vcc, 0, v17, vcc
	global_load_ushort v16, v[16:17], off offset:3136
	v_mov_b32_e32 v17, s61
	s_waitcnt vmcnt(0) lgkmcnt(0)
	v_lshlrev_b32_e32 v53, 16, v16
	v_or_b32_e32 v16, 51, v42
	v_mad_u64_u32 v[50:51], s[8:9], v16, s2, v[50:51]
	v_add_u32_e32 v51, s6, v51
	v_lshl_add_u64 v[50:51], v[50:51], 0, s[72:73]
	v_lshl_add_u64 v[50:51], v[50:51], 0, v[24:25]
	v_lshl_add_u64 v[50:51], v[50:51], 0, v[112:113]
	v_add_co_u32_e32 v50, vcc, s77, v50
	s_add_u32 s6, s58, s72
	s_nop 0
	v_addc_co_u32_e32 v51, vcc, 0, v51, vcc
	global_load_ushort v50, v[50:51], off offset:3136
	v_lshl_add_u32 v51, v83, 2, s74
	ds_read_b128 v[72:75], v51
	v_mul_f32_e32 v51, 0xbfb8aa3b, v67
	v_exp_f32_e32 v51, v51
	s_addc_u32 s7, s59, 0
	v_lshl_add_u64 v[24:25], s[6:7], 0, v[24:25]
	s_waitcnt lgkmcnt(0)
	v_mul_f32_e32 v12, v12, v72
	v_add_f32_e32 v51, 1.0, v51
	v_rcp_f32_e32 v51, v51
	v_mul_f32_e32 v12, v52, v12
	v_lshl_add_u64 v[24:25], v[24:25], 0, v[112:113]
	s_mov_b64 s[6:7], 0x6300400
	v_mul_f32_e32 v51, v51, v67
	v_mul_f32_e32 v12, v51, v12
	v_lshl_add_u64 v[24:25], v[24:25], 0, s[6:7]
	v_bfe_u32 v51, v12, 16, 1
	v_lshlrev_b64 v[42:43], 12, v[42:43]
	v_add3_u32 v12, v12, v51, s1
	v_lshl_add_u64 v[42:43], v[24:25], 0, v[42:43]
	global_store_short_d16_hi v[42:43], v12, off
	v_mul_f32_e32 v12, v13, v73
	v_mul_f32_e32 v13, 0xbfb8aa3b, v68
	v_exp_f32_e32 v13, v13
	v_mul_f32_e32 v12, v52, v12
	v_lshl_add_u64 v[40:41], v[24:25], 0, v[40:41]
	s_add_i32 s4, s4, s70
	v_add_f32_e32 v13, 1.0, v13
	v_rcp_f32_e32 v13, v13
	s_cmpk_gt_i32 s4, 0x7ff
	v_mul_f32_e32 v13, v13, v68
	v_mul_f32_e32 v12, v13, v12
	v_bfe_u32 v13, v12, 16, 1
	v_add3_u32 v42, v12, v13, s1
	v_lshlrev_b64 v[12:13], 12, v[44:45]
	v_lshl_add_u64 v[12:13], v[24:25], 0, v[12:13]
	global_store_short_d16_hi v[12:13], v42, off
	v_mul_f32_e32 v13, 0xbfb8aa3b, v69
	v_exp_f32_e32 v13, v13
	v_mul_f32_e32 v12, v14, v74
	v_mul_f32_e32 v12, v52, v12
	v_add_f32_e32 v13, 1.0, v13
	v_rcp_f32_e32 v13, v13
	s_waitcnt vmcnt(0)
	v_lshlrev_b32_e32 v50, 16, v50
	v_mul_f32_e32 v13, v13, v69
	v_mul_f32_e32 v12, v13, v12
	v_bfe_u32 v13, v12, 16, 1
	v_add3_u32 v14, v12, v13, s1
	v_lshlrev_b64 v[12:13], 12, v[46:47]
	v_lshl_add_u64 v[12:13], v[24:25], 0, v[12:13]
	global_store_short_d16_hi v[12:13], v14, off
	v_mul_f32_e32 v13, 0xbfb8aa3b, v70
	v_exp_f32_e32 v13, v13
	v_mul_f32_e32 v12, v15, v75
	v_mul_f32_e32 v12, v52, v12
	v_add_f32_e32 v13, 1.0, v13
	v_rcp_f32_e32 v13, v13
	s_nop 0
	v_mul_f32_e32 v13, v13, v70
	v_mul_f32_e32 v12, v13, v12
	v_bfe_u32 v13, v12, 16, 1
	v_add3_u32 v14, v12, v13, s1
	v_lshlrev_b64 v[12:13], 12, v[48:49]
	v_lshl_add_u64 v[12:13], v[24:25], 0, v[12:13]
	global_store_short_d16_hi v[12:13], v14, off
	v_lshl_add_u32 v12, v66, 2, s74
	ds_read_b128 v[12:15], v12
	s_waitcnt lgkmcnt(0)
; __device__ __forceinline__ unsigned f2bf(float f) { unsigned u = __float_as_uint(f); return (u + 0x7fffu + ((u >> 16) & 1u)) >> 16; }
; __device__ __forceinline__ float silu_(float z) { return z * sigmoid_(z); }
; template <int TYPE>
; __device__ __forceinline__ void pass3_item(const KArgs& a, int l, int item, LAS unsigned char* lds) {
;     ...
; #pragma unroll
;     for (int it = 0; it < 4; ++it)
; #pragma unroll
;         for (int r = 0; r < 4; ++r) { const int i = it * 16 + fq * 4 + r;
;             const float rstd = RSTD[i];
;             const float gt = gtv[it][r];
;             const float yv = o[it][r] * rstd * gain * silu_(gt);
;             mix[(tok0 + i) * DM + (TYPE ? 512 : 0) + h * 128 + wid * 16 + fr] = (bf16_t)f2bf(yv); }
	v_mul_f32_e32 v8, v8, v12
	v_mul_f32_e32 v12, 0xbfb8aa3b, v65
	v_exp_f32_e32 v12, v12
	v_mul_f32_e32 v8, v52, v8
	v_add_f32_e32 v12, 1.0, v12
	v_rcp_f32_e32 v12, v12
	s_nop 0
	v_mul_f32_e32 v12, v12, v65
	v_mul_f32_e32 v8, v12, v8
	v_bfe_u32 v12, v8, 16, 1
	v_add3_u32 v8, v8, v12, s1
	global_store_short_d16_hi v[40:41], v8, off
	v_mul_f32_e32 v8, v9, v13
	v_mul_f32_e32 v9, 0xbfb8aa3b, v64
	v_exp_f32_e32 v9, v9
	v_mul_f32_e32 v8, v52, v8
	v_add_f32_e32 v9, 1.0, v9
	v_rcp_f32_e32 v9, v9
	s_nop 0
	v_mul_f32_e32 v9, v9, v64
	v_mul_f32_e32 v8, v9, v8
	v_bfe_u32 v9, v8, 16, 1
	v_add3_u32 v12, v8, v9, s1
	v_lshlrev_b64 v[8:9], 12, v[38:39]
	v_lshl_add_u64 v[8:9], v[24:25], 0, v[8:9]
	global_store_short_d16_hi v[8:9], v12, off
	v_mul_f32_e32 v9, 0xbfb8aa3b, v62
	v_exp_f32_e32 v9, v9
	v_mul_f32_e32 v8, v10, v14
	v_mul_f32_e32 v8, v52, v8
	v_lshlrev_b64 v[12:13], 12, v[26:27]
	v_add_f32_e32 v9, 1.0, v9
	v_rcp_f32_e32 v9, v9
	v_lshl_add_u64 v[12:13], v[24:25], 0, v[12:13]
	v_mul_f32_e32 v9, v9, v62
	v_mul_f32_e32 v8, v9, v8
	v_bfe_u32 v9, v8, 16, 1
	v_add3_u32 v10, v8, v9, s1
	v_lshlrev_b64 v[8:9], 12, v[34:35]
	v_lshl_add_u64 v[8:9], v[24:25], 0, v[8:9]
	global_store_short_d16_hi v[8:9], v10, off
	v_mul_f32_e32 v9, 0xbfb8aa3b, v60
	v_exp_f32_e32 v9, v9
	v_mul_f32_e32 v8, v11, v15
	v_mul_f32_e32 v8, v52, v8
	v_add_f32_e32 v9, 1.0, v9
	v_rcp_f32_e32 v9, v9
	s_nop 0
	v_mul_f32_e32 v9, v9, v60
	v_mul_f32_e32 v8, v9, v8
	v_bfe_u32 v9, v8, 16, 1
	v_add3_u32 v10, v8, v9, s1
	v_lshlrev_b64 v[8:9], 12, v[28:29]
	v_lshl_add_u64 v[8:9], v[24:25], 0, v[8:9]
	global_store_short_d16_hi v[8:9], v10, off
	v_lshl_add_u32 v8, v59, 2, s74
	ds_read_b128 v[8:11], v8
	s_waitcnt lgkmcnt(0)
	v_mul_f32_e32 v4, v4, v8
	v_mul_f32_e32 v8, 0xbfb8aa3b, v57
	v_exp_f32_e32 v8, v8
	v_mul_f32_e32 v4, v52, v4
	v_add_f32_e32 v8, 1.0, v8
	v_rcp_f32_e32 v8, v8
	s_nop 0
	v_mul_f32_e32 v8, v8, v57
	v_mul_f32_e32 v4, v8, v4
	v_bfe_u32 v8, v4, 16, 1
	v_add3_u32 v4, v4, v8, s1
	global_store_short_d16_hi v[12:13], v4, off
	v_mul_f32_e32 v4, v5, v9
	v_mul_f32_e32 v5, 0xbfb8aa3b, v58
	v_exp_f32_e32 v5, v5
	v_mul_f32_e32 v4, v52, v4
	v_add_f32_e32 v5, 1.0, v5
	v_rcp_f32_e32 v5, v5
	s_nop 0
	v_mul_f32_e32 v5, v5, v58
	v_mul_f32_e32 v4, v5, v4
	v_bfe_u32 v5, v4, 16, 1
	v_add3_u32 v8, v4, v5, s1
	v_lshlrev_b64 v[4:5], 12, v[30:31]
	v_lshl_add_u64 v[4:5], v[24:25], 0, v[4:5]
	global_store_short_d16_hi v[4:5], v8, off
	v_mul_f32_e32 v5, 0xbfb8aa3b, v61
	v_exp_f32_e32 v5, v5
	v_mul_f32_e32 v4, v6, v10
	v_mul_f32_e32 v4, v52, v4
	v_lshlrev_b64 v[8:9], 12, v[22:23]
	v_add_f32_e32 v5, 1.0, v5
	v_rcp_f32_e32 v5, v5
	v_lshl_add_u64 v[8:9], v[24:25], 0, v[8:9]
	v_mul_f32_e32 v5, v5, v61
	v_mul_f32_e32 v4, v5, v4
	v_bfe_u32 v5, v4, 16, 1
	v_add3_u32 v6, v4, v5, s1
	v_lshlrev_b64 v[4:5], 12, v[32:33]
	v_lshl_add_u64 v[4:5], v[24:25], 0, v[4:5]
	global_store_short_d16_hi v[4:5], v6, off
	v_mul_f32_e32 v5, 0xbfb8aa3b, v63
	v_exp_f32_e32 v5, v5
	v_mul_f32_e32 v4, v7, v11
	v_mul_f32_e32 v4, v52, v4
	v_add_f32_e32 v5, 1.0, v5
	v_rcp_f32_e32 v5, v5
	s_nop 0
	v_mul_f32_e32 v5, v5, v63
	v_mul_f32_e32 v4, v5, v4
	v_bfe_u32 v5, v4, 16, 1
	v_add3_u32 v6, v4, v5, s1
	v_lshlrev_b64 v[4:5], 12, v[36:37]
	v_lshl_add_u64 v[4:5], v[24:25], 0, v[4:5]
	global_store_short_d16_hi v[4:5], v6, off
	v_lshl_add_u32 v4, v56, 2, s74
	ds_read_b128 v[4:7], v4
	s_waitcnt lgkmcnt(0)
	v_mul_f32_e32 v0, v0, v4
	v_mul_f32_e32 v4, 0xbfb8aa3b, v55
	v_exp_f32_e32 v4, v4
	v_mul_f32_e32 v0, v52, v0
	v_add_f32_e32 v4, 1.0, v4
	v_rcp_f32_e32 v4, v4
	s_nop 0
	v_mul_f32_e32 v4, v4, v55
	v_mul_f32_e32 v0, v4, v0
	v_bfe_u32 v4, v0, 16, 1
	v_add3_u32 v0, v0, v4, s1
	global_store_short_d16_hi v[8:9], v0, off
	v_mul_f32_e32 v0, v1, v5
	v_mul_f32_e32 v1, 0xbfb8aa3b, v54
	v_exp_f32_e32 v1, v1
	v_mul_f32_e32 v0, v52, v0
	v_add_f32_e32 v1, 1.0, v1
	v_rcp_f32_e32 v1, v1
	s_nop 0
	v_mul_f32_e32 v1, v1, v54
	v_mul_f32_e32 v0, v1, v0
	v_bfe_u32 v1, v0, 16, 1
	v_add3_u32 v4, v0, v1, s1
	v_lshlrev_b64 v[0:1], 12, v[20:21]
	v_lshl_add_u64 v[0:1], v[24:25], 0, v[0:1]
	global_store_short_d16_hi v[0:1], v4, off
	v_mul_f32_e32 v1, 0xbfb8aa3b, v53
	v_exp_f32_e32 v1, v1
	v_mul_f32_e32 v0, v2, v6
	v_mul_f32_e32 v0, v52, v0
	v_add_f32_e32 v1, 1.0, v1
	v_rcp_f32_e32 v1, v1
	s_nop 0
	v_mul_f32_e32 v1, v1, v53
	v_mul_f32_e32 v0, v1, v0
	v_bfe_u32 v1, v0, 16, 1
	v_add3_u32 v2, v0, v1, s1
	v_lshlrev_b64 v[0:1], 12, v[18:19]
	v_lshl_add_u64 v[0:1], v[24:25], 0, v[0:1]
	global_store_short_d16_hi v[0:1], v2, off
	v_mul_f32_e32 v1, 0xbfb8aa3b, v50
	v_exp_f32_e32 v1, v1
	v_mul_f32_e32 v0, v3, v7
	v_mul_f32_e32 v0, v52, v0
	v_add_f32_e32 v1, 1.0, v1
	v_rcp_f32_e32 v1, v1
	s_nop 0
	v_mul_f32_e32 v1, v1, v50
	v_mul_f32_e32 v0, v1, v0
	v_bfe_u32 v1, v0, 16, 1
	v_add3_u32 v2, v0, v1, s1
	v_lshlrev_b64 v[0:1], 12, v[16:17]
	v_lshl_add_u64 v[0:1], v[24:25], 0, v[0:1]
	global_store_short_d16_hi v[0:1], v2, off
	s_cbranch_scc1 .LBB0_508
; #define LAS __attribute__((address_space(3)))
; __device__ __forceinline__ float silu_(float z) { return z * sigmoid_(z); }
; __device__ __forceinline__ void vT_write(const VRaw& r, LAS unsigned char* lds, int tid) {
;     LAS bf16_t* VT = (LAS bf16_t*)(lds + SC_VT);
;     const int v8 = tid & 15;
; #pragma unroll
;     for (int e2 = 0; e2 < 2; ++e2) { const int i = (tid >> 4) + 32 * e2; const bf16x8 x = e2 ? r.x1 : r.x0; const int pc = ((((i >> 3) ^ (v8 & 7)) << 3) | (i & 7));
; #pragma unroll
;         for (int e = 0; e < 8; ++e) VT[(v8 * 8 + e) * LDT + pc] = (bf16_t)x[e]; }
; }
; template <int TYPE>
; __device__ __forceinline__ void pass3_item(const KArgs& a, int l, int item, LAS unsigned char* lds) {
;     ...
;     const int c = item & (NCH - 1), h = (item >> 8) & 3, b = item >> 10;
;     const size_t tok0 = (size_t)b * T + (size_t)c * 64;
;     const bf16_t* u = (const bf16_t*)(wsb + WS_U);
;     const int wid = tid >> 6, lane = tid & 63, fr = lane & 15, fq = lane >> 4;
;     LAS float* G = (LAS float*)(lds + SC_G); LAS bf16_t* Kb = (LAS bf16_t*)(lds + SC_K); LAS bf16_t* QT = (LAS bf16_t*)(lds + SC_QT); LAS bf16_t* QG = (LAS bf16_t*)(lds + SC_QG);
;     LAS bf16_t* VT = (LAS bf16_t*)(lds + SC_VT); LAS bf16_t* P = (LAS bf16_t*)(lds + SC_P); LAS float* RSQ = (LAS float*)(lds + SC_RSQ);
;     const VRaw vr = vT_issue(u + tok0 * DINP + (TYPE ? C_HI : C_GV) + h * 128, tid);
;     bf16x8 qraw[DK / 64];
; #pragma unroll
;     for (int e2 = 0; e2 < DK / 64; ++e2) { const int task = tid + 512 * e2, i = task / C::ND8, d8 = task % C::ND8;
;         qraw[e2] = *(const bf16x8*)(u + (tok0 + i) * DINP + (TYPE ? C_HQ + h * 128 : C_GQ + h * 64) + d8 * 8); }
;     const LgRaw raw0 = lg_issue<TYPE>(u, h, 0, tok0, tid), raw1 = lg_issue<TYPE>(u, h, 1, tok0, tid);
;     __syncthreads();
;     vT_write(vr, lds, tid);
;     float qf[DK / 64][8];
; #pragma unroll
;     for (int e2 = 0; e2 < DK / 64; ++e2) { unpack8(qraw[e2], qf[e2]);
; #pragma unroll
;         for (int e = 0; e < 8; ++e) qf[e2][e] = TYPE ? silu_(qf[e2][e]) : qf[e2][e] * 0.125f; }
.LBB0_493:
	s_ashr_i32 s6, s4, 10
	s_and_b32 s57, s4, 0xff
	s_ashr_i32 s7, s6, 31
	s_lshl_b64 s[60:61], s[6:7], 14
	s_lshl_b32 s5, s57, 6
	s_mov_b64 s[58:59], s[68:69]
	s_bfe_u32 s8, s4, 0x20008
	s_or_b32 s60, s60, s5
	s_add_u32 s62, s58, 0xe300000
	s_mul_i32 s5, s61, 0x2a00
	s_mul_hi_u32 s7, s60, 0x2a00
	s_addc_u32 s63, s59, 0
	s_add_i32 s7, s7, s5
	s_mul_i32 s5, s60, 0x2a00
	s_add_u32 s9, s62, s5
	s_addc_u32 s7, s63, s7
	s_lshl_b32 s5, s8, 7
	s_lshl_b32 s12, s8, 8
	s_add_u32 s9, s9, s12
	s_addc_u32 s7, s7, 0
	v_mov_b32_e32 v65, v195
	s_add_u32 s10, s9, 0x1840
	s_addc_u32 s11, s7, 0
	v_ashrrev_i32_e32 v0, 4, v65
	v_lshlrev_b32_e32 v40, 3, v65
	v_mov_b64_e32 v[2:3], s[10:11]
	v_and_b32_e32 v42, 0x78, v40
	v_add_u32_e32 v1, 32, v0
	v_ashrrev_i32_e32 v43, 31, v65
	v_mad_i64_i32 v[4:5], s[10:11], v0, s2, v[2:3]
	v_lshlrev_b32_e32 v112, 1, v42
	v_mad_i64_i32 v[2:3], s[10:11], v1, s2, v[2:3]
	v_lshrrev_b32_e32 v1, 28, v43
	v_lshl_add_u64 v[4:5], v[4:5], 0, v[112:113]
	v_add_u32_e32 v1, v65, v1
	global_load_dwordx4 v[6:9], v[4:5], off
	v_lshl_add_u64 v[4:5], v[2:3], 0, v[112:113]
	s_add_u32 s10, s62, s12
	v_ashrrev_i32_e32 v2, 4, v1
	s_addc_u32 s11, s63, 0
	v_and_b32_e32 v1, -16, v1
	v_ashrrev_i32_e32 v3, 31, v2
	v_sub_u32_e32 v44, v65, v1
	v_lshl_add_u64 v[14:15], s[60:61], 0, v[2:3]
	v_mov_b64_e32 v[16:17], s[10:11]
	global_load_dwordx4 v[10:13], v[4:5], off
	v_mad_u64_u32 v[4:5], s[10:11], v14, s2, v[16:17]
	v_lshlrev_b32_e32 v14, 3, v44
	v_mad_i32_i24 v5, v15, s2, v5
	v_ashrrev_i32_e32 v15, 31, v14
	v_lshl_add_u64 v[4:5], v[14:15], 1, v[4:5]
	global_load_dwordx4 v[32:35], v[4:5], off offset:3136
	v_add_u32_e32 v5, 0x200, v65
	v_ashrrev_i32_e32 v4, 31, v5
	v_lshrrev_b32_e32 v4, 28, v4
	v_add_u32_e32 v14, v5, v4
	v_ashrrev_i32_e32 v4, 4, v14
	v_and_b32_e32 v14, -16, v14
	v_sub_u32_e32 v45, v5, v14
	v_ashrrev_i32_e32 v5, 31, v4
	v_lshl_add_u64 v[14:15], s[60:61], 0, v[4:5]
	v_mad_u64_u32 v[16:17], s[10:11], v14, s2, v[16:17]
	v_lshlrev_b32_e32 v14, 3, v45
	v_mad_i32_i24 v17, v15, s2, v17
	v_ashrrev_i32_e32 v15, 31, v14
	v_lshl_add_u64 v[14:15], v[14:15], 1, v[16:17]
	global_load_dwordx4 v[36:39], v[14:15], off offset:3136
	v_ashrrev_i32_e32 v1, 31, v0
	v_lshl_add_u64 v[14:15], s[60:61], 0, v[0:1]
	v_mov_b64_e32 v[16:17], s[62:63]
	v_mad_u64_u32 v[24:25], s[10:11], v14, s2, v[16:17]
	v_or_b32_e32 v1, s5, v42
	v_mad_i32_i24 v25, v15, s2, v25
	v_lshlrev_b32_e32 v1, 1, v1
	s_mov_b64 s[10:11], 0x54000
	v_add_u32_e32 v14, 0x1040, v1
	v_mov_b32_e32 v15, v113
	v_lshl_add_u64 v[26:27], v[24:25], 0, s[10:11]
	v_lshl_add_u64 v[16:17], v[24:25], 0, v[14:15]
	v_lshl_add_u64 v[14:15], v[26:27], 0, v[14:15]
	global_load_dwordx4 v[16:19], v[16:17], off
	s_nop 0
	global_load_dwordx4 v[20:23], v[14:15], off
	v_add_u32_e32 v14, 0x1440, v1
	v_mov_b32_e32 v15, v113
	v_and_b32_e32 v1, 56, v40
	v_lshlrev_b32_e32 v5, 1, v0
	v_lshl_add_u64 v[24:25], v[24:25], 0, v[14:15]
	v_lshl_add_u64 v[14:15], v[26:27], 0, v[14:15]
	v_and_b32_e32 v5, 14, v5
	v_bitop3_b32 v1, v0, v1, -8 bitop3:0x6c
	global_load_dwordx4 v[24:27], v[24:25], off
	s_nop 0
	global_load_dwordx4 v[28:31], v[14:15], off
	v_add_u32_e32 v5, s95, v5
	v_lshlrev_b32_e32 v1, 1, v1
	v_mul_u32_u24_e32 v15, 0x90, v42
	v_and_b32_e32 v14, -8, v0
	v_add3_u32 v1, v5, v1, v15
	s_waitcnt lgkmcnt(0)
	s_barrier
	s_waitcnt vmcnt(0)
	ds_write_b16 v1, v6
	ds_write_b16_d16_hi v1, v6 offset:144
	ds_write_b16 v1, v7 offset:288
	ds_write_b16_d16_hi v1, v7 offset:432
	ds_write_b16 v1, v8 offset:576
	ds_write_b16_d16_hi v1, v8 offset:720
	ds_write_b16 v1, v9 offset:864
	ds_write_b16_d16_hi v1, v9 offset:1008
	v_add_u32_e32 v1, 32, v14
	v_bitop3_b32 v1, v1, v40, 56 bitop3:0x78
	v_lshlrev_b32_e32 v1, 1, v1
	v_add3_u32 v1, v5, v1, v15
	ds_write_b16 v1, v10
	ds_write_b16_d16_hi v1, v10 offset:144
	ds_write_b16 v1, v11 offset:288
	ds_write_b16_d16_hi v1, v11 offset:432
	ds_write_b16 v1, v12 offset:576
	ds_write_b16_d16_hi v1, v12 offset:720
	ds_write_b16 v1, v13 offset:864
	ds_write_b16_d16_hi v1, v13 offset:1008
	v_ashrrev_i32_e32 v3, 6, v65
	v_and_b32_e32 v89, 15, v65
	v_lshlrev_b32_e32 v64, 4, v3
	s_lshl_b32 s6, s6, 3
	s_lshl_b32 s7, s8, 1
	v_mov_b32_e32 v83, v113
	v_lshlrev_b32_e32 v6, 16, v32
	v_and_b32_e32 v7, 0xffff0000, v32
	v_mul_f32_e32 v1, 0xbfb8aa3b, v6
	v_exp_f32_e32 v1, v1
	v_mul_f32_e32 v5, 0xbfb8aa3b, v7
	v_exp_f32_e32 v5, v5
	v_lshlrev_b32_e32 v8, 16, v33
	v_add_f32_e32 v1, 1.0, v1
	v_and_b32_e32 v9, 0xffff0000, v33
	v_rcp_f32_e32 v14, v1
	v_add_f32_e32 v1, 1.0, v5
	v_mul_f32_e32 v5, 0xbfb8aa3b, v8
	v_exp_f32_e32 v5, v5
	v_mul_f32_e32 v15, 0xbfb8aa3b, v9
	v_exp_f32_e32 v33, v15
	v_lshlrev_b32_e32 v10, 16, v34
	v_and_b32_e32 v11, 0xffff0000, v34
	v_rcp_f32_e32 v15, v1
	v_add_f32_e32 v1, 1.0, v5
	v_mul_f32_e32 v5, 0xbfb8aa3b, v10
	v_rcp_f32_e32 v32, v1
	v_add_f32_e32 v1, 1.0, v33
	v_exp_f32_e32 v5, v5
	v_mul_f32_e32 v33, 0xbfb8aa3b, v11
	v_and_b32_e32 v13, 0xffff0000, v35
	v_lshlrev_b32_e32 v12, 16, v35
	v_exp_f32_e32 v35, v33
	v_rcp_f32_e32 v33, v1
	v_add_f32_e32 v1, 1.0, v5
	v_mul_f32_e32 v5, 0xbfb8aa3b, v12
	v_rcp_f32_e32 v34, v1
	v_add_f32_e32 v1, 1.0, v35
	v_exp_f32_e32 v5, v5
	v_mul_f32_e32 v35, 0xbfb8aa3b, v13
	v_exp_f32_e32 v41, v35
	v_rcp_f32_e32 v35, v1
	v_add_f32_e32 v1, 1.0, v5
	v_rcp_f32_e32 v40, v1
	v_add_f32_e32 v1, 1.0, v41
	v_pk_mul_f32 v[66:67], v[14:15], v[6:7]
	v_lshlrev_b32_e32 v6, 16, v36
	v_rcp_f32_e32 v41, v1
	v_and_b32_e32 v7, 0xffff0000, v36
	v_mul_f32_e32 v1, 0xbfb8aa3b, v6
	v_exp_f32_e32 v1, v1
	v_mul_f32_e32 v5, 0xbfb8aa3b, v7
	v_exp_f32_e32 v5, v5
	v_pk_mul_f32 v[68:69], v[32:33], v[8:9]
	v_lshlrev_b32_e32 v8, 16, v37
	v_add_f32_e32 v1, 1.0, v1
; template <int TYPE>
; __device__ __forceinline__ void pass3_item(const KArgs& a, int l, int item, LAS unsigned char* lds) {
;     ...
;     float qf[DK / 64][8];
; #pragma unroll
;     for (int e2 = 0; e2 < DK / 64; ++e2) { unpack8(qraw[e2], qf[e2]);
; #pragma unroll
;         for (int e = 0; e < 8; ++e) qf[e2][e] = TYPE ? silu_(qf[e2][e]) : qf[e2][e] * 0.125f; }
;     f32x4 o[4];
; #pragma unroll
;     for (int it = 0; it < 4; ++it) o[it] = (f32x4){0.f, 0.f, 0.f, 0.f};
; #pragma unroll 1
;     for (int dir = 0; dir < 2; ++dir) {
;         const int sitem = ((b * 4 + h) * 2 + dir) * NCH + c;
;         const bf16_t* ST = (const bf16_t*)(wsb + (TYPE ? WS_SH : WS_SG)) + (size_t)sitem * 128 * DK + (size_t)(wid * 16 + fr) * DK + fq * 8;
;         bf16x8 sf[DK / 32];
; #pragma unroll
;         for (int ks = 0; ks < DK / 32; ++ks) sf[ks] = *(const bf16x8*)(ST + ks * 32);
;         if (dir) __syncthreads();
;         { LgRaw rw; rw.a0 = dir ? raw1.a0 : raw0.a0; rw.a1 = dir ? raw1.a1 : raw0.a1; rw.k = dir ? raw1.k : raw0.k; lg_compute<TYPE>(a, wsb, l, h, dir, rw, lds, tid); }
;         cumsum_g<TYPE>(dir, lds, tid);
; #pragma unroll
;         for (int e2 = 0; e2 < DK / 64; ++e2) { const int task = tid + 512 * e2, i = task / C::ND8, d8 = task % C::ND8;
;             const f32x4 g0 = *(LAS f32x4*)(G + i * C::LDG + d8 * 8), g1 = *(LAS f32x4*)(G + i * C::LDG + d8 * 8 + 4);
;             const f32x4 m0 = *(LAS f32x4*)(G + 32 * C::LDG + d8 * 8), m1 = *(LAS f32x4*)(G + 32 * C::LDG + d8 * 8 + 4);
;             float kk[8], qq[8], qt[8], qg[8]; unpack8(*(LAS bf16x8*)(Kb + i * C::LDK_ + d8 * 8), kk);
; #pragma unroll
;             for (int e = 0; e < 8; ++e) qq[e] = qf[e2][e];
; #pragma unroll
;             for (int e = 0; e < 8; ++e) { const float gg = e < 4 ? g0[e] : g1[e - 4], gm = e < 4 ? m0[e] : m1[e - 4];
;                 const float q = qq[e];
;                 qt[e] = q * __expf(gg - gm); qg[e] = q * __expf(gg); kk[e] = kk[e] * __expf(gm - gg); }
;             *(LAS bf16x8*)(QT + i * C::LDK_ + d8 * 8) = pack8(qt); *(LAS bf16x8*)(QG + i * C::LDK_ + d8 * 8) = pack8(qg); *(LAS bf16x8*)(Kb + i * C::LDK_ + d8 * 8) = pack8(kk); }
;         __syncthreads();
;         { const int it = wid >> 1;
; #pragma unroll
;           for (int jj = 0; jj < 2; ++jj) { const int jt = 2 * (wid & 1) + jj;
;             f32x4 acc = {0.f, 0.f, 0.f, 0.f};
; #pragma unroll
	v_and_b32_e32 v9, 0xffff0000, v37
	v_rcp_f32_e32 v14, v1
	v_add_f32_e32 v1, 1.0, v5
	v_mul_f32_e32 v5, 0xbfb8aa3b, v8
	v_exp_f32_e32 v5, v5
	v_mul_f32_e32 v15, 0xbfb8aa3b, v9
	v_exp_f32_e32 v33, v15
	v_pk_mul_f32 v[70:71], v[34:35], v[10:11]
	v_lshlrev_b32_e32 v10, 16, v38
	v_and_b32_e32 v11, 0xffff0000, v38
	v_rcp_f32_e32 v15, v1
	v_add_f32_e32 v1, 1.0, v5
	v_mul_f32_e32 v5, 0xbfb8aa3b, v10
	v_rcp_f32_e32 v32, v1
	v_add_f32_e32 v1, 1.0, v33
	v_exp_f32_e32 v5, v5
	v_mul_f32_e32 v33, 0xbfb8aa3b, v11
	v_exp_f32_e32 v35, v33
	v_pk_mul_f32 v[72:73], v[40:41], v[12:13]
	v_lshlrev_b32_e32 v12, 16, v39
	v_and_b32_e32 v13, 0xffff0000, v39
	v_rcp_f32_e32 v33, v1
	v_add_f32_e32 v1, 1.0, v5
	v_mul_f32_e32 v5, 0xbfb8aa3b, v12
	v_rcp_f32_e32 v34, v1
	v_add_f32_e32 v1, 1.0, v35
	v_exp_f32_e32 v5, v5
	v_mul_f32_e32 v35, 0xbfb8aa3b, v13
	v_exp_f32_e32 v37, v35
	v_rcp_f32_e32 v35, v1
	v_add_f32_e32 v1, 1.0, v5
	v_pk_mul_f32 v[74:75], v[14:15], v[6:7]
	v_or_b32_e32 v6, v64, v89
	v_rcp_f32_e32 v36, v1
	v_add_f32_e32 v1, 1.0, v37
	v_ashrrev_i32_e32 v7, 31, v6
	v_rcp_f32_e32 v37, v1
	v_pk_mul_f32 v[76:77], v[32:33], v[8:9]
	v_bfe_u32 v1, v65, 4, 2
	v_lshlrev_b64 v[8:9], 8, v[6:7]
	v_lshl_add_u64 v[8:9], s[58:59], 0, v[8:9]
	v_lshlrev_b32_e32 v82, 4, v1
	s_or_b32 s70, s7, s6
	v_lshl_add_u64 v[8:9], v[8:9], 0, v[82:83]
	s_mov_b64 s[6:7], 0x35700000
	v_lshl_add_u64 v[84:85], v[8:9], 0, s[6:7]
	s_lshl_b32 s6, s8, 9
	s_add_u32 s6, s58, s6
	s_addc_u32 s7, s59, 0
	v_lshlrev_b32_e32 v8, 2, v42
	v_mov_b32_e32 v9, v113
	v_pk_mul_f32 v[78:79], v[34:35], v[10:11]
	v_lshl_add_u64 v[10:11], s[6:7], 0, v[8:9]
	s_mov_b64 s[6:7], 0x3e200000
	s_movk_i32 s22, 0x110
	v_lshl_add_u64 v[86:87], v[10:11], 0, s[6:7]
	v_mul_lo_u32 v9, v0, s91
	v_mul_lo_u32 v10, v0, s22
	v_lshrrev_b32_e32 v0, 25, v43
	v_add_u32_e32 v0, v65, v0
	v_ashrrev_i32_e32 v11, 7, v0
	v_and_b32_e32 v0, 0x3fffff80, v0
	v_sub_u32_e32 v0, v65, v0
	v_lshlrev_b32_e32 v0, 2, v0
	v_add_u32_e32 v88, 0, v0
	v_add_u32_e32 v106, s74, v0
	v_ashrrev_i32_e32 v0, 3, v65
	v_pk_mul_f32 v[80:81], v[36:37], v[12:13]
	s_movk_i32 s0, 0xff81
	v_and_b32_e32 v12, -16, v0
	v_bfi_b32 v13, -16, v0, v65
	v_add_u32_e32 v0, 0, v82
	v_lshlrev_b32_e32 v83, 2, v1
	v_lshlrev_b32_e32 v5, 3, v1
	v_cmp_gt_i32_e64 s[6:7], s0, v65
	s_movk_i32 s0, 0x7f
	v_mad_u64_u32 v[90:91], s[20:21], v13, s22, v[0:1]
	v_or_b32_e32 v1, v83, v12
	v_mul_lo_u32 v12, v6, s3
	v_cmp_lt_i32_e64 s[64:65], s0, v65
	s_movk_i32 s0, 0x17f
	v_add_u32_e32 v12, s95, v12
	v_bitop3_b32 v13, v64, 56, v89 bitop3:0xc8
	v_bitop3_b32 v6, v6, v5, 56 bitop3:0x6c
	v_cmp_lt_i32_e64 s[14:15], s0, v65
	s_movk_i32 s0, 0x180
	v_lshl_add_u32 v91, v6, 1, v12
	v_bitop3_b32 v5, v5, v13, 32 bitop3:0x36
	v_mul_lo_u32 v6, v2, s91
	v_cmp_gt_i32_e64 s[16:17], s0, v65
	s_movk_i32 s0, 0x1ff
	v_lshl_add_u32 v107, v5, 1, v12
	v_add_u32_e32 v6, 0, v6
	v_lshlrev_b32_e32 v12, 5, v44
	v_cmp_lt_i32_e64 s[18:19], s0, v65
	s_movk_i32 s0, 0x2100
	v_add_u32_e32 v108, v6, v12
	v_add_u32_e32 v109, 0, v12
	v_lshlrev_b32_e32 v12, 8, v2
	v_lshlrev_b32_e32 v105, 4, v11
	v_mul_lo_u32 v11, v11, s0
	v_readlane_b32 s0, v255, 8
	v_sub_u32_e32 v6, v6, v12
	v_lshlrev_b32_e32 v12, 4, v44
	v_mul_lo_u32 v2, v2, s22
	v_add3_u32 v111, s0, v2, v12
	v_mul_lo_u32 v2, v4, s91
	v_add_u32_e32 v7, 0, v8
	v_add_u32_e32 v110, v6, v12
	v_add_u32_e32 v2, 0, v2
	v_lshlrev_b32_e32 v6, 5, v45
	v_sub_u32_e32 v8, v7, v112
	v_add_u32_e32 v112, v2, v6
	v_add_u32_e32 v114, 0, v6
	v_lshlrev_b32_e32 v6, 8, v4
	v_sub_u32_e32 v2, v2, v6
	v_lshlrev_b32_e32 v6, 4, v45
	v_lshlrev_b32_e32 v3, 5, v3
	v_add_u32_e32 v115, v2, v6
	v_mul_lo_u32 v2, v4, s22
	v_add_u32_e32 v5, s0, v82
	v_add3_u32 v116, s0, v2, v6
	v_and_or_b32 v2, v3, 32, v89
	v_readlane_b32 s0, v255, 9
	v_or_b32_e32 v12, 1, v1
	v_or_b32_e32 v13, 2, v1
	v_or_b32_e32 v14, 3, v1
	v_mul_u32_u24_e32 v3, 0x110, v2
	v_lshl_add_u32 v4, v2, 1, s0
	v_cmp_ge_i32_e64 s[20:21], v2, v1
	v_cmp_le_i32_e64 s[22:23], v2, v1
	v_cmp_gt_i32_e64 s[24:25], v2, v1
	v_cmp_le_i32_e64 s[26:27], v2, v12
	v_cmp_ge_i32_e64 s[28:29], v2, v13
	v_cmp_le_i32_e64 s[30:31], v2, v13
	v_cmp_ge_i32_e64 s[34:35], v2, v14
	v_cmp_le_i32_e64 s[36:37], v2, v14
	v_or_b32_e32 v2, 16, v2
	v_mul_lo_u32 v6, v1, s3
	v_cmp_ge_i32_e64 s[38:39], v2, v1
	v_cmp_le_i32_e64 s[40:41], v2, v1
	v_lshlrev_b32_e32 v15, 1, v2
	v_cmp_gt_i32_e64 s[42:43], v2, v1
	v_mul_u32_u24_e32 v1, 0x90, v89
	s_movk_i32 s10, 0xff
	v_add3_u32 v117, s0, v6, v15
	v_cmp_le_i32_e64 s[44:45], v2, v12
	v_add3_u32 v121, s0, v1, v82
	v_mul_u32_u24_e32 v1, 0x110, v89
	v_mov_b32_e32 v12, 0
	v_lshl_add_u32 v104, v65, 2, s74
	v_cmp_gt_i32_e64 s[8:9], s66, v65
	v_cmp_lt_i32_e64 s[10:11], s10, v65
	v_cmp_gt_i32_e64 s[12:13], s67, v65
	v_add_u32_e32 v118, 0x90, v117
	v_cmp_ge_i32_e64 s[46:47], v2, v13
	v_cmp_le_i32_e64 s[48:49], v2, v13
	v_add_u32_e32 v119, 0x120, v117
	v_cmp_ge_i32_e64 s[50:51], v2, v14
	v_cmp_le_i32_e64 s[52:53], v2, v14
	v_add_u32_e32 v120, 0x1b0, v117
	v_add_u32_e32 v122, 0x900, v121
	v_add_u32_e32 v123, 0x1200, v121
	v_add_u32_e32 v124, 0x1b00, v121
	s_mov_b32 s54, 0
	s_mov_b64 s[66:67], -1
	v_add_u32_e32 v125, v7, v9
	v_add_u32_e32 v126, v8, v10
	v_add_u32_e32 v127, v88, v11
	v_add_u32_e32 v128, v0, v3
	v_add_u32_e32 v129, v4, v6
	v_add_u32_e32 v130, v5, v1
	v_mov_b32_e32 v13, v12
	v_mov_b32_e32 v14, v12
	v_mov_b32_e32 v15, v12
	v_mov_b32_e32 v8, v12
	v_mov_b32_e32 v9, v12
	v_mov_b32_e32 v10, v12
	v_mov_b32_e32 v11, v12
	v_mov_b32_e32 v4, v12
	v_mov_b32_e32 v5, v12
	v_mov_b32_e32 v6, v12
	v_mov_b32_e32 v7, v12
	v_mov_b32_e32 v0, v12
	v_mov_b32_e32 v1, v12
	v_mov_b32_e32 v2, v12
	v_mov_b32_e32 v3, v12
	s_branch .LBB0_495

; template <int TYPE>
; __device__ __forceinline__ void pass3_item(const KArgs& a, int l, int item, LAS unsigned char* lds) {
;     ...
; #pragma unroll 1
;     for (int dir = 0; dir < 2; ++dir) {
;         const int sitem = ((b * 4 + h) * 2 + dir) * NCH + c;
;         const bf16_t* ST = (const bf16_t*)(wsb + (TYPE ? WS_SH : WS_SG)) + (size_t)sitem * 128 * DK + (size_t)(wid * 16 + fr) * DK + fq * 8;
;         bf16x8 sf[DK / 32];
; #pragma unroll
;         for (int ks = 0; ks < DK / 32; ++ks) sf[ks] = *(const bf16x8*)(ST + ks * 32);
;         if (dir) __syncthreads();
;         { LgRaw rw; rw.a0 = dir ? raw1.a0 : raw0.a0; rw.a1 = dir ? raw1.a1 : raw0.a1; rw.k = dir ? raw1.k : raw0.k; lg_compute<TYPE>(a, wsb, l, h, dir, rw, lds, tid); }
;         cumsum_g<TYPE>(dir, lds, tid);
.LBB0_495:
	s_or_b32 s55, s54, s70
	s_lshl_b32 s55, s55, 8
	s_or_b32 s68, s55, s57
	s_ashr_i32 s69, s68, 31
	s_lshl_b64 s[68:69], s[68:69], 15
	v_lshl_add_u64 v[32:33], v[84:85], 0, s[68:69]
	global_load_dwordx4 v[44:47], v[32:33], off
	global_load_dwordx4 v[40:43], v[32:33], off offset:64
	global_load_dwordx4 v[36:39], v[32:33], off offset:128
	s_nop 0
	global_load_dwordx4 v[32:35], v[32:33], off offset:192
	s_mov_b32 s0, s95
	s_mov_b32 s77, 8
	s_mov_b32 s71, 15
	s_and_b64 vcc, exec, s[66:67]
	s_cbranch_vccnz .LBB0_497
	s_andn2_b64 s[68:69], s[64:65], exec
	s_and_b64 vcc, s[6:7], exec
	v_mov_b64_e32 v[58:59], v[30:31]
	v_mov_b64_e32 v[62:63], v[26:27]
	s_mov_b32 s95, 15
	s_mov_b32 s87, 14
	s_mov_b32 s86, 13
	s_mov_b32 s85, 12
	s_mov_b32 s84, 11
	s_mov_b32 s83, 10
	s_mov_b32 s82, 9
	s_mov_b32 s81, 8
	s_mov_b32 s77, 7
	s_mov_b32 s80, 6
	s_mov_b32 s79, 5
	s_mov_b32 s78, 4
	s_mov_b32 s76, 3
	s_mov_b32 s75, 2
	s_mov_b32 s74, 1
	s_mov_b32 s71, 0
	s_or_b64 s[68:69], s[68:69], vcc
	v_mov_b64_e32 v[56:57], v[28:29]
	v_mov_b64_e32 v[60:61], v[24:25]
	s_waitcnt lgkmcnt(0)
	s_barrier
	s_branch .LBB0_498

; #define LAS __attribute__((address_space(3)))
; __device__ __forceinline__ float sigmoid_(float z) { return __builtin_amdgcn_rcpf(1.f + __expf(-z)); }
; template <int TYPE>
; __device__ __forceinline__ void lg_compute(const KArgs& a, unsigned char* wsb, int l, int h, int dir, const LgRaw& raw, LAS unsigned char* lds, int tid) {
;     using C = Cfg<TYPE>;
;     LAS float* G = (LAS float*)(lds + SC_G); LAS bf16_t* Kb = (LAS bf16_t*)(lds + SC_K);
;     if constexpr (TYPE == 1) {
;         const float* lbp = (const float*)(wsb + WS_LB) + (dir * DEPTH + l) * 512 + h * 128;
;         const int d8 = tid & 15;
;         const f32x4 lb0 = *(const f32x4*)(lbp + d8 * 8), lb1 = *(const f32x4*)(lbp + d8 * 8 + 4);
;         const float lb[8] = {lb0[0], lb0[1], lb0[2], lb0[3], lb1[0], lb1[1], lb1[2], lb1[3]};
; #pragma unroll
;         for (int e2 = 0; e2 < 2; ++e2) { const int i = (tid >> 4) + 32 * e2;
;             float z[8], lg[8], kk[8]; unpack8(e2 ? raw.a1 : raw.a0, z);
; #pragma unroll
;             for (int e = 0; e < 8; ++e) { const float sg = sigmoid_(fmaxf(z[e], -80.f)); lg[e] = __logf(lb[e] + (1.f - lb[e]) * sg); kk[e] = (1.f - lb[e]) * (1.f - sg); }
;             *(LAS f32x4*)(G + i * C::LDG + d8 * 8) = (f32x4){lg[0], lg[1], lg[2], lg[3]}; *(LAS f32x4*)(G + i * C::LDG + d8 * 8 + 4) = (f32x4){lg[4], lg[5], lg[6], lg[7]};
;             *(LAS bf16x8*)(Kb + i * C::LDK_ + d8 * 8) = pack8(kk); }
.LBB0_498:
	s_lshl_b32 s54, s54, 10
	s_or_b32 s72, s54, s56
	v_lshl_add_u64 v[48:49], s[72:73], 2, v[86:87]
	global_load_dwordx4 v[52:55], v[48:49], off
	s_nop 0
	global_load_dwordx4 v[48:51], v[48:49], off offset:16
	v_lshlrev_b32_e32 v92, 16, v60
	v_lshlrev_b32_e32 v101, 16, v61
	v_and_b32_e32 v102, 0xffff0000, v61
	v_max_f32_e32 v61, v92, v92
	v_max_f32_e32 v61, 0xc2a00000, v61
	v_mul_f32_e32 v61, 0xbfb8aa3b, v61
	v_and_b32_e32 v60, 0xffff0000, v60
	v_exp_f32_e32 v61, v61
	v_max_f32_e32 v60, v60, v60
	v_max_f32_e32 v60, 0xc2a00000, v60
	v_mul_f32_e32 v60, 0xbfb8aa3b, v60
	v_add_f32_e32 v61, 1.0, v61
	v_exp_f32_e32 v60, v60
	v_lshlrev_b32_e32 v131, 16, v62
	v_and_b32_e32 v100, 0xffff0000, v62
	v_rcp_f32_e32 v62, v61
	v_add_f32_e32 v60, 1.0, v60
	v_lshlrev_b32_e32 v99, 16, v63
	v_and_b32_e32 v98, 0xffff0000, v63
	v_rcp_f32_e32 v63, v60
	v_max_f32_e32 v100, v100, v100
	v_max_f32_e32 v100, 0xc2a00000, v100
	v_mul_f32_e32 v100, 0xbfb8aa3b, v100
	v_pk_add_f32 v[94:95], v[62:63], 1.0 op_sel_hi:[1,0] neg_lo:[1,0] neg_hi:[1,0]
	v_exp_f32_e32 v100, v100
	v_max_f32_e32 v99, v99, v99
	v_max_f32_e32 v99, 0xc2a00000, v99
	v_mul_f32_e32 v99, 0xbfb8aa3b, v99
	v_add_f32_e32 v100, 1.0, v100
	v_rcp_f32_e32 v135, v100
	v_exp_f32_e32 v99, v99
	v_max_f32_e32 v98, v98, v98
	v_max_f32_e32 v98, 0xc2a00000, v98
	v_mul_f32_e32 v98, 0xbfb8aa3b, v98
	v_exp_f32_e32 v98, v98
	v_add_f32_e32 v99, 1.0, v99
	v_rcp_f32_e32 v138, v99
	v_add_f32_e32 v98, 1.0, v98
	v_rcp_f32_e32 v139, v98
	s_waitcnt vmcnt(0) lgkmcnt(0)
	v_pk_add_f32 v[92:93], v[52:53], 1.0 op_sel_hi:[1,0] neg_lo:[1,0] neg_hi:[1,0]
	s_nop 0
	v_fma_f32 v60, v92, v62, v52
	v_cmp_gt_f32_e32 vcc, s33, v60
	v_pk_mul_f32 v[96:97], v[92:93], v[94:95]
	v_pk_add_f32 v[94:95], v[54:55], 1.0 op_sel_hi:[1,0] neg_lo:[1,0] neg_hi:[1,0]
	v_cndmask_b32_e64 v61, 0, 32, vcc
	v_ldexp_f32 v60, v60, v61
	v_log_f32_e32 v60, v60
	v_pk_add_f32 v[98:99], v[50:51], 1.0 op_sel_hi:[1,0] neg_lo:[1,0] neg_hi:[1,0]
	v_pk_add_f32 v[140:141], v[138:139], 1.0 op_sel_hi:[1,0] neg_lo:[1,0] neg_hi:[1,0]
	v_mul_f32_e32 v61, 0x3f317217, v60
	v_fma_f32 v61, v60, s92, -v61
	v_fmac_f32_e32 v61, 0x3377d1cf, v60
	v_fmac_f32_e32 v61, 0x3f317217, v60
	v_cmp_lt_f32_e64 s[54:55], |v60|, s90
	v_pk_mul_f32 v[140:141], v[98:99], v[140:141]
	s_nop 0
	v_cndmask_b32_e64 v60, v60, v61, s[54:55]
	v_cndmask_b32_e32 v61, 0, v238, vcc
	v_sub_f32_e32 v60, v60, v61
	v_fma_f32 v61, v93, v63, v53
	v_cmp_gt_f32_e32 vcc, s33, v61
	s_nop 1
	v_cndmask_b32_e64 v62, 0, 32, vcc
	v_ldexp_f32 v61, v61, v62
	v_log_f32_e32 v61, v61
	s_nop 0
	v_mul_f32_e32 v62, 0x3f317217, v61
	v_fma_f32 v62, v61, s92, -v62
	v_fmac_f32_e32 v62, 0x3377d1cf, v61
	v_fmac_f32_e32 v62, 0x3f317217, v61
	v_cmp_lt_f32_e64 s[54:55], |v61|, s90
	s_nop 1
	v_cndmask_b32_e64 v61, v61, v62, s[54:55]
	v_cndmask_b32_e32 v62, 0, v238, vcc
	v_sub_f32_e32 v61, v61, v62
	v_max_f32_e32 v62, v101, v101
	v_max_f32_e32 v62, 0xc2a00000, v62
	v_mul_f32_e32 v62, 0xbfb8aa3b, v62
	v_exp_f32_e32 v62, v62
	s_nop 0
	v_add_f32_e32 v62, 1.0, v62
	v_rcp_f32_e32 v132, v62
	v_max_f32_e32 v62, v102, v102
	v_max_f32_e32 v62, 0xc2a00000, v62
	v_mul_f32_e32 v62, 0xbfb8aa3b, v62
	v_exp_f32_e32 v62, v62
	s_nop 0
	v_add_f32_e32 v62, 1.0, v62
	v_rcp_f32_e32 v133, v62
	v_fma_f32 v62, v94, v132, v54
	v_cmp_gt_f32_e32 vcc, s33, v62
	v_pk_add_f32 v[102:103], v[132:133], 1.0 op_sel_hi:[1,0] neg_lo:[1,0] neg_hi:[1,0]
	s_nop 0
	v_cndmask_b32_e64 v63, 0, 32, vcc
	v_ldexp_f32 v62, v62, v63
	v_log_f32_e32 v62, v62
	v_pk_mul_f32 v[102:103], v[94:95], v[102:103]
	v_mul_f32_e32 v63, 0x3f317217, v62
	v_fma_f32 v63, v62, s92, -v63
	v_fmac_f32_e32 v63, 0x3377d1cf, v62
	v_fmac_f32_e32 v63, 0x3f317217, v62
	v_cmp_lt_f32_e64 s[54:55], |v62|, s90
	s_nop 1
	v_cndmask_b32_e64 v62, v62, v63, s[54:55]
	v_cndmask_b32_e32 v63, 0, v238, vcc
	v_sub_f32_e32 v62, v62, v63
	v_fma_f32 v63, v95, v133, v55
	v_cmp_gt_f32_e32 vcc, s33, v63
	s_nop 1
	v_cndmask_b32_e64 v101, 0, 32, vcc
	v_ldexp_f32 v63, v63, v101
	v_log_f32_e32 v63, v63
	s_nop 0
	v_mul_f32_e32 v101, 0x3f317217, v63
	v_fma_f32 v101, v63, s92, -v101
	v_fmac_f32_e32 v101, 0x3377d1cf, v63
	v_fmac_f32_e32 v101, 0x3f317217, v63
	v_cmp_lt_f32_e64 s[54:55], |v63|, s90
	s_nop 1
	v_cndmask_b32_e64 v63, v63, v101, s[54:55]
	v_cndmask_b32_e32 v101, 0, v238, vcc
	v_sub_f32_e32 v63, v63, v101
	v_max_f32_e32 v101, v131, v131
	v_max_f32_e32 v101, 0xc2a00000, v101
	v_mul_f32_e32 v101, 0xbfb8aa3b, v101
	v_exp_f32_e32 v101, v101
	s_nop 0
	v_add_f32_e32 v101, 1.0, v101
	v_rcp_f32_e32 v134, v101
	v_pk_add_f32 v[100:101], v[48:49], 1.0 op_sel_hi:[1,0] neg_lo:[1,0] neg_hi:[1,0]
	v_pk_add_f32 v[136:137], v[134:135], 1.0 op_sel_hi:[1,0] neg_lo:[1,0] neg_hi:[1,0]
	v_fma_f32 v131, v100, v134, v48
	v_cmp_gt_f32_e32 vcc, s33, v131
	v_pk_mul_f32 v[136:137], v[100:101], v[136:137]
	s_nop 0
	v_cndmask_b32_e64 v132, 0, 32, vcc
	v_ldexp_f32 v131, v131, v132
	v_log_f32_e32 v131, v131
	s_nop 0
	v_mul_f32_e32 v132, 0x3f317217, v131
	v_fma_f32 v132, v131, s92, -v132
	v_fmac_f32_e32 v132, 0x3377d1cf, v131
	v_fmac_f32_e32 v132, 0x3f317217, v131
	v_cmp_lt_f32_e64 s[54:55], |v131|, s90
	s_nop 1
	v_cndmask_b32_e64 v131, v131, v132, s[54:55]
	v_cndmask_b32_e32 v132, 0, v238, vcc
	v_sub_f32_e32 v132, v131, v132
	v_fma_f32 v131, v101, v135, v49
	v_cmp_gt_f32_e32 vcc, s33, v131
	s_nop 1
	v_cndmask_b32_e64 v133, 0, 32, vcc
	v_ldexp_f32 v131, v131, v133
	v_log_f32_e32 v131, v131
	s_nop 0
	v_mul_f32_e32 v133, 0x3f317217, v131
	v_fma_f32 v133, v131, s92, -v133
	v_fmac_f32_e32 v133, 0x3377d1cf, v131
	v_fmac_f32_e32 v133, 0x3f317217, v131
	v_cmp_lt_f32_e64 s[54:55], |v131|, s90
	s_nop 1
	v_cndmask_b32_e64 v131, v131, v133, s[54:55]
	v_cndmask_b32_e32 v133, 0, v238, vcc
; #define LAS __attribute__((address_space(3)))
; __device__ __forceinline__ float sigmoid_(float z) { return __builtin_amdgcn_rcpf(1.f + __expf(-z)); }
; template <int TYPE>
; __device__ __forceinline__ void lg_compute(const KArgs& a, unsigned char* wsb, int l, int h, int dir, const LgRaw& raw, LAS unsigned char* lds, int tid) {
;     ...
;         for (int e2 = 0; e2 < 2; ++e2) { const int i = (tid >> 4) + 32 * e2;
;             float z[8], lg[8], kk[8]; unpack8(e2 ? raw.a1 : raw.a0, z);
; #pragma unroll
;             for (int e = 0; e < 8; ++e) { const float sg = sigmoid_(fmaxf(z[e], -80.f)); lg[e] = __logf(lb[e] + (1.f - lb[e]) * sg); kk[e] = (1.f - lb[e]) * (1.f - sg); }
;             *(LAS f32x4*)(G + i * C::LDG + d8 * 8) = (f32x4){lg[0], lg[1], lg[2], lg[3]}; *(LAS f32x4*)(G + i * C::LDG + d8 * 8 + 4) = (f32x4){lg[4], lg[5], lg[6], lg[7]};
;             *(LAS bf16x8*)(Kb + i * C::LDK_ + d8 * 8) = pack8(kk); }
	v_sub_f32_e32 v133, v131, v133
	v_fma_f32 v131, v98, v138, v50
	v_cmp_gt_f32_e32 vcc, s33, v131
	s_nop 1
	v_cndmask_b32_e64 v134, 0, 32, vcc
	v_ldexp_f32 v131, v131, v134
	v_log_f32_e32 v131, v131
	s_nop 0
	v_mul_f32_e32 v134, 0x3f317217, v131
	v_fma_f32 v134, v131, s92, -v134
	v_fmac_f32_e32 v134, 0x3377d1cf, v131
	v_fmac_f32_e32 v134, 0x3f317217, v131
	v_cmp_lt_f32_e64 s[54:55], |v131|, s90
	s_nop 1
	v_cndmask_b32_e64 v131, v131, v134, s[54:55]
	v_cndmask_b32_e32 v134, 0, v238, vcc
	v_sub_f32_e32 v134, v131, v134
	v_fma_f32 v131, v99, v139, v51
	v_cmp_gt_f32_e32 vcc, s33, v131
	s_nop 1
	v_cndmask_b32_e64 v135, 0, 32, vcc
	v_ldexp_f32 v131, v131, v135
	v_log_f32_e32 v131, v131
	s_nop 0
	v_mul_f32_e32 v135, 0x3f317217, v131
	v_fma_f32 v135, v131, s92, -v135
	v_fmac_f32_e32 v135, 0x3377d1cf, v131
	v_fmac_f32_e32 v135, 0x3f317217, v131
	v_cmp_lt_f32_e64 s[54:55], |v131|, s90
	s_nop 1
	v_cndmask_b32_e64 v131, v131, v135, s[54:55]
	v_cndmask_b32_e32 v135, 0, v238, vcc
	v_sub_f32_e32 v135, v131, v135
	ds_write_b128 v125, v[60:63]
	ds_write_b128 v125, v[132:135] offset:16
	v_cvt_pk_bf16_f32 v60, v96, v97
	v_cvt_pk_bf16_f32 v61, v102, v103
	v_cvt_pk_bf16_f32 v62, v136, v137
	v_cvt_pk_bf16_f32 v63, v140, v141
	ds_write_b128 v126, v[60:63] offset:33792
	v_lshlrev_b32_e32 v62, 16, v56
	v_and_b32_e32 v63, 0xffff0000, v56
	v_max_f32_e32 v56, v62, v62
	v_max_f32_e32 v56, 0xc2a00000, v56
	v_mul_f32_e32 v56, 0xbfb8aa3b, v56
	v_exp_f32_e32 v56, v56
	v_lshlrev_b32_e32 v96, 16, v57
	v_and_b32_e32 v97, 0xffff0000, v57
	v_lshlrev_b32_e32 v102, 16, v58
	v_add_f32_e32 v56, 1.0, v56
	v_rcp_f32_e32 v56, v56
	v_and_b32_e32 v103, 0xffff0000, v58
	v_lshlrev_b32_e32 v61, 16, v59
	v_and_b32_e32 v60, 0xffff0000, v59
	v_fma_f32 v52, v92, v56, v52
	v_cmp_gt_f32_e32 vcc, s33, v52
	v_max_f32_e32 v61, v61, v61
	v_max_f32_e32 v61, 0xc2a00000, v61
	v_cndmask_b32_e64 v57, 0, 32, vcc
	v_ldexp_f32 v52, v52, v57
	v_log_f32_e32 v52, v52
	v_mul_f32_e32 v61, 0xbfb8aa3b, v61
	v_exp_f32_e32 v61, v61
	v_max_f32_e32 v60, v60, v60
	v_mul_f32_e32 v57, 0x3f317217, v52
	v_fma_f32 v57, v52, s92, -v57
	v_fmac_f32_e32 v57, 0x3377d1cf, v52
	v_fmac_f32_e32 v57, 0x3f317217, v52
	v_cmp_lt_f32_e64 s[54:55], |v52|, s90
	v_add_f32_e32 v61, 1.0, v61
	v_max_f32_e32 v60, 0xc2a00000, v60
	v_cndmask_b32_e64 v52, v52, v57, s[54:55]
	v_cndmask_b32_e32 v57, 0, v238, vcc
	v_sub_f32_e32 v52, v52, v57
	v_max_f32_e32 v57, v63, v63
	v_max_f32_e32 v57, 0xc2a00000, v57
	v_mul_f32_e32 v57, 0xbfb8aa3b, v57
	v_exp_f32_e32 v57, v57
	v_mul_f32_e32 v60, 0xbfb8aa3b, v60
	v_exp_f32_e32 v60, v60
	v_add_f32_e32 v57, 1.0, v57
	v_rcp_f32_e32 v57, v57
	v_add_f32_e32 v60, 1.0, v60
	v_fma_f32 v53, v93, v57, v53
	v_cmp_gt_f32_e32 vcc, s33, v53
	v_pk_add_f32 v[56:57], v[56:57], 1.0 op_sel_hi:[1,0] neg_lo:[1,0] neg_hi:[1,0]
	s_nop 0
	v_cndmask_b32_e64 v58, 0, 32, vcc
	v_ldexp_f32 v53, v53, v58
	v_log_f32_e32 v53, v53
	v_pk_mul_f32 v[56:57], v[92:93], v[56:57]
	v_rcp_f32_e32 v93, v60
	v_mul_f32_e32 v58, 0x3f317217, v53
	v_fma_f32 v58, v53, s92, -v58
	v_fmac_f32_e32 v58, 0x3377d1cf, v53
	v_fmac_f32_e32 v58, 0x3f317217, v53
	v_cmp_lt_f32_e64 s[54:55], |v53|, s90
	v_fmac_f32_e32 v51, v99, v93
	s_nop 0
	v_cndmask_b32_e64 v53, v53, v58, s[54:55]
	v_cndmask_b32_e32 v58, 0, v238, vcc
	v_sub_f32_e32 v53, v53, v58
	v_max_f32_e32 v58, v96, v96
	v_max_f32_e32 v58, 0xc2a00000, v58
	v_mul_f32_e32 v58, 0xbfb8aa3b, v58
	v_exp_f32_e32 v58, v58
	s_nop 0
	v_add_f32_e32 v58, 1.0, v58
	v_rcp_f32_e32 v58, v58
	s_nop 0
	v_fma_f32 v54, v94, v58, v54
	v_cmp_gt_f32_e32 vcc, s33, v54
	s_nop 1
	v_cndmask_b32_e64 v59, 0, 32, vcc
	v_ldexp_f32 v54, v54, v59
	v_log_f32_e32 v54, v54
	s_nop 0
	v_mul_f32_e32 v59, 0x3f317217, v54
	v_fma_f32 v59, v54, s92, -v59
	v_fmac_f32_e32 v59, 0x3377d1cf, v54
	v_fmac_f32_e32 v59, 0x3f317217, v54
	v_cmp_lt_f32_e64 s[54:55], |v54|, s90
	s_nop 1
	v_cndmask_b32_e64 v54, v54, v59, s[54:55]
	v_cndmask_b32_e32 v59, 0, v238, vcc
	v_sub_f32_e32 v54, v54, v59
	v_max_f32_e32 v59, v97, v97
	v_max_f32_e32 v59, 0xc2a00000, v59
	v_mul_f32_e32 v59, 0xbfb8aa3b, v59
	v_exp_f32_e32 v59, v59
	s_nop 0
	v_add_f32_e32 v59, 1.0, v59
	v_rcp_f32_e32 v59, v59
	s_nop 0
	v_fmac_f32_e32 v55, v95, v59
	v_cmp_gt_f32_e32 vcc, s33, v55
	v_pk_add_f32 v[58:59], v[58:59], 1.0 op_sel_hi:[1,0] neg_lo:[1,0] neg_hi:[1,0]
	s_nop 0
	v_cndmask_b32_e64 v62, 0, 32, vcc
	v_ldexp_f32 v55, v55, v62
	v_log_f32_e32 v55, v55
	v_pk_mul_f32 v[58:59], v[94:95], v[58:59]
	v_mul_f32_e32 v62, 0x3f317217, v55
	v_fma_f32 v62, v55, s92, -v62
	v_fmac_f32_e32 v62, 0x3377d1cf, v55
	v_fmac_f32_e32 v62, 0x3f317217, v55
	v_cmp_lt_f32_e64 s[54:55], |v55|, s90
	s_nop 1
	v_cndmask_b32_e64 v55, v55, v62, s[54:55]
	v_cndmask_b32_e32 v62, 0, v238, vcc
	v_sub_f32_e32 v55, v55, v62
	v_max_f32_e32 v62, v102, v102
	v_max_f32_e32 v62, 0xc2a00000, v62
	v_mul_f32_e32 v62, 0xbfb8aa3b, v62
	v_exp_f32_e32 v62, v62
	s_nop 0
	v_add_f32_e32 v62, 1.0, v62
	v_rcp_f32_e32 v62, v62
	s_nop 0
	v_fma_f32 v48, v100, v62, v48
	v_cmp_gt_f32_e32 vcc, s33, v48
	s_nop 1
	v_cndmask_b32_e64 v63, 0, 32, vcc
	v_ldexp_f32 v48, v48, v63
	v_log_f32_e32 v48, v48
	s_nop 0
	v_mul_f32_e32 v63, 0x3f317217, v48
	v_fma_f32 v63, v48, s92, -v63
	v_fmac_f32_e32 v63, 0x3377d1cf, v48
	v_fmac_f32_e32 v63, 0x3f317217, v48
	v_cmp_lt_f32_e64 s[54:55], |v48|, s90
	s_nop 1
	v_cndmask_b32_e64 v48, v48, v63, s[54:55]
; #define LAS __attribute__((address_space(3)))
; __device__ __forceinline__ float sigmoid_(float z) { return __builtin_amdgcn_rcpf(1.f + __expf(-z)); }
; template <int TYPE>
; __device__ __forceinline__ void lg_compute(const KArgs& a, unsigned char* wsb, int l, int h, int dir, const LgRaw& raw, LAS unsigned char* lds, int tid) {
;     ...
;         for (int e2 = 0; e2 < 2; ++e2) { const int i = (tid >> 4) + 32 * e2;
;             float z[8], lg[8], kk[8]; unpack8(e2 ? raw.a1 : raw.a0, z);
; #pragma unroll
;             for (int e = 0; e < 8; ++e) { const float sg = sigmoid_(fmaxf(z[e], -80.f)); lg[e] = __logf(lb[e] + (1.f - lb[e]) * sg); kk[e] = (1.f - lb[e]) * (1.f - sg); }
;             *(LAS f32x4*)(G + i * C::LDG + d8 * 8) = (f32x4){lg[0], lg[1], lg[2], lg[3]}; *(LAS f32x4*)(G + i * C::LDG + d8 * 8 + 4) = (f32x4){lg[4], lg[5], lg[6], lg[7]};
;             *(LAS bf16x8*)(Kb + i * C::LDK_ + d8 * 8) = pack8(kk); }
; template <int TYPE>
; __device__ __forceinline__ void cumsum_g(int dir, LAS unsigned char* lds, int tid) {
;     using C = Cfg<TYPE>; constexpr int NSEG = 512 / C::DK, SEGL = 64 / NSEG;
;     LAS float* G = (LAS float*)(lds + SC_G); LAS float* SG = (LAS float*)(lds + SC_SEG);
;     const int d = tid % C::DK, seg = tid / C::DK;
;     __syncthreads();
;     float run = 0.f;
; #pragma unroll
;     for (int ii = 0; ii < SEGL; ++ii) { const int i = seg * SEGL + (dir ? SEGL - 1 - ii : ii); run += G[i * C::LDG + d]; G[i * C::LDG + d] = run; }
;     SG[seg * 128 + d] = run;
;     __syncthreads();
;     float off = 0.f;
; #pragma unroll
;     for (int s = 0; s < NSEG; ++s) { const bool before = dir ? (s > seg) : (s < seg); if (before) off += SG[s * 128 + d]; }
; #pragma unroll
;     for (int ii = 0; ii < SEGL; ++ii) { const int i = seg * SEGL + ii; G[i * C::LDG + d] += off; }
	v_cndmask_b32_e32 v63, 0, v238, vcc
	v_sub_f32_e32 v48, v48, v63
	v_max_f32_e32 v63, v103, v103
	v_max_f32_e32 v63, 0xc2a00000, v63
	v_mul_f32_e32 v63, 0xbfb8aa3b, v63
	v_exp_f32_e32 v63, v63
	s_nop 0
	v_add_f32_e32 v63, 1.0, v63
	v_rcp_f32_e32 v63, v63
	s_nop 0
	v_fma_f32 v49, v101, v63, v49
	v_cmp_gt_f32_e32 vcc, s33, v49
	v_pk_add_f32 v[62:63], v[62:63], 1.0 op_sel_hi:[1,0] neg_lo:[1,0] neg_hi:[1,0]
	s_nop 0
	v_cndmask_b32_e64 v92, 0, 32, vcc
	v_ldexp_f32 v49, v49, v92
	v_log_f32_e32 v49, v49
	v_pk_mul_f32 v[62:63], v[100:101], v[62:63]
	v_mul_f32_e32 v92, 0x3f317217, v49
	v_fma_f32 v92, v49, s92, -v92
	v_fmac_f32_e32 v92, 0x3377d1cf, v49
	v_fmac_f32_e32 v92, 0x3f317217, v49
	v_cmp_lt_f32_e64 s[54:55], |v49|, s90
	s_nop 1
	v_cndmask_b32_e64 v49, v49, v92, s[54:55]
	v_cndmask_b32_e32 v92, 0, v238, vcc
	v_sub_f32_e32 v49, v49, v92
	v_rcp_f32_e32 v92, v61
	s_nop 0
	v_fma_f32 v50, v98, v92, v50
	v_cmp_gt_f32_e32 vcc, s33, v50
	s_nop 1
	v_cndmask_b32_e64 v61, 0, 32, vcc
	v_ldexp_f32 v50, v50, v61
	v_log_f32_e32 v50, v50
	s_nop 0
	v_mul_f32_e32 v61, 0x3f317217, v50
	v_fma_f32 v61, v50, s92, -v61
	v_fmac_f32_e32 v61, 0x3377d1cf, v50
	v_fmac_f32_e32 v61, 0x3f317217, v50
	v_cmp_lt_f32_e64 s[54:55], |v50|, s90
	s_nop 1
	v_cndmask_b32_e64 v50, v50, v61, s[54:55]
	v_cndmask_b32_e32 v61, 0, v238, vcc
	v_cmp_gt_f32_e32 vcc, s33, v51
	v_sub_f32_e32 v50, v50, v61
	s_nop 0
	v_cndmask_b32_e64 v60, 0, 32, vcc
	v_ldexp_f32 v51, v51, v60
	v_log_f32_e32 v51, v51
	s_nop 0
	v_mul_f32_e32 v60, 0x3f317217, v51
	v_fma_f32 v60, v51, s92, -v60
	v_fmac_f32_e32 v60, 0x3377d1cf, v51
	v_fmac_f32_e32 v60, 0x3f317217, v51
	v_cmp_lt_f32_e64 s[54:55], |v51|, s90
	s_nop 1
	v_cndmask_b32_e64 v51, v51, v60, s[54:55]
	v_cndmask_b32_e32 v60, 0, v238, vcc
	v_sub_f32_e32 v51, v51, v60
	v_pk_add_f32 v[60:61], v[92:93], 1.0 op_sel_hi:[1,0] neg_lo:[1,0] neg_hi:[1,0]
	ds_write_b128 v125, v[52:55] offset:16896
	ds_write_b128 v125, v[48:51] offset:16912
	v_pk_mul_f32 v[60:61], v[98:99], v[60:61]
	v_cvt_pk_bf16_f32 v48, v56, v57
	v_cvt_pk_bf16_f32 v49, v58, v59
	v_cvt_pk_bf16_f32 v50, v62, v63
	v_cvt_pk_bf16_f32 v51, v60, v61
	ds_write_b128 v126, v[48:51] offset:42496
	v_or_b32_e32 v48, s95, v105
	v_mad_u64_u32 v[48:49], s[54:55], v48, s91, v[88:89]
	s_waitcnt lgkmcnt(0)
	s_barrier
	ds_read_b32 v49, v48
	s_waitcnt lgkmcnt(0)
	v_add_f32_e32 v50, 0, v49
	ds_write_b32 v48, v50
	v_or_b32_e32 v48, s87, v105
	v_mad_u64_u32 v[48:49], s[54:55], v48, s91, v[88:89]
	ds_read_b32 v49, v48
	s_waitcnt lgkmcnt(0)
	v_add_f32_e32 v50, v50, v49
	ds_write_b32 v48, v50
	v_or_b32_e32 v48, s86, v105
	v_mad_u64_u32 v[48:49], s[54:55], v48, s91, v[88:89]
	ds_read_b32 v49, v48
	s_waitcnt lgkmcnt(0)
	v_add_f32_e32 v50, v50, v49
	ds_write_b32 v48, v50
	v_or_b32_e32 v48, s85, v105
	v_mad_u64_u32 v[48:49], s[54:55], v48, s91, v[88:89]
	ds_read_b32 v49, v48
	s_waitcnt lgkmcnt(0)
	v_add_f32_e32 v50, v50, v49
	ds_write_b32 v48, v50
	v_or_b32_e32 v48, s84, v105
	v_mad_u64_u32 v[48:49], s[54:55], v48, s91, v[88:89]
	ds_read_b32 v49, v48
	s_waitcnt lgkmcnt(0)
	v_add_f32_e32 v50, v50, v49
	ds_write_b32 v48, v50
	v_or_b32_e32 v48, s83, v105
	v_mad_u64_u32 v[48:49], s[54:55], v48, s91, v[88:89]
	ds_read_b32 v49, v48
	s_waitcnt lgkmcnt(0)
	v_add_f32_e32 v50, v50, v49
	ds_write_b32 v48, v50
	v_or_b32_e32 v48, s82, v105
	v_mad_u64_u32 v[48:49], s[54:55], v48, s91, v[88:89]
	ds_read_b32 v49, v48
	s_waitcnt lgkmcnt(0)
	v_add_f32_e32 v50, v50, v49
	ds_write_b32 v48, v50
	v_or_b32_e32 v48, s81, v105
	v_mad_u64_u32 v[48:49], s[54:55], v48, s91, v[88:89]
	ds_read_b32 v49, v48
	s_waitcnt lgkmcnt(0)
	v_add_f32_e32 v50, v50, v49
	ds_write_b32 v48, v50
	v_or_b32_e32 v48, s77, v105
	v_mad_u64_u32 v[48:49], s[54:55], v48, s91, v[88:89]
	ds_read_b32 v49, v48
	s_waitcnt lgkmcnt(0)
	v_add_f32_e32 v50, v50, v49
	ds_write_b32 v48, v50
	v_or_b32_e32 v48, s80, v105
	v_mad_u64_u32 v[48:49], s[54:55], v48, s91, v[88:89]
	ds_read_b32 v49, v48
	s_waitcnt lgkmcnt(0)
	v_add_f32_e32 v50, v50, v49
	ds_write_b32 v48, v50
	v_or_b32_e32 v48, s79, v105
	v_mad_u64_u32 v[48:49], s[54:55], v48, s91, v[88:89]
	ds_read_b32 v49, v48
	s_waitcnt lgkmcnt(0)
	v_add_f32_e32 v50, v50, v49
	ds_write_b32 v48, v50
	v_or_b32_e32 v48, s78, v105
	v_mad_u64_u32 v[48:49], s[54:55], v48, s91, v[88:89]
	ds_read_b32 v49, v48
	s_waitcnt lgkmcnt(0)
	v_add_f32_e32 v50, v50, v49
	ds_write_b32 v48, v50
	v_or_b32_e32 v48, s76, v105
	v_mad_u64_u32 v[48:49], s[54:55], v48, s91, v[88:89]
	ds_read_b32 v49, v48
	s_waitcnt lgkmcnt(0)
	v_add_f32_e32 v50, v50, v49
	ds_write_b32 v48, v50
	v_or_b32_e32 v48, s75, v105
	v_mad_u64_u32 v[48:49], s[54:55], v48, s91, v[88:89]
	ds_read_b32 v49, v48
	s_waitcnt lgkmcnt(0)
	v_add_f32_e32 v50, v50, v49
	ds_write_b32 v48, v50
	v_or_b32_e32 v48, s74, v105
	v_mad_u64_u32 v[48:49], s[54:55], v48, s91, v[88:89]
	ds_read_b32 v49, v48
	s_waitcnt lgkmcnt(0)
	v_add_f32_e32 v50, v50, v49
	ds_write_b32 v48, v50
	v_or_b32_e32 v48, s71, v105
	v_mad_u64_u32 v[48:49], s[54:55], v48, s91, v[88:89]
	ds_read_b32 v49, v48
	s_waitcnt lgkmcnt(0)
	v_add_f32_e32 v49, v50, v49
	ds_write_b32 v48, v49
	ds_write_b32 v104, v49
	v_mov_b32_e32 v48, 0
	s_waitcnt lgkmcnt(0)
	s_barrier
	s_and_saveexec_b64 s[54:55], s[68:69]
	s_cbranch_execz .LBB0_500
	ds_read_b32 v48, v106
	s_waitcnt lgkmcnt(0)
	v_add_f32_e32 v48, 0, v48

; __device__ __forceinline__ float bf2f(unsigned v) { return __uint_as_float(v << 16); }
; template <int TYPE>
; __device__ __forceinline__ void pass3_item(const KArgs& a, int l, int item, LAS unsigned char* lds) {
;     ...
;     const float gain = ((const float*)a.in[TYPE ? 7 : 5])[l * 128 + wid * 16 + fr];
;     bf16_t* mix = (bf16_t*)(wsb + WS_XN);
;     float gtv[4][4];
; #pragma unroll
;     for (int it = 0; it < 4; ++it)
; #pragma unroll
;         for (int r = 0; r < 4; ++r) gtv[it][r] = bf2f(u[(tok0 + it * 16 + fq * 4 + r) * DINP + (TYPE ? C_HG : C_GG) + h * 128 + wid * 16 + fr]);
.LBB0_509:
	s_or_b64 exec, exec, s[8:9]
	v_readlane_b32 s4, v255, 29
	v_readlane_b32 s40, v253, 48
	v_readlane_b32 s50, v253, 58
	v_add_u32_e32 v12, s4, v52
	v_or_b32_e32 v12, v12, v67
	v_ashrrev_i32_e32 v13, 31, v12
	v_readlane_b32 s51, v253, 59
	v_readlane_b32 s6, v255, 31
	v_readlane_b32 s8, v255, 33
	v_lshl_add_u64 v[12:13], v[12:13], 2, s[50:51]
	v_readlane_b32 s7, v255, 32
	s_waitcnt lgkmcnt(0)
	s_barrier
	global_load_dword v54, v[12:13], off
	v_or_b32_e32 v12, s8, v63
	v_mov_b64_e32 v[50:51], s[6:7]
	s_movk_i32 s2, 0x2a00
	v_readlane_b32 s9, v255, 34
	v_mad_u64_u32 v[14:15], s[6:7], v12, s2, v[50:51]
	s_mul_i32 s4, s9, 0x2a00
	v_readlane_b32 s6, v255, 35
	v_ashrrev_i32_e32 v53, 31, v52
	v_add_u32_e32 v15, s4, v15
	s_lshl_b32 s72, s6, 1
	v_lshl_add_u64 v[14:15], v[14:15], 0, s[72:73]
	v_lshlrev_b64 v[24:25], 1, v[52:53]
	v_lshl_add_u64 v[14:15], v[14:15], 0, v[24:25]
	v_lshlrev_b32_e32 v112, 1, v67
	v_lshl_add_u64 v[14:15], v[14:15], 0, v[112:113]
	global_load_ushort v14, v[14:15], off offset:2112
	v_readlane_b32 s7, v255, 36
	v_or_b32_e32 v46, 2, v12
	v_or_b32_e32 v48, 3, v12
	v_or_b32_e32 v67, 16, v63
	v_or_b32_e32 v44, s8, v67
	v_or_b32_e32 v42, 17, v12
	v_or_b32_e32 v40, 18, v12
	v_or_b32_e32 v28, 19, v12
	v_or_b32_e32 v60, 32, v63
	v_or_b32_e32 v26, s8, v60
	v_or_b32_e32 v30, 33, v12
	v_or_b32_e32 v36, 34, v12
	v_or_b32_e32 v38, 35, v12
	v_or_b32_e32 v56, 48, v63
	v_or_b32_e32 v22, s8, v56
	v_or_b32_e32 v20, 49, v12
	v_or_b32_e32 v18, 50, v12
	v_readlane_b32 s74, v255, 20
	v_mov_b32_e32 v13, s9
	v_mov_b32_e32 v15, s9
	v_mov_b32_e32 v47, s9
	v_mov_b32_e32 v49, s9
	v_mov_b32_e32 v45, s9
	v_mov_b32_e32 v43, s9
	v_mov_b32_e32 v41, s9
	v_mov_b32_e32 v29, s9
	v_mov_b32_e32 v27, s9
	v_mov_b32_e32 v31, s9
	v_mov_b32_e32 v37, s9
	v_mov_b32_e32 v39, s9
	v_mov_b32_e32 v23, s9
	v_mov_b32_e32 v21, s9
	v_mov_b32_e32 v19, s9
	v_readlane_b32 s68, v255, 16
	v_readlane_b32 s70, v255, 18
	v_readlane_b32 s41, v253, 49
	v_readlane_b32 s46, v253, 54
	v_readlane_b32 s47, v253, 55
	v_readlane_b32 s48, v253, 56
	v_readlane_b32 s49, v253, 57
	v_readlane_b32 s54, v253, 62
	v_readlane_b32 s55, v253, 63
	v_readlane_b32 s69, v255, 17
	v_readlane_b32 s71, v255, 19
	s_movk_i32 s66, 0x80
	s_movk_i32 s67, 0x100
	s_movk_i32 s3, 0x90
	v_readlane_b32 s42, v253, 50
	v_readlane_b32 s43, v253, 51
	v_readlane_b32 s44, v253, 52
	v_readlane_b32 s45, v253, 53
	v_readlane_b32 s52, v253, 60
	v_readlane_b32 s53, v253, 61
	s_waitcnt vmcnt(0) lgkmcnt(0)
	v_lshlrev_b32_e32 v68, 16, v14
	v_or_b32_e32 v14, 1, v12
	v_mad_u64_u32 v[16:17], s[6:7], v14, s2, v[50:51]
	v_add_u32_e32 v17, s4, v17
	v_lshl_add_u64 v[16:17], v[16:17], 0, s[72:73]
	v_lshl_add_u64 v[16:17], v[16:17], 0, v[24:25]
	v_lshl_add_u64 v[16:17], v[16:17], 0, v[112:113]
	global_load_ushort v16, v[16:17], off offset:2112
	s_waitcnt vmcnt(0) lgkmcnt(0)
	v_lshlrev_b32_e32 v69, 16, v16
	v_mad_u64_u32 v[16:17], s[6:7], v46, s2, v[50:51]
	v_add_u32_e32 v17, s4, v17
	v_lshl_add_u64 v[16:17], v[16:17], 0, s[72:73]
	v_lshl_add_u64 v[16:17], v[16:17], 0, v[24:25]
	v_lshl_add_u64 v[16:17], v[16:17], 0, v[112:113]
	global_load_ushort v16, v[16:17], off offset:2112
	s_waitcnt vmcnt(0) lgkmcnt(0)
	v_lshlrev_b32_e32 v70, 16, v16
	v_mad_u64_u32 v[16:17], s[6:7], v48, s2, v[50:51]
	v_add_u32_e32 v17, s4, v17
	v_lshl_add_u64 v[16:17], v[16:17], 0, s[72:73]
	v_lshl_add_u64 v[16:17], v[16:17], 0, v[24:25]
	v_lshl_add_u64 v[16:17], v[16:17], 0, v[112:113]
	global_load_ushort v16, v[16:17], off offset:2112
	s_waitcnt vmcnt(0) lgkmcnt(0)
	v_lshlrev_b32_e32 v71, 16, v16
	v_mad_u64_u32 v[16:17], s[6:7], v44, s2, v[50:51]
	v_add_u32_e32 v17, s4, v17
	v_lshl_add_u64 v[16:17], v[16:17], 0, s[72:73]
	v_lshl_add_u64 v[16:17], v[16:17], 0, v[24:25]
	v_lshl_add_u64 v[16:17], v[16:17], 0, v[112:113]
	global_load_ushort v16, v[16:17], off offset:2112
	s_waitcnt vmcnt(0) lgkmcnt(0)
	v_lshlrev_b32_e32 v66, 16, v16
	v_mad_u64_u32 v[16:17], s[6:7], v42, s2, v[50:51]
	v_add_u32_e32 v17, s4, v17
	v_lshl_add_u64 v[16:17], v[16:17], 0, s[72:73]
	v_lshl_add_u64 v[16:17], v[16:17], 0, v[24:25]
	v_lshl_add_u64 v[16:17], v[16:17], 0, v[112:113]
	global_load_ushort v16, v[16:17], off offset:2112
	s_waitcnt vmcnt(0) lgkmcnt(0)
	v_lshlrev_b32_e32 v65, 16, v16
	v_mad_u64_u32 v[16:17], s[6:7], v40, s2, v[50:51]
	v_add_u32_e32 v17, s4, v17
	v_lshl_add_u64 v[16:17], v[16:17], 0, s[72:73]
	v_lshl_add_u64 v[16:17], v[16:17], 0, v[24:25]
	v_lshl_add_u64 v[16:17], v[16:17], 0, v[112:113]
	global_load_ushort v16, v[16:17], off offset:2112
	s_waitcnt vmcnt(0) lgkmcnt(0)
	v_lshlrev_b32_e32 v64, 16, v16
	v_mad_u64_u32 v[16:17], s[6:7], v28, s2, v[50:51]
	v_add_u32_e32 v17, s4, v17
	v_lshl_add_u64 v[16:17], v[16:17], 0, s[72:73]
	v_lshl_add_u64 v[16:17], v[16:17], 0, v[24:25]
	v_lshl_add_u64 v[16:17], v[16:17], 0, v[112:113]
	global_load_ushort v16, v[16:17], off offset:2112
	s_waitcnt vmcnt(0) lgkmcnt(0)
	v_lshlrev_b32_e32 v61, 16, v16
	v_mad_u64_u32 v[16:17], s[6:7], v26, s2, v[50:51]
	v_add_u32_e32 v17, s4, v17
	v_lshl_add_u64 v[16:17], v[16:17], 0, s[72:73]
	v_lshl_add_u64 v[16:17], v[16:17], 0, v[24:25]
	v_lshl_add_u64 v[16:17], v[16:17], 0, v[112:113]
	global_load_ushort v16, v[16:17], off offset:2112
	s_waitcnt vmcnt(0) lgkmcnt(0)
	v_lshlrev_b32_e32 v57, 16, v16
	v_mad_u64_u32 v[16:17], s[6:7], v30, s2, v[50:51]
	v_add_u32_e32 v17, s4, v17
	v_lshl_add_u64 v[16:17], v[16:17], 0, s[72:73]
	v_lshl_add_u64 v[16:17], v[16:17], 0, v[24:25]
	v_lshl_add_u64 v[16:17], v[16:17], 0, v[112:113]
	global_load_ushort v16, v[16:17], off offset:2112
	s_waitcnt vmcnt(0) lgkmcnt(0)
; __device__ __forceinline__ float bf2f(unsigned v) { return __uint_as_float(v << 16); }
; __device__ __forceinline__ unsigned f2bf(float f) { unsigned u = __float_as_uint(f); return (u + 0x7fffu + ((u >> 16) & 1u)) >> 16; }
; __device__ __forceinline__ float silu_(float z) { return z * sigmoid_(z); }
; template <int TYPE>
; __device__ __forceinline__ void pass3_item(const KArgs& a, int l, int item, LAS unsigned char* lds) {
;     ...
;     const float gain = ((const float*)a.in[TYPE ? 7 : 5])[l * 128 + wid * 16 + fr];
;     bf16_t* mix = (bf16_t*)(wsb + WS_XN);
;     float gtv[4][4];
; #pragma unroll
;     for (int it = 0; it < 4; ++it)
; #pragma unroll
;         for (int r = 0; r < 4; ++r) gtv[it][r] = bf2f(u[(tok0 + it * 16 + fq * 4 + r) * DINP + (TYPE ? C_HG : C_GG) + h * 128 + wid * 16 + fr]);
; #pragma unroll
;     for (int it = 0; it < 4; ++it)
; #pragma unroll
;         for (int r = 0; r < 4; ++r) { const int i = it * 16 + fq * 4 + r;
;             const float rstd = RSTD[i];
;             const float gt = gtv[it][r];
;             const float yv = o[it][r] * rstd * gain * silu_(gt);
;             mix[(tok0 + i) * DM + (TYPE ? 512 : 0) + h * 128 + wid * 16 + fr] = (bf16_t)f2bf(yv); }
	v_lshlrev_b32_e32 v58, 16, v16
	v_mad_u64_u32 v[16:17], s[6:7], v36, s2, v[50:51]
	v_add_u32_e32 v17, s4, v17
	v_lshl_add_u64 v[16:17], v[16:17], 0, s[72:73]
	v_lshl_add_u64 v[16:17], v[16:17], 0, v[24:25]
	v_lshl_add_u64 v[16:17], v[16:17], 0, v[112:113]
	global_load_ushort v16, v[16:17], off offset:2112
	s_waitcnt vmcnt(0) lgkmcnt(0)
	v_lshlrev_b32_e32 v59, 16, v16
	v_mad_u64_u32 v[16:17], s[6:7], v38, s2, v[50:51]
	v_add_u32_e32 v17, s4, v17
	v_lshl_add_u64 v[16:17], v[16:17], 0, s[72:73]
	v_lshl_add_u64 v[16:17], v[16:17], 0, v[24:25]
	v_lshl_add_u64 v[16:17], v[16:17], 0, v[112:113]
	global_load_ushort v16, v[16:17], off offset:2112
	s_waitcnt vmcnt(0) lgkmcnt(0)
	v_lshlrev_b32_e32 v62, 16, v16
	v_mad_u64_u32 v[16:17], s[6:7], v22, s2, v[50:51]
	v_add_u32_e32 v17, s4, v17
	v_lshl_add_u64 v[16:17], v[16:17], 0, s[72:73]
	v_lshl_add_u64 v[16:17], v[16:17], 0, v[24:25]
	v_lshl_add_u64 v[16:17], v[16:17], 0, v[112:113]
	global_load_ushort v16, v[16:17], off offset:2112
	s_waitcnt vmcnt(0) lgkmcnt(0)
	v_lshlrev_b32_e32 v55, 16, v16
	v_mad_u64_u32 v[16:17], s[6:7], v20, s2, v[50:51]
	v_add_u32_e32 v17, s4, v17
	v_lshl_add_u64 v[16:17], v[16:17], 0, s[72:73]
	v_lshl_add_u64 v[16:17], v[16:17], 0, v[24:25]
	v_lshl_add_u64 v[16:17], v[16:17], 0, v[112:113]
	global_load_ushort v16, v[16:17], off offset:2112
	s_waitcnt vmcnt(0) lgkmcnt(0)
	v_lshlrev_b32_e32 v53, 16, v16
	v_mad_u64_u32 v[16:17], s[6:7], v18, s2, v[50:51]
	v_add_u32_e32 v17, s4, v17
	v_lshl_add_u64 v[16:17], v[16:17], 0, s[72:73]
	v_lshl_add_u64 v[16:17], v[16:17], 0, v[24:25]
	v_lshl_add_u64 v[16:17], v[16:17], 0, v[112:113]
	global_load_ushort v16, v[16:17], off offset:2112
	v_mov_b32_e32 v17, s9
	s_waitcnt vmcnt(0) lgkmcnt(0)
	v_lshlrev_b32_e32 v52, 16, v16
	v_or_b32_e32 v16, 51, v12
	v_mad_u64_u32 v[50:51], s[6:7], v16, s2, v[50:51]
	v_add_u32_e32 v51, s4, v51
	v_lshl_add_u64 v[50:51], v[50:51], 0, s[72:73]
	v_lshl_add_u64 v[50:51], v[50:51], 0, v[24:25]
	v_lshl_add_u64 v[50:51], v[50:51], 0, v[112:113]
	global_load_ushort v50, v[50:51], off offset:2112
	v_lshl_add_u32 v51, v63, 2, s74
	ds_read_b128 v[72:75], v51
	v_mul_f32_e32 v51, 0xbfb8aa3b, v68
	v_exp_f32_e32 v51, v51
	v_readlane_b32 s6, v255, 37
	v_readlane_b32 s7, v255, 38
	s_add_u32 s6, s6, s72
	v_add_f32_e32 v51, 1.0, v51
	v_rcp_f32_e32 v51, v51
	s_addc_u32 s7, s7, 0
	s_waitcnt lgkmcnt(0)
	v_mul_f32_e32 v32, v32, v72
	v_lshl_add_u64 v[24:25], s[6:7], 0, v[24:25]
	v_mul_f32_e32 v32, v54, v32
	v_mul_f32_e32 v51, v51, v68
	v_lshl_add_u64 v[24:25], v[24:25], 0, v[112:113]
	s_mov_b64 s[6:7], 0x6300000
	v_mul_f32_e32 v32, v51, v32
	v_lshl_add_u64 v[24:25], v[24:25], 0, s[6:7]
	v_bfe_u32 v51, v32, 16, 1
	v_lshlrev_b64 v[12:13], 12, v[12:13]
	v_add3_u32 v32, v32, v51, s1
	v_lshl_add_u64 v[12:13], v[24:25], 0, v[12:13]
	global_store_short_d16_hi v[12:13], v32, off
	v_mul_f32_e32 v13, 0xbfb8aa3b, v69
	v_exp_f32_e32 v13, v13
	v_mul_f32_e32 v12, v33, v73
	v_mul_f32_e32 v12, v54, v12
	v_readlane_b32 s4, v255, 30
	v_add_f32_e32 v13, 1.0, v13
	v_rcp_f32_e32 v13, v13
	s_add_i32 s4, s4, s70
	s_cmpk_gt_i32 s4, 0x7ff
	v_mul_f32_e32 v13, v13, v69
	v_mul_f32_e32 v12, v13, v12
	v_bfe_u32 v13, v12, 16, 1
	v_add3_u32 v32, v12, v13, s1
	v_lshlrev_b64 v[12:13], 12, v[14:15]
	v_lshl_add_u64 v[12:13], v[24:25], 0, v[12:13]
	global_store_short_d16_hi v[12:13], v32, off
	v_mul_f32_e32 v13, 0xbfb8aa3b, v70
	v_exp_f32_e32 v13, v13
	v_mul_f32_e32 v12, v34, v74
	v_mul_f32_e32 v12, v54, v12
	v_lshlrev_b64 v[32:33], 12, v[44:45]
	v_add_f32_e32 v13, 1.0, v13
	v_rcp_f32_e32 v13, v13
	v_lshl_add_u64 v[32:33], v[24:25], 0, v[32:33]
	v_mul_f32_e32 v13, v13, v70
	v_mul_f32_e32 v12, v13, v12
	v_bfe_u32 v13, v12, 16, 1
	v_add3_u32 v14, v12, v13, s1
	v_lshlrev_b64 v[12:13], 12, v[46:47]
	v_lshl_add_u64 v[12:13], v[24:25], 0, v[12:13]
	global_store_short_d16_hi v[12:13], v14, off
	v_mul_f32_e32 v13, 0xbfb8aa3b, v71
	v_exp_f32_e32 v13, v13
	v_mul_f32_e32 v12, v35, v75
	v_mul_f32_e32 v12, v54, v12
	v_add_f32_e32 v13, 1.0, v13
	v_rcp_f32_e32 v13, v13
	s_waitcnt vmcnt(0)
	v_lshlrev_b32_e32 v50, 16, v50
	v_mul_f32_e32 v13, v13, v71
	v_mul_f32_e32 v12, v13, v12
	v_bfe_u32 v13, v12, 16, 1
	v_add3_u32 v14, v12, v13, s1
	v_lshlrev_b64 v[12:13], 12, v[48:49]
	v_lshl_add_u64 v[12:13], v[24:25], 0, v[12:13]
	global_store_short_d16_hi v[12:13], v14, off
	v_lshl_add_u32 v12, v67, 2, s74
	ds_read_b128 v[12:15], v12
	s_waitcnt lgkmcnt(0)
	v_mul_f32_e32 v8, v8, v12
	v_mul_f32_e32 v12, 0xbfb8aa3b, v66
	v_exp_f32_e32 v12, v12
	v_mul_f32_e32 v8, v54, v8
	v_add_f32_e32 v12, 1.0, v12
	v_rcp_f32_e32 v12, v12
	s_nop 0
	v_mul_f32_e32 v12, v12, v66
	v_mul_f32_e32 v8, v12, v8
	v_bfe_u32 v12, v8, 16, 1
	v_add3_u32 v8, v8, v12, s1
	global_store_short_d16_hi v[32:33], v8, off
	v_mul_f32_e32 v8, v9, v13
	v_mul_f32_e32 v9, 0xbfb8aa3b, v65
	v_exp_f32_e32 v9, v9
	v_mul_f32_e32 v8, v54, v8
	v_add_f32_e32 v9, 1.0, v9
	v_rcp_f32_e32 v9, v9
	s_nop 0
	v_mul_f32_e32 v9, v9, v65
	v_mul_f32_e32 v8, v9, v8
	v_bfe_u32 v9, v8, 16, 1
	v_add3_u32 v12, v8, v9, s1
	v_lshlrev_b64 v[8:9], 12, v[42:43]
	v_lshl_add_u64 v[8:9], v[24:25], 0, v[8:9]
	global_store_short_d16_hi v[8:9], v12, off
	v_mul_f32_e32 v9, 0xbfb8aa3b, v64
	v_exp_f32_e32 v9, v9
	v_mul_f32_e32 v8, v10, v14
	v_mul_f32_e32 v8, v54, v8
	v_lshlrev_b64 v[12:13], 12, v[26:27]
	v_add_f32_e32 v9, 1.0, v9
	v_rcp_f32_e32 v9, v9
	v_lshl_add_u64 v[12:13], v[24:25], 0, v[12:13]
	v_mul_f32_e32 v9, v9, v64
	v_mul_f32_e32 v8, v9, v8
	v_bfe_u32 v9, v8, 16, 1
	v_add3_u32 v10, v8, v9, s1
	v_lshlrev_b64 v[8:9], 12, v[40:41]
	v_lshl_add_u64 v[8:9], v[24:25], 0, v[8:9]
	global_store_short_d16_hi v[8:9], v10, off
	v_mul_f32_e32 v9, 0xbfb8aa3b, v61
	v_exp_f32_e32 v9, v9
	v_mul_f32_e32 v8, v11, v15
	v_mul_f32_e32 v8, v54, v8
	v_add_f32_e32 v9, 1.0, v9
	v_rcp_f32_e32 v9, v9
	s_nop 0
	v_mul_f32_e32 v9, v9, v61
	v_mul_f32_e32 v8, v9, v8
	v_bfe_u32 v9, v8, 16, 1
	v_add3_u32 v10, v8, v9, s1
	v_lshlrev_b64 v[8:9], 12, v[28:29]
	v_lshl_add_u64 v[8:9], v[24:25], 0, v[8:9]
	global_store_short_d16_hi v[8:9], v10, off
	v_lshl_add_u32 v8, v60, 2, s74
	ds_read_b128 v[8:11], v8
	s_waitcnt lgkmcnt(0)
; #define LAS __attribute__((address_space(3)))
; __device__ __forceinline__ unsigned f2bf(float f) { unsigned u = __float_as_uint(f); return (u + 0x7fffu + ((u >> 16) & 1u)) >> 16; }
; __device__ __forceinline__ unsigned char* opq(unsigned char* q) { asm volatile("" : "+s"(q)); return q; }
; __device__ __forceinline__ int opaque_tid() { int t = threadIdx.x; asm volatile("" : "+v"(t)); return t; }
; __device__ __forceinline__ float silu_(float z) { return z * sigmoid_(z); }
; template <int TYPE>
; __device__ __forceinline__ void pass3_item(const KArgs& a, int l, int item, LAS unsigned char* lds) {
;     unsigned char* const wsb = opq(a.ws);
;     const int tid = opaque_tid();
;     using C = Cfg<TYPE>; constexpr int DK = C::DK;
;     const int c = item & (NCH - 1), h = (item >> 8) & 3, b = item >> 10;
;     const size_t tok0 = (size_t)b * T + (size_t)c * 64;
;     const bf16_t* u = (const bf16_t*)(wsb + WS_U);
;     const int wid = tid >> 6, lane = tid & 63, fr = lane & 15, fq = lane >> 4;
;     LAS float* G = (LAS float*)(lds + SC_G); LAS bf16_t* Kb = (LAS bf16_t*)(lds + SC_K); LAS bf16_t* QT = (LAS bf16_t*)(lds + SC_QT); LAS bf16_t* QG = (LAS bf16_t*)(lds + SC_QG);
;     LAS bf16_t* VT = (LAS bf16_t*)(lds + SC_VT); LAS bf16_t* P = (LAS bf16_t*)(lds + SC_P); LAS float* RSQ = (LAS float*)(lds + SC_RSQ);
;     const VRaw vr = vT_issue(u + tok0 * DINP + (TYPE ? C_HI : C_GV) + h * 128, tid);
;     bf16x8 qraw[DK / 64];
; #pragma unroll
;     for (int e2 = 0; e2 < DK / 64; ++e2) { const int task = tid + 512 * e2, i = task / C::ND8, d8 = task % C::ND8;
;         qraw[e2] = *(const bf16x8*)(u + (tok0 + i) * DINP + (TYPE ? C_HQ + h * 128 : C_GQ + h * 64) + d8 * 8); }
;     const LgRaw raw0 = lg_issue<TYPE>(u, h, 0, tok0, tid), raw1 = lg_issue<TYPE>(u, h, 1, tok0, tid);
;     ...
; #pragma unroll
;     for (int it = 0; it < 4; ++it)
; #pragma unroll
;         for (int r = 0; r < 4; ++r) { const int i = it * 16 + fq * 4 + r;
;             const float rstd = RSTD[i];
;             const float gt = gtv[it][r];
;             const float yv = o[it][r] * rstd * gain * silu_(gt);
;             mix[(tok0 + i) * DM + (TYPE ? 512 : 0) + h * 128 + wid * 16 + fr] = (bf16_t)f2bf(yv); }
	v_mul_f32_e32 v4, v4, v8
	v_mul_f32_e32 v8, 0xbfb8aa3b, v57
	v_exp_f32_e32 v8, v8
	v_mul_f32_e32 v4, v54, v4
	v_add_f32_e32 v8, 1.0, v8
	v_rcp_f32_e32 v8, v8
	s_nop 0
	v_mul_f32_e32 v8, v8, v57
	v_mul_f32_e32 v4, v8, v4
	v_bfe_u32 v8, v4, 16, 1
	v_add3_u32 v4, v4, v8, s1
	global_store_short_d16_hi v[12:13], v4, off
	v_mul_f32_e32 v4, v5, v9
	v_mul_f32_e32 v5, 0xbfb8aa3b, v58
	v_exp_f32_e32 v5, v5
	v_mul_f32_e32 v4, v54, v4
	v_add_f32_e32 v5, 1.0, v5
	v_rcp_f32_e32 v5, v5
	s_nop 0
	v_mul_f32_e32 v5, v5, v58
	v_mul_f32_e32 v4, v5, v4
	v_bfe_u32 v5, v4, 16, 1
	v_add3_u32 v8, v4, v5, s1
	v_lshlrev_b64 v[4:5], 12, v[30:31]
	v_lshl_add_u64 v[4:5], v[24:25], 0, v[4:5]
	global_store_short_d16_hi v[4:5], v8, off
	v_mul_f32_e32 v5, 0xbfb8aa3b, v59
	v_exp_f32_e32 v5, v5
	v_mul_f32_e32 v4, v6, v10
	v_mul_f32_e32 v4, v54, v4
	v_lshlrev_b64 v[8:9], 12, v[22:23]
	v_add_f32_e32 v5, 1.0, v5
	v_rcp_f32_e32 v5, v5
	v_lshl_add_u64 v[8:9], v[24:25], 0, v[8:9]
	v_mul_f32_e32 v5, v5, v59
	v_mul_f32_e32 v4, v5, v4
	v_bfe_u32 v5, v4, 16, 1
	v_add3_u32 v6, v4, v5, s1
	v_lshlrev_b64 v[4:5], 12, v[36:37]
	v_lshl_add_u64 v[4:5], v[24:25], 0, v[4:5]
	global_store_short_d16_hi v[4:5], v6, off
	v_mul_f32_e32 v5, 0xbfb8aa3b, v62
	v_exp_f32_e32 v5, v5
	v_mul_f32_e32 v4, v7, v11
	v_mul_f32_e32 v4, v54, v4
	v_add_f32_e32 v5, 1.0, v5
	v_rcp_f32_e32 v5, v5
	s_nop 0
	v_mul_f32_e32 v5, v5, v62
	v_mul_f32_e32 v4, v5, v4
	v_bfe_u32 v5, v4, 16, 1
	v_add3_u32 v6, v4, v5, s1
	v_lshlrev_b64 v[4:5], 12, v[38:39]
	v_lshl_add_u64 v[4:5], v[24:25], 0, v[4:5]
	global_store_short_d16_hi v[4:5], v6, off
	v_lshl_add_u32 v4, v56, 2, s74
	ds_read_b128 v[4:7], v4
	s_waitcnt lgkmcnt(0)
	v_mul_f32_e32 v0, v0, v4
	v_mul_f32_e32 v4, 0xbfb8aa3b, v55
	v_exp_f32_e32 v4, v4
	v_mul_f32_e32 v0, v54, v0
	v_add_f32_e32 v4, 1.0, v4
	v_rcp_f32_e32 v4, v4
	s_nop 0
	v_mul_f32_e32 v4, v4, v55
	v_mul_f32_e32 v0, v4, v0
	v_bfe_u32 v4, v0, 16, 1
	v_add3_u32 v0, v0, v4, s1
	global_store_short_d16_hi v[8:9], v0, off
	v_mul_f32_e32 v0, v1, v5
	v_mul_f32_e32 v1, 0xbfb8aa3b, v53
	v_exp_f32_e32 v1, v1
	v_mul_f32_e32 v0, v54, v0
	v_add_f32_e32 v1, 1.0, v1
	v_rcp_f32_e32 v1, v1
	s_nop 0
	v_mul_f32_e32 v1, v1, v53
	v_mul_f32_e32 v0, v1, v0
	v_bfe_u32 v1, v0, 16, 1
	v_add3_u32 v4, v0, v1, s1
	v_lshlrev_b64 v[0:1], 12, v[20:21]
	v_lshl_add_u64 v[0:1], v[24:25], 0, v[0:1]
	global_store_short_d16_hi v[0:1], v4, off
	v_mul_f32_e32 v1, 0xbfb8aa3b, v52
	v_exp_f32_e32 v1, v1
	v_mul_f32_e32 v0, v2, v6
	v_mul_f32_e32 v0, v54, v0
	v_add_f32_e32 v1, 1.0, v1
	v_rcp_f32_e32 v1, v1
	s_nop 0
	v_mul_f32_e32 v1, v1, v52
	v_mul_f32_e32 v0, v1, v0
	v_bfe_u32 v1, v0, 16, 1
	v_add3_u32 v2, v0, v1, s1
	v_lshlrev_b64 v[0:1], 12, v[18:19]
	v_lshl_add_u64 v[0:1], v[24:25], 0, v[0:1]
	global_store_short_d16_hi v[0:1], v2, off
	v_mul_f32_e32 v1, 0xbfb8aa3b, v50
	v_exp_f32_e32 v1, v1
	v_mul_f32_e32 v0, v3, v7
	v_mul_f32_e32 v0, v54, v0
	v_add_f32_e32 v1, 1.0, v1
	v_rcp_f32_e32 v1, v1
	s_nop 0
	v_mul_f32_e32 v1, v1, v50
	v_mul_f32_e32 v0, v1, v0
	v_bfe_u32 v1, v0, 16, 1
	v_add3_u32 v2, v0, v1, s1
	v_lshlrev_b64 v[0:1], 12, v[16:17]
	v_lshl_add_u64 v[0:1], v[24:25], 0, v[0:1]
	global_store_short_d16_hi v[0:1], v2, off
	s_cbranch_scc1 .LBB0_533
.LBB0_510:
	s_ashr_i32 s6, s4, 10
	s_and_b32 s95, s4, 0xff
	s_ashr_i32 s7, s6, 31
	s_bfe_u32 s8, s4, 0x20008
	v_writelane_b32 v255, s4, 30
	s_lshl_b64 s[14:15], s[6:7], 14
	s_lshl_b32 s4, s95, 6
	s_mov_b64 s[12:13], s[68:69]
	s_or_b32 s14, s14, s4
	s_add_u32 s16, s12, 0xe300000
	s_mul_i32 s4, s15, 0x2a00
	s_mul_hi_u32 s7, s14, 0x2a00
	s_addc_u32 s17, s13, 0
	s_add_i32 s7, s7, s4
	s_mul_i32 s4, s14, 0x2a00
	s_add_u32 s9, s16, s4
	s_addc_u32 s7, s17, s7
	s_lshl_b32 s18, s8, 7
	s_lshl_b32 s4, s8, 8
	v_mov_b32_e32 v53, v195
	s_add_u32 s10, s9, s4
	s_addc_u32 s11, s7, 0
	v_lshlrev_b32_e32 v41, 3, v53
	v_ashrrev_i32_e32 v40, 4, v53
	v_mov_b64_e32 v[0:1], s[10:11]
	v_and_b32_e32 v42, 0x78, v41
	v_mad_i64_i32 v[2:3], s[10:11], v40, s2, v[0:1]
	v_lshlrev_b32_e32 v112, 1, v42
	v_lshl_add_u64 v[10:11], v[2:3], 0, v[112:113]
	v_add_u32_e32 v2, 32, v40
	v_mad_i64_i32 v[0:1], s[10:11], v2, s2, v[0:1]
	v_ashrrev_i32_e32 v43, 31, v53
	v_lshl_add_u64 v[36:37], v[0:1], 0, v[112:113]
	v_lshrrev_b32_e32 v0, 29, v43
	v_add_u32_e32 v0, v53, v0
	v_ashrrev_i32_e32 v4, 3, v0
	v_and_b32_e32 v0, -8, v0
	v_ashrrev_i32_e32 v5, 31, v4
	v_sub_u32_e32 v9, v53, v0
	v_lshl_add_u64 v[0:1], s[14:15], 0, v[4:5]
	v_writelane_b32 v255, s16, 31
	v_ashrrev_i32_e32 v6, 3, v53
	v_ashrrev_i32_e32 v7, 31, v6
	v_mov_b64_e32 v[12:13], s[16:17]
	v_writelane_b32 v255, s17, 32
	v_mad_u64_u32 v[2:3], s[10:11], v0, s2, v[12:13]
	s_mov_b32 s19, s73
	v_mad_i32_i24 v3, v1, s2, v3
	v_writelane_b32 v255, s14, 33
	v_lshl_add_u64 v[0:1], v[2:3], 0, s[18:19]
	v_lshlrev_b32_e32 v2, 3, v9
	v_lshl_add_u64 v[14:15], s[14:15], 0, v[6:7]
	v_mad_u64_u32 v[28:29], s[10:11], v14, s2, v[12:13]
	v_ashrrev_i32_e32 v3, 31, v2
	v_mad_i32_i24 v29, v15, s2, v29
	v_and_b32_e32 v5, 56, v41
	v_lshl_add_u64 v[0:1], v[2:3], 1, v[0:1]
	v_lshl_add_u64 v[20:21], v[28:29], 0, s[18:19]
	v_lshlrev_b32_e32 v112, 1, v5
	global_load_dwordx4 v[0:3], v[0:1], off
	v_lshl_add_u64 v[20:21], v[20:21], 0, v[112:113]
	global_load_dwordx4 v[12:15], v[28:29], off offset:2048
	global_load_dwordx4 v[16:19], v[28:29], off offset:2064
	s_nop 0
	global_load_dwordx4 v[20:23], v[20:21], off offset:512
	s_nop 0
	global_load_dwordx4 v[24:27], v[28:29], off offset:2080
	s_nop 0
	global_load_dwordx4 v[28:31], v[28:29], off offset:2096
	s_nop 0
	global_load_dwordx4 v[32:35], v[10:11], off offset:1024
	s_nop 0
	global_load_dwordx4 v[36:39], v[36:37], off offset:1024
	v_lshlrev_b32_e32 v7, 1, v40
	v_and_b32_e32 v10, -8, v40
	v_and_b32_e32 v7, 14, v7
	s_mov_b32 s2, s0
	v_bitop3_b32 v11, v40, v5, -8 bitop3:0x6c
	v_add_u32_e32 v10, 32, v10
	v_writelane_b32 v255, s15, 34
	s_mov_b32 s10, s18
	v_add_u32_e32 v7, s2, v7
	v_lshlrev_b32_e32 v11, 1, v11
	v_mul_u32_u24_e32 v40, 0x90, v42
	v_bitop3_b32 v10, v10, v41, 56 bitop3:0x78
	v_writelane_b32 v255, s10, 35
	v_add3_u32 v11, v7, v11, v40
	v_lshlrev_b32_e32 v10, 1, v10
	v_ashrrev_i32_e32 v8, 6, v53
	v_writelane_b32 v255, s11, 36
	s_waitcnt lgkmcnt(0)
	s_barrier
; template <int TYPE>
; __device__ __forceinline__ void pass3_item(const KArgs& a, int l, int item, LAS unsigned char* lds) {
;     ...
;     const VRaw vr = vT_issue(u + tok0 * DINP + (TYPE ? C_HI : C_GV) + h * 128, tid);
;     bf16x8 qraw[DK / 64];
; #pragma unroll
;     for (int e2 = 0; e2 < DK / 64; ++e2) { const int task = tid + 512 * e2, i = task / C::ND8, d8 = task % C::ND8;
;         qraw[e2] = *(const bf16x8*)(u + (tok0 + i) * DINP + (TYPE ? C_HQ + h * 128 : C_GQ + h * 64) + d8 * 8); }
;     const LgRaw raw0 = lg_issue<TYPE>(u, h, 0, tok0, tid), raw1 = lg_issue<TYPE>(u, h, 1, tok0, tid);
;     __syncthreads();
;     vT_write(vr, lds, tid);
;     float qf[DK / 64][8];
; #pragma unroll
;     for (int e2 = 0; e2 < DK / 64; ++e2) { unpack8(qraw[e2], qf[e2]);
; #pragma unroll
;         for (int e = 0; e < 8; ++e) qf[e2][e] = TYPE ? silu_(qf[e2][e]) : qf[e2][e] * 0.125f; }
;     f32x4 o[4];
; #pragma unroll
;     for (int it = 0; it < 4; ++it) o[it] = (f32x4){0.f, 0.f, 0.f, 0.f};
; #pragma unroll 1
;     for (int dir = 0; dir < 2; ++dir) {
;         const int sitem = ((b * 4 + h) * 2 + dir) * NCH + c;
;         const bf16_t* ST = (const bf16_t*)(wsb + (TYPE ? WS_SH : WS_SG)) + (size_t)sitem * 128 * DK + (size_t)(wid * 16 + fr) * DK + fq * 8;
;         bf16x8 sf[DK / 32];
; #pragma unroll
;         for (int ks = 0; ks < DK / 32; ++ks) sf[ks] = *(const bf16x8*)(ST + ks * 32);
;         if (dir) __syncthreads();
;         { LgRaw rw; rw.a0 = dir ? raw1.a0 : raw0.a0; rw.a1 = dir ? raw1.a1 : raw0.a1; rw.k = dir ? raw1.k : raw0.k; lg_compute<TYPE>(a, wsb, l, h, dir, rw, lds, tid); }
;         cumsum_g<TYPE>(dir, lds, tid);
; #pragma unroll
;         for (int e2 = 0; e2 < DK / 64; ++e2) { const int task = tid + 512 * e2, i = task / C::ND8, d8 = task % C::ND8;
;             const f32x4 g0 = *(LAS f32x4*)(G + i * C::LDG + d8 * 8), g1 = *(LAS f32x4*)(G + i * C::LDG + d8 * 8 + 4);
;             const f32x4 m0 = *(LAS f32x4*)(G + 32 * C::LDG + d8 * 8), m1 = *(LAS f32x4*)(G + 32 * C::LDG + d8 * 8 + 4);
;             float kk[8], qq[8], qt[8], qg[8]; unpack8(*(LAS bf16x8*)(Kb + i * C::LDK_ + d8 * 8), kk);
; #pragma unroll
;             for (int e = 0; e < 8; ++e) qq[e] = qf[e2][e];
; #pragma unroll
;             for (int e = 0; e < 8; ++e) { const float gg = e < 4 ? g0[e] : g1[e - 4], gm = e < 4 ? m0[e] : m1[e - 4];
;                 const float q = qq[e];
	v_add3_u32 v7, v7, v10, v40
	s_mov_b32 s10, 0x3e000000
	v_and_b32_e32 v67, 15, v53
	v_lshlrev_b32_e32 v52, 4, v8
	s_lshl_b32 s6, s6, 3
	s_lshl_b32 s7, s8, 1
	v_writelane_b32 v255, s12, 37
	v_mov_b32_e32 v63, v113
	s_or_b32 s81, s7, s6
	s_mov_b64 s[6:7], 0x31700000
	s_movk_i32 s38, 0x110
	v_writelane_b32 v255, s13, 38
	s_movk_i32 s39, 0x880
	v_cmp_gt_i32_e64 s[20:21], s67, v53
	s_waitcnt vmcnt(0)
	ds_write_b16 v11, v32
	ds_write_b16_d16_hi v11, v32 offset:144
	ds_write_b16 v11, v33 offset:288
	ds_write_b16_d16_hi v11, v33 offset:432
	ds_write_b16 v11, v34 offset:576
	ds_write_b16_d16_hi v11, v34 offset:720
	ds_write_b16 v11, v35 offset:864
	ds_write_b16_d16_hi v11, v35 offset:1008
	v_and_b32_e32 v11, 0xffff0000, v0
	v_lshlrev_b32_e32 v10, 16, v0
	v_pk_mul_f32 v[54:55], v[10:11], s[10:11] op_sel_hi:[1,0]
	v_and_b32_e32 v11, 0xffff0000, v1
	v_lshlrev_b32_e32 v10, 16, v1
	v_pk_mul_f32 v[56:57], v[10:11], s[10:11] op_sel_hi:[1,0]
	v_and_b32_e32 v1, 0xffff0000, v2
	v_lshlrev_b32_e32 v0, 16, v2
	v_or_b32_e32 v10, v52, v67
	v_pk_mul_f32 v[58:59], v[0:1], s[10:11] op_sel_hi:[1,0]
	v_and_b32_e32 v1, 0xffff0000, v3
	v_lshlrev_b32_e32 v0, 16, v3
	v_ashrrev_i32_e32 v11, 31, v10
	v_pk_mul_f32 v[60:61], v[0:1], s[10:11] op_sel_hi:[1,0]
	v_bfe_u32 v3, v53, 4, 2
	v_lshlrev_b64 v[0:1], 7, v[10:11]
	v_lshl_add_u64 v[0:1], s[12:13], 0, v[0:1]
	v_lshlrev_b32_e32 v62, 4, v3
	v_lshl_add_u64 v[0:1], v[0:1], 0, v[62:63]
	v_lshl_add_u64 v[64:65], v[0:1], 0, s[6:7]
	v_mul_lo_u32 v0, v6, s38
	v_add_u32_e32 v0, 0, v0
	v_lshlrev_b32_e32 v2, 2, v5
	v_lshlrev_b32_e32 v1, 7, v6
	v_add_u32_e32 v83, v0, v2
	v_sub_u32_e32 v0, v0, v1
	v_add_u32_e32 v85, v0, v112
	v_lshrrev_b32_e32 v0, 26, v43
	v_add_u32_e32 v0, v53, v0
	v_ashrrev_i32_e32 v1, 6, v0
	v_and_b32_e32 v0, 0x3fffffc0, v0
	v_sub_u32_e32 v0, v53, v0
	v_lshlrev_b32_e32 v0, 2, v0
	v_add_u32_e32 v66, 0, v0
	v_add_u32_e32 v89, s74, v0
	s_movk_i32 s6, 0xffc1
	v_mul_lo_u32 v0, v4, s38
	v_cmp_gt_i32_e64 s[6:7], s6, v53
	v_add_u32_e32 v0, 0, v0
	v_lshlrev_b32_e32 v5, 5, v9
	v_writelane_b32 v255, s6, 39
	v_add_u32_e32 v94, v0, v5
	v_add_u32_e32 v95, 0, v5
	v_lshlrev_b32_e32 v5, 7, v4
	v_writelane_b32 v255, s7, 40
	v_sub_u32_e32 v0, v0, v5
	v_lshlrev_b32_e32 v5, 4, v9
	v_add_u32_e32 v96, v0, v5
	v_mul_lo_u32 v0, v4, s3
	v_readlane_b32 s70, v255, 8
	v_lshlrev_b32_e32 v63, 2, v3
	ds_write_b16 v7, v36
	ds_write_b16_d16_hi v7, v36 offset:144
	ds_write_b16 v7, v37 offset:288
	ds_write_b16_d16_hi v7, v37 offset:432
	ds_write_b16 v7, v38 offset:576
	ds_write_b16_d16_hi v7, v38 offset:720
	ds_write_b16 v7, v39 offset:864
	ds_write_b16_d16_hi v7, v39 offset:1008
	v_add3_u32 v97, s70, v0, v5
	v_and_b32_e32 v5, -16, v6
	v_lshlrev_b32_e32 v7, 3, v3
	v_lshlrev_b32_e32 v87, 3, v1
	v_lshl_add_u32 v93, v1, 9, v89
	v_mul_lo_u32 v1, v1, s39
	v_bfi_b32 v6, -16, v6, v53
	v_add_u32_e32 v0, 0, v62
	v_or_b32_e32 v3, v63, v5
	v_mul_lo_u32 v5, v10, s3
	v_lshlrev_b32_e32 v4, 5, v8
	v_mad_u64_u32 v[68:69], s[38:39], v6, s3, v[0:1]
	v_add_u32_e32 v5, s2, v5
	v_bitop3_b32 v6, v52, 56, v67 bitop3:0xc8
	v_bitop3_b32 v8, v10, v7, 56 bitop3:0x6c
	v_lshl_add_u32 v69, v8, 1, v5
	v_bitop3_b32 v6, v7, v6, 32 bitop3:0x36
	v_and_or_b32 v7, v4, 32, v67
	v_readlane_b32 s71, v255, 9
	v_or_b32_e32 v8, 1, v3
	v_or_b32_e32 v9, 2, v3
	v_or_b32_e32 v10, 3, v3
	v_lshl_add_u32 v98, v6, 1, v5
	v_mul_u32_u24_e32 v4, 0x90, v7
	v_lshl_add_u32 v5, v7, 1, s71
	v_cmp_ge_i32_e64 s[38:39], v7, v3
	v_cmp_le_i32_e64 s[40:41], v7, v3
	v_cmp_gt_i32_e64 s[42:43], v7, v3
	v_cmp_le_i32_e64 s[44:45], v7, v8
	v_cmp_ge_i32_e64 s[50:51], v7, v9
	v_cmp_le_i32_e64 s[52:53], v7, v9
	v_cmp_ge_i32_e64 s[54:55], v7, v10
	v_cmp_le_i32_e64 s[90:91], v7, v10
	v_or_b32_e32 v7, 16, v7
	v_mul_lo_u32 v6, v3, s3
	v_cmp_ge_i32_e64 s[2:3], v7, v3
	v_cmp_le_i32_e64 s[56:57], v7, v3
	v_cmp_gt_i32_e64 s[58:59], v7, v3
	v_mul_u32_u24_e32 v3, 0x48, v67
	v_lshlrev_b32_e32 v3, 1, v3
	v_cmp_gt_i32_e64 s[12:13], s66, v53
	v_lshlrev_b32_e32 v11, 1, v7
	v_cmp_le_i32_e64 s[60:61], v7, v8
	v_cmp_ge_i32_e64 s[62:63], v7, v9
	v_cmp_le_i32_e64 s[64:65], v7, v9
	v_cmp_ge_i32_e64 s[66:67], v7, v10
	v_cmp_le_i32_e64 s[68:69], v7, v10
	v_add_u32_e32 v7, s71, v62
	v_add_u32_e32 v8, 0x900, v3
	v_add_u32_e32 v103, v7, v3
	v_add3_u32 v104, s70, v62, v3
	v_add_u32_e32 v105, v7, v8
	v_add3_u32 v106, s71, v8, v62
	v_add_u32_e32 v8, 0x1200, v3
	v_add_u32_e32 v3, 0x1b00, v3
	s_add_u32 s70, s46, s4
	v_add3_u32 v99, s71, v6, v11
	v_add3_u32 v108, s71, v8, v62
	v_add_u32_e32 v109, v7, v3
	v_add3_u32 v110, s71, v3, v62
	s_addc_u32 s71, s47, 0
	v_mov_b32_e32 v3, v113
	v_lshl_add_u64 v[70:71], s[70:71], 0, v[2:3]
	s_add_u32 s70, s48, s4
	s_movk_i32 s10, 0x7f
	s_movk_i32 s14, 0xbf
	s_movk_i32 s16, 0xc0
	s_movk_i32 s18, 0xff
	s_movk_i32 s22, 0x13f
	s_movk_i32 s24, 0x140
	s_movk_i32 s26, 0x17f
	s_movk_i32 s28, 0x180
	s_movk_i32 s30, 0x1bf
	s_movk_i32 s34, 0x1c0
	s_movk_i32 s36, 0x1ff
	s_addc_u32 s71, s49, 0
	v_mov_b32_e32 v32, 0
	v_cmp_lt_i32_e64 s[82:83], 63, v53
	v_cmp_gt_i32_e64 s[6:7], 64, v53
	v_cmp_lt_i32_e64 s[10:11], s10, v53
	v_cmp_lt_i32_e64 s[14:15], s14, v53
	v_cmp_gt_i32_e64 s[16:17], s16, v53
	v_cmp_lt_i32_e64 s[18:19], s18, v53
	v_cmp_lt_i32_e64 s[22:23], s22, v53
	v_cmp_gt_i32_e64 s[24:25], s24, v53
	v_cmp_lt_i32_e64 s[26:27], s26, v53
	v_cmp_gt_i32_e64 s[28:29], s28, v53
	v_cmp_lt_i32_e64 s[30:31], s30, v53
	v_cmp_gt_i32_e64 s[34:35], s34, v53
	v_cmp_lt_i32_e64 s[36:37], s36, v53
	v_add_u32_e32 v100, 0x90, v99
	v_add_u32_e32 v101, 0x120, v99
	v_add_u32_e32 v102, 0x1b0, v99
	v_add_u32_e32 v107, v7, v8
	v_lshl_add_u64 v[72:73], s[70:71], 0, v[2:3]
	s_mov_b32 s70, 0
	s_mov_b64 s[84:85], -1
	v_add_u32_e32 v111, v66, v1
	v_add_u32_e32 v112, v0, v4
	v_add_u32_e32 v114, v5, v6
	v_mov_b32_e32 v33, v32
	v_mov_b32_e32 v34, v32
	v_mov_b32_e32 v35, v32
	v_mov_b32_e32 v8, v32
	v_mov_b32_e32 v9, v32
	v_mov_b32_e32 v10, v32
	v_mov_b32_e32 v11, v32
	v_mov_b32_e32 v4, v32
	v_mov_b32_e32 v5, v32
	v_mov_b32_e32 v6, v32
	v_mov_b32_e32 v7, v32
	v_mov_b32_e32 v0, v32
	v_mov_b32_e32 v1, v32
	v_mov_b32_e32 v2, v32
	v_mov_b32_e32 v3, v32
	s_branch .LBB0_512

; template <int TYPE>
; __device__ __forceinline__ void pass3_item(const KArgs& a, int l, int item, LAS unsigned char* lds) {
;     ...
;         const int sitem = ((b * 4 + h) * 2 + dir) * NCH + c;
;         const bf16_t* ST = (const bf16_t*)(wsb + (TYPE ? WS_SH : WS_SG)) + (size_t)sitem * 128 * DK + (size_t)(wid * 16 + fr) * DK + fq * 8;
;         bf16x8 sf[DK / 32];
; #pragma unroll
;         for (int ks = 0; ks < DK / 32; ++ks) sf[ks] = *(const bf16x8*)(ST + ks * 32);
;         if (dir) __syncthreads();
;         { LgRaw rw; rw.a0 = dir ? raw1.a0 : raw0.a0; rw.a1 = dir ? raw1.a1 : raw0.a1; rw.k = dir ? raw1.k : raw0.k; lg_compute<TYPE>(a, wsb, l, h, dir, rw, lds, tid); }
.LBB0_512:
	s_or_b32 s4, s70, s81
	s_lshl_b32 s4, s4, 8
	s_or_b32 s74, s4, s95
	s_ashr_i32 s75, s74, 31
	s_lshl_b64 s[74:75], s[74:75], 14
	v_lshl_add_u64 v[36:37], v[64:65], 0, s[74:75]
	global_load_dwordx4 v[40:43], v[36:37], off
	s_nop 0
	global_load_dwordx4 v[36:39], v[36:37], off offset:64
	s_and_b64 vcc, exec, s[84:85]
	s_cbranch_vccnz .LBB0_514
	v_readlane_b32 s8, v255, 39
	v_readlane_b32 s9, v255, 40
	s_andn2_b64 s[86:87], s[82:83], exec
	s_and_b64 vcc, s[8:9], exec
	v_mov_b64_e32 v[50:51], v[26:27]
	v_mov_b64_e32 v[46:47], v[30:31]
	s_mov_b32 s76, 7
	s_mov_b32 s93, 6
	s_mov_b32 s79, 5
	s_mov_b32 s78, 4
	s_mov_b32 s75, 3
	s_mov_b32 s74, 2
	s_mov_b32 s4, 1
	s_mov_b32 s80, 0
	s_or_b64 s[86:87], s[86:87], vcc
	v_mov_b64_e32 v[48:49], v[24:25]
	v_mov_b64_e32 v[44:45], v[28:29]
	s_waitcnt lgkmcnt(0)
	s_barrier
	s_branch .LBB0_515

; __device__ __forceinline__ unsigned xb_ld(unsigned* p)              { return __hip_atomic_load(p, __ATOMIC_RELAXED, __HIP_MEMORY_SCOPE_AGENT); }
; __device__ __forceinline__ void xcd_barrier_complete(unsigned* bar, unsigned x, unsigned& nloc, unsigned& nx) {
;     const unsigned G = gridDim.x * gridDim.y * gridDim.z;
;     unsigned sum, cnt, mine, sp = 0u;
;     for (;;) {
;         sum = 0u; cnt = 0u; mine = 0u;
; #pragma unroll
;         for (unsigned j = 0; j < 16; ++j) { const unsigned c = xb_ld(&bar[XB_XCNT(j)]); sum += c; cnt += (c > 0u) ? 1u : 0u; mine = (j == x) ? c : mine; }
;         if (sum == G) break;
;         __builtin_amdgcn_s_sleep(1);
;         if ((++sp & 255u) == 0u) { if (xb_ld(&bar[XB_TMO])) break; if (sp > XB_SPIN_CAP) { atomicAdd(&bar[XB_TMO], 1u); break; } }
;     }
;     nloc = mine > 0u ? mine : 1u; nx = cnt > 0u ? cnt : 1u;
; }
.LBB0_539:
	s_waitcnt lgkmcnt(0)
	v_mov_b64_e32 v[0:1], s[8:9]
	v_mov_b64_e32 v[2:3], s[10:11]
	global_load_dword v0, v[0:1], off sc1
	v_readlane_b32 s54, v255, 5
	global_load_dword v1, v[2:3], off sc1
	v_mov_b64_e32 v[2:3], s[12:13]
	global_load_dword v2, v[2:3], off sc1
	s_or_b64 s[52:53], s[52:53], exec
	s_or_b64 s[50:51], s[50:51], exec
	s_waitcnt vmcnt(0) lgkmcnt(0)
	v_add_u32_e32 v4, v1, v0
	v_add_u32_e32 v6, v4, v2
	v_mov_b64_e32 v[4:5], s[14:15]
	global_load_dword v3, v[4:5], off sc1
	v_mov_b64_e32 v[4:5], s[16:17]
	global_load_dword v4, v[4:5], off sc1
	s_waitcnt vmcnt(0) lgkmcnt(0)
	v_add_u32_e32 v6, v6, v3
	v_add_u32_e32 v8, v6, v4
	v_mov_b64_e32 v[6:7], s[18:19]
	global_load_dword v5, v[6:7], off sc1
	v_mov_b64_e32 v[6:7], s[20:21]
	global_load_dword v6, v[6:7], off sc1
	s_waitcnt vmcnt(0) lgkmcnt(0)
	v_add_u32_e32 v8, v8, v5
	v_add_u32_e32 v10, v8, v6
	v_mov_b64_e32 v[8:9], s[22:23]
	global_load_dword v7, v[8:9], off sc1
	v_mov_b64_e32 v[8:9], s[24:25]
	global_load_dword v8, v[8:9], off sc1
	s_waitcnt vmcnt(0) lgkmcnt(0)
	v_add_u32_e32 v10, v10, v7
	v_add_u32_e32 v12, v10, v8
	v_mov_b64_e32 v[10:11], s[26:27]
	global_load_dword v9, v[10:11], off sc1
	v_mov_b64_e32 v[10:11], s[28:29]
	global_load_dword v10, v[10:11], off sc1
	s_waitcnt vmcnt(0) lgkmcnt(0)
	v_add_u32_e32 v12, v12, v9
	v_add_u32_e32 v14, v12, v10
	v_mov_b64_e32 v[12:13], s[30:31]
	global_load_dword v11, v[12:13], off sc1
	v_mov_b64_e32 v[12:13], s[34:35]
	global_load_dword v12, v[12:13], off sc1
	s_waitcnt vmcnt(0) lgkmcnt(0)
	v_add_u32_e32 v14, v14, v11
	v_add_u32_e32 v16, v14, v12
	v_mov_b64_e32 v[14:15], s[36:37]
	global_load_dword v13, v[14:15], off sc1
	v_mov_b64_e32 v[14:15], s[42:43]
	global_load_dword v14, v[14:15], off sc1
	s_waitcnt vmcnt(0) lgkmcnt(0)
	v_add_u32_e32 v16, v16, v13
	v_add_u32_e32 v18, v16, v14
	v_mov_b64_e32 v[16:17], s[44:45]
	global_load_dword v15, v[16:17], off sc1
	s_waitcnt vmcnt(0) lgkmcnt(0)
	v_add_u32_e32 v16, v18, v15
	v_cmp_ne_u32_e32 vcc, s54, v16
	s_and_saveexec_b64 s[54:55], vcc
	s_cbranch_execz .LBB0_538
	s_and_b32 s58, s5, 0xff
	s_mov_b64 s[56:57], -1
	s_cmp_eq_u32 s58, 0
	s_mov_b64 s[60:61], -1
	s_mov_b64 s[58:59], -1
	s_sleep 1
	s_cbranch_scc1 .LBB0_542
	s_and_saveexec_b64 s[62:63], s[60:61]
	s_cbranch_execz .LBB0_537
	s_branch .LBB0_545
.LBB0_542:
	v_mov_b64_e32 v[16:17], s[6:7]
	global_load_dword v16, v[16:17], off sc1
	s_mov_b64 s[60:61], 0
	s_waitcnt vmcnt(0) lgkmcnt(0)
	v_cmp_eq_u32_e32 vcc, 0, v16
	s_and_saveexec_b64 s[62:63], vcc
	s_cmp_lt_u32 s5, 0x40001
	s_cselect_b64 s[60:61], -1, 0
	s_xor_b64 s[58:59], exec, -1
	s_and_b64 s[60:61], s[60:61], exec
	s_or_b64 exec, exec, s[62:63]
	s_and_saveexec_b64 s[62:63], s[60:61]
	s_cbranch_execz .LBB0_537

; __device__ __forceinline__ unsigned cvt_pk_bf16(float lo, float hi) { f32x2 v = {lo, hi}; bf16x2_t b = __builtin_convertvector(v, bf16x2_t); return __builtin_bit_cast(unsigned, b); }
;     __device__ __forceinline__ void operator()(const f32x4 (&acc)[2][2][4][2], const Unit& u, int wr, int wc, int fr, int fq) const {
;     ...
;             for (int m = 0; m < 4; ++m) { const size_t off = (size_t)(row0 + ai * HALF + m * 16) * DM + col0; float ss = 0.f;
; #pragma unroll
;                 for (int bj = 0; bj < 2; ++bj)
; #pragma unroll
;                     for (int n = 0; n < 2; ++n) { const f32x4 o = bs[m][bj][n] + acc[ai][bj][m][n];
;                         u32x2 w; w.x = cvt_pk_bf16(o[0], o[1]); w.y = cvt_pk_bf16(o[2], o[3]);
;                         *(u32x2*)(h1 + off + bj * HALF + n * 16) = w;
;                         if (h2) *(u32x2*)(h2 + off + bj * HALF + n * 16) = w;
;                         ss += (o[0] * o[0] + o[1] * o[1]) + (o[2] * o[2] + o[3] * o[3]); }
;                 ss += __shfl_xor(ss, 16); ss += __shfl_xor(ss, 32);
;                 if (fq == 0) rsq[(size_t)(row0 + ai * HALF + m * 16) * 32 + u.pn * 4 + wc] = ss; } }
.LBB0_598:
	s_waitcnt vmcnt(0)
	v_pk_add_f32 v[126:127], v[126:127], v[190:191]
	v_pk_add_f32 v[128:129], v[128:129], v[192:193]
	v_cvt_pk_bf16_f32 v190, v126, v127
	v_mul_f32_e32 v127, v127, v127
	v_fmac_f32_e32 v127, v126, v126
	v_mul_f32_e32 v126, v129, v129
	v_fmac_f32_e32 v126, v128, v128
	v_pk_add_f32 v[122:123], v[122:123], v[186:187]
	v_add_f32_e32 v127, v127, v126
	v_pk_add_f32 v[124:125], v[124:125], v[188:189]
	v_cvt_pk_bf16_f32 v126, v122, v123
	v_mul_f32_e32 v123, v123, v123
	v_fmac_f32_e32 v123, v122, v122
	v_mul_f32_e32 v122, v125, v125
	v_fmac_f32_e32 v122, v124, v124
	v_add_f32_e32 v122, v123, v122
	v_pk_add_f32 v[120:121], v[120:121], v[184:185]
	v_pk_add_f32 v[118:119], v[118:119], v[182:183]
	v_add_f32_e32 v122, v122, v127
	v_mul_f32_e32 v123, v119, v119
	v_mul_f32_e32 v127, v121, v121
	v_fmac_f32_e32 v123, v118, v118
	v_fmac_f32_e32 v127, v120, v120
	v_add_f32_e32 v123, v123, v127
	v_and_b32_e32 v197, 64, v237
	v_add_f32_e32 v127, v123, v122
	v_pk_add_f32 v[116:117], v[116:117], v[180:181]
	v_pk_add_f32 v[122:123], v[114:115], v[178:179]
	v_xor_b32_e32 v196, 16, v237
	v_add_u32_e32 v197, 64, v197
	v_mul_f32_e32 v114, v123, v123
	v_mul_f32_e32 v115, v117, v117
	v_cmp_lt_i32_e32 vcc, v196, v197
	v_fmac_f32_e32 v114, v122, v122
	v_fmac_f32_e32 v115, v116, v116
	v_cndmask_b32_e32 v196, v237, v196, vcc
	v_add_f32_e32 v114, v114, v115
	v_lshlrev_b32_e32 v248, 2, v196
	v_add_f32_e32 v114, v114, v127
	ds_bpermute_b32 v115, v248, v114
	v_xor_b32_e32 v196, 32, v237
	v_cmp_lt_i32_e32 vcc, v196, v197
	v_lshl_add_u64 v[192:193], s[16:17], 0, v[234:235]
	s_lshl_b32 s30, s49, 2
	v_cndmask_b32_e32 v196, v237, v196, vcc
	v_lshlrev_b32_e32 v247, 2, v196
	s_waitcnt lgkmcnt(0)
	v_add_f32_e32 v114, v114, v115
	ds_bpermute_b32 v115, v247, v114
	v_lshl_add_u64 v[192:193], v[212:213], 1, v[192:193]
	v_cvt_pk_bf16_f32 v118, v118, v119
	v_cvt_pk_bf16_f32 v119, v120, v121
	s_ashr_i32 s31, s30, 31
	v_cvt_pk_bf16_f32 v191, v128, v129
	v_cvt_pk_bf16_f32 v127, v124, v125
	global_store_dwordx2 v[192:193], v[118:119], off offset:256
	v_cvt_pk_bf16_f32 v118, v122, v123
	v_cvt_pk_bf16_f32 v119, v116, v117
	global_store_dwordx2 v[192:193], v[190:191], off
	global_store_dwordx2 v[192:193], v[126:127], off offset:32
	global_store_dwordx2 v[192:193], v[118:119], off offset:288
	s_and_saveexec_b64 s[34:35], s[6:7]
	s_cbranch_execz .LBB0_600
	v_lshlrev_b64 v[116:117], 7, v[214:215]
	v_lshl_add_u64 v[116:117], s[18:19], 0, v[116:117]
	v_lshl_add_u64 v[116:117], s[30:31], 2, v[116:117]
	s_lshl_b32 s72, s45, 2
	v_lshl_add_u64 v[116:117], v[116:117], 0, s[72:73]
	s_waitcnt lgkmcnt(0)
	v_add_f32_e32 v114, v114, v115
	global_store_dword v[116:117], v114, off
.LBB0_600:
	s_or_b64 exec, exec, s[34:35]
	v_pk_add_f32 v[108:109], v[108:109], v[174:175]
	v_pk_add_f32 v[110:111], v[110:111], v[176:177]
	v_cvt_pk_bf16_f32 v114, v108, v109
	v_mul_f32_e32 v109, v109, v109
	v_fmac_f32_e32 v109, v108, v108
	v_mul_f32_e32 v108, v111, v111
	v_fmac_f32_e32 v108, v110, v110
	v_pk_add_f32 v[104:105], v[104:105], v[170:171]
	v_add_f32_e32 v109, v109, v108
	v_pk_add_f32 v[106:107], v[106:107], v[172:173]
	v_cvt_pk_bf16_f32 v108, v104, v105
	v_mul_f32_e32 v105, v105, v105
	v_fmac_f32_e32 v105, v104, v104
	v_mul_f32_e32 v104, v107, v107
	v_fmac_f32_e32 v104, v106, v106
	v_add_f32_e32 v104, v105, v104
	v_pk_add_f32 v[102:103], v[102:103], v[168:169]
	v_pk_add_f32 v[100:101], v[100:101], v[166:167]
	v_add_f32_e32 v104, v104, v109
	v_mul_f32_e32 v105, v101, v101
	v_mul_f32_e32 v109, v103, v103
	v_fmac_f32_e32 v105, v100, v100
	v_fmac_f32_e32 v109, v102, v102
	v_add_f32_e32 v105, v105, v109
	v_add_f32_e32 v109, v105, v104
	v_pk_add_f32 v[98:99], v[98:99], v[164:165]
	v_pk_add_f32 v[104:105], v[96:97], v[162:163]
	v_mul_f32_e32 v97, v99, v99
	v_mul_f32_e32 v96, v105, v105
	v_fmac_f32_e32 v96, v104, v104
	v_fmac_f32_e32 v97, v98, v98
	v_add_f32_e32 v96, v96, v97
	v_add_f32_e32 v96, v96, v109
	ds_bpermute_b32 v97, v248, v96
	v_lshl_add_u64 v[116:117], s[16:17], 0, v[232:233]
	v_lshl_add_u64 v[116:117], v[212:213], 1, v[116:117]
	v_cvt_pk_bf16_f32 v100, v100, v101
	v_cvt_pk_bf16_f32 v101, v102, v103
	s_waitcnt lgkmcnt(0)
	v_add_f32_e32 v96, v96, v97
	ds_bpermute_b32 v97, v247, v96
	v_cvt_pk_bf16_f32 v115, v110, v111
	v_cvt_pk_bf16_f32 v109, v106, v107
	global_store_dwordx2 v[116:117], v[100:101], off offset:256
	v_cvt_pk_bf16_f32 v100, v104, v105
	v_cvt_pk_bf16_f32 v101, v98, v99
	global_store_dwordx2 v[116:117], v[114:115], off
	global_store_dwordx2 v[116:117], v[108:109], off offset:32
	global_store_dwordx2 v[116:117], v[100:101], off offset:288
	s_and_saveexec_b64 s[34:35], s[6:7]
	s_cbranch_execz .LBB0_602
	v_lshlrev_b64 v[98:99], 7, v[228:229]
	v_lshl_add_u64 v[98:99], s[18:19], 0, v[98:99]
	v_lshl_add_u64 v[98:99], s[30:31], 2, v[98:99]
	s_lshl_b32 s72, s45, 2
	v_lshl_add_u64 v[98:99], v[98:99], 0, s[72:73]
	s_waitcnt lgkmcnt(0)
	v_add_f32_e32 v96, v96, v97
	global_store_dword v[98:99], v96, off
; __device__ __forceinline__ unsigned cvt_pk_bf16(float lo, float hi) { f32x2 v = {lo, hi}; bf16x2_t b = __builtin_convertvector(v, bf16x2_t); return __builtin_bit_cast(unsigned, b); }
;     __device__ __forceinline__ void operator()(const f32x4 (&acc)[2][2][4][2], const Unit& u, int wr, int wc, int fr, int fq) const {
;     ...
;             for (int m = 0; m < 4; ++m) { const size_t off = (size_t)(row0 + ai * HALF + m * 16) * DM + col0; float ss = 0.f;
; #pragma unroll
;                 for (int bj = 0; bj < 2; ++bj)
; #pragma unroll
;                     for (int n = 0; n < 2; ++n) { const f32x4 o = bs[m][bj][n] + acc[ai][bj][m][n];
;                         u32x2 w; w.x = cvt_pk_bf16(o[0], o[1]); w.y = cvt_pk_bf16(o[2], o[3]);
;                         *(u32x2*)(h1 + off + bj * HALF + n * 16) = w;
;                         if (h2) *(u32x2*)(h2 + off + bj * HALF + n * 16) = w;
;                         ss += (o[0] * o[0] + o[1] * o[1]) + (o[2] * o[2] + o[3] * o[3]); }
;                 ss += __shfl_xor(ss, 16); ss += __shfl_xor(ss, 32);
;                 if (fq == 0) rsq[(size_t)(row0 + ai * HALF + m * 16) * 32 + u.pn * 4 + wc] = ss; } }
.LBB0_602:
	s_or_b64 exec, exec, s[34:35]
	v_pk_add_f32 v[92:93], v[92:93], v[158:159]
	v_pk_add_f32 v[94:95], v[94:95], v[160:161]
	v_cvt_pk_bf16_f32 v96, v92, v93
	v_mul_f32_e32 v93, v93, v93
	v_fmac_f32_e32 v93, v92, v92
	v_mul_f32_e32 v92, v95, v95
	v_fmac_f32_e32 v92, v94, v94
	v_pk_add_f32 v[88:89], v[88:89], v[154:155]
	v_add_f32_e32 v93, v93, v92
	v_pk_add_f32 v[90:91], v[90:91], v[156:157]
	v_cvt_pk_bf16_f32 v92, v88, v89
	v_mul_f32_e32 v89, v89, v89
	v_fmac_f32_e32 v89, v88, v88
	v_mul_f32_e32 v88, v91, v91
	v_fmac_f32_e32 v88, v90, v90
	v_add_f32_e32 v88, v89, v88
	v_pk_add_f32 v[86:87], v[86:87], v[152:153]
	v_pk_add_f32 v[84:85], v[84:85], v[150:151]
	v_add_f32_e32 v88, v88, v93
	v_mul_f32_e32 v89, v85, v85
	v_mul_f32_e32 v93, v87, v87
	v_fmac_f32_e32 v89, v84, v84
	v_fmac_f32_e32 v93, v86, v86
	v_add_f32_e32 v89, v89, v93
	v_add_f32_e32 v93, v89, v88
	v_pk_add_f32 v[82:83], v[82:83], v[148:149]
	v_pk_add_f32 v[88:89], v[80:81], v[146:147]
	v_mul_f32_e32 v81, v83, v83
	v_mul_f32_e32 v80, v89, v89
	v_fmac_f32_e32 v80, v88, v88
	v_fmac_f32_e32 v81, v82, v82
	v_add_f32_e32 v80, v80, v81
	v_add_f32_e32 v80, v80, v93
	ds_bpermute_b32 v81, v248, v80
	v_lshl_add_u64 v[98:99], s[16:17], 0, v[230:231]
	v_lshl_add_u64 v[98:99], v[212:213], 1, v[98:99]
	v_cvt_pk_bf16_f32 v84, v84, v85
	v_cvt_pk_bf16_f32 v85, v86, v87
	s_waitcnt lgkmcnt(0)
	v_add_f32_e32 v80, v80, v81
	ds_bpermute_b32 v81, v247, v80
	v_cvt_pk_bf16_f32 v97, v94, v95
	v_cvt_pk_bf16_f32 v93, v90, v91
	global_store_dwordx2 v[98:99], v[84:85], off offset:256
	v_cvt_pk_bf16_f32 v84, v88, v89
	v_cvt_pk_bf16_f32 v85, v82, v83
	global_store_dwordx2 v[98:99], v[96:97], off
	global_store_dwordx2 v[98:99], v[92:93], off offset:32
	global_store_dwordx2 v[98:99], v[84:85], off offset:288
	s_and_saveexec_b64 s[34:35], s[6:7]
	s_cbranch_execz .LBB0_604
	v_lshlrev_b64 v[82:83], 7, v[226:227]
	v_lshl_add_u64 v[82:83], s[18:19], 0, v[82:83]
	v_lshl_add_u64 v[82:83], s[30:31], 2, v[82:83]
	s_lshl_b32 s72, s45, 2
	v_lshl_add_u64 v[82:83], v[82:83], 0, s[72:73]
	s_waitcnt lgkmcnt(0)
	v_add_f32_e32 v80, v80, v81
	global_store_dword v[82:83], v80, off
.LBB0_604:
	s_or_b64 exec, exec, s[34:35]
	v_pk_add_f32 v[76:77], v[76:77], v[142:143]
	v_pk_add_f32 v[78:79], v[78:79], v[144:145]
	v_cvt_pk_bf16_f32 v80, v76, v77
	v_mul_f32_e32 v77, v77, v77
	v_fmac_f32_e32 v77, v76, v76
	v_mul_f32_e32 v76, v79, v79
	v_fmac_f32_e32 v76, v78, v78
	v_pk_add_f32 v[72:73], v[72:73], v[138:139]
	v_add_f32_e32 v77, v77, v76
	v_pk_add_f32 v[74:75], v[74:75], v[140:141]
	v_cvt_pk_bf16_f32 v76, v72, v73
	v_mul_f32_e32 v73, v73, v73
	v_fmac_f32_e32 v73, v72, v72
	v_mul_f32_e32 v72, v75, v75
	v_fmac_f32_e32 v72, v74, v74
	v_add_f32_e32 v72, v73, v72
	v_pk_add_f32 v[70:71], v[70:71], v[136:137]
	v_pk_add_f32 v[68:69], v[68:69], v[134:135]
	v_add_f32_e32 v72, v72, v77
	v_mul_f32_e32 v73, v69, v69
	v_mul_f32_e32 v77, v71, v71
	v_fmac_f32_e32 v73, v68, v68
	v_fmac_f32_e32 v77, v70, v70
	v_add_f32_e32 v73, v73, v77
	v_add_f32_e32 v77, v73, v72
	v_pk_add_f32 v[66:67], v[66:67], v[132:133]
	v_pk_add_f32 v[72:73], v[64:65], v[130:131]
	v_mul_f32_e32 v65, v67, v67
	v_mul_f32_e32 v64, v73, v73
	v_fmac_f32_e32 v64, v72, v72
	v_fmac_f32_e32 v65, v66, v66
	v_add_f32_e32 v64, v64, v65
	v_add_f32_e32 v64, v64, v77
	ds_bpermute_b32 v65, v248, v64
	v_ashrrev_i32_e32 v225, 31, v224
	v_lshlrev_b64 v[82:83], 12, v[224:225]
	v_lshl_add_u64 v[82:83], s[16:17], 0, v[82:83]
	v_lshl_add_u64 v[82:83], v[212:213], 1, v[82:83]
	s_waitcnt lgkmcnt(0)
	v_add_f32_e32 v64, v64, v65
	ds_bpermute_b32 v65, v247, v64
	v_cvt_pk_bf16_f32 v68, v68, v69
	v_cvt_pk_bf16_f32 v69, v70, v71
	v_cvt_pk_bf16_f32 v81, v78, v79
	v_cvt_pk_bf16_f32 v77, v74, v75
	global_store_dwordx2 v[82:83], v[68:69], off offset:256
	v_cvt_pk_bf16_f32 v68, v72, v73
	v_cvt_pk_bf16_f32 v69, v66, v67
	global_store_dwordx2 v[82:83], v[80:81], off
	global_store_dwordx2 v[82:83], v[76:77], off offset:32
	global_store_dwordx2 v[82:83], v[68:69], off offset:288
	s_and_saveexec_b64 s[34:35], s[6:7]
	s_cbranch_execz .LBB0_606
	v_lshlrev_b64 v[66:67], 7, v[224:225]
	v_lshl_add_u64 v[66:67], s[18:19], 0, v[66:67]
	v_lshl_add_u64 v[66:67], s[30:31], 2, v[66:67]
	s_lshl_b32 s72, s45, 2
	v_lshl_add_u64 v[66:67], v[66:67], 0, s[72:73]
	s_waitcnt lgkmcnt(0)
	v_add_f32_e32 v64, v64, v65
	global_store_dword v[66:67], v64, off

; __device__ __forceinline__ unsigned cvt_pk_bf16(float lo, float hi) { f32x2 v = {lo, hi}; bf16x2_t b = __builtin_convertvector(v, bf16x2_t); return __builtin_bit_cast(unsigned, b); }
;     __device__ __forceinline__ void operator()(const f32x4 (&acc)[2][2][4][2], const Unit& u, int wr, int wc, int fr, int fq) const {
;     ...
;             for (int m = 0; m < 4; ++m) { const size_t off = (size_t)(row0 + ai * HALF + m * 16) * DM + col0; float ss = 0.f;
; #pragma unroll
;                 for (int bj = 0; bj < 2; ++bj)
; #pragma unroll
;                     for (int n = 0; n < 2; ++n) { const f32x4 o = bs[m][bj][n] + acc[ai][bj][m][n];
;                         u32x2 w; w.x = cvt_pk_bf16(o[0], o[1]); w.y = cvt_pk_bf16(o[2], o[3]);
;                         *(u32x2*)(h1 + off + bj * HALF + n * 16) = w;
;                         if (h2) *(u32x2*)(h2 + off + bj * HALF + n * 16) = w;
;                         ss += (o[0] * o[0] + o[1] * o[1]) + (o[2] * o[2] + o[3] * o[3]); }
;                 ss += __shfl_xor(ss, 16); ss += __shfl_xor(ss, 32);
;                 if (fq == 0) rsq[(size_t)(row0 + ai * HALF + m * 16) * 32 + u.pn * 4 + wc] = ss; } }
.LBB0_610:
	s_waitcnt vmcnt(0)
	v_pk_add_f32 v[60:61], v[60:61], v[126:127]
	v_pk_add_f32 v[62:63], v[62:63], v[128:129]
	v_cvt_pk_bf16_f32 v126, v60, v61
	v_mul_f32_e32 v61, v61, v61
	v_fmac_f32_e32 v61, v60, v60
	v_mul_f32_e32 v60, v63, v63
	v_fmac_f32_e32 v60, v62, v62
	v_pk_add_f32 v[56:57], v[56:57], v[122:123]
	v_add_f32_e32 v61, v61, v60
	v_pk_add_f32 v[58:59], v[58:59], v[124:125]
	v_cvt_pk_bf16_f32 v60, v56, v57
	v_mul_f32_e32 v57, v57, v57
	v_fmac_f32_e32 v57, v56, v56
	v_mul_f32_e32 v56, v59, v59
	v_fmac_f32_e32 v56, v58, v58
	v_add_f32_e32 v56, v57, v56
	v_pk_add_f32 v[54:55], v[54:55], v[120:121]
	v_pk_add_f32 v[52:53], v[52:53], v[118:119]
	v_add_f32_e32 v56, v56, v61
	v_mul_f32_e32 v57, v53, v53
	v_mul_f32_e32 v61, v55, v55
	v_fmac_f32_e32 v57, v52, v52
	v_fmac_f32_e32 v61, v54, v54
	v_add_f32_e32 v57, v57, v61
	v_add_f32_e32 v61, v57, v56
	v_pk_add_f32 v[50:51], v[50:51], v[116:117]
	v_pk_add_f32 v[56:57], v[48:49], v[114:115]
	v_mul_f32_e32 v49, v51, v51
	v_mul_f32_e32 v48, v57, v57
	v_fmac_f32_e32 v48, v56, v56
	v_fmac_f32_e32 v49, v50, v50
	v_add_f32_e32 v48, v48, v49
	v_add_f32_e32 v48, v48, v61
	ds_bpermute_b32 v49, v248, v48
	v_lshl_add_u64 v[128:129], s[16:17], 0, v[142:143]
	v_lshl_add_u64 v[128:129], v[212:213], 1, v[128:129]
	v_cvt_pk_bf16_f32 v52, v52, v53
	v_cvt_pk_bf16_f32 v53, v54, v55
	s_waitcnt lgkmcnt(0)
	v_add_f32_e32 v48, v48, v49
	ds_bpermute_b32 v49, v247, v48
	v_cvt_pk_bf16_f32 v127, v62, v63
	v_cvt_pk_bf16_f32 v61, v58, v59
	global_store_dwordx2 v[128:129], v[52:53], off offset:256
	v_cvt_pk_bf16_f32 v52, v56, v57
	v_cvt_pk_bf16_f32 v53, v50, v51
	global_store_dwordx2 v[128:129], v[126:127], off
	global_store_dwordx2 v[128:129], v[60:61], off offset:32
	global_store_dwordx2 v[128:129], v[52:53], off offset:288
	s_and_saveexec_b64 s[10:11], s[6:7]
	s_cbranch_execz .LBB0_612
	v_lshlrev_b64 v[50:51], 7, v[136:137]
	v_lshl_add_u64 v[50:51], s[18:19], 0, v[50:51]
	v_lshl_add_u64 v[50:51], s[30:31], 2, v[50:51]
	s_lshl_b32 s72, s45, 2
	v_lshl_add_u64 v[50:51], v[50:51], 0, s[72:73]
	s_waitcnt lgkmcnt(0)
	v_add_f32_e32 v48, v48, v49
	global_store_dword v[50:51], v48, off
.LBB0_612:
	s_or_b64 exec, exec, s[10:11]
	v_pk_add_f32 v[44:45], v[44:45], v[108:109]
	v_pk_add_f32 v[46:47], v[46:47], v[110:111]
	v_cvt_pk_bf16_f32 v48, v44, v45
	v_mul_f32_e32 v45, v45, v45
	v_fmac_f32_e32 v45, v44, v44
	v_mul_f32_e32 v44, v47, v47
	v_fmac_f32_e32 v44, v46, v46
	v_pk_add_f32 v[40:41], v[40:41], v[104:105]
	v_add_f32_e32 v45, v45, v44
	v_pk_add_f32 v[42:43], v[42:43], v[106:107]
	v_cvt_pk_bf16_f32 v44, v40, v41
	v_mul_f32_e32 v41, v41, v41
	v_fmac_f32_e32 v41, v40, v40
	v_mul_f32_e32 v40, v43, v43
	v_fmac_f32_e32 v40, v42, v42
	v_add_f32_e32 v40, v41, v40
	v_pk_add_f32 v[38:39], v[38:39], v[102:103]
	v_pk_add_f32 v[36:37], v[36:37], v[100:101]
	v_add_f32_e32 v40, v40, v45
	v_mul_f32_e32 v41, v37, v37
	v_mul_f32_e32 v45, v39, v39
	v_fmac_f32_e32 v41, v36, v36
	v_fmac_f32_e32 v45, v38, v38
	v_add_f32_e32 v41, v41, v45
	v_add_f32_e32 v45, v41, v40
	v_pk_add_f32 v[34:35], v[34:35], v[98:99]
	v_pk_add_f32 v[40:41], v[32:33], v[96:97]
	v_mul_f32_e32 v33, v35, v35
	v_mul_f32_e32 v32, v41, v41
	v_fmac_f32_e32 v32, v40, v40
	v_fmac_f32_e32 v33, v34, v34
	v_add_f32_e32 v32, v32, v33
	v_add_f32_e32 v32, v32, v45
	ds_bpermute_b32 v33, v248, v32
	v_lshl_add_u64 v[50:51], s[16:17], 0, v[138:139]
	v_lshl_add_u64 v[50:51], v[212:213], 1, v[50:51]
	v_cvt_pk_bf16_f32 v36, v36, v37
	v_cvt_pk_bf16_f32 v37, v38, v39
	s_waitcnt lgkmcnt(0)
	v_add_f32_e32 v32, v32, v33
	ds_bpermute_b32 v33, v247, v32
	v_cvt_pk_bf16_f32 v49, v46, v47
	v_cvt_pk_bf16_f32 v45, v42, v43
	global_store_dwordx2 v[50:51], v[36:37], off offset:256
	v_cvt_pk_bf16_f32 v36, v40, v41
	v_cvt_pk_bf16_f32 v37, v34, v35
	global_store_dwordx2 v[50:51], v[48:49], off
	global_store_dwordx2 v[50:51], v[44:45], off offset:32
	global_store_dwordx2 v[50:51], v[36:37], off offset:288
	s_and_saveexec_b64 s[10:11], s[6:7]
	s_cbranch_execz .LBB0_614
	v_lshlrev_b64 v[34:35], 7, v[132:133]
	v_lshl_add_u64 v[34:35], s[18:19], 0, v[34:35]
	v_lshl_add_u64 v[34:35], s[30:31], 2, v[34:35]
	s_lshl_b32 s72, s45, 2
	v_lshl_add_u64 v[34:35], v[34:35], 0, s[72:73]
	s_waitcnt lgkmcnt(0)
	v_add_f32_e32 v32, v32, v33
	global_store_dword v[34:35], v32, off
; __device__ __forceinline__ unsigned cvt_pk_bf16(float lo, float hi) { f32x2 v = {lo, hi}; bf16x2_t b = __builtin_convertvector(v, bf16x2_t); return __builtin_bit_cast(unsigned, b); }
;     __device__ __forceinline__ void operator()(const f32x4 (&acc)[2][2][4][2], const Unit& u, int wr, int wc, int fr, int fq) const {
;     ...
;             for (int m = 0; m < 4; ++m) { const size_t off = (size_t)(row0 + ai * HALF + m * 16) * DM + col0; float ss = 0.f;
; #pragma unroll
;                 for (int bj = 0; bj < 2; ++bj)
; #pragma unroll
;                     for (int n = 0; n < 2; ++n) { const f32x4 o = bs[m][bj][n] + acc[ai][bj][m][n];
;                         u32x2 w; w.x = cvt_pk_bf16(o[0], o[1]); w.y = cvt_pk_bf16(o[2], o[3]);
;                         *(u32x2*)(h1 + off + bj * HALF + n * 16) = w;
;                         if (h2) *(u32x2*)(h2 + off + bj * HALF + n * 16) = w;
;                         ss += (o[0] * o[0] + o[1] * o[1]) + (o[2] * o[2] + o[3] * o[3]); }
;                 ss += __shfl_xor(ss, 16); ss += __shfl_xor(ss, 32);
;                 if (fq == 0) rsq[(size_t)(row0 + ai * HALF + m * 16) * 32 + u.pn * 4 + wc] = ss; } }
.LBB0_614:
	s_or_b64 exec, exec, s[10:11]
	v_pk_add_f32 v[28:29], v[28:29], v[92:93]
	v_pk_add_f32 v[30:31], v[30:31], v[94:95]
	v_cvt_pk_bf16_f32 v32, v28, v29
	v_mul_f32_e32 v29, v29, v29
	v_fmac_f32_e32 v29, v28, v28
	v_mul_f32_e32 v28, v31, v31
	v_fmac_f32_e32 v28, v30, v30
	v_pk_add_f32 v[24:25], v[24:25], v[88:89]
	v_add_f32_e32 v29, v29, v28
	v_pk_add_f32 v[26:27], v[26:27], v[90:91]
	v_cvt_pk_bf16_f32 v28, v24, v25
	v_mul_f32_e32 v25, v25, v25
	v_fmac_f32_e32 v25, v24, v24
	v_mul_f32_e32 v24, v27, v27
	v_fmac_f32_e32 v24, v26, v26
	v_add_f32_e32 v24, v25, v24
	v_pk_add_f32 v[22:23], v[22:23], v[86:87]
	v_pk_add_f32 v[20:21], v[20:21], v[84:85]
	v_add_f32_e32 v24, v24, v29
	v_mul_f32_e32 v25, v21, v21
	v_mul_f32_e32 v29, v23, v23
	v_fmac_f32_e32 v25, v20, v20
	v_fmac_f32_e32 v29, v22, v22
	v_add_f32_e32 v25, v25, v29
	v_add_f32_e32 v29, v25, v24
	v_pk_add_f32 v[18:19], v[18:19], v[82:83]
	v_pk_add_f32 v[24:25], v[16:17], v[80:81]
	v_mul_f32_e32 v17, v19, v19
	v_mul_f32_e32 v16, v25, v25
	v_fmac_f32_e32 v16, v24, v24
	v_fmac_f32_e32 v17, v18, v18
	v_add_f32_e32 v16, v16, v17
	v_add_f32_e32 v16, v16, v29
	ds_bpermute_b32 v17, v248, v16
	v_lshl_add_u64 v[34:35], s[16:17], 0, v[134:135]
	v_lshl_add_u64 v[34:35], v[212:213], 1, v[34:35]
	v_cvt_pk_bf16_f32 v20, v20, v21
	v_cvt_pk_bf16_f32 v21, v22, v23
	s_waitcnt lgkmcnt(0)
	v_add_f32_e32 v16, v16, v17
	ds_bpermute_b32 v17, v247, v16
	v_cvt_pk_bf16_f32 v33, v30, v31
	v_cvt_pk_bf16_f32 v29, v26, v27
	global_store_dwordx2 v[34:35], v[20:21], off offset:256
	v_cvt_pk_bf16_f32 v20, v24, v25
	v_cvt_pk_bf16_f32 v21, v18, v19
	global_store_dwordx2 v[34:35], v[32:33], off
	global_store_dwordx2 v[34:35], v[28:29], off offset:32
	global_store_dwordx2 v[34:35], v[20:21], off offset:288
	s_and_saveexec_b64 s[10:11], s[6:7]
	s_cbranch_execz .LBB0_616
	v_lshlrev_b64 v[18:19], 7, v[130:131]
	v_lshl_add_u64 v[18:19], s[18:19], 0, v[18:19]
	v_lshl_add_u64 v[18:19], s[30:31], 2, v[18:19]
	s_lshl_b32 s72, s45, 2
	v_lshl_add_u64 v[18:19], v[18:19], 0, s[72:73]
	s_waitcnt lgkmcnt(0)
	v_add_f32_e32 v16, v16, v17
	global_store_dword v[18:19], v16, off
.LBB0_616:
	s_or_b64 exec, exec, s[10:11]
	v_pk_add_f32 v[12:13], v[12:13], v[76:77]
	v_pk_add_f32 v[14:15], v[14:15], v[78:79]
	v_cvt_pk_bf16_f32 v18, v12, v13
	v_mul_f32_e32 v13, v13, v13
	v_fmac_f32_e32 v13, v12, v12
	v_mul_f32_e32 v12, v15, v15
	v_fmac_f32_e32 v12, v14, v14
	v_pk_add_f32 v[8:9], v[8:9], v[72:73]
	v_add_f32_e32 v13, v13, v12
	v_pk_add_f32 v[10:11], v[10:11], v[74:75]
	v_cvt_pk_bf16_f32 v12, v8, v9
	v_mul_f32_e32 v9, v9, v9
	v_fmac_f32_e32 v9, v8, v8
	v_mul_f32_e32 v8, v11, v11
	v_fmac_f32_e32 v8, v10, v10
	v_add_f32_e32 v8, v9, v8
	v_pk_add_f32 v[6:7], v[6:7], v[70:71]
	v_pk_add_f32 v[4:5], v[4:5], v[68:69]
	v_add_f32_e32 v8, v8, v13
	v_mul_f32_e32 v9, v5, v5
	v_mul_f32_e32 v13, v7, v7
	v_fmac_f32_e32 v9, v4, v4
	v_fmac_f32_e32 v13, v6, v6
	v_add_f32_e32 v9, v9, v13
	v_add_f32_e32 v13, v9, v8
	v_pk_add_f32 v[2:3], v[2:3], v[66:67]
	v_pk_add_f32 v[8:9], v[0:1], v[64:65]
	v_mul_f32_e32 v1, v3, v3
	v_mul_f32_e32 v0, v9, v9
	v_fmac_f32_e32 v0, v8, v8
	v_fmac_f32_e32 v1, v2, v2
	v_add_f32_e32 v0, v0, v1
	v_add_f32_e32 v0, v0, v13
	ds_bpermute_b32 v1, v248, v0
	v_add_u32_e32 v16, 0xb0, v214
	s_waitcnt lgkmcnt(0)
	v_ashrrev_i32_e32 v17, 31, v16
	v_lshlrev_b64 v[20:21], 12, v[16:17]
	v_lshl_add_u64 v[20:21], s[16:17], 0, v[20:21]
	v_add_f32_e32 v0, v0, v1
	ds_bpermute_b32 v1, v247, v0
	v_lshl_add_u64 v[20:21], v[212:213], 1, v[20:21]
	v_cvt_pk_bf16_f32 v4, v4, v5
	v_cvt_pk_bf16_f32 v5, v6, v7
	v_cvt_pk_bf16_f32 v19, v14, v15
	v_cvt_pk_bf16_f32 v13, v10, v11
	global_store_dwordx2 v[20:21], v[4:5], off offset:256
	v_cvt_pk_bf16_f32 v4, v8, v9
	v_cvt_pk_bf16_f32 v5, v2, v3
	global_store_dwordx2 v[20:21], v[18:19], off
	global_store_dwordx2 v[20:21], v[12:13], off offset:32
	global_store_dwordx2 v[20:21], v[4:5], off offset:288
	s_and_saveexec_b64 s[10:11], s[6:7]
	s_cbranch_execz .LBB0_618
	v_lshlrev_b64 v[2:3], 7, v[16:17]
	v_lshl_add_u64 v[2:3], s[18:19], 0, v[2:3]
	v_lshl_add_u64 v[2:3], s[30:31], 2, v[2:3]
	s_lshl_b32 s72, s45, 2
	v_lshl_add_u64 v[2:3], v[2:3], 0, s[72:73]
	s_waitcnt lgkmcnt(0)
	v_add_f32_e32 v0, v0, v1
	global_store_dword v[2:3], v0, off

; __device__ __forceinline__ unsigned xb_ld(unsigned* p)              { return __hip_atomic_load(p, __ATOMIC_RELAXED, __HIP_MEMORY_SCOPE_AGENT); }
; __device__ __forceinline__ void xcd_barrier_complete(unsigned* bar, unsigned x, unsigned& nloc, unsigned& nx) {
;     const unsigned G = gridDim.x * gridDim.y * gridDim.z;
;     unsigned sum, cnt, mine, sp = 0u;
;     for (;;) {
;         sum = 0u; cnt = 0u; mine = 0u;
; #pragma unroll
;         for (unsigned j = 0; j < 16; ++j) { const unsigned c = xb_ld(&bar[XB_XCNT(j)]); sum += c; cnt += (c > 0u) ? 1u : 0u; mine = (j == x) ? c : mine; }
;         if (sum == G) break;
;         __builtin_amdgcn_s_sleep(1);
;         if ((++sp & 255u) == 0u) { if (xb_ld(&bar[XB_TMO])) break; if (sp > XB_SPIN_CAP) { atomicAdd(&bar[XB_TMO], 1u); break; } }
;     }
;     nloc = mine > 0u ? mine : 1u; nx = cnt > 0u ? cnt : 1u;
; }
.LBB0_627:
	s_waitcnt lgkmcnt(0)
	v_mov_b64_e32 v[0:1], s[8:9]
	v_mov_b64_e32 v[2:3], s[10:11]
	global_load_dword v0, v[0:1], off sc1
	v_readlane_b32 s56, v255, 5
	global_load_dword v1, v[2:3], off sc1
	v_mov_b64_e32 v[2:3], s[12:13]
	global_load_dword v2, v[2:3], off sc1
	s_or_b64 s[54:55], s[54:55], exec
	s_or_b64 s[52:53], s[52:53], exec
	s_waitcnt vmcnt(0) lgkmcnt(0)
	v_add_u32_e32 v4, v1, v0
	v_add_u32_e32 v6, v4, v2
	v_mov_b64_e32 v[4:5], s[14:15]
	global_load_dword v3, v[4:5], off sc1
	v_mov_b64_e32 v[4:5], s[16:17]
	global_load_dword v4, v[4:5], off sc1
	s_waitcnt vmcnt(0) lgkmcnt(0)
	v_add_u32_e32 v6, v6, v3
	v_add_u32_e32 v8, v6, v4
	v_mov_b64_e32 v[6:7], s[18:19]
	global_load_dword v5, v[6:7], off sc1
	v_mov_b64_e32 v[6:7], s[20:21]
	global_load_dword v6, v[6:7], off sc1
	s_waitcnt vmcnt(0) lgkmcnt(0)
	v_add_u32_e32 v8, v8, v5
	v_add_u32_e32 v10, v8, v6
	v_mov_b64_e32 v[8:9], s[22:23]
	global_load_dword v7, v[8:9], off sc1
	v_mov_b64_e32 v[8:9], s[24:25]
	global_load_dword v8, v[8:9], off sc1
	s_waitcnt vmcnt(0) lgkmcnt(0)
	v_add_u32_e32 v10, v10, v7
	v_add_u32_e32 v12, v10, v8
	v_mov_b64_e32 v[10:11], s[26:27]
	global_load_dword v9, v[10:11], off sc1
	v_mov_b64_e32 v[10:11], s[28:29]
	global_load_dword v10, v[10:11], off sc1
	s_waitcnt vmcnt(0) lgkmcnt(0)
	v_add_u32_e32 v12, v12, v9
	v_add_u32_e32 v14, v12, v10
	v_mov_b64_e32 v[12:13], s[30:31]
	global_load_dword v11, v[12:13], off sc1
	v_mov_b64_e32 v[12:13], s[34:35]
	global_load_dword v12, v[12:13], off sc1
	s_waitcnt vmcnt(0) lgkmcnt(0)
	v_add_u32_e32 v14, v14, v11
	v_add_u32_e32 v16, v14, v12
	v_mov_b64_e32 v[14:15], s[36:37]
	global_load_dword v13, v[14:15], off sc1
	v_mov_b64_e32 v[14:15], s[44:45]
	global_load_dword v14, v[14:15], off sc1
	s_waitcnt vmcnt(0) lgkmcnt(0)
	v_add_u32_e32 v16, v16, v13
	v_add_u32_e32 v18, v16, v14
	v_mov_b64_e32 v[16:17], s[46:47]
	global_load_dword v15, v[16:17], off sc1
	s_waitcnt vmcnt(0) lgkmcnt(0)
	v_add_u32_e32 v16, v18, v15
	v_cmp_ne_u32_e32 vcc, s56, v16
	s_and_saveexec_b64 s[56:57], vcc
	s_cbranch_execz .LBB0_626
	s_and_b32 s60, s5, 0xff
	s_mov_b64 s[58:59], -1
	s_cmp_eq_u32 s60, 0
	s_mov_b64 s[62:63], -1
	s_mov_b64 s[60:61], -1
	s_sleep 1
	s_cbranch_scc1 .LBB0_630
	s_and_saveexec_b64 s[64:65], s[62:63]
	s_cbranch_execz .LBB0_625
	s_branch .LBB0_633

; __device__ __forceinline__ unsigned xb_ld(unsigned* p)              { return __hip_atomic_load(p, __ATOMIC_RELAXED, __HIP_MEMORY_SCOPE_AGENT); }
; __device__ __forceinline__ unsigned xb_add(unsigned* p, unsigned v) { return __hip_atomic_fetch_add(p, v, __ATOMIC_RELAXED, __HIP_MEMORY_SCOPE_AGENT); }
; #define XB_SPIN(cond, bar) do { unsigned _sp = 0; while (cond) { __builtin_amdgcn_s_sleep(1); \
;     if ((++_sp & 255u) == 0u) { if (xb_ld(&(bar)[XB_TMO])) break; if (_sp > XB_SPIN_CAP) { atomicAdd(&(bar)[XB_TMO], 1u); break; } } } } while (0)
; __device__ __forceinline__ void xcd_barrier(const XcdBarrier& b) {
;     ...
;     if (threadIdx.x == 0) {
;         unsigned* bar = b.bar;
;         __builtin_amdgcn_s_waitcnt(0);
;         unsigned nloc = b.st[0], nx = b.st[1];
;         if (nloc == 0u) { xcd_barrier_complete(bar, b.x, nloc, nx); b.st[0] = nloc; b.st[1] = nx; }
;         const unsigned old = xb_add(&bar[XB_XSUB(b.x)], 1u);
;         const unsigned gen = old / nloc;
;         if (old + 1u == (gen + 1u) * nloc) {
;             __builtin_amdgcn_fence(__ATOMIC_RELEASE, "agent");
;             asm volatile("s_waitcnt vmcnt(0)" ::: "memory");
;             const unsigned og = xb_add(&bar[XB_TOP], 1u);
;             const unsigned tg = og / nx;
;             if (og + 1u == (tg + 1u) * nx) xb_add(&bar[XB_TOPGEN], 1u);
;             else XB_SPIN(xb_ld(&bar[XB_TOPGEN]) == tg, bar);
;             __builtin_amdgcn_fence(__ATOMIC_ACQUIRE, "agent");
;             xb_add(&bar[XB_XGEN(b.x)], 1u);
;             asm volatile("s_waitcnt vmcnt(0)" ::: "memory");
;         } else {
;             XB_SPIN(xb_ld(&bar[XB_XGEN(b.x)]) == gen, bar);
.LBB0_637:
	s_lshl_b32 s4, s4, 8
	s_add_u32 s6, s42, s4
	s_addc_u32 s7, s43, 0
	v_mov_b32_e32 v1, s6
	v_add_co_u32_e32 v4, vcc, 0x3e301000, v1
	v_mov_b32_e32 v1, s7
	s_nop 0
	v_addc_co_u32_e32 v5, vcc, 0, v1, vcc
	flat_atomic_add v3, v[4:5], v239 offset:1024 sc0
	v_cvt_f32_u32_e32 v1, v2
	v_sub_u32_e32 v4, 0, v2
	s_add_u32 s5, s6, 0x3e300000
	s_addc_u32 s4, s7, 0
	v_rcp_iflag_f32_e32 v1, v1
	s_nop 0
	v_mul_f32_e32 v1, 0x4f7ffffe, v1
	v_cvt_u32_f32_e32 v1, v1
	v_mul_lo_u32 v4, v4, v1
	v_mul_hi_u32 v4, v1, v4
	v_add_u32_e32 v1, v1, v4
	s_waitcnt vmcnt(0) lgkmcnt(0)
	v_mul_hi_u32 v1, v3, v1
	v_mul_lo_u32 v4, v1, v2
	v_sub_u32_e32 v4, v3, v4
	v_cmp_ge_u32_e32 vcc, v4, v2
	v_add_u32_e32 v5, 1, v1
	s_nop 0
	v_cndmask_b32_e32 v1, v1, v5, vcc
	v_sub_u32_e32 v5, v4, v2
	v_cndmask_b32_e32 v4, v4, v5, vcc
	v_cmp_ge_u32_e32 vcc, v4, v2
	v_add_u32_e32 v4, 1, v1
	s_nop 0
	v_cndmask_b32_e32 v1, v1, v4, vcc
	v_add_u32_e32 v4, 1, v3
	v_mad_u64_u32 v[2:3], s[6:7], v2, v1, v[2:3]
	v_cmp_ne_u32_e32 vcc, v4, v2
	s_and_saveexec_b64 s[6:7], vcc
	s_xor_b64 s[6:7], exec, s[6:7]
	s_cbranch_execz .LBB0_650
	v_mov_b32_e32 v0, s5
	v_add_co_u32_e32 v2, vcc, 0x2000, v0
	v_mov_b32_e32 v0, s4
	s_nop 0
	v_addc_co_u32_e32 v3, vcc, 0, v0, vcc
	global_load_dword v0, v[2:3], off offset:1024 sc1
	s_add_u32 s10, s5, 0x2400
	s_addc_u32 s11, s4, 0
	s_waitcnt vmcnt(0) lgkmcnt(0)
	v_cmp_eq_u32_e32 vcc, v0, v1
	s_and_saveexec_b64 s[8:9], vcc
	s_cbranch_execz .LBB0_649
	s_add_u32 s12, s42, 0x3e300200
	s_addc_u32 s13, s43, 0
	s_mov_b32 s28, 1
	s_mov_b64 s[14:15], 0
	s_branch .LBB0_641

; __device__ __forceinline__ unsigned xb_ld(unsigned* p)              { return __hip_atomic_load(p, __ATOMIC_RELAXED, __HIP_MEMORY_SCOPE_AGENT); }
; __device__ __forceinline__ unsigned xb_add(unsigned* p, unsigned v) { return __hip_atomic_fetch_add(p, v, __ATOMIC_RELAXED, __HIP_MEMORY_SCOPE_AGENT); }
; #define XB_SPIN(cond, bar) do { unsigned _sp = 0; while (cond) { __builtin_amdgcn_s_sleep(1); \
;     if ((++_sp & 255u) == 0u) { if (xb_ld(&(bar)[XB_TMO])) break; if (_sp > XB_SPIN_CAP) { atomicAdd(&(bar)[XB_TMO], 1u); break; } } } } while (0)
; __device__ __forceinline__ void xcd_barrier(const XcdBarrier& b) {
;     ...
;         if (old + 1u == (gen + 1u) * nloc) {
;             __builtin_amdgcn_fence(__ATOMIC_RELEASE, "agent");
;             asm volatile("s_waitcnt vmcnt(0)" ::: "memory");
;             const unsigned og = xb_add(&bar[XB_TOP], 1u);
;             const unsigned tg = og / nx;
;             if (og + 1u == (tg + 1u) * nx) xb_add(&bar[XB_TOPGEN], 1u);
;             else XB_SPIN(xb_ld(&bar[XB_TOPGEN]) == tg, bar);
;             __builtin_amdgcn_fence(__ATOMIC_ACQUIRE, "agent");
;             xb_add(&bar[XB_XGEN(b.x)], 1u);
.LBB0_650:
	s_andn2_saveexec_b64 s[6:7], s[6:7]
	s_cbranch_execz .LBB0_666
	v_mov_b32_e32 v1, s42
	v_add_co_u32_e32 v2, vcc, 0x3e303000, v1
	v_mov_b32_e32 v1, s43
	buffer_wbl2 sc1
	s_waitcnt vmcnt(0)
	v_addc_co_u32_e32 v3, vcc, 0, v1, vcc
	flat_atomic_add v1, v[2:3], v239 offset:1024 sc0
	v_cvt_f32_u32_e32 v2, v0
	v_sub_u32_e32 v3, 0, v0
	s_mov_b64 s[10:11], -1
	v_rcp_iflag_f32_e32 v2, v2
	s_nop 0
	v_mul_f32_e32 v2, 0x4f7ffffe, v2
	v_cvt_u32_f32_e32 v2, v2
	v_mul_lo_u32 v3, v3, v2
	v_mul_hi_u32 v3, v2, v3
	v_add_u32_e32 v2, v2, v3
	s_waitcnt vmcnt(0) lgkmcnt(0)
	v_mul_hi_u32 v2, v1, v2
	v_mul_lo_u32 v3, v2, v0
	v_sub_u32_e32 v3, v1, v3
	v_cmp_ge_u32_e32 vcc, v3, v0
	v_add_u32_e32 v4, 1, v2
	s_nop 0
	v_cndmask_b32_e32 v2, v2, v4, vcc
	v_sub_u32_e32 v4, v3, v0
	v_cndmask_b32_e32 v3, v3, v4, vcc
	v_cmp_ge_u32_e32 vcc, v3, v0
	v_add_u32_e32 v3, 1, v2
	s_nop 0
	v_cndmask_b32_e32 v2, v2, v3, vcc
	v_add_u32_e32 v3, 1, v1
	v_mad_u64_u32 v[0:1], s[6:7], v0, v2, v[0:1]
	s_add_u32 s6, s42, 0x3e303500
	s_addc_u32 s7, s43, 0
	v_cmp_ne_u32_e32 vcc, v3, v0
	v_mov_b64_e32 v[0:1], s[6:7]
	s_and_saveexec_b64 s[8:9], vcc
	s_cbranch_execz .LBB0_663
	v_mov_b64_e32 v[0:1], s[6:7]
	global_load_dword v0, v[0:1], off sc1
	s_mov_b64 s[14:15], 0
	s_waitcnt vmcnt(0) lgkmcnt(0)
	v_cmp_eq_u32_e32 vcc, v0, v2
	s_and_saveexec_b64 s[12:13], vcc
	s_cbranch_execz .LBB0_662
	s_add_u32 s10, s42, 0x3e300200
	s_addc_u32 s11, s43, 0
	s_mov_b32 s26, 1
	s_branch .LBB0_655

; __device__ __forceinline__ int opaque_tid() { int t = threadIdx.x; asm volatile("" : "+v"(t)); return t; }
; __device__ __forceinline__ void reduce_slots(const float* slots, float* rsq) {
;     for (int row = blockIdx.x * 512 + opaque_tid(); row < M; row += gridDim.x * 512) {
;         const f32x4* s4 = (const f32x4*)(slots + (size_t)row * 32); float s = 0.f;
; #pragma unroll
;         for (int j = 0; j < 8; ++j) { const f32x4 v = s4[j]; s += (v[0] + v[1]) + (v[2] + v[3]); }
;         rsq[row] = s; }
; }
.LBB0_668:
	v_ashrrev_i32_e32 v1, 31, v0
	v_lshlrev_b64 v[2:3], 7, v[0:1]
	v_lshl_add_u64 v[10:11], s[8:9], 0, v[2:3]
	global_load_dwordx4 v[2:5], v[10:11], off
	global_load_dwordx4 v[6:9], v[10:11], off offset:16
	s_waitcnt vmcnt(0) lgkmcnt(0)
	v_mov_b32_e32 v12, v2
	v_mov_b32_e32 v13, v6
	v_mov_b32_e32 v6, v3
	v_pk_add_f32 v[2:3], v[12:13], v[6:7]
	v_mov_b32_e32 v6, v4
	v_mov_b32_e32 v7, v8
	v_mov_b32_e32 v8, v5
	v_pk_add_f32 v[4:5], v[6:7], v[8:9]
	s_nop 0
	v_pk_add_f32 v[2:3], v[2:3], v[4:5]
	s_nop 0
	v_add_f32_e32 v2, 0, v2
	v_add_f32_e32 v6, v2, v3
	global_load_dwordx4 v[2:5], v[10:11], off offset:32
	s_waitcnt vmcnt(0) lgkmcnt(0)
	v_mov_b32_e32 v8, v3
	v_mov_b32_e32 v9, v4
	v_mov_b32_e32 v3, v5
	v_pk_add_f32 v[2:3], v[8:9], v[2:3]
	s_nop 0
	v_pk_add_f32 v[8:9], v[2:3], v[2:3] op_sel:[0,1] op_sel_hi:[1,0]
	global_load_dwordx4 v[2:5], v[10:11], off offset:48
	s_waitcnt vmcnt(0) lgkmcnt(0)
	v_add_f32_e32 v12, v2, v3
	v_add_f32_e32 v14, v4, v5
	global_load_dwordx4 v[2:5], v[10:11], off offset:64
	s_waitcnt vmcnt(0) lgkmcnt(0)
	v_mov_b32_e32 v7, v2
	v_mov_b32_e32 v9, v3
	v_mov_b32_e32 v13, v4
	v_mov_b32_e32 v15, v5
	v_pk_add_f32 v[2:3], v[6:7], v[8:9]
	v_pk_add_f32 v[4:5], v[12:13], v[14:15]
	s_nop 0
	v_pk_add_f32 v[2:3], v[2:3], v[4:5]
	s_nop 0
	v_pk_add_f32 v[6:7], v[2:3], v[2:3] op_sel:[0,1] op_sel_hi:[1,0]
	global_load_dwordx4 v[2:5], v[10:11], off offset:80
	s_waitcnt vmcnt(0) lgkmcnt(0)
	v_mov_b32_e32 v8, v3
	v_mov_b32_e32 v9, v4
	v_mov_b32_e32 v3, v5
	v_pk_add_f32 v[2:3], v[8:9], v[2:3]
	s_nop 0
	v_pk_add_f32 v[8:9], v[2:3], v[2:3] op_sel:[0,1] op_sel_hi:[1,0]
	global_load_dwordx4 v[2:5], v[10:11], off offset:96
	s_waitcnt vmcnt(0) lgkmcnt(0)
	v_add_f32_e32 v12, v2, v3
	v_add_f32_e32 v14, v4, v5
	global_load_dwordx4 v[2:5], v[10:11], off offset:112
	s_waitcnt vmcnt(0) lgkmcnt(0)
	v_mov_b32_e32 v7, v2
	v_mov_b32_e32 v9, v3
	v_mov_b32_e32 v13, v4
	v_mov_b32_e32 v15, v5
	v_pk_add_f32 v[2:3], v[6:7], v[8:9]
	v_pk_add_f32 v[4:5], v[12:13], v[14:15]
	s_nop 0
	v_pk_add_f32 v[2:3], v[2:3], v[4:5]
	s_nop 0
	v_add_f32_e32 v4, v2, v3
	v_lshl_add_u64 v[2:3], v[0:1], 2, s[10:11]
	v_add_u32_e32 v0, s14, v0
	v_cmp_lt_i32_e32 vcc, s1, v0
	s_or_b64 s[12:13], vcc, s[12:13]
	global_store_dword v[2:3], v4, off
	s_andn2_b64 exec, exec, s[12:13]
	s_cbranch_execnz .LBB0_668

; __device__ __forceinline__ unsigned cvt_pk_bf16(float lo, float hi) { f32x2 v = {lo, hi}; bf16x2_t b = __builtin_convertvector(v, bf16x2_t); return __builtin_bit_cast(unsigned, b); }
; __device__ __forceinline__ float silu_(float z) { return z * sigmoid_(z); }
;     __device__ __forceinline__ void operator()(const f32x4 (&acc)[2][2][4][2], const Unit& u, int wr, int wc, int fr, int fq) const {
;         const int row0 = u.pm * BM + wr * 64 + fr;
;         float rsv[2][4];
; #pragma unroll
;         for (int ai = 0; ai < 2; ++ai)
; #pragma unroll
;             for (int m = 0; m < 4; ++m) rsv[ai][m] = row_stat(rsq, slots, row0 + ai * HALF + m * 16, fq);
; #pragma unroll
;         for (int ai = 0; ai < 2; ++ai)
; #pragma unroll
;             for (int m = 0; m < 4; ++m) { bf16_t* rowp = H + (size_t)(row0 + ai * HALF + m * 16) * DFF;
;                 const float rs = rsqrtf(rsv[ai][m] * (1.f / DM) + EPS);
; #pragma unroll
;                 for (int bj = 0; bj < 2; ++bj) { const f32x4 a = acc[ai][bj][m][0] * rs, g = acc[ai][bj][m][1] * rs;
;                     const int col = 16 * (8 * u.pn + 4 * bj + wc) + 4 * fq;
;                     u32x2 w; w.x = cvt_pk_bf16(silu_(a[0]) * g[0], silu_(a[1]) * g[1]); w.y = cvt_pk_bf16(silu_(a[2]) * g[2], silu_(a[3]) * g[3]);
;                     *(u32x2*)(rowp + col) = w; } }
;     }
.LBB0_725:
	v_lshl_add_u32 v154, s43, 8, v138
	v_ashrrev_i32_e32 v155, 31, v154
	v_lshl_add_u64 v[136:137], v[154:155], 2, s[12:13]
	global_load_dword v156, v[136:137], off
	global_load_dword v162, v[136:137], off offset:64
	global_load_dword v152, v[136:137], off offset:128
	global_load_dword v150, v[136:137], off offset:192
	global_load_dword v148, v[136:137], off offset:512
	global_load_dword v146, v[136:137], off offset:576
	global_load_dword v144, v[136:137], off offset:640
	global_load_dword v142, v[136:137], off offset:704
	v_or_b32_e32 v157, 16, v154
	v_mov_b64_e32 v[136:137], s[10:11]
	s_movk_i32 s0, 0x2c00
	v_or_b32_e32 v153, 32, v154
	v_or_b32_e32 v151, 48, v154
	v_add_u32_e32 v149, 0x80, v154
	v_add_u32_e32 v147, 0x90, v154
	v_add_u32_e32 v145, 0xa0, v154
	v_add_u32_e32 v143, 0xb0, v154
	v_mad_i64_i32 v[154:155], s[24:25], v154, s0, v[136:137]
	s_waitcnt vmcnt(0) lgkmcnt(0)
	v_fmamk_f32 v156, v156, 0x3a000000, v194
	v_cmp_gt_f32_e32 vcc, s33, v156
	v_mul_f32_e32 v158, 0x4b800000, v156
	s_nop 0
	v_cndmask_b32_e32 v156, v156, v158, vcc
	v_rsq_f32_e32 v156, v156
	s_nop 0
	v_mul_f32_e32 v158, 0x45800000, v156
	v_cndmask_b32_e32 v156, v156, v158, vcc
	v_pk_mul_f32 v[126:127], v[126:127], v[156:157] op_sel_hi:[1,0]
	v_pk_mul_f32 v[122:123], v[122:123], v[156:157] op_sel_hi:[1,0]
	v_mul_f32_e32 v159, 0xbfb8aa3b, v126
	v_exp_f32_e32 v159, v159
	v_pk_mul_f32 v[128:129], v[128:129], v[156:157] op_sel_hi:[1,0]
	v_pk_mul_f32 v[124:125], v[124:125], v[156:157] op_sel_hi:[1,0]
	v_lshl_or_b32 v158, s42, 7, v140
	v_add_f32_e32 v159, 1.0, v159
	v_rcp_f32_e32 v160, v159
	v_mul_f32_e32 v159, 0xbfb8aa3b, v127
	v_exp_f32_e32 v159, v159
	v_pk_mul_f32 v[118:119], v[118:119], v[156:157] op_sel_hi:[1,0]
	v_pk_mul_f32 v[114:115], v[114:115], v[156:157] op_sel_hi:[1,0]
	v_pk_mul_f32 v[120:121], v[120:121], v[156:157] op_sel_hi:[1,0]
	v_add_f32_e32 v159, 1.0, v159
	v_rcp_f32_e32 v161, v159
	v_ashrrev_i32_e32 v159, 31, v158
	v_pk_mul_f32 v[116:117], v[116:117], v[156:157] op_sel_hi:[1,0]
	v_pk_mul_f32 v[126:127], v[126:127], v[160:161]
	s_nop 0
	v_pk_mul_f32 v[122:123], v[122:123], v[126:127]
	s_nop 0
	v_cvt_pk_bf16_f32 v126, v122, v123
	v_mul_f32_e32 v122, 0xbfb8aa3b, v128
	v_mul_f32_e32 v123, 0xbfb8aa3b, v129
	v_exp_f32_e32 v122, v122
	v_exp_f32_e32 v123, v123
	v_add_f32_e32 v122, 1.0, v122
	v_add_f32_e32 v123, 1.0, v123
	v_rcp_f32_e32 v122, v122
	v_rcp_f32_e32 v123, v123
	s_nop 0
	v_pk_mul_f32 v[122:123], v[128:129], v[122:123]
	s_nop 0
	v_pk_mul_f32 v[122:123], v[124:125], v[122:123]
	s_nop 0
	v_cvt_pk_bf16_f32 v127, v122, v123
	v_lshlrev_b64 v[122:123], 1, v[158:159]
	v_lshl_add_u64 v[124:125], v[154:155], 0, v[122:123]
	global_store_dwordx2 v[124:125], v[126:127], off
	v_mul_f32_e32 v126, 0xbfb8aa3b, v118
	v_mul_f32_e32 v127, 0xbfb8aa3b, v119
	v_exp_f32_e32 v126, v126
	v_exp_f32_e32 v127, v127
	v_add_f32_e32 v126, 1.0, v126
	v_add_f32_e32 v127, 1.0, v127
	v_rcp_f32_e32 v126, v126
	v_rcp_f32_e32 v127, v127
	s_nop 0
	v_pk_mul_f32 v[118:119], v[118:119], v[126:127]
	s_nop 0
	v_pk_mul_f32 v[114:115], v[114:115], v[118:119]
	s_nop 0
	v_cvt_pk_bf16_f32 v114, v114, v115
	v_mul_f32_e32 v115, 0xbfb8aa3b, v120
	v_exp_f32_e32 v115, v115
	s_nop 0
	v_add_f32_e32 v115, 1.0, v115
	v_rcp_f32_e32 v118, v115
	v_mul_f32_e32 v115, 0xbfb8aa3b, v121
	v_exp_f32_e32 v115, v115
	s_nop 0
	v_add_f32_e32 v115, 1.0, v115
	v_rcp_f32_e32 v119, v115
	s_nop 0
	v_pk_mul_f32 v[118:119], v[120:121], v[118:119]
	s_nop 0
	v_pk_mul_f32 v[116:117], v[116:117], v[118:119]
	s_nop 0
	v_cvt_pk_bf16_f32 v115, v116, v117
	v_fmamk_f32 v116, v162, 0x3a000000, v194
	v_cmp_gt_f32_e32 vcc, s33, v116
	v_mul_f32_e32 v117, 0x4b800000, v116
	global_store_dwordx2 v[124:125], v[114:115], off offset:128
	v_cndmask_b32_e32 v116, v116, v117, vcc
	v_rsq_f32_e32 v116, v116
	v_mad_i64_i32 v[114:115], s[24:25], v157, s0, v[136:137]
	v_mul_f32_e32 v117, 0x45800000, v116
	v_cndmask_b32_e32 v116, v116, v117, vcc
	v_pk_mul_f32 v[108:109], v[108:109], v[116:117] op_sel_hi:[1,0]
	v_pk_mul_f32 v[110:111], v[110:111], v[116:117] op_sel_hi:[1,0]
	v_pk_mul_f32 v[106:107], v[106:107], v[116:117] op_sel_hi:[1,0]
	v_pk_mul_f32 v[104:105], v[104:105], v[116:117] op_sel_hi:[1,0]
	v_mul_f32_e32 v117, 0xbfb8aa3b, v108
	v_exp_f32_e32 v117, v117
	s_nop 0
	v_add_f32_e32 v117, 1.0, v117
	v_rcp_f32_e32 v118, v117
	v_mul_f32_e32 v117, 0xbfb8aa3b, v109
	v_exp_f32_e32 v117, v117
	s_nop 0
	v_add_f32_e32 v117, 1.0, v117
	v_rcp_f32_e32 v119, v117
	v_pk_mul_f32 v[100:101], v[100:101], v[116:117] op_sel_hi:[1,0]
	v_pk_mul_f32 v[96:97], v[96:97], v[116:117] op_sel_hi:[1,0]
	v_pk_mul_f32 v[102:103], v[102:103], v[116:117] op_sel_hi:[1,0]
	v_pk_mul_f32 v[108:109], v[108:109], v[118:119]
	v_pk_mul_f32 v[98:99], v[98:99], v[116:117] op_sel_hi:[1,0]
	v_pk_mul_f32 v[104:105], v[104:105], v[108:109]
	s_nop 0
	v_cvt_pk_bf16_f32 v104, v104, v105
	v_mul_f32_e32 v105, 0xbfb8aa3b, v110
	v_exp_f32_e32 v105, v105
	s_nop 0
	v_add_f32_e32 v105, 1.0, v105
	v_rcp_f32_e32 v108, v105
	v_mul_f32_e32 v105, 0xbfb8aa3b, v111
	v_exp_f32_e32 v105, v105
	s_nop 0
	v_add_f32_e32 v105, 1.0, v105
	v_rcp_f32_e32 v109, v105
	s_nop 0
	v_pk_mul_f32 v[108:109], v[110:111], v[108:109]
	s_nop 0
	v_pk_mul_f32 v[106:107], v[106:107], v[108:109]
	s_nop 0
	v_cvt_pk_bf16_f32 v105, v106, v107
	v_lshl_add_u64 v[106:107], v[114:115], 0, v[122:123]
	global_store_dwordx2 v[106:107], v[104:105], off
	v_mul_f32_e32 v104, 0xbfb8aa3b, v100
	v_mul_f32_e32 v105, 0xbfb8aa3b, v101
	v_exp_f32_e32 v104, v104
	v_exp_f32_e32 v105, v105
	v_add_f32_e32 v104, 1.0, v104
	v_add_f32_e32 v105, 1.0, v105
	v_rcp_f32_e32 v104, v104
	v_rcp_f32_e32 v105, v105
	s_nop 0
	v_pk_mul_f32 v[100:101], v[100:101], v[104:105]
; __device__ __forceinline__ unsigned cvt_pk_bf16(float lo, float hi) { f32x2 v = {lo, hi}; bf16x2_t b = __builtin_convertvector(v, bf16x2_t); return __builtin_bit_cast(unsigned, b); }
; __device__ __forceinline__ float silu_(float z) { return z * sigmoid_(z); }
;     __device__ __forceinline__ void operator()(const f32x4 (&acc)[2][2][4][2], const Unit& u, int wr, int wc, int fr, int fq) const {
;     ...
;         for (int ai = 0; ai < 2; ++ai)
; #pragma unroll
;             for (int m = 0; m < 4; ++m) rsv[ai][m] = row_stat(rsq, slots, row0 + ai * HALF + m * 16, fq);
; #pragma unroll
;         for (int ai = 0; ai < 2; ++ai)
; #pragma unroll
;             for (int m = 0; m < 4; ++m) { bf16_t* rowp = H + (size_t)(row0 + ai * HALF + m * 16) * DFF;
;                 const float rs = rsqrtf(rsv[ai][m] * (1.f / DM) + EPS);
; #pragma unroll
;                 for (int bj = 0; bj < 2; ++bj) { const f32x4 a = acc[ai][bj][m][0] * rs, g = acc[ai][bj][m][1] * rs;
;                     const int col = 16 * (8 * u.pn + 4 * bj + wc) + 4 * fq;
;                     u32x2 w; w.x = cvt_pk_bf16(silu_(a[0]) * g[0], silu_(a[1]) * g[1]); w.y = cvt_pk_bf16(silu_(a[2]) * g[2], silu_(a[3]) * g[3]);
;                     *(u32x2*)(rowp + col) = w; } }
;     }
	s_nop 0
	v_pk_mul_f32 v[96:97], v[96:97], v[100:101]
	s_nop 0
	v_cvt_pk_bf16_f32 v96, v96, v97
	v_mul_f32_e32 v97, 0xbfb8aa3b, v102
	v_exp_f32_e32 v97, v97
	s_nop 0
	v_add_f32_e32 v97, 1.0, v97
	v_rcp_f32_e32 v100, v97
	v_mul_f32_e32 v97, 0xbfb8aa3b, v103
	v_exp_f32_e32 v97, v97
	s_nop 0
	v_add_f32_e32 v97, 1.0, v97
	v_rcp_f32_e32 v101, v97
	s_nop 0
	v_pk_mul_f32 v[100:101], v[102:103], v[100:101]
	s_nop 0
	v_pk_mul_f32 v[98:99], v[98:99], v[100:101]
	s_nop 0
	v_cvt_pk_bf16_f32 v97, v98, v99
	v_fmamk_f32 v98, v152, 0x3a000000, v194
	v_cmp_gt_f32_e32 vcc, s33, v98
	v_mul_f32_e32 v99, 0x4b800000, v98
	global_store_dwordx2 v[106:107], v[96:97], off offset:128
	v_cndmask_b32_e32 v98, v98, v99, vcc
	v_rsq_f32_e32 v98, v98
	v_mad_i64_i32 v[96:97], s[24:25], v153, s0, v[136:137]
	v_mul_f32_e32 v99, 0x45800000, v98
	v_cndmask_b32_e32 v98, v98, v99, vcc
	v_pk_mul_f32 v[92:93], v[92:93], v[98:99] op_sel_hi:[1,0]
	v_pk_mul_f32 v[94:95], v[94:95], v[98:99] op_sel_hi:[1,0]
	v_pk_mul_f32 v[90:91], v[90:91], v[98:99] op_sel_hi:[1,0]
	v_pk_mul_f32 v[88:89], v[88:89], v[98:99] op_sel_hi:[1,0]
	v_mul_f32_e32 v99, 0xbfb8aa3b, v92
	v_exp_f32_e32 v99, v99
	s_nop 0
	v_add_f32_e32 v99, 1.0, v99
	v_rcp_f32_e32 v100, v99
	v_mul_f32_e32 v99, 0xbfb8aa3b, v93
	v_exp_f32_e32 v99, v99
	s_nop 0
	v_add_f32_e32 v99, 1.0, v99
	v_rcp_f32_e32 v101, v99
	v_pk_mul_f32 v[84:85], v[84:85], v[98:99] op_sel_hi:[1,0]
	v_pk_mul_f32 v[80:81], v[80:81], v[98:99] op_sel_hi:[1,0]
	v_pk_mul_f32 v[86:87], v[86:87], v[98:99] op_sel_hi:[1,0]
	v_pk_mul_f32 v[92:93], v[92:93], v[100:101]
	v_pk_mul_f32 v[82:83], v[82:83], v[98:99] op_sel_hi:[1,0]
	v_pk_mul_f32 v[88:89], v[88:89], v[92:93]
	s_nop 0
	v_cvt_pk_bf16_f32 v88, v88, v89
	v_mul_f32_e32 v89, 0xbfb8aa3b, v94
	v_exp_f32_e32 v89, v89
	s_nop 0
	v_add_f32_e32 v89, 1.0, v89
	v_rcp_f32_e32 v92, v89
	v_mul_f32_e32 v89, 0xbfb8aa3b, v95
	v_exp_f32_e32 v89, v89
	s_nop 0
	v_add_f32_e32 v89, 1.0, v89
	v_rcp_f32_e32 v93, v89
	s_nop 0
	v_pk_mul_f32 v[92:93], v[94:95], v[92:93]
	s_nop 0
	v_pk_mul_f32 v[90:91], v[90:91], v[92:93]
	s_nop 0
	v_cvt_pk_bf16_f32 v89, v90, v91
	v_lshl_add_u64 v[90:91], v[96:97], 0, v[122:123]
	global_store_dwordx2 v[90:91], v[88:89], off
	v_mul_f32_e32 v88, 0xbfb8aa3b, v84
	v_mul_f32_e32 v89, 0xbfb8aa3b, v85
	v_exp_f32_e32 v88, v88
	v_exp_f32_e32 v89, v89
	v_add_f32_e32 v88, 1.0, v88
	v_add_f32_e32 v89, 1.0, v89
	v_rcp_f32_e32 v88, v88
	v_rcp_f32_e32 v89, v89
	s_nop 0
	v_pk_mul_f32 v[84:85], v[84:85], v[88:89]
	s_nop 0
	v_pk_mul_f32 v[80:81], v[80:81], v[84:85]
	s_nop 0
	v_cvt_pk_bf16_f32 v80, v80, v81
	v_mul_f32_e32 v81, 0xbfb8aa3b, v86
	v_exp_f32_e32 v81, v81
	s_nop 0
	v_add_f32_e32 v81, 1.0, v81
	v_rcp_f32_e32 v84, v81
	v_mul_f32_e32 v81, 0xbfb8aa3b, v87
	v_exp_f32_e32 v81, v81
	s_nop 0
	v_add_f32_e32 v81, 1.0, v81
	v_rcp_f32_e32 v85, v81
	s_nop 0
	v_pk_mul_f32 v[84:85], v[86:87], v[84:85]
	s_nop 0
	v_pk_mul_f32 v[82:83], v[82:83], v[84:85]
	s_nop 0
	v_cvt_pk_bf16_f32 v81, v82, v83
	v_fmamk_f32 v82, v150, 0x3a000000, v194
	v_cmp_gt_f32_e32 vcc, s33, v82
	v_mul_f32_e32 v83, 0x4b800000, v82
	global_store_dwordx2 v[90:91], v[80:81], off offset:128
	v_cndmask_b32_e32 v82, v82, v83, vcc
	v_rsq_f32_e32 v82, v82
	v_mad_i64_i32 v[80:81], s[24:25], v151, s0, v[136:137]
	v_mul_f32_e32 v83, 0x45800000, v82
	v_cndmask_b32_e32 v82, v82, v83, vcc
	v_pk_mul_f32 v[76:77], v[76:77], v[82:83] op_sel_hi:[1,0]
	v_pk_mul_f32 v[78:79], v[78:79], v[82:83] op_sel_hi:[1,0]
	v_pk_mul_f32 v[74:75], v[74:75], v[82:83] op_sel_hi:[1,0]
	v_pk_mul_f32 v[72:73], v[72:73], v[82:83] op_sel_hi:[1,0]
	v_mul_f32_e32 v83, 0xbfb8aa3b, v76
	v_exp_f32_e32 v83, v83
	s_nop 0
	v_add_f32_e32 v83, 1.0, v83
	v_rcp_f32_e32 v84, v83
	v_mul_f32_e32 v83, 0xbfb8aa3b, v77
	v_exp_f32_e32 v83, v83
	s_nop 0
	v_add_f32_e32 v83, 1.0, v83
	v_rcp_f32_e32 v85, v83
	v_pk_mul_f32 v[68:69], v[68:69], v[82:83] op_sel_hi:[1,0]
	v_pk_mul_f32 v[64:65], v[64:65], v[82:83] op_sel_hi:[1,0]
	v_pk_mul_f32 v[70:71], v[70:71], v[82:83] op_sel_hi:[1,0]
	v_pk_mul_f32 v[76:77], v[76:77], v[84:85]
	v_pk_mul_f32 v[66:67], v[66:67], v[82:83] op_sel_hi:[1,0]
	v_pk_mul_f32 v[72:73], v[72:73], v[76:77]
	s_nop 0
	v_cvt_pk_bf16_f32 v72, v72, v73
	v_mul_f32_e32 v73, 0xbfb8aa3b, v78
	v_exp_f32_e32 v73, v73
	s_nop 0
	v_add_f32_e32 v73, 1.0, v73
	v_rcp_f32_e32 v76, v73
	v_mul_f32_e32 v73, 0xbfb8aa3b, v79
	v_exp_f32_e32 v73, v73
	s_nop 0
	v_add_f32_e32 v73, 1.0, v73
	v_rcp_f32_e32 v77, v73
	s_nop 0
	v_pk_mul_f32 v[76:77], v[78:79], v[76:77]
	s_nop 0
	v_pk_mul_f32 v[74:75], v[74:75], v[76:77]
	s_nop 0
	v_cvt_pk_bf16_f32 v73, v74, v75
	v_lshl_add_u64 v[74:75], v[80:81], 0, v[122:123]
	global_store_dwordx2 v[74:75], v[72:73], off
	v_mul_f32_e32 v72, 0xbfb8aa3b, v68
	v_mul_f32_e32 v73, 0xbfb8aa3b, v69
	v_exp_f32_e32 v72, v72
	v_exp_f32_e32 v73, v73
	v_add_f32_e32 v72, 1.0, v72
	v_add_f32_e32 v73, 1.0, v73
	v_rcp_f32_e32 v72, v72
	v_rcp_f32_e32 v73, v73
	s_nop 0
	v_pk_mul_f32 v[68:69], v[68:69], v[72:73]
	s_nop 0
	v_pk_mul_f32 v[64:65], v[64:65], v[68:69]
	s_nop 0
	v_cvt_pk_bf16_f32 v64, v64, v65
	v_mul_f32_e32 v65, 0xbfb8aa3b, v70
	v_exp_f32_e32 v65, v65
	s_nop 0
	v_add_f32_e32 v65, 1.0, v65
	v_rcp_f32_e32 v68, v65
	v_mul_f32_e32 v65, 0xbfb8aa3b, v71
	v_exp_f32_e32 v65, v65
	s_nop 0
	v_add_f32_e32 v65, 1.0, v65
	v_rcp_f32_e32 v69, v65
	s_nop 0
	v_pk_mul_f32 v[68:69], v[70:71], v[68:69]
	s_nop 0
	v_pk_mul_f32 v[66:67], v[66:67], v[68:69]
	s_nop 0
	v_cvt_pk_bf16_f32 v65, v66, v67
	v_fmamk_f32 v66, v148, 0x3a000000, v194
	v_cmp_gt_f32_e32 vcc, s33, v66
	v_mul_f32_e32 v67, 0x4b800000, v66
	global_store_dwordx2 v[74:75], v[64:65], off offset:128
	v_cndmask_b32_e32 v66, v66, v67, vcc
	v_rsq_f32_e32 v66, v66
; __device__ __forceinline__ unsigned cvt_pk_bf16(float lo, float hi) { f32x2 v = {lo, hi}; bf16x2_t b = __builtin_convertvector(v, bf16x2_t); return __builtin_bit_cast(unsigned, b); }
; __device__ __forceinline__ float silu_(float z) { return z * sigmoid_(z); }
;     __device__ __forceinline__ void operator()(const f32x4 (&acc)[2][2][4][2], const Unit& u, int wr, int wc, int fr, int fq) const {
;     ...
;         for (int ai = 0; ai < 2; ++ai)
; #pragma unroll
;             for (int m = 0; m < 4; ++m) rsv[ai][m] = row_stat(rsq, slots, row0 + ai * HALF + m * 16, fq);
; #pragma unroll
;         for (int ai = 0; ai < 2; ++ai)
; #pragma unroll
;             for (int m = 0; m < 4; ++m) { bf16_t* rowp = H + (size_t)(row0 + ai * HALF + m * 16) * DFF;
;                 const float rs = rsqrtf(rsv[ai][m] * (1.f / DM) + EPS);
; #pragma unroll
;                 for (int bj = 0; bj < 2; ++bj) { const f32x4 a = acc[ai][bj][m][0] * rs, g = acc[ai][bj][m][1] * rs;
;                     const int col = 16 * (8 * u.pn + 4 * bj + wc) + 4 * fq;
;                     u32x2 w; w.x = cvt_pk_bf16(silu_(a[0]) * g[0], silu_(a[1]) * g[1]); w.y = cvt_pk_bf16(silu_(a[2]) * g[2], silu_(a[3]) * g[3]);
;                     *(u32x2*)(rowp + col) = w; } }
;     }
	v_mad_i64_i32 v[64:65], s[24:25], v149, s0, v[136:137]
	v_mul_f32_e32 v67, 0x45800000, v66
	v_cndmask_b32_e32 v66, v66, v67, vcc
	v_pk_mul_f32 v[60:61], v[60:61], v[66:67] op_sel_hi:[1,0]
	v_pk_mul_f32 v[62:63], v[62:63], v[66:67] op_sel_hi:[1,0]
	v_pk_mul_f32 v[58:59], v[58:59], v[66:67] op_sel_hi:[1,0]
	v_pk_mul_f32 v[56:57], v[56:57], v[66:67] op_sel_hi:[1,0]
	v_mul_f32_e32 v67, 0xbfb8aa3b, v60
	v_exp_f32_e32 v67, v67
	s_nop 0
	v_add_f32_e32 v67, 1.0, v67
	v_rcp_f32_e32 v68, v67
	v_mul_f32_e32 v67, 0xbfb8aa3b, v61
	v_exp_f32_e32 v67, v67
	s_nop 0
	v_add_f32_e32 v67, 1.0, v67
	v_rcp_f32_e32 v69, v67
	v_pk_mul_f32 v[52:53], v[52:53], v[66:67] op_sel_hi:[1,0]
	v_pk_mul_f32 v[48:49], v[48:49], v[66:67] op_sel_hi:[1,0]
	v_pk_mul_f32 v[54:55], v[54:55], v[66:67] op_sel_hi:[1,0]
	v_pk_mul_f32 v[60:61], v[60:61], v[68:69]
	v_pk_mul_f32 v[50:51], v[50:51], v[66:67] op_sel_hi:[1,0]
	v_pk_mul_f32 v[56:57], v[56:57], v[60:61]
	s_nop 0
	v_cvt_pk_bf16_f32 v56, v56, v57
	v_mul_f32_e32 v57, 0xbfb8aa3b, v62
	v_exp_f32_e32 v57, v57
	s_nop 0
	v_add_f32_e32 v57, 1.0, v57
	v_rcp_f32_e32 v60, v57
	v_mul_f32_e32 v57, 0xbfb8aa3b, v63
	v_exp_f32_e32 v57, v57
	s_nop 0
	v_add_f32_e32 v57, 1.0, v57
	v_rcp_f32_e32 v61, v57
	s_nop 0
	v_pk_mul_f32 v[60:61], v[62:63], v[60:61]
	s_nop 0
	v_pk_mul_f32 v[58:59], v[58:59], v[60:61]
	s_nop 0
	v_cvt_pk_bf16_f32 v57, v58, v59
	v_lshl_add_u64 v[58:59], v[64:65], 0, v[122:123]
	global_store_dwordx2 v[58:59], v[56:57], off
	v_mul_f32_e32 v56, 0xbfb8aa3b, v52
	v_mul_f32_e32 v57, 0xbfb8aa3b, v53
	v_exp_f32_e32 v56, v56
	v_exp_f32_e32 v57, v57
	v_add_f32_e32 v56, 1.0, v56
	v_add_f32_e32 v57, 1.0, v57
	v_rcp_f32_e32 v56, v56
	v_rcp_f32_e32 v57, v57
	s_nop 0
	v_pk_mul_f32 v[52:53], v[52:53], v[56:57]
	s_nop 0
	v_pk_mul_f32 v[48:49], v[48:49], v[52:53]
	s_nop 0
	v_cvt_pk_bf16_f32 v48, v48, v49
	v_mul_f32_e32 v49, 0xbfb8aa3b, v54
	v_exp_f32_e32 v49, v49
	s_nop 0
	v_add_f32_e32 v49, 1.0, v49
	v_rcp_f32_e32 v52, v49
	v_mul_f32_e32 v49, 0xbfb8aa3b, v55
	v_exp_f32_e32 v49, v49
	s_nop 0
	v_add_f32_e32 v49, 1.0, v49
	v_rcp_f32_e32 v53, v49
	s_nop 0
	v_pk_mul_f32 v[52:53], v[54:55], v[52:53]
	s_nop 0
	v_pk_mul_f32 v[50:51], v[50:51], v[52:53]
	s_nop 0
	v_cvt_pk_bf16_f32 v49, v50, v51
	v_fmamk_f32 v50, v146, 0x3a000000, v194
	v_cmp_gt_f32_e32 vcc, s33, v50
	v_mul_f32_e32 v51, 0x4b800000, v50
	global_store_dwordx2 v[58:59], v[48:49], off offset:128
	v_cndmask_b32_e32 v50, v50, v51, vcc
	v_rsq_f32_e32 v50, v50
	v_mad_i64_i32 v[48:49], s[24:25], v147, s0, v[136:137]
	v_mul_f32_e32 v51, 0x45800000, v50
	v_cndmask_b32_e32 v50, v50, v51, vcc
	v_pk_mul_f32 v[44:45], v[44:45], v[50:51] op_sel_hi:[1,0]
	v_pk_mul_f32 v[46:47], v[46:47], v[50:51] op_sel_hi:[1,0]
	v_pk_mul_f32 v[42:43], v[42:43], v[50:51] op_sel_hi:[1,0]
	v_pk_mul_f32 v[40:41], v[40:41], v[50:51] op_sel_hi:[1,0]
	v_mul_f32_e32 v51, 0xbfb8aa3b, v44
	v_exp_f32_e32 v51, v51
	s_nop 0
	v_add_f32_e32 v51, 1.0, v51
	v_rcp_f32_e32 v52, v51
	v_mul_f32_e32 v51, 0xbfb8aa3b, v45
	v_exp_f32_e32 v51, v51
	s_nop 0
	v_add_f32_e32 v51, 1.0, v51
	v_rcp_f32_e32 v53, v51
	v_pk_mul_f32 v[36:37], v[36:37], v[50:51] op_sel_hi:[1,0]
	v_pk_mul_f32 v[32:33], v[32:33], v[50:51] op_sel_hi:[1,0]
	v_pk_mul_f32 v[38:39], v[38:39], v[50:51] op_sel_hi:[1,0]
	v_pk_mul_f32 v[44:45], v[44:45], v[52:53]
	v_pk_mul_f32 v[34:35], v[34:35], v[50:51] op_sel_hi:[1,0]
	v_pk_mul_f32 v[40:41], v[40:41], v[44:45]
	s_nop 0
	v_cvt_pk_bf16_f32 v40, v40, v41
	v_mul_f32_e32 v41, 0xbfb8aa3b, v46
	v_exp_f32_e32 v41, v41
	s_nop 0
	v_add_f32_e32 v41, 1.0, v41
	v_rcp_f32_e32 v44, v41
	v_mul_f32_e32 v41, 0xbfb8aa3b, v47
	v_exp_f32_e32 v41, v41
	s_nop 0
	v_add_f32_e32 v41, 1.0, v41
	v_rcp_f32_e32 v45, v41
	s_nop 0
	v_pk_mul_f32 v[44:45], v[46:47], v[44:45]
	s_nop 0
	v_pk_mul_f32 v[42:43], v[42:43], v[44:45]
	s_nop 0
	v_cvt_pk_bf16_f32 v41, v42, v43
	v_lshl_add_u64 v[42:43], v[48:49], 0, v[122:123]
	global_store_dwordx2 v[42:43], v[40:41], off
	v_mul_f32_e32 v40, 0xbfb8aa3b, v36
	v_mul_f32_e32 v41, 0xbfb8aa3b, v37
	v_exp_f32_e32 v40, v40
	v_exp_f32_e32 v41, v41
	v_add_f32_e32 v40, 1.0, v40
	v_add_f32_e32 v41, 1.0, v41
	v_rcp_f32_e32 v40, v40
	v_rcp_f32_e32 v41, v41
	s_nop 0
	v_pk_mul_f32 v[36:37], v[36:37], v[40:41]
	s_nop 0
	v_pk_mul_f32 v[32:33], v[32:33], v[36:37]
	s_nop 0
	v_cvt_pk_bf16_f32 v32, v32, v33
	v_mul_f32_e32 v33, 0xbfb8aa3b, v38
	v_exp_f32_e32 v33, v33
	s_nop 0
	v_add_f32_e32 v33, 1.0, v33
	v_rcp_f32_e32 v36, v33
	v_mul_f32_e32 v33, 0xbfb8aa3b, v39
	v_exp_f32_e32 v33, v33
	s_nop 0
	v_add_f32_e32 v33, 1.0, v33
	v_rcp_f32_e32 v37, v33
	s_nop 0
	v_pk_mul_f32 v[36:37], v[38:39], v[36:37]
	s_nop 0
	v_pk_mul_f32 v[34:35], v[34:35], v[36:37]
	s_nop 0
	v_cvt_pk_bf16_f32 v33, v34, v35
	v_fmamk_f32 v34, v144, 0x3a000000, v194
	v_cmp_gt_f32_e32 vcc, s33, v34
	v_mul_f32_e32 v35, 0x4b800000, v34
	global_store_dwordx2 v[42:43], v[32:33], off offset:128
; __device__ __forceinline__ unsigned cvt_pk_bf16(float lo, float hi) { f32x2 v = {lo, hi}; bf16x2_t b = __builtin_convertvector(v, bf16x2_t); return __builtin_bit_cast(unsigned, b); }
; __device__ __forceinline__ float silu_(float z) { return z * sigmoid_(z); }
; #define PG8_BAR __builtin_amdgcn_s_barrier()
; template <class Epi, class Sched, bool ALIGN_EPI = false, bool SP2 = false>
; __device__ __forceinline__ void gemm_phase(PG8_LAS unsigned char* lds, const Gemm g, const Sched& S, const Epi& E) {
;     ...
;         if constexpr (!Epi::AFTER_DRAIN) { E(acc, cur, wr, wc, fr, fq); S.done(cur); }
;         if (!has_next) break;
; #pragma unroll
;         for (int a = 0; a < 2; ++a)
; #pragma unroll
;             for (int b = 0; b < 2; ++b)
; #pragma unroll
;                 for (int m = 0; m < 4; ++m)
; #pragma unroll
;                     for (int n = 0; n < 2; ++n) acc[a][b][m][n] = (f32x4){0.f, 0.f, 0.f, 0.f};
;         cur = nxt; cA = nA; cB = nB; ++ui;
;         if constexpr (ALIGN_EPI) { if (wr == 1) PG8_BAR; }
;     __device__ __forceinline__ void operator()(const f32x4 (&acc)[2][2][4][2], const Unit& u, int wr, int wc, int fr, int fq) const {
;     ...
;         for (int ai = 0; ai < 2; ++ai)
; #pragma unroll
;             for (int m = 0; m < 4; ++m) rsv[ai][m] = row_stat(rsq, slots, row0 + ai * HALF + m * 16, fq);
; #pragma unroll
;         for (int ai = 0; ai < 2; ++ai)
; #pragma unroll
;             for (int m = 0; m < 4; ++m) { bf16_t* rowp = H + (size_t)(row0 + ai * HALF + m * 16) * DFF;
;                 const float rs = rsqrtf(rsv[ai][m] * (1.f / DM) + EPS);
; #pragma unroll
;                 for (int bj = 0; bj < 2; ++bj) { const f32x4 a = acc[ai][bj][m][0] * rs, g = acc[ai][bj][m][1] * rs;
;                     const int col = 16 * (8 * u.pn + 4 * bj + wc) + 4 * fq;
;                     u32x2 w; w.x = cvt_pk_bf16(silu_(a[0]) * g[0], silu_(a[1]) * g[1]); w.y = cvt_pk_bf16(silu_(a[2]) * g[2], silu_(a[3]) * g[3]);
;                     *(u32x2*)(rowp + col) = w; } }
;     }
	v_cndmask_b32_e32 v34, v34, v35, vcc
	v_rsq_f32_e32 v34, v34
	v_mad_i64_i32 v[32:33], s[24:25], v145, s0, v[136:137]
	v_mul_f32_e32 v35, 0x45800000, v34
	v_cndmask_b32_e32 v34, v34, v35, vcc
	v_pk_mul_f32 v[28:29], v[28:29], v[34:35] op_sel_hi:[1,0]
	v_pk_mul_f32 v[30:31], v[30:31], v[34:35] op_sel_hi:[1,0]
	v_pk_mul_f32 v[26:27], v[26:27], v[34:35] op_sel_hi:[1,0]
	v_pk_mul_f32 v[24:25], v[24:25], v[34:35] op_sel_hi:[1,0]
	v_mul_f32_e32 v35, 0xbfb8aa3b, v28
	v_exp_f32_e32 v35, v35
	s_nop 0
	v_add_f32_e32 v35, 1.0, v35
	v_rcp_f32_e32 v36, v35
	v_mul_f32_e32 v35, 0xbfb8aa3b, v29
	v_exp_f32_e32 v35, v35
	s_nop 0
	v_add_f32_e32 v35, 1.0, v35
	v_rcp_f32_e32 v37, v35
	v_pk_mul_f32 v[20:21], v[20:21], v[34:35] op_sel_hi:[1,0]
	v_pk_mul_f32 v[16:17], v[16:17], v[34:35] op_sel_hi:[1,0]
	v_pk_mul_f32 v[22:23], v[22:23], v[34:35] op_sel_hi:[1,0]
	v_pk_mul_f32 v[28:29], v[28:29], v[36:37]
	v_pk_mul_f32 v[18:19], v[18:19], v[34:35] op_sel_hi:[1,0]
	v_pk_mul_f32 v[24:25], v[24:25], v[28:29]
	s_nop 0
	v_cvt_pk_bf16_f32 v24, v24, v25
	v_mul_f32_e32 v25, 0xbfb8aa3b, v30
	v_exp_f32_e32 v25, v25
	s_nop 0
	v_add_f32_e32 v25, 1.0, v25
	v_rcp_f32_e32 v28, v25
	v_mul_f32_e32 v25, 0xbfb8aa3b, v31
	v_exp_f32_e32 v25, v25
	s_nop 0
	v_add_f32_e32 v25, 1.0, v25
	v_rcp_f32_e32 v29, v25
	s_nop 0
	v_pk_mul_f32 v[28:29], v[30:31], v[28:29]
	s_nop 0
	v_pk_mul_f32 v[26:27], v[26:27], v[28:29]
	s_nop 0
	v_cvt_pk_bf16_f32 v25, v26, v27
	v_lshl_add_u64 v[26:27], v[32:33], 0, v[122:123]
	global_store_dwordx2 v[26:27], v[24:25], off
	v_mul_f32_e32 v24, 0xbfb8aa3b, v20
	v_mul_f32_e32 v25, 0xbfb8aa3b, v21
	v_exp_f32_e32 v24, v24
	v_exp_f32_e32 v25, v25
	v_add_f32_e32 v24, 1.0, v24
	v_add_f32_e32 v25, 1.0, v25
	v_rcp_f32_e32 v24, v24
	v_rcp_f32_e32 v25, v25
	s_nop 0
	v_pk_mul_f32 v[20:21], v[20:21], v[24:25]
	s_nop 0
	v_pk_mul_f32 v[16:17], v[16:17], v[20:21]
	s_nop 0
	v_cvt_pk_bf16_f32 v16, v16, v17
	v_mul_f32_e32 v17, 0xbfb8aa3b, v22
	v_exp_f32_e32 v17, v17
	s_nop 0
	v_add_f32_e32 v17, 1.0, v17
	v_rcp_f32_e32 v20, v17
	v_mul_f32_e32 v17, 0xbfb8aa3b, v23
	v_exp_f32_e32 v17, v17
	s_nop 0
	v_add_f32_e32 v17, 1.0, v17
	v_rcp_f32_e32 v21, v17
	s_nop 0
	v_pk_mul_f32 v[20:21], v[22:23], v[20:21]
	s_nop 0
	v_pk_mul_f32 v[18:19], v[18:19], v[20:21]
	s_nop 0
	v_cvt_pk_bf16_f32 v17, v18, v19
	v_fmamk_f32 v18, v142, 0x3a000000, v194
	v_cmp_gt_f32_e32 vcc, s33, v18
	v_mul_f32_e32 v19, 0x4b800000, v18
	global_store_dwordx2 v[26:27], v[16:17], off offset:128
	v_cndmask_b32_e32 v18, v18, v19, vcc
	v_rsq_f32_e32 v18, v18
	v_mad_i64_i32 v[16:17], s[24:25], v143, s0, v[136:137]
	s_mov_b64 s[24:25], -1
	v_mul_f32_e32 v19, 0x45800000, v18
	v_cndmask_b32_e32 v18, v18, v19, vcc
	v_pk_mul_f32 v[12:13], v[12:13], v[18:19] op_sel_hi:[1,0]
	v_pk_mul_f32 v[14:15], v[14:15], v[18:19] op_sel_hi:[1,0]
	v_pk_mul_f32 v[10:11], v[10:11], v[18:19] op_sel_hi:[1,0]
	v_pk_mul_f32 v[8:9], v[8:9], v[18:19] op_sel_hi:[1,0]
	v_mul_f32_e32 v19, 0xbfb8aa3b, v12
	v_exp_f32_e32 v19, v19
	s_andn2_b64 vcc, exec, s[6:7]
	v_add_f32_e32 v19, 1.0, v19
	v_rcp_f32_e32 v20, v19
	v_mul_f32_e32 v19, 0xbfb8aa3b, v13
	v_exp_f32_e32 v19, v19
	s_nop 0
	v_add_f32_e32 v19, 1.0, v19
	v_rcp_f32_e32 v21, v19
	v_pk_mul_f32 v[4:5], v[4:5], v[18:19] op_sel_hi:[1,0]
	v_pk_mul_f32 v[0:1], v[0:1], v[18:19] op_sel_hi:[1,0]
	v_pk_mul_f32 v[6:7], v[6:7], v[18:19] op_sel_hi:[1,0]
	v_pk_mul_f32 v[12:13], v[12:13], v[20:21]
	v_pk_mul_f32 v[2:3], v[2:3], v[18:19] op_sel_hi:[1,0]
	v_pk_mul_f32 v[8:9], v[8:9], v[12:13]
	s_nop 0
	v_cvt_pk_bf16_f32 v8, v8, v9
	v_mul_f32_e32 v9, 0xbfb8aa3b, v14
	v_exp_f32_e32 v9, v9
	s_nop 0
	v_add_f32_e32 v9, 1.0, v9
	v_rcp_f32_e32 v12, v9
	v_mul_f32_e32 v9, 0xbfb8aa3b, v15
	v_exp_f32_e32 v9, v9
	s_nop 0
	v_add_f32_e32 v9, 1.0, v9
	v_rcp_f32_e32 v13, v9
	s_nop 0
	v_pk_mul_f32 v[12:13], v[14:15], v[12:13]
	s_nop 0
	v_pk_mul_f32 v[10:11], v[10:11], v[12:13]
	s_nop 0
	v_cvt_pk_bf16_f32 v9, v10, v11
	v_lshl_add_u64 v[10:11], v[16:17], 0, v[122:123]
	global_store_dwordx2 v[10:11], v[8:9], off
	v_mul_f32_e32 v8, 0xbfb8aa3b, v4
	v_mul_f32_e32 v9, 0xbfb8aa3b, v5
	v_exp_f32_e32 v8, v8
	v_exp_f32_e32 v9, v9
	v_add_f32_e32 v8, 1.0, v8
	v_add_f32_e32 v9, 1.0, v9
	v_rcp_f32_e32 v8, v8
	v_rcp_f32_e32 v9, v9
	s_nop 0
	v_pk_mul_f32 v[4:5], v[4:5], v[8:9]
	s_nop 0
	v_pk_mul_f32 v[0:1], v[0:1], v[4:5]
	s_nop 0
	v_cvt_pk_bf16_f32 v0, v0, v1
	v_mul_f32_e32 v1, 0xbfb8aa3b, v6
	v_exp_f32_e32 v1, v1
	s_nop 0
	v_add_f32_e32 v1, 1.0, v1
	v_rcp_f32_e32 v4, v1
	v_mul_f32_e32 v1, 0xbfb8aa3b, v7
	v_exp_f32_e32 v1, v1
	s_nop 0
	v_add_f32_e32 v1, 1.0, v1
	v_rcp_f32_e32 v5, v1
	s_nop 0
	v_pk_mul_f32 v[4:5], v[6:7], v[4:5]
	s_nop 0
	v_pk_mul_f32 v[2:3], v[2:3], v[4:5]
	s_nop 0
	v_cvt_pk_bf16_f32 v1, v2, v3
	global_store_dwordx2 v[10:11], v[0:1], off offset:128
	s_cbranch_vccnz .LBB0_718
	s_andn2_b64 vcc, exec, s[8:9]
	s_cbranch_vccnz .LBB0_717
	s_barrier
	s_branch .LBB0_717

; __device__ __forceinline__ unsigned cvt_pk_bf16(float lo, float hi) { f32x2 v = {lo, hi}; bf16x2_t b = __builtin_convertvector(v, bf16x2_t); return __builtin_bit_cast(unsigned, b); }
;     __device__ __forceinline__ void operator()(const f32x4 (&acc)[2][2][4][2], const Unit& u, int wr, int wc, int fr, int fq) const {
;     ...
;                 u32x2 bw[4][2][2];
; #pragma unroll
;                 for (int m = 0; m < 4; ++m) { const size_t off = (size_t)(row0 + ai * HALF + m * 16) * DM + col0;
; #pragma unroll
;                     for (int bj = 0; bj < 2; ++bj)
; #pragma unroll
;                         for (int n = 0; n < 2; ++n) bw[m][bj][n] = *(const u32x2*)((const bf16_t*)base + off + bj * HALF + n * 16); }
; #pragma unroll
;                 for (int m = 0; m < 4; ++m)
; #pragma unroll
;                     for (int bj = 0; bj < 2; ++bj)
; #pragma unroll
;                         for (int n = 0; n < 2; ++n) { const u32x2 w = bw[m][bj][n];
;                             bs[m][bj][n] = (f32x4){__uint_as_float(w.x << 16), __uint_as_float(w.x & 0xffff0000u), __uint_as_float(w.y << 16), __uint_as_float(w.y & 0xffff0000u)}; }
;             }
; #pragma unroll
;             for (int m = 0; m < 4; ++m) { const size_t off = (size_t)(row0 + ai * HALF + m * 16) * DM + col0; float ss = 0.f;
; #pragma unroll
;                 for (int bj = 0; bj < 2; ++bj)
; #pragma unroll
;                     for (int n = 0; n < 2; ++n) { const f32x4 o = bs[m][bj][n] + acc[ai][bj][m][n];
;                         u32x2 w; w.x = cvt_pk_bf16(o[0], o[1]); w.y = cvt_pk_bf16(o[2], o[3]);
;                         *(u32x2*)(h1 + off + bj * HALF + n * 16) = w;
;                         if (h2) *(u32x2*)(h2 + off + bj * HALF + n * 16) = w;
;                         ss += (o[0] * o[0] + o[1] * o[1]) + (o[2] * o[2] + o[3] * o[3]); }
;                 ss += __shfl_xor(ss, 16); ss += __shfl_xor(ss, 32);
;                 if (fq == 0) rsq[(size_t)(row0 + ai * HALF + m * 16) * 32 + u.pn * 4 + wc] = ss; } }
.LBB0_795:
	v_and_b32_e32 v140, 64, v237
	v_xor_b32_e32 v139, 16, v237
	v_add_u32_e32 v140, 64, v140
	v_cmp_lt_i32_e32 vcc, v139, v140
	v_lshl_or_b32 v136, s47, 8, v208
	v_lshl_add_u32 v138, s48, 8, v206
	v_cndmask_b32_e32 v139, v237, v139, vcc
	v_lshlrev_b32_e32 v211, 2, v139
	v_xor_b32_e32 v139, 32, v237
	v_cmp_lt_i32_e32 vcc, v139, v140
	v_ashrrev_i32_e32 v137, 31, v136
	v_lshlrev_b64 v[186:187], 1, v[136:137]
	v_cndmask_b32_e32 v139, v237, v139, vcc
	v_lshlrev_b32_e32 v210, 2, v139
	v_ashrrev_i32_e32 v139, 31, v138
	v_lshl_add_u64 v[140:141], s[16:17], 0, v[186:187]
	v_lshlrev_b64 v[188:189], 12, v[138:139]
	v_lshl_add_u64 v[142:143], v[140:141], 0, v[188:189]
	global_load_dwordx2 v[178:179], v[142:143], off
	global_load_dwordx2 v[180:181], v[142:143], off offset:32
	global_load_dwordx2 v[184:185], v[142:143], off offset:256
	global_load_dwordx2 v[196:197], v[142:143], off offset:288
	v_or_b32_e32 v148, 16, v138
	v_ashrrev_i32_e32 v149, 31, v148
	v_or_b32_e32 v144, 32, v138
	v_ashrrev_i32_e32 v145, 31, v144
	v_lshlrev_b64 v[168:169], 12, v[148:149]
	v_lshl_add_u64 v[142:143], v[140:141], 0, v[168:169]
	v_lshlrev_b64 v[150:151], 12, v[144:145]
	global_load_dwordx2 v[176:177], v[142:143], off
	global_load_dwordx2 v[174:175], v[142:143], off offset:32
	global_load_dwordx2 v[172:173], v[142:143], off offset:256
	global_load_dwordx2 v[170:171], v[142:143], off offset:288
	v_lshl_add_u64 v[142:143], v[140:141], 0, v[150:151]
	global_load_dwordx2 v[166:167], v[142:143], off
	global_load_dwordx2 v[164:165], v[142:143], off offset:32
	global_load_dwordx2 v[162:163], v[142:143], off offset:256
	global_load_dwordx2 v[158:159], v[142:143], off offset:288
	v_or_b32_e32 v142, 48, v138
	v_ashrrev_i32_e32 v143, 31, v142
	v_lshlrev_b64 v[146:147], 12, v[142:143]
	v_lshl_add_u64 v[152:153], v[140:141], 0, v[146:147]
	global_load_dwordx2 v[160:161], v[152:153], off
	global_load_dwordx2 v[156:157], v[152:153], off offset:32
	global_load_dwordx2 v[154:155], v[152:153], off offset:256
	s_nop 0
	global_load_dwordx2 v[152:153], v[152:153], off offset:288
	s_lshl_b32 s22, s47, 2
	s_ashr_i32 s23, s22, 31
	s_waitcnt vmcnt(0) lgkmcnt(0)
	v_lshlrev_b32_e32 v202, 16, v179
	v_and_b32_e32 v203, 0xffff0000, v179
	v_lshlrev_b32_e32 v198, 16, v178
	v_and_b32_e32 v199, 0xffff0000, v178
	v_lshlrev_b32_e32 v190, 16, v180
	v_and_b32_e32 v191, 0xffff0000, v180
	v_pk_add_f32 v[128:129], v[128:129], v[202:203]
	v_lshlrev_b32_e32 v192, 16, v181
	v_and_b32_e32 v193, 0xffff0000, v181
	v_lshlrev_b32_e32 v178, 16, v196
	v_and_b32_e32 v179, 0xffff0000, v196
	v_lshlrev_b32_e32 v180, 16, v197
	v_and_b32_e32 v181, 0xffff0000, v197
	v_pk_add_f32 v[196:197], v[126:127], v[198:199]
	v_cvt_pk_bf16_f32 v199, v128, v129
	v_mul_f32_e32 v129, v129, v129
	v_pk_add_f32 v[122:123], v[122:123], v[190:191]
	v_lshl_add_u64 v[126:127], s[10:11], 0, v[188:189]
	v_fmac_f32_e32 v129, v128, v128
	v_pk_add_f32 v[124:125], v[124:125], v[192:193]
	v_cvt_pk_bf16_f32 v128, v122, v123
	v_mul_f32_e32 v123, v123, v123
	v_lshl_add_u64 v[126:127], v[126:127], 0, v[186:187]
	v_mul_f32_e32 v186, v197, v197
	v_fmac_f32_e32 v123, v122, v122
	v_mul_f32_e32 v122, v125, v125
	v_lshlrev_b32_e32 v182, 16, v184
	v_and_b32_e32 v183, 0xffff0000, v184
	v_fmac_f32_e32 v186, v196, v196
	v_fmac_f32_e32 v122, v124, v124
	v_lshlrev_b32_e32 v184, 16, v185
	v_and_b32_e32 v185, 0xffff0000, v185
	v_add_f32_e32 v186, v186, v129
	v_add_f32_e32 v122, v123, v122
	v_pk_add_f32 v[118:119], v[118:119], v[182:183]
	v_cvt_pk_bf16_f32 v129, v124, v125
	v_add_f32_e32 v124, v186, v122
	v_pk_add_f32 v[120:121], v[120:121], v[184:185]
	v_cvt_pk_bf16_f32 v122, v118, v119
	v_mul_f32_e32 v119, v119, v119
	v_fmac_f32_e32 v119, v118, v118
	v_mul_f32_e32 v118, v121, v121
	v_fmac_f32_e32 v118, v120, v120
	v_add_f32_e32 v118, v119, v118
	v_pk_add_f32 v[114:115], v[114:115], v[178:179]
	v_cvt_pk_bf16_f32 v123, v120, v121
	v_add_f32_e32 v120, v124, v118
	v_pk_add_f32 v[116:117], v[116:117], v[180:181]
	v_cvt_pk_bf16_f32 v118, v114, v115
	v_mul_f32_e32 v115, v115, v115
	v_fmac_f32_e32 v115, v114, v114
	v_mul_f32_e32 v114, v117, v117
	v_fmac_f32_e32 v114, v116, v116
	v_add_f32_e32 v114, v115, v114
	v_add_f32_e32 v114, v120, v114
	ds_bpermute_b32 v115, v211, v114
	v_cvt_pk_bf16_f32 v198, v196, v197
	v_cvt_pk_bf16_f32 v119, v116, v117
	global_store_dwordx2 v[126:127], v[198:199], off
	global_store_dwordx2 v[126:127], v[128:129], off offset:32
	s_waitcnt lgkmcnt(0)
	v_add_f32_e32 v114, v114, v115
	ds_bpermute_b32 v115, v210, v114
	global_store_dwordx2 v[126:127], v[122:123], off offset:256
	global_store_dwordx2 v[126:127], v[118:119], off offset:288
	s_and_saveexec_b64 s[24:25], s[4:5]
	s_cbranch_execz .LBB0_797
	v_lshlrev_b64 v[116:117], 7, v[138:139]
	v_lshl_add_u64 v[116:117], s[14:15], 0, v[116:117]
	v_lshl_add_u64 v[116:117], s[22:23], 2, v[116:117]
	s_lshl_b32 s72, s41, 2
	v_lshl_add_u64 v[116:117], v[116:117], 0, s[72:73]
	s_waitcnt lgkmcnt(0)
	v_add_f32_e32 v114, v114, v115
	global_store_dword v[116:117], v114, off
; __device__ __forceinline__ unsigned cvt_pk_bf16(float lo, float hi) { f32x2 v = {lo, hi}; bf16x2_t b = __builtin_convertvector(v, bf16x2_t); return __builtin_bit_cast(unsigned, b); }
;     __device__ __forceinline__ void operator()(const f32x4 (&acc)[2][2][4][2], const Unit& u, int wr, int wc, int fr, int fq) const {
;     ...
;                         for (int n = 0; n < 2; ++n) { const u32x2 w = bw[m][bj][n];
;                             bs[m][bj][n] = (f32x4){__uint_as_float(w.x << 16), __uint_as_float(w.x & 0xffff0000u), __uint_as_float(w.y << 16), __uint_as_float(w.y & 0xffff0000u)}; }
;             }
; #pragma unroll
;             for (int m = 0; m < 4; ++m) { const size_t off = (size_t)(row0 + ai * HALF + m * 16) * DM + col0; float ss = 0.f;
; #pragma unroll
;                 for (int bj = 0; bj < 2; ++bj)
; #pragma unroll
;                     for (int n = 0; n < 2; ++n) { const f32x4 o = bs[m][bj][n] + acc[ai][bj][m][n];
;                         u32x2 w; w.x = cvt_pk_bf16(o[0], o[1]); w.y = cvt_pk_bf16(o[2], o[3]);
;                         *(u32x2*)(h1 + off + bj * HALF + n * 16) = w;
;                         if (h2) *(u32x2*)(h2 + off + bj * HALF + n * 16) = w;
;                         ss += (o[0] * o[0] + o[1] * o[1]) + (o[2] * o[2] + o[3] * o[3]); }
;                 ss += __shfl_xor(ss, 16); ss += __shfl_xor(ss, 32);
;                 if (fq == 0) rsq[(size_t)(row0 + ai * HALF + m * 16) * 32 + u.pn * 4 + wc] = ss; } }
.LBB0_797:
	s_or_b64 exec, exec, s[24:25]
	v_lshlrev_b32_e32 v114, 16, v176
	s_waitcnt lgkmcnt(0)
	v_and_b32_e32 v115, 0xffff0000, v176
	v_lshlrev_b32_e32 v116, 16, v177
	v_and_b32_e32 v117, 0xffff0000, v177
	v_pk_add_f32 v[108:109], v[108:109], v[114:115]
	v_pk_add_f32 v[110:111], v[110:111], v[116:117]
	v_cvt_pk_bf16_f32 v114, v108, v109
	v_mul_f32_e32 v109, v109, v109
	v_lshlrev_b32_e32 v118, 16, v174
	v_and_b32_e32 v119, 0xffff0000, v174
	v_fmac_f32_e32 v109, v108, v108
	v_mul_f32_e32 v108, v111, v111
	v_lshlrev_b32_e32 v120, 16, v175
	v_and_b32_e32 v121, 0xffff0000, v175
	v_fmac_f32_e32 v108, v110, v110
	v_pk_add_f32 v[104:105], v[104:105], v[118:119]
	v_add_f32_e32 v109, v109, v108
	v_pk_add_f32 v[106:107], v[106:107], v[120:121]
	v_cvt_pk_bf16_f32 v108, v104, v105
	v_mul_f32_e32 v105, v105, v105
	v_fmac_f32_e32 v105, v104, v104
	v_mul_f32_e32 v104, v107, v107
	v_lshlrev_b32_e32 v122, 16, v172
	v_and_b32_e32 v123, 0xffff0000, v172
	v_lshlrev_b32_e32 v124, 16, v173
	v_and_b32_e32 v125, 0xffff0000, v173
	v_fmac_f32_e32 v104, v106, v106
	v_add_f32_e32 v104, v105, v104
	v_pk_add_f32 v[102:103], v[102:103], v[124:125]
	v_pk_add_f32 v[100:101], v[100:101], v[122:123]
	v_add_f32_e32 v104, v109, v104
	v_mul_f32_e32 v105, v101, v101
	v_mul_f32_e32 v109, v103, v103
	v_fmac_f32_e32 v105, v100, v100
	v_fmac_f32_e32 v109, v102, v102
	v_lshlrev_b32_e32 v126, 16, v170
	v_and_b32_e32 v127, 0xffff0000, v170
	v_lshlrev_b32_e32 v128, 16, v171
	v_and_b32_e32 v129, 0xffff0000, v171
	v_add_f32_e32 v105, v105, v109
	v_add_f32_e32 v109, v104, v105
	v_pk_add_f32 v[98:99], v[98:99], v[128:129]
	v_pk_add_f32 v[104:105], v[96:97], v[126:127]
	v_mul_f32_e32 v97, v99, v99
	v_mul_f32_e32 v96, v105, v105
	v_fmac_f32_e32 v96, v104, v104
	v_fmac_f32_e32 v97, v98, v98
	v_add_f32_e32 v96, v96, v97
	v_add_f32_e32 v96, v109, v96
	ds_bpermute_b32 v97, v211, v96
	v_lshl_add_u64 v[116:117], s[10:11], 0, v[168:169]
	v_lshl_add_u64 v[116:117], v[136:137], 1, v[116:117]
	v_cvt_pk_bf16_f32 v100, v100, v101
	v_cvt_pk_bf16_f32 v101, v102, v103
	s_waitcnt lgkmcnt(0)
	v_add_f32_e32 v96, v96, v97
	ds_bpermute_b32 v97, v210, v96
	v_cvt_pk_bf16_f32 v115, v110, v111
	v_cvt_pk_bf16_f32 v109, v106, v107
	global_store_dwordx2 v[116:117], v[100:101], off offset:256
	v_cvt_pk_bf16_f32 v100, v104, v105
	v_cvt_pk_bf16_f32 v101, v98, v99
	global_store_dwordx2 v[116:117], v[114:115], off
	global_store_dwordx2 v[116:117], v[108:109], off offset:32
	global_store_dwordx2 v[116:117], v[100:101], off offset:288
	s_and_saveexec_b64 s[24:25], s[4:5]
	s_cbranch_execz .LBB0_799
	v_lshlrev_b64 v[98:99], 7, v[148:149]
	v_lshl_add_u64 v[98:99], s[14:15], 0, v[98:99]
	v_lshl_add_u64 v[98:99], s[22:23], 2, v[98:99]
	s_lshl_b32 s72, s41, 2
	v_lshl_add_u64 v[98:99], v[98:99], 0, s[72:73]
	s_waitcnt lgkmcnt(0)
	v_add_f32_e32 v96, v96, v97
	global_store_dword v[98:99], v96, off
.LBB0_799:
	s_or_b64 exec, exec, s[24:25]
	v_lshlrev_b32_e32 v96, 16, v166
	s_waitcnt lgkmcnt(0)
	v_and_b32_e32 v97, 0xffff0000, v166
	v_lshlrev_b32_e32 v98, 16, v167
	v_and_b32_e32 v99, 0xffff0000, v167
	v_pk_add_f32 v[92:93], v[92:93], v[96:97]
	v_pk_add_f32 v[94:95], v[94:95], v[98:99]
	v_cvt_pk_bf16_f32 v96, v92, v93
	v_mul_f32_e32 v93, v93, v93
	v_lshlrev_b32_e32 v100, 16, v164
	v_and_b32_e32 v101, 0xffff0000, v164
	v_fmac_f32_e32 v93, v92, v92
	v_mul_f32_e32 v92, v95, v95
	v_lshlrev_b32_e32 v102, 16, v165
	v_and_b32_e32 v103, 0xffff0000, v165
	v_fmac_f32_e32 v92, v94, v94
	v_pk_add_f32 v[88:89], v[88:89], v[100:101]
	v_add_f32_e32 v93, v93, v92
	v_pk_add_f32 v[90:91], v[90:91], v[102:103]
	v_cvt_pk_bf16_f32 v92, v88, v89
	v_mul_f32_e32 v89, v89, v89
	v_fmac_f32_e32 v89, v88, v88
	v_mul_f32_e32 v88, v91, v91
	v_lshlrev_b32_e32 v104, 16, v162
	v_and_b32_e32 v105, 0xffff0000, v162
	v_lshlrev_b32_e32 v106, 16, v163
	v_and_b32_e32 v107, 0xffff0000, v163
	v_fmac_f32_e32 v88, v90, v90
	v_add_f32_e32 v88, v89, v88
	v_pk_add_f32 v[86:87], v[86:87], v[106:107]
	v_pk_add_f32 v[84:85], v[84:85], v[104:105]
	v_add_f32_e32 v88, v93, v88
	v_mul_f32_e32 v89, v85, v85
	v_mul_f32_e32 v93, v87, v87
	v_fmac_f32_e32 v89, v84, v84
	v_fmac_f32_e32 v93, v86, v86
	v_lshlrev_b32_e32 v108, 16, v158
	v_and_b32_e32 v109, 0xffff0000, v158
	v_lshlrev_b32_e32 v110, 16, v159
	v_and_b32_e32 v111, 0xffff0000, v159
	v_add_f32_e32 v89, v89, v93
	v_add_f32_e32 v93, v88, v89
	v_pk_add_f32 v[82:83], v[82:83], v[110:111]
	v_pk_add_f32 v[88:89], v[80:81], v[108:109]
	v_mul_f32_e32 v81, v83, v83
	v_mul_f32_e32 v80, v89, v89
	v_fmac_f32_e32 v80, v88, v88
	v_fmac_f32_e32 v81, v82, v82
	v_add_f32_e32 v80, v80, v81
	v_add_f32_e32 v80, v93, v80
	ds_bpermute_b32 v81, v211, v80
	v_lshl_add_u64 v[98:99], s[10:11], 0, v[150:151]
	v_lshl_add_u64 v[98:99], v[136:137], 1, v[98:99]
	v_cvt_pk_bf16_f32 v84, v84, v85
	v_cvt_pk_bf16_f32 v85, v86, v87
	s_waitcnt lgkmcnt(0)
	v_add_f32_e32 v80, v80, v81
	ds_bpermute_b32 v81, v210, v80
	v_cvt_pk_bf16_f32 v97, v94, v95
	v_cvt_pk_bf16_f32 v93, v90, v91
	global_store_dwordx2 v[98:99], v[84:85], off offset:256
	v_cvt_pk_bf16_f32 v84, v88, v89
	v_cvt_pk_bf16_f32 v85, v82, v83
	global_store_dwordx2 v[98:99], v[96:97], off
	global_store_dwordx2 v[98:99], v[92:93], off offset:32
	global_store_dwordx2 v[98:99], v[84:85], off offset:288
	s_and_saveexec_b64 s[24:25], s[4:5]
	s_cbranch_execz .LBB0_801
	v_lshlrev_b64 v[82:83], 7, v[144:145]
	v_lshl_add_u64 v[82:83], s[14:15], 0, v[82:83]
	v_lshl_add_u64 v[82:83], s[22:23], 2, v[82:83]
	s_lshl_b32 s72, s41, 2
	v_lshl_add_u64 v[82:83], v[82:83], 0, s[72:73]
	s_waitcnt lgkmcnt(0)
	v_add_f32_e32 v80, v80, v81
	global_store_dword v[82:83], v80, off
; __device__ __forceinline__ unsigned cvt_pk_bf16(float lo, float hi) { f32x2 v = {lo, hi}; bf16x2_t b = __builtin_convertvector(v, bf16x2_t); return __builtin_bit_cast(unsigned, b); }
;     __device__ __forceinline__ void operator()(const f32x4 (&acc)[2][2][4][2], const Unit& u, int wr, int wc, int fr, int fq) const {
;     ...
;                 u32x2 bw[4][2][2];
; #pragma unroll
;                 for (int m = 0; m < 4; ++m) { const size_t off = (size_t)(row0 + ai * HALF + m * 16) * DM + col0;
; #pragma unroll
;                     for (int bj = 0; bj < 2; ++bj)
; #pragma unroll
;                         for (int n = 0; n < 2; ++n) bw[m][bj][n] = *(const u32x2*)((const bf16_t*)base + off + bj * HALF + n * 16); }
; #pragma unroll
;                 for (int m = 0; m < 4; ++m)
; #pragma unroll
;                     for (int bj = 0; bj < 2; ++bj)
; #pragma unroll
;                         for (int n = 0; n < 2; ++n) { const u32x2 w = bw[m][bj][n];
;                             bs[m][bj][n] = (f32x4){__uint_as_float(w.x << 16), __uint_as_float(w.x & 0xffff0000u), __uint_as_float(w.y << 16), __uint_as_float(w.y & 0xffff0000u)}; }
;             }
; #pragma unroll
;             for (int m = 0; m < 4; ++m) { const size_t off = (size_t)(row0 + ai * HALF + m * 16) * DM + col0; float ss = 0.f;
; #pragma unroll
;                 for (int bj = 0; bj < 2; ++bj)
; #pragma unroll
;                     for (int n = 0; n < 2; ++n) { const f32x4 o = bs[m][bj][n] + acc[ai][bj][m][n];
;                         u32x2 w; w.x = cvt_pk_bf16(o[0], o[1]); w.y = cvt_pk_bf16(o[2], o[3]);
;                         *(u32x2*)(h1 + off + bj * HALF + n * 16) = w;
;                         if (h2) *(u32x2*)(h2 + off + bj * HALF + n * 16) = w;
;                         ss += (o[0] * o[0] + o[1] * o[1]) + (o[2] * o[2] + o[3] * o[3]); }
;                 ss += __shfl_xor(ss, 16); ss += __shfl_xor(ss, 32);
;                 if (fq == 0) rsq[(size_t)(row0 + ai * HALF + m * 16) * 32 + u.pn * 4 + wc] = ss; } }
.LBB0_801:
	s_or_b64 exec, exec, s[24:25]
	v_lshlrev_b32_e32 v80, 16, v160
	s_waitcnt lgkmcnt(0)
	v_and_b32_e32 v81, 0xffff0000, v160
	v_lshlrev_b32_e32 v82, 16, v161
	v_and_b32_e32 v83, 0xffff0000, v161
	v_pk_add_f32 v[76:77], v[76:77], v[80:81]
	v_pk_add_f32 v[78:79], v[78:79], v[82:83]
	v_cvt_pk_bf16_f32 v80, v76, v77
	v_mul_f32_e32 v77, v77, v77
	v_lshlrev_b32_e32 v84, 16, v156
	v_and_b32_e32 v85, 0xffff0000, v156
	v_fmac_f32_e32 v77, v76, v76
	v_mul_f32_e32 v76, v79, v79
	v_lshlrev_b32_e32 v86, 16, v157
	v_and_b32_e32 v87, 0xffff0000, v157
	v_fmac_f32_e32 v76, v78, v78
	v_pk_add_f32 v[72:73], v[72:73], v[84:85]
	v_add_f32_e32 v77, v77, v76
	v_pk_add_f32 v[74:75], v[74:75], v[86:87]
	v_cvt_pk_bf16_f32 v76, v72, v73
	v_mul_f32_e32 v73, v73, v73
	v_fmac_f32_e32 v73, v72, v72
	v_mul_f32_e32 v72, v75, v75
	v_lshlrev_b32_e32 v88, 16, v154
	v_and_b32_e32 v89, 0xffff0000, v154
	v_lshlrev_b32_e32 v90, 16, v155
	v_and_b32_e32 v91, 0xffff0000, v155
	v_fmac_f32_e32 v72, v74, v74
	v_add_f32_e32 v72, v73, v72
	v_pk_add_f32 v[70:71], v[70:71], v[90:91]
	v_pk_add_f32 v[68:69], v[68:69], v[88:89]
	v_add_f32_e32 v72, v77, v72
	v_mul_f32_e32 v73, v69, v69
	v_mul_f32_e32 v77, v71, v71
	v_fmac_f32_e32 v73, v68, v68
	v_fmac_f32_e32 v77, v70, v70
	v_lshlrev_b32_e32 v92, 16, v152
	v_and_b32_e32 v93, 0xffff0000, v152
	v_lshlrev_b32_e32 v94, 16, v153
	v_and_b32_e32 v95, 0xffff0000, v153
	v_add_f32_e32 v73, v73, v77
	v_add_f32_e32 v77, v72, v73
	v_pk_add_f32 v[66:67], v[66:67], v[94:95]
	v_pk_add_f32 v[72:73], v[64:65], v[92:93]
	v_mul_f32_e32 v65, v67, v67
	v_mul_f32_e32 v64, v73, v73
	v_fmac_f32_e32 v64, v72, v72
	v_fmac_f32_e32 v65, v66, v66
	v_add_f32_e32 v64, v64, v65
	v_add_f32_e32 v64, v77, v64
	ds_bpermute_b32 v65, v211, v64
	v_lshl_add_u64 v[82:83], s[10:11], 0, v[146:147]
	v_lshl_add_u64 v[82:83], v[136:137], 1, v[82:83]
	v_cvt_pk_bf16_f32 v68, v68, v69
	v_cvt_pk_bf16_f32 v69, v70, v71
	s_waitcnt lgkmcnt(0)
	v_add_f32_e32 v64, v64, v65
	ds_bpermute_b32 v65, v210, v64
	v_cvt_pk_bf16_f32 v81, v78, v79
	v_cvt_pk_bf16_f32 v77, v74, v75
	global_store_dwordx2 v[82:83], v[68:69], off offset:256
	v_cvt_pk_bf16_f32 v68, v72, v73
	v_cvt_pk_bf16_f32 v69, v66, v67
	global_store_dwordx2 v[82:83], v[80:81], off
	global_store_dwordx2 v[82:83], v[76:77], off offset:32
	global_store_dwordx2 v[82:83], v[68:69], off offset:288
	s_and_saveexec_b64 s[24:25], s[4:5]
	s_cbranch_execz .LBB0_803
	v_lshlrev_b64 v[66:67], 7, v[142:143]
	v_lshl_add_u64 v[66:67], s[14:15], 0, v[66:67]
	v_lshl_add_u64 v[66:67], s[22:23], 2, v[66:67]
	s_lshl_b32 s72, s41, 2
	v_lshl_add_u64 v[66:67], v[66:67], 0, s[72:73]
	s_waitcnt lgkmcnt(0)
	v_add_f32_e32 v64, v64, v65
	global_store_dword v[66:67], v64, off
.LBB0_803:
	s_or_b64 exec, exec, s[24:25]
	v_add_u32_e32 v92, 0x80, v138
	v_ashrrev_i32_e32 v93, 31, v92
	v_lshlrev_b64 v[102:103], 12, v[92:93]
	s_waitcnt lgkmcnt(0)
	v_lshl_add_u64 v[64:65], v[140:141], 0, v[102:103]
	global_load_dwordx2 v[104:105], v[64:65], off
	global_load_dwordx2 v[106:107], v[64:65], off offset:32
	global_load_dwordx2 v[108:109], v[64:65], off offset:256
	global_load_dwordx2 v[110:111], v[64:65], off offset:288
	v_add_u32_e32 v80, 0x90, v138
	v_add_u32_e32 v68, 0xa0, v138
	v_add_u32_e32 v64, 0xb0, v138
	v_ashrrev_i32_e32 v81, 31, v80
	v_ashrrev_i32_e32 v69, 31, v68
	v_ashrrev_i32_e32 v65, 31, v64
	v_lshlrev_b64 v[90:91], 12, v[80:81]
	v_lshlrev_b64 v[78:79], 12, v[68:69]
	v_lshlrev_b64 v[66:67], 12, v[64:65]
	v_lshl_add_u64 v[70:71], v[140:141], 0, v[90:91]
	v_lshl_add_u64 v[72:73], v[140:141], 0, v[78:79]
	v_lshl_add_u64 v[114:115], v[140:141], 0, v[66:67]
	global_load_dwordx2 v[100:101], v[70:71], off
	global_load_dwordx2 v[98:99], v[70:71], off offset:32
	global_load_dwordx2 v[96:97], v[70:71], off offset:256
	global_load_dwordx2 v[94:95], v[70:71], off offset:288
	global_load_dwordx2 v[88:89], v[72:73], off
	global_load_dwordx2 v[86:87], v[72:73], off offset:32
	global_load_dwordx2 v[84:85], v[72:73], off offset:256
	global_load_dwordx2 v[82:83], v[72:73], off offset:288
	global_load_dwordx2 v[76:77], v[114:115], off
	global_load_dwordx2 v[74:75], v[114:115], off offset:32
	s_nop 0
	global_load_dwordx2 v[72:73], v[114:115], off offset:256
	global_load_dwordx2 v[70:71], v[114:115], off offset:288
	v_lshl_add_u64 v[102:103], s[10:11], 0, v[102:103]
	v_lshl_add_u64 v[102:103], v[136:137], 1, v[102:103]
	s_waitcnt vmcnt(0) lgkmcnt(0)
	v_lshlrev_b32_e32 v114, 16, v104
	v_and_b32_e32 v115, 0xffff0000, v104
	v_lshlrev_b32_e32 v104, 16, v105
	v_and_b32_e32 v105, 0xffff0000, v105
	v_lshlrev_b32_e32 v116, 16, v106
	v_and_b32_e32 v117, 0xffff0000, v106
	v_lshlrev_b32_e32 v106, 16, v107
	v_and_b32_e32 v107, 0xffff0000, v107
	v_lshlrev_b32_e32 v118, 16, v108
	v_and_b32_e32 v119, 0xffff0000, v108
	v_lshlrev_b32_e32 v108, 16, v109
	v_and_b32_e32 v109, 0xffff0000, v109
	v_lshlrev_b32_e32 v120, 16, v110
	v_and_b32_e32 v121, 0xffff0000, v110
	v_pk_add_f32 v[62:63], v[62:63], v[104:105]
	v_pk_add_f32 v[60:61], v[60:61], v[114:115]
	v_pk_add_f32 v[58:59], v[58:59], v[106:107]
	v_pk_add_f32 v[56:57], v[56:57], v[116:117]
	v_lshlrev_b32_e32 v110, 16, v111
	v_and_b32_e32 v111, 0xffff0000, v111
	v_pk_add_f32 v[54:55], v[54:55], v[108:109]
	v_pk_add_f32 v[52:53], v[52:53], v[118:119]
	v_pk_add_f32 v[104:105], v[48:49], v[120:121]
	v_cvt_pk_bf16_f32 v48, v60, v61
	v_cvt_pk_bf16_f32 v49, v62, v63
	v_mul_f32_e32 v61, v61, v61
	v_mul_f32_e32 v63, v63, v63
	v_cvt_pk_bf16_f32 v106, v56, v57
	v_mul_f32_e32 v57, v57, v57
	v_mul_f32_e32 v107, v59, v59
	v_pk_add_f32 v[50:51], v[50:51], v[110:111]
	v_mul_f32_e32 v108, v53, v53
	v_mul_f32_e32 v109, v55, v55
	v_fmac_f32_e32 v61, v60, v60
	v_fmac_f32_e32 v63, v62, v62
	v_fmac_f32_e32 v57, v56, v56
	v_fmac_f32_e32 v107, v58, v58
	v_mul_f32_e32 v110, v105, v105
	v_mul_f32_e32 v111, v51, v51
	global_store_dwordx2 v[102:103], v[48:49], off
	v_fmac_f32_e32 v108, v52, v52
	v_fmac_f32_e32 v109, v54, v54
	v_add_f32_e32 v48, v61, v63
	v_add_f32_e32 v49, v57, v107
	v_fmac_f32_e32 v110, v104, v104
	v_fmac_f32_e32 v111, v50, v50
	v_add_f32_e32 v56, v108, v109
	v_add_f32_e32 v48, v48, v49
	v_add_f32_e32 v48, v48, v56
	v_add_f32_e32 v49, v110, v111
	v_add_f32_e32 v48, v48, v49
	ds_bpermute_b32 v49, v211, v48
	v_cvt_pk_bf16_f32 v52, v52, v53
	v_cvt_pk_bf16_f32 v53, v54, v55
	v_cvt_pk_bf16_f32 v107, v58, v59
	global_store_dwordx2 v[102:103], v[52:53], off offset:256
	s_waitcnt lgkmcnt(0)
	v_add_f32_e32 v48, v48, v49
	ds_bpermute_b32 v49, v210, v48
	v_cvt_pk_bf16_f32 v52, v104, v105
	v_cvt_pk_bf16_f32 v53, v50, v51
	global_store_dwordx2 v[102:103], v[106:107], off offset:32
	global_store_dwordx2 v[102:103], v[52:53], off offset:288
	s_and_saveexec_b64 s[24:25], s[4:5]
	s_cbranch_execz .LBB0_805
	v_lshlrev_b64 v[50:51], 7, v[92:93]
	v_lshl_add_u64 v[50:51], s[14:15], 0, v[50:51]
	v_lshl_add_u64 v[50:51], s[22:23], 2, v[50:51]
	s_lshl_b32 s72, s41, 2
	v_lshl_add_u64 v[50:51], v[50:51], 0, s[72:73]
	s_waitcnt lgkmcnt(0)
	v_add_f32_e32 v48, v48, v49
	global_store_dword v[50:51], v48, off
; __device__ __forceinline__ unsigned cvt_pk_bf16(float lo, float hi) { f32x2 v = {lo, hi}; bf16x2_t b = __builtin_convertvector(v, bf16x2_t); return __builtin_bit_cast(unsigned, b); }
;     __device__ __forceinline__ void operator()(const f32x4 (&acc)[2][2][4][2], const Unit& u, int wr, int wc, int fr, int fq) const {
;     ...
;                         for (int n = 0; n < 2; ++n) { const u32x2 w = bw[m][bj][n];
;                             bs[m][bj][n] = (f32x4){__uint_as_float(w.x << 16), __uint_as_float(w.x & 0xffff0000u), __uint_as_float(w.y << 16), __uint_as_float(w.y & 0xffff0000u)}; }
;             }
; #pragma unroll
;             for (int m = 0; m < 4; ++m) { const size_t off = (size_t)(row0 + ai * HALF + m * 16) * DM + col0; float ss = 0.f;
; #pragma unroll
;                 for (int bj = 0; bj < 2; ++bj)
; #pragma unroll
;                     for (int n = 0; n < 2; ++n) { const f32x4 o = bs[m][bj][n] + acc[ai][bj][m][n];
;                         u32x2 w; w.x = cvt_pk_bf16(o[0], o[1]); w.y = cvt_pk_bf16(o[2], o[3]);
;                         *(u32x2*)(h1 + off + bj * HALF + n * 16) = w;
;                         if (h2) *(u32x2*)(h2 + off + bj * HALF + n * 16) = w;
;                         ss += (o[0] * o[0] + o[1] * o[1]) + (o[2] * o[2] + o[3] * o[3]); }
;                 ss += __shfl_xor(ss, 16); ss += __shfl_xor(ss, 32);
;                 if (fq == 0) rsq[(size_t)(row0 + ai * HALF + m * 16) * 32 + u.pn * 4 + wc] = ss; } }
.LBB0_805:
	s_or_b64 exec, exec, s[24:25]
	v_lshlrev_b32_e32 v48, 16, v100
	s_waitcnt lgkmcnt(0)
	v_and_b32_e32 v49, 0xffff0000, v100
	v_lshlrev_b32_e32 v50, 16, v101
	v_and_b32_e32 v51, 0xffff0000, v101
	v_pk_add_f32 v[44:45], v[44:45], v[48:49]
	v_pk_add_f32 v[46:47], v[46:47], v[50:51]
	v_cvt_pk_bf16_f32 v48, v44, v45
	v_mul_f32_e32 v45, v45, v45
	v_lshlrev_b32_e32 v52, 16, v98
	v_and_b32_e32 v53, 0xffff0000, v98
	v_fmac_f32_e32 v45, v44, v44
	v_mul_f32_e32 v44, v47, v47
	v_lshlrev_b32_e32 v54, 16, v99
	v_and_b32_e32 v55, 0xffff0000, v99
	v_fmac_f32_e32 v44, v46, v46
	v_pk_add_f32 v[40:41], v[40:41], v[52:53]
	v_add_f32_e32 v45, v45, v44
	v_pk_add_f32 v[42:43], v[42:43], v[54:55]
	v_cvt_pk_bf16_f32 v44, v40, v41
	v_mul_f32_e32 v41, v41, v41
	v_fmac_f32_e32 v41, v40, v40
	v_mul_f32_e32 v40, v43, v43
	v_lshlrev_b32_e32 v56, 16, v96
	v_and_b32_e32 v57, 0xffff0000, v96
	v_lshlrev_b32_e32 v58, 16, v97
	v_and_b32_e32 v59, 0xffff0000, v97
	v_fmac_f32_e32 v40, v42, v42
	v_add_f32_e32 v40, v41, v40
	v_pk_add_f32 v[38:39], v[38:39], v[58:59]
	v_pk_add_f32 v[36:37], v[36:37], v[56:57]
	v_add_f32_e32 v40, v45, v40
	v_mul_f32_e32 v41, v37, v37
	v_mul_f32_e32 v45, v39, v39
	v_fmac_f32_e32 v41, v36, v36
	v_fmac_f32_e32 v45, v38, v38
	v_lshlrev_b32_e32 v60, 16, v94
	v_and_b32_e32 v61, 0xffff0000, v94
	v_lshlrev_b32_e32 v62, 16, v95
	v_and_b32_e32 v63, 0xffff0000, v95
	v_add_f32_e32 v41, v41, v45
	v_add_f32_e32 v45, v40, v41
	v_pk_add_f32 v[34:35], v[34:35], v[62:63]
	v_pk_add_f32 v[40:41], v[32:33], v[60:61]
	v_mul_f32_e32 v33, v35, v35
	v_mul_f32_e32 v32, v41, v41
	v_fmac_f32_e32 v32, v40, v40
	v_fmac_f32_e32 v33, v34, v34
	v_add_f32_e32 v32, v32, v33
	v_add_f32_e32 v32, v45, v32
	ds_bpermute_b32 v33, v211, v32
	v_lshl_add_u64 v[50:51], s[10:11], 0, v[90:91]
	v_lshl_add_u64 v[50:51], v[136:137], 1, v[50:51]
	v_cvt_pk_bf16_f32 v36, v36, v37
	v_cvt_pk_bf16_f32 v37, v38, v39
	s_waitcnt lgkmcnt(0)
	v_add_f32_e32 v32, v32, v33
	ds_bpermute_b32 v33, v210, v32
	v_cvt_pk_bf16_f32 v49, v46, v47
	v_cvt_pk_bf16_f32 v45, v42, v43
	global_store_dwordx2 v[50:51], v[36:37], off offset:256
	v_cvt_pk_bf16_f32 v36, v40, v41
	v_cvt_pk_bf16_f32 v37, v34, v35
	global_store_dwordx2 v[50:51], v[48:49], off
	global_store_dwordx2 v[50:51], v[44:45], off offset:32
	global_store_dwordx2 v[50:51], v[36:37], off offset:288
	s_and_saveexec_b64 s[24:25], s[4:5]
	s_cbranch_execz .LBB0_807
	v_lshlrev_b64 v[34:35], 7, v[80:81]
	v_lshl_add_u64 v[34:35], s[14:15], 0, v[34:35]
	v_lshl_add_u64 v[34:35], s[22:23], 2, v[34:35]
	s_lshl_b32 s72, s41, 2
	v_lshl_add_u64 v[34:35], v[34:35], 0, s[72:73]
	s_waitcnt lgkmcnt(0)
	v_add_f32_e32 v32, v32, v33
	global_store_dword v[34:35], v32, off
; __device__ __forceinline__ unsigned cvt_pk_bf16(float lo, float hi) { f32x2 v = {lo, hi}; bf16x2_t b = __builtin_convertvector(v, bf16x2_t); return __builtin_bit_cast(unsigned, b); }
;     __device__ __forceinline__ void operator()(const f32x4 (&acc)[2][2][4][2], const Unit& u, int wr, int wc, int fr, int fq) const {
;     ...
;                         for (int n = 0; n < 2; ++n) { const u32x2 w = bw[m][bj][n];
;                             bs[m][bj][n] = (f32x4){__uint_as_float(w.x << 16), __uint_as_float(w.x & 0xffff0000u), __uint_as_float(w.y << 16), __uint_as_float(w.y & 0xffff0000u)}; }
;             }
; #pragma unroll
;             for (int m = 0; m < 4; ++m) { const size_t off = (size_t)(row0 + ai * HALF + m * 16) * DM + col0; float ss = 0.f;
; #pragma unroll
;                 for (int bj = 0; bj < 2; ++bj)
; #pragma unroll
;                     for (int n = 0; n < 2; ++n) { const f32x4 o = bs[m][bj][n] + acc[ai][bj][m][n];
;                         u32x2 w; w.x = cvt_pk_bf16(o[0], o[1]); w.y = cvt_pk_bf16(o[2], o[3]);
;                         *(u32x2*)(h1 + off + bj * HALF + n * 16) = w;
;                         if (h2) *(u32x2*)(h2 + off + bj * HALF + n * 16) = w;
;                         ss += (o[0] * o[0] + o[1] * o[1]) + (o[2] * o[2] + o[3] * o[3]); }
;                 ss += __shfl_xor(ss, 16); ss += __shfl_xor(ss, 32);
;                 if (fq == 0) rsq[(size_t)(row0 + ai * HALF + m * 16) * 32 + u.pn * 4 + wc] = ss; } }
.LBB0_807:
	s_or_b64 exec, exec, s[24:25]
	v_lshlrev_b32_e32 v32, 16, v88
	s_waitcnt lgkmcnt(0)
	v_and_b32_e32 v33, 0xffff0000, v88
	v_lshlrev_b32_e32 v34, 16, v89
	v_and_b32_e32 v35, 0xffff0000, v89
	v_pk_add_f32 v[28:29], v[28:29], v[32:33]
	v_pk_add_f32 v[30:31], v[30:31], v[34:35]
	v_cvt_pk_bf16_f32 v32, v28, v29
	v_mul_f32_e32 v29, v29, v29
	v_lshlrev_b32_e32 v36, 16, v86
	v_and_b32_e32 v37, 0xffff0000, v86
	v_fmac_f32_e32 v29, v28, v28
	v_mul_f32_e32 v28, v31, v31
	v_lshlrev_b32_e32 v38, 16, v87
	v_and_b32_e32 v39, 0xffff0000, v87
	v_fmac_f32_e32 v28, v30, v30
	v_pk_add_f32 v[24:25], v[24:25], v[36:37]
	v_add_f32_e32 v29, v29, v28
	v_pk_add_f32 v[26:27], v[26:27], v[38:39]
	v_cvt_pk_bf16_f32 v28, v24, v25
	v_mul_f32_e32 v25, v25, v25
	v_fmac_f32_e32 v25, v24, v24
	v_mul_f32_e32 v24, v27, v27
	v_lshlrev_b32_e32 v40, 16, v84
	v_and_b32_e32 v41, 0xffff0000, v84
	v_lshlrev_b32_e32 v42, 16, v85
	v_and_b32_e32 v43, 0xffff0000, v85
	v_fmac_f32_e32 v24, v26, v26
	v_add_f32_e32 v24, v25, v24
	v_pk_add_f32 v[22:23], v[22:23], v[42:43]
	v_pk_add_f32 v[20:21], v[20:21], v[40:41]
	v_add_f32_e32 v24, v29, v24
	v_mul_f32_e32 v25, v21, v21
	v_mul_f32_e32 v29, v23, v23
	v_fmac_f32_e32 v25, v20, v20
	v_fmac_f32_e32 v29, v22, v22
	v_lshlrev_b32_e32 v44, 16, v82
	v_and_b32_e32 v45, 0xffff0000, v82
	v_lshlrev_b32_e32 v46, 16, v83
	v_and_b32_e32 v47, 0xffff0000, v83
	v_add_f32_e32 v25, v25, v29
	v_add_f32_e32 v29, v24, v25
	v_pk_add_f32 v[18:19], v[18:19], v[46:47]
	v_pk_add_f32 v[24:25], v[16:17], v[44:45]
	v_mul_f32_e32 v17, v19, v19
	v_mul_f32_e32 v16, v25, v25
	v_fmac_f32_e32 v16, v24, v24
	v_fmac_f32_e32 v17, v18, v18
	v_add_f32_e32 v16, v16, v17
	v_add_f32_e32 v16, v29, v16
	ds_bpermute_b32 v17, v211, v16
	v_lshl_add_u64 v[34:35], s[10:11], 0, v[78:79]
	v_lshl_add_u64 v[34:35], v[136:137], 1, v[34:35]
	v_cvt_pk_bf16_f32 v20, v20, v21
	v_cvt_pk_bf16_f32 v21, v22, v23
	s_waitcnt lgkmcnt(0)
	v_add_f32_e32 v16, v16, v17
	ds_bpermute_b32 v17, v210, v16
	v_cvt_pk_bf16_f32 v33, v30, v31
	v_cvt_pk_bf16_f32 v29, v26, v27
	global_store_dwordx2 v[34:35], v[20:21], off offset:256
	v_cvt_pk_bf16_f32 v20, v24, v25
	v_cvt_pk_bf16_f32 v21, v18, v19
	global_store_dwordx2 v[34:35], v[32:33], off
	global_store_dwordx2 v[34:35], v[28:29], off offset:32
	global_store_dwordx2 v[34:35], v[20:21], off offset:288
	s_and_saveexec_b64 s[24:25], s[4:5]
	s_cbranch_execz .LBB0_809
	v_lshlrev_b64 v[18:19], 7, v[68:69]
	v_lshl_add_u64 v[18:19], s[14:15], 0, v[18:19]
	v_lshl_add_u64 v[18:19], s[22:23], 2, v[18:19]
	s_lshl_b32 s72, s41, 2
	v_lshl_add_u64 v[18:19], v[18:19], 0, s[72:73]
	s_waitcnt lgkmcnt(0)
	v_add_f32_e32 v16, v16, v17
	global_store_dword v[18:19], v16, off
.LBB0_809:
	s_or_b64 exec, exec, s[24:25]
	v_lshlrev_b32_e32 v16, 16, v76
	s_waitcnt lgkmcnt(0)
	v_and_b32_e32 v17, 0xffff0000, v76
	v_lshlrev_b32_e32 v18, 16, v77
	v_and_b32_e32 v19, 0xffff0000, v77
	v_pk_add_f32 v[12:13], v[12:13], v[16:17]
	v_pk_add_f32 v[14:15], v[14:15], v[18:19]
	v_cvt_pk_bf16_f32 v16, v12, v13
	v_mul_f32_e32 v13, v13, v13
	v_lshlrev_b32_e32 v20, 16, v74
	v_and_b32_e32 v21, 0xffff0000, v74
	v_fmac_f32_e32 v13, v12, v12
	v_mul_f32_e32 v12, v15, v15
	v_lshlrev_b32_e32 v22, 16, v75
	v_and_b32_e32 v23, 0xffff0000, v75
	v_fmac_f32_e32 v12, v14, v14
	v_pk_add_f32 v[8:9], v[8:9], v[20:21]
	v_add_f32_e32 v13, v13, v12
	v_pk_add_f32 v[10:11], v[10:11], v[22:23]
	v_cvt_pk_bf16_f32 v12, v8, v9
	v_mul_f32_e32 v9, v9, v9
	v_fmac_f32_e32 v9, v8, v8
	v_mul_f32_e32 v8, v11, v11
	v_lshlrev_b32_e32 v24, 16, v72
	v_and_b32_e32 v25, 0xffff0000, v72
	v_lshlrev_b32_e32 v26, 16, v73
	v_and_b32_e32 v27, 0xffff0000, v73
	v_fmac_f32_e32 v8, v10, v10
	v_add_f32_e32 v8, v9, v8
	v_pk_add_f32 v[6:7], v[6:7], v[26:27]
	v_pk_add_f32 v[4:5], v[4:5], v[24:25]
	v_add_f32_e32 v8, v13, v8
	v_mul_f32_e32 v9, v5, v5
	v_mul_f32_e32 v13, v7, v7
	v_fmac_f32_e32 v9, v4, v4
	v_fmac_f32_e32 v13, v6, v6
	v_lshlrev_b32_e32 v28, 16, v70
	v_and_b32_e32 v29, 0xffff0000, v70
	v_lshlrev_b32_e32 v30, 16, v71
	v_and_b32_e32 v31, 0xffff0000, v71
	v_add_f32_e32 v9, v9, v13
	v_add_f32_e32 v13, v8, v9
	v_pk_add_f32 v[2:3], v[2:3], v[30:31]
	v_pk_add_f32 v[8:9], v[0:1], v[28:29]
	v_mul_f32_e32 v1, v3, v3
	v_mul_f32_e32 v0, v9, v9
	v_fmac_f32_e32 v0, v8, v8
	v_fmac_f32_e32 v1, v2, v2
	v_add_f32_e32 v0, v0, v1
	v_add_f32_e32 v0, v13, v0
	ds_bpermute_b32 v1, v211, v0
	v_lshl_add_u64 v[18:19], s[10:11], 0, v[66:67]
	v_lshl_add_u64 v[18:19], v[136:137], 1, v[18:19]
	v_cvt_pk_bf16_f32 v4, v4, v5
	v_cvt_pk_bf16_f32 v5, v6, v7
	s_waitcnt lgkmcnt(0)
	v_add_f32_e32 v0, v0, v1
	ds_bpermute_b32 v1, v210, v0
	v_cvt_pk_bf16_f32 v17, v14, v15
	v_cvt_pk_bf16_f32 v13, v10, v11
	global_store_dwordx2 v[18:19], v[4:5], off offset:256
	v_cvt_pk_bf16_f32 v4, v8, v9
	v_cvt_pk_bf16_f32 v5, v2, v3
	global_store_dwordx2 v[18:19], v[16:17], off
	global_store_dwordx2 v[18:19], v[12:13], off offset:32
	global_store_dwordx2 v[18:19], v[4:5], off offset:288
	s_and_saveexec_b64 s[24:25], s[4:5]
	s_cbranch_execz .LBB0_811
	v_lshlrev_b64 v[2:3], 7, v[64:65]
	v_lshl_add_u64 v[2:3], s[14:15], 0, v[2:3]
	v_lshl_add_u64 v[2:3], s[22:23], 2, v[2:3]
	s_lshl_b32 s72, s41, 2
	v_lshl_add_u64 v[2:3], v[2:3], 0, s[72:73]
	s_waitcnt lgkmcnt(0)
	v_add_f32_e32 v0, v0, v1
	global_store_dword v[2:3], v0, off

; __device__ __forceinline__ int opaque_tid() { int t = threadIdx.x; asm volatile("" : "+v"(t)); return t; }
; __device__ __forceinline__ void rmsnorm_rows_bf16_to_f32(const bf16_t* src, const float* gain, float* dst) {
;     const int tid = opaque_tid(), lane = tid & 63, gw = blockIdx.x * 8 + (tid >> 6), ngw = gridDim.x * 8;
;     for (int m = gw; m < M; m += ngw) {
;         const bf16x8* xr = (const bf16x8*)(src + (size_t)m * DM) + lane;
;         float v[4][8]; float s = 0.f;
; #pragma unroll
;         for (int j = 0; j < 4; ++j) { unpack8(xr[64 * j], v[j]);
; #pragma unroll
;             for (int e = 0; e < 8; ++e) s += v[j][e] * v[j][e]; }
;         const float rstd = rsqrtf(wave_sum(s) * (1.f / DM) + EPS);
; #pragma unroll
;         for (int j = 0; j < 4; ++j) { const int c = (lane + 64 * j) * 8; const f32x4 g0 = *(const f32x4*)(gain + c), g1 = *(const f32x4*)(gain + c + 4);
;             f32x4 o0 = {v[j][0] * rstd * g0[0], v[j][1] * rstd * g0[1], v[j][2] * rstd * g0[2], v[j][3] * rstd * g0[3]};
;             f32x4 o1 = {v[j][4] * rstd * g1[0], v[j][5] * rstd * g1[1], v[j][6] * rstd * g1[2], v[j][7] * rstd * g1[3]};
;             *(f32x4*)(dst + (size_t)m * DM + c) = o0; *(f32x4*)(dst + (size_t)m * DM + c + 4) = o1; }
;     }
; }
.LBB0_860:
	global_load_dwordx4 v[18:21], v[8:9], off
	global_load_dwordx4 v[22:25], v[8:9], off offset:1024
	global_load_dwordx4 v[26:29], v[8:9], off offset:2048
	global_load_dwordx4 v[30:33], v[8:9], off offset:3072
	global_load_dwordx4 v[34:37], v[2:3], off offset:16
	global_load_dwordx4 v[38:41], v[2:3], off
	v_add_u32_e32 v0, s8, v0
	v_lshl_add_u64 v[8:9], v[8:9], 0, s[0:1]
	s_waitcnt vmcnt(0) lgkmcnt(0)
	v_and_b32_e32 v43, 0xffff0000, v20
	v_lshlrev_b32_e32 v42, 16, v20
	v_and_b32_e32 v45, 0xffff0000, v21
	v_lshlrev_b32_e32 v44, 16, v21
	v_and_b32_e32 v21, 0xffff0000, v18
	v_lshlrev_b32_e32 v20, 16, v18
	v_and_b32_e32 v47, 0xffff0000, v19
	v_lshlrev_b32_e32 v46, 16, v19
	v_and_b32_e32 v49, 0xffff0000, v24
	v_lshlrev_b32_e32 v48, 16, v24
	v_and_b32_e32 v51, 0xffff0000, v25
	v_lshlrev_b32_e32 v50, 16, v25
	v_pk_mul_f32 v[24:25], v[20:21], v[20:21]
	v_and_b32_e32 v57, 0xffff0000, v28
	v_lshlrev_b32_e32 v56, 16, v28
	v_and_b32_e32 v59, 0xffff0000, v29
	v_lshlrev_b32_e32 v58, 16, v29
	v_and_b32_e32 v29, 0xffff0000, v26
	v_lshlrev_b32_e32 v28, 16, v26
	v_and_b32_e32 v61, 0xffff0000, v27
	v_lshlrev_b32_e32 v60, 16, v27
	v_and_b32_e32 v27, 0xffff0000, v32
	v_lshlrev_b32_e32 v26, 16, v32
	v_and_b32_e32 v63, 0xffff0000, v33
	v_lshlrev_b32_e32 v62, 16, v33
	v_and_b32_e32 v33, 0xffff0000, v30
	v_lshlrev_b32_e32 v32, 16, v30
	v_and_b32_e32 v65, 0xffff0000, v31
	v_lshlrev_b32_e32 v64, 16, v31
	v_pk_mul_f32 v[30:31], v[46:47], v[46:47]
	v_add_f32_e32 v24, v24, v25
	v_add_f32_e32 v24, v30, v24
	v_pk_mul_f32 v[18:19], v[42:43], v[42:43]
	v_add_f32_e32 v24, v31, v24
	v_add_f32_e32 v18, v18, v24
	v_and_b32_e32 v53, 0xffff0000, v22
	v_lshlrev_b32_e32 v52, 16, v22
	v_and_b32_e32 v55, 0xffff0000, v23
	v_lshlrev_b32_e32 v54, 16, v23
	v_pk_mul_f32 v[22:23], v[44:45], v[44:45]
	v_add_f32_e32 v18, v19, v18
	v_add_f32_e32 v18, v22, v18
	v_pk_mul_f32 v[70:71], v[52:53], v[52:53]
	v_add_f32_e32 v18, v23, v18
	v_add_f32_e32 v18, v70, v18
	v_pk_mul_f32 v[72:73], v[54:55], v[54:55]
	v_add_f32_e32 v18, v71, v18
	v_add_f32_e32 v18, v72, v18
	v_pk_mul_f32 v[66:67], v[48:49], v[48:49]
	v_add_f32_e32 v18, v73, v18
	v_add_f32_e32 v18, v66, v18
	v_pk_mul_f32 v[68:69], v[50:51], v[50:51]
	v_add_f32_e32 v18, v67, v18
	v_add_f32_e32 v18, v68, v18
	v_pk_mul_f32 v[78:79], v[28:29], v[28:29]
	v_add_f32_e32 v18, v69, v18
	v_add_f32_e32 v18, v78, v18
	v_pk_mul_f32 v[80:81], v[60:61], v[60:61]
	v_add_f32_e32 v18, v79, v18
	v_add_f32_e32 v18, v80, v18
	v_pk_mul_f32 v[74:75], v[56:57], v[56:57]
	v_add_f32_e32 v18, v81, v18
	v_add_f32_e32 v18, v74, v18
	v_pk_mul_f32 v[76:77], v[58:59], v[58:59]
	v_add_f32_e32 v18, v75, v18
	v_add_f32_e32 v18, v76, v18
	v_pk_mul_f32 v[86:87], v[32:33], v[32:33]
	v_add_f32_e32 v18, v77, v18
	v_add_f32_e32 v18, v86, v18
	v_pk_mul_f32 v[88:89], v[64:65], v[64:65]
	v_add_f32_e32 v18, v87, v18
	v_add_f32_e32 v18, v88, v18
	v_pk_mul_f32 v[82:83], v[26:27], v[26:27]
	v_add_f32_e32 v18, v89, v18
	v_add_f32_e32 v18, v82, v18
	v_pk_mul_f32 v[84:85], v[62:63], v[62:63]
	v_add_f32_e32 v18, v83, v18
	v_add_f32_e32 v18, v84, v18
	v_add_f32_e32 v18, v85, v18
	ds_bpermute_b32 v19, v12, v18
	s_waitcnt lgkmcnt(0)
	v_add_f32_e32 v18, v18, v19
	ds_bpermute_b32 v19, v13, v18
	s_waitcnt lgkmcnt(0)
	v_add_f32_e32 v18, v18, v19
	ds_bpermute_b32 v19, v14, v18
	s_waitcnt lgkmcnt(0)
	v_add_f32_e32 v18, v18, v19
	ds_bpermute_b32 v19, v15, v18
	s_waitcnt lgkmcnt(0)
	v_add_f32_e32 v18, v18, v19
	ds_bpermute_b32 v19, v16, v18
	s_waitcnt lgkmcnt(0)
	v_add_f32_e32 v18, v18, v19
	ds_bpermute_b32 v19, v17, v18
	s_waitcnt lgkmcnt(0)
	v_add_f32_e32 v18, v18, v19
	v_fmamk_f32 v18, v18, 0x3a000000, v1
	v_mul_f32_e32 v19, 0x4b800000, v18
	v_cmp_gt_f32_e32 vcc, s6, v18
	s_nop 1
	v_cndmask_b32_e32 v18, v18, v19, vcc
	v_rsq_f32_e32 v18, v18
	s_nop 0
	v_mul_f32_e32 v19, 0x45800000, v18
	v_cndmask_b32_e32 v30, v18, v19, vcc
	v_pk_mul_f32 v[18:19], v[30:31], v[20:21] op_sel_hi:[0,1]
	v_pk_mul_f32 v[20:21], v[30:31], v[46:47] op_sel_hi:[0,1]
	v_pk_mul_f32 v[22:23], v[30:31], v[42:43] op_sel_hi:[0,1]
	v_pk_mul_f32 v[24:25], v[30:31], v[44:45] op_sel_hi:[0,1]
	v_pk_mul_f32 v[20:21], v[40:41], v[20:21]
	v_pk_mul_f32 v[18:19], v[38:39], v[18:19]
	v_pk_mul_f32 v[24:25], v[36:37], v[24:25]
	v_pk_mul_f32 v[22:23], v[34:35], v[22:23]
	global_store_dwordx4 v[10:11], v[18:21], off offset:-4096
	global_store_dwordx4 v[10:11], v[22:25], off offset:-4080
	global_load_dwordx4 v[18:21], v[2:3], off offset:2048
	s_nop 0
	global_load_dwordx4 v[22:25], v[2:3], off offset:2064
	v_pk_mul_f32 v[34:35], v[30:31], v[54:55] op_sel_hi:[0,1]
	v_pk_mul_f32 v[36:37], v[30:31], v[52:53] op_sel_hi:[0,1]
	v_pk_mul_f32 v[38:39], v[30:31], v[50:51] op_sel_hi:[0,1]
	v_pk_mul_f32 v[40:41], v[30:31], v[48:49] op_sel_hi:[0,1]
	v_pk_mul_f32 v[28:29], v[30:31], v[28:29] op_sel_hi:[0,1]
	v_pk_mul_f32 v[32:33], v[30:31], v[32:33] op_sel_hi:[0,1]
	v_cmp_lt_i32_e32 vcc, s7, v0
	v_pk_mul_f32 v[26:27], v[30:31], v[26:27] op_sel_hi:[0,1]
	s_or_b64 s[4:5], vcc, s[4:5]
	s_waitcnt vmcnt(1)
	v_pk_mul_f32 v[18:19], v[18:19], v[36:37]
	v_pk_mul_f32 v[20:21], v[20:21], v[34:35]
	s_waitcnt vmcnt(0)
	v_pk_mul_f32 v[22:23], v[22:23], v[40:41]
	v_pk_mul_f32 v[24:25], v[24:25], v[38:39]
	global_store_dwordx4 v[10:11], v[18:21], off offset:-2048
	global_store_dwordx4 v[10:11], v[22:25], off offset:-2032
	global_load_dwordx4 v[18:21], v[4:5], off
	s_nop 0
	global_load_dwordx4 v[22:25], v[4:5], off offset:16
	v_pk_mul_f32 v[34:35], v[30:31], v[60:61] op_sel_hi:[0,1]
	v_pk_mul_f32 v[36:37], v[30:31], v[58:59] op_sel_hi:[0,1]
	v_pk_mul_f32 v[38:39], v[30:31], v[56:57] op_sel_hi:[0,1]
	s_waitcnt vmcnt(1)
	v_pk_mul_f32 v[18:19], v[18:19], v[28:29]
	v_pk_mul_f32 v[20:21], v[20:21], v[34:35]
	s_waitcnt vmcnt(0)
	v_pk_mul_f32 v[22:23], v[22:23], v[38:39]
	v_pk_mul_f32 v[24:25], v[24:25], v[36:37]
	global_store_dwordx4 v[10:11], v[18:21], off
	global_store_dwordx4 v[10:11], v[22:25], off offset:16
	global_load_dwordx4 v[18:21], v[6:7], off
	s_nop 0
	global_load_dwordx4 v[22:25], v[6:7], off offset:16
	v_pk_mul_f32 v[28:29], v[30:31], v[64:65] op_sel_hi:[0,1]
	v_pk_mul_f32 v[34:35], v[30:31], v[62:63] op_sel_hi:[0,1]
	s_waitcnt vmcnt(1)
	v_pk_mul_f32 v[18:19], v[18:19], v[32:33]
	v_pk_mul_f32 v[20:21], v[20:21], v[28:29]
	s_waitcnt vmcnt(0)
	v_pk_mul_f32 v[22:23], v[22:23], v[26:27]
	v_pk_mul_f32 v[24:25], v[24:25], v[34:35]
	global_store_dwordx4 v[10:11], v[18:21], off offset:2048
	global_store_dwordx4 v[10:11], v[22:25], off offset:2064
	v_lshl_add_u64 v[10:11], v[10:11], 0, s[2:3]
	s_andn2_b64 exec, exec, s[4:5]
	s_cbranch_execnz .LBB0_860
